# sc1 write-through on all 16-byte stores so the grid barrier's L2 write-back is short
# baseline (speedup 1.0000x reference)
; #define LAS __attribute__((address_space(3)))
; __device__ __forceinline__ unsigned cvt_pk_bf16(float lo, float hi) { unsigned r; asm volatile("v_cvt_pk_bf16_f32 %0, %1, %2" : "=v"(r) : "v"(lo), "v"(hi)); return r; }
; __device__ __forceinline__ float bflo(unsigned w) { return __uint_as_float(w << 16); }
; __device__ __forceinline__ float bfhi(unsigned w) { return __uint_as_float(w & 0xffff0000u); }
; __device__ __forceinline__ void transpose_item(const float* W, int N, bf16_t* WT, int ldk, int k0, int n0, int dst_row0, LAS float* scr, int lane, const float* fg, const float* fb, float* cs) {
;     ...
;     for (int j = 0; j < 4; ++j) { const int n = (lane >> 3) + 8 * j; const LAS float* s = scr + (8 * c) * 33 + n;
;         const f32x4 w0 = (f32x4){s[0 * 33], s[1 * 33], s[2 * 33], s[3 * 33]}, w1 = (f32x4){s[4 * 33], s[5 * 33], s[6 * 33], s[7 * 33]};
;         const f32x4 f0 = w0 * g0, f1 = w1 * g1;
;         u32x4 o; o.x = cvt_pk_bf16(f0[0], f0[1]); o.y = cvt_pk_bf16(f0[2], f0[3]); o.z = cvt_pk_bf16(f1[0], f1[1]); o.w = cvt_pk_bf16(f1[2], f1[3]);
;         *(u32x4*)(WT + (size_t)(dst_row0 + n) * ldk + k0 + 8 * c) = o;
;         if (fg) {
;             float p1 = ((bflo(o.x) + bfhi(o.x)) + (bflo(o.y) + bfhi(o.y))) + ((bflo(o.z) + bfhi(o.z)) + (bflo(o.w) + bfhi(o.w)));
;             const f32x4 t0 = w0 * b0, t1 = w1 * b1;
;             float p2 = ((t0[0] + t0[1]) + (t0[2] + t0[3])) + ((t1[0] + t1[1]) + (t1[2] + t1[3]));
;             p1 += __shfl_xor(p1, 1); p2 += __shfl_xor(p2, 1); p1 += __shfl_xor(p1, 2); p2 += __shfl_xor(p2, 2); p1 += __shfl_xor(p1, 4); p2 += __shfl_xor(p2, 4);
;             if (c == 0) { atomicAdd(cs + dst_row0 + n, p1); atomicAdd(cs + NZ + dst_row0 + n, p2); }
.LBB0_46:
	ds_read2_b32 v[32:33], v40 offset0:66 offset1:99
	ds_read2_b32 v[34:35], v40 offset1:33
	ds_read2_b32 v[36:37], v40 offset0:198 offset1:231
	ds_read2_b32 v[38:39], v40 offset0:132 offset1:165
	s_lshl_b64 s[28:29], s[96:97], 1
	s_add_u32 s4, s4, s28
	s_addc_u32 s5, s5, s29
	s_ashr_i32 s11, s10, 31
	v_lshl_add_u64 v[30:31], s[4:5], 0, v[24:25]
	s_lshl_b64 s[4:5], s[10:11], 2
	s_waitcnt vmcnt(2) lgkmcnt(3)
	v_pk_mul_f32 v[20:21], v[16:17], v[32:33]
	s_waitcnt lgkmcnt(2)
	v_pk_mul_f32 v[18:19], v[14:15], v[34:35]
	s_waitcnt lgkmcnt(1)
	v_pk_mul_f32 v[58:59], v[12:13], v[36:37]
	v_add_u32_e32 v57, s10, v22
	s_add_u32 s84, s86, s4
	s_waitcnt lgkmcnt(0)
	v_pk_mul_f32 v[60:61], v[10:11], v[38:39]
	v_cvt_pk_bf16_f32 v18, v18, v19
	v_cvt_pk_bf16_f32 v19, v20, v21
	s_addc_u32 s85, s87, s5
	v_cvt_pk_bf16_f32 v20, v60, v61
	v_cvt_pk_bf16_f32 v21, v58, v59
	v_ashrrev_i32_e32 v58, 31, v57
	v_mul_lo_u32 v60, s26, v58
	v_mul_lo_u32 v61, s27, v57
	v_mad_u64_u32 v[58:59], s[4:5], s26, v57, 0
	s_add_u32 s86, s84, 0xb000
	v_add3_u32 v59, v59, v60, v61
	v_cndmask_b32_e64 v57, 0, 1, vcc
	s_addc_u32 s87, s85, 0
	v_lshl_add_u64 v[58:59], v[58:59], 1, v[30:31]
	v_cmp_ne_u32_e64 s[4:5], 1, v57
	s_andn2_b64 vcc, exec, vcc
	global_store_dwordx4 v[58:59], v[18:21], off sc1
	s_cbranch_vccnz .LBB0_50
	v_lshlrev_b32_e32 v57, 16, v18
	v_and_b32_e32 v18, 0xffff0000, v18
	v_add_f32_e32 v18, v57, v18
	v_lshlrev_b32_e32 v57, 16, v19
	v_and_b32_e32 v19, 0xffff0000, v19
	v_add_f32_e32 v19, v57, v19
	v_add_f32_e32 v18, v18, v19
	v_lshlrev_b32_e32 v19, 16, v20
	v_and_b32_e32 v20, 0xffff0000, v20
	v_add_f32_e32 v19, v19, v20
	v_lshlrev_b32_e32 v20, 16, v21
	v_and_b32_e32 v21, 0xffff0000, v21
	v_add_f32_e32 v20, v20, v21
	v_add_f32_e32 v19, v19, v20
	v_add_f32_e32 v57, v18, v19
	s_waitcnt vmcnt(1)
	v_pk_mul_f32 v[18:19], v[8:9], v[32:33]
	v_pk_mul_f32 v[20:21], v[6:7], v[34:35]
	v_pk_mul_f32 v[32:33], v[4:5], v[36:37]
	v_pk_mul_f32 v[34:35], v[2:3], v[38:39]
	v_add_f32_e32 v20, v20, v21
	v_add_f32_e32 v18, v18, v19
	v_add_f32_e32 v18, v20, v18
	v_add_f32_e32 v19, v34, v35
	v_add_f32_e32 v20, v32, v33
	v_add_f32_e32 v19, v19, v20
	v_and_b32_e32 v20, 64, v56
	v_add_f32_e32 v18, v18, v19
	v_xor_b32_e32 v19, 1, v56
	v_add_u32_e32 v20, 64, v20
	v_cmp_lt_i32_e32 vcc, v19, v20
	s_nop 1
	v_cndmask_b32_e32 v19, v56, v19, vcc
	v_lshlrev_b32_e32 v19, 2, v19
	ds_bpermute_b32 v21, v19, v57
	ds_bpermute_b32 v19, v19, v18
	s_waitcnt lgkmcnt(1)
	v_add_f32_e32 v21, v57, v21
	s_waitcnt lgkmcnt(0)
	v_add_f32_e32 v19, v18, v19
	v_xor_b32_e32 v18, 2, v56
	v_cmp_lt_i32_e32 vcc, v18, v20
	s_nop 1
	v_cndmask_b32_e32 v18, v56, v18, vcc
	v_lshlrev_b32_e32 v18, 2, v18
	ds_bpermute_b32 v32, v18, v21
	ds_bpermute_b32 v33, v18, v19
	s_waitcnt lgkmcnt(1)
	v_add_f32_e32 v18, v21, v32
	v_xor_b32_e32 v21, 4, v56
	v_cmp_lt_i32_e32 vcc, v21, v20
	s_waitcnt lgkmcnt(0)
	v_add_f32_e32 v19, v19, v33
	v_cndmask_b32_e32 v20, v56, v21, vcc
	v_lshlrev_b32_e32 v21, 2, v20
	ds_bpermute_b32 v20, v21, v18
	ds_bpermute_b32 v21, v21, v19
	s_and_saveexec_b64 s[28:29], s[0:1]
	s_cbranch_execz .LBB0_49
	v_lshlrev_b32_e32 v32, 2, v22
	s_waitcnt lgkmcnt(1)
	v_add_f32_e32 v18, v18, v20
	s_waitcnt lgkmcnt(0)
	v_add_f32_e32 v19, v19, v21
	global_atomic_add_f32 v32, v18, s[84:85]
	global_atomic_add_f32 v32, v19, s[86:87]

; #define LAS __attribute__((address_space(3)))
; __device__ __forceinline__ unsigned cvt_pk_bf16(float lo, float hi) { unsigned r; asm volatile("v_cvt_pk_bf16_f32 %0, %1, %2" : "=v"(r) : "v"(lo), "v"(hi)); return r; }
; __device__ __forceinline__ float bflo(unsigned w) { return __uint_as_float(w << 16); }
; __device__ __forceinline__ float bfhi(unsigned w) { return __uint_as_float(w & 0xffff0000u); }
; __device__ __forceinline__ void transpose_item(const float* W, int N, bf16_t* WT, int ldk, int k0, int n0, int dst_row0, LAS float* scr, int lane, const float* fg, const float* fb, float* cs) {
;     ...
;     for (int j = 0; j < 4; ++j) { const int n = (lane >> 3) + 8 * j; const LAS float* s = scr + (8 * c) * 33 + n;
;         const f32x4 w0 = (f32x4){s[0 * 33], s[1 * 33], s[2 * 33], s[3 * 33]}, w1 = (f32x4){s[4 * 33], s[5 * 33], s[6 * 33], s[7 * 33]};
;         const f32x4 f0 = w0 * g0, f1 = w1 * g1;
;         u32x4 o; o.x = cvt_pk_bf16(f0[0], f0[1]); o.y = cvt_pk_bf16(f0[2], f0[3]); o.z = cvt_pk_bf16(f1[0], f1[1]); o.w = cvt_pk_bf16(f1[2], f1[3]);
;         *(u32x4*)(WT + (size_t)(dst_row0 + n) * ldk + k0 + 8 * c) = o;
;         if (fg) {
;             float p1 = ((bflo(o.x) + bfhi(o.x)) + (bflo(o.y) + bfhi(o.y))) + ((bflo(o.z) + bfhi(o.z)) + (bflo(o.w) + bfhi(o.w)));
;             const f32x4 t0 = w0 * b0, t1 = w1 * b1;
;             float p2 = ((t0[0] + t0[1]) + (t0[2] + t0[3])) + ((t1[0] + t1[1]) + (t1[2] + t1[3]));
;             p1 += __shfl_xor(p1, 1); p2 += __shfl_xor(p2, 1); p1 += __shfl_xor(p1, 2); p2 += __shfl_xor(p2, 2); p1 += __shfl_xor(p1, 4); p2 += __shfl_xor(p2, 4);
;             if (c == 0) { atomicAdd(cs + dst_row0 + n, p1); atomicAdd(cs + NZ + dst_row0 + n, p2); }
.LBB0_50:
	ds_read2_b32 v[32:33], v40 offset0:74 offset1:107
	ds_read2_b32 v[34:35], v40 offset0:8 offset1:41
	ds_read2_b32 v[36:37], v40 offset0:206 offset1:239
	ds_read2_b32 v[38:39], v40 offset0:140 offset1:173
	v_add_u32_e32 v57, s10, v1
	s_waitcnt lgkmcnt(3)
	v_pk_mul_f32 v[20:21], v[16:17], v[32:33]
	s_waitcnt lgkmcnt(2)
	v_pk_mul_f32 v[18:19], v[14:15], v[34:35]
	s_waitcnt lgkmcnt(1)
	v_pk_mul_f32 v[58:59], v[12:13], v[36:37]
	s_waitcnt lgkmcnt(0)
	v_pk_mul_f32 v[60:61], v[10:11], v[38:39]
	v_cvt_pk_bf16_f32 v18, v18, v19
	v_cvt_pk_bf16_f32 v19, v20, v21
	s_and_b64 vcc, exec, s[4:5]
	v_cvt_pk_bf16_f32 v20, v60, v61
	v_cvt_pk_bf16_f32 v21, v58, v59
	v_ashrrev_i32_e32 v58, 31, v57
	v_mul_lo_u32 v60, s26, v58
	v_mul_lo_u32 v61, s27, v57
	v_mad_u64_u32 v[58:59], s[28:29], s26, v57, 0
	v_add3_u32 v59, v59, v60, v61
	v_lshl_add_u64 v[58:59], v[58:59], 1, v[30:31]
	global_store_dwordx4 v[58:59], v[18:21], off sc1
	s_cbranch_vccnz .LBB0_54
	v_lshlrev_b32_e32 v57, 16, v18
	v_and_b32_e32 v18, 0xffff0000, v18
	v_add_f32_e32 v18, v57, v18
	v_lshlrev_b32_e32 v57, 16, v19
	v_and_b32_e32 v19, 0xffff0000, v19
	v_add_f32_e32 v19, v57, v19
	v_add_f32_e32 v18, v18, v19
	v_lshlrev_b32_e32 v19, 16, v20
	v_and_b32_e32 v20, 0xffff0000, v20
	v_add_f32_e32 v19, v19, v20
	v_lshlrev_b32_e32 v20, 16, v21
	v_and_b32_e32 v21, 0xffff0000, v21
	v_add_f32_e32 v20, v20, v21
	v_add_f32_e32 v19, v19, v20
	v_add_f32_e32 v57, v18, v19
	s_waitcnt vmcnt(2)
	v_pk_mul_f32 v[18:19], v[8:9], v[32:33]
	v_pk_mul_f32 v[20:21], v[6:7], v[34:35]
	v_pk_mul_f32 v[32:33], v[4:5], v[36:37]
	v_pk_mul_f32 v[34:35], v[2:3], v[38:39]
	v_add_f32_e32 v20, v20, v21
	v_add_f32_e32 v18, v18, v19
	v_add_f32_e32 v18, v20, v18
	v_add_f32_e32 v19, v34, v35
	v_add_f32_e32 v20, v32, v33
	v_add_f32_e32 v19, v19, v20
	v_and_b32_e32 v20, 64, v56
	v_add_f32_e32 v18, v18, v19
	v_xor_b32_e32 v19, 1, v56
	v_add_u32_e32 v20, 64, v20
	v_cmp_lt_i32_e32 vcc, v19, v20
	s_nop 1
	v_cndmask_b32_e32 v19, v56, v19, vcc
	v_lshlrev_b32_e32 v19, 2, v19
	ds_bpermute_b32 v21, v19, v57
	ds_bpermute_b32 v19, v19, v18
	s_waitcnt lgkmcnt(1)
	v_add_f32_e32 v21, v57, v21
	s_waitcnt lgkmcnt(0)
	v_add_f32_e32 v19, v18, v19
	v_xor_b32_e32 v18, 2, v56
	v_cmp_lt_i32_e32 vcc, v18, v20
	s_nop 1
	v_cndmask_b32_e32 v18, v56, v18, vcc
	v_lshlrev_b32_e32 v18, 2, v18
	ds_bpermute_b32 v32, v18, v21
	ds_bpermute_b32 v33, v18, v19
	s_waitcnt lgkmcnt(1)
	v_add_f32_e32 v18, v21, v32
	v_xor_b32_e32 v21, 4, v56
	v_cmp_lt_i32_e32 vcc, v21, v20
	s_waitcnt lgkmcnt(0)
	v_add_f32_e32 v19, v19, v33
	v_cndmask_b32_e32 v20, v56, v21, vcc
	v_lshlrev_b32_e32 v21, 2, v20
	ds_bpermute_b32 v20, v21, v18
	ds_bpermute_b32 v21, v21, v19
	s_and_saveexec_b64 s[28:29], s[0:1]
	s_cbranch_execz .LBB0_53
	v_lshlrev_b32_e32 v32, 2, v22
	s_waitcnt lgkmcnt(1)
	v_add_f32_e32 v18, v18, v20
	s_waitcnt lgkmcnt(0)
	v_add_f32_e32 v19, v19, v21
	global_atomic_add_f32 v32, v18, s[84:85] offset:32
	global_atomic_add_f32 v32, v19, s[86:87] offset:32

; #define LAS __attribute__((address_space(3)))
; __device__ __forceinline__ unsigned cvt_pk_bf16(float lo, float hi) { unsigned r; asm volatile("v_cvt_pk_bf16_f32 %0, %1, %2" : "=v"(r) : "v"(lo), "v"(hi)); return r; }
; __device__ __forceinline__ float bflo(unsigned w) { return __uint_as_float(w << 16); }
; __device__ __forceinline__ float bfhi(unsigned w) { return __uint_as_float(w & 0xffff0000u); }
; __device__ __forceinline__ void transpose_item(const float* W, int N, bf16_t* WT, int ldk, int k0, int n0, int dst_row0, LAS float* scr, int lane, const float* fg, const float* fb, float* cs) {
;     ...
;     for (int j = 0; j < 4; ++j) { const int n = (lane >> 3) + 8 * j; const LAS float* s = scr + (8 * c) * 33 + n;
;         const f32x4 w0 = (f32x4){s[0 * 33], s[1 * 33], s[2 * 33], s[3 * 33]}, w1 = (f32x4){s[4 * 33], s[5 * 33], s[6 * 33], s[7 * 33]};
;         const f32x4 f0 = w0 * g0, f1 = w1 * g1;
;         u32x4 o; o.x = cvt_pk_bf16(f0[0], f0[1]); o.y = cvt_pk_bf16(f0[2], f0[3]); o.z = cvt_pk_bf16(f1[0], f1[1]); o.w = cvt_pk_bf16(f1[2], f1[3]);
;         *(u32x4*)(WT + (size_t)(dst_row0 + n) * ldk + k0 + 8 * c) = o;
;         if (fg) {
;             float p1 = ((bflo(o.x) + bfhi(o.x)) + (bflo(o.y) + bfhi(o.y))) + ((bflo(o.z) + bfhi(o.z)) + (bflo(o.w) + bfhi(o.w)));
;             const f32x4 t0 = w0 * b0, t1 = w1 * b1;
;             float p2 = ((t0[0] + t0[1]) + (t0[2] + t0[3])) + ((t1[0] + t1[1]) + (t1[2] + t1[3]));
;             p1 += __shfl_xor(p1, 1); p2 += __shfl_xor(p2, 1); p1 += __shfl_xor(p1, 2); p2 += __shfl_xor(p2, 2); p1 += __shfl_xor(p1, 4); p2 += __shfl_xor(p2, 4);
;             if (c == 0) { atomicAdd(cs + dst_row0 + n, p1); atomicAdd(cs + NZ + dst_row0 + n, p2); }
.LBB0_54:
	ds_read2_b32 v[32:33], v40 offset0:82 offset1:115
	ds_read2_b32 v[34:35], v40 offset0:16 offset1:49
	ds_read2_b32 v[36:37], v40 offset0:214 offset1:247
	ds_read2_b32 v[38:39], v40 offset0:148 offset1:181
	v_add_u32_e32 v57, s10, v23
	s_waitcnt lgkmcnt(3)
	v_pk_mul_f32 v[20:21], v[16:17], v[32:33]
	s_waitcnt lgkmcnt(2)
	v_pk_mul_f32 v[18:19], v[14:15], v[34:35]
	s_waitcnt lgkmcnt(1)
	v_pk_mul_f32 v[58:59], v[12:13], v[36:37]
	s_waitcnt lgkmcnt(0)
	v_pk_mul_f32 v[60:61], v[10:11], v[38:39]
	v_cvt_pk_bf16_f32 v18, v18, v19
	v_cvt_pk_bf16_f32 v19, v20, v21
	s_and_b64 vcc, exec, s[4:5]
	v_cvt_pk_bf16_f32 v20, v60, v61
	v_cvt_pk_bf16_f32 v21, v58, v59
	v_ashrrev_i32_e32 v58, 31, v57
	v_mul_lo_u32 v60, s26, v58
	v_mul_lo_u32 v61, s27, v57
	v_mad_u64_u32 v[58:59], s[28:29], s26, v57, 0
	v_add3_u32 v59, v59, v60, v61
	v_lshl_add_u64 v[58:59], v[58:59], 1, v[30:31]
	global_store_dwordx4 v[58:59], v[18:21], off sc1
	s_cbranch_vccnz .LBB0_58
	v_lshlrev_b32_e32 v57, 16, v18
	v_and_b32_e32 v18, 0xffff0000, v18
	v_add_f32_e32 v18, v57, v18
	v_lshlrev_b32_e32 v57, 16, v19
	v_and_b32_e32 v19, 0xffff0000, v19
	v_add_f32_e32 v19, v57, v19
	v_add_f32_e32 v18, v18, v19
	v_lshlrev_b32_e32 v19, 16, v20
	v_and_b32_e32 v20, 0xffff0000, v20
	v_add_f32_e32 v19, v19, v20
	v_lshlrev_b32_e32 v20, 16, v21
	v_and_b32_e32 v21, 0xffff0000, v21
	v_add_f32_e32 v20, v20, v21
	v_add_f32_e32 v19, v19, v20
	v_add_f32_e32 v57, v18, v19
	s_waitcnt vmcnt(3)
	v_pk_mul_f32 v[18:19], v[8:9], v[32:33]
	v_pk_mul_f32 v[20:21], v[6:7], v[34:35]
	v_pk_mul_f32 v[32:33], v[4:5], v[36:37]
	v_pk_mul_f32 v[34:35], v[2:3], v[38:39]
	v_add_f32_e32 v20, v20, v21
	v_add_f32_e32 v18, v18, v19
	v_add_f32_e32 v18, v20, v18
	v_add_f32_e32 v19, v34, v35
	v_add_f32_e32 v20, v32, v33
	v_add_f32_e32 v19, v19, v20
	v_and_b32_e32 v20, 64, v56
	v_add_f32_e32 v18, v18, v19
	v_xor_b32_e32 v19, 1, v56
	v_add_u32_e32 v20, 64, v20
	v_cmp_lt_i32_e32 vcc, v19, v20
	s_nop 1
	v_cndmask_b32_e32 v19, v56, v19, vcc
	v_lshlrev_b32_e32 v19, 2, v19
	ds_bpermute_b32 v21, v19, v57
	ds_bpermute_b32 v19, v19, v18
	s_waitcnt lgkmcnt(1)
	v_add_f32_e32 v21, v57, v21
	s_waitcnt lgkmcnt(0)
	v_add_f32_e32 v19, v18, v19
	v_xor_b32_e32 v18, 2, v56
	v_cmp_lt_i32_e32 vcc, v18, v20
	s_nop 1
	v_cndmask_b32_e32 v18, v56, v18, vcc
	v_lshlrev_b32_e32 v18, 2, v18
	ds_bpermute_b32 v32, v18, v21
	ds_bpermute_b32 v33, v18, v19
	s_waitcnt lgkmcnt(1)
	v_add_f32_e32 v18, v21, v32
	v_xor_b32_e32 v21, 4, v56
	v_cmp_lt_i32_e32 vcc, v21, v20
	s_waitcnt lgkmcnt(0)
	v_add_f32_e32 v19, v19, v33
	v_cndmask_b32_e32 v20, v56, v21, vcc
	v_lshlrev_b32_e32 v21, 2, v20
	ds_bpermute_b32 v20, v21, v18
	ds_bpermute_b32 v21, v21, v19
	s_and_saveexec_b64 s[28:29], s[0:1]
	s_cbranch_execz .LBB0_57
	v_lshlrev_b32_e32 v32, 2, v22
	s_waitcnt lgkmcnt(1)
	v_add_f32_e32 v18, v18, v20
	s_waitcnt lgkmcnt(0)
	v_add_f32_e32 v19, v19, v21
	global_atomic_add_f32 v32, v18, s[84:85] offset:64
	global_atomic_add_f32 v32, v19, s[86:87] offset:64

; #define LAS __attribute__((address_space(3)))
; __device__ __forceinline__ unsigned cvt_pk_bf16(float lo, float hi) { unsigned r; asm volatile("v_cvt_pk_bf16_f32 %0, %1, %2" : "=v"(r) : "v"(lo), "v"(hi)); return r; }
; __device__ __forceinline__ float bflo(unsigned w) { return __uint_as_float(w << 16); }
; __device__ __forceinline__ float bfhi(unsigned w) { return __uint_as_float(w & 0xffff0000u); }
; __device__ __forceinline__ void transpose_item(const float* W, int N, bf16_t* WT, int ldk, int k0, int n0, int dst_row0, LAS float* scr, int lane, const float* fg, const float* fb, float* cs) {
;     ...
;     for (int j = 0; j < 4; ++j) { const int n = (lane >> 3) + 8 * j; const LAS float* s = scr + (8 * c) * 33 + n;
;         const f32x4 w0 = (f32x4){s[0 * 33], s[1 * 33], s[2 * 33], s[3 * 33]}, w1 = (f32x4){s[4 * 33], s[5 * 33], s[6 * 33], s[7 * 33]};
;         const f32x4 f0 = w0 * g0, f1 = w1 * g1;
;         u32x4 o; o.x = cvt_pk_bf16(f0[0], f0[1]); o.y = cvt_pk_bf16(f0[2], f0[3]); o.z = cvt_pk_bf16(f1[0], f1[1]); o.w = cvt_pk_bf16(f1[2], f1[3]);
;         *(u32x4*)(WT + (size_t)(dst_row0 + n) * ldk + k0 + 8 * c) = o;
;         if (fg) {
;             float p1 = ((bflo(o.x) + bfhi(o.x)) + (bflo(o.y) + bfhi(o.y))) + ((bflo(o.z) + bfhi(o.z)) + (bflo(o.w) + bfhi(o.w)));
;             const f32x4 t0 = w0 * b0, t1 = w1 * b1;
;             float p2 = ((t0[0] + t0[1]) + (t0[2] + t0[3])) + ((t1[0] + t1[1]) + (t1[2] + t1[3]));
;             p1 += __shfl_xor(p1, 1); p2 += __shfl_xor(p2, 1); p1 += __shfl_xor(p1, 2); p2 += __shfl_xor(p2, 2); p1 += __shfl_xor(p1, 4); p2 += __shfl_xor(p2, 4);
;             if (c == 0) { atomicAdd(cs + dst_row0 + n, p1); atomicAdd(cs + NZ + dst_row0 + n, p2); }
;         } }
.LBB0_58:
	ds_read2_b32 v[18:19], v40 offset0:90 offset1:123
	s_waitcnt lgkmcnt(1)
	ds_read2_b32 v[20:21], v40 offset0:24 offset1:57
	ds_read2_b32 v[32:33], v40 offset0:222 offset1:255
	ds_read2_b32 v[34:35], v40 offset0:156 offset1:189
	s_and_b64 vcc, exec, s[4:5]
	s_waitcnt lgkmcnt(3)
	v_pk_mul_f32 v[16:17], v[16:17], v[18:19]
	s_waitcnt lgkmcnt(2)
	v_pk_mul_f32 v[14:15], v[14:15], v[20:21]
	s_waitcnt lgkmcnt(1)
	v_pk_mul_f32 v[36:37], v[12:13], v[32:33]
	s_waitcnt lgkmcnt(0)
	v_pk_mul_f32 v[12:13], v[10:11], v[34:35]
	v_cvt_pk_bf16_f32 v10, v14, v15
	v_add_u32_e32 v14, s10, v27
	v_ashrrev_i32_e32 v15, 31, v14
	v_cvt_pk_bf16_f32 v11, v16, v17
	v_mul_lo_u32 v16, s26, v15
	v_mul_lo_u32 v17, s27, v14
	v_mad_u64_u32 v[14:15], s[10:11], s26, v14, 0
	v_add3_u32 v15, v15, v16, v17
	v_lshl_add_u64 v[14:15], v[14:15], 1, v[30:31]
	v_cvt_pk_bf16_f32 v12, v12, v13
	v_cvt_pk_bf16_f32 v13, v36, v37
	global_store_dwordx4 v[14:15], v[10:13], off sc1
	s_cbranch_vccnz .LBB0_8
	v_lshlrev_b32_e32 v14, 16, v10
	v_and_b32_e32 v10, 0xffff0000, v10
	v_add_f32_e32 v10, v14, v10
	v_lshlrev_b32_e32 v14, 16, v11
	v_and_b32_e32 v11, 0xffff0000, v11
	v_add_f32_e32 v11, v14, v11
	s_waitcnt vmcnt(5)
	v_pk_mul_f32 v[4:5], v[4:5], v[32:33]
	v_pk_mul_f32 v[2:3], v[2:3], v[34:35]
	v_add_f32_e32 v10, v10, v11
	v_lshlrev_b32_e32 v11, 16, v12
	v_and_b32_e32 v12, 0xffff0000, v12
	v_add_f32_e32 v2, v2, v3
	v_add_f32_e32 v3, v4, v5
	v_and_b32_e32 v4, 64, v56
	v_add_f32_e32 v11, v11, v12
	v_lshlrev_b32_e32 v12, 16, v13
	v_and_b32_e32 v13, 0xffff0000, v13
	s_waitcnt vmcnt(4)
	v_pk_mul_f32 v[8:9], v[8:9], v[18:19]
	v_pk_mul_f32 v[6:7], v[6:7], v[20:21]
	v_add_f32_e32 v2, v2, v3
	v_xor_b32_e32 v3, 1, v56
	v_add_u32_e32 v4, 64, v4
	v_add_f32_e32 v12, v12, v13
	v_add_f32_e32 v6, v6, v7
	v_add_f32_e32 v7, v8, v9
	v_cmp_lt_i32_e32 vcc, v3, v4
	v_add_f32_e32 v11, v11, v12
	v_add_f32_e32 v6, v6, v7
	v_cndmask_b32_e32 v3, v56, v3, vcc
	v_add_f32_e32 v10, v10, v11
	v_add_f32_e32 v2, v6, v2
	v_lshlrev_b32_e32 v3, 2, v3
	ds_bpermute_b32 v5, v3, v10
	ds_bpermute_b32 v3, v3, v2
	s_waitcnt lgkmcnt(1)
	v_add_f32_e32 v5, v10, v5
	s_waitcnt lgkmcnt(0)
	v_add_f32_e32 v3, v2, v3
	v_xor_b32_e32 v2, 2, v56
	v_cmp_lt_i32_e32 vcc, v2, v4
	s_nop 1
	v_cndmask_b32_e32 v2, v56, v2, vcc
	v_lshlrev_b32_e32 v2, 2, v2
	ds_bpermute_b32 v6, v2, v5
	ds_bpermute_b32 v7, v2, v3
	s_waitcnt lgkmcnt(1)
	v_add_f32_e32 v2, v5, v6
	v_xor_b32_e32 v5, 4, v56
	v_cmp_lt_i32_e32 vcc, v5, v4
	s_waitcnt lgkmcnt(0)
	v_add_f32_e32 v3, v3, v7
	v_cndmask_b32_e32 v4, v56, v5, vcc
	v_lshlrev_b32_e32 v5, 2, v4
	ds_bpermute_b32 v4, v5, v2
	ds_bpermute_b32 v5, v5, v3
	s_and_saveexec_b64 s[4:5], s[0:1]
	s_cbranch_execz .LBB0_7
	v_lshlrev_b32_e32 v6, 2, v22
	s_waitcnt lgkmcnt(1)
	v_add_f32_e32 v2, v2, v4
	s_waitcnt lgkmcnt(0)
	v_add_f32_e32 v3, v3, v5
	global_atomic_add_f32 v6, v2, s[84:85] offset:96
	global_atomic_add_f32 v6, v3, s[86:87] offset:96
	s_branch .LBB0_7

; __device__ __forceinline__ unsigned cvt_pk_bf16(float lo, float hi) { unsigned r; asm volatile("v_cvt_pk_bf16_f32 %0, %1, %2" : "=v"(r) : "v"(lo), "v"(hi)); return r; }
; __global__ void __launch_bounds__(NTHREADS, 2) fwd_kernel(Params P) {
;     ...
;         for (size_t i = (size_t)gw * 64 + lane; i < (size_t)MPAD * D / 8; i += (size_t)NGW * 64) {
;             const size_t e = i * 8; const int r = (int)(e / D);
;             u32x4 w = (u32x4){0u, 0u, 0u, 0u};
;             if (r < MR) { const float* src = (r < MP) ? P.in[I_XP] + e : P.in[I_XS] + (e - (size_t)MP * D);
;                 const f32x4 a = __builtin_nontemporal_load((const f32x4*)src), b = __builtin_nontemporal_load((const f32x4*)(src + 4));
;                 w.x = cvt_pk_bf16(a[0], a[1]); w.y = cvt_pk_bf16(a[2], a[3]); w.z = cvt_pk_bf16(b[0], b[1]); w.w = cvt_pk_bf16(b[2], b[3]); }
;             *(u32x4*)(XB + e) = w;
.LBB0_65:
	s_or_b64 exec, exec, s[4:5]
	s_ashr_i32 s31, s30, 31
	v_lshlrev_b32_e32 v176, 4, v237
	v_mov_b32_e32 v177, 0
	s_ashr_i32 s87, s86, 31
	v_readlane_b32 s52, v254, 45
	v_readlane_b32 s53, v254, 46
	v_readlane_b32 s60, v254, 47
	v_readlane_b32 s61, v254, 48
	s_add_u32 s54, s92, 0xcca0000
	s_addc_u32 s55, s93, 0
	v_lshl_add_u32 v2, s34, 9, v178
	v_lshlrev_b32_e32 v3, 5, v2
	v_lshlrev_b32_e32 v4, 4, v2
	s_nop 4
	global_load_dwordx4 v[16:19], v3, s[52:53] nt
	global_load_dwordx4 v[20:23], v3, s[52:53] offset:16 nt
	s_add_u32 s56, s52, 0x400000
	s_addc_u32 s57, s53, 0
	global_load_dwordx4 v[24:27], v3, s[56:57] nt
	global_load_dwordx4 v[28:31], v3, s[56:57] offset:16 nt
	s_add_u32 s56, s52, 0x800000
	s_addc_u32 s57, s53, 0
	global_load_dwordx4 v[32:35], v3, s[56:57] nt
	global_load_dwordx4 v[36:39], v3, s[56:57] offset:16 nt
	s_add_u32 s56, s52, 0xc00000
	s_addc_u32 s57, s53, 0
	global_load_dwordx4 v[40:43], v3, s[56:57] nt
	global_load_dwordx4 v[44:47], v3, s[56:57] offset:16 nt
	s_add_u32 s56, s52, 0x1000000
	s_addc_u32 s57, s53, 0
	global_load_dwordx4 v[48:51], v3, s[56:57] nt
	global_load_dwordx4 v[52:55], v3, s[56:57] offset:16 nt
	s_add_u32 s56, s52, 0x1400000
	s_addc_u32 s57, s53, 0
	global_load_dwordx4 v[56:59], v3, s[56:57] nt
	global_load_dwordx4 v[60:63], v3, s[56:57] offset:16 nt
	s_add_u32 s56, s52, 0x1800000
	s_addc_u32 s57, s53, 0
	global_load_dwordx4 v[64:67], v3, s[56:57] nt
	global_load_dwordx4 v[68:71], v3, s[56:57] offset:16 nt
	s_add_u32 s56, s52, 0x1c00000
	s_addc_u32 s57, s53, 0
	global_load_dwordx4 v[72:75], v3, s[56:57] nt
	global_load_dwordx4 v[76:79], v3, s[56:57] offset:16 nt
	s_waitcnt vmcnt(14)
	v_cvt_pk_bf16_f32 v16, v16, v17
	v_cvt_pk_bf16_f32 v17, v18, v19
	v_cvt_pk_bf16_f32 v18, v20, v21
	v_cvt_pk_bf16_f32 v19, v22, v23
	global_store_dwordx4 v4, v[16:19], s[54:55] sc1
	s_waitcnt vmcnt(13)
	v_cvt_pk_bf16_f32 v24, v24, v25
	v_cvt_pk_bf16_f32 v25, v26, v27
	v_cvt_pk_bf16_f32 v26, v28, v29
	v_cvt_pk_bf16_f32 v27, v30, v31
	s_add_u32 s58, s54, 0x200000
	s_addc_u32 s59, s55, 0
	global_store_dwordx4 v4, v[24:27], s[58:59] sc1
	s_waitcnt vmcnt(12)
	v_cvt_pk_bf16_f32 v32, v32, v33
	v_cvt_pk_bf16_f32 v33, v34, v35
	v_cvt_pk_bf16_f32 v34, v36, v37
	v_cvt_pk_bf16_f32 v35, v38, v39
	s_add_u32 s58, s54, 0x400000
	s_addc_u32 s59, s55, 0
	global_store_dwordx4 v4, v[32:35], s[58:59] sc1
	s_waitcnt vmcnt(11)
	v_cvt_pk_bf16_f32 v40, v40, v41
	v_cvt_pk_bf16_f32 v41, v42, v43
	v_cvt_pk_bf16_f32 v42, v44, v45
	v_cvt_pk_bf16_f32 v43, v46, v47
	s_add_u32 s58, s54, 0x600000
	s_addc_u32 s59, s55, 0
	global_store_dwordx4 v4, v[40:43], s[58:59] sc1
	s_waitcnt vmcnt(10)
	v_cvt_pk_bf16_f32 v48, v48, v49
	v_cvt_pk_bf16_f32 v49, v50, v51
	v_cvt_pk_bf16_f32 v50, v52, v53
	v_cvt_pk_bf16_f32 v51, v54, v55
	s_add_u32 s58, s54, 0x800000
	s_addc_u32 s59, s55, 0
	global_store_dwordx4 v4, v[48:51], s[58:59] sc1
	s_waitcnt vmcnt(9)
	v_cvt_pk_bf16_f32 v56, v56, v57
	v_cvt_pk_bf16_f32 v57, v58, v59
	v_cvt_pk_bf16_f32 v58, v60, v61
	v_cvt_pk_bf16_f32 v59, v62, v63
	s_add_u32 s58, s54, 0xa00000
	s_addc_u32 s59, s55, 0
	global_store_dwordx4 v4, v[56:59], s[58:59] sc1
	s_waitcnt vmcnt(8)
	v_cvt_pk_bf16_f32 v64, v64, v65
	v_cvt_pk_bf16_f32 v65, v66, v67
	v_cvt_pk_bf16_f32 v66, v68, v69
	v_cvt_pk_bf16_f32 v67, v70, v71
	s_add_u32 s58, s54, 0xc00000
	s_addc_u32 s59, s55, 0
	global_store_dwordx4 v4, v[64:67], s[58:59] sc1
	s_waitcnt vmcnt(7)
	v_cvt_pk_bf16_f32 v72, v72, v73
	v_cvt_pk_bf16_f32 v73, v74, v75
	v_cvt_pk_bf16_f32 v74, v76, v77
	v_cvt_pk_bf16_f32 v75, v78, v79
	s_add_u32 s58, s54, 0xe00000
	s_addc_u32 s59, s55, 0
	global_store_dwordx4 v4, v[72:75], s[58:59] sc1
	s_add_u32 s56, s52, 0x2000000
	s_addc_u32 s57, s53, 0
	global_load_dwordx4 v[16:19], v3, s[56:57] nt
	global_load_dwordx4 v[20:23], v3, s[56:57] offset:16 nt
	s_add_u32 s56, s52, 0x2400000
	s_addc_u32 s57, s53, 0
	global_load_dwordx4 v[24:27], v3, s[56:57] nt
	global_load_dwordx4 v[28:31], v3, s[56:57] offset:16 nt
	s_add_u32 s56, s52, 0x2800000
	s_addc_u32 s57, s53, 0
	global_load_dwordx4 v[32:35], v3, s[56:57] nt
	global_load_dwordx4 v[36:39], v3, s[56:57] offset:16 nt
	s_add_u32 s56, s52, 0x2c00000
	s_addc_u32 s57, s53, 0
	global_load_dwordx4 v[40:43], v3, s[56:57] nt
	global_load_dwordx4 v[44:47], v3, s[56:57] offset:16 nt
	s_add_u32 s56, s52, 0x3000000
	s_addc_u32 s57, s53, 0
	global_load_dwordx4 v[48:51], v3, s[56:57] nt
	global_load_dwordx4 v[52:55], v3, s[56:57] offset:16 nt
	s_add_u32 s56, s52, 0x3400000
	s_addc_u32 s57, s53, 0
	global_load_dwordx4 v[56:59], v3, s[56:57] nt
	global_load_dwordx4 v[60:63], v3, s[56:57] offset:16 nt
	s_add_u32 s56, s52, 0x3800000
	s_addc_u32 s57, s53, 0
	global_load_dwordx4 v[64:67], v3, s[56:57] nt
	global_load_dwordx4 v[68:71], v3, s[56:57] offset:16 nt
	s_add_u32 s56, s52, 0x3c00000
	s_addc_u32 s57, s53, 0
	global_load_dwordx4 v[72:75], v3, s[56:57] nt
	global_load_dwordx4 v[76:79], v3, s[56:57] offset:16 nt
	s_waitcnt vmcnt(14)
	v_cvt_pk_bf16_f32 v16, v16, v17
	v_cvt_pk_bf16_f32 v17, v18, v19
	v_cvt_pk_bf16_f32 v18, v20, v21
	v_cvt_pk_bf16_f32 v19, v22, v23
	s_add_u32 s58, s54, 0x1000000
	s_addc_u32 s59, s55, 0
	global_store_dwordx4 v4, v[16:19], s[58:59] sc1
	s_waitcnt vmcnt(13)
	v_cvt_pk_bf16_f32 v24, v24, v25
	v_cvt_pk_bf16_f32 v25, v26, v27
	v_cvt_pk_bf16_f32 v26, v28, v29
	v_cvt_pk_bf16_f32 v27, v30, v31
	s_add_u32 s58, s54, 0x1200000
	s_addc_u32 s59, s55, 0
	global_store_dwordx4 v4, v[24:27], s[58:59] sc1
	s_waitcnt vmcnt(12)
	v_cvt_pk_bf16_f32 v32, v32, v33
	v_cvt_pk_bf16_f32 v33, v34, v35
	v_cvt_pk_bf16_f32 v34, v36, v37
	v_cvt_pk_bf16_f32 v35, v38, v39
	s_add_u32 s58, s54, 0x1400000
	s_addc_u32 s59, s55, 0
	global_store_dwordx4 v4, v[32:35], s[58:59] sc1
	s_waitcnt vmcnt(11)
	v_cvt_pk_bf16_f32 v40, v40, v41
	v_cvt_pk_bf16_f32 v41, v42, v43
	v_cvt_pk_bf16_f32 v42, v44, v45
	v_cvt_pk_bf16_f32 v43, v46, v47
	s_add_u32 s58, s54, 0x1600000
	s_addc_u32 s59, s55, 0
	global_store_dwordx4 v4, v[40:43], s[58:59] sc1
	s_waitcnt vmcnt(10)
	v_cvt_pk_bf16_f32 v48, v48, v49
	v_cvt_pk_bf16_f32 v49, v50, v51
	v_cvt_pk_bf16_f32 v50, v52, v53
	v_cvt_pk_bf16_f32 v51, v54, v55
	s_add_u32 s58, s54, 0x1800000
	s_addc_u32 s59, s55, 0
	global_store_dwordx4 v4, v[48:51], s[58:59] sc1
	s_waitcnt vmcnt(9)
	v_cvt_pk_bf16_f32 v56, v56, v57
	v_cvt_pk_bf16_f32 v57, v58, v59
	v_cvt_pk_bf16_f32 v58, v60, v61
	v_cvt_pk_bf16_f32 v59, v62, v63
	s_add_u32 s58, s54, 0x1a00000
	s_addc_u32 s59, s55, 0
	global_store_dwordx4 v4, v[56:59], s[58:59] sc1
	s_waitcnt vmcnt(8)
	v_cvt_pk_bf16_f32 v64, v64, v65
	v_cvt_pk_bf16_f32 v65, v66, v67
	v_cvt_pk_bf16_f32 v66, v68, v69
	v_cvt_pk_bf16_f32 v67, v70, v71
	s_add_u32 s58, s54, 0x1c00000
	s_addc_u32 s59, s55, 0
	global_store_dwordx4 v4, v[64:67], s[58:59] sc1
	s_waitcnt vmcnt(7)
	v_cvt_pk_bf16_f32 v72, v72, v73
	v_cvt_pk_bf16_f32 v73, v74, v75
	v_cvt_pk_bf16_f32 v74, v76, v77
	v_cvt_pk_bf16_f32 v75, v78, v79
	s_add_u32 s58, s54, 0x1e00000
	s_addc_u32 s59, s55, 0
	global_store_dwordx4 v4, v[72:75], s[58:59] sc1
	s_cmp_lt_u32 s34, 128
	s_cbranch_scc0 .Lxb_done
; __device__ __forceinline__ unsigned cvt_pk_bf16(float lo, float hi) { unsigned r; asm volatile("v_cvt_pk_bf16_f32 %0, %1, %2" : "=v"(r) : "v"(lo), "v"(hi)); return r; }
; __global__ void __launch_bounds__(NTHREADS, 2) fwd_kernel(Params P) {
;     ...
;             if (r < MR) { const float* src = (r < MP) ? P.in[I_XP] + e : P.in[I_XS] + (e - (size_t)MP * D);
;                 const f32x4 a = __builtin_nontemporal_load((const f32x4*)src), b = __builtin_nontemporal_load((const f32x4*)(src + 4));
;                 w.x = cvt_pk_bf16(a[0], a[1]); w.y = cvt_pk_bf16(a[2], a[3]); w.z = cvt_pk_bf16(b[0], b[1]); w.w = cvt_pk_bf16(b[2], b[3]); }
;             *(u32x4*)(XB + e) = w;
	s_add_u32 s58, s54, 0x2000000
	s_addc_u32 s59, s55, 0
	s_cmp_lt_u32 s34, 64
	s_cbranch_scc0 .Lxb_zero
	global_load_dwordx4 v[16:19], v3, s[60:61] nt
	global_load_dwordx4 v[20:23], v3, s[60:61] offset:16 nt
	s_waitcnt vmcnt(0)
	v_cvt_pk_bf16_f32 v16, v16, v17
	v_cvt_pk_bf16_f32 v17, v18, v19
	v_cvt_pk_bf16_f32 v18, v20, v21
	v_cvt_pk_bf16_f32 v19, v22, v23
	global_store_dwordx4 v4, v[16:19], s[58:59] sc1
	s_branch .Lxb_done
.Lxb_zero:
	s_nop 1
	v_mov_b32_e32 v16, 0
	v_mov_b32_e32 v17, 0
	v_mov_b32_e32 v18, 0
	v_mov_b32_e32 v19, 0
	global_store_dwordx4 v4, v[16:19], s[58:59] sc1

; __device__ __forceinline__ unsigned cvt_pk_bf16(float lo, float hi) { unsigned r; asm volatile("v_cvt_pk_bf16_f32 %0, %1, %2" : "=v"(r) : "v"(lo), "v"(hi)); return r; }
; __device__ __forceinline__ float siluf_(float x) { return x * sigmoidf_(x); }
; __device__ __forceinline__ f32x2 ln_stats(f32x2 sm) { const float mu = sm[0] * (1.f / D); const float var = fmaxf(sm[1] * (1.f / D) - mu * mu, 0.f); return (f32x2){mu, 1.0f / sqrtf(var + LN_EPS)}; }
;     __device__ __forceinline__ void operator()(const f32x4 (&acc)[2][2][4][2], const Unit& u, int wr, int wc, int fr, int fq) const {
;     ...
; #pragma unroll
;         for (int ai = 0; ai < 2; ++ai)
; #pragma unroll
;             for (int m = 0; m < 4; ++m) {
;                 const int r = row0 + ai * HALF + m * 16;
;                 bf16_t* rowp = H + (size_t)r * ldh + col0;
;                 f32x2 st = (f32x2){0.f, 1.f};
;                 if (rsum) st = ln_stats(*(const f32x2*)(rsum + 2 * (size_t)r));
;                 f32x4 v0, v1;
; #pragma unroll
;                 for (int j = 0; j < 4; ++j) {
;                     const float g0 = st[1] * (acc[ai][0][m][0][j] - st[0] * s1[0][0][j]) + s2[0][0][j], u0 = st[1] * (acc[ai][1][m][0][j] - st[0] * s1[1][0][j]) + s2[1][0][j];
;                     const float g1 = st[1] * (acc[ai][0][m][1][j] - st[0] * s1[0][1][j]) + s2[0][1][j], u1 = st[1] * (acc[ai][1][m][1][j] - st[0] * s1[1][1][j]) + s2[1][1][j];
;                     v0[j] = siluf_(g0) * u0; v1[j] = siluf_(g1) * u1;
;                 }
;                 u32x4 w; w.x = cvt_pk_bf16(v0[0], v0[1]); w.y = cvt_pk_bf16(v0[2], v0[3]); w.z = cvt_pk_bf16(v1[0], v1[1]); w.w = cvt_pk_bf16(v1[2], v1[3]);
;                 *(u32x4*)rowp = w;
.LBB0_158:
	v_mov_b32_e32 v154, v124
	v_mov_b32_e32 v155, v116
	v_pk_add_f32 v[154:155], v[154:155], 0 op_sel_hi:[1,0]
	v_mov_b32_e32 v156, v120
	v_mul_f32_e32 v116, 0xbfb8aa3b, v154
	v_exp_f32_e32 v116, v116
	v_mov_b32_e32 v157, v112
	v_pk_add_f32 v[156:157], v[156:157], 0 op_sel_hi:[1,0]
	v_lshl_or_b32 v140, s53, 7, v146
	v_add_f32_e32 v112, 1.0, v116
	v_rcp_f32_e32 v112, v112
	v_mul_f32_e32 v116, 0xbfb8aa3b, v156
	v_exp_f32_e32 v116, v116
	v_lshl_add_u32 v150, s18, 8, v144
	v_mul_f32_e32 v112, v154, v112
	v_mul_f32_e32 v124, v112, v155
	v_add_f32_e32 v112, 1.0, v116
	v_mov_b32_e32 v116, v125
	v_pk_add_f32 v[116:117], v[116:117], 0 op_sel_hi:[1,0]
	v_rcp_f32_e32 v120, v112
	v_mov_b32_e32 v112, v121
	v_mul_f32_e32 v121, 0xbfb8aa3b, v116
	v_exp_f32_e32 v121, v121
	v_pk_add_f32 v[112:113], v[112:113], 0 op_sel_hi:[1,0]
	v_mul_f32_e32 v120, v156, v120
	v_mul_f32_e32 v125, 0xbfb8aa3b, v112
	v_add_f32_e32 v121, 1.0, v121
	v_rcp_f32_e32 v121, v121
	v_exp_f32_e32 v125, v125
	v_mul_f32_e32 v151, v120, v157
	v_mov_b32_e32 v120, v122
	v_mul_f32_e32 v116, v116, v121
	v_mul_f32_e32 v154, v116, v117
	v_mov_b32_e32 v116, v126
	v_mov_b32_e32 v117, v118
	v_pk_add_f32 v[116:117], v[116:117], 0 op_sel_hi:[1,0]
	v_add_f32_e32 v125, 1.0, v125
	v_mul_f32_e32 v118, 0xbfb8aa3b, v116
	v_exp_f32_e32 v118, v118
	v_mov_b32_e32 v121, v114
	v_rcp_f32_e32 v125, v125
	v_pk_add_f32 v[120:121], v[120:121], 0 op_sel_hi:[1,0]
	v_add_f32_e32 v114, 1.0, v118
	v_rcp_f32_e32 v114, v114
	v_mul_f32_e32 v118, 0xbfb8aa3b, v120
	v_exp_f32_e32 v118, v118
	v_mul_f32_e32 v112, v112, v125
	v_mul_f32_e32 v122, v112, v113
	v_mul_f32_e32 v112, v116, v114
	v_mul_f32_e32 v116, v112, v117
	v_add_f32_e32 v112, 1.0, v118
	v_mov_b32_e32 v118, v127
	v_rcp_f32_e32 v117, v112
	v_pk_add_f32 v[112:113], v[118:119], 0 op_sel_hi:[1,0]
	v_mov_b32_e32 v114, v123
	v_pk_add_f32 v[114:115], v[114:115], 0 op_sel_hi:[1,0]
	v_mul_f32_e32 v118, 0xbfb8aa3b, v112
	v_exp_f32_e32 v118, v118
	v_mul_f32_e32 v119, 0xbfb8aa3b, v114
	v_exp_f32_e32 v119, v119
	v_ashrrev_i32_e32 v141, 31, v140
	v_add_f32_e32 v118, 1.0, v118
	v_rcp_f32_e32 v118, v118
	v_add_f32_e32 v119, 1.0, v119
	v_rcp_f32_e32 v119, v119
	v_mov_b64_e32 v[142:143], s[40:41]
	v_mul_f32_e32 v112, v112, v118
	v_mul_f32_e32 v113, v112, v113
	v_mul_f32_e32 v112, v114, v119
	v_mad_i64_i32 v[152:153], s[20:21], v150, s51, v[142:143]
	v_lshlrev_b64 v[140:141], 1, v[140:141]
	v_mul_f32_e32 v117, v120, v117
	v_mul_f32_e32 v115, v112, v115
	v_lshl_add_u64 v[152:153], v[152:153], 0, v[140:141]
	v_mul_f32_e32 v117, v117, v121
	v_cvt_pk_bf16_f32 v112, v124, v154
	v_cvt_pk_bf16_f32 v113, v116, v113
	v_cvt_pk_bf16_f32 v114, v151, v122
	v_cvt_pk_bf16_f32 v115, v117, v115
	global_store_dwordx4 v[152:153], v[112:115], off sc1
	v_mov_b32_e32 v116, v104
	v_mov_b32_e32 v117, v96
	v_mov_b32_e32 v114, v108
	v_mov_b32_e32 v115, v100
	v_pk_add_f32 v[114:115], v[114:115], 0 op_sel_hi:[1,0]
	v_pk_add_f32 v[116:117], v[116:117], 0 op_sel_hi:[1,0]
	v_mul_f32_e32 v100, 0xbfb8aa3b, v114
	v_exp_f32_e32 v100, v100
	v_or_b32_e32 v112, 16, v150
	v_mad_i64_i32 v[112:113], s[20:21], v112, s51, v[142:143]
	v_add_f32_e32 v96, 1.0, v100
	v_rcp_f32_e32 v96, v96
	v_mul_f32_e32 v100, 0xbfb8aa3b, v116
	v_exp_f32_e32 v100, v100
	v_lshl_add_u64 v[112:113], v[112:113], 0, v[140:141]
	v_mul_f32_e32 v96, v114, v96
	v_mul_f32_e32 v108, v96, v115
	v_add_f32_e32 v96, 1.0, v100
	v_mov_b32_e32 v100, v109
	v_pk_add_f32 v[100:101], v[100:101], 0 op_sel_hi:[1,0]
	v_rcp_f32_e32 v104, v96
	v_mov_b32_e32 v96, v105
	v_mul_f32_e32 v105, 0xbfb8aa3b, v100
	v_exp_f32_e32 v105, v105
	v_pk_add_f32 v[96:97], v[96:97], 0 op_sel_hi:[1,0]
	v_mul_f32_e32 v104, v116, v104
	v_mul_f32_e32 v109, 0xbfb8aa3b, v96
	v_add_f32_e32 v105, 1.0, v105
	v_rcp_f32_e32 v105, v105
	v_exp_f32_e32 v109, v109
	v_mul_f32_e32 v114, v104, v117
	v_mov_b32_e32 v104, v106
	v_mul_f32_e32 v100, v100, v105
	v_mul_f32_e32 v115, v100, v101
	v_mov_b32_e32 v100, v110
	v_mov_b32_e32 v101, v102
	v_pk_add_f32 v[100:101], v[100:101], 0 op_sel_hi:[1,0]
	v_add_f32_e32 v109, 1.0, v109
	v_mul_f32_e32 v102, 0xbfb8aa3b, v100
	v_exp_f32_e32 v102, v102
	v_mov_b32_e32 v105, v98
	v_rcp_f32_e32 v109, v109
	v_pk_add_f32 v[104:105], v[104:105], 0 op_sel_hi:[1,0]
	v_add_f32_e32 v98, 1.0, v102
	v_rcp_f32_e32 v98, v98
	v_mul_f32_e32 v102, 0xbfb8aa3b, v104
	v_exp_f32_e32 v102, v102
	v_mul_f32_e32 v96, v96, v109
	v_mul_f32_e32 v106, v96, v97
	v_mul_f32_e32 v96, v100, v98
	v_mul_f32_e32 v100, v96, v101
	v_add_f32_e32 v96, 1.0, v102
	v_mov_b32_e32 v102, v111
	v_rcp_f32_e32 v101, v96
	v_pk_add_f32 v[96:97], v[102:103], 0 op_sel_hi:[1,0]
	v_mov_b32_e32 v98, v107
	v_pk_add_f32 v[98:99], v[98:99], 0 op_sel_hi:[1,0]
	v_mul_f32_e32 v102, 0xbfb8aa3b, v96
	v_exp_f32_e32 v102, v102
	v_mul_f32_e32 v103, 0xbfb8aa3b, v98
	v_exp_f32_e32 v103, v103
	v_mul_f32_e32 v101, v104, v101
	v_add_f32_e32 v102, 1.0, v102
	v_rcp_f32_e32 v102, v102
	v_add_f32_e32 v103, 1.0, v103
	v_rcp_f32_e32 v103, v103
	v_mul_f32_e32 v101, v101, v105
	v_mul_f32_e32 v96, v96, v102
	v_mul_f32_e32 v97, v96, v97
	v_mul_f32_e32 v96, v98, v103
	v_mul_f32_e32 v99, v96, v99
	v_cvt_pk_bf16_f32 v96, v108, v115
	v_cvt_pk_bf16_f32 v97, v100, v97
	v_cvt_pk_bf16_f32 v98, v114, v106
	v_cvt_pk_bf16_f32 v99, v101, v99
	global_store_dwordx4 v[112:113], v[96:99], off sc1
	v_mov_b32_e32 v100, v88
	v_mov_b32_e32 v101, v80
	v_mov_b32_e32 v98, v92
	v_mov_b32_e32 v99, v84
	v_pk_add_f32 v[98:99], v[98:99], 0 op_sel_hi:[1,0]
	v_pk_add_f32 v[100:101], v[100:101], 0 op_sel_hi:[1,0]
	v_mul_f32_e32 v84, 0xbfb8aa3b, v98
	v_exp_f32_e32 v84, v84
	v_or_b32_e32 v96, 32, v150
	v_mad_i64_i32 v[96:97], s[20:21], v96, s51, v[142:143]
	v_add_f32_e32 v80, 1.0, v84
; __device__ __forceinline__ unsigned cvt_pk_bf16(float lo, float hi) { unsigned r; asm volatile("v_cvt_pk_bf16_f32 %0, %1, %2" : "=v"(r) : "v"(lo), "v"(hi)); return r; }
; __device__ __forceinline__ float siluf_(float x) { return x * sigmoidf_(x); }
; __device__ __forceinline__ f32x2 ln_stats(f32x2 sm) { const float mu = sm[0] * (1.f / D); const float var = fmaxf(sm[1] * (1.f / D) - mu * mu, 0.f); return (f32x2){mu, 1.0f / sqrtf(var + LN_EPS)}; }
;     __device__ __forceinline__ void operator()(const f32x4 (&acc)[2][2][4][2], const Unit& u, int wr, int wc, int fr, int fq) const {
;     ...
; #pragma unroll
;         for (int ai = 0; ai < 2; ++ai)
; #pragma unroll
;             for (int m = 0; m < 4; ++m) {
;                 const int r = row0 + ai * HALF + m * 16;
;                 bf16_t* rowp = H + (size_t)r * ldh + col0;
;                 f32x2 st = (f32x2){0.f, 1.f};
;                 if (rsum) st = ln_stats(*(const f32x2*)(rsum + 2 * (size_t)r));
;                 f32x4 v0, v1;
; #pragma unroll
;                 for (int j = 0; j < 4; ++j) {
;                     const float g0 = st[1] * (acc[ai][0][m][0][j] - st[0] * s1[0][0][j]) + s2[0][0][j], u0 = st[1] * (acc[ai][1][m][0][j] - st[0] * s1[1][0][j]) + s2[1][0][j];
;                     const float g1 = st[1] * (acc[ai][0][m][1][j] - st[0] * s1[0][1][j]) + s2[0][1][j], u1 = st[1] * (acc[ai][1][m][1][j] - st[0] * s1[1][1][j]) + s2[1][1][j];
;                     v0[j] = siluf_(g0) * u0; v1[j] = siluf_(g1) * u1;
;                 }
;                 u32x4 w; w.x = cvt_pk_bf16(v0[0], v0[1]); w.y = cvt_pk_bf16(v0[2], v0[3]); w.z = cvt_pk_bf16(v1[0], v1[1]); w.w = cvt_pk_bf16(v1[2], v1[3]);
;                 *(u32x4*)rowp = w;
	v_rcp_f32_e32 v80, v80
	v_mul_f32_e32 v84, 0xbfb8aa3b, v100
	v_exp_f32_e32 v84, v84
	v_lshl_add_u64 v[96:97], v[96:97], 0, v[140:141]
	v_mul_f32_e32 v80, v98, v80
	v_mul_f32_e32 v92, v80, v99
	v_add_f32_e32 v80, 1.0, v84
	v_mov_b32_e32 v84, v93
	v_pk_add_f32 v[84:85], v[84:85], 0 op_sel_hi:[1,0]
	v_rcp_f32_e32 v88, v80
	v_mov_b32_e32 v80, v89
	v_mul_f32_e32 v89, 0xbfb8aa3b, v84
	v_exp_f32_e32 v89, v89
	v_pk_add_f32 v[80:81], v[80:81], 0 op_sel_hi:[1,0]
	v_mul_f32_e32 v88, v100, v88
	v_mul_f32_e32 v93, 0xbfb8aa3b, v80
	v_add_f32_e32 v89, 1.0, v89
	v_rcp_f32_e32 v89, v89
	v_exp_f32_e32 v93, v93
	v_mul_f32_e32 v98, v88, v101
	v_mov_b32_e32 v88, v90
	v_mul_f32_e32 v84, v84, v89
	v_mul_f32_e32 v99, v84, v85
	v_mov_b32_e32 v84, v94
	v_mov_b32_e32 v85, v86
	v_pk_add_f32 v[84:85], v[84:85], 0 op_sel_hi:[1,0]
	v_add_f32_e32 v93, 1.0, v93
	v_mul_f32_e32 v86, 0xbfb8aa3b, v84
	v_exp_f32_e32 v86, v86
	v_mov_b32_e32 v89, v82
	v_rcp_f32_e32 v93, v93
	v_pk_add_f32 v[88:89], v[88:89], 0 op_sel_hi:[1,0]
	v_add_f32_e32 v82, 1.0, v86
	v_rcp_f32_e32 v82, v82
	v_mul_f32_e32 v86, 0xbfb8aa3b, v88
	v_exp_f32_e32 v86, v86
	v_mul_f32_e32 v80, v80, v93
	v_mul_f32_e32 v90, v80, v81
	v_mul_f32_e32 v80, v84, v82
	v_mul_f32_e32 v84, v80, v85
	v_add_f32_e32 v80, 1.0, v86
	v_mov_b32_e32 v86, v95
	v_rcp_f32_e32 v85, v80
	v_pk_add_f32 v[80:81], v[86:87], 0 op_sel_hi:[1,0]
	v_mov_b32_e32 v82, v91
	v_pk_add_f32 v[82:83], v[82:83], 0 op_sel_hi:[1,0]
	v_mul_f32_e32 v86, 0xbfb8aa3b, v80
	v_exp_f32_e32 v86, v86
	v_mul_f32_e32 v87, 0xbfb8aa3b, v82
	v_exp_f32_e32 v87, v87
	v_mul_f32_e32 v85, v88, v85
	v_add_f32_e32 v86, 1.0, v86
	v_rcp_f32_e32 v86, v86
	v_add_f32_e32 v87, 1.0, v87
	v_rcp_f32_e32 v87, v87
	v_mul_f32_e32 v85, v85, v89
	v_mul_f32_e32 v80, v80, v86
	v_mul_f32_e32 v81, v80, v81
	v_mul_f32_e32 v80, v82, v87
	v_mul_f32_e32 v83, v80, v83
	v_cvt_pk_bf16_f32 v80, v92, v99
	v_cvt_pk_bf16_f32 v81, v84, v81
	v_cvt_pk_bf16_f32 v82, v98, v90
	v_cvt_pk_bf16_f32 v83, v85, v83
	global_store_dwordx4 v[96:97], v[80:83], off sc1
	v_mov_b32_e32 v84, v72
	v_mov_b32_e32 v85, v64
	v_mov_b32_e32 v82, v76
	v_mov_b32_e32 v83, v68
	v_pk_add_f32 v[82:83], v[82:83], 0 op_sel_hi:[1,0]
	v_pk_add_f32 v[84:85], v[84:85], 0 op_sel_hi:[1,0]
	v_mul_f32_e32 v68, 0xbfb8aa3b, v82
	v_exp_f32_e32 v68, v68
	v_or_b32_e32 v80, 48, v150
	v_mad_i64_i32 v[80:81], s[20:21], v80, s51, v[142:143]
	v_add_f32_e32 v64, 1.0, v68
	v_rcp_f32_e32 v64, v64
	v_mul_f32_e32 v68, 0xbfb8aa3b, v84
	v_exp_f32_e32 v68, v68
	v_lshl_add_u64 v[80:81], v[80:81], 0, v[140:141]
	v_mul_f32_e32 v64, v82, v64
	v_mul_f32_e32 v76, v64, v83
	v_add_f32_e32 v64, 1.0, v68
	v_mov_b32_e32 v68, v77
	v_pk_add_f32 v[68:69], v[68:69], 0 op_sel_hi:[1,0]
	v_rcp_f32_e32 v72, v64
	v_mov_b32_e32 v64, v73
	v_mul_f32_e32 v73, 0xbfb8aa3b, v68
	v_exp_f32_e32 v73, v73
	v_pk_add_f32 v[64:65], v[64:65], 0 op_sel_hi:[1,0]
	v_mul_f32_e32 v72, v84, v72
	v_mul_f32_e32 v77, 0xbfb8aa3b, v64
	v_add_f32_e32 v73, 1.0, v73
	v_rcp_f32_e32 v73, v73
	v_exp_f32_e32 v77, v77
	v_mul_f32_e32 v82, v72, v85
	v_mov_b32_e32 v72, v74
	v_mul_f32_e32 v68, v68, v73
	v_mul_f32_e32 v83, v68, v69
	v_mov_b32_e32 v68, v78
	v_mov_b32_e32 v69, v70
	v_pk_add_f32 v[68:69], v[68:69], 0 op_sel_hi:[1,0]
	v_add_f32_e32 v77, 1.0, v77
	v_mul_f32_e32 v70, 0xbfb8aa3b, v68
	v_exp_f32_e32 v70, v70
	v_mov_b32_e32 v73, v66
	v_rcp_f32_e32 v77, v77
	v_pk_add_f32 v[72:73], v[72:73], 0 op_sel_hi:[1,0]
	v_add_f32_e32 v66, 1.0, v70
	v_rcp_f32_e32 v66, v66
	v_mul_f32_e32 v70, 0xbfb8aa3b, v72
	v_exp_f32_e32 v70, v70
	v_mul_f32_e32 v64, v64, v77
	v_mul_f32_e32 v74, v64, v65
	v_mul_f32_e32 v64, v68, v66
	v_mul_f32_e32 v68, v64, v69
	v_add_f32_e32 v64, 1.0, v70
	v_mov_b32_e32 v70, v79
	v_rcp_f32_e32 v69, v64
	v_pk_add_f32 v[64:65], v[70:71], 0 op_sel_hi:[1,0]
	v_mov_b32_e32 v66, v75
	v_pk_add_f32 v[66:67], v[66:67], 0 op_sel_hi:[1,0]
	v_mul_f32_e32 v70, 0xbfb8aa3b, v64
	v_exp_f32_e32 v70, v70
	v_mul_f32_e32 v71, 0xbfb8aa3b, v66
	v_exp_f32_e32 v71, v71
	v_mul_f32_e32 v69, v72, v69
	v_add_f32_e32 v70, 1.0, v70
	v_rcp_f32_e32 v70, v70
	v_add_f32_e32 v71, 1.0, v71
	v_rcp_f32_e32 v71, v71
	v_mul_f32_e32 v69, v69, v73
	v_mul_f32_e32 v64, v64, v70
	v_mul_f32_e32 v65, v64, v65
	v_mul_f32_e32 v64, v66, v71
	v_mul_f32_e32 v67, v64, v67
	v_cvt_pk_bf16_f32 v64, v76, v83
	v_cvt_pk_bf16_f32 v65, v68, v65
	v_cvt_pk_bf16_f32 v66, v82, v74
	v_cvt_pk_bf16_f32 v67, v69, v67
	global_store_dwordx4 v[80:81], v[64:67], off sc1
	v_mov_b32_e32 v68, v56
	v_mov_b32_e32 v69, v48
	v_mov_b32_e32 v66, v60
	v_mov_b32_e32 v67, v52
	v_pk_add_f32 v[66:67], v[66:67], 0 op_sel_hi:[1,0]
	v_pk_add_f32 v[68:69], v[68:69], 0 op_sel_hi:[1,0]
	v_mul_f32_e32 v52, 0xbfb8aa3b, v66
	v_exp_f32_e32 v52, v52
	v_add_u32_e32 v64, 0x80, v150
	v_mad_i64_i32 v[64:65], s[20:21], v64, s51, v[142:143]
	v_add_f32_e32 v48, 1.0, v52
	v_rcp_f32_e32 v48, v48
	v_mul_f32_e32 v52, 0xbfb8aa3b, v68
	v_exp_f32_e32 v52, v52
	v_lshl_add_u64 v[64:65], v[64:65], 0, v[140:141]
	v_mul_f32_e32 v48, v66, v48
	v_mul_f32_e32 v60, v48, v67
	v_add_f32_e32 v48, 1.0, v52
	v_mov_b32_e32 v52, v61
	v_pk_add_f32 v[52:53], v[52:53], 0 op_sel_hi:[1,0]
	v_rcp_f32_e32 v56, v48
	v_mov_b32_e32 v48, v57
	v_mul_f32_e32 v57, 0xbfb8aa3b, v52
	v_exp_f32_e32 v57, v57
	v_pk_add_f32 v[48:49], v[48:49], 0 op_sel_hi:[1,0]
	v_mul_f32_e32 v56, v68, v56
	v_mul_f32_e32 v61, 0xbfb8aa3b, v48
	v_add_f32_e32 v57, 1.0, v57
	v_rcp_f32_e32 v57, v57
	v_exp_f32_e32 v61, v61
	v_mul_f32_e32 v66, v56, v69
	v_mov_b32_e32 v56, v58
	v_mul_f32_e32 v52, v52, v57
	v_mul_f32_e32 v67, v52, v53
	v_mov_b32_e32 v52, v62
	v_mov_b32_e32 v53, v54
	v_pk_add_f32 v[52:53], v[52:53], 0 op_sel_hi:[1,0]
	v_add_f32_e32 v61, 1.0, v61
	v_mul_f32_e32 v54, 0xbfb8aa3b, v52
; __device__ __forceinline__ unsigned cvt_pk_bf16(float lo, float hi) { unsigned r; asm volatile("v_cvt_pk_bf16_f32 %0, %1, %2" : "=v"(r) : "v"(lo), "v"(hi)); return r; }
; __device__ __forceinline__ float siluf_(float x) { return x * sigmoidf_(x); }
; __device__ __forceinline__ f32x2 ln_stats(f32x2 sm) { const float mu = sm[0] * (1.f / D); const float var = fmaxf(sm[1] * (1.f / D) - mu * mu, 0.f); return (f32x2){mu, 1.0f / sqrtf(var + LN_EPS)}; }
;     __device__ __forceinline__ void operator()(const f32x4 (&acc)[2][2][4][2], const Unit& u, int wr, int wc, int fr, int fq) const {
;     ...
; #pragma unroll
;         for (int ai = 0; ai < 2; ++ai)
; #pragma unroll
;             for (int m = 0; m < 4; ++m) {
;                 const int r = row0 + ai * HALF + m * 16;
;                 bf16_t* rowp = H + (size_t)r * ldh + col0;
;                 f32x2 st = (f32x2){0.f, 1.f};
;                 if (rsum) st = ln_stats(*(const f32x2*)(rsum + 2 * (size_t)r));
;                 f32x4 v0, v1;
; #pragma unroll
;                 for (int j = 0; j < 4; ++j) {
;                     const float g0 = st[1] * (acc[ai][0][m][0][j] - st[0] * s1[0][0][j]) + s2[0][0][j], u0 = st[1] * (acc[ai][1][m][0][j] - st[0] * s1[1][0][j]) + s2[1][0][j];
;                     const float g1 = st[1] * (acc[ai][0][m][1][j] - st[0] * s1[0][1][j]) + s2[0][1][j], u1 = st[1] * (acc[ai][1][m][1][j] - st[0] * s1[1][1][j]) + s2[1][1][j];
;                     v0[j] = siluf_(g0) * u0; v1[j] = siluf_(g1) * u1;
;                 }
;                 u32x4 w; w.x = cvt_pk_bf16(v0[0], v0[1]); w.y = cvt_pk_bf16(v0[2], v0[3]); w.z = cvt_pk_bf16(v1[0], v1[1]); w.w = cvt_pk_bf16(v1[2], v1[3]);
;                 *(u32x4*)rowp = w;
	v_exp_f32_e32 v54, v54
	v_mov_b32_e32 v57, v50
	v_rcp_f32_e32 v61, v61
	v_pk_add_f32 v[56:57], v[56:57], 0 op_sel_hi:[1,0]
	v_add_f32_e32 v50, 1.0, v54
	v_rcp_f32_e32 v50, v50
	v_mul_f32_e32 v54, 0xbfb8aa3b, v56
	v_exp_f32_e32 v54, v54
	v_mul_f32_e32 v48, v48, v61
	v_mul_f32_e32 v58, v48, v49
	v_mul_f32_e32 v48, v52, v50
	v_mul_f32_e32 v52, v48, v53
	v_add_f32_e32 v48, 1.0, v54
	v_mov_b32_e32 v54, v63
	v_rcp_f32_e32 v53, v48
	v_pk_add_f32 v[48:49], v[54:55], 0 op_sel_hi:[1,0]
	v_mov_b32_e32 v50, v59
	v_pk_add_f32 v[50:51], v[50:51], 0 op_sel_hi:[1,0]
	v_mul_f32_e32 v54, 0xbfb8aa3b, v48
	v_exp_f32_e32 v54, v54
	v_mul_f32_e32 v55, 0xbfb8aa3b, v50
	v_exp_f32_e32 v55, v55
	v_mul_f32_e32 v53, v56, v53
	v_add_f32_e32 v54, 1.0, v54
	v_rcp_f32_e32 v54, v54
	v_add_f32_e32 v55, 1.0, v55
	v_rcp_f32_e32 v55, v55
	v_mul_f32_e32 v53, v53, v57
	v_mul_f32_e32 v48, v48, v54
	v_mul_f32_e32 v49, v48, v49
	v_mul_f32_e32 v48, v50, v55
	v_mul_f32_e32 v51, v48, v51
	v_cvt_pk_bf16_f32 v48, v60, v67
	v_cvt_pk_bf16_f32 v49, v52, v49
	v_cvt_pk_bf16_f32 v50, v66, v58
	v_cvt_pk_bf16_f32 v51, v53, v51
	global_store_dwordx4 v[64:65], v[48:51], off sc1
	v_mov_b32_e32 v52, v40
	v_mov_b32_e32 v53, v32
	v_mov_b32_e32 v50, v44
	v_mov_b32_e32 v51, v36
	v_pk_add_f32 v[50:51], v[50:51], 0 op_sel_hi:[1,0]
	v_pk_add_f32 v[52:53], v[52:53], 0 op_sel_hi:[1,0]
	v_mul_f32_e32 v36, 0xbfb8aa3b, v50
	v_exp_f32_e32 v36, v36
	v_add_u32_e32 v48, 0x90, v150
	v_mad_i64_i32 v[48:49], s[20:21], v48, s51, v[142:143]
	v_add_f32_e32 v32, 1.0, v36
	v_rcp_f32_e32 v32, v32
	v_mul_f32_e32 v36, 0xbfb8aa3b, v52
	v_exp_f32_e32 v36, v36
	v_lshl_add_u64 v[48:49], v[48:49], 0, v[140:141]
	v_mul_f32_e32 v32, v50, v32
	v_mul_f32_e32 v44, v32, v51
	v_add_f32_e32 v32, 1.0, v36
	v_mov_b32_e32 v36, v45
	v_pk_add_f32 v[36:37], v[36:37], 0 op_sel_hi:[1,0]
	v_rcp_f32_e32 v40, v32
	v_mov_b32_e32 v32, v41
	v_mul_f32_e32 v41, 0xbfb8aa3b, v36
	v_exp_f32_e32 v41, v41
	v_pk_add_f32 v[32:33], v[32:33], 0 op_sel_hi:[1,0]
	v_mul_f32_e32 v40, v52, v40
	v_mul_f32_e32 v45, 0xbfb8aa3b, v32
	v_add_f32_e32 v41, 1.0, v41
	v_rcp_f32_e32 v41, v41
	v_exp_f32_e32 v45, v45
	v_mul_f32_e32 v50, v40, v53
	v_mov_b32_e32 v40, v42
	v_mul_f32_e32 v36, v36, v41
	v_mul_f32_e32 v51, v36, v37
	v_mov_b32_e32 v36, v46
	v_mov_b32_e32 v37, v38
	v_pk_add_f32 v[36:37], v[36:37], 0 op_sel_hi:[1,0]
	v_add_f32_e32 v45, 1.0, v45
	v_mul_f32_e32 v38, 0xbfb8aa3b, v36
	v_exp_f32_e32 v38, v38
	v_mov_b32_e32 v41, v34
	v_rcp_f32_e32 v45, v45
	v_pk_add_f32 v[40:41], v[40:41], 0 op_sel_hi:[1,0]
	v_add_f32_e32 v34, 1.0, v38
	v_rcp_f32_e32 v34, v34
	v_mul_f32_e32 v38, 0xbfb8aa3b, v40
	v_exp_f32_e32 v38, v38
	v_mul_f32_e32 v32, v32, v45
	v_mul_f32_e32 v42, v32, v33
	v_mul_f32_e32 v32, v36, v34
	v_mul_f32_e32 v36, v32, v37
	v_add_f32_e32 v32, 1.0, v38
	v_mov_b32_e32 v38, v47
	v_rcp_f32_e32 v37, v32
	v_pk_add_f32 v[32:33], v[38:39], 0 op_sel_hi:[1,0]
	v_mov_b32_e32 v34, v43
	v_pk_add_f32 v[34:35], v[34:35], 0 op_sel_hi:[1,0]
	v_mul_f32_e32 v38, 0xbfb8aa3b, v32
	v_exp_f32_e32 v38, v38
	v_mul_f32_e32 v39, 0xbfb8aa3b, v34
	v_exp_f32_e32 v39, v39
	v_mul_f32_e32 v37, v40, v37
	v_add_f32_e32 v38, 1.0, v38
	v_rcp_f32_e32 v38, v38
	v_add_f32_e32 v39, 1.0, v39
	v_rcp_f32_e32 v39, v39
	v_mul_f32_e32 v37, v37, v41
	v_mul_f32_e32 v32, v32, v38
	v_mul_f32_e32 v33, v32, v33
	v_mul_f32_e32 v32, v34, v39
	v_mul_f32_e32 v35, v32, v35
	v_cvt_pk_bf16_f32 v32, v44, v51
	v_cvt_pk_bf16_f32 v33, v36, v33
	v_cvt_pk_bf16_f32 v34, v50, v42
	v_cvt_pk_bf16_f32 v35, v37, v35
	global_store_dwordx4 v[48:49], v[32:35], off sc1
	v_mov_b32_e32 v36, v24
	v_mov_b32_e32 v37, v16
	v_mov_b32_e32 v34, v28
	v_mov_b32_e32 v35, v20
	v_pk_add_f32 v[34:35], v[34:35], 0 op_sel_hi:[1,0]
	v_pk_add_f32 v[36:37], v[36:37], 0 op_sel_hi:[1,0]
	v_mul_f32_e32 v20, 0xbfb8aa3b, v34
	v_exp_f32_e32 v20, v20
	v_add_u32_e32 v32, 0xa0, v150
	v_mad_i64_i32 v[32:33], s[20:21], v32, s51, v[142:143]
	v_add_f32_e32 v16, 1.0, v20
	v_rcp_f32_e32 v16, v16
	v_mul_f32_e32 v20, 0xbfb8aa3b, v36
	v_exp_f32_e32 v20, v20
	v_lshl_add_u64 v[32:33], v[32:33], 0, v[140:141]
	v_mul_f32_e32 v16, v34, v16
	v_mul_f32_e32 v28, v16, v35
	v_add_f32_e32 v16, 1.0, v20
	v_mov_b32_e32 v20, v29
; __device__ __forceinline__ unsigned cvt_pk_bf16(float lo, float hi) { unsigned r; asm volatile("v_cvt_pk_bf16_f32 %0, %1, %2" : "=v"(r) : "v"(lo), "v"(hi)); return r; }
; __device__ __forceinline__ float siluf_(float x) { return x * sigmoidf_(x); }
; template <class Sched, class Epi, bool ALIGN_EPI, bool SP2>
; __device__ __forceinline__ void gemm_phase(LAS unsigned char* lds, const int K, const int lda, const int ldb, const Sched& S, const Epi& E) {
;     ...
;         if constexpr (ALIGN_EPI) { if (wr == 0) PG8_BAR; }
;         E(acc, cur, wr, wc, fr, fq);
;         if (!has_next) break;
;         bool keep = false;
;         if constexpr (Epi::CAN_KEEP) keep = (cur.kind < 2);
;         if (!keep) {
; #pragma unroll
;         for (int a = 0; a < 2; ++a)
; #pragma unroll
;             for (int b = 0; b < 2; ++b)
; #pragma unroll
;                 for (int m = 0; m < 4; ++m)
; #pragma unroll
;                     for (int n = 0; n < 2; ++n) acc[a][b][m][n] = (f32x4){0.f, 0.f, 0.f, 0.f};
;         }
;         cur = nxt; cA = nA; cB = nB; ++ui;
;         if constexpr (ALIGN_EPI) { if (wr == 1) PG8_BAR; }
;     __device__ __forceinline__ void operator()(const f32x4 (&acc)[2][2][4][2], const Unit& u, int wr, int wc, int fr, int fq) const {
;     ...
; #pragma unroll
;         for (int ai = 0; ai < 2; ++ai)
; #pragma unroll
;             for (int m = 0; m < 4; ++m) {
;                 const int r = row0 + ai * HALF + m * 16;
;                 bf16_t* rowp = H + (size_t)r * ldh + col0;
;                 f32x2 st = (f32x2){0.f, 1.f};
;                 if (rsum) st = ln_stats(*(const f32x2*)(rsum + 2 * (size_t)r));
;                 f32x4 v0, v1;
; #pragma unroll
;                 for (int j = 0; j < 4; ++j) {
;                     const float g0 = st[1] * (acc[ai][0][m][0][j] - st[0] * s1[0][0][j]) + s2[0][0][j], u0 = st[1] * (acc[ai][1][m][0][j] - st[0] * s1[1][0][j]) + s2[1][0][j];
;                     const float g1 = st[1] * (acc[ai][0][m][1][j] - st[0] * s1[0][1][j]) + s2[0][1][j], u1 = st[1] * (acc[ai][1][m][1][j] - st[0] * s1[1][1][j]) + s2[1][1][j];
;                     v0[j] = siluf_(g0) * u0; v1[j] = siluf_(g1) * u1;
;                 }
;                 u32x4 w; w.x = cvt_pk_bf16(v0[0], v0[1]); w.y = cvt_pk_bf16(v0[2], v0[3]); w.z = cvt_pk_bf16(v1[0], v1[1]); w.w = cvt_pk_bf16(v1[2], v1[3]);
;                 *(u32x4*)rowp = w;
	v_pk_add_f32 v[20:21], v[20:21], 0 op_sel_hi:[1,0]
	v_rcp_f32_e32 v24, v16
	v_mov_b32_e32 v16, v25
	v_mul_f32_e32 v25, 0xbfb8aa3b, v20
	v_exp_f32_e32 v25, v25
	v_pk_add_f32 v[16:17], v[16:17], 0 op_sel_hi:[1,0]
	v_mul_f32_e32 v24, v36, v24
	v_mul_f32_e32 v29, 0xbfb8aa3b, v16
	v_add_f32_e32 v25, 1.0, v25
	v_rcp_f32_e32 v25, v25
	v_exp_f32_e32 v29, v29
	v_mul_f32_e32 v34, v24, v37
	v_mov_b32_e32 v24, v26
	v_mul_f32_e32 v20, v20, v25
	v_mul_f32_e32 v35, v20, v21
	v_mov_b32_e32 v20, v30
	v_mov_b32_e32 v21, v22
	v_pk_add_f32 v[20:21], v[20:21], 0 op_sel_hi:[1,0]
	v_add_f32_e32 v29, 1.0, v29
	v_mul_f32_e32 v22, 0xbfb8aa3b, v20
	v_exp_f32_e32 v22, v22
	v_mov_b32_e32 v25, v18
	v_rcp_f32_e32 v29, v29
	v_pk_add_f32 v[24:25], v[24:25], 0 op_sel_hi:[1,0]
	v_add_f32_e32 v18, 1.0, v22
	v_rcp_f32_e32 v18, v18
	v_mul_f32_e32 v22, 0xbfb8aa3b, v24
	v_exp_f32_e32 v22, v22
	v_mul_f32_e32 v16, v16, v29
	v_mul_f32_e32 v26, v16, v17
	v_mul_f32_e32 v16, v20, v18
	v_mul_f32_e32 v20, v16, v21
	v_add_f32_e32 v16, 1.0, v22
	v_mov_b32_e32 v22, v31
	v_rcp_f32_e32 v21, v16
	v_pk_add_f32 v[16:17], v[22:23], 0 op_sel_hi:[1,0]
	v_mov_b32_e32 v18, v27
	v_pk_add_f32 v[18:19], v[18:19], 0 op_sel_hi:[1,0]
	v_mul_f32_e32 v22, 0xbfb8aa3b, v16
	v_exp_f32_e32 v22, v22
	v_mul_f32_e32 v23, 0xbfb8aa3b, v18
	v_exp_f32_e32 v23, v23
	v_mul_f32_e32 v21, v24, v21
	v_add_f32_e32 v22, 1.0, v22
	v_rcp_f32_e32 v22, v22
	v_add_f32_e32 v23, 1.0, v23
	v_rcp_f32_e32 v23, v23
	v_mul_f32_e32 v21, v21, v25
	v_mul_f32_e32 v16, v16, v22
	v_mul_f32_e32 v17, v16, v17
	v_mul_f32_e32 v16, v18, v23
	v_mul_f32_e32 v19, v16, v19
	v_cvt_pk_bf16_f32 v16, v28, v35
	v_cvt_pk_bf16_f32 v17, v20, v17
	v_cvt_pk_bf16_f32 v18, v34, v26
	v_cvt_pk_bf16_f32 v19, v21, v19
	global_store_dwordx4 v[32:33], v[16:19], off sc1
	v_mov_b32_e32 v20, v8
	v_mov_b32_e32 v21, v0
	v_mov_b32_e32 v18, v12
	v_mov_b32_e32 v19, v4
	v_pk_add_f32 v[18:19], v[18:19], 0 op_sel_hi:[1,0]
	v_pk_add_f32 v[20:21], v[20:21], 0 op_sel_hi:[1,0]
	v_mul_f32_e32 v4, 0xbfb8aa3b, v18
	v_exp_f32_e32 v4, v4
	v_add_u32_e32 v16, 0xb0, v150
	v_mad_i64_i32 v[16:17], s[20:21], v16, s51, v[142:143]
	v_add_f32_e32 v0, 1.0, v4
	v_rcp_f32_e32 v0, v0
	v_mul_f32_e32 v4, 0xbfb8aa3b, v20
	v_exp_f32_e32 v4, v4
	v_lshl_add_u64 v[16:17], v[16:17], 0, v[140:141]
	v_mul_f32_e32 v0, v18, v0
	v_mul_f32_e32 v12, v0, v19
	v_add_f32_e32 v0, 1.0, v4
	v_mov_b32_e32 v4, v13
	v_pk_add_f32 v[4:5], v[4:5], 0 op_sel_hi:[1,0]
	v_rcp_f32_e32 v8, v0
	v_mov_b32_e32 v0, v9
	v_mul_f32_e32 v9, 0xbfb8aa3b, v4
	v_exp_f32_e32 v9, v9
	v_pk_add_f32 v[0:1], v[0:1], 0 op_sel_hi:[1,0]
	v_mul_f32_e32 v8, v20, v8
	v_mul_f32_e32 v13, 0xbfb8aa3b, v0
	v_add_f32_e32 v9, 1.0, v9
	v_rcp_f32_e32 v9, v9
	v_exp_f32_e32 v13, v13
	v_mul_f32_e32 v18, v8, v21
	v_mov_b32_e32 v8, v10
	v_mul_f32_e32 v4, v4, v9
	v_mul_f32_e32 v19, v4, v5
	v_mov_b32_e32 v4, v14
	v_mov_b32_e32 v5, v6
	v_pk_add_f32 v[4:5], v[4:5], 0 op_sel_hi:[1,0]
	v_add_f32_e32 v13, 1.0, v13
	v_mul_f32_e32 v6, 0xbfb8aa3b, v4
	v_exp_f32_e32 v6, v6
	v_mov_b32_e32 v9, v2
	v_rcp_f32_e32 v13, v13
	v_pk_add_f32 v[8:9], v[8:9], 0 op_sel_hi:[1,0]
	v_add_f32_e32 v2, 1.0, v6
	v_rcp_f32_e32 v2, v2
	v_mul_f32_e32 v6, 0xbfb8aa3b, v8
	v_exp_f32_e32 v6, v6
	v_mul_f32_e32 v0, v0, v13
	v_mul_f32_e32 v10, v0, v1
	v_mul_f32_e32 v0, v4, v2
	v_mul_f32_e32 v4, v0, v5
	v_add_f32_e32 v0, 1.0, v6
	v_mov_b32_e32 v6, v15
	v_rcp_f32_e32 v5, v0
	v_pk_add_f32 v[0:1], v[6:7], 0 op_sel_hi:[1,0]
	v_mov_b32_e32 v2, v11
	v_pk_add_f32 v[2:3], v[2:3], 0 op_sel_hi:[1,0]
	v_mul_f32_e32 v6, 0xbfb8aa3b, v0
	v_exp_f32_e32 v6, v6
	v_mul_f32_e32 v7, 0xbfb8aa3b, v2
	v_exp_f32_e32 v7, v7
	v_mul_f32_e32 v5, v8, v5
	v_add_f32_e32 v6, 1.0, v6
	v_rcp_f32_e32 v6, v6
	v_add_f32_e32 v7, 1.0, v7
	v_rcp_f32_e32 v7, v7
	s_andn2_b64 vcc, exec, s[10:11]
	v_mul_f32_e32 v0, v0, v6
	v_mul_f32_e32 v1, v0, v1
	v_mul_f32_e32 v0, v2, v7
	v_mul_f32_e32 v3, v0, v3
	s_mov_b64 s[10:11], -1
	v_mul_f32_e32 v5, v5, v9
	v_cvt_pk_bf16_f32 v0, v12, v19
	v_cvt_pk_bf16_f32 v1, v4, v1
	v_cvt_pk_bf16_f32 v2, v18, v10
	v_cvt_pk_bf16_f32 v3, v5, v3
	global_store_dwordx4 v[16:17], v[0:3], off sc1
	s_cbranch_vccnz .LBB0_147
	s_andn2_b64 vcc, exec, s[0:1]
	s_cbranch_vccnz .LBB0_146
	s_barrier
	s_branch .LBB0_146

; __device__ __forceinline__ unsigned cvt_pk_bf16(float lo, float hi) { unsigned r; asm volatile("v_cvt_pk_bf16_f32 %0, %1, %2" : "=v"(r) : "v"(lo), "v"(hi)); return r; }
; __device__ __forceinline__ f32x2 ln_stats(f32x2 sm) { const float mu = sm[0] * (1.f / D); const float var = fmaxf(sm[1] * (1.f / D) - mu * mu, 0.f); return (f32x2){mu, 1.0f / sqrtf(var + LN_EPS)}; }
; template <int MODE> ...
;     ...
;         if (kh == 1) red[tw * 64 + lane] = tot;
;         __syncthreads();
;         if (kh == 0) {
;             tot += red[tw * 64 + lane];
;             const size_t off = (size_t)(rt * 16 + fr) * D + ct * 16 + 4 * fq;
;             if (MODE == 0) {
;                 f32x4 xv = *(const f32x4*)(res + off);
;                 if (rin) { const f32x2 st = ln_stats(*(const f32x2*)(rin + 2 * (rt * 16 + fr))); const int cc = ct * 16 + 4 * fq;
;                     xv = (xv - st[0]) * (*(const f32x4*)(lg + cc) * st[1]) + *(const f32x4*)(lb + cc); }
;                 const f32x4 o = xv * alpha + tot * scale;
;                 *(f32x4*)(Ys + off) = o;
;                 if (ybs) { u32x2 w; w.x = cvt_pk_bf16(o[0], o[1]); w.y = cvt_pk_bf16(o[2], o[3]); *(u32x2*)(ybs + off) = w; }
;                 if (rout) { float ps = (o[0] + o[1]) + (o[2] + o[3]), pq = (o[0] * o[0] + o[1] * o[1]) + (o[2] * o[2] + o[3] * o[3]);
;                     ps += __shfl_xor(ps, 16); pq += __shfl_xor(pq, 16); ps += __shfl_xor(ps, 32); pq += __shfl_xor(pq, 32);
;                     if (fq == 0) { atomicAdd(rout + 2 * (rt * 16 + fr), ps); atomicAdd(rout + 2 * (rt * 16 + fr) + 1, pq); } }
;             }
.LBB0_220:
	s_and_b64 vcc, exec, s[6:7]
	s_waitcnt lgkmcnt(0)
	s_barrier
	s_cbranch_vccnz .LBB0_217
	v_ashrrev_i32_e32 v13, 31, v12
	v_lshlrev_b64 v[28:29], 11, v[12:13]
	v_or_b32_e32 v4, s14, v28
	v_or_b32_e32 v28, v4, v10
	v_readlane_b32 s60, v254, 45
	v_lshlrev_b64 v[30:31], 2, v[28:29]
	v_readlane_b32 s62, v254, 47
	v_readlane_b32 s63, v254, 48
	ds_read_b128 v[24:27], v14
	v_cmp_lt_i32_e32 vcc, v16, v17
	v_lshl_add_u64 v[20:21], s[62:63], 0, v[30:31]
	global_load_dwordx4 v[20:23], v[20:21], off
	v_cndmask_b32_e32 v4, v15, v16, vcc
	s_waitcnt lgkmcnt(0)
	v_pk_add_f32 v[2:3], v[2:3], v[26:27]
	v_pk_add_f32 v[0:1], v[0:1], v[24:25]
	v_lshlrev_b32_e32 v4, 2, v4
	v_cmp_lt_i32_e32 vcc, v18, v17
	v_readlane_b32 s61, v254, 46
	v_readlane_b32 s64, v254, 49
	v_cndmask_b32_e32 v13, v15, v18, vcc
	v_lshlrev_b32_e32 v13, 2, v13
	v_readlane_b32 s65, v254, 50
	v_readlane_b32 s66, v254, 51
	v_readlane_b32 s67, v254, 52
	v_readlane_b32 s68, v254, 53
	v_readlane_b32 s69, v254, 54
	v_readlane_b32 s70, v254, 55
	v_readlane_b32 s71, v254, 56
	v_readlane_b32 s72, v254, 57
	v_readlane_b32 s73, v254, 58
	v_readlane_b32 s74, v254, 59
	v_readlane_b32 s75, v254, 60
	s_waitcnt vmcnt(0)
	v_pk_mul_f32 v[22:23], v[22:23], s[12:13] op_sel_hi:[1,0]
	v_pk_mul_f32 v[20:21], v[20:21], s[12:13] op_sel_hi:[1,0]
	v_pk_fma_f32 v[22:23], v[2:3], 0.5, v[22:23] op_sel_hi:[1,0,1]
	v_pk_fma_f32 v[20:21], v[0:1], 0.5, v[20:21] op_sel_hi:[1,0,1]
	v_mul_f32_e32 v3, v23, v23
	v_mul_f32_e32 v2, v21, v21
	v_add_f32_e32 v0, v20, v21
	v_add_f32_e32 v1, v22, v23
	v_fmac_f32_e32 v2, v20, v20
	v_fmac_f32_e32 v3, v22, v22
	v_add_f32_e32 v19, v0, v1
	v_add_f32_e32 v2, v2, v3
	ds_bpermute_b32 v3, v4, v19
	ds_bpermute_b32 v4, v4, v2
	v_lshl_add_u64 v[0:1], s[24:25], 0, v[30:31]
	global_store_dwordx4 v[0:1], v[20:23], off sc1
	s_waitcnt lgkmcnt(1)
	v_add_f32_e32 v0, v19, v3
	s_waitcnt lgkmcnt(0)
	v_add_f32_e32 v1, v2, v4
	ds_bpermute_b32 v2, v13, v0
	ds_bpermute_b32 v3, v13, v1
	v_cvt_pk_bf16_f32 v20, v20, v21
	v_cvt_pk_bf16_f32 v21, v22, v23
	v_lshl_add_u64 v[22:23], v[28:29], 1, s[28:29]
	global_store_dwordx2 v[22:23], v[20:21], off
	s_and_saveexec_b64 s[14:15], s[0:1]
	s_cbranch_execz .LBB0_216
	s_waitcnt lgkmcnt(1)
	v_add_f32_e32 v2, v0, v2
	v_lshlrev_b32_e32 v0, 1, v12
	s_waitcnt lgkmcnt(0)
	v_add_f32_e32 v3, v1, v3
	v_ashrrev_i32_e32 v1, 31, v0
	v_lshl_add_u64 v[0:1], v[0:1], 2, s[22:23]
	global_atomic_add_f32 v[0:1], v2, off
	global_atomic_add_f32 v[0:1], v3, off offset:4
	s_branch .LBB0_216

; __device__ __forceinline__ unsigned cvt_pk_bf16(float lo, float hi) { unsigned r; asm volatile("v_cvt_pk_bf16_f32 %0, %1, %2" : "=v"(r) : "v"(lo), "v"(hi)); return r; }
;     __device__ __forceinline__ void operator()(const f32x4 (&acc)[2][2][4][2], const Unit& u, int wr, int wc, int fr, int fq) const {
;     ...
; #pragma unroll
;         for (int ai = 0; ai < 2; ++ai)
; #pragma unroll
;             for (int m2 = 0; m2 < 2; ++m2) {
;                 f32x4 xv[2][2][2]; f32x2 st[2];
; #pragma unroll
;                 for (int mm = 0; mm < 2; ++mm) {
;                     const int r = row0 + ai * HALF + (2 * m2 + mm) * 16;
;                     st[mm] = (f32x2){0.f, 1.f};
;                     if (rin) st[mm] = ln_stats(*(const f32x2*)(rin + 2 * (size_t)r));
; #pragma unroll
;                     for (int bj = 0; bj < 2; ++bj)
; #pragma unroll
;                         for (int n = 0; n < 2; ++n) { const f32x4* rp = (const f32x4*)(res + (size_t)r * D + col0 + bj * HALF + n * 16); xv[mm][bj][n] = stream ? __builtin_nontemporal_load(rp) : *rp; }
;                 }
; #pragma unroll
;                 for (int mm = 0; mm < 2; ++mm) {
;                     const int r = row0 + ai * HALF + (2 * m2 + mm) * 16;
;                     float ps = 0.f, pq = 0.f;
; #pragma unroll
;                     for (int bj = 0; bj < 2; ++bj)
; #pragma unroll
;                         for (int n = 0; n < 2; ++n) {
;                             const f32x4 x = (xv[mm][bj][n] - st[mm][0]) * (gg[bj][n] * st[mm][1]) + bb[bj][n];
;                             const f32x4 o = x * alpha + acc[ai][bj][2 * m2 + mm][n] * scale;
;                             const size_t off = (size_t)r * D + col0 + bj * HALF + n * 16;
;                             *(f32x4*)(Y + off) = o;
;                             if (yb) { u32x2 w; w.x = cvt_pk_bf16(o[0], o[1]); w.y = cvt_pk_bf16(o[2], o[3]); *(u32x2*)(yb + off) = w; }
;                             ps += (o[0] + o[1]) + (o[2] + o[3]); pq += (o[0] * o[0] + o[1] * o[1]) + (o[2] * o[2] + o[3] * o[3]);
;                         }
;                     if (rout) {
;                         ps += __shfl_xor(ps, 16); pq += __shfl_xor(pq, 16); ps += __shfl_xor(ps, 32); pq += __shfl_xor(pq, 32);
;                         if (fq == 0) { atomicAdd(rout + 2 * (size_t)r, ps); atomicAdd(rout + 2 * (size_t)r + 1, pq); }
;                     }
.LBB0_246:
	v_mbcnt_lo_u32_b32 v246, -1, 0
	v_mbcnt_hi_u32_b32 v246, -1, v246
	v_lshrrev_b32_e32 v247, 2, v246
	v_and_b32_e32 v248, 3, v246
	v_lshl_add_u32 v238, v248, 4, v247
	v_lshlrev_b32_e32 v238, 2, v238
	v_and_b32_e32 v249, 15, v246
	v_sub_u32_e32 v247, v247, v249
	v_lshrrev_b32_e32 v249, 4, v246
	v_sub_u32_e32 v248, v248, v249
	v_mul_i32_i24_e32 v240, 0x2000, v247
	v_lshl_add_u32 v240, v248, 4, v240
	v_ashrrev_i32_e32 v241, 31, v240
	v_mul_i32_i24_e32 v242, 0x1000, v247
	v_lshl_add_u32 v242, v248, 3, v242
	v_ashrrev_i32_e32 v243, 31, v242
	v_lshl_or_b32 v156, s88, 8, v168
	v_lshl_add_u32 v158, s87, 8, v166
	v_readlane_b32 s60, v254, 45
	v_ashrrev_i32_e32 v157, 31, v156
	v_readlane_b32 s61, v254, 46
	v_ashrrev_i32_e32 v159, 31, v158
	v_lshlrev_b64 v[124:125], 13, v[158:159]
	v_lshl_add_u64 v[160:161], v[156:157], 2, s[60:61]
	v_lshl_add_u64 v[124:125], v[160:161], 0, v[124:125]
	global_load_dwordx4 v[182:185], v[124:125], off
	global_load_dwordx4 v[186:189], v[124:125], off offset:64
	global_load_dwordx4 v[190:193], v[124:125], off offset:512
	global_load_dwordx4 v[144:147], v[124:125], off offset:576
	v_or_b32_e32 v162, 16, v158
	v_ashrrev_i32_e32 v163, 31, v162
	v_lshlrev_b64 v[124:125], 13, v[162:163]
	v_lshl_add_u64 v[124:125], v[160:161], 0, v[124:125]
	global_load_dwordx4 v[140:143], v[124:125], off
	global_load_dwordx4 v[136:139], v[124:125], off offset:64
	global_load_dwordx4 v[132:135], v[124:125], off offset:512
	s_nop 0
	global_load_dwordx4 v[124:127], v[124:125], off offset:576
	v_lshlrev_b64 v[164:165], 11, v[158:159]
	v_lshl_add_u64 v[164:165], v[164:165], 0, v[156:157]
	v_readlane_b32 s62, v254, 47
	v_readlane_b32 s63, v254, 48
	v_readlane_b32 s64, v254, 49
	v_readlane_b32 s65, v254, 50
	v_readlane_b32 s66, v254, 51
	v_readlane_b32 s67, v254, 52
	v_readlane_b32 s68, v254, 53
	v_readlane_b32 s69, v254, 54
	v_readlane_b32 s70, v254, 55
	v_readlane_b32 s71, v254, 56
	v_readlane_b32 s72, v254, 57
	v_readlane_b32 s73, v254, 58
	v_readlane_b32 s74, v254, 59
	v_readlane_b32 s75, v254, 60
	s_waitcnt vmcnt(0)
	v_pk_add_f32 v[174:175], v[184:185], 0 op_sel_hi:[1,0]
	v_pk_add_f32 v[182:183], v[182:183], 0 op_sel_hi:[1,0]
	v_pk_mul_f32 v[174:175], v[174:175], s[12:13] op_sel_hi:[1,0]
	v_pk_mul_f32 v[182:183], v[182:183], s[12:13] op_sel_hi:[1,0]
	v_pk_fma_f32 v[130:131], v[130:131], 0.5, v[174:175] op_sel_hi:[1,0,1]
	v_pk_fma_f32 v[128:129], v[128:129], 0.5, v[182:183] op_sel_hi:[1,0,1]
	v_lshl_add_u64 v[174:175], v[164:165], 2, s[38:39]
	ds_bpermute_b32 v246, v238, v128
	ds_bpermute_b32 v247, v238, v129
	ds_bpermute_b32 v248, v238, v130
	ds_bpermute_b32 v249, v238, v131
	v_lshl_add_u64 v[244:245], v[174:175], 0, v[240:241]
	s_waitcnt lgkmcnt(0)
	global_store_dwordx4 v[244:245], v[246:249], off sc1
	v_cvt_pk_bf16_f32 v174, v128, v129
	v_add_f32_e32 v173, v128, v129
	v_lshl_add_u64 v[182:183], v[164:165], 1, s[58:59]
	v_mul_f32_e32 v129, v129, v129
	v_fmac_f32_e32 v129, v128, v128
	v_mul_f32_e32 v128, v130, v130
	v_cvt_pk_bf16_f32 v175, v130, v131
	ds_bpermute_b32 v250, v238, v174
	ds_bpermute_b32 v251, v238, v175
	v_lshl_add_u64 v[244:245], v[182:183], 0, v[242:243]
	s_waitcnt lgkmcnt(0)
	global_store_dwordx2 v[244:245], v[250:251], off
	v_add_f32_e32 v174, v131, v130
	v_fmac_f32_e32 v128, v131, v131
	v_add_f32_e32 v173, v173, v174
	v_add_f32_e32 v174, v129, v128
	v_pk_add_f32 v[128:129], v[188:189], 0 op_sel_hi:[1,0]
	v_pk_add_f32 v[130:131], v[186:187], 0 op_sel_hi:[1,0]
	v_pk_mul_f32 v[128:129], v[128:129], s[12:13] op_sel_hi:[1,0]
	v_pk_mul_f32 v[130:131], v[130:131], s[12:13] op_sel_hi:[1,0]
	v_pk_fma_f32 v[122:123], v[122:123], 0.5, v[128:129] op_sel_hi:[1,0,1]
	v_or_b32_e32 v128, 16, v164
	v_mov_b32_e32 v129, v165
	v_pk_fma_f32 v[120:121], v[120:121], 0.5, v[130:131] op_sel_hi:[1,0,1]
	v_lshl_add_u64 v[130:131], v[128:129], 2, s[38:39]
	v_lshl_add_u64 v[128:129], v[128:129], 1, s[58:59]
	ds_bpermute_b32 v246, v238, v120
	ds_bpermute_b32 v247, v238, v121
	ds_bpermute_b32 v248, v238, v122
	ds_bpermute_b32 v249, v238, v123
	v_lshl_add_u64 v[244:245], v[130:131], 0, v[240:241]
	s_waitcnt lgkmcnt(0)
	global_store_dwordx4 v[244:245], v[246:249], off sc1
	v_cvt_pk_bf16_f32 v130, v120, v121
	v_cvt_pk_bf16_f32 v131, v122, v123
	ds_bpermute_b32 v250, v238, v130
	ds_bpermute_b32 v251, v238, v131
	v_lshl_add_u64 v[244:245], v[128:129], 0, v[242:243]
	s_waitcnt lgkmcnt(0)
	global_store_dwordx2 v[244:245], v[250:251], off
	v_add_f32_e32 v128, v120, v121
	v_mul_f32_e32 v121, v121, v121
	v_add_f32_e32 v129, v123, v122
	v_fmac_f32_e32 v121, v120, v120
	v_mul_f32_e32 v120, v122, v122
	v_add_f32_e32 v173, 0, v173
	v_add_f32_e32 v128, v128, v129
	v_fmac_f32_e32 v120, v123, v123
	v_add_f32_e32 v130, v173, v128
	v_add_f32_e32 v120, v121, v120
	v_pk_add_f32 v[122:123], v[192:193], 0 op_sel_hi:[1,0]
	v_pk_add_f32 v[128:129], v[190:191], 0 op_sel_hi:[1,0]
	v_add_f32_e32 v131, v174, v120
	v_or_b32_e32 v120, 0x80, v164
	v_mov_b32_e32 v121, v165
	v_pk_mul_f32 v[122:123], v[122:123], s[12:13] op_sel_hi:[1,0]
	v_pk_mul_f32 v[128:129], v[128:129], s[12:13] op_sel_hi:[1,0]
	v_pk_fma_f32 v[118:119], v[118:119], 0.5, v[122:123] op_sel_hi:[1,0,1]
	v_pk_fma_f32 v[116:117], v[116:117], 0.5, v[128:129] op_sel_hi:[1,0,1]
	v_lshl_add_u64 v[122:123], v[120:121], 2, s[38:39]
	v_lshl_add_u64 v[120:121], v[120:121], 1, s[58:59]
	ds_bpermute_b32 v246, v238, v116
	ds_bpermute_b32 v247, v238, v117
	ds_bpermute_b32 v248, v238, v118
	ds_bpermute_b32 v249, v238, v119
	v_lshl_add_u64 v[244:245], v[122:123], 0, v[240:241]
	s_waitcnt lgkmcnt(0)
; __device__ __forceinline__ unsigned cvt_pk_bf16(float lo, float hi) { unsigned r; asm volatile("v_cvt_pk_bf16_f32 %0, %1, %2" : "=v"(r) : "v"(lo), "v"(hi)); return r; }
;     __device__ __forceinline__ void operator()(const f32x4 (&acc)[2][2][4][2], const Unit& u, int wr, int wc, int fr, int fq) const {
;     ...
; #pragma unroll
;         for (int ai = 0; ai < 2; ++ai)
; #pragma unroll
;             for (int m2 = 0; m2 < 2; ++m2) {
;                 f32x4 xv[2][2][2]; f32x2 st[2];
; #pragma unroll
;                 for (int mm = 0; mm < 2; ++mm) {
;                     const int r = row0 + ai * HALF + (2 * m2 + mm) * 16;
;                     st[mm] = (f32x2){0.f, 1.f};
;                     if (rin) st[mm] = ln_stats(*(const f32x2*)(rin + 2 * (size_t)r));
; #pragma unroll
;                     for (int bj = 0; bj < 2; ++bj)
; #pragma unroll
;                         for (int n = 0; n < 2; ++n) { const f32x4* rp = (const f32x4*)(res + (size_t)r * D + col0 + bj * HALF + n * 16); xv[mm][bj][n] = stream ? __builtin_nontemporal_load(rp) : *rp; }
;                 }
; #pragma unroll
;                 for (int mm = 0; mm < 2; ++mm) {
;                     const int r = row0 + ai * HALF + (2 * m2 + mm) * 16;
;                     float ps = 0.f, pq = 0.f;
; #pragma unroll
;                     for (int bj = 0; bj < 2; ++bj)
; #pragma unroll
;                         for (int n = 0; n < 2; ++n) {
;                             const f32x4 x = (xv[mm][bj][n] - st[mm][0]) * (gg[bj][n] * st[mm][1]) + bb[bj][n];
;                             const f32x4 o = x * alpha + acc[ai][bj][2 * m2 + mm][n] * scale;
;                             const size_t off = (size_t)r * D + col0 + bj * HALF + n * 16;
;                             *(f32x4*)(Y + off) = o;
;                             if (yb) { u32x2 w; w.x = cvt_pk_bf16(o[0], o[1]); w.y = cvt_pk_bf16(o[2], o[3]); *(u32x2*)(yb + off) = w; }
;                             ps += (o[0] + o[1]) + (o[2] + o[3]); pq += (o[0] * o[0] + o[1] * o[1]) + (o[2] * o[2] + o[3] * o[3]);
;                         }
;                     if (rout) {
;                         ps += __shfl_xor(ps, 16); pq += __shfl_xor(pq, 16); ps += __shfl_xor(ps, 32); pq += __shfl_xor(pq, 32);
;                         if (fq == 0) { atomicAdd(rout + 2 * (size_t)r, ps); atomicAdd(rout + 2 * (size_t)r + 1, pq); }
;                     }
	global_store_dwordx4 v[244:245], v[246:249], off sc1
	v_cvt_pk_bf16_f32 v122, v116, v117
	v_cvt_pk_bf16_f32 v123, v118, v119
	ds_bpermute_b32 v250, v238, v122
	ds_bpermute_b32 v251, v238, v123
	v_lshl_add_u64 v[244:245], v[120:121], 0, v[242:243]
	s_waitcnt lgkmcnt(0)
	global_store_dwordx2 v[244:245], v[250:251], off
	v_add_f32_e32 v120, v116, v117
	v_mul_f32_e32 v117, v117, v117
	v_fmac_f32_e32 v117, v116, v116
	v_mul_f32_e32 v116, v118, v118
	v_fmac_f32_e32 v116, v119, v119
	v_add_f32_e32 v121, v119, v118
	v_add_f32_e32 v116, v117, v116
	v_add_f32_e32 v120, v120, v121
	v_add_f32_e32 v121, v131, v116
	v_pk_add_f32 v[116:117], v[146:147], 0 op_sel_hi:[1,0]
	v_pk_add_f32 v[118:119], v[144:145], 0 op_sel_hi:[1,0]
	v_pk_mul_f32 v[116:117], v[116:117], s[12:13] op_sel_hi:[1,0]
	v_pk_mul_f32 v[118:119], v[118:119], s[12:13] op_sel_hi:[1,0]
	v_or_b32_e32 v164, 0x90, v164
	v_pk_fma_f32 v[114:115], v[114:115], 0.5, v[116:117] op_sel_hi:[1,0,1]
	v_pk_fma_f32 v[112:113], v[112:113], 0.5, v[118:119] op_sel_hi:[1,0,1]
	v_lshl_add_u64 v[116:117], v[164:165], 2, s[38:39]
	ds_bpermute_b32 v246, v238, v112
	ds_bpermute_b32 v247, v238, v113
	ds_bpermute_b32 v248, v238, v114
	ds_bpermute_b32 v249, v238, v115
	v_lshl_add_u64 v[244:245], v[116:117], 0, v[240:241]
	s_waitcnt lgkmcnt(0)
	global_store_dwordx4 v[244:245], v[246:249], off sc1
	v_cvt_pk_bf16_f32 v116, v112, v113
	v_lshl_add_u64 v[118:119], v[164:165], 1, s[58:59]
	v_cvt_pk_bf16_f32 v117, v114, v115
	ds_bpermute_b32 v250, v238, v116
	ds_bpermute_b32 v251, v238, v117
	v_lshl_add_u64 v[244:245], v[118:119], 0, v[242:243]
	s_waitcnt lgkmcnt(0)
	global_store_dwordx2 v[244:245], v[250:251], off
	v_mul_f32_e32 v116, v113, v113
	v_fmac_f32_e32 v116, v112, v112
	v_mul_f32_e32 v117, v114, v114
	v_add_f32_e32 v112, v112, v113
	v_add_f32_e32 v113, v115, v114
	v_and_b32_e32 v114, 64, v172
	v_add_f32_e32 v112, v112, v113
	v_xor_b32_e32 v113, 16, v172
	v_add_u32_e32 v114, 64, v114
	v_cmp_lt_i32_e32 vcc, v113, v114
	v_add_f32_e32 v120, v130, v120
	v_add_f32_e32 v112, v120, v112
	v_cndmask_b32_e32 v113, v172, v113, vcc
	v_lshlrev_b32_e32 v122, 2, v113
	ds_bpermute_b32 v113, v122, v112
	v_fmac_f32_e32 v117, v115, v115
	v_add_f32_e32 v116, v116, v117
	v_add_f32_e32 v116, v121, v116
	v_xor_b32_e32 v115, 32, v172
	s_waitcnt lgkmcnt(0)
	v_add_f32_e32 v112, v112, v113
	ds_bpermute_b32 v113, v122, v116
	v_cmp_lt_i32_e32 vcc, v115, v114
	s_waitcnt lgkmcnt(0)
	v_add_f32_e32 v113, v116, v113
	v_cndmask_b32_e32 v114, v172, v115, vcc
	v_lshlrev_b32_e32 v123, 2, v114
	ds_bpermute_b32 v114, v123, v112
	ds_bpermute_b32 v115, v123, v113
	s_and_saveexec_b64 s[20:21], s[4:5]
	s_cbranch_execz .LBB0_248
	v_lshl_add_u64 v[116:117], v[158:159], 3, s[54:55]
	s_waitcnt lgkmcnt(1)
	v_add_f32_e32 v112, v112, v114
	s_waitcnt lgkmcnt(0)
	v_add_f32_e32 v113, v113, v115
	global_atomic_add_f32 v[116:117], v112, off
	global_atomic_add_f32 v[116:117], v113, off offset:4
.LBB0_248:
	s_or_b64 exec, exec, s[20:21]
	v_lshlrev_b64 v[112:113], 11, v[162:163]
	s_waitcnt lgkmcnt(0)
	v_pk_add_f32 v[114:115], v[142:143], 0 op_sel_hi:[1,0]
	v_pk_add_f32 v[116:117], v[140:141], 0 op_sel_hi:[1,0]
	v_lshl_add_u64 v[112:113], v[112:113], 0, v[156:157]
	v_pk_mul_f32 v[114:115], v[114:115], s[12:13] op_sel_hi:[1,0]
	v_pk_mul_f32 v[116:117], v[116:117], s[12:13] op_sel_hi:[1,0]
	v_pk_fma_f32 v[110:111], v[110:111], 0.5, v[114:115] op_sel_hi:[1,0,1]
	v_pk_fma_f32 v[108:109], v[108:109], 0.5, v[116:117] op_sel_hi:[1,0,1]
	v_lshl_add_u64 v[114:115], v[112:113], 2, s[38:39]
	ds_bpermute_b32 v246, v238, v108
	ds_bpermute_b32 v247, v238, v109
	ds_bpermute_b32 v248, v238, v110
	ds_bpermute_b32 v249, v238, v111
	v_lshl_add_u64 v[244:245], v[114:115], 0, v[240:241]
	s_waitcnt lgkmcnt(0)
	global_store_dwordx4 v[244:245], v[246:249], off sc1
	v_cvt_pk_bf16_f32 v114, v108, v109
	v_lshl_add_u64 v[116:117], v[112:113], 1, s[58:59]
	v_cvt_pk_bf16_f32 v115, v110, v111
	ds_bpermute_b32 v250, v238, v114
	ds_bpermute_b32 v251, v238, v115
	v_lshl_add_u64 v[244:245], v[116:117], 0, v[242:243]
	s_waitcnt lgkmcnt(0)
	global_store_dwordx2 v[244:245], v[250:251], off
	v_add_f32_e32 v114, v108, v109
	v_mul_f32_e32 v109, v109, v109
	v_fmac_f32_e32 v109, v108, v108
	v_mul_f32_e32 v108, v110, v110
	v_add_f32_e32 v115, v111, v110
	v_fmac_f32_e32 v108, v111, v111
	v_add_f32_e32 v114, v114, v115
	v_add_f32_e32 v115, v109, v108
	v_pk_add_f32 v[108:109], v[138:139], 0 op_sel_hi:[1,0]
	v_pk_add_f32 v[110:111], v[136:137], 0 op_sel_hi:[1,0]
	v_pk_mul_f32 v[108:109], v[108:109], s[12:13] op_sel_hi:[1,0]
	v_pk_mul_f32 v[110:111], v[110:111], s[12:13] op_sel_hi:[1,0]
	v_pk_fma_f32 v[106:107], v[106:107], 0.5, v[108:109] op_sel_hi:[1,0,1]
	v_or_b32_e32 v108, 16, v112
	v_mov_b32_e32 v109, v113
	v_pk_fma_f32 v[104:105], v[104:105], 0.5, v[110:111] op_sel_hi:[1,0,1]
	v_lshl_add_u64 v[110:111], v[108:109], 2, s[38:39]
	v_lshl_add_u64 v[108:109], v[108:109], 1, s[58:59]
	ds_bpermute_b32 v246, v238, v104
	ds_bpermute_b32 v247, v238, v105
	ds_bpermute_b32 v248, v238, v106
	ds_bpermute_b32 v249, v238, v107
	v_lshl_add_u64 v[244:245], v[110:111], 0, v[240:241]
	s_waitcnt lgkmcnt(0)
	global_store_dwordx4 v[244:245], v[246:249], off sc1
	v_cvt_pk_bf16_f32 v110, v104, v105
	v_cvt_pk_bf16_f32 v111, v106, v107
	ds_bpermute_b32 v250, v238, v110
	ds_bpermute_b32 v251, v238, v111
	v_lshl_add_u64 v[244:245], v[108:109], 0, v[242:243]
	s_waitcnt lgkmcnt(0)
; __device__ __forceinline__ unsigned cvt_pk_bf16(float lo, float hi) { unsigned r; asm volatile("v_cvt_pk_bf16_f32 %0, %1, %2" : "=v"(r) : "v"(lo), "v"(hi)); return r; }
;     __device__ __forceinline__ void operator()(const f32x4 (&acc)[2][2][4][2], const Unit& u, int wr, int wc, int fr, int fq) const {
;     ...
; #pragma unroll
;         for (int ai = 0; ai < 2; ++ai)
; #pragma unroll
;             for (int m2 = 0; m2 < 2; ++m2) {
;                 f32x4 xv[2][2][2]; f32x2 st[2];
; #pragma unroll
;                 for (int mm = 0; mm < 2; ++mm) {
;                     const int r = row0 + ai * HALF + (2 * m2 + mm) * 16;
;                     st[mm] = (f32x2){0.f, 1.f};
;                     if (rin) st[mm] = ln_stats(*(const f32x2*)(rin + 2 * (size_t)r));
; #pragma unroll
;                     for (int bj = 0; bj < 2; ++bj)
; #pragma unroll
;                         for (int n = 0; n < 2; ++n) { const f32x4* rp = (const f32x4*)(res + (size_t)r * D + col0 + bj * HALF + n * 16); xv[mm][bj][n] = stream ? __builtin_nontemporal_load(rp) : *rp; }
;                 }
; #pragma unroll
;                 for (int mm = 0; mm < 2; ++mm) {
;                     const int r = row0 + ai * HALF + (2 * m2 + mm) * 16;
;                     float ps = 0.f, pq = 0.f;
; #pragma unroll
;                     for (int bj = 0; bj < 2; ++bj)
; #pragma unroll
;                         for (int n = 0; n < 2; ++n) {
;                             const f32x4 x = (xv[mm][bj][n] - st[mm][0]) * (gg[bj][n] * st[mm][1]) + bb[bj][n];
;                             const f32x4 o = x * alpha + acc[ai][bj][2 * m2 + mm][n] * scale;
;                             const size_t off = (size_t)r * D + col0 + bj * HALF + n * 16;
;                             *(f32x4*)(Y + off) = o;
;                             if (yb) { u32x2 w; w.x = cvt_pk_bf16(o[0], o[1]); w.y = cvt_pk_bf16(o[2], o[3]); *(u32x2*)(yb + off) = w; }
;                             ps += (o[0] + o[1]) + (o[2] + o[3]); pq += (o[0] * o[0] + o[1] * o[1]) + (o[2] * o[2] + o[3] * o[3]);
;                         }
;                     if (rout) {
;                         ps += __shfl_xor(ps, 16); pq += __shfl_xor(pq, 16); ps += __shfl_xor(ps, 32); pq += __shfl_xor(pq, 32);
;                         if (fq == 0) { atomicAdd(rout + 2 * (size_t)r, ps); atomicAdd(rout + 2 * (size_t)r + 1, pq); }
;                     }
	global_store_dwordx2 v[244:245], v[250:251], off
	v_add_f32_e32 v108, v104, v105
	v_mul_f32_e32 v105, v105, v105
	v_add_f32_e32 v109, v107, v106
	v_fmac_f32_e32 v105, v104, v104
	v_mul_f32_e32 v104, v106, v106
	v_add_f32_e32 v114, 0, v114
	v_add_f32_e32 v108, v108, v109
	v_fmac_f32_e32 v104, v107, v107
	v_add_f32_e32 v110, v114, v108
	v_add_f32_e32 v104, v105, v104
	v_pk_add_f32 v[106:107], v[134:135], 0 op_sel_hi:[1,0]
	v_pk_add_f32 v[108:109], v[132:133], 0 op_sel_hi:[1,0]
	v_add_f32_e32 v111, v115, v104
	v_or_b32_e32 v104, 0x80, v112
	v_mov_b32_e32 v105, v113
	v_pk_mul_f32 v[106:107], v[106:107], s[12:13] op_sel_hi:[1,0]
	v_pk_mul_f32 v[108:109], v[108:109], s[12:13] op_sel_hi:[1,0]
	v_pk_fma_f32 v[102:103], v[102:103], 0.5, v[106:107] op_sel_hi:[1,0,1]
	v_pk_fma_f32 v[100:101], v[100:101], 0.5, v[108:109] op_sel_hi:[1,0,1]
	v_lshl_add_u64 v[106:107], v[104:105], 2, s[38:39]
	v_lshl_add_u64 v[104:105], v[104:105], 1, s[58:59]
	ds_bpermute_b32 v246, v238, v100
	ds_bpermute_b32 v247, v238, v101
	ds_bpermute_b32 v248, v238, v102
	ds_bpermute_b32 v249, v238, v103
	v_lshl_add_u64 v[244:245], v[106:107], 0, v[240:241]
	s_waitcnt lgkmcnt(0)
	global_store_dwordx4 v[244:245], v[246:249], off sc1
	v_cvt_pk_bf16_f32 v106, v100, v101
	v_cvt_pk_bf16_f32 v107, v102, v103
	ds_bpermute_b32 v250, v238, v106
	ds_bpermute_b32 v251, v238, v107
	v_lshl_add_u64 v[244:245], v[104:105], 0, v[242:243]
	s_waitcnt lgkmcnt(0)
	global_store_dwordx2 v[244:245], v[250:251], off
	v_add_f32_e32 v104, v100, v101
	v_mul_f32_e32 v101, v101, v101
	v_fmac_f32_e32 v101, v100, v100
	v_mul_f32_e32 v100, v102, v102
	v_fmac_f32_e32 v100, v103, v103
	v_add_f32_e32 v105, v103, v102
	v_add_f32_e32 v100, v101, v100
	v_add_f32_e32 v104, v104, v105
	v_add_f32_e32 v107, v111, v100
	v_pk_add_f32 v[100:101], v[126:127], 0 op_sel_hi:[1,0]
	v_pk_add_f32 v[102:103], v[124:125], 0 op_sel_hi:[1,0]
	v_add_f32_e32 v106, v110, v104
	v_pk_mul_f32 v[100:101], v[100:101], s[12:13] op_sel_hi:[1,0]
	v_pk_mul_f32 v[104:105], v[102:103], s[12:13] op_sel_hi:[1,0]
	v_pk_fma_f32 v[102:103], v[98:99], 0.5, v[100:101] op_sel_hi:[1,0,1]
	v_pk_fma_f32 v[100:101], v[96:97], 0.5, v[104:105] op_sel_hi:[1,0,1]
	v_mul_f32_e32 v97, v102, v102
	v_mul_f32_e32 v96, v101, v101
	v_fmac_f32_e32 v96, v100, v100
	v_fmac_f32_e32 v97, v103, v103
	v_add_f32_e32 v96, v96, v97
	v_add_f32_e32 v98, v107, v96
	v_add_f32_e32 v96, v100, v101
	v_add_f32_e32 v97, v103, v102
	v_add_f32_e32 v96, v96, v97
	v_add_f32_e32 v99, v106, v96
	ds_bpermute_b32 v104, v122, v99
	ds_bpermute_b32 v105, v122, v98
	v_or_b32_e32 v112, 0x90, v112
	v_lshl_add_u64 v[96:97], v[112:113], 2, s[38:39]
	ds_bpermute_b32 v246, v238, v100
	ds_bpermute_b32 v247, v238, v101
	ds_bpermute_b32 v248, v238, v102
	ds_bpermute_b32 v249, v238, v103
	v_lshl_add_u64 v[244:245], v[96:97], 0, v[240:241]
	s_waitcnt lgkmcnt(0)
	global_store_dwordx4 v[244:245], v[246:249], off sc1
	s_waitcnt lgkmcnt(1)
	v_add_f32_e32 v96, v99, v104
	s_waitcnt lgkmcnt(0)
	v_add_f32_e32 v97, v98, v105
	ds_bpermute_b32 v98, v123, v96
	ds_bpermute_b32 v99, v123, v97
	v_cvt_pk_bf16_f32 v100, v100, v101
	v_cvt_pk_bf16_f32 v101, v102, v103
	v_lshl_add_u64 v[102:103], v[112:113], 1, s[58:59]
	ds_bpermute_b32 v250, v238, v100
	ds_bpermute_b32 v251, v238, v101
	v_lshl_add_u64 v[244:245], v[102:103], 0, v[242:243]
	s_waitcnt lgkmcnt(0)
	global_store_dwordx2 v[244:245], v[250:251], off
	s_and_saveexec_b64 s[20:21], s[4:5]
	s_cbranch_execz .LBB0_250
	v_lshl_add_u64 v[100:101], v[162:163], 3, s[54:55]
	s_waitcnt lgkmcnt(1)
	v_add_f32_e32 v96, v96, v98
	s_waitcnt lgkmcnt(0)
	v_add_f32_e32 v97, v97, v99
	global_atomic_add_f32 v[100:101], v96, off
	global_atomic_add_f32 v[100:101], v97, off offset:4
.LBB0_250:
	s_or_b64 exec, exec, s[20:21]
	v_or_b32_e32 v118, 32, v158
	v_ashrrev_i32_e32 v119, 31, v118
	v_lshlrev_b64 v[96:97], 13, v[118:119]
	v_lshl_add_u64 v[96:97], v[160:161], 0, v[96:97]
	global_load_dwordx4 v[124:127], v[96:97], off
	global_load_dwordx4 v[128:131], v[96:97], off offset:64
	global_load_dwordx4 v[132:135], v[96:97], off offset:512
	global_load_dwordx4 v[112:115], v[96:97], off offset:576
	v_or_b32_e32 v116, 48, v158
	v_ashrrev_i32_e32 v117, 31, v116
	v_lshlrev_b64 v[96:97], 13, v[116:117]
	v_lshl_add_u64 v[96:97], v[160:161], 0, v[96:97]
	global_load_dwordx4 v[108:111], v[96:97], off
	global_load_dwordx4 v[104:107], v[96:97], off offset:64
	global_load_dwordx4 v[100:103], v[96:97], off offset:512
	s_waitcnt lgkmcnt(0)
	global_load_dwordx4 v[96:99], v[96:97], off offset:576
	v_lshlrev_b64 v[120:121], 11, v[118:119]
	v_lshl_add_u64 v[120:121], v[120:121], 0, v[156:157]
	s_waitcnt vmcnt(7)
	v_pk_add_f32 v[126:127], v[126:127], 0 op_sel_hi:[1,0]
	v_pk_add_f32 v[124:125], v[124:125], 0 op_sel_hi:[1,0]
	v_pk_mul_f32 v[126:127], v[126:127], s[12:13] op_sel_hi:[1,0]
	v_pk_mul_f32 v[124:125], v[124:125], s[12:13] op_sel_hi:[1,0]
	v_pk_fma_f32 v[94:95], v[94:95], 0.5, v[126:127] op_sel_hi:[1,0,1]
	v_pk_fma_f32 v[92:93], v[92:93], 0.5, v[124:125] op_sel_hi:[1,0,1]
	v_lshl_add_u64 v[124:125], v[120:121], 2, s[38:39]
	ds_bpermute_b32 v246, v238, v92
	ds_bpermute_b32 v247, v238, v93
	ds_bpermute_b32 v248, v238, v94
	ds_bpermute_b32 v249, v238, v95
	v_lshl_add_u64 v[244:245], v[124:125], 0, v[240:241]
	s_waitcnt lgkmcnt(0)
	global_store_dwordx4 v[244:245], v[246:249], off sc1
	v_cvt_pk_bf16_f32 v124, v92, v93
	v_lshl_add_u64 v[126:127], v[120:121], 1, s[58:59]
	v_cvt_pk_bf16_f32 v125, v94, v95
	ds_bpermute_b32 v250, v238, v124
	ds_bpermute_b32 v251, v238, v125
	v_lshl_add_u64 v[244:245], v[126:127], 0, v[242:243]
	s_waitcnt lgkmcnt(0)
; __device__ __forceinline__ unsigned cvt_pk_bf16(float lo, float hi) { unsigned r; asm volatile("v_cvt_pk_bf16_f32 %0, %1, %2" : "=v"(r) : "v"(lo), "v"(hi)); return r; }
;     __device__ __forceinline__ void operator()(const f32x4 (&acc)[2][2][4][2], const Unit& u, int wr, int wc, int fr, int fq) const {
;     ...
; #pragma unroll
;         for (int ai = 0; ai < 2; ++ai)
; #pragma unroll
;             for (int m2 = 0; m2 < 2; ++m2) {
;                 f32x4 xv[2][2][2]; f32x2 st[2];
; #pragma unroll
;                 for (int mm = 0; mm < 2; ++mm) {
;                     const int r = row0 + ai * HALF + (2 * m2 + mm) * 16;
;                     st[mm] = (f32x2){0.f, 1.f};
;                     if (rin) st[mm] = ln_stats(*(const f32x2*)(rin + 2 * (size_t)r));
; #pragma unroll
;                     for (int bj = 0; bj < 2; ++bj)
; #pragma unroll
;                         for (int n = 0; n < 2; ++n) { const f32x4* rp = (const f32x4*)(res + (size_t)r * D + col0 + bj * HALF + n * 16); xv[mm][bj][n] = stream ? __builtin_nontemporal_load(rp) : *rp; }
;                 }
; #pragma unroll
;                 for (int mm = 0; mm < 2; ++mm) {
;                     const int r = row0 + ai * HALF + (2 * m2 + mm) * 16;
;                     float ps = 0.f, pq = 0.f;
; #pragma unroll
;                     for (int bj = 0; bj < 2; ++bj)
; #pragma unroll
;                         for (int n = 0; n < 2; ++n) {
;                             const f32x4 x = (xv[mm][bj][n] - st[mm][0]) * (gg[bj][n] * st[mm][1]) + bb[bj][n];
;                             const f32x4 o = x * alpha + acc[ai][bj][2 * m2 + mm][n] * scale;
;                             const size_t off = (size_t)r * D + col0 + bj * HALF + n * 16;
;                             *(f32x4*)(Y + off) = o;
;                             if (yb) { u32x2 w; w.x = cvt_pk_bf16(o[0], o[1]); w.y = cvt_pk_bf16(o[2], o[3]); *(u32x2*)(yb + off) = w; }
;                             ps += (o[0] + o[1]) + (o[2] + o[3]); pq += (o[0] * o[0] + o[1] * o[1]) + (o[2] * o[2] + o[3] * o[3]);
;                         }
;                     if (rout) {
;                         ps += __shfl_xor(ps, 16); pq += __shfl_xor(pq, 16); ps += __shfl_xor(ps, 32); pq += __shfl_xor(pq, 32);
;                         if (fq == 0) { atomicAdd(rout + 2 * (size_t)r, ps); atomicAdd(rout + 2 * (size_t)r + 1, pq); }
;                     }
	global_store_dwordx2 v[244:245], v[250:251], off
	v_add_f32_e32 v124, v92, v93
	v_mul_f32_e32 v93, v93, v93
	v_fmac_f32_e32 v93, v92, v92
	v_mul_f32_e32 v92, v94, v94
	v_add_f32_e32 v125, v95, v94
	v_fmac_f32_e32 v92, v95, v95
	v_add_f32_e32 v124, v124, v125
	v_add_f32_e32 v125, v93, v92
	s_waitcnt vmcnt(8)
	v_pk_add_f32 v[92:93], v[130:131], 0 op_sel_hi:[1,0]
	v_pk_add_f32 v[94:95], v[128:129], 0 op_sel_hi:[1,0]
	v_pk_mul_f32 v[92:93], v[92:93], s[12:13] op_sel_hi:[1,0]
	v_pk_mul_f32 v[94:95], v[94:95], s[12:13] op_sel_hi:[1,0]
	v_pk_fma_f32 v[90:91], v[90:91], 0.5, v[92:93] op_sel_hi:[1,0,1]
	v_or_b32_e32 v92, 16, v120
	v_mov_b32_e32 v93, v121
	v_pk_fma_f32 v[88:89], v[88:89], 0.5, v[94:95] op_sel_hi:[1,0,1]
	v_lshl_add_u64 v[94:95], v[92:93], 2, s[38:39]
	v_lshl_add_u64 v[92:93], v[92:93], 1, s[58:59]
	ds_bpermute_b32 v246, v238, v88
	ds_bpermute_b32 v247, v238, v89
	ds_bpermute_b32 v248, v238, v90
	ds_bpermute_b32 v249, v238, v91
	v_lshl_add_u64 v[244:245], v[94:95], 0, v[240:241]
	s_waitcnt lgkmcnt(0)
	global_store_dwordx4 v[244:245], v[246:249], off sc1
	v_cvt_pk_bf16_f32 v94, v88, v89
	v_cvt_pk_bf16_f32 v95, v90, v91
	ds_bpermute_b32 v250, v238, v94
	ds_bpermute_b32 v251, v238, v95
	v_lshl_add_u64 v[244:245], v[92:93], 0, v[242:243]
	s_waitcnt lgkmcnt(0)
	global_store_dwordx2 v[244:245], v[250:251], off
	v_add_f32_e32 v92, v88, v89
	v_mul_f32_e32 v89, v89, v89
	v_add_f32_e32 v93, v91, v90
	v_fmac_f32_e32 v89, v88, v88
	v_mul_f32_e32 v88, v90, v90
	v_add_f32_e32 v124, 0, v124
	v_add_f32_e32 v92, v92, v93
	v_fmac_f32_e32 v88, v91, v91
	v_add_f32_e32 v94, v124, v92
	v_add_f32_e32 v88, v89, v88
	s_waitcnt vmcnt(9)
	v_pk_add_f32 v[90:91], v[134:135], 0 op_sel_hi:[1,0]
	v_pk_add_f32 v[92:93], v[132:133], 0 op_sel_hi:[1,0]
	v_add_f32_e32 v95, v125, v88
	v_or_b32_e32 v88, 0x80, v120
	v_mov_b32_e32 v89, v121
	v_pk_mul_f32 v[90:91], v[90:91], s[12:13] op_sel_hi:[1,0]
	v_pk_mul_f32 v[92:93], v[92:93], s[12:13] op_sel_hi:[1,0]
	v_pk_fma_f32 v[86:87], v[86:87], 0.5, v[90:91] op_sel_hi:[1,0,1]
	v_pk_fma_f32 v[84:85], v[84:85], 0.5, v[92:93] op_sel_hi:[1,0,1]
	v_lshl_add_u64 v[90:91], v[88:89], 2, s[38:39]
	v_lshl_add_u64 v[88:89], v[88:89], 1, s[58:59]
	ds_bpermute_b32 v246, v238, v84
	ds_bpermute_b32 v247, v238, v85
	ds_bpermute_b32 v248, v238, v86
	ds_bpermute_b32 v249, v238, v87
	v_lshl_add_u64 v[244:245], v[90:91], 0, v[240:241]
	s_waitcnt lgkmcnt(0)
	global_store_dwordx4 v[244:245], v[246:249], off sc1
	v_cvt_pk_bf16_f32 v90, v84, v85
	v_cvt_pk_bf16_f32 v91, v86, v87
	ds_bpermute_b32 v250, v238, v90
	ds_bpermute_b32 v251, v238, v91
	v_lshl_add_u64 v[244:245], v[88:89], 0, v[242:243]
	s_waitcnt lgkmcnt(0)
	global_store_dwordx2 v[244:245], v[250:251], off
	v_add_f32_e32 v88, v84, v85
	v_mul_f32_e32 v85, v85, v85
	v_fmac_f32_e32 v85, v84, v84
	v_mul_f32_e32 v84, v86, v86
	v_fmac_f32_e32 v84, v87, v87
	v_add_f32_e32 v89, v87, v86
	v_add_f32_e32 v84, v85, v84
	v_add_f32_e32 v88, v88, v89
	v_add_f32_e32 v89, v95, v84
	s_waitcnt vmcnt(10)
	v_pk_add_f32 v[84:85], v[114:115], 0 op_sel_hi:[1,0]
	v_pk_add_f32 v[86:87], v[112:113], 0 op_sel_hi:[1,0]
	v_pk_mul_f32 v[84:85], v[84:85], s[12:13] op_sel_hi:[1,0]
	v_pk_mul_f32 v[86:87], v[86:87], s[12:13] op_sel_hi:[1,0]
	v_or_b32_e32 v120, 0x90, v120
	v_pk_fma_f32 v[82:83], v[82:83], 0.5, v[84:85] op_sel_hi:[1,0,1]
	v_pk_fma_f32 v[80:81], v[80:81], 0.5, v[86:87] op_sel_hi:[1,0,1]
	v_lshl_add_u64 v[84:85], v[120:121], 2, s[38:39]
	ds_bpermute_b32 v246, v238, v80
	ds_bpermute_b32 v247, v238, v81
	ds_bpermute_b32 v248, v238, v82
	ds_bpermute_b32 v249, v238, v83
	v_lshl_add_u64 v[244:245], v[84:85], 0, v[240:241]
	s_waitcnt lgkmcnt(0)
	global_store_dwordx4 v[244:245], v[246:249], off sc1
	v_cvt_pk_bf16_f32 v84, v80, v81
	v_lshl_add_u64 v[86:87], v[120:121], 1, s[58:59]
	v_cvt_pk_bf16_f32 v85, v82, v83
	ds_bpermute_b32 v250, v238, v84
	ds_bpermute_b32 v251, v238, v85
	v_lshl_add_u64 v[244:245], v[86:87], 0, v[242:243]
	s_waitcnt lgkmcnt(0)
	global_store_dwordx2 v[244:245], v[250:251], off
	v_mul_f32_e32 v84, v81, v81
	v_fmac_f32_e32 v84, v80, v80
	v_add_f32_e32 v80, v80, v81
	v_add_f32_e32 v81, v83, v82
	v_add_f32_e32 v88, v94, v88
	v_add_f32_e32 v80, v80, v81
	v_add_f32_e32 v80, v88, v80
	ds_bpermute_b32 v81, v122, v80
	v_mul_f32_e32 v85, v82, v82
	v_fmac_f32_e32 v85, v83, v83
	v_add_f32_e32 v84, v84, v85
	v_add_f32_e32 v84, v89, v84
	s_waitcnt lgkmcnt(0)
	v_add_f32_e32 v80, v80, v81
	ds_bpermute_b32 v81, v122, v84
	ds_bpermute_b32 v82, v123, v80
	s_waitcnt lgkmcnt(1)
	v_add_f32_e32 v81, v84, v81
	ds_bpermute_b32 v83, v123, v81
	s_and_saveexec_b64 s[20:21], s[4:5]
	s_cbranch_execz .LBB0_252
	v_lshl_add_u64 v[84:85], v[118:119], 3, s[54:55]
	s_waitcnt lgkmcnt(1)
	v_add_f32_e32 v80, v80, v82
	s_waitcnt lgkmcnt(0)
	v_add_f32_e32 v81, v81, v83
	global_atomic_add_f32 v[84:85], v80, off
	global_atomic_add_f32 v[84:85], v81, off offset:4
; __device__ __forceinline__ unsigned cvt_pk_bf16(float lo, float hi) { unsigned r; asm volatile("v_cvt_pk_bf16_f32 %0, %1, %2" : "=v"(r) : "v"(lo), "v"(hi)); return r; }
;     __device__ __forceinline__ void operator()(const f32x4 (&acc)[2][2][4][2], const Unit& u, int wr, int wc, int fr, int fq) const {
;     ...
; #pragma unroll
;         for (int ai = 0; ai < 2; ++ai)
; #pragma unroll
;             for (int m2 = 0; m2 < 2; ++m2) {
;                 f32x4 xv[2][2][2]; f32x2 st[2];
; #pragma unroll
;                 for (int mm = 0; mm < 2; ++mm) {
;                     const int r = row0 + ai * HALF + (2 * m2 + mm) * 16;
;                     st[mm] = (f32x2){0.f, 1.f};
;                     if (rin) st[mm] = ln_stats(*(const f32x2*)(rin + 2 * (size_t)r));
; #pragma unroll
;                     for (int bj = 0; bj < 2; ++bj)
; #pragma unroll
;                         for (int n = 0; n < 2; ++n) { const f32x4* rp = (const f32x4*)(res + (size_t)r * D + col0 + bj * HALF + n * 16); xv[mm][bj][n] = stream ? __builtin_nontemporal_load(rp) : *rp; }
;                 }
; #pragma unroll
;                 for (int mm = 0; mm < 2; ++mm) {
;                     const int r = row0 + ai * HALF + (2 * m2 + mm) * 16;
;                     float ps = 0.f, pq = 0.f;
; #pragma unroll
;                     for (int bj = 0; bj < 2; ++bj)
; #pragma unroll
;                         for (int n = 0; n < 2; ++n) {
;                             const f32x4 x = (xv[mm][bj][n] - st[mm][0]) * (gg[bj][n] * st[mm][1]) + bb[bj][n];
;                             const f32x4 o = x * alpha + acc[ai][bj][2 * m2 + mm][n] * scale;
;                             const size_t off = (size_t)r * D + col0 + bj * HALF + n * 16;
;                             *(f32x4*)(Y + off) = o;
;                             if (yb) { u32x2 w; w.x = cvt_pk_bf16(o[0], o[1]); w.y = cvt_pk_bf16(o[2], o[3]); *(u32x2*)(yb + off) = w; }
;                             ps += (o[0] + o[1]) + (o[2] + o[3]); pq += (o[0] * o[0] + o[1] * o[1]) + (o[2] * o[2] + o[3] * o[3]);
;                         }
;                     if (rout) {
;                         ps += __shfl_xor(ps, 16); pq += __shfl_xor(pq, 16); ps += __shfl_xor(ps, 32); pq += __shfl_xor(pq, 32);
;                         if (fq == 0) { atomicAdd(rout + 2 * (size_t)r, ps); atomicAdd(rout + 2 * (size_t)r + 1, pq); }
;                     }
.LBB0_252:
	s_or_b64 exec, exec, s[20:21]
	v_lshlrev_b64 v[80:81], 11, v[116:117]
	s_waitcnt vmcnt(11) lgkmcnt(0)
	v_pk_add_f32 v[82:83], v[110:111], 0 op_sel_hi:[1,0]
	v_pk_add_f32 v[84:85], v[108:109], 0 op_sel_hi:[1,0]
	v_lshl_add_u64 v[80:81], v[80:81], 0, v[156:157]
	v_pk_mul_f32 v[82:83], v[82:83], s[12:13] op_sel_hi:[1,0]
	v_pk_mul_f32 v[84:85], v[84:85], s[12:13] op_sel_hi:[1,0]
	v_pk_fma_f32 v[78:79], v[78:79], 0.5, v[82:83] op_sel_hi:[1,0,1]
	v_pk_fma_f32 v[76:77], v[76:77], 0.5, v[84:85] op_sel_hi:[1,0,1]
	v_lshl_add_u64 v[82:83], v[80:81], 2, s[38:39]
	ds_bpermute_b32 v246, v238, v76
	ds_bpermute_b32 v247, v238, v77
	ds_bpermute_b32 v248, v238, v78
	ds_bpermute_b32 v249, v238, v79
	v_lshl_add_u64 v[244:245], v[82:83], 0, v[240:241]
	s_waitcnt lgkmcnt(0)
	global_store_dwordx4 v[244:245], v[246:249], off sc1
	v_cvt_pk_bf16_f32 v82, v76, v77
	v_lshl_add_u64 v[84:85], v[80:81], 1, s[58:59]
	v_cvt_pk_bf16_f32 v83, v78, v79
	ds_bpermute_b32 v250, v238, v82
	ds_bpermute_b32 v251, v238, v83
	v_lshl_add_u64 v[244:245], v[84:85], 0, v[242:243]
	s_waitcnt lgkmcnt(0)
	global_store_dwordx2 v[244:245], v[250:251], off
	v_add_f32_e32 v82, v76, v77
	v_mul_f32_e32 v77, v77, v77
	v_fmac_f32_e32 v77, v76, v76
	v_mul_f32_e32 v76, v78, v78
	v_add_f32_e32 v83, v79, v78
	v_fmac_f32_e32 v76, v79, v79
	v_add_f32_e32 v82, v82, v83
	v_add_f32_e32 v83, v77, v76
	s_waitcnt vmcnt(12)
	v_pk_add_f32 v[76:77], v[106:107], 0 op_sel_hi:[1,0]
	v_pk_add_f32 v[78:79], v[104:105], 0 op_sel_hi:[1,0]
	v_pk_mul_f32 v[76:77], v[76:77], s[12:13] op_sel_hi:[1,0]
	v_pk_mul_f32 v[78:79], v[78:79], s[12:13] op_sel_hi:[1,0]
	v_pk_fma_f32 v[74:75], v[74:75], 0.5, v[76:77] op_sel_hi:[1,0,1]
	v_or_b32_e32 v76, 16, v80
	v_mov_b32_e32 v77, v81
	v_pk_fma_f32 v[72:73], v[72:73], 0.5, v[78:79] op_sel_hi:[1,0,1]
	v_lshl_add_u64 v[78:79], v[76:77], 2, s[38:39]
	v_lshl_add_u64 v[76:77], v[76:77], 1, s[58:59]
	ds_bpermute_b32 v246, v238, v72
	ds_bpermute_b32 v247, v238, v73
	ds_bpermute_b32 v248, v238, v74
	ds_bpermute_b32 v249, v238, v75
	v_lshl_add_u64 v[244:245], v[78:79], 0, v[240:241]
	s_waitcnt lgkmcnt(0)
	global_store_dwordx4 v[244:245], v[246:249], off sc1
	v_cvt_pk_bf16_f32 v78, v72, v73
	v_cvt_pk_bf16_f32 v79, v74, v75
	ds_bpermute_b32 v250, v238, v78
	ds_bpermute_b32 v251, v238, v79
	v_lshl_add_u64 v[244:245], v[76:77], 0, v[242:243]
	s_waitcnt lgkmcnt(0)
	global_store_dwordx2 v[244:245], v[250:251], off
	v_add_f32_e32 v76, v72, v73
	v_mul_f32_e32 v73, v73, v73
	v_add_f32_e32 v77, v75, v74
	v_fmac_f32_e32 v73, v72, v72
	v_mul_f32_e32 v72, v74, v74
	v_add_f32_e32 v82, 0, v82
	v_add_f32_e32 v76, v76, v77
	v_fmac_f32_e32 v72, v75, v75
	v_add_f32_e32 v78, v82, v76
	v_add_f32_e32 v72, v73, v72
	s_waitcnt vmcnt(13)
	v_pk_add_f32 v[74:75], v[102:103], 0 op_sel_hi:[1,0]
	v_pk_add_f32 v[76:77], v[100:101], 0 op_sel_hi:[1,0]
	v_add_f32_e32 v79, v83, v72
	v_or_b32_e32 v72, 0x80, v80
	v_mov_b32_e32 v73, v81
	v_pk_mul_f32 v[74:75], v[74:75], s[12:13] op_sel_hi:[1,0]
	v_pk_mul_f32 v[76:77], v[76:77], s[12:13] op_sel_hi:[1,0]
	v_pk_fma_f32 v[70:71], v[70:71], 0.5, v[74:75] op_sel_hi:[1,0,1]
	v_pk_fma_f32 v[68:69], v[68:69], 0.5, v[76:77] op_sel_hi:[1,0,1]
	v_lshl_add_u64 v[74:75], v[72:73], 2, s[38:39]
	v_lshl_add_u64 v[72:73], v[72:73], 1, s[58:59]
	ds_bpermute_b32 v246, v238, v68
	ds_bpermute_b32 v247, v238, v69
	ds_bpermute_b32 v248, v238, v70
	ds_bpermute_b32 v249, v238, v71
	v_lshl_add_u64 v[244:245], v[74:75], 0, v[240:241]
	s_waitcnt lgkmcnt(0)
	global_store_dwordx4 v[244:245], v[246:249], off sc1
	v_cvt_pk_bf16_f32 v74, v68, v69
	v_cvt_pk_bf16_f32 v75, v70, v71
	ds_bpermute_b32 v250, v238, v74
	ds_bpermute_b32 v251, v238, v75
	v_lshl_add_u64 v[244:245], v[72:73], 0, v[242:243]
	s_waitcnt lgkmcnt(0)
	global_store_dwordx2 v[244:245], v[250:251], off
	v_add_f32_e32 v72, v68, v69
	v_mul_f32_e32 v69, v69, v69
	v_fmac_f32_e32 v69, v68, v68
	v_mul_f32_e32 v68, v70, v70
	v_fmac_f32_e32 v68, v71, v71
	v_add_f32_e32 v73, v71, v70
	v_add_f32_e32 v68, v69, v68
	v_add_f32_e32 v72, v72, v73
	v_add_f32_e32 v75, v79, v68
	s_waitcnt vmcnt(14)
	v_pk_add_f32 v[68:69], v[98:99], 0 op_sel_hi:[1,0]
	v_pk_add_f32 v[70:71], v[96:97], 0 op_sel_hi:[1,0]
	v_add_f32_e32 v74, v78, v72
	v_pk_mul_f32 v[68:69], v[68:69], s[12:13] op_sel_hi:[1,0]
	v_pk_mul_f32 v[72:73], v[70:71], s[12:13] op_sel_hi:[1,0]
	v_pk_fma_f32 v[70:71], v[66:67], 0.5, v[68:69] op_sel_hi:[1,0,1]
	v_pk_fma_f32 v[68:69], v[64:65], 0.5, v[72:73] op_sel_hi:[1,0,1]
	v_mul_f32_e32 v65, v70, v70
	v_mul_f32_e32 v64, v69, v69
	v_fmac_f32_e32 v64, v68, v68
	v_fmac_f32_e32 v65, v71, v71
	v_add_f32_e32 v64, v64, v65
	v_add_f32_e32 v66, v75, v64
	v_add_f32_e32 v64, v68, v69
	v_add_f32_e32 v65, v71, v70
	v_add_f32_e32 v64, v64, v65
	v_add_f32_e32 v67, v74, v64
	ds_bpermute_b32 v72, v122, v67
	ds_bpermute_b32 v73, v122, v66
	v_or_b32_e32 v80, 0x90, v80
	v_lshl_add_u64 v[64:65], v[80:81], 2, s[38:39]
	ds_bpermute_b32 v246, v238, v68
	ds_bpermute_b32 v247, v238, v69
	ds_bpermute_b32 v248, v238, v70
	ds_bpermute_b32 v249, v238, v71
	v_lshl_add_u64 v[244:245], v[64:65], 0, v[240:241]
	s_waitcnt lgkmcnt(0)
	global_store_dwordx4 v[244:245], v[246:249], off sc1
	s_waitcnt lgkmcnt(1)
	v_add_f32_e32 v64, v67, v72
	s_waitcnt lgkmcnt(0)
	v_add_f32_e32 v65, v66, v73
	ds_bpermute_b32 v66, v123, v64
	ds_bpermute_b32 v67, v123, v65
	v_cvt_pk_bf16_f32 v68, v68, v69
	v_cvt_pk_bf16_f32 v69, v70, v71
	v_lshl_add_u64 v[70:71], v[80:81], 1, s[58:59]
	ds_bpermute_b32 v250, v238, v68
	ds_bpermute_b32 v251, v238, v69
	v_lshl_add_u64 v[244:245], v[70:71], 0, v[242:243]
	s_waitcnt lgkmcnt(0)
	global_store_dwordx2 v[244:245], v[250:251], off
	s_and_saveexec_b64 s[20:21], s[4:5]
	s_cbranch_execz .LBB0_254
	v_lshl_add_u64 v[68:69], v[116:117], 3, s[54:55]
	s_waitcnt lgkmcnt(1)
	v_add_f32_e32 v64, v64, v66
	s_waitcnt lgkmcnt(0)
	v_add_f32_e32 v65, v65, v67
	global_atomic_add_f32 v[68:69], v64, off
	global_atomic_add_f32 v[68:69], v65, off offset:4
; __device__ __forceinline__ unsigned cvt_pk_bf16(float lo, float hi) { unsigned r; asm volatile("v_cvt_pk_bf16_f32 %0, %1, %2" : "=v"(r) : "v"(lo), "v"(hi)); return r; }
;     __device__ __forceinline__ void operator()(const f32x4 (&acc)[2][2][4][2], const Unit& u, int wr, int wc, int fr, int fq) const {
;     ...
; #pragma unroll
;         for (int ai = 0; ai < 2; ++ai)
; #pragma unroll
;             for (int m2 = 0; m2 < 2; ++m2) {
;                 f32x4 xv[2][2][2]; f32x2 st[2];
; #pragma unroll
;                 for (int mm = 0; mm < 2; ++mm) {
;                     const int r = row0 + ai * HALF + (2 * m2 + mm) * 16;
;                     st[mm] = (f32x2){0.f, 1.f};
;                     if (rin) st[mm] = ln_stats(*(const f32x2*)(rin + 2 * (size_t)r));
; #pragma unroll
;                     for (int bj = 0; bj < 2; ++bj)
; #pragma unroll
;                         for (int n = 0; n < 2; ++n) { const f32x4* rp = (const f32x4*)(res + (size_t)r * D + col0 + bj * HALF + n * 16); xv[mm][bj][n] = stream ? __builtin_nontemporal_load(rp) : *rp; }
;                 }
; #pragma unroll
;                 for (int mm = 0; mm < 2; ++mm) {
;                     const int r = row0 + ai * HALF + (2 * m2 + mm) * 16;
;                     float ps = 0.f, pq = 0.f;
; #pragma unroll
;                     for (int bj = 0; bj < 2; ++bj)
; #pragma unroll
;                         for (int n = 0; n < 2; ++n) {
;                             const f32x4 x = (xv[mm][bj][n] - st[mm][0]) * (gg[bj][n] * st[mm][1]) + bb[bj][n];
;                             const f32x4 o = x * alpha + acc[ai][bj][2 * m2 + mm][n] * scale;
;                             const size_t off = (size_t)r * D + col0 + bj * HALF + n * 16;
;                             *(f32x4*)(Y + off) = o;
;                             if (yb) { u32x2 w; w.x = cvt_pk_bf16(o[0], o[1]); w.y = cvt_pk_bf16(o[2], o[3]); *(u32x2*)(yb + off) = w; }
;                             ps += (o[0] + o[1]) + (o[2] + o[3]); pq += (o[0] * o[0] + o[1] * o[1]) + (o[2] * o[2] + o[3] * o[3]);
;                         }
;                     if (rout) {
;                         ps += __shfl_xor(ps, 16); pq += __shfl_xor(pq, 16); ps += __shfl_xor(ps, 32); pq += __shfl_xor(pq, 32);
;                         if (fq == 0) { atomicAdd(rout + 2 * (size_t)r, ps); atomicAdd(rout + 2 * (size_t)r + 1, pq); }
;                     }
.LBB0_254:
	s_or_b64 exec, exec, s[20:21]
	v_add_u32_e32 v86, 0x80, v158
	v_ashrrev_i32_e32 v87, 31, v86
	v_lshlrev_b64 v[64:65], 13, v[86:87]
	v_lshl_add_u64 v[64:65], v[160:161], 0, v[64:65]
	global_load_dwordx4 v[90:93], v[64:65], off
	global_load_dwordx4 v[94:97], v[64:65], off offset:64
	global_load_dwordx4 v[98:101], v[64:65], off offset:512
	global_load_dwordx4 v[80:83], v[64:65], off offset:576
	v_add_u32_e32 v84, 0x90, v158
	v_ashrrev_i32_e32 v85, 31, v84
	v_lshlrev_b64 v[64:65], 13, v[84:85]
	v_lshl_add_u64 v[64:65], v[160:161], 0, v[64:65]
	global_load_dwordx4 v[76:79], v[64:65], off
	global_load_dwordx4 v[72:75], v[64:65], off offset:64
	global_load_dwordx4 v[68:71], v[64:65], off offset:512
	s_waitcnt lgkmcnt(0)
	global_load_dwordx4 v[64:67], v[64:65], off offset:576
	v_lshlrev_b64 v[88:89], 11, v[86:87]
	v_lshl_add_u64 v[88:89], v[88:89], 0, v[156:157]
	s_waitcnt vmcnt(7)
	v_pk_add_f32 v[92:93], v[92:93], 0 op_sel_hi:[1,0]
	v_pk_add_f32 v[90:91], v[90:91], 0 op_sel_hi:[1,0]
	v_pk_mul_f32 v[92:93], v[92:93], s[12:13] op_sel_hi:[1,0]
	v_pk_mul_f32 v[90:91], v[90:91], s[12:13] op_sel_hi:[1,0]
	v_pk_fma_f32 v[62:63], v[62:63], 0.5, v[92:93] op_sel_hi:[1,0,1]
	v_pk_fma_f32 v[60:61], v[60:61], 0.5, v[90:91] op_sel_hi:[1,0,1]
	v_lshl_add_u64 v[90:91], v[88:89], 2, s[38:39]
	ds_bpermute_b32 v246, v238, v60
	ds_bpermute_b32 v247, v238, v61
	ds_bpermute_b32 v248, v238, v62
	ds_bpermute_b32 v249, v238, v63
	v_lshl_add_u64 v[244:245], v[90:91], 0, v[240:241]
	s_waitcnt lgkmcnt(0)
	global_store_dwordx4 v[244:245], v[246:249], off sc1
	v_cvt_pk_bf16_f32 v90, v60, v61
	v_lshl_add_u64 v[92:93], v[88:89], 1, s[58:59]
	v_cvt_pk_bf16_f32 v91, v62, v63
	ds_bpermute_b32 v250, v238, v90
	ds_bpermute_b32 v251, v238, v91
	v_lshl_add_u64 v[244:245], v[92:93], 0, v[242:243]
	s_waitcnt lgkmcnt(0)
	global_store_dwordx2 v[244:245], v[250:251], off
	v_add_f32_e32 v90, v60, v61
	v_mul_f32_e32 v61, v61, v61
	v_fmac_f32_e32 v61, v60, v60
	v_mul_f32_e32 v60, v62, v62
	v_add_f32_e32 v91, v63, v62
	v_fmac_f32_e32 v60, v63, v63
	v_add_f32_e32 v90, v90, v91
	v_add_f32_e32 v91, v61, v60
	s_waitcnt vmcnt(8)
	v_pk_add_f32 v[60:61], v[96:97], 0 op_sel_hi:[1,0]
	v_pk_add_f32 v[62:63], v[94:95], 0 op_sel_hi:[1,0]
	v_pk_mul_f32 v[60:61], v[60:61], s[12:13] op_sel_hi:[1,0]
	v_pk_mul_f32 v[62:63], v[62:63], s[12:13] op_sel_hi:[1,0]
	v_pk_fma_f32 v[58:59], v[58:59], 0.5, v[60:61] op_sel_hi:[1,0,1]
	v_or_b32_e32 v60, 16, v88
	v_mov_b32_e32 v61, v89
	v_pk_fma_f32 v[56:57], v[56:57], 0.5, v[62:63] op_sel_hi:[1,0,1]
	v_lshl_add_u64 v[62:63], v[60:61], 2, s[38:39]
	v_lshl_add_u64 v[60:61], v[60:61], 1, s[58:59]
	ds_bpermute_b32 v246, v238, v56
	ds_bpermute_b32 v247, v238, v57
	ds_bpermute_b32 v248, v238, v58
	ds_bpermute_b32 v249, v238, v59
	v_lshl_add_u64 v[244:245], v[62:63], 0, v[240:241]
	s_waitcnt lgkmcnt(0)
	global_store_dwordx4 v[244:245], v[246:249], off sc1
	v_cvt_pk_bf16_f32 v62, v56, v57
	v_cvt_pk_bf16_f32 v63, v58, v59
	ds_bpermute_b32 v250, v238, v62
	ds_bpermute_b32 v251, v238, v63
	v_lshl_add_u64 v[244:245], v[60:61], 0, v[242:243]
	s_waitcnt lgkmcnt(0)
	global_store_dwordx2 v[244:245], v[250:251], off
	v_add_f32_e32 v60, v56, v57
	v_mul_f32_e32 v57, v57, v57
	v_add_f32_e32 v61, v59, v58
	v_fmac_f32_e32 v57, v56, v56
	v_mul_f32_e32 v56, v58, v58
	v_add_f32_e32 v90, 0, v90
	v_add_f32_e32 v60, v60, v61
	v_fmac_f32_e32 v56, v59, v59
	v_add_f32_e32 v62, v90, v60
	v_add_f32_e32 v56, v57, v56
	s_waitcnt vmcnt(9)
	v_pk_add_f32 v[58:59], v[100:101], 0 op_sel_hi:[1,0]
	v_pk_add_f32 v[60:61], v[98:99], 0 op_sel_hi:[1,0]
	v_add_f32_e32 v63, v91, v56
	v_or_b32_e32 v56, 0x80, v88
	v_mov_b32_e32 v57, v89
	v_pk_mul_f32 v[58:59], v[58:59], s[12:13] op_sel_hi:[1,0]
	v_pk_mul_f32 v[60:61], v[60:61], s[12:13] op_sel_hi:[1,0]
	v_pk_fma_f32 v[54:55], v[54:55], 0.5, v[58:59] op_sel_hi:[1,0,1]
	v_pk_fma_f32 v[52:53], v[52:53], 0.5, v[60:61] op_sel_hi:[1,0,1]
	v_lshl_add_u64 v[58:59], v[56:57], 2, s[38:39]
	v_lshl_add_u64 v[56:57], v[56:57], 1, s[58:59]
	ds_bpermute_b32 v246, v238, v52
	ds_bpermute_b32 v247, v238, v53
	ds_bpermute_b32 v248, v238, v54
	ds_bpermute_b32 v249, v238, v55
	v_lshl_add_u64 v[244:245], v[58:59], 0, v[240:241]
	s_waitcnt lgkmcnt(0)
	global_store_dwordx4 v[244:245], v[246:249], off sc1
	v_cvt_pk_bf16_f32 v58, v52, v53
	v_cvt_pk_bf16_f32 v59, v54, v55
	ds_bpermute_b32 v250, v238, v58
	ds_bpermute_b32 v251, v238, v59
	v_lshl_add_u64 v[244:245], v[56:57], 0, v[242:243]
	s_waitcnt lgkmcnt(0)
	global_store_dwordx2 v[244:245], v[250:251], off
	v_add_f32_e32 v56, v52, v53
	v_mul_f32_e32 v53, v53, v53
	v_fmac_f32_e32 v53, v52, v52
	v_mul_f32_e32 v52, v54, v54
	v_fmac_f32_e32 v52, v55, v55
	v_add_f32_e32 v57, v55, v54
	v_add_f32_e32 v52, v53, v52
	v_add_f32_e32 v56, v56, v57
	v_add_f32_e32 v57, v63, v52
	s_waitcnt vmcnt(10)
	v_pk_add_f32 v[52:53], v[82:83], 0 op_sel_hi:[1,0]
	v_pk_add_f32 v[54:55], v[80:81], 0 op_sel_hi:[1,0]
	v_pk_mul_f32 v[52:53], v[52:53], s[12:13] op_sel_hi:[1,0]
	v_pk_mul_f32 v[54:55], v[54:55], s[12:13] op_sel_hi:[1,0]
	v_or_b32_e32 v88, 0x90, v88
	v_pk_fma_f32 v[50:51], v[50:51], 0.5, v[52:53] op_sel_hi:[1,0,1]
	v_pk_fma_f32 v[48:49], v[48:49], 0.5, v[54:55] op_sel_hi:[1,0,1]
	v_lshl_add_u64 v[52:53], v[88:89], 2, s[38:39]
	ds_bpermute_b32 v246, v238, v48
	ds_bpermute_b32 v247, v238, v49
	ds_bpermute_b32 v248, v238, v50
	ds_bpermute_b32 v249, v238, v51
	v_lshl_add_u64 v[244:245], v[52:53], 0, v[240:241]
	s_waitcnt lgkmcnt(0)
	global_store_dwordx4 v[244:245], v[246:249], off sc1
	v_cvt_pk_bf16_f32 v52, v48, v49
	v_lshl_add_u64 v[54:55], v[88:89], 1, s[58:59]
	v_cvt_pk_bf16_f32 v53, v50, v51
	ds_bpermute_b32 v250, v238, v52
	ds_bpermute_b32 v251, v238, v53
	v_lshl_add_u64 v[244:245], v[54:55], 0, v[242:243]
	s_waitcnt lgkmcnt(0)
	global_store_dwordx2 v[244:245], v[250:251], off
	v_mul_f32_e32 v52, v49, v49
	v_fmac_f32_e32 v52, v48, v48
	v_add_f32_e32 v48, v48, v49
	v_add_f32_e32 v49, v51, v50
	v_add_f32_e32 v56, v62, v56
	v_add_f32_e32 v48, v48, v49
	v_add_f32_e32 v48, v56, v48
	ds_bpermute_b32 v49, v122, v48
	v_mul_f32_e32 v53, v50, v50
	v_fmac_f32_e32 v53, v51, v51
	v_add_f32_e32 v52, v52, v53
	v_add_f32_e32 v52, v57, v52
	s_waitcnt lgkmcnt(0)
	v_add_f32_e32 v48, v48, v49
	ds_bpermute_b32 v49, v122, v52
	ds_bpermute_b32 v50, v123, v48
	s_waitcnt lgkmcnt(1)
	v_add_f32_e32 v49, v52, v49
	ds_bpermute_b32 v51, v123, v49
	s_and_saveexec_b64 s[20:21], s[4:5]
	s_cbranch_execz .LBB0_256
	v_lshl_add_u64 v[52:53], v[86:87], 3, s[54:55]
	s_waitcnt lgkmcnt(1)
	v_add_f32_e32 v48, v48, v50
	s_waitcnt lgkmcnt(0)
	v_add_f32_e32 v49, v49, v51
	global_atomic_add_f32 v[52:53], v48, off
	global_atomic_add_f32 v[52:53], v49, off offset:4
; __device__ __forceinline__ unsigned cvt_pk_bf16(float lo, float hi) { unsigned r; asm volatile("v_cvt_pk_bf16_f32 %0, %1, %2" : "=v"(r) : "v"(lo), "v"(hi)); return r; }
;     __device__ __forceinline__ void operator()(const f32x4 (&acc)[2][2][4][2], const Unit& u, int wr, int wc, int fr, int fq) const {
;     ...
; #pragma unroll
;         for (int ai = 0; ai < 2; ++ai)
; #pragma unroll
;             for (int m2 = 0; m2 < 2; ++m2) {
;                 f32x4 xv[2][2][2]; f32x2 st[2];
; #pragma unroll
;                 for (int mm = 0; mm < 2; ++mm) {
;                     const int r = row0 + ai * HALF + (2 * m2 + mm) * 16;
;                     st[mm] = (f32x2){0.f, 1.f};
;                     if (rin) st[mm] = ln_stats(*(const f32x2*)(rin + 2 * (size_t)r));
; #pragma unroll
;                     for (int bj = 0; bj < 2; ++bj)
; #pragma unroll
;                         for (int n = 0; n < 2; ++n) { const f32x4* rp = (const f32x4*)(res + (size_t)r * D + col0 + bj * HALF + n * 16); xv[mm][bj][n] = stream ? __builtin_nontemporal_load(rp) : *rp; }
;                 }
; #pragma unroll
;                 for (int mm = 0; mm < 2; ++mm) {
;                     const int r = row0 + ai * HALF + (2 * m2 + mm) * 16;
;                     float ps = 0.f, pq = 0.f;
; #pragma unroll
;                     for (int bj = 0; bj < 2; ++bj)
; #pragma unroll
;                         for (int n = 0; n < 2; ++n) {
;                             const f32x4 x = (xv[mm][bj][n] - st[mm][0]) * (gg[bj][n] * st[mm][1]) + bb[bj][n];
;                             const f32x4 o = x * alpha + acc[ai][bj][2 * m2 + mm][n] * scale;
;                             const size_t off = (size_t)r * D + col0 + bj * HALF + n * 16;
;                             *(f32x4*)(Y + off) = o;
;                             if (yb) { u32x2 w; w.x = cvt_pk_bf16(o[0], o[1]); w.y = cvt_pk_bf16(o[2], o[3]); *(u32x2*)(yb + off) = w; }
;                             ps += (o[0] + o[1]) + (o[2] + o[3]); pq += (o[0] * o[0] + o[1] * o[1]) + (o[2] * o[2] + o[3] * o[3]);
;                         }
;                     if (rout) {
;                         ps += __shfl_xor(ps, 16); pq += __shfl_xor(pq, 16); ps += __shfl_xor(ps, 32); pq += __shfl_xor(pq, 32);
;                         if (fq == 0) { atomicAdd(rout + 2 * (size_t)r, ps); atomicAdd(rout + 2 * (size_t)r + 1, pq); }
;                     }
.LBB0_256:
	s_or_b64 exec, exec, s[20:21]
	v_lshlrev_b64 v[48:49], 11, v[84:85]
	s_waitcnt vmcnt(11) lgkmcnt(0)
	v_pk_add_f32 v[50:51], v[78:79], 0 op_sel_hi:[1,0]
	v_pk_add_f32 v[52:53], v[76:77], 0 op_sel_hi:[1,0]
	v_lshl_add_u64 v[48:49], v[48:49], 0, v[156:157]
	v_pk_mul_f32 v[50:51], v[50:51], s[12:13] op_sel_hi:[1,0]
	v_pk_mul_f32 v[52:53], v[52:53], s[12:13] op_sel_hi:[1,0]
	v_pk_fma_f32 v[46:47], v[46:47], 0.5, v[50:51] op_sel_hi:[1,0,1]
	v_pk_fma_f32 v[44:45], v[44:45], 0.5, v[52:53] op_sel_hi:[1,0,1]
	v_lshl_add_u64 v[50:51], v[48:49], 2, s[38:39]
	ds_bpermute_b32 v246, v238, v44
	ds_bpermute_b32 v247, v238, v45
	ds_bpermute_b32 v248, v238, v46
	ds_bpermute_b32 v249, v238, v47
	v_lshl_add_u64 v[244:245], v[50:51], 0, v[240:241]
	s_waitcnt lgkmcnt(0)
	global_store_dwordx4 v[244:245], v[246:249], off sc1
	v_cvt_pk_bf16_f32 v50, v44, v45
	v_lshl_add_u64 v[52:53], v[48:49], 1, s[58:59]
	v_cvt_pk_bf16_f32 v51, v46, v47
	ds_bpermute_b32 v250, v238, v50
	ds_bpermute_b32 v251, v238, v51
	v_lshl_add_u64 v[244:245], v[52:53], 0, v[242:243]
	s_waitcnt lgkmcnt(0)
	global_store_dwordx2 v[244:245], v[250:251], off
	v_add_f32_e32 v50, v44, v45
	v_mul_f32_e32 v45, v45, v45
	v_fmac_f32_e32 v45, v44, v44
	v_mul_f32_e32 v44, v46, v46
	v_add_f32_e32 v51, v47, v46
	v_fmac_f32_e32 v44, v47, v47
	v_add_f32_e32 v50, v50, v51
	v_add_f32_e32 v51, v45, v44
	s_waitcnt vmcnt(12)
	v_pk_add_f32 v[44:45], v[74:75], 0 op_sel_hi:[1,0]
	v_pk_add_f32 v[46:47], v[72:73], 0 op_sel_hi:[1,0]
	v_pk_mul_f32 v[44:45], v[44:45], s[12:13] op_sel_hi:[1,0]
	v_pk_mul_f32 v[46:47], v[46:47], s[12:13] op_sel_hi:[1,0]
	v_pk_fma_f32 v[42:43], v[42:43], 0.5, v[44:45] op_sel_hi:[1,0,1]
	v_or_b32_e32 v44, 16, v48
	v_mov_b32_e32 v45, v49
	v_pk_fma_f32 v[40:41], v[40:41], 0.5, v[46:47] op_sel_hi:[1,0,1]
	v_lshl_add_u64 v[46:47], v[44:45], 2, s[38:39]
	v_lshl_add_u64 v[44:45], v[44:45], 1, s[58:59]
	ds_bpermute_b32 v246, v238, v40
	ds_bpermute_b32 v247, v238, v41
	ds_bpermute_b32 v248, v238, v42
	ds_bpermute_b32 v249, v238, v43
	v_lshl_add_u64 v[244:245], v[46:47], 0, v[240:241]
	s_waitcnt lgkmcnt(0)
	global_store_dwordx4 v[244:245], v[246:249], off sc1
	v_cvt_pk_bf16_f32 v46, v40, v41
	v_cvt_pk_bf16_f32 v47, v42, v43
	ds_bpermute_b32 v250, v238, v46
	ds_bpermute_b32 v251, v238, v47
	v_lshl_add_u64 v[244:245], v[44:45], 0, v[242:243]
	s_waitcnt lgkmcnt(0)
	global_store_dwordx2 v[244:245], v[250:251], off
	v_add_f32_e32 v44, v40, v41
	v_mul_f32_e32 v41, v41, v41
	v_add_f32_e32 v45, v43, v42
	v_fmac_f32_e32 v41, v40, v40
	v_mul_f32_e32 v40, v42, v42
	v_add_f32_e32 v50, 0, v50
	v_add_f32_e32 v44, v44, v45
	v_fmac_f32_e32 v40, v43, v43
	v_add_f32_e32 v46, v50, v44
	v_add_f32_e32 v40, v41, v40
	s_waitcnt vmcnt(13)
	v_pk_add_f32 v[42:43], v[70:71], 0 op_sel_hi:[1,0]
	v_pk_add_f32 v[44:45], v[68:69], 0 op_sel_hi:[1,0]
	v_add_f32_e32 v47, v51, v40
	v_or_b32_e32 v40, 0x80, v48
	v_mov_b32_e32 v41, v49
	v_pk_mul_f32 v[42:43], v[42:43], s[12:13] op_sel_hi:[1,0]
	v_pk_mul_f32 v[44:45], v[44:45], s[12:13] op_sel_hi:[1,0]
	v_pk_fma_f32 v[38:39], v[38:39], 0.5, v[42:43] op_sel_hi:[1,0,1]
	v_pk_fma_f32 v[36:37], v[36:37], 0.5, v[44:45] op_sel_hi:[1,0,1]
	v_lshl_add_u64 v[42:43], v[40:41], 2, s[38:39]
	v_lshl_add_u64 v[40:41], v[40:41], 1, s[58:59]
	ds_bpermute_b32 v246, v238, v36
	ds_bpermute_b32 v247, v238, v37
	ds_bpermute_b32 v248, v238, v38
	ds_bpermute_b32 v249, v238, v39
	v_lshl_add_u64 v[244:245], v[42:43], 0, v[240:241]
	s_waitcnt lgkmcnt(0)
	global_store_dwordx4 v[244:245], v[246:249], off sc1
	v_cvt_pk_bf16_f32 v42, v36, v37
	v_cvt_pk_bf16_f32 v43, v38, v39
	ds_bpermute_b32 v250, v238, v42
	ds_bpermute_b32 v251, v238, v43
	v_lshl_add_u64 v[244:245], v[40:41], 0, v[242:243]
	s_waitcnt lgkmcnt(0)
	global_store_dwordx2 v[244:245], v[250:251], off
	v_add_f32_e32 v40, v36, v37
	v_mul_f32_e32 v37, v37, v37
	v_fmac_f32_e32 v37, v36, v36
	v_mul_f32_e32 v36, v38, v38
	v_fmac_f32_e32 v36, v39, v39
	v_add_f32_e32 v41, v39, v38
	v_add_f32_e32 v36, v37, v36
	v_add_f32_e32 v40, v40, v41
	v_add_f32_e32 v43, v47, v36
	s_waitcnt vmcnt(14)
	v_pk_add_f32 v[36:37], v[66:67], 0 op_sel_hi:[1,0]
	v_pk_add_f32 v[38:39], v[64:65], 0 op_sel_hi:[1,0]
	v_add_f32_e32 v42, v46, v40
	v_pk_mul_f32 v[36:37], v[36:37], s[12:13] op_sel_hi:[1,0]
	v_pk_mul_f32 v[40:41], v[38:39], s[12:13] op_sel_hi:[1,0]
	v_pk_fma_f32 v[38:39], v[34:35], 0.5, v[36:37] op_sel_hi:[1,0,1]
	v_pk_fma_f32 v[36:37], v[32:33], 0.5, v[40:41] op_sel_hi:[1,0,1]
	v_mul_f32_e32 v33, v38, v38
	v_mul_f32_e32 v32, v37, v37
	v_fmac_f32_e32 v32, v36, v36
	v_fmac_f32_e32 v33, v39, v39
	v_add_f32_e32 v32, v32, v33
	v_add_f32_e32 v34, v43, v32
	v_add_f32_e32 v32, v36, v37
	v_add_f32_e32 v33, v39, v38
	v_add_f32_e32 v32, v32, v33
	v_add_f32_e32 v35, v42, v32
	ds_bpermute_b32 v40, v122, v35
	ds_bpermute_b32 v41, v122, v34
	v_or_b32_e32 v48, 0x90, v48
	v_lshl_add_u64 v[32:33], v[48:49], 2, s[38:39]
	ds_bpermute_b32 v246, v238, v36
	ds_bpermute_b32 v247, v238, v37
	ds_bpermute_b32 v248, v238, v38
	ds_bpermute_b32 v249, v238, v39
	v_lshl_add_u64 v[244:245], v[32:33], 0, v[240:241]
	s_waitcnt lgkmcnt(0)
	global_store_dwordx4 v[244:245], v[246:249], off sc1
	s_waitcnt lgkmcnt(1)
	v_add_f32_e32 v32, v35, v40
	s_waitcnt lgkmcnt(0)
	v_add_f32_e32 v33, v34, v41
	ds_bpermute_b32 v34, v123, v32
	ds_bpermute_b32 v35, v123, v33
	v_cvt_pk_bf16_f32 v36, v36, v37
	v_cvt_pk_bf16_f32 v37, v38, v39
	v_lshl_add_u64 v[38:39], v[48:49], 1, s[58:59]
	ds_bpermute_b32 v250, v238, v36
	ds_bpermute_b32 v251, v238, v37
	v_lshl_add_u64 v[244:245], v[38:39], 0, v[242:243]
	s_waitcnt lgkmcnt(0)
	global_store_dwordx2 v[244:245], v[250:251], off
	s_and_saveexec_b64 s[20:21], s[4:5]
	s_cbranch_execz .LBB0_258
	v_lshl_add_u64 v[36:37], v[84:85], 3, s[54:55]
	s_waitcnt lgkmcnt(1)
	v_add_f32_e32 v32, v32, v34
	s_waitcnt lgkmcnt(0)
	v_add_f32_e32 v33, v33, v35
	global_atomic_add_f32 v[36:37], v32, off
	global_atomic_add_f32 v[36:37], v33, off offset:4
; __device__ __forceinline__ unsigned cvt_pk_bf16(float lo, float hi) { unsigned r; asm volatile("v_cvt_pk_bf16_f32 %0, %1, %2" : "=v"(r) : "v"(lo), "v"(hi)); return r; }
;     __device__ __forceinline__ void operator()(const f32x4 (&acc)[2][2][4][2], const Unit& u, int wr, int wc, int fr, int fq) const {
;     ...
; #pragma unroll
;         for (int ai = 0; ai < 2; ++ai)
; #pragma unroll
;             for (int m2 = 0; m2 < 2; ++m2) {
;                 f32x4 xv[2][2][2]; f32x2 st[2];
; #pragma unroll
;                 for (int mm = 0; mm < 2; ++mm) {
;                     const int r = row0 + ai * HALF + (2 * m2 + mm) * 16;
;                     st[mm] = (f32x2){0.f, 1.f};
;                     if (rin) st[mm] = ln_stats(*(const f32x2*)(rin + 2 * (size_t)r));
; #pragma unroll
;                     for (int bj = 0; bj < 2; ++bj)
; #pragma unroll
;                         for (int n = 0; n < 2; ++n) { const f32x4* rp = (const f32x4*)(res + (size_t)r * D + col0 + bj * HALF + n * 16); xv[mm][bj][n] = stream ? __builtin_nontemporal_load(rp) : *rp; }
;                 }
; #pragma unroll
;                 for (int mm = 0; mm < 2; ++mm) {
;                     const int r = row0 + ai * HALF + (2 * m2 + mm) * 16;
;                     float ps = 0.f, pq = 0.f;
; #pragma unroll
;                     for (int bj = 0; bj < 2; ++bj)
; #pragma unroll
;                         for (int n = 0; n < 2; ++n) {
;                             const f32x4 x = (xv[mm][bj][n] - st[mm][0]) * (gg[bj][n] * st[mm][1]) + bb[bj][n];
;                             const f32x4 o = x * alpha + acc[ai][bj][2 * m2 + mm][n] * scale;
;                             const size_t off = (size_t)r * D + col0 + bj * HALF + n * 16;
;                             *(f32x4*)(Y + off) = o;
;                             if (yb) { u32x2 w; w.x = cvt_pk_bf16(o[0], o[1]); w.y = cvt_pk_bf16(o[2], o[3]); *(u32x2*)(yb + off) = w; }
;                             ps += (o[0] + o[1]) + (o[2] + o[3]); pq += (o[0] * o[0] + o[1] * o[1]) + (o[2] * o[2] + o[3] * o[3]);
;                         }
;                     if (rout) {
;                         ps += __shfl_xor(ps, 16); pq += __shfl_xor(pq, 16); ps += __shfl_xor(ps, 32); pq += __shfl_xor(pq, 32);
;                         if (fq == 0) { atomicAdd(rout + 2 * (size_t)r, ps); atomicAdd(rout + 2 * (size_t)r + 1, pq); }
;                     }
.LBB0_258:
	s_or_b64 exec, exec, s[20:21]
	v_add_u32_e32 v54, 0xa0, v158
	v_ashrrev_i32_e32 v55, 31, v54
	v_lshlrev_b64 v[32:33], 13, v[54:55]
	v_lshl_add_u64 v[32:33], v[160:161], 0, v[32:33]
	global_load_dwordx4 v[58:61], v[32:33], off
	global_load_dwordx4 v[62:65], v[32:33], off offset:64
	global_load_dwordx4 v[66:69], v[32:33], off offset:512
	global_load_dwordx4 v[48:51], v[32:33], off offset:576
	v_add_u32_e32 v52, 0xb0, v158
	v_ashrrev_i32_e32 v53, 31, v52
	v_lshlrev_b64 v[32:33], 13, v[52:53]
	v_lshl_add_u64 v[32:33], v[160:161], 0, v[32:33]
	global_load_dwordx4 v[44:47], v[32:33], off
	global_load_dwordx4 v[40:43], v[32:33], off offset:64
	global_load_dwordx4 v[36:39], v[32:33], off offset:512
	s_waitcnt lgkmcnt(0)
	global_load_dwordx4 v[32:35], v[32:33], off offset:576
	v_lshlrev_b64 v[56:57], 11, v[54:55]
	v_lshl_add_u64 v[56:57], v[56:57], 0, v[156:157]
	s_waitcnt vmcnt(7)
	v_pk_add_f32 v[60:61], v[60:61], 0 op_sel_hi:[1,0]
	v_pk_add_f32 v[58:59], v[58:59], 0 op_sel_hi:[1,0]
	v_pk_mul_f32 v[60:61], v[60:61], s[12:13] op_sel_hi:[1,0]
	v_pk_mul_f32 v[58:59], v[58:59], s[12:13] op_sel_hi:[1,0]
	v_pk_fma_f32 v[30:31], v[30:31], 0.5, v[60:61] op_sel_hi:[1,0,1]
	v_pk_fma_f32 v[28:29], v[28:29], 0.5, v[58:59] op_sel_hi:[1,0,1]
	v_lshl_add_u64 v[58:59], v[56:57], 2, s[38:39]
	ds_bpermute_b32 v246, v238, v28
	ds_bpermute_b32 v247, v238, v29
	ds_bpermute_b32 v248, v238, v30
	ds_bpermute_b32 v249, v238, v31
	v_lshl_add_u64 v[244:245], v[58:59], 0, v[240:241]
	s_waitcnt lgkmcnt(0)
	global_store_dwordx4 v[244:245], v[246:249], off sc1
	v_cvt_pk_bf16_f32 v58, v28, v29
	v_lshl_add_u64 v[60:61], v[56:57], 1, s[58:59]
	v_cvt_pk_bf16_f32 v59, v30, v31
	ds_bpermute_b32 v250, v238, v58
	ds_bpermute_b32 v251, v238, v59
	v_lshl_add_u64 v[244:245], v[60:61], 0, v[242:243]
	s_waitcnt lgkmcnt(0)
	global_store_dwordx2 v[244:245], v[250:251], off
	v_add_f32_e32 v58, v28, v29
	v_mul_f32_e32 v29, v29, v29
	v_fmac_f32_e32 v29, v28, v28
	v_mul_f32_e32 v28, v30, v30
	v_add_f32_e32 v59, v31, v30
	v_fmac_f32_e32 v28, v31, v31
	v_add_f32_e32 v58, v58, v59
	v_add_f32_e32 v59, v29, v28
	s_waitcnt vmcnt(8)
	v_pk_add_f32 v[28:29], v[64:65], 0 op_sel_hi:[1,0]
	v_pk_add_f32 v[30:31], v[62:63], 0 op_sel_hi:[1,0]
	v_pk_mul_f32 v[28:29], v[28:29], s[12:13] op_sel_hi:[1,0]
	v_pk_mul_f32 v[30:31], v[30:31], s[12:13] op_sel_hi:[1,0]
	v_pk_fma_f32 v[26:27], v[26:27], 0.5, v[28:29] op_sel_hi:[1,0,1]
	v_or_b32_e32 v28, 16, v56
	v_mov_b32_e32 v29, v57
	v_pk_fma_f32 v[24:25], v[24:25], 0.5, v[30:31] op_sel_hi:[1,0,1]
	v_lshl_add_u64 v[30:31], v[28:29], 2, s[38:39]
	v_lshl_add_u64 v[28:29], v[28:29], 1, s[58:59]
	ds_bpermute_b32 v246, v238, v24
	ds_bpermute_b32 v247, v238, v25
	ds_bpermute_b32 v248, v238, v26
	ds_bpermute_b32 v249, v238, v27
	v_lshl_add_u64 v[244:245], v[30:31], 0, v[240:241]
	s_waitcnt lgkmcnt(0)
	global_store_dwordx4 v[244:245], v[246:249], off sc1
	v_cvt_pk_bf16_f32 v30, v24, v25
	v_cvt_pk_bf16_f32 v31, v26, v27
	ds_bpermute_b32 v250, v238, v30
	ds_bpermute_b32 v251, v238, v31
	v_lshl_add_u64 v[244:245], v[28:29], 0, v[242:243]
	s_waitcnt lgkmcnt(0)
	global_store_dwordx2 v[244:245], v[250:251], off
	v_add_f32_e32 v28, v24, v25
	v_mul_f32_e32 v25, v25, v25
	v_add_f32_e32 v29, v27, v26
	v_fmac_f32_e32 v25, v24, v24
	v_mul_f32_e32 v24, v26, v26
	v_add_f32_e32 v58, 0, v58
	v_add_f32_e32 v28, v28, v29
	v_fmac_f32_e32 v24, v27, v27
	v_add_f32_e32 v30, v58, v28
	v_add_f32_e32 v24, v25, v24
	s_waitcnt vmcnt(9)
	v_pk_add_f32 v[26:27], v[68:69], 0 op_sel_hi:[1,0]
	v_pk_add_f32 v[28:29], v[66:67], 0 op_sel_hi:[1,0]
	v_add_f32_e32 v31, v59, v24
	v_or_b32_e32 v24, 0x80, v56
	v_mov_b32_e32 v25, v57
	v_pk_mul_f32 v[26:27], v[26:27], s[12:13] op_sel_hi:[1,0]
	v_pk_mul_f32 v[28:29], v[28:29], s[12:13] op_sel_hi:[1,0]
	v_pk_fma_f32 v[22:23], v[22:23], 0.5, v[26:27] op_sel_hi:[1,0,1]
	v_pk_fma_f32 v[20:21], v[20:21], 0.5, v[28:29] op_sel_hi:[1,0,1]
	v_lshl_add_u64 v[26:27], v[24:25], 2, s[38:39]
	v_lshl_add_u64 v[24:25], v[24:25], 1, s[58:59]
	ds_bpermute_b32 v246, v238, v20
	ds_bpermute_b32 v247, v238, v21
	ds_bpermute_b32 v248, v238, v22
	ds_bpermute_b32 v249, v238, v23
	v_lshl_add_u64 v[244:245], v[26:27], 0, v[240:241]
	s_waitcnt lgkmcnt(0)
	global_store_dwordx4 v[244:245], v[246:249], off sc1
	v_cvt_pk_bf16_f32 v26, v20, v21
	v_cvt_pk_bf16_f32 v27, v22, v23
	ds_bpermute_b32 v250, v238, v26
	ds_bpermute_b32 v251, v238, v27
	v_lshl_add_u64 v[244:245], v[24:25], 0, v[242:243]
	s_waitcnt lgkmcnt(0)
	global_store_dwordx2 v[244:245], v[250:251], off
	v_add_f32_e32 v24, v20, v21
	v_mul_f32_e32 v21, v21, v21
	v_fmac_f32_e32 v21, v20, v20
	v_mul_f32_e32 v20, v22, v22
	v_fmac_f32_e32 v20, v23, v23
	v_add_f32_e32 v25, v23, v22
	v_add_f32_e32 v20, v21, v20
	v_add_f32_e32 v24, v24, v25
	v_add_f32_e32 v25, v31, v20
	s_waitcnt vmcnt(10)
	v_pk_add_f32 v[20:21], v[50:51], 0 op_sel_hi:[1,0]
	v_pk_add_f32 v[22:23], v[48:49], 0 op_sel_hi:[1,0]
	v_pk_mul_f32 v[20:21], v[20:21], s[12:13] op_sel_hi:[1,0]
	v_pk_mul_f32 v[22:23], v[22:23], s[12:13] op_sel_hi:[1,0]
	v_or_b32_e32 v56, 0x90, v56
	v_pk_fma_f32 v[18:19], v[18:19], 0.5, v[20:21] op_sel_hi:[1,0,1]
	v_pk_fma_f32 v[16:17], v[16:17], 0.5, v[22:23] op_sel_hi:[1,0,1]
	v_lshl_add_u64 v[20:21], v[56:57], 2, s[38:39]
	ds_bpermute_b32 v246, v238, v16
	ds_bpermute_b32 v247, v238, v17
	ds_bpermute_b32 v248, v238, v18
	ds_bpermute_b32 v249, v238, v19
	v_lshl_add_u64 v[244:245], v[20:21], 0, v[240:241]
	s_waitcnt lgkmcnt(0)
	global_store_dwordx4 v[244:245], v[246:249], off sc1
	v_cvt_pk_bf16_f32 v20, v16, v17
	v_lshl_add_u64 v[22:23], v[56:57], 1, s[58:59]
	v_cvt_pk_bf16_f32 v21, v18, v19
	ds_bpermute_b32 v250, v238, v20
	ds_bpermute_b32 v251, v238, v21
	v_lshl_add_u64 v[244:245], v[22:23], 0, v[242:243]
	s_waitcnt lgkmcnt(0)
	global_store_dwordx2 v[244:245], v[250:251], off
	v_mul_f32_e32 v20, v17, v17
	v_fmac_f32_e32 v20, v16, v16
	v_add_f32_e32 v16, v16, v17
	v_add_f32_e32 v17, v19, v18
	v_add_f32_e32 v24, v30, v24
	v_add_f32_e32 v16, v16, v17
	v_add_f32_e32 v16, v24, v16
	ds_bpermute_b32 v17, v122, v16
	v_mul_f32_e32 v21, v18, v18
	v_fmac_f32_e32 v21, v19, v19
	v_add_f32_e32 v20, v20, v21
	v_add_f32_e32 v20, v25, v20
	s_waitcnt lgkmcnt(0)
	v_add_f32_e32 v16, v16, v17
	ds_bpermute_b32 v17, v122, v20
	ds_bpermute_b32 v18, v123, v16
	s_waitcnt lgkmcnt(1)
	v_add_f32_e32 v17, v20, v17
	ds_bpermute_b32 v19, v123, v17
	s_and_saveexec_b64 s[20:21], s[4:5]
	s_cbranch_execz .LBB0_260
	v_lshl_add_u64 v[20:21], v[54:55], 3, s[54:55]
	s_waitcnt lgkmcnt(1)
	v_add_f32_e32 v16, v16, v18
	s_waitcnt lgkmcnt(0)
	v_add_f32_e32 v17, v17, v19
	global_atomic_add_f32 v[20:21], v16, off
	global_atomic_add_f32 v[20:21], v17, off offset:4
; __device__ __forceinline__ unsigned cvt_pk_bf16(float lo, float hi) { unsigned r; asm volatile("v_cvt_pk_bf16_f32 %0, %1, %2" : "=v"(r) : "v"(lo), "v"(hi)); return r; }
;     __device__ __forceinline__ void operator()(const f32x4 (&acc)[2][2][4][2], const Unit& u, int wr, int wc, int fr, int fq) const {
;     ...
; #pragma unroll
;         for (int ai = 0; ai < 2; ++ai)
; #pragma unroll
;             for (int m2 = 0; m2 < 2; ++m2) {
;                 f32x4 xv[2][2][2]; f32x2 st[2];
; #pragma unroll
;                 for (int mm = 0; mm < 2; ++mm) {
;                     const int r = row0 + ai * HALF + (2 * m2 + mm) * 16;
;                     st[mm] = (f32x2){0.f, 1.f};
;                     if (rin) st[mm] = ln_stats(*(const f32x2*)(rin + 2 * (size_t)r));
; #pragma unroll
;                     for (int bj = 0; bj < 2; ++bj)
; #pragma unroll
;                         for (int n = 0; n < 2; ++n) { const f32x4* rp = (const f32x4*)(res + (size_t)r * D + col0 + bj * HALF + n * 16); xv[mm][bj][n] = stream ? __builtin_nontemporal_load(rp) : *rp; }
;                 }
; #pragma unroll
;                 for (int mm = 0; mm < 2; ++mm) {
;                     const int r = row0 + ai * HALF + (2 * m2 + mm) * 16;
;                     float ps = 0.f, pq = 0.f;
; #pragma unroll
;                     for (int bj = 0; bj < 2; ++bj)
; #pragma unroll
;                         for (int n = 0; n < 2; ++n) {
;                             const f32x4 x = (xv[mm][bj][n] - st[mm][0]) * (gg[bj][n] * st[mm][1]) + bb[bj][n];
;                             const f32x4 o = x * alpha + acc[ai][bj][2 * m2 + mm][n] * scale;
;                             const size_t off = (size_t)r * D + col0 + bj * HALF + n * 16;
;                             *(f32x4*)(Y + off) = o;
;                             if (yb) { u32x2 w; w.x = cvt_pk_bf16(o[0], o[1]); w.y = cvt_pk_bf16(o[2], o[3]); *(u32x2*)(yb + off) = w; }
;                             ps += (o[0] + o[1]) + (o[2] + o[3]); pq += (o[0] * o[0] + o[1] * o[1]) + (o[2] * o[2] + o[3] * o[3]);
;                         }
;                     if (rout) {
;                         ps += __shfl_xor(ps, 16); pq += __shfl_xor(pq, 16); ps += __shfl_xor(ps, 32); pq += __shfl_xor(pq, 32);
;                         if (fq == 0) { atomicAdd(rout + 2 * (size_t)r, ps); atomicAdd(rout + 2 * (size_t)r + 1, pq); }
;                     }
.LBB0_260:
	s_or_b64 exec, exec, s[20:21]
	v_lshlrev_b64 v[16:17], 11, v[52:53]
	s_waitcnt vmcnt(11) lgkmcnt(0)
	v_pk_add_f32 v[18:19], v[46:47], 0 op_sel_hi:[1,0]
	v_pk_add_f32 v[20:21], v[44:45], 0 op_sel_hi:[1,0]
	v_lshl_add_u64 v[16:17], v[16:17], 0, v[156:157]
	v_pk_mul_f32 v[18:19], v[18:19], s[12:13] op_sel_hi:[1,0]
	v_pk_mul_f32 v[20:21], v[20:21], s[12:13] op_sel_hi:[1,0]
	v_pk_fma_f32 v[14:15], v[14:15], 0.5, v[18:19] op_sel_hi:[1,0,1]
	v_pk_fma_f32 v[12:13], v[12:13], 0.5, v[20:21] op_sel_hi:[1,0,1]
	v_lshl_add_u64 v[18:19], v[16:17], 2, s[38:39]
	ds_bpermute_b32 v246, v238, v12
	ds_bpermute_b32 v247, v238, v13
	ds_bpermute_b32 v248, v238, v14
	ds_bpermute_b32 v249, v238, v15
	v_lshl_add_u64 v[244:245], v[18:19], 0, v[240:241]
	s_waitcnt lgkmcnt(0)
	global_store_dwordx4 v[244:245], v[246:249], off sc1
	v_cvt_pk_bf16_f32 v18, v12, v13
	v_lshl_add_u64 v[20:21], v[16:17], 1, s[58:59]
	v_cvt_pk_bf16_f32 v19, v14, v15
	ds_bpermute_b32 v250, v238, v18
	ds_bpermute_b32 v251, v238, v19
	v_lshl_add_u64 v[244:245], v[20:21], 0, v[242:243]
	s_waitcnt lgkmcnt(0)
	global_store_dwordx2 v[244:245], v[250:251], off
	v_add_f32_e32 v18, v12, v13
	v_mul_f32_e32 v13, v13, v13
	v_fmac_f32_e32 v13, v12, v12
	v_mul_f32_e32 v12, v14, v14
	v_add_f32_e32 v19, v15, v14
	v_fmac_f32_e32 v12, v15, v15
	v_add_f32_e32 v18, v18, v19
	v_add_f32_e32 v19, v13, v12
	s_waitcnt vmcnt(12)
	v_pk_add_f32 v[12:13], v[42:43], 0 op_sel_hi:[1,0]
	v_pk_add_f32 v[14:15], v[40:41], 0 op_sel_hi:[1,0]
	v_pk_mul_f32 v[12:13], v[12:13], s[12:13] op_sel_hi:[1,0]
	v_pk_mul_f32 v[14:15], v[14:15], s[12:13] op_sel_hi:[1,0]
	v_pk_fma_f32 v[10:11], v[10:11], 0.5, v[12:13] op_sel_hi:[1,0,1]
	v_or_b32_e32 v12, 16, v16
	v_mov_b32_e32 v13, v17
	v_pk_fma_f32 v[8:9], v[8:9], 0.5, v[14:15] op_sel_hi:[1,0,1]
	v_lshl_add_u64 v[14:15], v[12:13], 2, s[38:39]
	v_lshl_add_u64 v[12:13], v[12:13], 1, s[58:59]
	ds_bpermute_b32 v246, v238, v8
	ds_bpermute_b32 v247, v238, v9
	ds_bpermute_b32 v248, v238, v10
	ds_bpermute_b32 v249, v238, v11
	v_lshl_add_u64 v[244:245], v[14:15], 0, v[240:241]
	s_waitcnt lgkmcnt(0)
	global_store_dwordx4 v[244:245], v[246:249], off sc1
	v_cvt_pk_bf16_f32 v14, v8, v9
	v_cvt_pk_bf16_f32 v15, v10, v11
	ds_bpermute_b32 v250, v238, v14
	ds_bpermute_b32 v251, v238, v15
	v_lshl_add_u64 v[244:245], v[12:13], 0, v[242:243]
	s_waitcnt lgkmcnt(0)
	global_store_dwordx2 v[244:245], v[250:251], off
	v_add_f32_e32 v12, v8, v9
	v_mul_f32_e32 v9, v9, v9
	v_add_f32_e32 v13, v11, v10
	v_fmac_f32_e32 v9, v8, v8
	v_mul_f32_e32 v8, v10, v10
	v_add_f32_e32 v18, 0, v18
	v_add_f32_e32 v12, v12, v13
	v_fmac_f32_e32 v8, v11, v11
	v_add_f32_e32 v14, v18, v12
	v_add_f32_e32 v8, v9, v8
	s_waitcnt vmcnt(13)
	v_pk_add_f32 v[10:11], v[38:39], 0 op_sel_hi:[1,0]
	v_pk_add_f32 v[12:13], v[36:37], 0 op_sel_hi:[1,0]
	v_add_f32_e32 v15, v19, v8
	v_or_b32_e32 v8, 0x80, v16
	v_mov_b32_e32 v9, v17
	v_pk_mul_f32 v[10:11], v[10:11], s[12:13] op_sel_hi:[1,0]
	v_pk_mul_f32 v[12:13], v[12:13], s[12:13] op_sel_hi:[1,0]
	v_pk_fma_f32 v[6:7], v[6:7], 0.5, v[10:11] op_sel_hi:[1,0,1]
	v_pk_fma_f32 v[4:5], v[4:5], 0.5, v[12:13] op_sel_hi:[1,0,1]
	v_lshl_add_u64 v[10:11], v[8:9], 2, s[38:39]
	v_lshl_add_u64 v[8:9], v[8:9], 1, s[58:59]
	ds_bpermute_b32 v246, v238, v4
	ds_bpermute_b32 v247, v238, v5
	ds_bpermute_b32 v248, v238, v6
	ds_bpermute_b32 v249, v238, v7
	v_lshl_add_u64 v[244:245], v[10:11], 0, v[240:241]
	s_waitcnt lgkmcnt(0)
	global_store_dwordx4 v[244:245], v[246:249], off sc1
	v_cvt_pk_bf16_f32 v10, v4, v5
	v_cvt_pk_bf16_f32 v11, v6, v7
	ds_bpermute_b32 v250, v238, v10
	ds_bpermute_b32 v251, v238, v11
	v_lshl_add_u64 v[244:245], v[8:9], 0, v[242:243]
	s_waitcnt lgkmcnt(0)
	global_store_dwordx2 v[244:245], v[250:251], off
	v_add_f32_e32 v8, v4, v5
	v_mul_f32_e32 v5, v5, v5
	v_fmac_f32_e32 v5, v4, v4
	v_mul_f32_e32 v4, v6, v6
	v_fmac_f32_e32 v4, v7, v7
	v_add_f32_e32 v9, v7, v6
	v_add_f32_e32 v4, v5, v4
	v_add_f32_e32 v8, v8, v9
	v_add_f32_e32 v11, v15, v4
	s_waitcnt vmcnt(14)
	v_pk_add_f32 v[4:5], v[34:35], 0 op_sel_hi:[1,0]
	v_pk_add_f32 v[6:7], v[32:33], 0 op_sel_hi:[1,0]
	v_add_f32_e32 v10, v14, v8
	v_pk_mul_f32 v[4:5], v[4:5], s[12:13] op_sel_hi:[1,0]
	v_pk_mul_f32 v[8:9], v[6:7], s[12:13] op_sel_hi:[1,0]
	v_pk_fma_f32 v[6:7], v[2:3], 0.5, v[4:5] op_sel_hi:[1,0,1]
	v_pk_fma_f32 v[4:5], v[0:1], 0.5, v[8:9] op_sel_hi:[1,0,1]
	v_mul_f32_e32 v1, v6, v6
	v_mul_f32_e32 v0, v5, v5
	v_fmac_f32_e32 v0, v4, v4
	v_fmac_f32_e32 v1, v7, v7
	v_add_f32_e32 v0, v0, v1
	v_add_f32_e32 v2, v11, v0
	v_add_f32_e32 v0, v4, v5
	v_add_f32_e32 v1, v7, v6
	v_add_f32_e32 v0, v0, v1
	v_add_f32_e32 v3, v10, v0
	ds_bpermute_b32 v8, v122, v3
	ds_bpermute_b32 v9, v122, v2
	v_or_b32_e32 v16, 0x90, v16
	v_lshl_add_u64 v[0:1], v[16:17], 2, s[38:39]
	ds_bpermute_b32 v246, v238, v4
	ds_bpermute_b32 v247, v238, v5
	ds_bpermute_b32 v248, v238, v6
	ds_bpermute_b32 v249, v238, v7
	v_lshl_add_u64 v[244:245], v[0:1], 0, v[240:241]
	s_waitcnt lgkmcnt(0)
	global_store_dwordx4 v[244:245], v[246:249], off sc1
	s_waitcnt lgkmcnt(1)
	v_add_f32_e32 v0, v3, v8
	s_waitcnt lgkmcnt(0)
	v_add_f32_e32 v1, v2, v9
	ds_bpermute_b32 v2, v123, v0
	ds_bpermute_b32 v3, v123, v1
	v_cvt_pk_bf16_f32 v4, v4, v5
	v_cvt_pk_bf16_f32 v5, v6, v7
	v_lshl_add_u64 v[6:7], v[16:17], 1, s[58:59]
	ds_bpermute_b32 v250, v238, v4
	ds_bpermute_b32 v251, v238, v5
	v_lshl_add_u64 v[244:245], v[6:7], 0, v[242:243]
	s_waitcnt lgkmcnt(0)
	global_store_dwordx2 v[244:245], v[250:251], off
	s_and_saveexec_b64 s[20:21], s[4:5]
	s_cbranch_execz .LBB0_262
	v_lshl_add_u64 v[4:5], v[52:53], 3, s[54:55]
	s_waitcnt lgkmcnt(1)
	v_add_f32_e32 v0, v0, v2
	s_waitcnt lgkmcnt(0)
	v_add_f32_e32 v1, v1, v3
	global_atomic_add_f32 v[4:5], v0, off
	global_atomic_add_f32 v[4:5], v1, off offset:4

; __device__ __forceinline__ unsigned cvt_pk_bf16(float lo, float hi) { unsigned r; asm volatile("v_cvt_pk_bf16_f32 %0, %1, %2" : "=v"(r) : "v"(lo), "v"(hi)); return r; }
;     __device__ __forceinline__ void operator()(const f32x4 (&acc)[2][2][4][2], const Unit& u, int wr, int wc, int fr, int fq) const {
;     ...
;         } else if (u.kind == 1) {
;             const bool isk = u.pn < 4; const int c0 = col0 - (isk ? 0 : 1024);
;             float* ob = isk ? outK : outV;
; #pragma unroll
;             for (int ai = 0; ai < 2; ++ai)
; #pragma unroll
;                 for (int m = 0; m < 4; ++m) {
;                     const size_t off = (size_t)(row0 + ai * HALF + m * 16) * 1024 + c0;
; #pragma unroll
;                     for (int bj = 0; bj < 2; ++bj) {
;                         const f32x4 v0 = acc[ai][bj][m][0], v1 = acc[ai][bj][m][1];
;                         __builtin_nontemporal_store(v0, (f32x4*)(ob + off + bj * HALF)); __builtin_nontemporal_store(v1, (f32x4*)(ob + off + bj * HALF + 4));
;                         if (isk) { u32x4 w; w.x = cvt_pk_bf16(v0[0], v0[1]); w.y = cvt_pk_bf16(v0[2], v0[3]); w.z = cvt_pk_bf16(v1[0], v1[1]); w.w = cvt_pk_bf16(v1[2], v1[3]); *(u32x4*)(KB + off + bj * HALF) = w; }
;                     }
;                 }
.LBB0_360:
	s_andn2_b64 vcc, exec, s[36:37]
	s_cbranch_vccnz .LBB0_362
	v_cvt_pk_bf16_f32 v48, v172, v173
	v_cvt_pk_bf16_f32 v49, v174, v175
	v_cvt_pk_bf16_f32 v50, v168, v169
	v_cvt_pk_bf16_f32 v51, v170, v171
	v_lshl_add_u64 v[38:39], v[36:37], 1, s[42:43]
	global_store_dwordx4 v[38:39], v[48:51], off sc1
	global_store_dwordx4 v[34:35], v[164:167], off offset:512 nt
	global_store_dwordx4 v[34:35], v[160:163], off offset:528 nt
	v_cvt_pk_bf16_f32 v34, v164, v165
	v_cvt_pk_bf16_f32 v35, v166, v167
	v_cvt_pk_bf16_f32 v36, v160, v161
	v_cvt_pk_bf16_f32 v37, v162, v163
	global_store_dwordx4 v[38:39], v[34:37], off offset:256 sc1

; __device__ __forceinline__ unsigned cvt_pk_bf16(float lo, float hi) { unsigned r; asm volatile("v_cvt_pk_bf16_f32 %0, %1, %2" : "=v"(r) : "v"(lo), "v"(hi)); return r; }
;     __device__ __forceinline__ void operator()(const f32x4 (&acc)[2][2][4][2], const Unit& u, int wr, int wc, int fr, int fq) const {
;     ...
;         } else if (u.kind == 1) {
;             const bool isk = u.pn < 4; const int c0 = col0 - (isk ? 0 : 1024);
;             float* ob = isk ? outK : outV;
; #pragma unroll
;             for (int ai = 0; ai < 2; ++ai)
; #pragma unroll
;                 for (int m = 0; m < 4; ++m) {
;                     const size_t off = (size_t)(row0 + ai * HALF + m * 16) * 1024 + c0;
; #pragma unroll
;                     for (int bj = 0; bj < 2; ++bj) {
;                         const f32x4 v0 = acc[ai][bj][m][0], v1 = acc[ai][bj][m][1];
;                         __builtin_nontemporal_store(v0, (f32x4*)(ob + off + bj * HALF)); __builtin_nontemporal_store(v1, (f32x4*)(ob + off + bj * HALF + 4));
;                         if (isk) { u32x4 w; w.x = cvt_pk_bf16(v0[0], v0[1]); w.y = cvt_pk_bf16(v0[2], v0[3]); w.z = cvt_pk_bf16(v1[0], v1[1]); w.w = cvt_pk_bf16(v1[2], v1[3]); *(u32x4*)(KB + off + bj * HALF) = w; }
;                     }
;                 }
.LBB0_364:
	s_andn2_b64 vcc, exec, s[36:37]
	s_cbranch_vccnz .LBB0_366
	v_cvt_pk_bf16_f32 v48, v156, v157
	v_cvt_pk_bf16_f32 v49, v158, v159
	v_cvt_pk_bf16_f32 v50, v152, v153
	v_cvt_pk_bf16_f32 v51, v154, v155
	v_lshl_add_u64 v[38:39], v[36:37], 1, s[42:43]
	global_store_dwordx4 v[38:39], v[48:51], off sc1
	global_store_dwordx4 v[34:35], v[148:151], off offset:512 nt
	global_store_dwordx4 v[34:35], v[144:147], off offset:528 nt
	v_cvt_pk_bf16_f32 v34, v148, v149
	v_cvt_pk_bf16_f32 v35, v150, v151
	v_cvt_pk_bf16_f32 v36, v144, v145
	v_cvt_pk_bf16_f32 v37, v146, v147
	global_store_dwordx4 v[38:39], v[34:37], off offset:256 sc1

; __device__ __forceinline__ unsigned cvt_pk_bf16(float lo, float hi) { unsigned r; asm volatile("v_cvt_pk_bf16_f32 %0, %1, %2" : "=v"(r) : "v"(lo), "v"(hi)); return r; }
;     __device__ __forceinline__ void operator()(const f32x4 (&acc)[2][2][4][2], const Unit& u, int wr, int wc, int fr, int fq) const {
;     ...
;         } else if (u.kind == 1) {
;             const bool isk = u.pn < 4; const int c0 = col0 - (isk ? 0 : 1024);
;             float* ob = isk ? outK : outV;
; #pragma unroll
;             for (int ai = 0; ai < 2; ++ai)
; #pragma unroll
;                 for (int m = 0; m < 4; ++m) {
;                     const size_t off = (size_t)(row0 + ai * HALF + m * 16) * 1024 + c0;
; #pragma unroll
;                     for (int bj = 0; bj < 2; ++bj) {
;                         const f32x4 v0 = acc[ai][bj][m][0], v1 = acc[ai][bj][m][1];
;                         __builtin_nontemporal_store(v0, (f32x4*)(ob + off + bj * HALF)); __builtin_nontemporal_store(v1, (f32x4*)(ob + off + bj * HALF + 4));
;                         if (isk) { u32x4 w; w.x = cvt_pk_bf16(v0[0], v0[1]); w.y = cvt_pk_bf16(v0[2], v0[3]); w.z = cvt_pk_bf16(v1[0], v1[1]); w.w = cvt_pk_bf16(v1[2], v1[3]); *(u32x4*)(KB + off + bj * HALF) = w; }
;                     }
;                 }
.LBB0_368:
	s_andn2_b64 vcc, exec, s[36:37]
	s_cbranch_vccnz .LBB0_370
	v_cvt_pk_bf16_f32 v48, v140, v141
	v_cvt_pk_bf16_f32 v49, v142, v143
	v_cvt_pk_bf16_f32 v50, v136, v137
	v_cvt_pk_bf16_f32 v51, v138, v139
	v_lshl_add_u64 v[38:39], v[36:37], 1, s[42:43]
	global_store_dwordx4 v[38:39], v[48:51], off sc1
	global_store_dwordx4 v[34:35], v[132:135], off offset:512 nt
	global_store_dwordx4 v[34:35], v[128:131], off offset:528 nt
	v_cvt_pk_bf16_f32 v34, v132, v133
	v_cvt_pk_bf16_f32 v35, v134, v135
	v_cvt_pk_bf16_f32 v36, v128, v129
	v_cvt_pk_bf16_f32 v37, v130, v131
	global_store_dwordx4 v[38:39], v[34:37], off offset:256 sc1

; __device__ __forceinline__ unsigned cvt_pk_bf16(float lo, float hi) { unsigned r; asm volatile("v_cvt_pk_bf16_f32 %0, %1, %2" : "=v"(r) : "v"(lo), "v"(hi)); return r; }
;     __device__ __forceinline__ void operator()(const f32x4 (&acc)[2][2][4][2], const Unit& u, int wr, int wc, int fr, int fq) const {
;     ...
;         } else if (u.kind == 1) {
;             const bool isk = u.pn < 4; const int c0 = col0 - (isk ? 0 : 1024);
;             float* ob = isk ? outK : outV;
; #pragma unroll
;             for (int ai = 0; ai < 2; ++ai)
; #pragma unroll
;                 for (int m = 0; m < 4; ++m) {
;                     const size_t off = (size_t)(row0 + ai * HALF + m * 16) * 1024 + c0;
; #pragma unroll
;                     for (int bj = 0; bj < 2; ++bj) {
;                         const f32x4 v0 = acc[ai][bj][m][0], v1 = acc[ai][bj][m][1];
;                         __builtin_nontemporal_store(v0, (f32x4*)(ob + off + bj * HALF)); __builtin_nontemporal_store(v1, (f32x4*)(ob + off + bj * HALF + 4));
;                         if (isk) { u32x4 w; w.x = cvt_pk_bf16(v0[0], v0[1]); w.y = cvt_pk_bf16(v0[2], v0[3]); w.z = cvt_pk_bf16(v1[0], v1[1]); w.w = cvt_pk_bf16(v1[2], v1[3]); *(u32x4*)(KB + off + bj * HALF) = w; }
;                     }
;                 }
.LBB0_372:
	s_andn2_b64 vcc, exec, s[36:37]
	s_cbranch_vccnz .LBB0_374
	v_cvt_pk_bf16_f32 v48, v124, v125
	v_cvt_pk_bf16_f32 v49, v126, v127
	v_cvt_pk_bf16_f32 v50, v120, v121
	v_cvt_pk_bf16_f32 v51, v122, v123
	v_lshl_add_u64 v[38:39], v[36:37], 1, s[42:43]
	global_store_dwordx4 v[38:39], v[48:51], off sc1
	global_store_dwordx4 v[34:35], v[116:119], off offset:512 nt
	global_store_dwordx4 v[34:35], v[112:115], off offset:528 nt
	v_cvt_pk_bf16_f32 v34, v116, v117
	v_cvt_pk_bf16_f32 v35, v118, v119
	v_cvt_pk_bf16_f32 v36, v112, v113
	v_cvt_pk_bf16_f32 v37, v114, v115
	global_store_dwordx4 v[38:39], v[34:37], off offset:256 sc1

; __device__ __forceinline__ unsigned cvt_pk_bf16(float lo, float hi) { unsigned r; asm volatile("v_cvt_pk_bf16_f32 %0, %1, %2" : "=v"(r) : "v"(lo), "v"(hi)); return r; }
;     __device__ __forceinline__ void operator()(const f32x4 (&acc)[2][2][4][2], const Unit& u, int wr, int wc, int fr, int fq) const {
;     ...
;         } else if (u.kind == 1) {
;             const bool isk = u.pn < 4; const int c0 = col0 - (isk ? 0 : 1024);
;             float* ob = isk ? outK : outV;
; #pragma unroll
;             for (int ai = 0; ai < 2; ++ai)
; #pragma unroll
;                 for (int m = 0; m < 4; ++m) {
;                     const size_t off = (size_t)(row0 + ai * HALF + m * 16) * 1024 + c0;
; #pragma unroll
;                     for (int bj = 0; bj < 2; ++bj) {
;                         const f32x4 v0 = acc[ai][bj][m][0], v1 = acc[ai][bj][m][1];
;                         __builtin_nontemporal_store(v0, (f32x4*)(ob + off + bj * HALF)); __builtin_nontemporal_store(v1, (f32x4*)(ob + off + bj * HALF + 4));
;                         if (isk) { u32x4 w; w.x = cvt_pk_bf16(v0[0], v0[1]); w.y = cvt_pk_bf16(v0[2], v0[3]); w.z = cvt_pk_bf16(v1[0], v1[1]); w.w = cvt_pk_bf16(v1[2], v1[3]); *(u32x4*)(KB + off + bj * HALF) = w; }
;                     }
;                 }
.LBB0_376:
	s_andn2_b64 vcc, exec, s[36:37]
	s_cbranch_vccnz .LBB0_378
	v_cvt_pk_bf16_f32 v48, v108, v109
	v_cvt_pk_bf16_f32 v49, v110, v111
	v_cvt_pk_bf16_f32 v50, v104, v105
	v_cvt_pk_bf16_f32 v51, v106, v107
	v_lshl_add_u64 v[38:39], v[36:37], 1, s[42:43]
	global_store_dwordx4 v[38:39], v[48:51], off sc1
	global_store_dwordx4 v[34:35], v[100:103], off offset:512 nt
	global_store_dwordx4 v[34:35], v[96:99], off offset:528 nt
	v_cvt_pk_bf16_f32 v34, v100, v101
	v_cvt_pk_bf16_f32 v35, v102, v103
	v_cvt_pk_bf16_f32 v36, v96, v97
	v_cvt_pk_bf16_f32 v37, v98, v99
	global_store_dwordx4 v[38:39], v[34:37], off offset:256 sc1

; __device__ __forceinline__ unsigned cvt_pk_bf16(float lo, float hi) { unsigned r; asm volatile("v_cvt_pk_bf16_f32 %0, %1, %2" : "=v"(r) : "v"(lo), "v"(hi)); return r; }
;     __device__ __forceinline__ void operator()(const f32x4 (&acc)[2][2][4][2], const Unit& u, int wr, int wc, int fr, int fq) const {
;     ...
;         } else if (u.kind == 1) {
;             const bool isk = u.pn < 4; const int c0 = col0 - (isk ? 0 : 1024);
;             float* ob = isk ? outK : outV;
; #pragma unroll
;             for (int ai = 0; ai < 2; ++ai)
; #pragma unroll
;                 for (int m = 0; m < 4; ++m) {
;                     const size_t off = (size_t)(row0 + ai * HALF + m * 16) * 1024 + c0;
; #pragma unroll
;                     for (int bj = 0; bj < 2; ++bj) {
;                         const f32x4 v0 = acc[ai][bj][m][0], v1 = acc[ai][bj][m][1];
;                         __builtin_nontemporal_store(v0, (f32x4*)(ob + off + bj * HALF)); __builtin_nontemporal_store(v1, (f32x4*)(ob + off + bj * HALF + 4));
;                         if (isk) { u32x4 w; w.x = cvt_pk_bf16(v0[0], v0[1]); w.y = cvt_pk_bf16(v0[2], v0[3]); w.z = cvt_pk_bf16(v1[0], v1[1]); w.w = cvt_pk_bf16(v1[2], v1[3]); *(u32x4*)(KB + off + bj * HALF) = w; }
;                     }
;                 }
.LBB0_380:
	s_andn2_b64 vcc, exec, s[36:37]
	s_cbranch_vccnz .LBB0_382
	v_cvt_pk_bf16_f32 v48, v84, v85
	v_cvt_pk_bf16_f32 v49, v86, v87
	v_cvt_pk_bf16_f32 v50, v72, v73
	v_cvt_pk_bf16_f32 v51, v74, v75
	v_lshl_add_u64 v[38:39], v[36:37], 1, s[42:43]
	global_store_dwordx4 v[38:39], v[48:51], off sc1
	global_store_dwordx4 v[34:35], v[44:47], off offset:512 nt
	global_store_dwordx4 v[34:35], v[40:43], off offset:528 nt
	v_cvt_pk_bf16_f32 v34, v44, v45
	v_cvt_pk_bf16_f32 v35, v46, v47
	v_cvt_pk_bf16_f32 v36, v40, v41
	v_cvt_pk_bf16_f32 v37, v42, v43
	global_store_dwordx4 v[38:39], v[34:37], off offset:256 sc1

; __device__ __forceinline__ unsigned cvt_pk_bf16(float lo, float hi) { unsigned r; asm volatile("v_cvt_pk_bf16_f32 %0, %1, %2" : "=v"(r) : "v"(lo), "v"(hi)); return r; }
;     __device__ __forceinline__ void operator()(const f32x4 (&acc)[2][2][4][2], const Unit& u, int wr, int wc, int fr, int fq) const {
;     ...
;         } else if (u.kind == 1) {
;             const bool isk = u.pn < 4; const int c0 = col0 - (isk ? 0 : 1024);
;             float* ob = isk ? outK : outV;
; #pragma unroll
;             for (int ai = 0; ai < 2; ++ai)
; #pragma unroll
;                 for (int m = 0; m < 4; ++m) {
;                     const size_t off = (size_t)(row0 + ai * HALF + m * 16) * 1024 + c0;
; #pragma unroll
;                     for (int bj = 0; bj < 2; ++bj) {
;                         const f32x4 v0 = acc[ai][bj][m][0], v1 = acc[ai][bj][m][1];
;                         __builtin_nontemporal_store(v0, (f32x4*)(ob + off + bj * HALF)); __builtin_nontemporal_store(v1, (f32x4*)(ob + off + bj * HALF + 4));
;                         if (isk) { u32x4 w; w.x = cvt_pk_bf16(v0[0], v0[1]); w.y = cvt_pk_bf16(v0[2], v0[3]); w.z = cvt_pk_bf16(v1[0], v1[1]); w.w = cvt_pk_bf16(v1[2], v1[3]); *(u32x4*)(KB + off + bj * HALF) = w; }
;                     }
;                 }
.LBB0_384:
	s_andn2_b64 vcc, exec, s[36:37]
	s_cbranch_vccnz .LBB0_386
	v_cvt_pk_bf16_f32 v48, v28, v29
	v_cvt_pk_bf16_f32 v49, v30, v31
	v_cvt_pk_bf16_f32 v50, v24, v25
	v_cvt_pk_bf16_f32 v51, v26, v27
	v_lshl_add_u64 v[38:39], v[36:37], 1, s[42:43]
	global_store_dwordx4 v[38:39], v[48:51], off sc1
	global_store_dwordx4 v[34:35], v[20:23], off offset:512 nt
	global_store_dwordx4 v[34:35], v[16:19], off offset:528 nt
	v_cvt_pk_bf16_f32 v34, v20, v21
	v_cvt_pk_bf16_f32 v35, v22, v23
	v_cvt_pk_bf16_f32 v36, v16, v17
	v_cvt_pk_bf16_f32 v37, v18, v19
	global_store_dwordx4 v[38:39], v[34:37], off offset:256 sc1

; __device__ __forceinline__ unsigned cvt_pk_bf16(float lo, float hi) { unsigned r; asm volatile("v_cvt_pk_bf16_f32 %0, %1, %2" : "=v"(r) : "v"(lo), "v"(hi)); return r; }
;     __device__ __forceinline__ void operator()(const f32x4 (&acc)[2][2][4][2], const Unit& u, int wr, int wc, int fr, int fq) const {
;     ...
;         } else if (u.kind == 1) {
;             const bool isk = u.pn < 4; const int c0 = col0 - (isk ? 0 : 1024);
;             float* ob = isk ? outK : outV;
; #pragma unroll
;             for (int ai = 0; ai < 2; ++ai)
; #pragma unroll
;                 for (int m = 0; m < 4; ++m) {
;                     const size_t off = (size_t)(row0 + ai * HALF + m * 16) * 1024 + c0;
; #pragma unroll
;                     for (int bj = 0; bj < 2; ++bj) {
;                         const f32x4 v0 = acc[ai][bj][m][0], v1 = acc[ai][bj][m][1];
;                         __builtin_nontemporal_store(v0, (f32x4*)(ob + off + bj * HALF)); __builtin_nontemporal_store(v1, (f32x4*)(ob + off + bj * HALF + 4));
;                         if (isk) { u32x4 w; w.x = cvt_pk_bf16(v0[0], v0[1]); w.y = cvt_pk_bf16(v0[2], v0[3]); w.z = cvt_pk_bf16(v1[0], v1[1]); w.w = cvt_pk_bf16(v1[2], v1[3]); *(u32x4*)(KB + off + bj * HALF) = w; }
;                     }
;                 }
.LBB0_388:
	s_andn2_b64 vcc, exec, s[28:29]
	s_cbranch_vccnz .LBB0_390
	v_cvt_pk_bf16_f32 v36, v12, v13
	v_cvt_pk_bf16_f32 v37, v14, v15
	v_cvt_pk_bf16_f32 v38, v8, v9
	v_cvt_pk_bf16_f32 v39, v10, v11
	v_lshl_add_u64 v[48:49], v[34:35], 1, s[42:43]
	global_store_dwordx4 v[48:49], v[36:39], off sc1
	global_store_dwordx4 v[32:33], v[4:7], off offset:512 nt
	global_store_dwordx4 v[32:33], v[0:3], off offset:528 nt
	v_cvt_pk_bf16_f32 v32, v4, v5
	v_cvt_pk_bf16_f32 v33, v6, v7
	v_cvt_pk_bf16_f32 v34, v0, v1
	v_cvt_pk_bf16_f32 v35, v2, v3
	global_store_dwordx4 v[48:49], v[32:35], off offset:256 sc1

; __device__ __forceinline__ unsigned cvt_pk_bf16(float lo, float hi) { unsigned r; asm volatile("v_cvt_pk_bf16_f32 %0, %1, %2" : "=v"(r) : "v"(lo), "v"(hi)); return r; }
;     __device__ __forceinline__ void operator()(const f32x4 (&acc)[2][2][4][2], const Unit& u, int wr, int wc, int fr, int fq) const {
;     ...
;         } else {
; #pragma unroll
;             for (int ai = 0; ai < 2; ++ai)
; #pragma unroll
;                 for (int m = 0; m < 4; ++m) {
;                     bf16_t* rowp = VT + (size_t)(row0 + ai * HALF + m * 16) * 1024 + col0;
; #pragma unroll
;                     for (int bj = 0; bj < 2; ++bj) {
;                         const f32x4 v0 = acc[ai][bj][m][0], v1 = acc[ai][bj][m][1];
;                         u32x4 w; w.x = cvt_pk_bf16(v0[0], v0[1]); w.y = cvt_pk_bf16(v0[2], v0[3]); w.z = cvt_pk_bf16(v1[0], v1[1]); w.w = cvt_pk_bf16(v1[2], v1[3]);
;                         *(u32x4*)(rowp + bj * HALF) = w;
;                     }
;                 }
.LBB0_394:
	v_or_b32_e32 v204, 16, v198
	v_or_b32_e32 v202, 32, v198
	v_or_b32_e32 v200, 48, v198
	s_andn2_b64 vcc, exec, s[26:27]
	v_ashrrev_i32_e32 v197, 31, v196
	v_ashrrev_i32_e32 v199, 31, v198
	v_ashrrev_i32_e32 v205, 31, v204
	v_ashrrev_i32_e32 v203, 31, v202
	v_ashrrev_i32_e32 v201, 31, v200
	s_cbranch_vccnz .LBB0_397
	v_lshlrev_b64 v[32:33], 11, v[198:199]
	v_lshl_add_u64 v[32:33], s[52:53], 0, v[32:33]
	v_lshlrev_b64 v[38:39], 1, v[196:197]
	v_lshl_add_u64 v[32:33], v[32:33], 0, v[38:39]
	v_cvt_pk_bf16_f32 v34, v172, v173
	v_cvt_pk_bf16_f32 v35, v174, v175
	v_cvt_pk_bf16_f32 v36, v168, v169
	v_cvt_pk_bf16_f32 v37, v170, v171
	global_store_dwordx4 v[32:33], v[34:37], off sc1
	s_mov_b64 s[0:1], 0x40000
	s_nop 0
	v_cvt_pk_bf16_f32 v34, v164, v165
	v_cvt_pk_bf16_f32 v35, v166, v167
	v_cvt_pk_bf16_f32 v36, v160, v161
	v_cvt_pk_bf16_f32 v37, v162, v163
	global_store_dwordx4 v[32:33], v[34:37], off offset:256 sc1
	s_nop 1
	v_lshlrev_b64 v[34:35], 11, v[204:205]
	v_lshl_add_u64 v[34:35], s[52:53], 0, v[34:35]
	v_lshl_add_u64 v[48:49], v[34:35], 0, v[38:39]
	v_cvt_pk_bf16_f32 v34, v156, v157
	v_cvt_pk_bf16_f32 v35, v158, v159
	v_cvt_pk_bf16_f32 v36, v152, v153
	v_cvt_pk_bf16_f32 v37, v154, v155
	global_store_dwordx4 v[48:49], v[34:37], off sc1
	s_nop 1
	v_cvt_pk_bf16_f32 v34, v148, v149
	v_cvt_pk_bf16_f32 v35, v150, v151
	v_cvt_pk_bf16_f32 v36, v144, v145
	v_cvt_pk_bf16_f32 v37, v146, v147
	global_store_dwordx4 v[48:49], v[34:37], off offset:256 sc1
	s_nop 1
	v_lshlrev_b64 v[34:35], 11, v[202:203]
	v_lshl_add_u64 v[34:35], s[52:53], 0, v[34:35]
	v_lshl_add_u64 v[48:49], v[34:35], 0, v[38:39]
	v_cvt_pk_bf16_f32 v34, v140, v141
	v_cvt_pk_bf16_f32 v35, v142, v143
	v_cvt_pk_bf16_f32 v36, v136, v137
	v_cvt_pk_bf16_f32 v37, v138, v139
	global_store_dwordx4 v[48:49], v[34:37], off sc1
	s_nop 1
	v_cvt_pk_bf16_f32 v34, v132, v133
	v_cvt_pk_bf16_f32 v35, v134, v135
	v_cvt_pk_bf16_f32 v36, v128, v129
	v_cvt_pk_bf16_f32 v37, v130, v131
	global_store_dwordx4 v[48:49], v[34:37], off offset:256 sc1
	s_nop 1
	v_lshlrev_b64 v[34:35], 11, v[200:201]
	v_lshl_add_u64 v[34:35], s[52:53], 0, v[34:35]
	v_lshl_add_u64 v[38:39], v[34:35], 0, v[38:39]
	v_cvt_pk_bf16_f32 v34, v124, v125
	v_cvt_pk_bf16_f32 v35, v126, v127
	v_cvt_pk_bf16_f32 v36, v120, v121
	v_cvt_pk_bf16_f32 v37, v122, v123
	global_store_dwordx4 v[38:39], v[34:37], off sc1
	s_nop 1
	v_cvt_pk_bf16_f32 v34, v116, v117
	v_cvt_pk_bf16_f32 v35, v118, v119
	v_cvt_pk_bf16_f32 v36, v112, v113
	v_cvt_pk_bf16_f32 v37, v114, v115
	global_store_dwordx4 v[38:39], v[34:37], off offset:256 sc1
	v_lshl_add_u64 v[38:39], v[32:33], 0, s[0:1]
	s_mov_b32 s0, 0x40000
	v_add_co_u32_e32 v48, vcc, s0, v32
	v_cvt_pk_bf16_f32 v34, v108, v109
	v_cvt_pk_bf16_f32 v35, v110, v111
	v_cvt_pk_bf16_f32 v36, v104, v105
	v_cvt_pk_bf16_f32 v37, v106, v107
	s_nop 1
	v_addc_co_u32_e32 v49, vcc, 0, v33, vcc
	s_mov_b64 s[0:1], 0x48000
	global_store_dwordx4 v[48:49], v[34:37], off sc1
	s_nop 1
	v_cvt_pk_bf16_f32 v34, v100, v101
	v_cvt_pk_bf16_f32 v35, v102, v103
	v_cvt_pk_bf16_f32 v36, v96, v97
	v_cvt_pk_bf16_f32 v37, v98, v99
	global_store_dwordx4 v[38:39], v[34:37], off offset:256 sc1
	v_lshl_add_u64 v[38:39], v[32:33], 0, s[0:1]
	s_mov_b32 s0, 0x48000
	v_add_co_u32_e32 v48, vcc, s0, v32
	v_cvt_pk_bf16_f32 v34, v84, v85
	v_cvt_pk_bf16_f32 v35, v86, v87
	v_cvt_pk_bf16_f32 v36, v72, v73
	v_cvt_pk_bf16_f32 v37, v74, v75
	s_nop 1
	v_addc_co_u32_e32 v49, vcc, 0, v33, vcc
	s_mov_b64 s[0:1], 0x50000
	global_store_dwordx4 v[48:49], v[34:37], off sc1
	s_nop 1
	v_cvt_pk_bf16_f32 v34, v44, v45
	v_cvt_pk_bf16_f32 v35, v46, v47
	v_cvt_pk_bf16_f32 v36, v40, v41
	v_cvt_pk_bf16_f32 v37, v42, v43
	global_store_dwordx4 v[38:39], v[34:37], off offset:256 sc1
	v_lshl_add_u64 v[38:39], v[32:33], 0, s[0:1]
	s_mov_b32 s0, 0x50000
	v_add_co_u32_e32 v48, vcc, s0, v32
	v_cvt_pk_bf16_f32 v34, v28, v29
	v_cvt_pk_bf16_f32 v35, v30, v31
	v_cvt_pk_bf16_f32 v36, v24, v25
	v_cvt_pk_bf16_f32 v37, v26, v27
	s_nop 1
	v_addc_co_u32_e32 v49, vcc, 0, v33, vcc
	s_mov_b64 s[0:1], 0x58000
	global_store_dwordx4 v[48:49], v[34:37], off sc1
	s_nop 1
	v_cvt_pk_bf16_f32 v34, v20, v21
	v_cvt_pk_bf16_f32 v35, v22, v23
	v_cvt_pk_bf16_f32 v36, v16, v17
	v_cvt_pk_bf16_f32 v37, v18, v19
	global_store_dwordx4 v[38:39], v[34:37], off offset:256 sc1
	v_lshl_add_u64 v[38:39], v[32:33], 0, s[0:1]
	s_mov_b32 s0, 0x58000
	v_add_co_u32_e32 v32, vcc, s0, v32
	v_cvt_pk_bf16_f32 v34, v12, v13
	v_cvt_pk_bf16_f32 v35, v14, v15
	s_nop 1
	v_addc_co_u32_e32 v33, vcc, 0, v33, vcc
	v_cvt_pk_bf16_f32 v36, v8, v9
	v_cvt_pk_bf16_f32 v37, v10, v11
	global_store_dwordx4 v[32:33], v[34:37], off sc1
	v_cvt_pk_bf16_f32 v32, v4, v5
	v_cvt_pk_bf16_f32 v33, v6, v7
	s_nop 1
	v_cvt_pk_bf16_f32 v34, v0, v1
	v_cvt_pk_bf16_f32 v35, v2, v3
	global_store_dwordx4 v[38:39], v[32:35], off offset:256 sc1
	s_cbranch_execz .LBB0_398

; __device__ __forceinline__ unsigned cvt_pk_bf16(float lo, float hi) { unsigned r; asm volatile("v_cvt_pk_bf16_f32 %0, %1, %2" : "=v"(r) : "v"(lo), "v"(hi)); return r; }
; __device__ __forceinline__ float sigmoidf_(float x) { return __builtin_amdgcn_rcpf(1.0f + __expf(-x)); }
; __device__ __forceinline__ float gelu_tanh(float x) { return x * sigmoidf_(1.5957691216057308f * (x + 0.044715f * x * x * x)); }
; __device__ __forceinline__ f32x2 ln_stats(f32x2 sm) { const float mu = sm[0] * (1.f / D); const float var = fmaxf(sm[1] * (1.f / D) - mu * mu, 0.f); return (f32x2){mu, 1.0f / sqrtf(var + LN_EPS)}; }
;     __device__ __forceinline__ void operator()(const f32x4 (&acc)[2][2][4][2], const Unit& u, int wr, int wc, int fr, int fq) const {
;     ...
;                     const int r = row0 + ai * HALF + m * 16;
;                     bf16_t* rowp = Z + (size_t)r * NZ + col0;
;                     const f32x2 st = ln_stats(*(const f32x2*)(rsum + 2 * (size_t)r));
; #pragma unroll
;                     for (int bj = 0; bj < 2; ++bj) {
;                         f32x4 v0 = (acc[ai][bj][m][0] - s1[bj][0] * st[0]) * st[1] + s2[bj][0], v1 = (acc[ai][bj][m][1] - s1[bj][1] * st[0]) * st[1] + s2[bj][1];
;                         if (mode == 1) {
; #pragma unroll
;                             for (int j = 0; j < 4; ++j) { v0[j] = gelu_tanh(v0[j]); v1[j] = gelu_tanh(v1[j]); }
;                         } else if (mode == 2) {
; #pragma unroll
;                             for (int j = 0; j < 4; ++j) { v0[j] = sigmoidf_(v0[j] + gb[bj][0][j]); v1[j] = sigmoidf_(v1[j] + gb[bj][1][j]); }
;                         }
;                         u32x4 w; w.x = cvt_pk_bf16(v0[0], v0[1]); w.y = cvt_pk_bf16(v0[2], v0[3]); w.z = cvt_pk_bf16(v1[0], v1[1]); w.w = cvt_pk_bf16(v1[2], v1[3]);
;                         *(u32x4*)(rowp + bj * HALF) = w;
.LBB0_412:
	v_mov_b64_e32 v[168:169], s[40:41]
	v_mad_i64_i32 v[168:169], s[0:1], v198, s78, v[168:169]
	v_lshl_add_u64 v[168:169], v[196:197], 1, v[168:169]
	v_cvt_pk_bf16_f32 v172, v199, v216
	v_cvt_pk_bf16_f32 v173, v218, v221
	v_cvt_pk_bf16_f32 v174, v215, v217
	v_cvt_pk_bf16_f32 v175, v219, v220
	v_mov_b32_e32 v207, v206
	global_store_dwordx4 v[168:169], v[172:175], off sc1
	v_mov_b32_e32 v171, v170
	v_xor_b32_e32 v63, 0x80000000, v63
	v_pk_fma_f32 v[172:173], v[60:61], v[206:207], v[164:165] neg_lo:[1,0,0] neg_hi:[1,0,0]
	v_xor_b32_e32 v62, 0x80000000, v62
	v_mov_b32_e32 v174, v206
	v_mov_b32_e32 v175, v206
	v_pk_fma_f32 v[164:165], v[62:63], v[174:175], v[166:167]
	v_pk_fma_f32 v[166:167], v[172:173], v[170:171], v[56:57]
	v_xor_b32_e32 v173, 0x80000000, v53
	v_xor_b32_e32 v172, 0x80000000, v52
	v_xor_b32_e32 v55, 0x80000000, v55
	v_xor_b32_e32 v54, 0x80000000, v54
	v_mov_b32_e32 v208, v170
	v_mov_b32_e32 v209, v170
	v_pk_fma_f32 v[172:173], v[172:173], v[206:207], v[160:161]
	v_pk_fma_f32 v[160:161], v[54:55], v[174:175], v[162:163]
	v_pk_fma_f32 v[164:165], v[164:165], v[208:209], v[58:59]
	v_pk_fma_f32 v[160:161], v[160:161], v[208:209], v[50:51]
	v_pk_fma_f32 v[162:163], v[172:173], v[170:171], v[48:49]
	s_cmp_gt_i32 s2, 1
	s_mov_b64 s[0:1], -1
	s_cbranch_scc0 .LBB0_414
	s_waitcnt lgkmcnt(0)
	v_add_f32_e32 v199, v39, v165
	v_add_f32_e32 v170, v36, v166
	v_add_f32_e32 v171, v32, v162
	v_add_f32_e32 v172, v37, v167
	v_add_f32_e32 v173, v33, v163
	v_add_f32_e32 v174, v38, v164
	v_add_f32_e32 v175, v34, v160
	v_mul_f32_e32 v199, 0xbfb8aa3b, v199
	v_add_f32_e32 v206, v35, v161
	v_mul_f32_e32 v170, 0xbfb8aa3b, v170
	v_mul_f32_e32 v171, 0xbfb8aa3b, v171
	v_mul_f32_e32 v172, 0xbfb8aa3b, v172
	v_mul_f32_e32 v173, 0xbfb8aa3b, v173
	v_mul_f32_e32 v174, 0xbfb8aa3b, v174
	v_mul_f32_e32 v175, 0xbfb8aa3b, v175
	v_exp_f32_e32 v199, v199
	v_mul_f32_e32 v206, 0xbfb8aa3b, v206
	v_exp_f32_e32 v170, v170
	v_exp_f32_e32 v171, v171
	v_exp_f32_e32 v172, v172
	v_exp_f32_e32 v173, v173
	v_exp_f32_e32 v174, v174
	v_exp_f32_e32 v175, v175
	v_exp_f32_e32 v207, v206
	v_add_f32_e32 v199, 1.0, v199
	v_add_f32_e32 v170, 1.0, v170
	v_add_f32_e32 v171, 1.0, v171
	v_add_f32_e32 v172, 1.0, v172
	v_add_f32_e32 v173, 1.0, v173
	v_add_f32_e32 v174, 1.0, v174
	v_add_f32_e32 v175, 1.0, v175
	v_rcp_f32_e32 v206, v199
	v_add_f32_e32 v199, 1.0, v207
	v_rcp_f32_e32 v170, v170
	v_rcp_f32_e32 v171, v171
	v_rcp_f32_e32 v172, v172
	v_rcp_f32_e32 v173, v173
	v_rcp_f32_e32 v174, v174
	v_rcp_f32_e32 v175, v175
	v_rcp_f32_e32 v199, v199
	s_mov_b64 s[0:1], 0

; __device__ __forceinline__ unsigned cvt_pk_bf16(float lo, float hi) { unsigned r; asm volatile("v_cvt_pk_bf16_f32 %0, %1, %2" : "=v"(r) : "v"(lo), "v"(hi)); return r; }
; __device__ __forceinline__ float sigmoidf_(float x) { return __builtin_amdgcn_rcpf(1.0f + __expf(-x)); }
; __device__ __forceinline__ float gelu_tanh(float x) { return x * sigmoidf_(1.5957691216057308f * (x + 0.044715f * x * x * x)); }
; __device__ __forceinline__ f32x2 ln_stats(f32x2 sm) { const float mu = sm[0] * (1.f / D); const float var = fmaxf(sm[1] * (1.f / D) - mu * mu, 0.f); return (f32x2){mu, 1.0f / sqrtf(var + LN_EPS)}; }
;     __device__ __forceinline__ void operator()(const f32x4 (&acc)[2][2][4][2], const Unit& u, int wr, int wc, int fr, int fq) const {
;     ...
;                     const int r = row0 + ai * HALF + m * 16;
;                     bf16_t* rowp = Z + (size_t)r * NZ + col0;
;                     const f32x2 st = ln_stats(*(const f32x2*)(rsum + 2 * (size_t)r));
; #pragma unroll
;                     for (int bj = 0; bj < 2; ++bj) {
;                         f32x4 v0 = (acc[ai][bj][m][0] - s1[bj][0] * st[0]) * st[1] + s2[bj][0], v1 = (acc[ai][bj][m][1] - s1[bj][1] * st[0]) * st[1] + s2[bj][1];
;                         if (mode == 1) {
; #pragma unroll
;                             for (int j = 0; j < 4; ++j) { v0[j] = gelu_tanh(v0[j]); v1[j] = gelu_tanh(v1[j]); }
;                         } else if (mode == 2) {
; #pragma unroll
;                             for (int j = 0; j < 4; ++j) { v0[j] = sigmoidf_(v0[j] + gb[bj][0][j]); v1[j] = sigmoidf_(v1[j] + gb[bj][1][j]); }
;                         }
;                         u32x4 w; w.x = cvt_pk_bf16(v0[0], v0[1]); w.y = cvt_pk_bf16(v0[2], v0[3]); w.z = cvt_pk_bf16(v1[0], v1[1]); w.w = cvt_pk_bf16(v1[2], v1[3]);
;                         *(u32x4*)(rowp + bj * HALF) = w;
.LBB0_418:
	v_cvt_pk_bf16_f32 v160, v170, v172
	v_cvt_pk_bf16_f32 v161, v174, v206
	v_cvt_pk_bf16_f32 v162, v171, v173
	v_cvt_pk_bf16_f32 v163, v175, v199
	global_store_dwordx4 v[168:169], v[160:163], off offset:256 sc1
	s_cmp_gt_i32 s2, 1
	s_nop 0
	v_lshl_add_u64 v[160:161], v[204:205], 3, s[54:55]
	v_mov_b32_e32 v160, v238
	v_mov_b32_e32 v161, v239
	s_nop 0
	v_pk_mul_f32 v[160:161], v[160:161], s[16:17] op_sel_hi:[1,0]
	s_nop 0
	v_fma_f32 v162, -v160, v160, v161
	v_max_f32_e32 v162, 0, v162
	v_add_f32_e32 v162, 0x3727c5ac, v162
	v_mul_f32_e32 v163, 0x4f800000, v162
	v_cmp_gt_f32_e32 vcc, s33, v162
	v_pk_fma_f32 v[158:159], v[94:95], v[160:161], v[158:159] op_sel_hi:[1,0,1]
	v_pk_fma_f32 v[156:157], v[92:93], v[160:161], v[156:157] op_sel_hi:[1,0,1] neg_lo:[1,0,0] neg_hi:[1,0,0]
	v_cndmask_b32_e32 v164, v162, v163, vcc
	v_sqrt_f32_e32 v165, v164
	v_pk_fma_f32 v[162:163], v[90:91], v[160:161], v[154:155] op_sel_hi:[1,0,1]
	v_add_u32_e32 v154, -1, v165
	v_add_u32_e32 v155, 1, v165
	v_fma_f32 v166, -v154, v165, v164
	v_fma_f32 v167, -v155, v165, v164
	v_cmp_ge_f32_e64 s[0:1], 0, v166
	s_nop 1
	v_cndmask_b32_e64 v154, v165, v154, s[0:1]
	v_cmp_lt_f32_e64 s[0:1], 0, v167
	s_nop 1
	v_cndmask_b32_e64 v154, v154, v155, s[0:1]
	v_mul_f32_e32 v155, 0x37800000, v154
	v_cndmask_b32_e32 v154, v154, v155, vcc
	v_cmp_class_f32_e32 vcc, v164, v214
	s_nop 1
	v_cndmask_b32_e32 v154, v154, v164, vcc
	v_div_scale_f32 v155, s[0:1], v154, v154, 1.0
	v_rcp_f32_e32 v166, v155
	v_pk_fma_f32 v[164:165], v[88:89], v[160:161], v[152:153] op_sel_hi:[1,0,1] neg_lo:[1,0,0] neg_hi:[1,0,0]
	v_div_scale_f32 v152, vcc, 1.0, v154, 1.0
	v_fma_f32 v153, -v155, v166, 1.0
	v_fmac_f32_e32 v166, v153, v166
	v_mul_f32_e32 v153, v152, v166
	v_fma_f32 v161, -v155, v153, v152
	v_fmac_f32_e32 v153, v161, v166
	v_fma_f32 v152, -v155, v153, v152
	v_div_fmas_f32 v152, v152, v166, v153
	v_div_fixup_f32 v154, v152, v154, 1.0
	v_pk_fma_f32 v[152:153], v[158:159], v[154:155], v[82:83] op_sel_hi:[1,0,1]
	v_pk_fma_f32 v[156:157], v[156:157], v[154:155], v[80:81] op_sel_hi:[1,0,1]
	v_pk_fma_f32 v[158:159], v[162:163], v[154:155], v[78:79] op_sel_hi:[1,0,1]
	v_pk_fma_f32 v[162:163], v[164:165], v[154:155], v[76:77] op_sel_hi:[1,0,1]
	s_mov_b64 s[0:1], -1
	s_cbranch_scc0 .LBB0_420
	s_waitcnt lgkmcnt(0)
	v_add_f32_e32 v155, v68, v156
	v_mul_f32_e32 v155, 0xbfb8aa3b, v155
	v_add_f32_e32 v161, v64, v162
	v_exp_f32_e32 v155, v155
	v_mul_f32_e32 v161, 0xbfb8aa3b, v161
	v_exp_f32_e32 v161, v161
	v_add_f32_e32 v165, v65, v163
	v_add_f32_e32 v155, 1.0, v155
	v_rcp_f32_e32 v164, v155
	v_add_f32_e32 v155, 1.0, v161
	v_add_f32_e32 v161, v69, v157
	v_mul_f32_e32 v161, 0xbfb8aa3b, v161
	v_exp_f32_e32 v161, v161
	v_mul_f32_e32 v165, 0xbfb8aa3b, v165
	v_exp_f32_e32 v167, v165
	v_rcp_f32_e32 v165, v155
	v_add_f32_e32 v155, 1.0, v161
	v_add_f32_e32 v161, v70, v152
	v_rcp_f32_e32 v166, v155
	v_add_f32_e32 v155, 1.0, v167
	v_mul_f32_e32 v161, 0xbfb8aa3b, v161
	v_add_f32_e32 v167, v66, v158
	v_exp_f32_e32 v161, v161
	v_mul_f32_e32 v167, 0xbfb8aa3b, v167
	v_exp_f32_e32 v169, v167
	v_rcp_f32_e32 v167, v155
	v_add_f32_e32 v155, 1.0, v161
	v_add_f32_e32 v161, v71, v153
	v_rcp_f32_e32 v168, v155
	v_add_f32_e32 v155, 1.0, v169
	v_mul_f32_e32 v161, 0xbfb8aa3b, v161
	v_add_f32_e32 v169, v67, v159
	v_exp_f32_e32 v161, v161
	v_mul_f32_e32 v169, 0xbfb8aa3b, v169
	v_exp_f32_e32 v170, v169
	v_rcp_f32_e32 v169, v155
	v_add_f32_e32 v155, 1.0, v161
	v_rcp_f32_e32 v171, v155
	v_add_f32_e32 v155, 1.0, v170
	v_rcp_f32_e32 v170, v155
	s_mov_b64 s[0:1], 0

; __device__ __forceinline__ unsigned cvt_pk_bf16(float lo, float hi) { unsigned r; asm volatile("v_cvt_pk_bf16_f32 %0, %1, %2" : "=v"(r) : "v"(lo), "v"(hi)); return r; }
; __device__ __forceinline__ float sigmoidf_(float x) { return __builtin_amdgcn_rcpf(1.0f + __expf(-x)); }
; __device__ __forceinline__ float gelu_tanh(float x) { return x * sigmoidf_(1.5957691216057308f * (x + 0.044715f * x * x * x)); }
; __device__ __forceinline__ f32x2 ln_stats(f32x2 sm) { const float mu = sm[0] * (1.f / D); const float var = fmaxf(sm[1] * (1.f / D) - mu * mu, 0.f); return (f32x2){mu, 1.0f / sqrtf(var + LN_EPS)}; }
;     __device__ __forceinline__ void operator()(const f32x4 (&acc)[2][2][4][2], const Unit& u, int wr, int wc, int fr, int fq) const {
;     ...
;                     const int r = row0 + ai * HALF + m * 16;
;                     bf16_t* rowp = Z + (size_t)r * NZ + col0;
;                     const f32x2 st = ln_stats(*(const f32x2*)(rsum + 2 * (size_t)r));
; #pragma unroll
;                     for (int bj = 0; bj < 2; ++bj) {
;                         f32x4 v0 = (acc[ai][bj][m][0] - s1[bj][0] * st[0]) * st[1] + s2[bj][0], v1 = (acc[ai][bj][m][1] - s1[bj][1] * st[0]) * st[1] + s2[bj][1];
;                         if (mode == 1) {
; #pragma unroll
;                             for (int j = 0; j < 4; ++j) { v0[j] = gelu_tanh(v0[j]); v1[j] = gelu_tanh(v1[j]); }
;                         } else if (mode == 2) {
; #pragma unroll
;                             for (int j = 0; j < 4; ++j) { v0[j] = sigmoidf_(v0[j] + gb[bj][0][j]); v1[j] = sigmoidf_(v1[j] + gb[bj][1][j]); }
;                         }
;                         u32x4 w; w.x = cvt_pk_bf16(v0[0], v0[1]); w.y = cvt_pk_bf16(v0[2], v0[3]); w.z = cvt_pk_bf16(v1[0], v1[1]); w.w = cvt_pk_bf16(v1[2], v1[3]);
;                         *(u32x4*)(rowp + bj * HALF) = w;
.LBB0_424:
	v_mov_b64_e32 v[152:153], s[40:41]
	v_mad_i64_i32 v[152:153], s[0:1], v204, s78, v[152:153]
	v_lshl_add_u64 v[152:153], v[196:197], 1, v[152:153]
	v_cvt_pk_bf16_f32 v156, v164, v166
	v_cvt_pk_bf16_f32 v157, v168, v171
	v_cvt_pk_bf16_f32 v158, v165, v167
	v_cvt_pk_bf16_f32 v159, v169, v170
	v_mov_b32_e32 v161, v160
	global_store_dwordx4 v[152:153], v[156:159], off sc1
	v_mov_b32_e32 v155, v154
	v_mov_b32_e32 v162, v154
	v_pk_fma_f32 v[156:157], v[60:61], v[160:161], v[148:149] neg_lo:[1,0,0] neg_hi:[1,0,0]
	v_mov_b32_e32 v158, v160
	v_mov_b32_e32 v159, v160
	v_pk_fma_f32 v[148:149], v[62:63], v[158:159], v[150:151]
	v_mov_b32_e32 v163, v154
	v_pk_fma_f32 v[150:151], v[156:157], v[154:155], v[56:57]
	v_pk_fma_f32 v[156:157], v[52:53], v[160:161], v[144:145] neg_lo:[1,0,0] neg_hi:[1,0,0]
	v_pk_fma_f32 v[144:145], v[54:55], v[158:159], v[146:147]
	v_pk_fma_f32 v[148:149], v[148:149], v[162:163], v[58:59]
	v_pk_fma_f32 v[144:145], v[144:145], v[162:163], v[50:51]
	v_pk_fma_f32 v[146:147], v[156:157], v[154:155], v[48:49]
	s_cmp_gt_i32 s2, 1
	s_mov_b64 s[0:1], -1
	s_cbranch_scc0 .LBB0_426
	s_waitcnt lgkmcnt(0)
	v_add_f32_e32 v160, v39, v149
	v_add_f32_e32 v154, v36, v150
	v_add_f32_e32 v155, v32, v146
	v_add_f32_e32 v156, v37, v151
	v_add_f32_e32 v157, v33, v147
	v_add_f32_e32 v158, v38, v148
	v_add_f32_e32 v159, v34, v144
	v_mul_f32_e32 v160, 0xbfb8aa3b, v160
	v_add_f32_e32 v161, v35, v145
	v_mul_f32_e32 v154, 0xbfb8aa3b, v154
	v_mul_f32_e32 v155, 0xbfb8aa3b, v155
	v_mul_f32_e32 v156, 0xbfb8aa3b, v156
	v_mul_f32_e32 v157, 0xbfb8aa3b, v157
	v_mul_f32_e32 v158, 0xbfb8aa3b, v158
	v_mul_f32_e32 v159, 0xbfb8aa3b, v159
	v_exp_f32_e32 v160, v160
	v_mul_f32_e32 v161, 0xbfb8aa3b, v161
	v_exp_f32_e32 v154, v154
	v_exp_f32_e32 v155, v155
	v_exp_f32_e32 v156, v156
	v_exp_f32_e32 v157, v157
	v_exp_f32_e32 v158, v158
	v_exp_f32_e32 v159, v159
	v_exp_f32_e32 v162, v161
	v_add_f32_e32 v160, 1.0, v160
	v_add_f32_e32 v154, 1.0, v154
	v_add_f32_e32 v155, 1.0, v155
	v_add_f32_e32 v156, 1.0, v156
	v_add_f32_e32 v157, 1.0, v157
	v_add_f32_e32 v158, 1.0, v158
	v_add_f32_e32 v159, 1.0, v159
	v_rcp_f32_e32 v161, v160
	v_add_f32_e32 v160, 1.0, v162
	v_rcp_f32_e32 v154, v154
	v_rcp_f32_e32 v155, v155
	v_rcp_f32_e32 v156, v156
	v_rcp_f32_e32 v157, v157
	v_rcp_f32_e32 v158, v158
	v_rcp_f32_e32 v159, v159
	v_rcp_f32_e32 v160, v160
	s_mov_b64 s[0:1], 0

; __device__ __forceinline__ unsigned cvt_pk_bf16(float lo, float hi) { unsigned r; asm volatile("v_cvt_pk_bf16_f32 %0, %1, %2" : "=v"(r) : "v"(lo), "v"(hi)); return r; }
; __device__ __forceinline__ float sigmoidf_(float x) { return __builtin_amdgcn_rcpf(1.0f + __expf(-x)); }
; __device__ __forceinline__ float gelu_tanh(float x) { return x * sigmoidf_(1.5957691216057308f * (x + 0.044715f * x * x * x)); }
; __device__ __forceinline__ f32x2 ln_stats(f32x2 sm) { const float mu = sm[0] * (1.f / D); const float var = fmaxf(sm[1] * (1.f / D) - mu * mu, 0.f); return (f32x2){mu, 1.0f / sqrtf(var + LN_EPS)}; }
;     __device__ __forceinline__ void operator()(const f32x4 (&acc)[2][2][4][2], const Unit& u, int wr, int wc, int fr, int fq) const {
;     ...
;                     const int r = row0 + ai * HALF + m * 16;
;                     bf16_t* rowp = Z + (size_t)r * NZ + col0;
;                     const f32x2 st = ln_stats(*(const f32x2*)(rsum + 2 * (size_t)r));
; #pragma unroll
;                     for (int bj = 0; bj < 2; ++bj) {
;                         f32x4 v0 = (acc[ai][bj][m][0] - s1[bj][0] * st[0]) * st[1] + s2[bj][0], v1 = (acc[ai][bj][m][1] - s1[bj][1] * st[0]) * st[1] + s2[bj][1];
;                         if (mode == 1) {
; #pragma unroll
;                             for (int j = 0; j < 4; ++j) { v0[j] = gelu_tanh(v0[j]); v1[j] = gelu_tanh(v1[j]); }
;                         } else if (mode == 2) {
; #pragma unroll
;                             for (int j = 0; j < 4; ++j) { v0[j] = sigmoidf_(v0[j] + gb[bj][0][j]); v1[j] = sigmoidf_(v1[j] + gb[bj][1][j]); }
;                         }
;                         u32x4 w; w.x = cvt_pk_bf16(v0[0], v0[1]); w.y = cvt_pk_bf16(v0[2], v0[3]); w.z = cvt_pk_bf16(v1[0], v1[1]); w.w = cvt_pk_bf16(v1[2], v1[3]);
;                         *(u32x4*)(rowp + bj * HALF) = w;
.LBB0_430:
	v_cvt_pk_bf16_f32 v144, v154, v156
	v_cvt_pk_bf16_f32 v145, v158, v161
	v_cvt_pk_bf16_f32 v146, v155, v157
	v_cvt_pk_bf16_f32 v147, v159, v160
	global_store_dwordx4 v[152:153], v[144:147], off offset:256 sc1
	s_cmp_gt_i32 s2, 1
	s_nop 0
	v_lshl_add_u64 v[144:145], v[202:203], 3, s[54:55]
	v_mov_b32_e32 v144, v240
	v_mov_b32_e32 v145, v241
	s_nop 0
	v_pk_mul_f32 v[144:145], v[144:145], s[16:17] op_sel_hi:[1,0]
	s_nop 0
	v_fma_f32 v146, -v144, v144, v145
	v_max_f32_e32 v146, 0, v146
	v_add_f32_e32 v146, 0x3727c5ac, v146
	v_mul_f32_e32 v147, 0x4f800000, v146
	v_cmp_gt_f32_e32 vcc, s33, v146
	v_pk_fma_f32 v[142:143], v[94:95], v[144:145], v[142:143] op_sel_hi:[1,0,1]
	v_pk_fma_f32 v[140:141], v[92:93], v[144:145], v[140:141] op_sel_hi:[1,0,1] neg_lo:[1,0,0] neg_hi:[1,0,0]
	v_cndmask_b32_e32 v148, v146, v147, vcc
	v_sqrt_f32_e32 v149, v148
	v_pk_fma_f32 v[146:147], v[90:91], v[144:145], v[138:139] op_sel_hi:[1,0,1]
	v_add_u32_e32 v138, -1, v149
	v_add_u32_e32 v139, 1, v149
	v_fma_f32 v150, -v138, v149, v148
	v_fma_f32 v151, -v139, v149, v148
	v_cmp_ge_f32_e64 s[0:1], 0, v150
	s_nop 1
	v_cndmask_b32_e64 v138, v149, v138, s[0:1]
	v_cmp_lt_f32_e64 s[0:1], 0, v151
	s_nop 1
	v_cndmask_b32_e64 v138, v138, v139, s[0:1]
	v_mul_f32_e32 v139, 0x37800000, v138
	v_cndmask_b32_e32 v138, v138, v139, vcc
	v_cmp_class_f32_e32 vcc, v148, v214
	s_nop 1
	v_cndmask_b32_e32 v138, v138, v148, vcc
	v_div_scale_f32 v139, s[0:1], v138, v138, 1.0
	v_rcp_f32_e32 v150, v139
	v_pk_fma_f32 v[148:149], v[88:89], v[144:145], v[136:137] op_sel_hi:[1,0,1] neg_lo:[1,0,0] neg_hi:[1,0,0]
	v_div_scale_f32 v136, vcc, 1.0, v138, 1.0
	v_fma_f32 v137, -v139, v150, 1.0
	v_fmac_f32_e32 v150, v137, v150
	v_mul_f32_e32 v137, v136, v150
	v_fma_f32 v145, -v139, v137, v136
	v_fmac_f32_e32 v137, v145, v150
	v_fma_f32 v136, -v139, v137, v136
	v_div_fmas_f32 v136, v136, v150, v137
	v_div_fixup_f32 v138, v136, v138, 1.0
	v_pk_fma_f32 v[136:137], v[142:143], v[138:139], v[82:83] op_sel_hi:[1,0,1]
	v_pk_fma_f32 v[140:141], v[140:141], v[138:139], v[80:81] op_sel_hi:[1,0,1]
	v_pk_fma_f32 v[142:143], v[146:147], v[138:139], v[78:79] op_sel_hi:[1,0,1]
	v_pk_fma_f32 v[146:147], v[148:149], v[138:139], v[76:77] op_sel_hi:[1,0,1]
	s_mov_b64 s[0:1], -1
	s_cbranch_scc0 .LBB0_432
	s_waitcnt lgkmcnt(0)
	v_add_f32_e32 v139, v68, v140
	v_mul_f32_e32 v139, 0xbfb8aa3b, v139
	v_add_f32_e32 v145, v64, v146
	v_exp_f32_e32 v139, v139
	v_mul_f32_e32 v145, 0xbfb8aa3b, v145
	v_exp_f32_e32 v145, v145
	v_add_f32_e32 v149, v65, v147
	v_add_f32_e32 v139, 1.0, v139
	v_rcp_f32_e32 v148, v139
	v_add_f32_e32 v139, 1.0, v145
	v_add_f32_e32 v145, v69, v141
	v_mul_f32_e32 v145, 0xbfb8aa3b, v145
	v_exp_f32_e32 v145, v145
	v_mul_f32_e32 v149, 0xbfb8aa3b, v149
	v_exp_f32_e32 v151, v149
	v_rcp_f32_e32 v149, v139
	v_add_f32_e32 v139, 1.0, v145
	v_add_f32_e32 v145, v70, v136
	v_rcp_f32_e32 v150, v139
	v_add_f32_e32 v139, 1.0, v151
	v_mul_f32_e32 v145, 0xbfb8aa3b, v145
	v_add_f32_e32 v151, v66, v142
	v_exp_f32_e32 v145, v145
	v_mul_f32_e32 v151, 0xbfb8aa3b, v151
	v_exp_f32_e32 v153, v151
	v_rcp_f32_e32 v151, v139
	v_add_f32_e32 v139, 1.0, v145
	v_add_f32_e32 v145, v71, v137
	v_rcp_f32_e32 v152, v139
	v_add_f32_e32 v139, 1.0, v153
	v_mul_f32_e32 v145, 0xbfb8aa3b, v145
	v_add_f32_e32 v153, v67, v143
	v_exp_f32_e32 v145, v145
	v_mul_f32_e32 v153, 0xbfb8aa3b, v153
	v_exp_f32_e32 v154, v153
	v_rcp_f32_e32 v153, v139
	v_add_f32_e32 v139, 1.0, v145
	v_rcp_f32_e32 v155, v139
	v_add_f32_e32 v139, 1.0, v154
	v_rcp_f32_e32 v154, v139
	s_mov_b64 s[0:1], 0

; __device__ __forceinline__ unsigned cvt_pk_bf16(float lo, float hi) { unsigned r; asm volatile("v_cvt_pk_bf16_f32 %0, %1, %2" : "=v"(r) : "v"(lo), "v"(hi)); return r; }
; __device__ __forceinline__ float sigmoidf_(float x) { return __builtin_amdgcn_rcpf(1.0f + __expf(-x)); }
; __device__ __forceinline__ float gelu_tanh(float x) { return x * sigmoidf_(1.5957691216057308f * (x + 0.044715f * x * x * x)); }
; __device__ __forceinline__ f32x2 ln_stats(f32x2 sm) { const float mu = sm[0] * (1.f / D); const float var = fmaxf(sm[1] * (1.f / D) - mu * mu, 0.f); return (f32x2){mu, 1.0f / sqrtf(var + LN_EPS)}; }
;     __device__ __forceinline__ void operator()(const f32x4 (&acc)[2][2][4][2], const Unit& u, int wr, int wc, int fr, int fq) const {
;     ...
;                     const int r = row0 + ai * HALF + m * 16;
;                     bf16_t* rowp = Z + (size_t)r * NZ + col0;
;                     const f32x2 st = ln_stats(*(const f32x2*)(rsum + 2 * (size_t)r));
; #pragma unroll
;                     for (int bj = 0; bj < 2; ++bj) {
;                         f32x4 v0 = (acc[ai][bj][m][0] - s1[bj][0] * st[0]) * st[1] + s2[bj][0], v1 = (acc[ai][bj][m][1] - s1[bj][1] * st[0]) * st[1] + s2[bj][1];
;                         if (mode == 1) {
; #pragma unroll
;                             for (int j = 0; j < 4; ++j) { v0[j] = gelu_tanh(v0[j]); v1[j] = gelu_tanh(v1[j]); }
;                         } else if (mode == 2) {
; #pragma unroll
;                             for (int j = 0; j < 4; ++j) { v0[j] = sigmoidf_(v0[j] + gb[bj][0][j]); v1[j] = sigmoidf_(v1[j] + gb[bj][1][j]); }
;                         }
;                         u32x4 w; w.x = cvt_pk_bf16(v0[0], v0[1]); w.y = cvt_pk_bf16(v0[2], v0[3]); w.z = cvt_pk_bf16(v1[0], v1[1]); w.w = cvt_pk_bf16(v1[2], v1[3]);
;                         *(u32x4*)(rowp + bj * HALF) = w;
.LBB0_436:
	v_mov_b64_e32 v[136:137], s[40:41]
	v_mad_i64_i32 v[136:137], s[0:1], v202, s78, v[136:137]
	v_lshl_add_u64 v[136:137], v[196:197], 1, v[136:137]
	v_cvt_pk_bf16_f32 v140, v148, v150
	v_cvt_pk_bf16_f32 v141, v152, v155
	v_cvt_pk_bf16_f32 v142, v149, v151
	v_cvt_pk_bf16_f32 v143, v153, v154
	v_mov_b32_e32 v145, v144
	global_store_dwordx4 v[136:137], v[140:143], off sc1
	v_mov_b32_e32 v139, v138
	v_mov_b32_e32 v146, v138
	v_pk_fma_f32 v[140:141], v[60:61], v[144:145], v[132:133] neg_lo:[1,0,0] neg_hi:[1,0,0]
	v_mov_b32_e32 v142, v144
	v_mov_b32_e32 v143, v144
	v_pk_fma_f32 v[132:133], v[62:63], v[142:143], v[134:135]
	v_mov_b32_e32 v147, v138
	v_pk_fma_f32 v[134:135], v[140:141], v[138:139], v[56:57]
	v_pk_fma_f32 v[140:141], v[52:53], v[144:145], v[128:129] neg_lo:[1,0,0] neg_hi:[1,0,0]
	v_pk_fma_f32 v[128:129], v[54:55], v[142:143], v[130:131]
	v_pk_fma_f32 v[132:133], v[132:133], v[146:147], v[58:59]
	v_pk_fma_f32 v[128:129], v[128:129], v[146:147], v[50:51]
	v_pk_fma_f32 v[130:131], v[140:141], v[138:139], v[48:49]
	s_cmp_gt_i32 s2, 1
	s_mov_b64 s[0:1], -1
	s_cbranch_scc0 .LBB0_438
	s_waitcnt lgkmcnt(0)
	v_add_f32_e32 v144, v39, v133
	v_add_f32_e32 v138, v36, v134
	v_add_f32_e32 v139, v32, v130
	v_add_f32_e32 v140, v37, v135
	v_add_f32_e32 v141, v33, v131
	v_add_f32_e32 v142, v38, v132
	v_add_f32_e32 v143, v34, v128
	v_mul_f32_e32 v144, 0xbfb8aa3b, v144
	v_add_f32_e32 v145, v35, v129
	v_mul_f32_e32 v138, 0xbfb8aa3b, v138
	v_mul_f32_e32 v139, 0xbfb8aa3b, v139
	v_mul_f32_e32 v140, 0xbfb8aa3b, v140
	v_mul_f32_e32 v141, 0xbfb8aa3b, v141
	v_mul_f32_e32 v142, 0xbfb8aa3b, v142
	v_mul_f32_e32 v143, 0xbfb8aa3b, v143
	v_exp_f32_e32 v144, v144
	v_mul_f32_e32 v145, 0xbfb8aa3b, v145
	v_exp_f32_e32 v138, v138
	v_exp_f32_e32 v139, v139
	v_exp_f32_e32 v140, v140
	v_exp_f32_e32 v141, v141
	v_exp_f32_e32 v142, v142
	v_exp_f32_e32 v143, v143
	v_exp_f32_e32 v146, v145
	v_add_f32_e32 v144, 1.0, v144
	v_add_f32_e32 v138, 1.0, v138
	v_add_f32_e32 v139, 1.0, v139
	v_add_f32_e32 v140, 1.0, v140
	v_add_f32_e32 v141, 1.0, v141
	v_add_f32_e32 v142, 1.0, v142
	v_add_f32_e32 v143, 1.0, v143
	v_rcp_f32_e32 v145, v144
	v_add_f32_e32 v144, 1.0, v146
	v_rcp_f32_e32 v138, v138
	v_rcp_f32_e32 v139, v139
	v_rcp_f32_e32 v140, v140
	v_rcp_f32_e32 v141, v141
	v_rcp_f32_e32 v142, v142
	v_rcp_f32_e32 v143, v143
	v_rcp_f32_e32 v144, v144
	s_mov_b64 s[0:1], 0

; __device__ __forceinline__ unsigned cvt_pk_bf16(float lo, float hi) { unsigned r; asm volatile("v_cvt_pk_bf16_f32 %0, %1, %2" : "=v"(r) : "v"(lo), "v"(hi)); return r; }
; __device__ __forceinline__ float sigmoidf_(float x) { return __builtin_amdgcn_rcpf(1.0f + __expf(-x)); }
; __device__ __forceinline__ float gelu_tanh(float x) { return x * sigmoidf_(1.5957691216057308f * (x + 0.044715f * x * x * x)); }
; __device__ __forceinline__ f32x2 ln_stats(f32x2 sm) { const float mu = sm[0] * (1.f / D); const float var = fmaxf(sm[1] * (1.f / D) - mu * mu, 0.f); return (f32x2){mu, 1.0f / sqrtf(var + LN_EPS)}; }
;     __device__ __forceinline__ void operator()(const f32x4 (&acc)[2][2][4][2], const Unit& u, int wr, int wc, int fr, int fq) const {
;     ...
;                     const int r = row0 + ai * HALF + m * 16;
;                     bf16_t* rowp = Z + (size_t)r * NZ + col0;
;                     const f32x2 st = ln_stats(*(const f32x2*)(rsum + 2 * (size_t)r));
; #pragma unroll
;                     for (int bj = 0; bj < 2; ++bj) {
;                         f32x4 v0 = (acc[ai][bj][m][0] - s1[bj][0] * st[0]) * st[1] + s2[bj][0], v1 = (acc[ai][bj][m][1] - s1[bj][1] * st[0]) * st[1] + s2[bj][1];
;                         if (mode == 1) {
; #pragma unroll
;                             for (int j = 0; j < 4; ++j) { v0[j] = gelu_tanh(v0[j]); v1[j] = gelu_tanh(v1[j]); }
;                         } else if (mode == 2) {
; #pragma unroll
;                             for (int j = 0; j < 4; ++j) { v0[j] = sigmoidf_(v0[j] + gb[bj][0][j]); v1[j] = sigmoidf_(v1[j] + gb[bj][1][j]); }
;                         }
;                         u32x4 w; w.x = cvt_pk_bf16(v0[0], v0[1]); w.y = cvt_pk_bf16(v0[2], v0[3]); w.z = cvt_pk_bf16(v1[0], v1[1]); w.w = cvt_pk_bf16(v1[2], v1[3]);
;                         *(u32x4*)(rowp + bj * HALF) = w;
.LBB0_442:
	v_cvt_pk_bf16_f32 v128, v138, v140
	v_cvt_pk_bf16_f32 v129, v142, v145
	v_cvt_pk_bf16_f32 v130, v139, v141
	v_cvt_pk_bf16_f32 v131, v143, v144
	global_store_dwordx4 v[136:137], v[128:131], off offset:256 sc1
	s_cmp_gt_i32 s2, 1
	s_nop 0
	v_lshl_add_u64 v[128:129], v[200:201], 3, s[54:55]
	v_mov_b32_e32 v128, v242
	v_mov_b32_e32 v129, v243
	s_nop 0
	v_pk_mul_f32 v[128:129], v[128:129], s[16:17] op_sel_hi:[1,0]
	s_nop 0
	v_fma_f32 v130, -v128, v128, v129
	v_max_f32_e32 v130, 0, v130
	v_add_f32_e32 v130, 0x3727c5ac, v130
	v_mul_f32_e32 v131, 0x4f800000, v130
	v_cmp_gt_f32_e32 vcc, s33, v130
	v_pk_fma_f32 v[126:127], v[94:95], v[128:129], v[126:127] op_sel_hi:[1,0,1]
	v_pk_fma_f32 v[124:125], v[92:93], v[128:129], v[124:125] op_sel_hi:[1,0,1] neg_lo:[1,0,0] neg_hi:[1,0,0]
	v_cndmask_b32_e32 v132, v130, v131, vcc
	v_sqrt_f32_e32 v133, v132
	v_pk_fma_f32 v[130:131], v[90:91], v[128:129], v[122:123] op_sel_hi:[1,0,1]
	v_add_u32_e32 v122, -1, v133
	v_add_u32_e32 v123, 1, v133
	v_fma_f32 v134, -v122, v133, v132
	v_fma_f32 v135, -v123, v133, v132
	v_cmp_ge_f32_e64 s[0:1], 0, v134
	s_nop 1
	v_cndmask_b32_e64 v122, v133, v122, s[0:1]
	v_cmp_lt_f32_e64 s[0:1], 0, v135
	s_nop 1
	v_cndmask_b32_e64 v122, v122, v123, s[0:1]
	v_mul_f32_e32 v123, 0x37800000, v122
	v_cndmask_b32_e32 v122, v122, v123, vcc
	v_cmp_class_f32_e32 vcc, v132, v214
	s_nop 1
	v_cndmask_b32_e32 v122, v122, v132, vcc
	v_div_scale_f32 v123, s[0:1], v122, v122, 1.0
	v_rcp_f32_e32 v134, v123
	v_pk_fma_f32 v[132:133], v[88:89], v[128:129], v[120:121] op_sel_hi:[1,0,1] neg_lo:[1,0,0] neg_hi:[1,0,0]
	v_div_scale_f32 v120, vcc, 1.0, v122, 1.0
	v_fma_f32 v121, -v123, v134, 1.0
	v_fmac_f32_e32 v134, v121, v134
	v_mul_f32_e32 v121, v120, v134
	v_fma_f32 v129, -v123, v121, v120
	v_fmac_f32_e32 v121, v129, v134
	v_fma_f32 v120, -v123, v121, v120
	v_div_fmas_f32 v120, v120, v134, v121
	v_div_fixup_f32 v122, v120, v122, 1.0
	v_pk_fma_f32 v[120:121], v[126:127], v[122:123], v[82:83] op_sel_hi:[1,0,1]
	v_pk_fma_f32 v[124:125], v[124:125], v[122:123], v[80:81] op_sel_hi:[1,0,1]
	v_pk_fma_f32 v[126:127], v[130:131], v[122:123], v[78:79] op_sel_hi:[1,0,1]
	v_pk_fma_f32 v[130:131], v[132:133], v[122:123], v[76:77] op_sel_hi:[1,0,1]
	s_mov_b64 s[0:1], -1
	s_cbranch_scc0 .LBB0_444
	s_waitcnt lgkmcnt(0)
	v_add_f32_e32 v123, v68, v124
	v_mul_f32_e32 v123, 0xbfb8aa3b, v123
	v_add_f32_e32 v129, v64, v130
	v_exp_f32_e32 v123, v123
	v_mul_f32_e32 v129, 0xbfb8aa3b, v129
	v_exp_f32_e32 v129, v129
	v_add_f32_e32 v133, v65, v131
	v_add_f32_e32 v123, 1.0, v123
	v_rcp_f32_e32 v132, v123
	v_add_f32_e32 v123, 1.0, v129
	v_add_f32_e32 v129, v69, v125
	v_mul_f32_e32 v129, 0xbfb8aa3b, v129
	v_exp_f32_e32 v129, v129
	v_mul_f32_e32 v133, 0xbfb8aa3b, v133
	v_exp_f32_e32 v135, v133
	v_rcp_f32_e32 v133, v123
	v_add_f32_e32 v123, 1.0, v129
	v_add_f32_e32 v129, v70, v120
	v_rcp_f32_e32 v134, v123
	v_add_f32_e32 v123, 1.0, v135
	v_mul_f32_e32 v129, 0xbfb8aa3b, v129
	v_add_f32_e32 v135, v66, v126
	v_exp_f32_e32 v129, v129
	v_mul_f32_e32 v135, 0xbfb8aa3b, v135
	v_exp_f32_e32 v137, v135
	v_rcp_f32_e32 v135, v123
	v_add_f32_e32 v123, 1.0, v129
	v_add_f32_e32 v129, v71, v121
	v_rcp_f32_e32 v136, v123
	v_add_f32_e32 v123, 1.0, v137
	v_mul_f32_e32 v129, 0xbfb8aa3b, v129
	v_add_f32_e32 v137, v67, v127
	v_exp_f32_e32 v129, v129
	v_mul_f32_e32 v137, 0xbfb8aa3b, v137
	v_exp_f32_e32 v138, v137
	v_rcp_f32_e32 v137, v123
	v_add_f32_e32 v123, 1.0, v129
	v_rcp_f32_e32 v139, v123
	v_add_f32_e32 v123, 1.0, v138
	v_rcp_f32_e32 v138, v123
	s_mov_b64 s[0:1], 0

; __device__ __forceinline__ unsigned cvt_pk_bf16(float lo, float hi) { unsigned r; asm volatile("v_cvt_pk_bf16_f32 %0, %1, %2" : "=v"(r) : "v"(lo), "v"(hi)); return r; }
; __device__ __forceinline__ float sigmoidf_(float x) { return __builtin_amdgcn_rcpf(1.0f + __expf(-x)); }
; __device__ __forceinline__ float gelu_tanh(float x) { return x * sigmoidf_(1.5957691216057308f * (x + 0.044715f * x * x * x)); }
; __device__ __forceinline__ f32x2 ln_stats(f32x2 sm) { const float mu = sm[0] * (1.f / D); const float var = fmaxf(sm[1] * (1.f / D) - mu * mu, 0.f); return (f32x2){mu, 1.0f / sqrtf(var + LN_EPS)}; }
;     __device__ __forceinline__ void operator()(const f32x4 (&acc)[2][2][4][2], const Unit& u, int wr, int wc, int fr, int fq) const {
;     ...
;                     const int r = row0 + ai * HALF + m * 16;
;                     bf16_t* rowp = Z + (size_t)r * NZ + col0;
;                     const f32x2 st = ln_stats(*(const f32x2*)(rsum + 2 * (size_t)r));
; #pragma unroll
;                     for (int bj = 0; bj < 2; ++bj) {
;                         f32x4 v0 = (acc[ai][bj][m][0] - s1[bj][0] * st[0]) * st[1] + s2[bj][0], v1 = (acc[ai][bj][m][1] - s1[bj][1] * st[0]) * st[1] + s2[bj][1];
;                         if (mode == 1) {
; #pragma unroll
;                             for (int j = 0; j < 4; ++j) { v0[j] = gelu_tanh(v0[j]); v1[j] = gelu_tanh(v1[j]); }
;                         } else if (mode == 2) {
; #pragma unroll
;                             for (int j = 0; j < 4; ++j) { v0[j] = sigmoidf_(v0[j] + gb[bj][0][j]); v1[j] = sigmoidf_(v1[j] + gb[bj][1][j]); }
;                         }
;                         u32x4 w; w.x = cvt_pk_bf16(v0[0], v0[1]); w.y = cvt_pk_bf16(v0[2], v0[3]); w.z = cvt_pk_bf16(v1[0], v1[1]); w.w = cvt_pk_bf16(v1[2], v1[3]);
;                         *(u32x4*)(rowp + bj * HALF) = w;
.LBB0_448:
	v_mov_b64_e32 v[120:121], s[40:41]
	v_mad_i64_i32 v[120:121], s[0:1], v200, s78, v[120:121]
	v_lshl_add_u64 v[120:121], v[196:197], 1, v[120:121]
	v_cvt_pk_bf16_f32 v124, v132, v134
	v_cvt_pk_bf16_f32 v125, v136, v139
	v_cvt_pk_bf16_f32 v126, v133, v135
	v_cvt_pk_bf16_f32 v127, v137, v138
	v_mov_b32_e32 v129, v128
	global_store_dwordx4 v[120:121], v[124:127], off sc1
	v_mov_b32_e32 v123, v122
	v_mov_b32_e32 v130, v122
	v_pk_fma_f32 v[124:125], v[60:61], v[128:129], v[116:117] neg_lo:[1,0,0] neg_hi:[1,0,0]
	v_mov_b32_e32 v126, v128
	v_mov_b32_e32 v127, v128
	v_pk_fma_f32 v[116:117], v[62:63], v[126:127], v[118:119]
	v_mov_b32_e32 v131, v122
	v_pk_fma_f32 v[118:119], v[124:125], v[122:123], v[56:57]
	v_pk_fma_f32 v[124:125], v[52:53], v[128:129], v[112:113] neg_lo:[1,0,0] neg_hi:[1,0,0]
	v_pk_fma_f32 v[112:113], v[54:55], v[126:127], v[114:115]
	v_pk_fma_f32 v[116:117], v[116:117], v[130:131], v[58:59]
	v_pk_fma_f32 v[112:113], v[112:113], v[130:131], v[50:51]
	v_pk_fma_f32 v[114:115], v[124:125], v[122:123], v[48:49]
	s_cmp_gt_i32 s2, 1
	s_mov_b64 s[0:1], -1
	s_cbranch_scc0 .LBB0_450
	s_waitcnt lgkmcnt(0)
	v_add_f32_e32 v128, v39, v117
	v_add_f32_e32 v122, v36, v118
	v_add_f32_e32 v123, v32, v114
	v_add_f32_e32 v124, v37, v119
	v_add_f32_e32 v125, v33, v115
	v_add_f32_e32 v126, v38, v116
	v_add_f32_e32 v127, v34, v112
	v_mul_f32_e32 v128, 0xbfb8aa3b, v128
	v_add_f32_e32 v129, v35, v113
	v_mul_f32_e32 v122, 0xbfb8aa3b, v122
	v_mul_f32_e32 v123, 0xbfb8aa3b, v123
	v_mul_f32_e32 v124, 0xbfb8aa3b, v124
	v_mul_f32_e32 v125, 0xbfb8aa3b, v125
	v_mul_f32_e32 v126, 0xbfb8aa3b, v126
	v_mul_f32_e32 v127, 0xbfb8aa3b, v127
	v_exp_f32_e32 v128, v128
	v_mul_f32_e32 v129, 0xbfb8aa3b, v129
	v_exp_f32_e32 v122, v122
	v_exp_f32_e32 v123, v123
	v_exp_f32_e32 v124, v124
	v_exp_f32_e32 v125, v125
	v_exp_f32_e32 v126, v126
	v_exp_f32_e32 v127, v127
	v_exp_f32_e32 v130, v129
	v_add_f32_e32 v128, 1.0, v128
	v_add_f32_e32 v122, 1.0, v122
	v_add_f32_e32 v123, 1.0, v123
	v_add_f32_e32 v124, 1.0, v124
	v_add_f32_e32 v125, 1.0, v125
	v_add_f32_e32 v126, 1.0, v126
	v_add_f32_e32 v127, 1.0, v127
	v_rcp_f32_e32 v129, v128
	v_add_f32_e32 v128, 1.0, v130
	v_rcp_f32_e32 v122, v122
	v_rcp_f32_e32 v123, v123
	v_rcp_f32_e32 v124, v124
	v_rcp_f32_e32 v125, v125
	v_rcp_f32_e32 v126, v126
	v_rcp_f32_e32 v127, v127
	v_rcp_f32_e32 v128, v128
	s_mov_b64 s[0:1], 0

; __device__ __forceinline__ unsigned cvt_pk_bf16(float lo, float hi) { unsigned r; asm volatile("v_cvt_pk_bf16_f32 %0, %1, %2" : "=v"(r) : "v"(lo), "v"(hi)); return r; }
; __device__ __forceinline__ float sigmoidf_(float x) { return __builtin_amdgcn_rcpf(1.0f + __expf(-x)); }
; __device__ __forceinline__ float gelu_tanh(float x) { return x * sigmoidf_(1.5957691216057308f * (x + 0.044715f * x * x * x)); }
; __device__ __forceinline__ f32x2 ln_stats(f32x2 sm) { const float mu = sm[0] * (1.f / D); const float var = fmaxf(sm[1] * (1.f / D) - mu * mu, 0.f); return (f32x2){mu, 1.0f / sqrtf(var + LN_EPS)}; }
;     __device__ __forceinline__ void operator()(const f32x4 (&acc)[2][2][4][2], const Unit& u, int wr, int wc, int fr, int fq) const {
;     ...
;                     const int r = row0 + ai * HALF + m * 16;
;                     bf16_t* rowp = Z + (size_t)r * NZ + col0;
;                     const f32x2 st = ln_stats(*(const f32x2*)(rsum + 2 * (size_t)r));
; #pragma unroll
;                     for (int bj = 0; bj < 2; ++bj) {
;                         f32x4 v0 = (acc[ai][bj][m][0] - s1[bj][0] * st[0]) * st[1] + s2[bj][0], v1 = (acc[ai][bj][m][1] - s1[bj][1] * st[0]) * st[1] + s2[bj][1];
;                         if (mode == 1) {
; #pragma unroll
;                             for (int j = 0; j < 4; ++j) { v0[j] = gelu_tanh(v0[j]); v1[j] = gelu_tanh(v1[j]); }
;                         } else if (mode == 2) {
; #pragma unroll
;                             for (int j = 0; j < 4; ++j) { v0[j] = sigmoidf_(v0[j] + gb[bj][0][j]); v1[j] = sigmoidf_(v1[j] + gb[bj][1][j]); }
;                         }
;                         u32x4 w; w.x = cvt_pk_bf16(v0[0], v0[1]); w.y = cvt_pk_bf16(v0[2], v0[3]); w.z = cvt_pk_bf16(v1[0], v1[1]); w.w = cvt_pk_bf16(v1[2], v1[3]);
;                         *(u32x4*)(rowp + bj * HALF) = w;
.LBB0_454:
	v_cvt_pk_bf16_f32 v112, v122, v124
	v_cvt_pk_bf16_f32 v113, v126, v129
	v_cvt_pk_bf16_f32 v114, v123, v125
	v_cvt_pk_bf16_f32 v115, v127, v128
	global_store_dwordx4 v[120:121], v[112:115], off offset:256 sc1
	s_cmp_gt_i32 s2, 1
	s_nop 0
	v_add_u32_e32 v112, 0x80, v198
	v_ashrrev_i32_e32 v113, 31, v112
	v_lshl_add_u64 v[114:115], v[112:113], 3, s[54:55]
	v_mov_b32_e32 v114, v244
	v_mov_b32_e32 v115, v245
	s_nop 0
	v_pk_mul_f32 v[114:115], v[114:115], s[16:17] op_sel_hi:[1,0]
	s_nop 0
	v_fma_f32 v113, -v114, v114, v115
	v_max_f32_e32 v113, 0, v113
	v_add_f32_e32 v113, 0x3727c5ac, v113
	v_mul_f32_e32 v116, 0x4f800000, v113
	v_cmp_gt_f32_e32 vcc, s33, v113
	v_pk_fma_f32 v[110:111], v[94:95], v[114:115], v[110:111] op_sel_hi:[1,0,1]
	v_pk_fma_f32 v[108:109], v[92:93], v[114:115], v[108:109] op_sel_hi:[1,0,1] neg_lo:[1,0,0] neg_hi:[1,0,0]
	v_cndmask_b32_e32 v113, v113, v116, vcc
	v_sqrt_f32_e32 v118, v113
	v_pk_fma_f32 v[116:117], v[90:91], v[114:115], v[106:107] op_sel_hi:[1,0,1]
	v_add_u32_e32 v106, -1, v118
	v_add_u32_e32 v107, 1, v118
	v_fma_f32 v119, -v106, v118, v113
	v_fma_f32 v120, -v107, v118, v113
	v_cmp_ge_f32_e64 s[0:1], 0, v119
	s_nop 1
	v_cndmask_b32_e64 v106, v118, v106, s[0:1]
	v_cmp_lt_f32_e64 s[0:1], 0, v120
	v_pk_fma_f32 v[118:119], v[88:89], v[114:115], v[104:105] op_sel_hi:[1,0,1] neg_lo:[1,0,0] neg_hi:[1,0,0]
	s_nop 0
	v_cndmask_b32_e64 v106, v106, v107, s[0:1]
	v_mul_f32_e32 v107, 0x37800000, v106
	v_cndmask_b32_e32 v106, v106, v107, vcc
	v_cmp_class_f32_e32 vcc, v113, v214
	s_nop 1
	v_cndmask_b32_e32 v106, v106, v113, vcc
	v_div_scale_f32 v107, s[0:1], v106, v106, 1.0
	v_rcp_f32_e32 v113, v107
	v_div_scale_f32 v104, vcc, 1.0, v106, 1.0
	s_mov_b64 s[0:1], -1
	v_fma_f32 v105, -v107, v113, 1.0
	v_fmac_f32_e32 v113, v105, v113
	v_mul_f32_e32 v105, v104, v113
	v_fma_f32 v115, -v107, v105, v104
	v_fmac_f32_e32 v105, v115, v113
	v_fma_f32 v104, -v107, v105, v104
	v_div_fmas_f32 v104, v104, v113, v105
	v_div_fixup_f32 v106, v104, v106, 1.0
	v_pk_fma_f32 v[104:105], v[110:111], v[106:107], v[82:83] op_sel_hi:[1,0,1]
	v_pk_fma_f32 v[108:109], v[108:109], v[106:107], v[80:81] op_sel_hi:[1,0,1]
	v_pk_fma_f32 v[110:111], v[116:117], v[106:107], v[78:79] op_sel_hi:[1,0,1]
	v_pk_fma_f32 v[116:117], v[118:119], v[106:107], v[76:77] op_sel_hi:[1,0,1]
	s_cbranch_scc0 .LBB0_456
	s_waitcnt lgkmcnt(0)
	v_add_f32_e32 v107, v68, v108
	v_mul_f32_e32 v107, 0xbfb8aa3b, v107
	v_add_f32_e32 v113, v64, v116
	v_exp_f32_e32 v107, v107
	v_mul_f32_e32 v113, 0xbfb8aa3b, v113
	v_exp_f32_e32 v115, v113
	v_add_f32_e32 v118, v65, v117
	v_add_f32_e32 v107, 1.0, v107
	v_rcp_f32_e32 v113, v107
	v_add_f32_e32 v107, 1.0, v115
	v_add_f32_e32 v115, v69, v109
	v_mul_f32_e32 v115, 0xbfb8aa3b, v115
	v_exp_f32_e32 v115, v115
	v_mul_f32_e32 v118, 0xbfb8aa3b, v118
	v_exp_f32_e32 v120, v118
	v_rcp_f32_e32 v118, v107
	v_add_f32_e32 v107, 1.0, v115
	v_add_f32_e32 v115, v70, v104
	v_rcp_f32_e32 v119, v107
	v_add_f32_e32 v107, 1.0, v120
	v_mul_f32_e32 v115, 0xbfb8aa3b, v115
	v_add_f32_e32 v120, v66, v110
	v_exp_f32_e32 v115, v115
	v_mul_f32_e32 v120, 0xbfb8aa3b, v120
	v_exp_f32_e32 v122, v120
	v_rcp_f32_e32 v120, v107
	v_add_f32_e32 v107, 1.0, v115
	v_add_f32_e32 v115, v71, v105
	v_rcp_f32_e32 v121, v107
	v_add_f32_e32 v107, 1.0, v122
	v_mul_f32_e32 v115, 0xbfb8aa3b, v115
	v_add_f32_e32 v122, v67, v111
	v_exp_f32_e32 v115, v115
	v_mul_f32_e32 v122, 0xbfb8aa3b, v122
	v_exp_f32_e32 v123, v122
	v_rcp_f32_e32 v122, v107
	v_add_f32_e32 v107, 1.0, v115
	v_rcp_f32_e32 v124, v107
	v_add_f32_e32 v107, 1.0, v123
	v_rcp_f32_e32 v123, v107
	s_mov_b64 s[0:1], 0

; __device__ __forceinline__ unsigned cvt_pk_bf16(float lo, float hi) { unsigned r; asm volatile("v_cvt_pk_bf16_f32 %0, %1, %2" : "=v"(r) : "v"(lo), "v"(hi)); return r; }
; __device__ __forceinline__ float sigmoidf_(float x) { return __builtin_amdgcn_rcpf(1.0f + __expf(-x)); }
; __device__ __forceinline__ float gelu_tanh(float x) { return x * sigmoidf_(1.5957691216057308f * (x + 0.044715f * x * x * x)); }
; __device__ __forceinline__ f32x2 ln_stats(f32x2 sm) { const float mu = sm[0] * (1.f / D); const float var = fmaxf(sm[1] * (1.f / D) - mu * mu, 0.f); return (f32x2){mu, 1.0f / sqrtf(var + LN_EPS)}; }
;     __device__ __forceinline__ void operator()(const f32x4 (&acc)[2][2][4][2], const Unit& u, int wr, int wc, int fr, int fq) const {
;     ...
;                     const int r = row0 + ai * HALF + m * 16;
;                     bf16_t* rowp = Z + (size_t)r * NZ + col0;
;                     const f32x2 st = ln_stats(*(const f32x2*)(rsum + 2 * (size_t)r));
; #pragma unroll
;                     for (int bj = 0; bj < 2; ++bj) {
;                         f32x4 v0 = (acc[ai][bj][m][0] - s1[bj][0] * st[0]) * st[1] + s2[bj][0], v1 = (acc[ai][bj][m][1] - s1[bj][1] * st[0]) * st[1] + s2[bj][1];
;                         if (mode == 1) {
; #pragma unroll
;                             for (int j = 0; j < 4; ++j) { v0[j] = gelu_tanh(v0[j]); v1[j] = gelu_tanh(v1[j]); }
;                         } else if (mode == 2) {
; #pragma unroll
;                             for (int j = 0; j < 4; ++j) { v0[j] = sigmoidf_(v0[j] + gb[bj][0][j]); v1[j] = sigmoidf_(v1[j] + gb[bj][1][j]); }
;                         }
;                         u32x4 w; w.x = cvt_pk_bf16(v0[0], v0[1]); w.y = cvt_pk_bf16(v0[2], v0[3]); w.z = cvt_pk_bf16(v1[0], v1[1]); w.w = cvt_pk_bf16(v1[2], v1[3]);
;                         *(u32x4*)(rowp + bj * HALF) = w;
.LBB0_460:
	v_mov_b64_e32 v[104:105], s[40:41]
	v_mad_i64_i32 v[104:105], s[0:1], v112, s78, v[104:105]
	v_lshl_add_u64 v[104:105], v[196:197], 1, v[104:105]
	v_cvt_pk_bf16_f32 v108, v113, v119
	v_cvt_pk_bf16_f32 v109, v121, v124
	v_cvt_pk_bf16_f32 v110, v118, v120
	v_cvt_pk_bf16_f32 v111, v122, v123
	v_mov_b32_e32 v115, v114
	global_store_dwordx4 v[104:105], v[108:111], off sc1
	v_mov_b32_e32 v107, v106
	v_mov_b32_e32 v112, v106
	v_pk_fma_f32 v[108:109], v[60:61], v[114:115], v[100:101] neg_lo:[1,0,0] neg_hi:[1,0,0]
	v_mov_b32_e32 v110, v114
	v_mov_b32_e32 v111, v114
	v_pk_fma_f32 v[100:101], v[62:63], v[110:111], v[102:103]
	v_mov_b32_e32 v113, v106
	v_pk_fma_f32 v[102:103], v[108:109], v[106:107], v[56:57]
	v_pk_fma_f32 v[108:109], v[52:53], v[114:115], v[96:97] neg_lo:[1,0,0] neg_hi:[1,0,0]
	v_pk_fma_f32 v[96:97], v[54:55], v[110:111], v[98:99]
	v_pk_fma_f32 v[100:101], v[100:101], v[112:113], v[58:59]
	v_pk_fma_f32 v[96:97], v[96:97], v[112:113], v[50:51]
	v_pk_fma_f32 v[98:99], v[108:109], v[106:107], v[48:49]
	s_cmp_gt_i32 s2, 1
	s_mov_b64 s[0:1], -1
	s_cbranch_scc0 .LBB0_462
	s_waitcnt lgkmcnt(0)
	v_add_f32_e32 v112, v39, v101
	v_add_f32_e32 v106, v36, v102
	v_add_f32_e32 v107, v32, v98
	v_add_f32_e32 v108, v37, v103
	v_add_f32_e32 v109, v33, v99
	v_add_f32_e32 v110, v38, v100
	v_add_f32_e32 v111, v34, v96
	v_mul_f32_e32 v112, 0xbfb8aa3b, v112
	v_add_f32_e32 v113, v35, v97
	v_mul_f32_e32 v106, 0xbfb8aa3b, v106
	v_mul_f32_e32 v107, 0xbfb8aa3b, v107
	v_mul_f32_e32 v108, 0xbfb8aa3b, v108
	v_mul_f32_e32 v109, 0xbfb8aa3b, v109
	v_mul_f32_e32 v110, 0xbfb8aa3b, v110
	v_mul_f32_e32 v111, 0xbfb8aa3b, v111
	v_exp_f32_e32 v112, v112
	v_mul_f32_e32 v113, 0xbfb8aa3b, v113
	v_exp_f32_e32 v106, v106
	v_exp_f32_e32 v107, v107
	v_exp_f32_e32 v108, v108
	v_exp_f32_e32 v109, v109
	v_exp_f32_e32 v110, v110
	v_exp_f32_e32 v111, v111
	v_exp_f32_e32 v114, v113
	v_add_f32_e32 v112, 1.0, v112
	v_add_f32_e32 v106, 1.0, v106
	v_add_f32_e32 v107, 1.0, v107
	v_add_f32_e32 v108, 1.0, v108
	v_add_f32_e32 v109, 1.0, v109
	v_add_f32_e32 v110, 1.0, v110
	v_add_f32_e32 v111, 1.0, v111
	v_rcp_f32_e32 v113, v112
	v_add_f32_e32 v112, 1.0, v114
	v_rcp_f32_e32 v106, v106
	v_rcp_f32_e32 v107, v107
	v_rcp_f32_e32 v108, v108
	v_rcp_f32_e32 v109, v109
	v_rcp_f32_e32 v110, v110
	v_rcp_f32_e32 v111, v111
	v_rcp_f32_e32 v112, v112
	s_mov_b64 s[0:1], 0

; __device__ __forceinline__ unsigned cvt_pk_bf16(float lo, float hi) { unsigned r; asm volatile("v_cvt_pk_bf16_f32 %0, %1, %2" : "=v"(r) : "v"(lo), "v"(hi)); return r; }
; __device__ __forceinline__ float sigmoidf_(float x) { return __builtin_amdgcn_rcpf(1.0f + __expf(-x)); }
; __device__ __forceinline__ float gelu_tanh(float x) { return x * sigmoidf_(1.5957691216057308f * (x + 0.044715f * x * x * x)); }
; __device__ __forceinline__ f32x2 ln_stats(f32x2 sm) { const float mu = sm[0] * (1.f / D); const float var = fmaxf(sm[1] * (1.f / D) - mu * mu, 0.f); return (f32x2){mu, 1.0f / sqrtf(var + LN_EPS)}; }
;     __device__ __forceinline__ void operator()(const f32x4 (&acc)[2][2][4][2], const Unit& u, int wr, int wc, int fr, int fq) const {
;     ...
;                     const int r = row0 + ai * HALF + m * 16;
;                     bf16_t* rowp = Z + (size_t)r * NZ + col0;
;                     const f32x2 st = ln_stats(*(const f32x2*)(rsum + 2 * (size_t)r));
; #pragma unroll
;                     for (int bj = 0; bj < 2; ++bj) {
;                         f32x4 v0 = (acc[ai][bj][m][0] - s1[bj][0] * st[0]) * st[1] + s2[bj][0], v1 = (acc[ai][bj][m][1] - s1[bj][1] * st[0]) * st[1] + s2[bj][1];
;                         if (mode == 1) {
; #pragma unroll
;                             for (int j = 0; j < 4; ++j) { v0[j] = gelu_tanh(v0[j]); v1[j] = gelu_tanh(v1[j]); }
;                         } else if (mode == 2) {
; #pragma unroll
;                             for (int j = 0; j < 4; ++j) { v0[j] = sigmoidf_(v0[j] + gb[bj][0][j]); v1[j] = sigmoidf_(v1[j] + gb[bj][1][j]); }
;                         }
;                         u32x4 w; w.x = cvt_pk_bf16(v0[0], v0[1]); w.y = cvt_pk_bf16(v0[2], v0[3]); w.z = cvt_pk_bf16(v1[0], v1[1]); w.w = cvt_pk_bf16(v1[2], v1[3]);
;                         *(u32x4*)(rowp + bj * HALF) = w;
.LBB0_466:
	v_cvt_pk_bf16_f32 v96, v106, v108
	v_cvt_pk_bf16_f32 v97, v110, v113
	v_cvt_pk_bf16_f32 v98, v107, v109
	v_cvt_pk_bf16_f32 v99, v111, v112
	global_store_dwordx4 v[104:105], v[96:99], off offset:256 sc1
	s_cmp_gt_i32 s2, 1
	s_nop 0
	v_add_u32_e32 v96, 0x90, v198
	v_ashrrev_i32_e32 v97, 31, v96
	v_lshl_add_u64 v[98:99], v[96:97], 3, s[54:55]
	v_mov_b32_e32 v98, v246
	v_mov_b32_e32 v99, v247
	s_nop 0
	v_pk_mul_f32 v[98:99], v[98:99], s[16:17] op_sel_hi:[1,0]
	s_nop 0
	v_fma_f32 v97, -v98, v98, v99
	v_max_f32_e32 v97, 0, v97
	v_add_f32_e32 v97, 0x3727c5ac, v97
	v_mul_f32_e32 v100, 0x4f800000, v97
	v_cmp_gt_f32_e32 vcc, s33, v97
	v_pk_fma_f32 v[86:87], v[94:95], v[98:99], v[86:87] op_sel_hi:[1,0,1]
	v_pk_fma_f32 v[84:85], v[92:93], v[98:99], v[84:85] op_sel_hi:[1,0,1] neg_lo:[1,0,0] neg_hi:[1,0,0]
	v_cndmask_b32_e32 v97, v97, v100, vcc
	v_sqrt_f32_e32 v102, v97
	v_pk_fma_f32 v[100:101], v[90:91], v[98:99], v[74:75] op_sel_hi:[1,0,1]
	v_add_u32_e32 v74, -1, v102
	v_add_u32_e32 v75, 1, v102
	v_fma_f32 v103, -v74, v102, v97
	v_fma_f32 v104, -v75, v102, v97
	v_cmp_ge_f32_e64 s[0:1], 0, v103
	s_nop 1
	v_cndmask_b32_e64 v74, v102, v74, s[0:1]
	v_cmp_lt_f32_e64 s[0:1], 0, v104
	v_pk_fma_f32 v[102:103], v[88:89], v[98:99], v[72:73] op_sel_hi:[1,0,1] neg_lo:[1,0,0] neg_hi:[1,0,0]
	s_nop 0
	v_cndmask_b32_e64 v74, v74, v75, s[0:1]
	v_mul_f32_e32 v75, 0x37800000, v74
	v_cndmask_b32_e32 v74, v74, v75, vcc
	v_cmp_class_f32_e32 vcc, v97, v214
	s_nop 1
	v_cndmask_b32_e32 v74, v74, v97, vcc
	v_div_scale_f32 v75, s[0:1], v74, v74, 1.0
	v_rcp_f32_e32 v97, v75
	v_div_scale_f32 v72, vcc, 1.0, v74, 1.0
	s_mov_b64 s[0:1], -1
	v_fma_f32 v73, -v75, v97, 1.0
	v_fmac_f32_e32 v97, v73, v97
	v_mul_f32_e32 v73, v72, v97
	v_fma_f32 v99, -v75, v73, v72
	v_fmac_f32_e32 v73, v99, v97
	v_fma_f32 v72, -v75, v73, v72
	v_div_fmas_f32 v72, v72, v97, v73
	v_div_fixup_f32 v74, v72, v74, 1.0
	v_pk_fma_f32 v[72:73], v[86:87], v[74:75], v[82:83] op_sel_hi:[1,0,1]
	v_pk_fma_f32 v[84:85], v[84:85], v[74:75], v[80:81] op_sel_hi:[1,0,1]
	v_pk_fma_f32 v[86:87], v[100:101], v[74:75], v[78:79] op_sel_hi:[1,0,1]
	v_pk_fma_f32 v[100:101], v[102:103], v[74:75], v[76:77] op_sel_hi:[1,0,1]
	s_cbranch_scc0 .LBB0_468
	s_waitcnt lgkmcnt(0)
	v_add_f32_e32 v75, v68, v84
	v_mul_f32_e32 v75, 0xbfb8aa3b, v75
	v_add_f32_e32 v97, v64, v100
	v_exp_f32_e32 v75, v75
	v_mul_f32_e32 v97, 0xbfb8aa3b, v97
	v_exp_f32_e32 v99, v97
	v_add_f32_e32 v102, v65, v101
	v_add_f32_e32 v75, 1.0, v75
	v_rcp_f32_e32 v97, v75
	v_add_f32_e32 v75, 1.0, v99
	v_add_f32_e32 v99, v69, v85
	v_mul_f32_e32 v99, 0xbfb8aa3b, v99
	v_exp_f32_e32 v99, v99
	v_mul_f32_e32 v102, 0xbfb8aa3b, v102
	v_exp_f32_e32 v104, v102
	v_rcp_f32_e32 v102, v75
	v_add_f32_e32 v75, 1.0, v99
	v_add_f32_e32 v99, v70, v72
	v_rcp_f32_e32 v103, v75
	v_add_f32_e32 v75, 1.0, v104
	v_mul_f32_e32 v99, 0xbfb8aa3b, v99
	v_add_f32_e32 v104, v66, v86
	v_exp_f32_e32 v99, v99
	v_mul_f32_e32 v104, 0xbfb8aa3b, v104
	v_exp_f32_e32 v106, v104
	v_rcp_f32_e32 v104, v75
	v_add_f32_e32 v75, 1.0, v99
	v_add_f32_e32 v99, v71, v73
	v_rcp_f32_e32 v105, v75
	v_add_f32_e32 v75, 1.0, v106
	v_mul_f32_e32 v99, 0xbfb8aa3b, v99
	v_add_f32_e32 v106, v67, v87
	v_exp_f32_e32 v99, v99
	v_mul_f32_e32 v106, 0xbfb8aa3b, v106
	v_exp_f32_e32 v107, v106
	v_rcp_f32_e32 v106, v75
	v_add_f32_e32 v75, 1.0, v99
	v_rcp_f32_e32 v108, v75
	v_add_f32_e32 v75, 1.0, v107
	v_rcp_f32_e32 v107, v75
	s_mov_b64 s[0:1], 0

; __device__ __forceinline__ unsigned cvt_pk_bf16(float lo, float hi) { unsigned r; asm volatile("v_cvt_pk_bf16_f32 %0, %1, %2" : "=v"(r) : "v"(lo), "v"(hi)); return r; }
; __device__ __forceinline__ float sigmoidf_(float x) { return __builtin_amdgcn_rcpf(1.0f + __expf(-x)); }
; __device__ __forceinline__ float gelu_tanh(float x) { return x * sigmoidf_(1.5957691216057308f * (x + 0.044715f * x * x * x)); }
; __device__ __forceinline__ f32x2 ln_stats(f32x2 sm) { const float mu = sm[0] * (1.f / D); const float var = fmaxf(sm[1] * (1.f / D) - mu * mu, 0.f); return (f32x2){mu, 1.0f / sqrtf(var + LN_EPS)}; }
;     __device__ __forceinline__ void operator()(const f32x4 (&acc)[2][2][4][2], const Unit& u, int wr, int wc, int fr, int fq) const {
;     ...
;                     const int r = row0 + ai * HALF + m * 16;
;                     bf16_t* rowp = Z + (size_t)r * NZ + col0;
;                     const f32x2 st = ln_stats(*(const f32x2*)(rsum + 2 * (size_t)r));
; #pragma unroll
;                     for (int bj = 0; bj < 2; ++bj) {
;                         f32x4 v0 = (acc[ai][bj][m][0] - s1[bj][0] * st[0]) * st[1] + s2[bj][0], v1 = (acc[ai][bj][m][1] - s1[bj][1] * st[0]) * st[1] + s2[bj][1];
;                         if (mode == 1) {
; #pragma unroll
;                             for (int j = 0; j < 4; ++j) { v0[j] = gelu_tanh(v0[j]); v1[j] = gelu_tanh(v1[j]); }
;                         } else if (mode == 2) {
; #pragma unroll
;                             for (int j = 0; j < 4; ++j) { v0[j] = sigmoidf_(v0[j] + gb[bj][0][j]); v1[j] = sigmoidf_(v1[j] + gb[bj][1][j]); }
;                         }
;                         u32x4 w; w.x = cvt_pk_bf16(v0[0], v0[1]); w.y = cvt_pk_bf16(v0[2], v0[3]); w.z = cvt_pk_bf16(v1[0], v1[1]); w.w = cvt_pk_bf16(v1[2], v1[3]);
;                         *(u32x4*)(rowp + bj * HALF) = w;
.LBB0_472:
	v_mov_b64_e32 v[72:73], s[40:41]
	v_mad_i64_i32 v[72:73], s[0:1], v96, s78, v[72:73]
	v_lshl_add_u64 v[72:73], v[196:197], 1, v[72:73]
	v_cvt_pk_bf16_f32 v84, v97, v103
	v_cvt_pk_bf16_f32 v85, v105, v108
	v_cvt_pk_bf16_f32 v86, v102, v104
	v_cvt_pk_bf16_f32 v87, v106, v107
	v_mov_b32_e32 v99, v98
	global_store_dwordx4 v[72:73], v[84:87], off sc1
	v_mov_b32_e32 v75, v74
	v_mov_b32_e32 v96, v74
	v_pk_fma_f32 v[84:85], v[60:61], v[98:99], v[44:45] neg_lo:[1,0,0] neg_hi:[1,0,0]
	v_mov_b32_e32 v86, v98
	v_mov_b32_e32 v87, v98
	v_pk_fma_f32 v[44:45], v[62:63], v[86:87], v[46:47]
	v_mov_b32_e32 v97, v74
	v_pk_fma_f32 v[46:47], v[84:85], v[74:75], v[56:57]
	v_pk_fma_f32 v[84:85], v[52:53], v[98:99], v[40:41] neg_lo:[1,0,0] neg_hi:[1,0,0]
	v_pk_fma_f32 v[40:41], v[54:55], v[86:87], v[42:43]
	v_pk_fma_f32 v[44:45], v[44:45], v[96:97], v[58:59]
	v_pk_fma_f32 v[40:41], v[40:41], v[96:97], v[50:51]
	v_pk_fma_f32 v[42:43], v[84:85], v[74:75], v[48:49]
	s_cmp_gt_i32 s2, 1
	s_mov_b64 s[0:1], -1
	s_cbranch_scc0 .LBB0_474
	s_waitcnt lgkmcnt(0)
	v_add_f32_e32 v96, v39, v45
	v_add_f32_e32 v74, v36, v46
	v_add_f32_e32 v75, v32, v42
	v_add_f32_e32 v84, v37, v47
	v_add_f32_e32 v85, v33, v43
	v_add_f32_e32 v86, v38, v44
	v_add_f32_e32 v87, v34, v40
	v_mul_f32_e32 v96, 0xbfb8aa3b, v96
	v_add_f32_e32 v97, v35, v41
	v_mul_f32_e32 v74, 0xbfb8aa3b, v74
	v_mul_f32_e32 v75, 0xbfb8aa3b, v75
	v_mul_f32_e32 v84, 0xbfb8aa3b, v84
	v_mul_f32_e32 v85, 0xbfb8aa3b, v85
	v_mul_f32_e32 v86, 0xbfb8aa3b, v86
	v_mul_f32_e32 v87, 0xbfb8aa3b, v87
	v_exp_f32_e32 v96, v96
	v_mul_f32_e32 v97, 0xbfb8aa3b, v97
	v_exp_f32_e32 v74, v74
	v_exp_f32_e32 v75, v75
	v_exp_f32_e32 v84, v84
	v_exp_f32_e32 v85, v85
	v_exp_f32_e32 v86, v86
	v_exp_f32_e32 v87, v87
	v_exp_f32_e32 v98, v97
	v_add_f32_e32 v96, 1.0, v96
	v_add_f32_e32 v74, 1.0, v74
	v_add_f32_e32 v75, 1.0, v75
	v_add_f32_e32 v84, 1.0, v84
	v_add_f32_e32 v85, 1.0, v85
	v_add_f32_e32 v86, 1.0, v86
	v_add_f32_e32 v87, 1.0, v87
	v_rcp_f32_e32 v97, v96
	v_add_f32_e32 v96, 1.0, v98
	v_rcp_f32_e32 v74, v74
	v_rcp_f32_e32 v75, v75
	v_rcp_f32_e32 v84, v84
	v_rcp_f32_e32 v85, v85
	v_rcp_f32_e32 v86, v86
	v_rcp_f32_e32 v87, v87
	v_rcp_f32_e32 v96, v96
	s_mov_b64 s[0:1], 0

; __device__ __forceinline__ unsigned cvt_pk_bf16(float lo, float hi) { unsigned r; asm volatile("v_cvt_pk_bf16_f32 %0, %1, %2" : "=v"(r) : "v"(lo), "v"(hi)); return r; }
; __device__ __forceinline__ float sigmoidf_(float x) { return __builtin_amdgcn_rcpf(1.0f + __expf(-x)); }
; __device__ __forceinline__ float gelu_tanh(float x) { return x * sigmoidf_(1.5957691216057308f * (x + 0.044715f * x * x * x)); }
; __device__ __forceinline__ f32x2 ln_stats(f32x2 sm) { const float mu = sm[0] * (1.f / D); const float var = fmaxf(sm[1] * (1.f / D) - mu * mu, 0.f); return (f32x2){mu, 1.0f / sqrtf(var + LN_EPS)}; }
;     __device__ __forceinline__ void operator()(const f32x4 (&acc)[2][2][4][2], const Unit& u, int wr, int wc, int fr, int fq) const {
;     ...
;                     const int r = row0 + ai * HALF + m * 16;
;                     bf16_t* rowp = Z + (size_t)r * NZ + col0;
;                     const f32x2 st = ln_stats(*(const f32x2*)(rsum + 2 * (size_t)r));
; #pragma unroll
;                     for (int bj = 0; bj < 2; ++bj) {
;                         f32x4 v0 = (acc[ai][bj][m][0] - s1[bj][0] * st[0]) * st[1] + s2[bj][0], v1 = (acc[ai][bj][m][1] - s1[bj][1] * st[0]) * st[1] + s2[bj][1];
;                         if (mode == 1) {
; #pragma unroll
;                             for (int j = 0; j < 4; ++j) { v0[j] = gelu_tanh(v0[j]); v1[j] = gelu_tanh(v1[j]); }
;                         } else if (mode == 2) {
; #pragma unroll
;                             for (int j = 0; j < 4; ++j) { v0[j] = sigmoidf_(v0[j] + gb[bj][0][j]); v1[j] = sigmoidf_(v1[j] + gb[bj][1][j]); }
;                         }
;                         u32x4 w; w.x = cvt_pk_bf16(v0[0], v0[1]); w.y = cvt_pk_bf16(v0[2], v0[3]); w.z = cvt_pk_bf16(v1[0], v1[1]); w.w = cvt_pk_bf16(v1[2], v1[3]);
;                         *(u32x4*)(rowp + bj * HALF) = w;
.LBB0_478:
	v_cvt_pk_bf16_f32 v40, v74, v84
	v_cvt_pk_bf16_f32 v41, v86, v97
	v_cvt_pk_bf16_f32 v42, v75, v85
	v_cvt_pk_bf16_f32 v43, v87, v96
	global_store_dwordx4 v[72:73], v[40:43], off offset:256 sc1
	s_cmp_gt_i32 s2, 1
	s_nop 0
	v_add_u32_e32 v40, 0xa0, v198
	v_ashrrev_i32_e32 v41, 31, v40
	v_lshl_add_u64 v[42:43], v[40:41], 3, s[54:55]
	v_mov_b32_e32 v42, v248
	v_mov_b32_e32 v43, v249
	s_nop 0
	v_pk_mul_f32 v[42:43], v[42:43], s[16:17] op_sel_hi:[1,0]
	s_nop 0
	v_fma_f32 v41, -v42, v42, v43
	v_max_f32_e32 v41, 0, v41
	v_add_f32_e32 v41, 0x3727c5ac, v41
	v_mul_f32_e32 v44, 0x4f800000, v41
	v_cmp_gt_f32_e32 vcc, s33, v41
	v_pk_fma_f32 v[30:31], v[94:95], v[42:43], v[30:31] op_sel_hi:[1,0,1]
	v_pk_fma_f32 v[28:29], v[92:93], v[42:43], v[28:29] op_sel_hi:[1,0,1] neg_lo:[1,0,0] neg_hi:[1,0,0]
	v_cndmask_b32_e32 v41, v41, v44, vcc
	v_sqrt_f32_e32 v46, v41
	v_pk_fma_f32 v[44:45], v[90:91], v[42:43], v[26:27] op_sel_hi:[1,0,1]
	v_add_u32_e32 v26, -1, v46
	v_add_u32_e32 v27, 1, v46
	v_fma_f32 v47, -v26, v46, v41
	v_fma_f32 v72, -v27, v46, v41
	v_cmp_ge_f32_e64 s[0:1], 0, v47
	s_nop 1
	v_cndmask_b32_e64 v26, v46, v26, s[0:1]
	v_cmp_lt_f32_e64 s[0:1], 0, v72
	v_pk_fma_f32 v[46:47], v[88:89], v[42:43], v[24:25] op_sel_hi:[1,0,1] neg_lo:[1,0,0] neg_hi:[1,0,0]
	s_nop 0
	v_cndmask_b32_e64 v26, v26, v27, s[0:1]
	v_mul_f32_e32 v27, 0x37800000, v26
	v_cndmask_b32_e32 v26, v26, v27, vcc
	v_cmp_class_f32_e32 vcc, v41, v214
	s_nop 1
	v_cndmask_b32_e32 v26, v26, v41, vcc
	v_div_scale_f32 v27, s[0:1], v26, v26, 1.0
	v_rcp_f32_e32 v41, v27
	v_div_scale_f32 v24, vcc, 1.0, v26, 1.0
	s_mov_b64 s[0:1], -1
	v_fma_f32 v25, -v27, v41, 1.0
	v_fmac_f32_e32 v41, v25, v41
	v_mul_f32_e32 v25, v24, v41
	v_fma_f32 v43, -v27, v25, v24
	v_fmac_f32_e32 v25, v43, v41
	v_fma_f32 v24, -v27, v25, v24
	v_div_fmas_f32 v24, v24, v41, v25
	v_div_fixup_f32 v26, v24, v26, 1.0
	v_pk_fma_f32 v[24:25], v[30:31], v[26:27], v[82:83] op_sel_hi:[1,0,1]
	v_pk_fma_f32 v[28:29], v[28:29], v[26:27], v[80:81] op_sel_hi:[1,0,1]
	v_pk_fma_f32 v[30:31], v[44:45], v[26:27], v[78:79] op_sel_hi:[1,0,1]
	v_pk_fma_f32 v[44:45], v[46:47], v[26:27], v[76:77] op_sel_hi:[1,0,1]
	s_cbranch_scc0 .LBB0_480
	s_waitcnt lgkmcnt(0)
	v_add_f32_e32 v27, v68, v28
	v_mul_f32_e32 v27, 0xbfb8aa3b, v27
	v_add_f32_e32 v41, v64, v44
	v_exp_f32_e32 v27, v27
	v_mul_f32_e32 v41, 0xbfb8aa3b, v41
	v_exp_f32_e32 v43, v41
	v_add_f32_e32 v46, v65, v45
	v_add_f32_e32 v27, 1.0, v27
	v_rcp_f32_e32 v41, v27
	v_add_f32_e32 v27, 1.0, v43
	v_add_f32_e32 v43, v69, v29
	v_mul_f32_e32 v43, 0xbfb8aa3b, v43
	v_exp_f32_e32 v43, v43
	v_mul_f32_e32 v46, 0xbfb8aa3b, v46
	v_exp_f32_e32 v72, v46
	v_rcp_f32_e32 v46, v27
	v_add_f32_e32 v27, 1.0, v43
	v_add_f32_e32 v43, v70, v24
	v_rcp_f32_e32 v47, v27
	v_add_f32_e32 v27, 1.0, v72
	v_mul_f32_e32 v43, 0xbfb8aa3b, v43
	v_add_f32_e32 v72, v66, v30
	v_exp_f32_e32 v43, v43
	v_mul_f32_e32 v72, 0xbfb8aa3b, v72
	v_exp_f32_e32 v74, v72
	v_rcp_f32_e32 v72, v27
	v_add_f32_e32 v27, 1.0, v43
	v_add_f32_e32 v43, v71, v25
	v_rcp_f32_e32 v73, v27
	v_add_f32_e32 v27, 1.0, v74
	v_mul_f32_e32 v43, 0xbfb8aa3b, v43
	v_add_f32_e32 v74, v67, v31
	v_exp_f32_e32 v43, v43
	v_mul_f32_e32 v74, 0xbfb8aa3b, v74
	v_exp_f32_e32 v75, v74
	v_rcp_f32_e32 v74, v27
	v_add_f32_e32 v27, 1.0, v43
	v_rcp_f32_e32 v84, v27
	v_add_f32_e32 v27, 1.0, v75
	v_rcp_f32_e32 v75, v27
	s_mov_b64 s[0:1], 0

; __device__ __forceinline__ unsigned cvt_pk_bf16(float lo, float hi) { unsigned r; asm volatile("v_cvt_pk_bf16_f32 %0, %1, %2" : "=v"(r) : "v"(lo), "v"(hi)); return r; }
; __device__ __forceinline__ float sigmoidf_(float x) { return __builtin_amdgcn_rcpf(1.0f + __expf(-x)); }
; __device__ __forceinline__ float gelu_tanh(float x) { return x * sigmoidf_(1.5957691216057308f * (x + 0.044715f * x * x * x)); }
; __device__ __forceinline__ f32x2 ln_stats(f32x2 sm) { const float mu = sm[0] * (1.f / D); const float var = fmaxf(sm[1] * (1.f / D) - mu * mu, 0.f); return (f32x2){mu, 1.0f / sqrtf(var + LN_EPS)}; }
;     __device__ __forceinline__ void operator()(const f32x4 (&acc)[2][2][4][2], const Unit& u, int wr, int wc, int fr, int fq) const {
;     ...
;                     const int r = row0 + ai * HALF + m * 16;
;                     bf16_t* rowp = Z + (size_t)r * NZ + col0;
;                     const f32x2 st = ln_stats(*(const f32x2*)(rsum + 2 * (size_t)r));
; #pragma unroll
;                     for (int bj = 0; bj < 2; ++bj) {
;                         f32x4 v0 = (acc[ai][bj][m][0] - s1[bj][0] * st[0]) * st[1] + s2[bj][0], v1 = (acc[ai][bj][m][1] - s1[bj][1] * st[0]) * st[1] + s2[bj][1];
;                         if (mode == 1) {
; #pragma unroll
;                             for (int j = 0; j < 4; ++j) { v0[j] = gelu_tanh(v0[j]); v1[j] = gelu_tanh(v1[j]); }
;                         } else if (mode == 2) {
; #pragma unroll
;                             for (int j = 0; j < 4; ++j) { v0[j] = sigmoidf_(v0[j] + gb[bj][0][j]); v1[j] = sigmoidf_(v1[j] + gb[bj][1][j]); }
;                         }
;                         u32x4 w; w.x = cvt_pk_bf16(v0[0], v0[1]); w.y = cvt_pk_bf16(v0[2], v0[3]); w.z = cvt_pk_bf16(v1[0], v1[1]); w.w = cvt_pk_bf16(v1[2], v1[3]);
;                         *(u32x4*)(rowp + bj * HALF) = w;
.LBB0_484:
	v_mov_b64_e32 v[24:25], s[40:41]
	v_mad_i64_i32 v[24:25], s[0:1], v40, s78, v[24:25]
	v_lshl_add_u64 v[24:25], v[196:197], 1, v[24:25]
	v_cvt_pk_bf16_f32 v28, v41, v47
	v_cvt_pk_bf16_f32 v29, v73, v84
	v_cvt_pk_bf16_f32 v30, v46, v72
	v_cvt_pk_bf16_f32 v31, v74, v75
	v_mov_b32_e32 v43, v42
	global_store_dwordx4 v[24:25], v[28:31], off sc1
	v_mov_b32_e32 v27, v26
	v_mov_b32_e32 v40, v26
	v_pk_fma_f32 v[28:29], v[60:61], v[42:43], v[20:21] neg_lo:[1,0,0] neg_hi:[1,0,0]
	v_mov_b32_e32 v30, v42
	v_mov_b32_e32 v31, v42
	v_pk_fma_f32 v[20:21], v[62:63], v[30:31], v[22:23]
	v_mov_b32_e32 v41, v26
	v_pk_fma_f32 v[22:23], v[28:29], v[26:27], v[56:57]
	v_pk_fma_f32 v[28:29], v[52:53], v[42:43], v[16:17] neg_lo:[1,0,0] neg_hi:[1,0,0]
	v_pk_fma_f32 v[16:17], v[54:55], v[30:31], v[18:19]
	v_pk_fma_f32 v[20:21], v[20:21], v[40:41], v[58:59]
	v_pk_fma_f32 v[16:17], v[16:17], v[40:41], v[50:51]
	v_pk_fma_f32 v[18:19], v[28:29], v[26:27], v[48:49]
	s_cmp_gt_i32 s2, 1
	s_mov_b64 s[0:1], -1
	s_cbranch_scc0 .LBB0_486
	s_waitcnt lgkmcnt(0)
	v_add_f32_e32 v40, v39, v21
	v_add_f32_e32 v26, v36, v22
	v_add_f32_e32 v27, v32, v18
	v_add_f32_e32 v28, v37, v23
	v_add_f32_e32 v29, v33, v19
	v_add_f32_e32 v30, v38, v20
	v_add_f32_e32 v31, v34, v16
	v_mul_f32_e32 v40, 0xbfb8aa3b, v40
	v_add_f32_e32 v41, v35, v17
	v_mul_f32_e32 v26, 0xbfb8aa3b, v26
	v_mul_f32_e32 v27, 0xbfb8aa3b, v27
	v_mul_f32_e32 v28, 0xbfb8aa3b, v28
	v_mul_f32_e32 v29, 0xbfb8aa3b, v29
	v_mul_f32_e32 v30, 0xbfb8aa3b, v30
	v_mul_f32_e32 v31, 0xbfb8aa3b, v31
	v_exp_f32_e32 v40, v40
	v_mul_f32_e32 v41, 0xbfb8aa3b, v41
	v_exp_f32_e32 v26, v26
	v_exp_f32_e32 v27, v27
	v_exp_f32_e32 v28, v28
	v_exp_f32_e32 v29, v29
	v_exp_f32_e32 v30, v30
	v_exp_f32_e32 v31, v31
	v_exp_f32_e32 v42, v41
	v_add_f32_e32 v40, 1.0, v40
	v_add_f32_e32 v26, 1.0, v26
	v_add_f32_e32 v27, 1.0, v27
	v_add_f32_e32 v28, 1.0, v28
	v_add_f32_e32 v29, 1.0, v29
	v_add_f32_e32 v30, 1.0, v30
	v_add_f32_e32 v31, 1.0, v31
	v_rcp_f32_e32 v41, v40
	v_add_f32_e32 v40, 1.0, v42
	v_rcp_f32_e32 v26, v26
	v_rcp_f32_e32 v27, v27
	v_rcp_f32_e32 v28, v28
	v_rcp_f32_e32 v29, v29
	v_rcp_f32_e32 v30, v30
	v_rcp_f32_e32 v31, v31
	v_rcp_f32_e32 v40, v40
	s_mov_b64 s[0:1], 0

; __device__ __forceinline__ unsigned cvt_pk_bf16(float lo, float hi) { unsigned r; asm volatile("v_cvt_pk_bf16_f32 %0, %1, %2" : "=v"(r) : "v"(lo), "v"(hi)); return r; }
; __device__ __forceinline__ float sigmoidf_(float x) { return __builtin_amdgcn_rcpf(1.0f + __expf(-x)); }
; __device__ __forceinline__ float gelu_tanh(float x) { return x * sigmoidf_(1.5957691216057308f * (x + 0.044715f * x * x * x)); }
; __device__ __forceinline__ f32x2 ln_stats(f32x2 sm) { const float mu = sm[0] * (1.f / D); const float var = fmaxf(sm[1] * (1.f / D) - mu * mu, 0.f); return (f32x2){mu, 1.0f / sqrtf(var + LN_EPS)}; }
;     __device__ __forceinline__ void operator()(const f32x4 (&acc)[2][2][4][2], const Unit& u, int wr, int wc, int fr, int fq) const {
;     ...
;                     const int r = row0 + ai * HALF + m * 16;
;                     bf16_t* rowp = Z + (size_t)r * NZ + col0;
;                     const f32x2 st = ln_stats(*(const f32x2*)(rsum + 2 * (size_t)r));
; #pragma unroll
;                     for (int bj = 0; bj < 2; ++bj) {
;                         f32x4 v0 = (acc[ai][bj][m][0] - s1[bj][0] * st[0]) * st[1] + s2[bj][0], v1 = (acc[ai][bj][m][1] - s1[bj][1] * st[0]) * st[1] + s2[bj][1];
;                         if (mode == 1) {
; #pragma unroll
;                             for (int j = 0; j < 4; ++j) { v0[j] = gelu_tanh(v0[j]); v1[j] = gelu_tanh(v1[j]); }
;                         } else if (mode == 2) {
; #pragma unroll
;                             for (int j = 0; j < 4; ++j) { v0[j] = sigmoidf_(v0[j] + gb[bj][0][j]); v1[j] = sigmoidf_(v1[j] + gb[bj][1][j]); }
;                         }
;                         u32x4 w; w.x = cvt_pk_bf16(v0[0], v0[1]); w.y = cvt_pk_bf16(v0[2], v0[3]); w.z = cvt_pk_bf16(v1[0], v1[1]); w.w = cvt_pk_bf16(v1[2], v1[3]);
;                         *(u32x4*)(rowp + bj * HALF) = w;
.LBB0_490:
	v_cvt_pk_bf16_f32 v16, v26, v28
	v_cvt_pk_bf16_f32 v17, v30, v41
	v_cvt_pk_bf16_f32 v18, v27, v29
	v_cvt_pk_bf16_f32 v19, v31, v40
	global_store_dwordx4 v[24:25], v[16:19], off offset:256 sc1
	s_cmp_gt_i32 s2, 1
	s_nop 0
	v_add_u32_e32 v16, 0xb0, v198
	v_ashrrev_i32_e32 v17, 31, v16
	v_lshl_add_u64 v[18:19], v[16:17], 3, s[54:55]
	v_mov_b32_e32 v18, v250
	v_mov_b32_e32 v19, v251
	s_nop 0
	v_pk_mul_f32 v[18:19], v[18:19], s[16:17] op_sel_hi:[1,0]
	s_nop 0
	v_fma_f32 v17, -v18, v18, v19
	v_max_f32_e32 v17, 0, v17
	v_add_f32_e32 v17, 0x3727c5ac, v17
	v_mul_f32_e32 v20, 0x4f800000, v17
	v_cmp_gt_f32_e32 vcc, s33, v17
	v_pk_fma_f32 v[14:15], v[94:95], v[18:19], v[14:15] op_sel_hi:[1,0,1]
	v_pk_fma_f32 v[12:13], v[92:93], v[18:19], v[12:13] op_sel_hi:[1,0,1] neg_lo:[1,0,0] neg_hi:[1,0,0]
	v_cndmask_b32_e32 v17, v17, v20, vcc
	v_sqrt_f32_e32 v22, v17
	v_pk_fma_f32 v[20:21], v[90:91], v[18:19], v[10:11] op_sel_hi:[1,0,1]
	v_add_u32_e32 v10, -1, v22
	v_add_u32_e32 v11, 1, v22
	v_fma_f32 v23, -v10, v22, v17
	v_fma_f32 v24, -v11, v22, v17
	v_cmp_ge_f32_e64 s[0:1], 0, v23
	s_nop 1
	v_cndmask_b32_e64 v10, v22, v10, s[0:1]
	v_cmp_lt_f32_e64 s[0:1], 0, v24
	v_pk_fma_f32 v[22:23], v[88:89], v[18:19], v[8:9] op_sel_hi:[1,0,1] neg_lo:[1,0,0] neg_hi:[1,0,0]
	s_nop 0
	v_cndmask_b32_e64 v10, v10, v11, s[0:1]
	v_mul_f32_e32 v11, 0x37800000, v10
	v_cndmask_b32_e32 v10, v10, v11, vcc
	v_cmp_class_f32_e32 vcc, v17, v214
	s_nop 1
	v_cndmask_b32_e32 v10, v10, v17, vcc
	v_div_scale_f32 v11, s[0:1], v10, v10, 1.0
	v_rcp_f32_e32 v17, v11
	v_div_scale_f32 v8, vcc, 1.0, v10, 1.0
	s_mov_b64 s[0:1], -1
	v_fma_f32 v9, -v11, v17, 1.0
	v_fmac_f32_e32 v17, v9, v17
	v_mul_f32_e32 v9, v8, v17
	v_fma_f32 v19, -v11, v9, v8
	v_fmac_f32_e32 v9, v19, v17
	v_fma_f32 v8, -v11, v9, v8
	v_div_fmas_f32 v8, v8, v17, v9
	v_div_fixup_f32 v10, v8, v10, 1.0
	v_pk_fma_f32 v[8:9], v[14:15], v[10:11], v[82:83] op_sel_hi:[1,0,1]
	v_pk_fma_f32 v[12:13], v[12:13], v[10:11], v[80:81] op_sel_hi:[1,0,1]
	v_pk_fma_f32 v[14:15], v[20:21], v[10:11], v[78:79] op_sel_hi:[1,0,1]
	v_pk_fma_f32 v[20:21], v[22:23], v[10:11], v[76:77] op_sel_hi:[1,0,1]
	s_cbranch_scc0 .LBB0_492
	s_waitcnt lgkmcnt(0)
	v_add_f32_e32 v11, v68, v12
	v_mul_f32_e32 v11, 0xbfb8aa3b, v11
	v_add_f32_e32 v17, v64, v20
	v_exp_f32_e32 v11, v11
	v_mul_f32_e32 v17, 0xbfb8aa3b, v17
	v_exp_f32_e32 v19, v17
	v_add_f32_e32 v22, v65, v21
	v_add_f32_e32 v11, 1.0, v11
	v_rcp_f32_e32 v17, v11
	v_add_f32_e32 v11, 1.0, v19
	v_add_f32_e32 v19, v69, v13
	v_mul_f32_e32 v19, 0xbfb8aa3b, v19
	v_exp_f32_e32 v19, v19
	v_mul_f32_e32 v22, 0xbfb8aa3b, v22
	v_exp_f32_e32 v24, v22
	v_rcp_f32_e32 v22, v11
	v_add_f32_e32 v11, 1.0, v19
	v_add_f32_e32 v19, v70, v8
	v_rcp_f32_e32 v23, v11
	v_add_f32_e32 v11, 1.0, v24
	v_mul_f32_e32 v19, 0xbfb8aa3b, v19
	v_add_f32_e32 v24, v66, v14
	v_exp_f32_e32 v19, v19
	v_mul_f32_e32 v24, 0xbfb8aa3b, v24
	v_exp_f32_e32 v26, v24
	v_rcp_f32_e32 v24, v11
	v_add_f32_e32 v11, 1.0, v19
	v_add_f32_e32 v19, v71, v9
	v_rcp_f32_e32 v25, v11
	v_add_f32_e32 v11, 1.0, v26
	v_mul_f32_e32 v19, 0xbfb8aa3b, v19
	v_add_f32_e32 v26, v67, v15
	v_exp_f32_e32 v19, v19
	v_mul_f32_e32 v26, 0xbfb8aa3b, v26
	v_exp_f32_e32 v27, v26
	v_rcp_f32_e32 v26, v11
	v_add_f32_e32 v11, 1.0, v19
	v_rcp_f32_e32 v28, v11
	v_add_f32_e32 v11, 1.0, v27
	v_rcp_f32_e32 v27, v11
	s_mov_b64 s[0:1], 0

; __device__ __forceinline__ unsigned cvt_pk_bf16(float lo, float hi) { unsigned r; asm volatile("v_cvt_pk_bf16_f32 %0, %1, %2" : "=v"(r) : "v"(lo), "v"(hi)); return r; }
; __device__ __forceinline__ float sigmoidf_(float x) { return __builtin_amdgcn_rcpf(1.0f + __expf(-x)); }
; __device__ __forceinline__ float gelu_tanh(float x) { return x * sigmoidf_(1.5957691216057308f * (x + 0.044715f * x * x * x)); }
; __device__ __forceinline__ f32x2 ln_stats(f32x2 sm) { const float mu = sm[0] * (1.f / D); const float var = fmaxf(sm[1] * (1.f / D) - mu * mu, 0.f); return (f32x2){mu, 1.0f / sqrtf(var + LN_EPS)}; }
;     __device__ __forceinline__ void operator()(const f32x4 (&acc)[2][2][4][2], const Unit& u, int wr, int wc, int fr, int fq) const {
;     ...
;                     const int r = row0 + ai * HALF + m * 16;
;                     bf16_t* rowp = Z + (size_t)r * NZ + col0;
;                     const f32x2 st = ln_stats(*(const f32x2*)(rsum + 2 * (size_t)r));
; #pragma unroll
;                     for (int bj = 0; bj < 2; ++bj) {
;                         f32x4 v0 = (acc[ai][bj][m][0] - s1[bj][0] * st[0]) * st[1] + s2[bj][0], v1 = (acc[ai][bj][m][1] - s1[bj][1] * st[0]) * st[1] + s2[bj][1];
;                         if (mode == 1) {
; #pragma unroll
;                             for (int j = 0; j < 4; ++j) { v0[j] = gelu_tanh(v0[j]); v1[j] = gelu_tanh(v1[j]); }
;                         } else if (mode == 2) {
; #pragma unroll
;                             for (int j = 0; j < 4; ++j) { v0[j] = sigmoidf_(v0[j] + gb[bj][0][j]); v1[j] = sigmoidf_(v1[j] + gb[bj][1][j]); }
;                         }
;                         u32x4 w; w.x = cvt_pk_bf16(v0[0], v0[1]); w.y = cvt_pk_bf16(v0[2], v0[3]); w.z = cvt_pk_bf16(v1[0], v1[1]); w.w = cvt_pk_bf16(v1[2], v1[3]);
;                         *(u32x4*)(rowp + bj * HALF) = w;
.LBB0_496:
	v_mov_b64_e32 v[8:9], s[40:41]
	v_mad_i64_i32 v[8:9], s[0:1], v16, s78, v[8:9]
	v_lshl_add_u64 v[8:9], v[196:197], 1, v[8:9]
	v_cvt_pk_bf16_f32 v12, v17, v23
	v_cvt_pk_bf16_f32 v13, v25, v28
	v_cvt_pk_bf16_f32 v14, v22, v24
	v_cvt_pk_bf16_f32 v15, v26, v27
	v_mov_b32_e32 v19, v18
	global_store_dwordx4 v[8:9], v[12:15], off sc1
	v_mov_b32_e32 v11, v10
	v_mov_b32_e32 v16, v10
	v_pk_fma_f32 v[12:13], v[60:61], v[18:19], v[4:5] neg_lo:[1,0,0] neg_hi:[1,0,0]
	v_mov_b32_e32 v14, v18
	v_mov_b32_e32 v15, v18
	v_pk_fma_f32 v[4:5], v[62:63], v[14:15], v[6:7]
	v_mov_b32_e32 v17, v10
	v_pk_fma_f32 v[6:7], v[12:13], v[10:11], v[56:57]
	v_pk_fma_f32 v[12:13], v[52:53], v[18:19], v[0:1] neg_lo:[1,0,0] neg_hi:[1,0,0]
	v_pk_fma_f32 v[0:1], v[54:55], v[14:15], v[2:3]
	v_pk_fma_f32 v[4:5], v[4:5], v[16:17], v[58:59]
	v_pk_fma_f32 v[0:1], v[0:1], v[16:17], v[50:51]
	v_pk_fma_f32 v[2:3], v[12:13], v[10:11], v[48:49]
	s_cmp_gt_i32 s2, 1
	s_mov_b64 s[0:1], -1
	s_cbranch_scc0 .LBB0_498
	s_waitcnt lgkmcnt(0)
	v_add_f32_e32 v16, v39, v5
	v_add_f32_e32 v10, v36, v6
	v_add_f32_e32 v11, v32, v2
	v_add_f32_e32 v12, v37, v7
	v_add_f32_e32 v13, v33, v3
	v_add_f32_e32 v14, v38, v4
	v_add_f32_e32 v15, v34, v0
	v_mul_f32_e32 v16, 0xbfb8aa3b, v16
	v_add_f32_e32 v17, v35, v1
	v_mul_f32_e32 v10, 0xbfb8aa3b, v10
	v_mul_f32_e32 v11, 0xbfb8aa3b, v11
	v_mul_f32_e32 v12, 0xbfb8aa3b, v12
	v_mul_f32_e32 v13, 0xbfb8aa3b, v13
	v_mul_f32_e32 v14, 0xbfb8aa3b, v14
	v_mul_f32_e32 v15, 0xbfb8aa3b, v15
	v_exp_f32_e32 v16, v16
	v_mul_f32_e32 v17, 0xbfb8aa3b, v17
	v_exp_f32_e32 v10, v10
	v_exp_f32_e32 v11, v11
	v_exp_f32_e32 v12, v12
	v_exp_f32_e32 v13, v13
	v_exp_f32_e32 v14, v14
	v_exp_f32_e32 v15, v15
	v_exp_f32_e32 v18, v17
	v_add_f32_e32 v16, 1.0, v16
	v_add_f32_e32 v10, 1.0, v10
	v_add_f32_e32 v11, 1.0, v11
	v_add_f32_e32 v12, 1.0, v12
	v_add_f32_e32 v13, 1.0, v13
	v_add_f32_e32 v14, 1.0, v14
	v_add_f32_e32 v15, 1.0, v15
	v_rcp_f32_e32 v17, v16
	v_add_f32_e32 v16, 1.0, v18
	v_rcp_f32_e32 v10, v10
	v_rcp_f32_e32 v11, v11
	v_rcp_f32_e32 v12, v12
	v_rcp_f32_e32 v13, v13
	v_rcp_f32_e32 v14, v14
	v_rcp_f32_e32 v15, v15
	v_rcp_f32_e32 v16, v16
	s_mov_b64 s[0:1], 0

; __device__ __forceinline__ unsigned cvt_pk_bf16(float lo, float hi) { unsigned r; asm volatile("v_cvt_pk_bf16_f32 %0, %1, %2" : "=v"(r) : "v"(lo), "v"(hi)); return r; }
;     __device__ __forceinline__ void operator()(const f32x4 (&acc)[2][2][4][2], const Unit& u, int wr, int wc, int fr, int fq) const {
;     ...
;                         u32x4 w; w.x = cvt_pk_bf16(v0[0], v0[1]); w.y = cvt_pk_bf16(v0[2], v0[3]); w.z = cvt_pk_bf16(v1[0], v1[1]); w.w = cvt_pk_bf16(v1[2], v1[3]);
;                         *(u32x4*)(rowp + bj * HALF) = w;
.LBB0_502:
	v_cvt_pk_bf16_f32 v0, v10, v12
	v_cvt_pk_bf16_f32 v1, v14, v17
	v_cvt_pk_bf16_f32 v2, v11, v13
	v_cvt_pk_bf16_f32 v3, v15, v16
	global_store_dwordx4 v[8:9], v[0:3], off offset:256 sc1
	s_andn2_b64 vcc, exec, s[24:25]
	s_mov_b64 s[0:1], -1
	s_cbranch_vccnz .LBB0_338

; __device__ __forceinline__ unsigned cvt_pk_bf16(float lo, float hi) { unsigned r; asm volatile("v_cvt_pk_bf16_f32 %0, %1, %2" : "=v"(r) : "v"(lo), "v"(hi)); return r; }
; __device__ __forceinline__ float bflo(unsigned w) { return __uint_as_float(w << 16); }
; __device__ __forceinline__ float bfhi(unsigned w) { return __uint_as_float(w & 0xffff0000u); }
; __global__ void __launch_bounds__(NTHREADS, 2) fwd_kernel(Params P) {
;     ...
;     if (PHON(5)) for (int r = gw; r < MR; r += NGW) {
;         const bf16_t* zr = Z + (size_t)r * NZ + 1024;
;         float v[16]; float s = 0.f;
; #pragma unroll
;         for (int h = 0; h < 2; ++h) { const u32x4 w = *(const u32x4*)(zr + 8 * lane + 512 * h);
;             v[8 * h + 0] = bflo(w.x); v[8 * h + 1] = bfhi(w.x); v[8 * h + 2] = bflo(w.y); v[8 * h + 3] = bfhi(w.y); v[8 * h + 4] = bflo(w.z); v[8 * h + 5] = bfhi(w.z); v[8 * h + 6] = bflo(w.w); v[8 * h + 7] = bfhi(w.w); }
; #pragma unroll
;         for (int j = 0; j < 16; ++j) s += v[j];
;         const float mean = wave_sum(s) * (1.f / BW); float s2 = 0.f;
; #pragma unroll
;         for (int j = 0; j < 16; ++j) { v[j] -= mean; s2 += v[j] * v[j]; }
;         const float rstd = 1.0f / sqrtf(wave_sum(s2) * (1.f / BW) + LN_EPS);
; #pragma unroll
;         for (int h = 0; h < 2; ++h) {
;             const int c0 = 8 * lane + 512 * h; float o[8];
; #pragma unroll
;             for (int j = 0; j < 8; ++j) o[j] = v[8 * h + j] * rstd * P.in[I_GLNG][c0 + j] + P.in[I_GLNB][c0 + j];
;             u32x4 w; w.x = cvt_pk_bf16(o[0], o[1]); w.y = cvt_pk_bf16(o[2], o[3]); w.z = cvt_pk_bf16(o[4], o[5]); w.w = cvt_pk_bf16(o[6], o[7]);
;             *(u32x4*)(VP + (size_t)r * BW + c0) = w;
;             if (r >= MP) { float* ov = out + O_VS + (size_t)(r - MP) * BW + c0; *(f32x4*)ov = (f32x4){o[0], o[1], o[2], o[3]}; *(f32x4*)(ov + 4) = (f32x4){o[4], o[5], o[6], o[7]}; }
.LBB0_573:
	v_lshl_add_u64 v[0:1], s[10:11], 0, v[176:177]
	v_add_co_u32_e32 v4, vcc, 0xeda0000, v0
	s_cmpk_gt_i32 s19, 0x1fff
	s_nop 0
	v_addc_co_u32_e32 v5, vcc, 0, v1, vcc
	global_load_dwordx4 v[0:3], v[4:5], off offset:3072
	s_nop 0
	global_load_dwordx4 v[4:7], v[4:5], off offset:2048
	s_cselect_b64 s[14:15], -1, 0
	s_add_i32 s4, s19, 0xffffe000
	s_lshl_b64 s[0:1], s[4:5], 12
	s_add_u32 s12, s2, s0
	s_addc_u32 s13, s3, s1
	s_cmpk_lt_i32 s19, 0x2000
	s_waitcnt vmcnt(1)
	v_lshlrev_b32_e32 v14, 16, v0
	s_waitcnt vmcnt(0)
	v_lshlrev_b32_e32 v22, 16, v4
	v_and_b32_e32 v15, 0xffff0000, v0
	v_and_b32_e32 v23, 0xffff0000, v4
	v_add_f32_e32 v0, 0, v22
	v_lshlrev_b32_e32 v4, 16, v5
	v_add_f32_e32 v0, v0, v23
	v_and_b32_e32 v5, 0xffff0000, v5
	v_add_f32_e32 v0, v0, v4
	v_lshlrev_b32_e32 v24, 16, v6
	v_add_f32_e32 v0, v0, v5
	v_and_b32_e32 v25, 0xffff0000, v6
	v_add_f32_e32 v0, v0, v24
	v_lshlrev_b32_e32 v6, 16, v7
	v_add_f32_e32 v0, v0, v25
	v_and_b32_e32 v7, 0xffff0000, v7
	v_add_f32_e32 v0, v0, v6
	v_add_f32_e32 v0, v0, v7
	v_add_f32_e32 v0, v0, v14
	v_lshlrev_b32_e32 v16, 16, v1
	v_add_f32_e32 v0, v0, v15
	v_and_b32_e32 v17, 0xffff0000, v1
	v_add_f32_e32 v0, v0, v16
	v_lshlrev_b32_e32 v18, 16, v2
	v_add_f32_e32 v0, v0, v17
	v_and_b32_e32 v19, 0xffff0000, v2
	v_add_f32_e32 v0, v0, v18
	v_lshlrev_b32_e32 v20, 16, v3
	v_add_f32_e32 v0, v0, v19
	v_and_b32_e32 v21, 0xffff0000, v3
	v_add_f32_e32 v0, v0, v20
	v_add_f32_e32 v0, v0, v21
	ds_bpermute_b32 v1, v9, v0
	s_waitcnt lgkmcnt(0)
	v_add_f32_e32 v0, v0, v1
	ds_bpermute_b32 v1, v26, v0
	s_waitcnt lgkmcnt(0)
	v_add_f32_e32 v0, v0, v1
	ds_bpermute_b32 v1, v27, v0
	s_waitcnt lgkmcnt(0)
	v_add_f32_e32 v0, v0, v1
	ds_bpermute_b32 v1, v28, v0
	s_waitcnt lgkmcnt(0)
	v_add_f32_e32 v0, v0, v1
	ds_bpermute_b32 v1, v29, v0
	s_waitcnt lgkmcnt(0)
	v_add_f32_e32 v33, v0, v1
	ds_bpermute_b32 v34, v30, v33
	v_mov_b32_e32 v0, v60
	v_mov_b32_e32 v1, v61
	v_mov_b32_e32 v2, v62
	v_mov_b32_e32 v3, v63
	s_waitcnt lgkmcnt(0)
	v_add_f32_e32 v33, v33, v34
	v_mul_f32_e32 v34, 0x3a800000, v33
	v_pk_add_f32 v[42:43], v[22:23], v[34:35] op_sel_hi:[1,0] neg_lo:[0,1] neg_hi:[0,1]
	v_pk_add_f32 v[44:45], v[4:5], v[34:35] op_sel_hi:[1,0] neg_lo:[0,1] neg_hi:[0,1]
	v_pk_mul_f32 v[4:5], v[42:43], v[42:43]
	v_pk_add_f32 v[48:49], v[6:7], v[34:35] op_sel_hi:[1,0] neg_lo:[0,1] neg_hi:[0,1]
	v_pk_mul_f32 v[6:7], v[44:45], v[44:45]
	v_add_f32_e32 v4, v4, v5
	v_pk_add_f32 v[46:47], v[24:25], v[34:35] op_sel_hi:[1,0] neg_lo:[0,1] neg_hi:[0,1]
	v_add_f32_e32 v4, v4, v6
	v_pk_mul_f32 v[22:23], v[46:47], v[46:47]
	v_add_f32_e32 v4, v4, v7
	v_add_f32_e32 v4, v4, v22
	v_pk_mul_f32 v[24:25], v[48:49], v[48:49]
	v_add_f32_e32 v4, v4, v23
	v_pk_add_f32 v[14:15], v[14:15], v[34:35] op_sel_hi:[1,0] neg_lo:[0,1] neg_hi:[0,1]
	v_add_f32_e32 v4, v4, v24
	v_pk_add_f32 v[16:17], v[16:17], v[34:35] op_sel_hi:[1,0] neg_lo:[0,1] neg_hi:[0,1]
	v_pk_add_f32 v[18:19], v[18:19], v[34:35] op_sel_hi:[1,0] neg_lo:[0,1] neg_hi:[0,1]
	v_pk_add_f32 v[20:21], v[20:21], v[34:35] op_sel_hi:[1,0] neg_lo:[0,1] neg_hi:[0,1]
	v_pk_mul_f32 v[34:35], v[14:15], v[14:15]
	v_add_f32_e32 v4, v4, v25
	v_add_f32_e32 v4, v4, v34
	v_pk_mul_f32 v[36:37], v[16:17], v[16:17]
	v_add_f32_e32 v4, v4, v35
	v_add_f32_e32 v4, v4, v36
	v_pk_mul_f32 v[38:39], v[18:19], v[18:19]
	v_add_f32_e32 v4, v4, v37
	v_add_f32_e32 v4, v4, v38
	v_pk_mul_f32 v[40:41], v[20:21], v[20:21]
	v_add_f32_e32 v4, v4, v39
	v_add_f32_e32 v4, v4, v40
	v_add_f32_e32 v22, v4, v41
	v_mov_b32_e32 v4, v64
	v_mov_b32_e32 v5, v65
	v_mov_b32_e32 v6, v66
	v_mov_b32_e32 v7, v67
	v_mov_b32_e32 v34, v68
	v_mov_b32_e32 v35, v69
	v_mov_b32_e32 v36, v70
	v_mov_b32_e32 v37, v71
	v_mov_b32_e32 v38, v72
	v_mov_b32_e32 v39, v73
	v_mov_b32_e32 v40, v74
	v_mov_b32_e32 v41, v75
	ds_bpermute_b32 v23, v9, v22
	s_waitcnt lgkmcnt(0)
	v_add_f32_e32 v22, v22, v23
	ds_bpermute_b32 v23, v26, v22
	s_waitcnt lgkmcnt(0)
	v_add_f32_e32 v22, v22, v23
	ds_bpermute_b32 v23, v27, v22
	s_waitcnt lgkmcnt(0)
	v_add_f32_e32 v22, v22, v23
	ds_bpermute_b32 v23, v28, v22
	s_waitcnt lgkmcnt(0)
	v_add_f32_e32 v22, v22, v23
	ds_bpermute_b32 v23, v29, v22
	s_waitcnt lgkmcnt(0)
	v_add_f32_e32 v24, v22, v23
	ds_bpermute_b32 v25, v30, v24
	v_lshl_add_u64 v[22:23], s[6:7], 0, v[176:177]
	s_waitcnt lgkmcnt(0)
	v_add_f32_e32 v24, v24, v25
	v_fmamk_f32 v24, v24, 0x3a800000, v31
	v_mul_f32_e32 v25, 0x4f800000, v24
	v_cmp_gt_f32_e32 vcc, s18, v24
	s_nop 1
	v_cndmask_b32_e32 v24, v24, v25, vcc
	v_sqrt_f32_e32 v25, v24
	s_nop 0
	v_add_u32_e32 v33, -1, v25
	v_add_u32_e32 v50, 1, v25
	v_fma_f32 v51, -v33, v25, v24
	v_fma_f32 v52, -v50, v25, v24
	v_cmp_ge_f32_e64 s[0:1], 0, v51
	s_nop 1
	v_cndmask_b32_e64 v25, v25, v33, s[0:1]
	v_cmp_lt_f32_e64 s[0:1], 0, v52
	s_nop 1
	v_cndmask_b32_e64 v25, v25, v50, s[0:1]
	v_mul_f32_e32 v33, 0x37800000, v25
	v_cndmask_b32_e32 v25, v25, v33, vcc
	v_cmp_class_f32_e32 vcc, v24, v32
	s_nop 1
	v_cndmask_b32_e32 v24, v25, v24, vcc
	v_div_scale_f32 v25, s[0:1], v24, v24, 1.0
	v_rcp_f32_e32 v33, v25
	v_div_scale_f32 v50, vcc, 1.0, v24, 1.0
	v_fma_f32 v51, -v25, v33, 1.0
	v_fmac_f32_e32 v33, v51, v33
	v_mul_f32_e32 v51, v50, v33
	v_fma_f32 v52, -v25, v51, v50
	v_fmac_f32_e32 v51, v52, v33
	v_fma_f32 v25, -v25, v51, v50
	v_div_fmas_f32 v25, v25, v33, v51
	v_div_fixup_f32 v24, v25, v24, 1.0
	v_add_co_u32_e32 v50, vcc, 0x22720000, v22
	v_pk_mul_f32 v[42:43], v[24:25], v[42:43] op_sel_hi:[0,1]
	v_pk_mul_f32 v[44:45], v[24:25], v[44:45] op_sel_hi:[0,1]
	v_pk_mul_f32 v[46:47], v[24:25], v[46:47] op_sel_hi:[0,1]
	v_pk_mul_f32 v[48:49], v[24:25], v[48:49] op_sel_hi:[0,1]
	v_addc_co_u32_e32 v51, vcc, 0, v23, vcc
	s_nop 0
	v_pk_fma_f32 v[4:5], v[42:43], v[4:5], v[0:1]
	v_pk_fma_f32 v[6:7], v[44:45], v[6:7], v[2:3]
	s_nop 0
	v_pk_fma_f32 v[0:1], v[46:47], v[34:35], v[38:39]
	v_pk_fma_f32 v[2:3], v[48:49], v[36:37], v[40:41]
	v_lshlrev_b32_e32 v33, 2, v8
	v_cvt_pk_bf16_f32 v34, v4, v5
	v_cvt_pk_bf16_f32 v35, v6, v7
	v_cvt_pk_bf16_f32 v36, v0, v1
	v_cvt_pk_bf16_f32 v37, v2, v3
	global_store_dwordx4 v[50:51], v[34:37], off sc1
	s_cbranch_scc1 .LBB0_575
	global_store_dwordx4 v33, v[4:7], s[12:13] sc1
	global_store_dwordx4 v33, v[0:3], s[12:13] offset:16 sc1
; __device__ __forceinline__ unsigned cvt_pk_bf16(float lo, float hi) { unsigned r; asm volatile("v_cvt_pk_bf16_f32 %0, %1, %2" : "=v"(r) : "v"(lo), "v"(hi)); return r; }
; __global__ void __launch_bounds__(NTHREADS, 2) fwd_kernel(Params P) {
;     ...
; #pragma unroll
;         for (int h = 0; h < 2; ++h) {
;             const int c0 = 8 * lane + 512 * h; float o[8];
; #pragma unroll
;             for (int j = 0; j < 8; ++j) o[j] = v[8 * h + j] * rstd * P.in[I_GLNG][c0 + j] + P.in[I_GLNB][c0 + j];
;             u32x4 w; w.x = cvt_pk_bf16(o[0], o[1]); w.y = cvt_pk_bf16(o[2], o[3]); w.z = cvt_pk_bf16(o[4], o[5]); w.w = cvt_pk_bf16(o[6], o[7]);
;             *(u32x4*)(VP + (size_t)r * BW + c0) = w;
;             if (r >= MP) { float* ov = out + O_VS + (size_t)(r - MP) * BW + c0; *(f32x4*)ov = (f32x4){o[0], o[1], o[2], o[3]}; *(f32x4*)(ov + 4) = (f32x4){o[4], o[5], o[6], o[7]}; }
.LBB0_575:
	s_nop 1
	v_mov_b32_e32 v0, v76
	v_mov_b32_e32 v1, v77
	v_mov_b32_e32 v2, v78
	v_mov_b32_e32 v3, v79
	s_nop 0
	v_mov_b32_e32 v4, v80
	v_mov_b32_e32 v5, v81
	v_mov_b32_e32 v6, v82
	v_mov_b32_e32 v7, v83
	v_mov_b32_e32 v34, v84
	v_mov_b32_e32 v35, v85
	v_mov_b32_e32 v36, v86
	v_mov_b32_e32 v37, v87
	v_mov_b32_e32 v38, v88
	v_mov_b32_e32 v39, v89
	v_mov_b32_e32 v40, v90
	v_mov_b32_e32 v41, v91
	v_mov_b32_e32 v25, v24
	v_add_co_u32_e32 v22, vcc, 0x22720000, v22
	v_pk_mul_f32 v[14:15], v[24:25], v[14:15]
	v_pk_mul_f32 v[16:17], v[24:25], v[16:17]
	v_pk_mul_f32 v[18:19], v[24:25], v[18:19]
	v_pk_mul_f32 v[20:21], v[24:25], v[20:21]
	v_addc_co_u32_e32 v23, vcc, 0, v23, vcc
	s_andn2_b64 vcc, exec, s[14:15]
	s_nop 0
	v_pk_fma_f32 v[4:5], v[14:15], v[4:5], v[0:1]
	v_pk_fma_f32 v[6:7], v[16:17], v[6:7], v[2:3]
	s_nop 0
	v_pk_fma_f32 v[0:1], v[18:19], v[34:35], v[38:39]
	v_pk_fma_f32 v[2:3], v[20:21], v[36:37], v[40:41]
	v_cvt_pk_bf16_f32 v14, v4, v5
	v_cvt_pk_bf16_f32 v15, v6, v7
	v_cvt_pk_bf16_f32 v16, v0, v1
	s_nop 0
	v_cvt_pk_bf16_f32 v17, v2, v3
	global_store_dwordx4 v[22:23], v[14:17], off offset:1024 sc1
	s_cbranch_vccnz .LBB0_572
	global_store_dwordx4 v33, v[4:7], s[12:13] offset:2048 sc1
	global_store_dwordx4 v33, v[0:3], s[12:13] offset:2064 sc1
	s_branch .LBB0_572

; #define LAS __attribute__((address_space(3)))
; __device__ __forceinline__ unsigned cvt_pk_bf16(float lo, float hi) { unsigned r; asm volatile("v_cvt_pk_bf16_f32 %0, %1, %2" : "=v"(r) : "v"(lo), "v"(hi)); return r; }
; #define ZF(i) ((f32x4){bflo(zr[i].x), bfhi(zr[i].x), bflo(zr[i].y), bfhi(zr[i].y)})
; __global__ void __launch_bounds__(NTHREADS, 2) fwd_kernel(Params P) {
;     ...
;                     for (int i = 0; i < 11; ++i) { zr[i] = (u32x2){0u, 0u}; if (i >= 3 || hist) zr[i] = *(const u32x2*)(Z + (size_t)(r0 + rs - 3 + i) * NZ + 2048 + ch); }
;     ...
; #pragma unroll
;                     for (int i = 0; i < 8; ++i) {
;                         const int row = rs + i;
;                         const f32x4 x0 = ZF(i + 3);
;                         const f32x4 xc = cb + w3 * x0 + w2 * ZF(i + 2) + w1 * ZF(i + 1) + w0 * ZF(i);
;                         *(LAS f32x4*)(XCF + row * 128 + c4) = xc;
;                         u32x2 w; w.x = cvt_pk_bf16(xc[0], xc[1]); w.y = cvt_pk_bf16(xc[2], xc[3]);
;                         *(LAS u32x2*)(XCB + row * 136 + c4) = w;
;                         if ((c & 15) == 15 && row >= 125) *(f32x4*)(out + O_CP + (size_t)((c >> 4) * 3 + (row - 125)) * BW + ch) = x0;
;                     }
.LBB0_590:
	s_or_b64 exec, exec, s[78:79]
	v_add_u32_e32 v42, s10, v146
	v_mov_b64_e32 v[30:31], s[92:93]
	v_mad_i64_i32 v[42:43], s[24:25], v42, s91, v[30:31]
	v_lshl_add_u64 v[42:43], v[42:43], 0, v[114:115]
	v_add_u32_e32 v46, 4, v29
	v_add_co_u32_e32 v42, vcc, 0xeda1000, v42
	v_mad_i64_i32 v[46:47], s[24:25], v46, s91, v[30:31]
	s_nop 0
	v_addc_co_u32_e32 v43, vcc, 0, v43, vcc
	v_lshl_add_u64 v[46:47], v[46:47], 0, v[114:115]
	v_add_u32_e32 v50, 5, v29
	v_add_co_u32_e32 v46, vcc, 0xeda1000, v46
	v_mad_i64_i32 v[50:51], s[24:25], v50, s91, v[30:31]
	s_nop 0
	v_addc_co_u32_e32 v47, vcc, 0, v47, vcc
	v_lshl_add_u64 v[50:51], v[50:51], 0, v[114:115]
	v_add_co_u32_e32 v52, vcc, 0xeda1000, v50
	v_add_u32_e32 v50, 6, v29
	s_nop 0
	v_addc_co_u32_e32 v53, vcc, 0, v51, vcc
	v_mad_i64_i32 v[50:51], s[24:25], v50, s91, v[30:31]
	v_lshl_add_u64 v[50:51], v[50:51], 0, v[114:115]
	v_add_co_u32_e32 v54, vcc, 0xeda1000, v50
	v_add_u32_e32 v56, 9, v29
	s_nop 0
	v_addc_co_u32_e32 v55, vcc, 0, v51, vcc
	global_load_dwordx2 v[62:63], v[42:43], off
	global_load_dwordx2 v[50:51], v[46:47], off
	s_nop 0
	global_load_dwordx2 v[46:47], v[52:53], off
	global_load_dwordx2 v[42:43], v[54:55], off
	v_add_u32_e32 v52, 7, v29
	v_mad_i64_i32 v[52:53], s[24:25], v52, s91, v[30:31]
	v_lshl_add_u64 v[52:53], v[52:53], 0, v[114:115]
	v_add_u32_e32 v54, 8, v29
	v_add_co_u32_e32 v52, vcc, 0xeda1000, v52
	v_mad_i64_i32 v[54:55], s[24:25], v54, s91, v[30:31]
	s_nop 0
	v_addc_co_u32_e32 v53, vcc, 0, v53, vcc
	v_lshl_add_u64 v[54:55], v[54:55], 0, v[114:115]
	v_add_co_u32_e32 v54, vcc, 0xeda1000, v54
	v_mad_i64_i32 v[56:57], s[24:25], v56, s91, v[30:31]
	s_nop 0
	v_addc_co_u32_e32 v55, vcc, 0, v55, vcc
	v_lshl_add_u64 v[56:57], v[56:57], 0, v[114:115]
	v_add_u32_e32 v29, 10, v29
	v_add_co_u32_e32 v56, vcc, 0xeda1000, v56
	v_mad_i64_i32 v[30:31], s[24:25], v29, s91, v[30:31]
	s_nop 0
	v_addc_co_u32_e32 v57, vcc, 0, v57, vcc
	v_lshl_add_u64 v[30:31], v[30:31], 0, v[114:115]
	v_add_co_u32_e32 v30, vcc, 0xeda1000, v30
	v_mov_b32_e32 v29, v115
	s_nop 0
	v_addc_co_u32_e32 v31, vcc, 0, v31, vcc
	global_load_dwordx2 v[60:61], v[52:53], off
	global_load_dwordx2 v[58:59], v[54:55], off
	s_nop 0
	global_load_dwordx2 v[56:57], v[56:57], off
	s_nop 0
	global_load_dwordx2 v[54:55], v[30:31], off
	v_lshl_add_u64 v[52:53], s[36:37], 0, v[28:29]
	s_cmp_eq_u32 s11, 15
	s_waitcnt vmcnt(8)
	v_lshlrev_b32_e32 v142, 16, v45
	v_and_b32_e32 v143, 0xffff0000, v45
	s_cselect_b64 s[24:25], -1, 0
	s_ashr_i32 s11, s3, 7
	v_and_b32_e32 v45, 0xffff0000, v48
	s_mul_i32 s11, s11, 3
	v_lshlrev_b32_e32 v206, 16, v40
	v_and_b32_e32 v207, 0xffff0000, v40
	v_lshlrev_b32_e32 v40, 16, v41
	v_and_b32_e32 v41, 0xffff0000, v41
	s_addk_i32 s11, 0xff83
	s_and_b64 s[88:89], s[24:25], s[44:45]
	s_waitcnt vmcnt(7)
	v_lshlrev_b32_e32 v28, 16, v62
	v_and_b32_e32 v29, 0xffff0000, v62
	v_lshlrev_b32_e32 v30, 16, v63
	v_and_b32_e32 v31, 0xffff0000, v63
	v_pk_fma_f32 v[144:145], v[16:17], v[28:29], v[24:25]
	v_pk_fma_f32 v[202:203], v[18:19], v[30:31], v[26:27]
	v_lshlrev_b32_e32 v62, 16, v44
	v_and_b32_e32 v63, 0xffff0000, v44
	v_pk_fma_f32 v[202:203], v[14:15], v[142:143], v[202:203]
	v_pk_fma_f32 v[204:205], v[12:13], v[62:63], v[144:145]
	v_lshlrev_b32_e32 v44, 16, v48
	v_lshlrev_b32_e32 v144, 16, v49
	v_and_b32_e32 v145, 0xffff0000, v49
	v_pk_fma_f32 v[48:49], v[8:9], v[44:45], v[204:205]
	v_pk_fma_f32 v[202:203], v[10:11], v[144:145], v[202:203]
	s_nop 0
	v_pk_fma_f32 v[204:205], v[22:23], v[40:41], v[202:203]
	v_pk_fma_f32 v[202:203], v[20:21], v[206:207], v[48:49]
	ds_write_b128 v185, v[202:205]
	v_cvt_pk_bf16_f32 v40, v202, v203
	v_cvt_pk_bf16_f32 v41, v204, v205
	ds_write_b64 v196, v[40:41]
	s_and_saveexec_b64 s[78:79], s[88:89]
	s_cbranch_execz .LBB0_592
	v_add_u32_e32 v40, s11, v146
	v_ashrrev_i32_e32 v41, 31, v40
	v_lshlrev_b64 v[40:41], 12, v[40:41]
	v_lshl_add_u64 v[40:41], v[52:53], 0, v[40:41]
	global_store_dwordx4 v[40:41], v[28:31], off sc1
.LBB0_592:
	s_or_b64 exec, exec, s[78:79]
	s_waitcnt vmcnt(6)
	v_lshlrev_b32_e32 v48, 16, v50
	v_and_b32_e32 v49, 0xffff0000, v50
	v_lshlrev_b32_e32 v50, 16, v51
	v_and_b32_e32 v51, 0xffff0000, v51
	v_pk_fma_f32 v[40:41], v[16:17], v[48:49], v[24:25]
	v_pk_fma_f32 v[202:203], v[18:19], v[50:51], v[26:27]
	v_pk_fma_f32 v[40:41], v[12:13], v[28:29], v[40:41]
	v_pk_fma_f32 v[202:203], v[14:15], v[30:31], v[202:203]
	v_pk_fma_f32 v[40:41], v[8:9], v[62:63], v[40:41]
	v_pk_fma_f32 v[202:203], v[10:11], v[142:143], v[202:203]
	s_and_b64 s[88:89], s[24:25], s[66:67]
	v_pk_fma_f32 v[204:205], v[22:23], v[144:145], v[202:203]
	v_pk_fma_f32 v[202:203], v[20:21], v[44:45], v[40:41]
	ds_write_b128 v186, v[202:205]
	v_cvt_pk_bf16_f32 v40, v202, v203
	v_cvt_pk_bf16_f32 v41, v204, v205
	ds_write_b64 v196, v[40:41] offset:272
	s_and_saveexec_b64 s[78:79], s[88:89]
	s_cbranch_execz .LBB0_594
	v_add_u32_e32 v40, s11, v151
	v_ashrrev_i32_e32 v41, 31, v40
	v_lshlrev_b64 v[40:41], 12, v[40:41]
	v_lshl_add_u64 v[40:41], v[52:53], 0, v[40:41]
	global_store_dwordx4 v[40:41], v[48:51], off sc1
.LBB0_594:
	s_or_b64 exec, exec, s[78:79]
	s_waitcnt vmcnt(5)
	v_lshlrev_b32_e32 v44, 16, v46
	v_and_b32_e32 v45, 0xffff0000, v46
	v_lshlrev_b32_e32 v46, 16, v47
	v_and_b32_e32 v47, 0xffff0000, v47
	v_pk_fma_f32 v[40:41], v[16:17], v[44:45], v[24:25]
	v_pk_fma_f32 v[144:145], v[18:19], v[46:47], v[26:27]
	v_pk_fma_f32 v[40:41], v[12:13], v[48:49], v[40:41]
	v_pk_fma_f32 v[144:145], v[14:15], v[50:51], v[144:145]
	v_pk_fma_f32 v[40:41], v[8:9], v[28:29], v[40:41]
	v_pk_fma_f32 v[144:145], v[10:11], v[30:31], v[144:145]
	s_nop 0
	v_pk_fma_f32 v[144:145], v[22:23], v[142:143], v[144:145]
	v_pk_fma_f32 v[142:143], v[20:21], v[62:63], v[40:41]
	ds_write_b128 v187, v[142:145]
	v_cvt_pk_bf16_f32 v40, v142, v143
	v_cvt_pk_bf16_f32 v41, v144, v145
	ds_write_b64 v196, v[40:41] offset:544
	s_and_saveexec_b64 s[78:79], s[88:89]
	s_cbranch_execz .LBB0_596
	v_add_u32_e32 v40, s11, v152
	v_ashrrev_i32_e32 v41, 31, v40
	v_lshlrev_b64 v[40:41], 12, v[40:41]
	v_lshl_add_u64 v[40:41], v[52:53], 0, v[40:41]
	global_store_dwordx4 v[40:41], v[44:47], off sc1
; #define LAS __attribute__((address_space(3)))
; __device__ __forceinline__ unsigned cvt_pk_bf16(float lo, float hi) { unsigned r; asm volatile("v_cvt_pk_bf16_f32 %0, %1, %2" : "=v"(r) : "v"(lo), "v"(hi)); return r; }
; #define ZF(i) ((f32x4){bflo(zr[i].x), bfhi(zr[i].x), bflo(zr[i].y), bfhi(zr[i].y)})
; __global__ void __launch_bounds__(NTHREADS, 2) fwd_kernel(Params P) {
;     ...
;                     for (int i = 0; i < 11; ++i) { zr[i] = (u32x2){0u, 0u}; if (i >= 3 || hist) zr[i] = *(const u32x2*)(Z + (size_t)(r0 + rs - 3 + i) * NZ + 2048 + ch); }
;     ...
; #pragma unroll
;                     for (int i = 0; i < 8; ++i) {
;                         const int row = rs + i;
;                         const f32x4 x0 = ZF(i + 3);
;                         const f32x4 xc = cb + w3 * x0 + w2 * ZF(i + 2) + w1 * ZF(i + 1) + w0 * ZF(i);
;                         *(LAS f32x4*)(XCF + row * 128 + c4) = xc;
;                         u32x2 w; w.x = cvt_pk_bf16(xc[0], xc[1]); w.y = cvt_pk_bf16(xc[2], xc[3]);
;                         *(LAS u32x2*)(XCB + row * 136 + c4) = w;
;                         if ((c & 15) == 15 && row >= 125) *(f32x4*)(out + O_CP + (size_t)((c >> 4) * 3 + (row - 125)) * BW + ch) = x0;
;                     }
.LBB0_596:
	s_or_b64 exec, exec, s[78:79]
	s_waitcnt vmcnt(4)
	v_lshlrev_b32_e32 v40, 16, v42
	v_and_b32_e32 v41, 0xffff0000, v42
	v_lshlrev_b32_e32 v42, 16, v43
	v_and_b32_e32 v43, 0xffff0000, v43
	v_pk_fma_f32 v[62:63], v[16:17], v[40:41], v[24:25]
	v_pk_fma_f32 v[142:143], v[18:19], v[42:43], v[26:27]
	v_pk_fma_f32 v[62:63], v[12:13], v[44:45], v[62:63]
	v_pk_fma_f32 v[142:143], v[14:15], v[46:47], v[142:143]
	v_pk_fma_f32 v[62:63], v[8:9], v[48:49], v[62:63]
	v_pk_fma_f32 v[142:143], v[10:11], v[50:51], v[142:143]
	v_pk_fma_f32 v[28:29], v[20:21], v[28:29], v[62:63]
	v_pk_fma_f32 v[30:31], v[22:23], v[30:31], v[142:143]
	s_and_b64 vcc, s[24:25], s[12:13]
	ds_write_b128 v188, v[28:31]
	v_cvt_pk_bf16_f32 v28, v28, v29
	v_cvt_pk_bf16_f32 v29, v30, v31
	ds_write_b64 v196, v[28:29] offset:816
	s_and_saveexec_b64 s[78:79], vcc
	s_cbranch_execz .LBB0_598
	v_add_u32_e32 v28, s11, v153
	v_ashrrev_i32_e32 v29, 31, v28
	v_lshlrev_b64 v[28:29], 12, v[28:29]
	v_lshl_add_u64 v[28:29], v[52:53], 0, v[28:29]
	global_store_dwordx4 v[28:29], v[40:43], off sc1
.LBB0_598:
	s_or_b64 exec, exec, s[78:79]
	s_waitcnt vmcnt(3)
	v_lshlrev_b32_e32 v28, 16, v60
	v_and_b32_e32 v29, 0xffff0000, v60
	v_lshlrev_b32_e32 v30, 16, v61
	v_and_b32_e32 v31, 0xffff0000, v61
	v_pk_fma_f32 v[60:61], v[16:17], v[28:29], v[24:25]
	v_pk_fma_f32 v[62:63], v[18:19], v[30:31], v[26:27]
	v_pk_fma_f32 v[60:61], v[12:13], v[40:41], v[60:61]
	v_pk_fma_f32 v[62:63], v[14:15], v[42:43], v[62:63]
	v_pk_fma_f32 v[60:61], v[8:9], v[44:45], v[60:61]
	v_pk_fma_f32 v[62:63], v[10:11], v[46:47], v[62:63]
	v_pk_fma_f32 v[48:49], v[20:21], v[48:49], v[60:61]
	v_pk_fma_f32 v[50:51], v[22:23], v[50:51], v[62:63]
	ds_write_b128 v189, v[48:51]
	v_cvt_pk_bf16_f32 v48, v48, v49
	v_cvt_pk_bf16_f32 v49, v50, v51
	ds_write_b64 v196, v[48:49] offset:1088
	s_and_saveexec_b64 s[78:79], s[88:89]
	s_cbranch_execz .LBB0_600
	v_add_u32_e32 v48, s11, v154
	v_ashrrev_i32_e32 v49, 31, v48
	v_lshlrev_b64 v[48:49], 12, v[48:49]
	v_lshl_add_u64 v[48:49], v[52:53], 0, v[48:49]
	global_store_dwordx4 v[48:49], v[28:31], off sc1
.LBB0_600:
	s_or_b64 exec, exec, s[78:79]
	s_waitcnt vmcnt(2)
	v_lshlrev_b32_e32 v48, 16, v58
	v_and_b32_e32 v49, 0xffff0000, v58
	v_lshlrev_b32_e32 v50, 16, v59
	v_and_b32_e32 v51, 0xffff0000, v59
	v_pk_fma_f32 v[58:59], v[16:17], v[48:49], v[24:25]
	v_pk_fma_f32 v[60:61], v[18:19], v[50:51], v[26:27]
	v_pk_fma_f32 v[58:59], v[12:13], v[28:29], v[58:59]
	v_pk_fma_f32 v[60:61], v[14:15], v[30:31], v[60:61]
	v_pk_fma_f32 v[58:59], v[8:9], v[40:41], v[58:59]
	v_pk_fma_f32 v[60:61], v[10:11], v[42:43], v[60:61]
	v_pk_fma_f32 v[44:45], v[20:21], v[44:45], v[58:59]
	v_pk_fma_f32 v[46:47], v[22:23], v[46:47], v[60:61]
	s_and_b64 s[88:89], s[24:25], s[14:15]
	ds_write_b128 v190, v[44:47]
	v_cvt_pk_bf16_f32 v44, v44, v45
	v_cvt_pk_bf16_f32 v45, v46, v47
	ds_write_b64 v196, v[44:45] offset:1360
	s_and_saveexec_b64 s[78:79], s[88:89]
	s_cbranch_execz .LBB0_602
	v_add_u32_e32 v44, s11, v155
	v_ashrrev_i32_e32 v45, 31, v44
	v_lshlrev_b64 v[44:45], 12, v[44:45]
	v_lshl_add_u64 v[44:45], v[52:53], 0, v[44:45]
	global_store_dwordx4 v[44:45], v[48:51], off sc1
.LBB0_602:
	s_or_b64 exec, exec, s[78:79]
	s_waitcnt vmcnt(1)
	v_lshlrev_b32_e32 v44, 16, v56
	v_and_b32_e32 v45, 0xffff0000, v56
	v_lshlrev_b32_e32 v46, 16, v57
	v_and_b32_e32 v47, 0xffff0000, v57
	v_pk_fma_f32 v[56:57], v[16:17], v[44:45], v[24:25]
	v_pk_fma_f32 v[58:59], v[18:19], v[46:47], v[26:27]
	v_pk_fma_f32 v[56:57], v[12:13], v[48:49], v[56:57]
	v_pk_fma_f32 v[58:59], v[14:15], v[50:51], v[58:59]
	v_pk_fma_f32 v[56:57], v[8:9], v[28:29], v[56:57]
	v_pk_fma_f32 v[58:59], v[10:11], v[30:31], v[58:59]
	v_pk_fma_f32 v[40:41], v[20:21], v[40:41], v[56:57]
	v_pk_fma_f32 v[42:43], v[22:23], v[42:43], v[58:59]
	s_and_b64 s[88:89], s[24:25], s[16:17]
	ds_write_b128 v191, v[40:43]
	v_cvt_pk_bf16_f32 v40, v40, v41
	v_cvt_pk_bf16_f32 v41, v42, v43
	ds_write_b64 v196, v[40:41] offset:1632
	s_and_saveexec_b64 s[78:79], s[88:89]
	s_cbranch_execz .LBB0_604
	v_add_u32_e32 v40, s11, v156
	v_ashrrev_i32_e32 v41, 31, v40
	v_lshlrev_b64 v[40:41], 12, v[40:41]
	v_lshl_add_u64 v[40:41], v[52:53], 0, v[40:41]
	global_store_dwordx4 v[40:41], v[44:47], off sc1
.LBB0_604:
	s_or_b64 exec, exec, s[78:79]
	s_waitcnt vmcnt(0)
	v_lshlrev_b32_e32 v40, 16, v54
	v_and_b32_e32 v41, 0xffff0000, v54
	v_lshlrev_b32_e32 v42, 16, v55
	v_and_b32_e32 v43, 0xffff0000, v55
	v_pk_fma_f32 v[54:55], v[16:17], v[40:41], v[24:25]
	v_pk_fma_f32 v[56:57], v[18:19], v[42:43], v[26:27]
	v_pk_fma_f32 v[44:45], v[12:13], v[44:45], v[54:55]
	v_pk_fma_f32 v[46:47], v[14:15], v[46:47], v[56:57]
	v_pk_fma_f32 v[44:45], v[8:9], v[48:49], v[44:45]
	v_pk_fma_f32 v[46:47], v[10:11], v[50:51], v[46:47]
	v_pk_fma_f32 v[28:29], v[20:21], v[28:29], v[44:45]
	v_pk_fma_f32 v[30:31], v[22:23], v[30:31], v[46:47]
	s_and_b64 s[78:79], s[24:25], s[18:19]
	ds_write_b128 v192, v[28:31]
	v_cvt_pk_bf16_f32 v28, v28, v29
	v_cvt_pk_bf16_f32 v29, v30, v31
	ds_write_b64 v193, v[28:29]
	s_and_saveexec_b64 s[24:25], s[78:79]
	s_cbranch_execz .LBB0_606
	v_add_u32_e32 v28, s11, v157
	v_ashrrev_i32_e32 v29, 31, v28
	v_lshlrev_b64 v[28:29], 12, v[28:29]
	v_lshl_add_u64 v[28:29], v[52:53], 0, v[28:29]
	global_store_dwordx4 v[28:29], v[40:43], off sc1

; #define LAS __attribute__((address_space(3)))
; __device__ __forceinline__ unsigned cvt_pk_bf16(float lo, float hi) { unsigned r; asm volatile("v_cvt_pk_bf16_f32 %0, %1, %2" : "=v"(r) : "v"(lo), "v"(hi)); return r; }
; __device__ __forceinline__ float bflo(unsigned w) { return __uint_as_float(w << 16); }
; __device__ __forceinline__ float bfhi(unsigned w) { return __uint_as_float(w & 0xffff0000u); }
; __global__ void __launch_bounds__(NTHREADS, 2) fwd_kernel(Params P) {
;     ...
; #pragma unroll 4
;                     for (int i = 0; i < 8; ++i) {
;                         const int row = rg * 8 + i;
;                         const float* sc = P.in[I_SCONV] + (size_t)row * 3 * BW + ch;
;                         const f32x4 b0 = *(const f32x4*)sc, b1 = *(const f32x4*)(sc + BW), b2 = *(const f32x4*)(sc + 2 * BW);
;                         const u32x2 a = *(const u32x2*)(Z + (size_t)(MP + row) * NZ + 2048 + ch);
;                         const f32x4 x0 = (f32x4){bflo(a.x), bfhi(a.x), bflo(a.y), bfhi(a.y)};
;                         const f32x4 xc = cb + w3 * x0 + w2 * b2 + w1 * b1 + w0 * b0;
;                         *(LAS f32x4*)(XCF + row * 128 + c4) = xc;
;                         u32x2 w; w.x = cvt_pk_bf16(xc[0], xc[1]); w.y = cvt_pk_bf16(xc[2], xc[3]);
;                         *(LAS u32x2*)(XCB + row * 136 + c4) = w;
;                         float* oc = out + O_CS + (size_t)row * 3 * BW + ch;
;                         *(f32x4*)oc = b1; *(f32x4*)(oc + BW) = b2; *(f32x4*)(oc + 2 * BW) = x0;
;                     }
.LBB0_609:
	v_lshl_add_u64 v[50:51], v[48:49], 0, s[24:25]
	v_add_co_u32_e32 v40, vcc, 0x1000, v50
	global_load_dwordx4 v[28:31], v[50:51], off
	s_nop 0
	v_addc_co_u32_e32 v41, vcc, 0, v51, vcc
	v_add_co_u32_e32 v52, vcc, 0x2000, v50
	global_load_dwordx4 v[40:43], v[40:41], off
	s_nop 0
	v_addc_co_u32_e32 v53, vcc, 0, v51, vcc
	global_load_dwordx4 v[58:61], v[52:53], off
	v_add_co_u32_e32 v52, vcc, 0xffff0000, v44
	s_mov_b32 s11, 0x4911000
	s_nop 0
	v_addc_co_u32_e32 v53, vcc, -1, v45, vcc
	global_load_dwordx2 v[52:53], v[52:53], off offset:-2048
	s_mov_b64 s[78:79], 0x16000
	s_waitcnt vmcnt(0)
	v_lshlrev_b32_e32 v144, 16, v53
	v_and_b32_e32 v145, 0xffff0000, v53
	v_lshlrev_b32_e32 v142, 16, v52
	v_and_b32_e32 v143, 0xffff0000, v52
	v_pk_fma_f32 v[56:57], v[18:19], v[144:145], v[26:27]
	v_pk_fma_f32 v[52:53], v[16:17], v[142:143], v[24:25]
	v_pk_fma_f32 v[56:57], v[14:15], v[60:61], v[56:57]
	v_pk_fma_f32 v[52:53], v[12:13], v[58:59], v[52:53]
	v_pk_fma_f32 v[56:57], v[10:11], v[42:43], v[56:57]
	v_pk_fma_f32 v[52:53], v[8:9], v[40:41], v[52:53]
	v_pk_fma_f32 v[30:31], v[22:23], v[30:31], v[56:57]
	v_add_u32_e32 v56, 0, v54
	v_pk_fma_f32 v[28:29], v[20:21], v[28:29], v[52:53]
	v_add_u32_e32 v52, 0x10000, v56
	ds_write_b128 v52, v[28:31]
	v_cvt_pk_bf16_f32 v28, v28, v29
	v_add_u32_e32 v57, 0, v55
	v_lshl_add_u64 v[52:53], v[46:47], 0, s[24:25]
	v_cvt_pk_bf16_f32 v29, v30, v31
	ds_write_b64 v57, v[28:29]
	v_add_co_u32_e32 v28, vcc, s11, v52
	s_mov_b32 s11, 0x4913000
	s_nop 0
	v_addc_co_u32_e32 v29, vcc, 0, v53, vcc
	v_add_co_u32_e32 v62, vcc, s11, v52
	s_movk_i32 s11, 0x4000
	s_nop 0
	v_addc_co_u32_e32 v63, vcc, 0, v53, vcc
	global_store_dwordx4 v[28:29], v[40:43], off offset:-4096 sc1
	global_store_dwordx4 v[28:29], v[58:61], off sc1
	global_store_dwordx4 v[62:63], v[142:145], off offset:-4096 sc1
	v_add_co_u32_e32 v40, vcc, s11, v50
	s_movk_i32 s11, 0x6000
	s_nop 0
	v_addc_co_u32_e32 v41, vcc, 0, v51, vcc
	v_add_co_u32_e32 v202, vcc, s11, v50
	s_mov_b32 s11, 0xffff5000
	s_nop 0
	v_addc_co_u32_e32 v203, vcc, 0, v51, vcc
	v_add_co_u32_e32 v142, vcc, s11, v44
	global_load_dwordx4 v[28:31], v[40:41], off offset:-4096
	s_nop 0
	global_load_dwordx4 v[40:43], v[40:41], off
	v_addc_co_u32_e32 v143, vcc, -1, v45, vcc
	global_load_dwordx2 v[144:145], v[142:143], off
	global_load_dwordx4 v[58:61], v[202:203], off offset:-4096
	v_add_u32_e32 v114, 0x10200, v56
	s_mov_b32 s11, 0x4915000
	s_add_u32 s24, s24, 0xc000
	s_addc_u32 s25, s25, 0
	v_add_u32_e32 v55, 0x440, v55
	v_add_u32_e32 v54, 0x800, v54
	s_cmp_eq_u32 s24, 0x18000
	s_waitcnt vmcnt(1)
	v_lshlrev_b32_e32 v142, 16, v144
	v_and_b32_e32 v143, 0xffff0000, v144
	v_lshlrev_b32_e32 v144, 16, v145
	v_and_b32_e32 v145, 0xffff0000, v145
	v_pk_fma_f32 v[204:205], v[16:17], v[142:143], v[24:25]
	v_pk_fma_f32 v[206:207], v[18:19], v[144:145], v[26:27]
	s_waitcnt vmcnt(0)
	v_pk_fma_f32 v[204:205], v[12:13], v[58:59], v[204:205]
	v_pk_fma_f32 v[206:207], v[14:15], v[60:61], v[206:207]
	v_pk_fma_f32 v[204:205], v[8:9], v[40:41], v[204:205]
	v_pk_fma_f32 v[206:207], v[10:11], v[42:43], v[206:207]
	v_pk_fma_f32 v[28:29], v[20:21], v[28:29], v[204:205]
	v_pk_fma_f32 v[30:31], v[22:23], v[30:31], v[206:207]
	ds_write_b128 v114, v[28:31]
	v_cvt_pk_bf16_f32 v28, v28, v29
	v_cvt_pk_bf16_f32 v29, v30, v31
	ds_write_b64 v57, v[28:29] offset:272
	v_add_co_u32_e32 v28, vcc, s11, v52
	global_store_dwordx4 v[62:63], v[40:43], off sc1
	s_nop 0
	v_addc_co_u32_e32 v29, vcc, 0, v53, vcc
	v_add_co_u32_e32 v40, vcc, s90, v50
	s_movk_i32 s11, 0xb000
	s_nop 0
	v_addc_co_u32_e32 v41, vcc, 0, v51, vcc
	v_add_co_u32_e32 v62, vcc, s11, v44
	global_store_dwordx4 v[28:29], v[58:61], off offset:-4096 sc1
	global_store_dwordx4 v[28:29], v[142:145], off sc1
	v_addc_co_u32_e32 v63, vcc, -1, v45, vcc
	global_load_dwordx4 v[58:61], v[202:203], off
	global_load_dwordx4 v[28:31], v[40:41], off offset:-4096
	s_nop 0
	global_load_dwordx4 v[40:43], v[40:41], off
	s_mov_b32 s11, 0x4917000
	global_load_dwordx2 v[62:63], v[62:63], off offset:-2048
	s_waitcnt vmcnt(0)
	v_lshlrev_b32_e32 v142, 16, v62
	v_and_b32_e32 v143, 0xffff0000, v62
	v_lshlrev_b32_e32 v144, 16, v63
	v_and_b32_e32 v145, 0xffff0000, v63
	v_pk_fma_f32 v[62:63], v[16:17], v[142:143], v[24:25]
	v_pk_fma_f32 v[202:203], v[18:19], v[144:145], v[26:27]
	v_pk_fma_f32 v[62:63], v[12:13], v[40:41], v[62:63]
	v_pk_fma_f32 v[202:203], v[14:15], v[42:43], v[202:203]
	v_pk_fma_f32 v[62:63], v[8:9], v[28:29], v[62:63]
	v_pk_fma_f32 v[202:203], v[10:11], v[30:31], v[202:203]
	v_pk_fma_f32 v[58:59], v[20:21], v[58:59], v[62:63]
	v_pk_fma_f32 v[60:61], v[22:23], v[60:61], v[202:203]
	v_add_u32_e32 v62, 0x10400, v56
	ds_write_b128 v62, v[58:61]
	v_cvt_pk_bf16_f32 v58, v58, v59
	v_cvt_pk_bf16_f32 v59, v60, v61
	ds_write_b64 v57, v[58:59] offset:544
	v_add_co_u32_e32 v58, vcc, s11, v52
	s_mov_b32 s11, 0x4919000
	s_nop 0
	v_addc_co_u32_e32 v59, vcc, 0, v53, vcc
	v_add_co_u32_e32 v62, vcc, s11, v52
	s_mov_b32 s11, 0xa000
	s_nop 0
	v_addc_co_u32_e32 v63, vcc, 0, v53, vcc
	global_store_dwordx4 v[58:59], v[28:31], off offset:-4096 sc1
	global_store_dwordx4 v[58:59], v[40:43], off sc1
	global_store_dwordx4 v[62:63], v[142:145], off offset:-4096 sc1
	s_nop 0
	v_add_co_u32_e32 v40, vcc, s11, v50
	s_mov_b32 s11, 0xb000
	s_nop 0
	v_addc_co_u32_e32 v41, vcc, 0, v51, vcc
	v_add_co_u32_e32 v50, vcc, s11, v50
	global_load_dwordx4 v[28:31], v[40:41], off offset:-4096
	s_nop 0
	global_load_dwordx4 v[40:43], v[40:41], off
	v_addc_co_u32_e32 v51, vcc, 0, v51, vcc
	global_load_dwordx4 v[58:61], v[50:51], off
	s_nop 0
	global_load_dwordx2 v[50:51], v[44:45], off
	s_mov_b32 s11, 0x491b000
	v_lshl_add_u64 v[44:45], v[44:45], 0, s[78:79]
	s_waitcnt vmcnt(0)
	v_lshlrev_b32_e32 v142, 16, v50
	v_and_b32_e32 v143, 0xffff0000, v50
	v_lshlrev_b32_e32 v144, 16, v51
	v_and_b32_e32 v145, 0xffff0000, v51
	v_pk_fma_f32 v[50:51], v[18:19], v[144:145], v[26:27]
	v_pk_fma_f32 v[202:203], v[16:17], v[142:143], v[24:25]
	v_pk_fma_f32 v[50:51], v[14:15], v[60:61], v[50:51]
	v_pk_fma_f32 v[202:203], v[12:13], v[58:59], v[202:203]
	v_pk_fma_f32 v[50:51], v[10:11], v[42:43], v[50:51]
	v_pk_fma_f32 v[202:203], v[8:9], v[40:41], v[202:203]
	v_pk_fma_f32 v[30:31], v[22:23], v[30:31], v[50:51]
	v_pk_fma_f32 v[28:29], v[20:21], v[28:29], v[202:203]
	v_add_u32_e32 v50, 0x10600, v56
	ds_write_b128 v50, v[28:31]
	v_cvt_pk_bf16_f32 v28, v28, v29
	v_cvt_pk_bf16_f32 v29, v30, v31
	ds_write_b64 v57, v[28:29] offset:816
	v_add_co_u32_e32 v28, vcc, s11, v52
	global_store_dwordx4 v[62:63], v[40:43], off sc1
	s_nop 0
	v_addc_co_u32_e32 v29, vcc, 0, v53, vcc
	global_store_dwordx4 v[28:29], v[58:61], off offset:-4096 sc1
	global_store_dwordx4 v[28:29], v[142:145], off sc1
	s_cbranch_scc0 .LBB0_609

; __global__ void __launch_bounds__(NTHREADS, 2) fwd_kernel(Params P) {
;     ...
;         const int c = it >> 2, rq = it & 3, n = c & 15, cb = c & ~15;
;         const int ch = 4 * (tid & 255), rhf = tid >> 8;
;         f32x4 carry = (f32x4){0.f, 0.f, 0.f, 0.f};
;         {
;             f32x4 pa[15], hh[15];
; #pragma unroll
;             for (int j = 0; j < 15; ++j) { pa[j] = (f32x4){1.f, 1.f, 1.f, 1.f}; hh[j] = (f32x4){0.f, 0.f, 0.f, 0.f};
;                 if (j < n) { pa[j] = *(const f32x4*)(SUM + (size_t)((cb + j) * 2 + 0) * BW + ch); hh[j] = *(const f32x4*)(SUM + (size_t)((cb + j) * 2 + 1) * BW + ch); } }
; #pragma unroll
;             for (int j = 0; j < 15; ++j) carry = pa[j] * carry + hh[j];
;         }
;         const int rbase = c * 128 + rq * 32 + rhf * 16;
;         u32x2 v1[16], v2[16];
; #pragma unroll
;         for (int i = 0; i < 16; ++i) { v1[i] = *(const u32x2*)(U1 + (size_t)(rbase + i) * BW + ch); v2[i] = *(const u32x2*)(U2 + (size_t)(rbase + i) * BW + ch); }
.LBB0_726:
	s_and_b32 s8, s6, 3
	s_lshl_b32 s9, s7, 7
	s_lshl_b32 s10, s8, 5
	s_or_b32 s9, s9, s10
	v_add_u32_e32 v224, s9, v181
	v_ashrrev_i32_e32 v225, 31, v224
	v_or_b32_e32 v218, 1, v224
	v_lshlrev_b64 v[130:131], 11, v[224:225]
	v_ashrrev_i32_e32 v219, 31, v218
	v_lshl_add_u64 v[132:133], v[120:121], 0, v[130:131]
	v_lshlrev_b64 v[134:135], 11, v[218:219]
	v_lshl_add_u64 v[130:131], v[122:123], 0, v[130:131]
	v_lshl_add_u64 v[136:137], v[120:121], 0, v[134:135]
	v_lshl_add_u64 v[134:135], v[122:123], 0, v[134:135]
	global_load_dwordx2 v[232:233], v[132:133], off
	global_load_dwordx2 v[230:231], v[130:131], off
	global_load_dwordx2 v[228:229], v[136:137], off
	global_load_dwordx2 v[226:227], v[134:135], off
	v_or_b32_e32 v212, 2, v224
	v_ashrrev_i32_e32 v213, 31, v212
	v_or_b32_e32 v206, 3, v224
	v_lshlrev_b64 v[130:131], 11, v[212:213]
	v_ashrrev_i32_e32 v207, 31, v206
	v_lshl_add_u64 v[132:133], v[120:121], 0, v[130:131]
	v_lshlrev_b64 v[134:135], 11, v[206:207]
	v_lshl_add_u64 v[130:131], v[122:123], 0, v[130:131]
	v_lshl_add_u64 v[136:137], v[120:121], 0, v[134:135]
	v_lshl_add_u64 v[134:135], v[122:123], 0, v[134:135]
	global_load_dwordx2 v[222:223], v[132:133], off
	global_load_dwordx2 v[220:221], v[130:131], off
	global_load_dwordx2 v[216:217], v[136:137], off
	global_load_dwordx2 v[214:215], v[134:135], off
	v_or_b32_e32 v200, 4, v224
	v_ashrrev_i32_e32 v201, 31, v200
	v_or_b32_e32 v194, 5, v224
	v_lshlrev_b64 v[130:131], 11, v[200:201]
	v_ashrrev_i32_e32 v195, 31, v194
	v_lshl_add_u64 v[132:133], v[120:121], 0, v[130:131]
	v_lshlrev_b64 v[134:135], 11, v[194:195]
	v_lshl_add_u64 v[130:131], v[122:123], 0, v[130:131]
	v_lshl_add_u64 v[136:137], v[120:121], 0, v[134:135]
	v_lshl_add_u64 v[134:135], v[122:123], 0, v[134:135]
	global_load_dwordx2 v[210:211], v[132:133], off
	global_load_dwordx2 v[208:209], v[130:131], off
	global_load_dwordx2 v[204:205], v[136:137], off
	global_load_dwordx2 v[202:203], v[134:135], off
	v_or_b32_e32 v188, 6, v224
	v_ashrrev_i32_e32 v189, 31, v188
	v_or_b32_e32 v174, 7, v224
	v_lshlrev_b64 v[130:131], 11, v[188:189]
	v_ashrrev_i32_e32 v175, 31, v174
	v_lshl_add_u64 v[132:133], v[120:121], 0, v[130:131]
	v_lshlrev_b64 v[134:135], 11, v[174:175]
	v_lshl_add_u64 v[130:131], v[122:123], 0, v[130:131]
	v_lshl_add_u64 v[136:137], v[120:121], 0, v[134:135]
	v_lshl_add_u64 v[134:135], v[122:123], 0, v[134:135]
	global_load_dwordx2 v[198:199], v[132:133], off
	global_load_dwordx2 v[196:197], v[130:131], off
	global_load_dwordx2 v[192:193], v[136:137], off
	global_load_dwordx2 v[190:191], v[134:135], off
	v_or_b32_e32 v168, 8, v224
	v_ashrrev_i32_e32 v169, 31, v168
	v_or_b32_e32 v162, 9, v224
	v_lshlrev_b64 v[130:131], 11, v[168:169]
	v_ashrrev_i32_e32 v163, 31, v162
	v_lshl_add_u64 v[132:133], v[120:121], 0, v[130:131]
	v_lshlrev_b64 v[134:135], 11, v[162:163]
	v_lshl_add_u64 v[130:131], v[122:123], 0, v[130:131]
	v_lshl_add_u64 v[136:137], v[120:121], 0, v[134:135]
	v_lshl_add_u64 v[134:135], v[122:123], 0, v[134:135]
	global_load_dwordx2 v[186:187], v[132:133], off
	global_load_dwordx2 v[184:185], v[130:131], off
	global_load_dwordx2 v[172:173], v[136:137], off
	global_load_dwordx2 v[170:171], v[134:135], off
	v_or_b32_e32 v156, 10, v224
	v_ashrrev_i32_e32 v157, 31, v156
	v_or_b32_e32 v150, 11, v224
	v_lshlrev_b64 v[130:131], 11, v[156:157]
	v_ashrrev_i32_e32 v151, 31, v150
	v_lshl_add_u64 v[132:133], v[120:121], 0, v[130:131]
	v_lshlrev_b64 v[134:135], 11, v[150:151]
	v_lshl_add_u64 v[130:131], v[122:123], 0, v[130:131]
	v_lshl_add_u64 v[136:137], v[120:121], 0, v[134:135]
	v_lshl_add_u64 v[134:135], v[122:123], 0, v[134:135]
	global_load_dwordx2 v[166:167], v[132:133], off
	global_load_dwordx2 v[164:165], v[130:131], off
	global_load_dwordx2 v[160:161], v[136:137], off
	global_load_dwordx2 v[158:159], v[134:135], off
	s_waitcnt vmcnt(24)
	v_pk_add_f32 v[0:1], v[126:127], v[0:1]
	v_pk_add_f32 v[2:3], v[128:129], v[2:3]
	v_pk_fma_f32 v[0:1], v[0:1], v[12:13], v[16:17]
	v_pk_fma_f32 v[2:3], v[2:3], v[14:15], v[18:19]
	v_pk_fma_f32 v[0:1], v[0:1], v[4:5], v[8:9]
	v_pk_fma_f32 v[2:3], v[2:3], v[6:7], v[10:11]
	v_pk_fma_f32 v[0:1], v[0:1], v[28:29], v[32:33]
	v_pk_fma_f32 v[2:3], v[2:3], v[30:31], v[34:35]
	v_pk_fma_f32 v[0:1], v[0:1], v[20:21], v[24:25]
	v_or_b32_e32 v144, 12, v224
	v_pk_fma_f32 v[2:3], v[2:3], v[22:23], v[26:27]
	v_pk_fma_f32 v[0:1], v[0:1], v[44:45], v[48:49]
	v_ashrrev_i32_e32 v145, 31, v144
	v_or_b32_e32 v138, 13, v224
	v_pk_fma_f32 v[2:3], v[2:3], v[46:47], v[50:51]
	v_pk_fma_f32 v[0:1], v[0:1], v[36:37], v[40:41]
	v_lshlrev_b64 v[130:131], 11, v[144:145]
	v_ashrrev_i32_e32 v139, 31, v138
	v_pk_fma_f32 v[2:3], v[2:3], v[38:39], v[42:43]
	v_pk_fma_f32 v[0:1], v[0:1], v[60:61], v[64:65]
	v_lshl_add_u64 v[132:133], v[120:121], 0, v[130:131]
	v_lshlrev_b64 v[134:135], 11, v[138:139]
	v_pk_fma_f32 v[2:3], v[2:3], v[62:63], v[66:67]
	v_pk_fma_f32 v[0:1], v[0:1], v[52:53], v[56:57]
	v_lshl_add_u64 v[130:131], v[122:123], 0, v[130:131]
	v_lshl_add_u64 v[136:137], v[120:121], 0, v[134:135]
	v_lshl_add_u64 v[134:135], v[122:123], 0, v[134:135]
	global_load_dwordx2 v[154:155], v[132:133], off
	global_load_dwordx2 v[152:153], v[130:131], off
	global_load_dwordx2 v[148:149], v[136:137], off
	global_load_dwordx2 v[146:147], v[134:135], off
	v_pk_fma_f32 v[2:3], v[2:3], v[54:55], v[58:59]
	v_pk_fma_f32 v[0:1], v[0:1], v[76:77], v[80:81]
	v_or_b32_e32 v132, 14, v224
	v_pk_fma_f32 v[2:3], v[2:3], v[78:79], v[82:83]
	v_pk_fma_f32 v[0:1], v[0:1], v[68:69], v[72:73]
	v_ashrrev_i32_e32 v133, 31, v132
	v_pk_fma_f32 v[2:3], v[2:3], v[70:71], v[74:75]
	v_pk_fma_f32 v[0:1], v[0:1], v[92:93], v[96:97]
	v_lshlrev_b64 v[130:131], 11, v[132:133]
	v_pk_fma_f32 v[2:3], v[2:3], v[94:95], v[98:99]
	v_pk_fma_f32 v[0:1], v[0:1], v[84:85], v[88:89]
	v_lshl_add_u64 v[134:135], v[120:121], 0, v[130:131]
	v_lshl_add_u64 v[136:137], v[122:123], 0, v[130:131]
	v_or_b32_e32 v130, 15, v224
	v_pk_fma_f32 v[2:3], v[2:3], v[86:87], v[90:91]
	v_pk_fma_f32 v[4:5], v[0:1], v[108:109], v[112:113]
	v_ashrrev_i32_e32 v131, 31, v130
	v_pk_fma_f32 v[0:1], v[2:3], v[110:111], v[114:115]
	v_pk_fma_f32 v[2:3], v[4:5], v[100:101], v[104:105]
	s_waitcnt vmcnt(27)
; __device__ __forceinline__ unsigned cvt_pk_bf16(float lo, float hi) { unsigned r; asm volatile("v_cvt_pk_bf16_f32 %0, %1, %2" : "=v"(r) : "v"(lo), "v"(hi)); return r; }
; __device__ __forceinline__ float bflo(unsigned w) { return __uint_as_float(w << 16); }
; __device__ __forceinline__ float bfhi(unsigned w) { return __uint_as_float(w & 0xffff0000u); }
; __global__ void __launch_bounds__(NTHREADS, 2) fwd_kernel(Params P) {
;     ...
; #pragma unroll
;         for (int i = 0; i < 16; ++i) {
;             const f32x4 a1 = (f32x4){bflo(v1[i].x), bfhi(v1[i].x), bflo(v1[i].y), bfhi(v1[i].y)}, a2 = (f32x4){bflo(v2[i].x), bfhi(v2[i].x), bflo(v2[i].y), bfhi(v2[i].y)};
;             const f32x4 y = a1 + a2 * carry;
;             u32x2 w; w.x = cvt_pk_bf16(y[0], y[1]); w.y = cvt_pk_bf16(y[2], y[3]);
;             *(u32x2*)(YS + (size_t)(rbase + i) * 3072 + 1024 + ch) = w;
;         }
	v_lshlrev_b32_e32 v4, 16, v232
	v_and_b32_e32 v5, 0xffff0000, v232
	s_waitcnt vmcnt(26)
	v_lshlrev_b32_e32 v8, 16, v230
	v_and_b32_e32 v9, 0xffff0000, v230
	v_lshlrev_b64 v[140:141], 11, v[130:131]
	v_pk_fma_f32 v[0:1], v[0:1], v[102:103], v[106:107]
	v_lshlrev_b32_e32 v6, 16, v233
	v_and_b32_e32 v7, 0xffff0000, v233
	v_lshlrev_b32_e32 v10, 16, v231
	v_and_b32_e32 v11, 0xffff0000, v231
	v_pk_fma_f32 v[4:5], v[2:3], v[8:9], v[4:5]
	v_lshl_add_u64 v[238:239], v[120:121], 0, v[140:141]
	v_lshl_add_u64 v[240:241], v[122:123], 0, v[140:141]
	global_load_dwordx2 v[142:143], v[134:135], off
	global_load_dwordx2 v[140:141], v[136:137], off
	s_nop 0
	global_load_dwordx2 v[136:137], v[238:239], off
	global_load_dwordx2 v[134:135], v[240:241], off
	v_pk_fma_f32 v[6:7], v[0:1], v[10:11], v[6:7]
	v_cvt_pk_bf16_f32 v8, v4, v5
	v_mov_b64_e32 v[4:5], s[92:93]
	v_cvt_pk_bf16_f32 v9, v6, v7
	v_mad_i64_i32 v[6:7], s[10:11], v224, s2, v[4:5]
	v_lshl_add_u64 v[6:7], v[6:7], 0, v[116:117]
	v_add_co_u32_e32 v6, vcc, s3, v6
	s_waitcnt vmcnt(28)
	v_lshlrev_b32_e32 v10, 16, v226
	v_addc_co_u32_e32 v7, vcc, 0, v7, vcc
	global_store_dwordx2 v[6:7], v[8:9], off offset:2048
	v_lshlrev_b32_e32 v6, 16, v228
	v_and_b32_e32 v7, 0xffff0000, v228
	v_lshlrev_b32_e32 v8, 16, v229
	v_and_b32_e32 v9, 0xffff0000, v229
	v_and_b32_e32 v11, 0xffff0000, v226
	v_lshlrev_b32_e32 v12, 16, v227
	v_and_b32_e32 v13, 0xffff0000, v227
	v_pk_fma_f32 v[8:9], v[0:1], v[12:13], v[8:9]
	v_pk_fma_f32 v[6:7], v[2:3], v[10:11], v[6:7]
	s_waitcnt vmcnt(27)
	v_lshlrev_b32_e32 v10, 16, v220
	v_cvt_pk_bf16_f32 v6, v6, v7
	v_cvt_pk_bf16_f32 v7, v8, v9
	v_mad_i64_i32 v[8:9], s[10:11], v218, s2, v[4:5]
	v_lshl_add_u64 v[8:9], v[8:9], 0, v[116:117]
	v_add_co_u32_e32 v8, vcc, s3, v8
	v_and_b32_e32 v11, 0xffff0000, v220
	s_nop 0
	v_addc_co_u32_e32 v9, vcc, 0, v9, vcc
	global_store_dwordx2 v[8:9], v[6:7], off offset:2048
	v_lshlrev_b32_e32 v6, 16, v222
	v_and_b32_e32 v7, 0xffff0000, v222
	v_lshlrev_b32_e32 v8, 16, v223
	v_and_b32_e32 v9, 0xffff0000, v223
	v_lshlrev_b32_e32 v12, 16, v221
	v_and_b32_e32 v13, 0xffff0000, v221
	v_pk_fma_f32 v[8:9], v[0:1], v[12:13], v[8:9]
	v_pk_fma_f32 v[6:7], v[2:3], v[10:11], v[6:7]
	s_waitcnt vmcnt(26)
	v_lshlrev_b32_e32 v10, 16, v214
	v_cvt_pk_bf16_f32 v6, v6, v7
	v_cvt_pk_bf16_f32 v7, v8, v9
	v_mad_i64_i32 v[8:9], s[10:11], v212, s2, v[4:5]
	v_lshl_add_u64 v[8:9], v[8:9], 0, v[116:117]
	v_add_co_u32_e32 v8, vcc, s3, v8
	v_and_b32_e32 v11, 0xffff0000, v214
	s_nop 0
	v_addc_co_u32_e32 v9, vcc, 0, v9, vcc
	global_store_dwordx2 v[8:9], v[6:7], off offset:2048
	v_lshlrev_b32_e32 v6, 16, v216
	v_and_b32_e32 v7, 0xffff0000, v216
	v_lshlrev_b32_e32 v8, 16, v217
	v_and_b32_e32 v9, 0xffff0000, v217
	v_lshlrev_b32_e32 v12, 16, v215
	v_and_b32_e32 v13, 0xffff0000, v215
	v_pk_fma_f32 v[8:9], v[0:1], v[12:13], v[8:9]
	v_pk_fma_f32 v[6:7], v[2:3], v[10:11], v[6:7]
	s_waitcnt vmcnt(25)
	v_lshlrev_b32_e32 v10, 16, v208
	v_cvt_pk_bf16_f32 v6, v6, v7
	v_cvt_pk_bf16_f32 v7, v8, v9
	v_mad_i64_i32 v[8:9], s[10:11], v206, s2, v[4:5]
	v_lshl_add_u64 v[8:9], v[8:9], 0, v[116:117]
	v_add_co_u32_e32 v8, vcc, s3, v8
	v_and_b32_e32 v11, 0xffff0000, v208
	s_nop 0
	v_addc_co_u32_e32 v9, vcc, 0, v9, vcc
	global_store_dwordx2 v[8:9], v[6:7], off offset:2048
	v_lshlrev_b32_e32 v6, 16, v210
	v_and_b32_e32 v7, 0xffff0000, v210
	v_lshlrev_b32_e32 v8, 16, v211
	v_and_b32_e32 v9, 0xffff0000, v211
	v_lshlrev_b32_e32 v12, 16, v209
	v_and_b32_e32 v13, 0xffff0000, v209
	v_pk_fma_f32 v[8:9], v[0:1], v[12:13], v[8:9]
	v_pk_fma_f32 v[6:7], v[2:3], v[10:11], v[6:7]
	s_waitcnt vmcnt(24)
	v_lshlrev_b32_e32 v10, 16, v202
	v_cvt_pk_bf16_f32 v6, v6, v7
	v_cvt_pk_bf16_f32 v7, v8, v9
	v_mad_i64_i32 v[8:9], s[10:11], v200, s2, v[4:5]
	v_lshl_add_u64 v[8:9], v[8:9], 0, v[116:117]
	v_add_co_u32_e32 v8, vcc, s3, v8
	v_and_b32_e32 v11, 0xffff0000, v202
	s_nop 0
	v_addc_co_u32_e32 v9, vcc, 0, v9, vcc
	global_store_dwordx2 v[8:9], v[6:7], off offset:2048
	v_lshlrev_b32_e32 v6, 16, v204
	v_and_b32_e32 v7, 0xffff0000, v204
	v_lshlrev_b32_e32 v8, 16, v205
	v_and_b32_e32 v9, 0xffff0000, v205
	v_lshlrev_b32_e32 v12, 16, v203
	v_and_b32_e32 v13, 0xffff0000, v203
	v_pk_fma_f32 v[8:9], v[0:1], v[12:13], v[8:9]
	v_pk_fma_f32 v[6:7], v[2:3], v[10:11], v[6:7]
	s_waitcnt vmcnt(23)
	v_lshlrev_b32_e32 v10, 16, v196
	v_cvt_pk_bf16_f32 v6, v6, v7
	v_cvt_pk_bf16_f32 v7, v8, v9
	v_mad_i64_i32 v[8:9], s[10:11], v194, s2, v[4:5]
	v_lshl_add_u64 v[8:9], v[8:9], 0, v[116:117]
	v_add_co_u32_e32 v8, vcc, s3, v8
	v_and_b32_e32 v11, 0xffff0000, v196
	s_nop 0
	v_addc_co_u32_e32 v9, vcc, 0, v9, vcc
	global_store_dwordx2 v[8:9], v[6:7], off offset:2048
	v_lshlrev_b32_e32 v6, 16, v198
	v_and_b32_e32 v7, 0xffff0000, v198
	v_lshlrev_b32_e32 v8, 16, v199
	v_and_b32_e32 v9, 0xffff0000, v199
	v_lshlrev_b32_e32 v12, 16, v197
	v_and_b32_e32 v13, 0xffff0000, v197
	v_pk_fma_f32 v[8:9], v[0:1], v[12:13], v[8:9]
	v_pk_fma_f32 v[6:7], v[2:3], v[10:11], v[6:7]
	s_waitcnt vmcnt(22)
	v_lshlrev_b32_e32 v10, 16, v190
	v_cvt_pk_bf16_f32 v6, v6, v7
	v_cvt_pk_bf16_f32 v7, v8, v9
	v_mad_i64_i32 v[8:9], s[10:11], v188, s2, v[4:5]
	v_lshl_add_u64 v[8:9], v[8:9], 0, v[116:117]
	v_add_co_u32_e32 v8, vcc, s3, v8
	v_and_b32_e32 v11, 0xffff0000, v190
	s_nop 0
	v_addc_co_u32_e32 v9, vcc, 0, v9, vcc
	global_store_dwordx2 v[8:9], v[6:7], off offset:2048
	v_lshlrev_b32_e32 v6, 16, v192
	v_and_b32_e32 v7, 0xffff0000, v192
	v_lshlrev_b32_e32 v8, 16, v193
	v_and_b32_e32 v9, 0xffff0000, v193
	v_lshlrev_b32_e32 v12, 16, v191
	v_and_b32_e32 v13, 0xffff0000, v191
	v_pk_fma_f32 v[8:9], v[0:1], v[12:13], v[8:9]
	v_pk_fma_f32 v[6:7], v[2:3], v[10:11], v[6:7]
	s_waitcnt vmcnt(21)
; __device__ __forceinline__ unsigned cvt_pk_bf16(float lo, float hi) { unsigned r; asm volatile("v_cvt_pk_bf16_f32 %0, %1, %2" : "=v"(r) : "v"(lo), "v"(hi)); return r; }
; __device__ __forceinline__ float bflo(unsigned w) { return __uint_as_float(w << 16); }
; __device__ __forceinline__ float bfhi(unsigned w) { return __uint_as_float(w & 0xffff0000u); }
; __global__ void __launch_bounds__(NTHREADS, 2) fwd_kernel(Params P) {
;     ...
; #pragma unroll
;         for (int i = 0; i < 16; ++i) {
;             const f32x4 a1 = (f32x4){bflo(v1[i].x), bfhi(v1[i].x), bflo(v1[i].y), bfhi(v1[i].y)}, a2 = (f32x4){bflo(v2[i].x), bfhi(v2[i].x), bflo(v2[i].y), bfhi(v2[i].y)};
;             const f32x4 y = a1 + a2 * carry;
;             u32x2 w; w.x = cvt_pk_bf16(y[0], y[1]); w.y = cvt_pk_bf16(y[2], y[3]);
;             *(u32x2*)(YS + (size_t)(rbase + i) * 3072 + 1024 + ch) = w;
;         }
;         if (n == 15 && rq == 3 && rhf == 1) {
;             const f32x4 pe = *(const f32x4*)(SUM + (size_t)(c * 2 + 0) * BW + ch), he = *(const f32x4*)(SUM + (size_t)(c * 2 + 1) * BW + ch);
;             *(f32x4*)(out + O_HP + (size_t)(c >> 4) * BW + ch) = he + pe * carry;
;         }
	v_lshlrev_b32_e32 v10, 16, v184
	v_cvt_pk_bf16_f32 v6, v6, v7
	v_cvt_pk_bf16_f32 v7, v8, v9
	v_mad_i64_i32 v[8:9], s[10:11], v174, s2, v[4:5]
	v_lshl_add_u64 v[8:9], v[8:9], 0, v[116:117]
	v_add_co_u32_e32 v8, vcc, s3, v8
	v_and_b32_e32 v11, 0xffff0000, v184
	s_nop 0
	v_addc_co_u32_e32 v9, vcc, 0, v9, vcc
	global_store_dwordx2 v[8:9], v[6:7], off offset:2048
	v_lshlrev_b32_e32 v6, 16, v186
	v_and_b32_e32 v7, 0xffff0000, v186
	v_lshlrev_b32_e32 v8, 16, v187
	v_and_b32_e32 v9, 0xffff0000, v187
	v_lshlrev_b32_e32 v12, 16, v185
	v_and_b32_e32 v13, 0xffff0000, v185
	v_pk_fma_f32 v[8:9], v[0:1], v[12:13], v[8:9]
	v_pk_fma_f32 v[6:7], v[2:3], v[10:11], v[6:7]
	s_waitcnt vmcnt(20)
	v_lshlrev_b32_e32 v10, 16, v170
	v_cvt_pk_bf16_f32 v6, v6, v7
	v_cvt_pk_bf16_f32 v7, v8, v9
	v_mad_i64_i32 v[8:9], s[10:11], v168, s2, v[4:5]
	v_lshl_add_u64 v[8:9], v[8:9], 0, v[116:117]
	v_add_co_u32_e32 v8, vcc, s3, v8
	v_and_b32_e32 v11, 0xffff0000, v170
	s_nop 0
	v_addc_co_u32_e32 v9, vcc, 0, v9, vcc
	global_store_dwordx2 v[8:9], v[6:7], off offset:2048
	v_lshlrev_b32_e32 v6, 16, v172
	v_and_b32_e32 v7, 0xffff0000, v172
	v_lshlrev_b32_e32 v8, 16, v173
	v_and_b32_e32 v9, 0xffff0000, v173
	v_lshlrev_b32_e32 v12, 16, v171
	v_and_b32_e32 v13, 0xffff0000, v171
	v_pk_fma_f32 v[8:9], v[0:1], v[12:13], v[8:9]
	v_pk_fma_f32 v[6:7], v[2:3], v[10:11], v[6:7]
	s_waitcnt vmcnt(19)
	v_lshlrev_b32_e32 v10, 16, v164
	v_cvt_pk_bf16_f32 v6, v6, v7
	v_cvt_pk_bf16_f32 v7, v8, v9
	v_mad_i64_i32 v[8:9], s[10:11], v162, s2, v[4:5]
	v_lshl_add_u64 v[8:9], v[8:9], 0, v[116:117]
	v_add_co_u32_e32 v8, vcc, s3, v8
	v_and_b32_e32 v11, 0xffff0000, v164
	s_nop 0
	v_addc_co_u32_e32 v9, vcc, 0, v9, vcc
	global_store_dwordx2 v[8:9], v[6:7], off offset:2048
	v_lshlrev_b32_e32 v6, 16, v166
	v_and_b32_e32 v7, 0xffff0000, v166
	v_lshlrev_b32_e32 v8, 16, v167
	v_and_b32_e32 v9, 0xffff0000, v167
	v_lshlrev_b32_e32 v12, 16, v165
	v_and_b32_e32 v13, 0xffff0000, v165
	v_pk_fma_f32 v[8:9], v[0:1], v[12:13], v[8:9]
	v_pk_fma_f32 v[6:7], v[2:3], v[10:11], v[6:7]
	s_waitcnt vmcnt(18)
	v_lshlrev_b32_e32 v10, 16, v158
	v_cvt_pk_bf16_f32 v6, v6, v7
	v_cvt_pk_bf16_f32 v7, v8, v9
	v_mad_i64_i32 v[8:9], s[10:11], v156, s2, v[4:5]
	v_lshl_add_u64 v[8:9], v[8:9], 0, v[116:117]
	v_add_co_u32_e32 v8, vcc, s3, v8
	v_and_b32_e32 v11, 0xffff0000, v158
	s_nop 0
	v_addc_co_u32_e32 v9, vcc, 0, v9, vcc
	global_store_dwordx2 v[8:9], v[6:7], off offset:2048
	v_lshlrev_b32_e32 v6, 16, v160
	v_and_b32_e32 v7, 0xffff0000, v160
	v_lshlrev_b32_e32 v8, 16, v161
	v_and_b32_e32 v9, 0xffff0000, v161
	v_lshlrev_b32_e32 v12, 16, v159
	v_and_b32_e32 v13, 0xffff0000, v159
	v_pk_fma_f32 v[8:9], v[0:1], v[12:13], v[8:9]
	v_pk_fma_f32 v[6:7], v[2:3], v[10:11], v[6:7]
	s_waitcnt vmcnt(17)
	v_lshlrev_b32_e32 v10, 16, v152
	v_cvt_pk_bf16_f32 v6, v6, v7
	v_cvt_pk_bf16_f32 v7, v8, v9
	v_mad_i64_i32 v[8:9], s[10:11], v150, s2, v[4:5]
	v_lshl_add_u64 v[8:9], v[8:9], 0, v[116:117]
	v_add_co_u32_e32 v8, vcc, s3, v8
	v_and_b32_e32 v11, 0xffff0000, v152
	s_nop 0
	v_addc_co_u32_e32 v9, vcc, 0, v9, vcc
	global_store_dwordx2 v[8:9], v[6:7], off offset:2048
	v_lshlrev_b32_e32 v6, 16, v154
	v_and_b32_e32 v7, 0xffff0000, v154
	v_lshlrev_b32_e32 v8, 16, v155
	v_and_b32_e32 v9, 0xffff0000, v155
	v_lshlrev_b32_e32 v12, 16, v153
	v_and_b32_e32 v13, 0xffff0000, v153
	v_pk_fma_f32 v[8:9], v[0:1], v[12:13], v[8:9]
	v_pk_fma_f32 v[6:7], v[2:3], v[10:11], v[6:7]
	s_waitcnt vmcnt(16)
	v_lshlrev_b32_e32 v10, 16, v146
	v_cvt_pk_bf16_f32 v6, v6, v7
	v_cvt_pk_bf16_f32 v7, v8, v9
	v_mad_i64_i32 v[8:9], s[10:11], v144, s2, v[4:5]
	v_lshl_add_u64 v[8:9], v[8:9], 0, v[116:117]
	v_add_co_u32_e32 v8, vcc, s3, v8
	v_and_b32_e32 v11, 0xffff0000, v146
	s_nop 0
	v_addc_co_u32_e32 v9, vcc, 0, v9, vcc
	global_store_dwordx2 v[8:9], v[6:7], off offset:2048
	v_lshlrev_b32_e32 v6, 16, v148
	v_and_b32_e32 v7, 0xffff0000, v148
	v_lshlrev_b32_e32 v8, 16, v149
	v_and_b32_e32 v9, 0xffff0000, v149
	v_lshlrev_b32_e32 v12, 16, v147
	v_and_b32_e32 v13, 0xffff0000, v147
	v_pk_fma_f32 v[8:9], v[0:1], v[12:13], v[8:9]
	v_pk_fma_f32 v[6:7], v[2:3], v[10:11], v[6:7]
	s_waitcnt vmcnt(15)
	v_lshlrev_b32_e32 v10, 16, v140
	v_cvt_pk_bf16_f32 v6, v6, v7
	v_cvt_pk_bf16_f32 v7, v8, v9
	v_mad_i64_i32 v[8:9], s[10:11], v138, s2, v[4:5]
	v_lshl_add_u64 v[8:9], v[8:9], 0, v[116:117]
	v_add_co_u32_e32 v8, vcc, s3, v8
	v_and_b32_e32 v11, 0xffff0000, v140
	s_nop 0
	v_addc_co_u32_e32 v9, vcc, 0, v9, vcc
	global_store_dwordx2 v[8:9], v[6:7], off offset:2048
	v_lshlrev_b32_e32 v6, 16, v142
	v_and_b32_e32 v7, 0xffff0000, v142
	v_lshlrev_b32_e32 v8, 16, v143
	v_and_b32_e32 v9, 0xffff0000, v143
	v_lshlrev_b32_e32 v12, 16, v141
	v_and_b32_e32 v13, 0xffff0000, v141
	v_pk_fma_f32 v[8:9], v[0:1], v[12:13], v[8:9]
	v_pk_fma_f32 v[6:7], v[2:3], v[10:11], v[6:7]
	s_cmp_eq_u32 s8, 3
	v_cvt_pk_bf16_f32 v6, v6, v7
	v_cvt_pk_bf16_f32 v7, v8, v9
	v_mad_i64_i32 v[8:9], s[10:11], v132, s2, v[4:5]
	v_lshl_add_u64 v[8:9], v[8:9], 0, v[116:117]
	v_add_co_u32_e32 v8, vcc, s3, v8
	v_mad_i64_i32 v[4:5], s[10:11], v130, s2, v[4:5]
	s_nop 0
	v_addc_co_u32_e32 v9, vcc, 0, v9, vcc
	v_lshl_add_u64 v[4:5], v[4:5], 0, v[116:117]
	s_cselect_b64 s[8:9], -1, 0
	global_store_dwordx2 v[8:9], v[6:7], off offset:2048
	s_waitcnt vmcnt(16)
	v_lshlrev_b32_e32 v6, 16, v136
	v_and_b32_e32 v7, 0xffff0000, v136
	s_waitcnt vmcnt(15)
	v_lshlrev_b32_e32 v10, 16, v134
	v_and_b32_e32 v11, 0xffff0000, v134
	v_add_co_u32_e32 v4, vcc, 0x27820000, v4
	s_and_b64 s[0:1], s[8:9], s[0:1]
	v_lshlrev_b32_e32 v8, 16, v137
	v_and_b32_e32 v9, 0xffff0000, v137
	v_lshlrev_b32_e32 v12, 16, v135
	v_and_b32_e32 v13, 0xffff0000, v135
	v_pk_fma_f32 v[6:7], v[2:3], v[10:11], v[6:7]
	v_addc_co_u32_e32 v5, vcc, 0, v5, vcc
	s_and_b64 s[8:9], s[4:5], s[0:1]
	v_pk_fma_f32 v[8:9], v[0:1], v[12:13], v[8:9]
	v_cvt_pk_bf16_f32 v6, v6, v7
	s_nop 0
	v_cvt_pk_bf16_f32 v7, v8, v9
	global_store_dwordx2 v[4:5], v[6:7], off offset:2048
	s_and_saveexec_b64 s[0:1], s[8:9]
	s_cbranch_execz .LBB0_695
	s_lshl_b32 s8, s7, 1
	s_ashr_i32 s9, s8, 31
	s_lshl_b64 s[10:11], s[8:9], 12
	s_or_b32 s8, s8, 1
	s_ashr_i32 s9, s8, 31
	s_lshl_b64 s[8:9], s[8:9], 12
	v_lshl_add_u64 v[4:5], v[118:119], 0, s[10:11]
	v_lshl_add_u64 v[8:9], v[118:119], 0, s[8:9]
	global_load_dwordx4 v[4:7], v[4:5], off
	s_nop 0
	global_load_dwordx4 v[8:11], v[8:9], off
	s_ashr_i32 s8, s6, 6
	s_ashr_i32 s9, s8, 31
	s_lshl_b64 s[8:9], s[8:9], 12
	s_waitcnt vmcnt(0)
	v_pk_fma_f32 v[6:7], v[0:1], v[6:7], v[10:11]
	v_pk_fma_f32 v[4:5], v[2:3], v[4:5], v[8:9]
	v_lshl_add_u64 v[0:1], v[124:125], 0, s[8:9]
	global_store_dwordx4 v[0:1], v[4:7], off sc1
	s_branch .LBB0_695

; __device__ __forceinline__ unsigned cvt_pk_bf16(float lo, float hi) { unsigned r; asm volatile("v_cvt_pk_bf16_f32 %0, %1, %2" : "=v"(r) : "v"(lo), "v"(hi)); return r; }
; __device__ __forceinline__ float bflo(unsigned w) { return __uint_as_float(w << 16); }
; __device__ __forceinline__ float bfhi(unsigned w) { return __uint_as_float(w & 0xffff0000u); }
;     __device__ __forceinline__ void operator()(f32x4 (&acc)[2][2][4][2], const Unit& u, int wr, int wc, int fr, int fq) const {
;     ...
;                 u32x4 ga[2][2], gb[2][2];
; #pragma unroll
;                 for (int mm = 0; mm < 2; ++mm)
; #pragma unroll
;                     for (int bj = 0; bj < 2; ++bj) {
;                         const bf16_t* zp = Z + (size_t)(row0 + ai * HALF + (2 * m2 + mm) * 16) * NZ + koff + col0 + bj * HALF;
;                         ga[mm][bj] = *(const u32x4*)zp;
;                         gb[mm][bj] = *(const u32x4*)(zp + noff);
;                     }
; #pragma unroll
;                 for (int mm = 0; mm < 2; ++mm)
; #pragma unroll
;                     for (int bj = 0; bj < 2; ++bj) {
;                         const int m = 2 * m2 + mm;
;                         const u32x4 a4 = ga[mm][bj], b4 = gb[mm][bj];
;                         f32x4 g0 = (f32x4){bflo(a4.x), bfhi(a4.x), bflo(a4.y), bfhi(a4.y)}, g1 = (f32x4){bflo(a4.z), bfhi(a4.z), bflo(a4.w), bfhi(a4.w)};
;                         const f32x4 h0 = (f32x4){bflo(b4.x), bfhi(b4.x), bflo(b4.y), bfhi(b4.y)}, h1 = (f32x4){bflo(b4.z), bfhi(b4.z), bflo(b4.w), bfhi(b4.w)};
; #pragma unroll
;                         for (int j = 0; j < 4; ++j) {
;                             g0[j] = fmaxf(g0[j], 1e-6f) * (last ? 1.0f : __builtin_amdgcn_rcpf(fmaxf(h0[j], 1e-6f)));
;                             g1[j] = fmaxf(g1[j], 1e-6f) * (last ? 1.0f : __builtin_amdgcn_rcpf(fmaxf(h1[j], 1e-6f)));
;                         }
;                         acc[ai][bj][m][0] *= g0; acc[ai][bj][m][1] *= g1;
;                         if (last) {
;                             const f32x4 v0 = acc[ai][bj][m][0], v1 = acc[ai][bj][m][1];
;                             u32x4 w; w.x = cvt_pk_bf16(v0[0], v0[1]); w.y = cvt_pk_bf16(v0[2], v0[3]); w.z = cvt_pk_bf16(v1[0], v1[1]); w.w = cvt_pk_bf16(v1[2], v1[3]);
;                             *(u32x4*)(MB + (size_t)(row0 + ai * HALF + m * 16) * D + col0 + bj * HALF) = w;
;                         }
.LBB0_824:
	s_lshl_b32 s4, s51, 11
	s_cmp_eq_u32 s51, 2
	s_cselect_b64 s[20:21], -1, 0
	s_and_b64 s[22:23], s[20:21], exec
	v_lshl_add_u32 v168, s0, 8, v153
	s_cselect_b32 s0, 0, 0x800
	s_ashr_i32 s5, s4, 31
	s_lshl_b64 s[4:5], s[4:5], 1
	s_add_u32 s22, s40, s4
	v_lshl_or_b32 v166, s52, 8, v182
	s_addc_u32 s23, s41, s5
	v_ashrrev_i32_e32 v167, 31, v166
	v_mov_b64_e32 v[128:129], s[22:23]
	v_mad_i64_i32 v[130:131], s[4:5], v168, s46, v[128:129]
	v_lshlrev_b64 v[170:171], 1, v[166:167]
	v_lshl_add_u64 v[130:131], v[130:131], 0, v[170:171]
	v_add_co_u32_e32 v132, vcc, s37, v130
	s_lshl_b32 s0, s0, 1
	s_nop 0
	v_addc_co_u32_e32 v133, vcc, 0, v131, vcc
	v_lshl_add_u64 v[130:131], v[130:131], 0, s[12:13]
	v_lshl_add_u64 v[136:137], v[130:131], 0, s[0:1]
	global_load_dwordx4 v[184:187], v[132:133], off offset:2048
	global_load_dwordx4 v[148:151], v[130:131], off offset:256
	global_load_dwordx4 v[188:191], v[136:137], off
	v_or_b32_e32 v172, 16, v168
	v_mad_i64_i32 v[128:129], s[4:5], v172, s46, v[128:129]
	v_lshl_add_u64 v[128:129], v[128:129], 0, v[170:171]
	v_lshl_add_u64 v[132:133], v[128:129], 0, s[12:13]
	v_add_co_u32_e32 v128, vcc, s37, v128
	v_lshl_add_u64 v[130:131], v[132:133], 0, s[0:1]
	s_nop 0
	v_addc_co_u32_e32 v129, vcc, 0, v129, vcc
	global_load_dwordx4 v[140:143], v[128:129], off offset:2048
	s_nop 0
	global_load_dwordx4 v[132:135], v[132:133], off offset:256
	s_nop 0
	global_load_dwordx4 v[144:147], v[136:137], off offset:256
	s_nop 0
	global_load_dwordx4 v[136:139], v[130:131], off
	s_nop 0
	global_load_dwordx4 v[128:131], v[130:131], off offset:256
	v_ashrrev_i32_e32 v169, 31, v168
	v_lshlrev_b64 v[174:175], 12, v[168:169]
	v_lshl_add_u64 v[174:175], s[58:59], 0, v[174:175]
	s_cmp_lg_u32 s51, 2
	v_lshl_add_u64 v[174:175], v[166:167], 1, v[174:175]
	s_waitcnt vmcnt(0)
	v_lshlrev_b32_e32 v169, 16, v184
	v_and_b32_e32 v173, 0xffff0000, v184
	v_lshlrev_b32_e32 v184, 16, v185
	v_and_b32_e32 v192, 0xffff0000, v185
	v_lshlrev_b32_e32 v185, 16, v186
	v_and_b32_e32 v186, 0xffff0000, v186
	v_lshlrev_b32_e32 v193, 16, v187
	v_and_b32_e32 v194, 0xffff0000, v187
	v_lshlrev_b32_e32 v187, 16, v188
	v_lshlrev_b32_e32 v195, 16, v189
	v_lshlrev_b32_e32 v196, 16, v190
	v_and_b32_e32 v190, 0xffff0000, v190
	v_max_f32_e32 v186, v186, v186
	v_max_f32_e32 v184, v184, v184
	v_max_f32_e32 v187, v187, v187
	v_max_f32_e32 v198, 0x358637bd, v186
	v_max_f32_e32 v186, v190, v190
	v_max_f32_e32 v190, 0x358637bd, v184
	v_max_f32_e32 v184, v195, v195
	v_max_f32_e32 v187, 0x358637bd, v187
	v_max_f32_e32 v184, 0x358637bd, v184
	v_rcp_f32_e32 v187, v187
	v_rcp_f32_e32 v184, v184
	v_and_b32_e32 v188, 0xffff0000, v188
	v_max_f32_e32 v169, v169, v169
	v_max_f32_e32 v196, v196, v196
	v_max_f32_e32 v188, v188, v188
	v_and_b32_e32 v189, 0xffff0000, v189
	v_max_f32_e32 v169, 0x358637bd, v169
	v_max_f32_e32 v196, 0x358637bd, v196
	v_max_f32_e32 v188, 0x358637bd, v188
	v_cndmask_b32_e64 v187, v187, 1.0, s[20:21]
	v_max_f32_e32 v186, 0x358637bd, v186
	v_rcp_f32_e32 v196, v196
	v_rcp_f32_e32 v188, v188
	v_cndmask_b32_e64 v199, v184, 1.0, s[20:21]
	v_mul_f32_e32 v184, v169, v187
	v_max_f32_e32 v169, v189, v189
	v_lshlrev_b32_e32 v197, 16, v191
	v_and_b32_e32 v191, 0xffff0000, v191
	v_rcp_f32_e32 v186, v186
	v_max_f32_e32 v169, 0x358637bd, v169
	v_max_f32_e32 v195, v197, v197
	v_rcp_f32_e32 v169, v169
	v_max_f32_e32 v189, v191, v191
	v_max_f32_e32 v185, v185, v185
	v_max_f32_e32 v173, v173, v173
	v_max_f32_e32 v195, 0x358637bd, v195
	v_max_f32_e32 v189, 0x358637bd, v189
	v_max_f32_e32 v185, 0x358637bd, v185
	v_max_f32_e32 v173, 0x358637bd, v173
	v_rcp_f32_e32 v195, v195
	v_cndmask_b32_e64 v196, v196, 1.0, s[20:21]
	v_cndmask_b32_e64 v188, v188, 1.0, s[20:21]
	v_rcp_f32_e32 v191, v189
	v_cndmask_b32_e64 v197, v186, 1.0, s[20:21]
	v_mul_f32_e32 v186, v185, v196
	v_mul_f32_e32 v185, v173, v188
	v_max_f32_e32 v173, v192, v192
	v_max_f32_e32 v173, 0x358637bd, v173
	v_cndmask_b32_e64 v169, v169, 1.0, s[20:21]
	v_max_f32_e32 v193, v193, v193
	v_mul_f32_e32 v189, v173, v169
	v_max_f32_e32 v169, v194, v194
	v_max_f32_e32 v193, 0x358637bd, v193
	v_cndmask_b32_e64 v195, v195, 1.0, s[20:21]
	v_max_f32_e32 v169, 0x358637bd, v169
	v_cndmask_b32_e64 v173, v191, 1.0, s[20:21]
	v_mul_f32_e32 v187, v198, v197
	v_mul_f32_e32 v188, v190, v199
	v_mul_f32_e32 v190, v193, v195
	v_mul_f32_e32 v191, v169, v173
	v_pk_mul_f32 v[126:127], v[126:127], v[188:189]
	v_pk_mul_f32 v[124:125], v[124:125], v[184:185]
	v_pk_mul_f32 v[122:123], v[122:123], v[190:191]
	v_pk_mul_f32 v[120:121], v[120:121], v[186:187]
	s_cbranch_scc1 .LBB0_826
	v_cvt_pk_bf16_f32 v184, v124, v125
	v_cvt_pk_bf16_f32 v185, v126, v127
	v_cvt_pk_bf16_f32 v186, v120, v121
	v_cvt_pk_bf16_f32 v187, v122, v123
	global_store_dwordx4 v[174:175], v[184:187], off sc1
; __device__ __forceinline__ unsigned cvt_pk_bf16(float lo, float hi) { unsigned r; asm volatile("v_cvt_pk_bf16_f32 %0, %1, %2" : "=v"(r) : "v"(lo), "v"(hi)); return r; }
; __device__ __forceinline__ float bflo(unsigned w) { return __uint_as_float(w << 16); }
; __device__ __forceinline__ float bfhi(unsigned w) { return __uint_as_float(w & 0xffff0000u); }
;     __device__ __forceinline__ void operator()(f32x4 (&acc)[2][2][4][2], const Unit& u, int wr, int wc, int fr, int fq) const {
;     ...
; #pragma unroll
;                 for (int mm = 0; mm < 2; ++mm)
; #pragma unroll
;                     for (int bj = 0; bj < 2; ++bj) {
;                         const int m = 2 * m2 + mm;
;                         const u32x4 a4 = ga[mm][bj], b4 = gb[mm][bj];
;                         f32x4 g0 = (f32x4){bflo(a4.x), bfhi(a4.x), bflo(a4.y), bfhi(a4.y)}, g1 = (f32x4){bflo(a4.z), bfhi(a4.z), bflo(a4.w), bfhi(a4.w)};
;                         const f32x4 h0 = (f32x4){bflo(b4.x), bfhi(b4.x), bflo(b4.y), bfhi(b4.y)}, h1 = (f32x4){bflo(b4.z), bfhi(b4.z), bflo(b4.w), bfhi(b4.w)};
; #pragma unroll
;                         for (int j = 0; j < 4; ++j) {
;                             g0[j] = fmaxf(g0[j], 1e-6f) * (last ? 1.0f : __builtin_amdgcn_rcpf(fmaxf(h0[j], 1e-6f)));
;                             g1[j] = fmaxf(g1[j], 1e-6f) * (last ? 1.0f : __builtin_amdgcn_rcpf(fmaxf(h1[j], 1e-6f)));
;                         }
;                         acc[ai][bj][m][0] *= g0; acc[ai][bj][m][1] *= g1;
;                         if (last) {
;                             const f32x4 v0 = acc[ai][bj][m][0], v1 = acc[ai][bj][m][1];
;                             u32x4 w; w.x = cvt_pk_bf16(v0[0], v0[1]); w.y = cvt_pk_bf16(v0[2], v0[3]); w.z = cvt_pk_bf16(v1[0], v1[1]); w.w = cvt_pk_bf16(v1[2], v1[3]);
;                             *(u32x4*)(MB + (size_t)(row0 + ai * HALF + m * 16) * D + col0 + bj * HALF) = w;
;                         }
.LBB0_826:
	s_nop 1
	v_lshlrev_b32_e32 v186, 16, v144
	v_and_b32_e32 v187, 0xffff0000, v144
	v_lshlrev_b32_e32 v188, 16, v145
	v_and_b32_e32 v189, 0xffff0000, v145
	v_lshlrev_b32_e32 v144, 16, v146
	v_and_b32_e32 v145, 0xffff0000, v146
	v_max_f32_e32 v146, v186, v186
	v_max_f32_e32 v146, 0x358637bd, v146
	v_max_f32_e32 v144, v144, v144
	v_lshlrev_b32_e32 v169, 16, v148
	v_rcp_f32_e32 v146, v146
	v_max_f32_e32 v144, 0x358637bd, v144
	v_lshlrev_b32_e32 v190, 16, v147
	v_and_b32_e32 v186, 0xffff0000, v147
	v_max_f32_e32 v147, v169, v169
	v_rcp_f32_e32 v169, v144
	v_max_f32_e32 v147, 0x358637bd, v147
	v_cndmask_b32_e64 v146, v146, 1.0, s[20:21]
	v_mul_f32_e32 v144, v147, v146
	v_cndmask_b32_e64 v147, v169, 1.0, s[20:21]
	v_max_f32_e32 v169, v187, v187
	v_max_f32_e32 v169, 0x358637bd, v169
	v_rcp_f32_e32 v169, v169
	v_lshlrev_b32_e32 v184, 16, v150
	v_max_f32_e32 v146, v184, v184
	v_max_f32_e32 v145, v145, v145
	v_and_b32_e32 v148, 0xffff0000, v148
	v_max_f32_e32 v146, 0x358637bd, v146
	v_max_f32_e32 v145, 0x358637bd, v145
	v_mul_f32_e32 v146, v146, v147
	v_max_f32_e32 v147, v148, v148
	v_cndmask_b32_e64 v148, v169, 1.0, s[20:21]
	v_rcp_f32_e32 v169, v145
	v_and_b32_e32 v150, 0xffff0000, v150
	v_max_f32_e32 v147, 0x358637bd, v147
	v_mul_f32_e32 v145, v147, v148
	v_max_f32_e32 v147, v150, v150
	v_max_f32_e32 v150, v188, v188
	v_max_f32_e32 v150, 0x358637bd, v150
	v_lshlrev_b32_e32 v173, 16, v149
	v_max_f32_e32 v147, 0x358637bd, v147
	v_cndmask_b32_e64 v148, v169, 1.0, s[20:21]
	v_rcp_f32_e32 v150, v150
	v_max_f32_e32 v169, v190, v190
	v_mul_f32_e32 v147, v147, v148
	v_max_f32_e32 v148, v173, v173
	v_max_f32_e32 v169, 0x358637bd, v169
	v_max_f32_e32 v173, v189, v189
	v_rcp_f32_e32 v169, v169
	v_max_f32_e32 v173, 0x358637bd, v173
	v_rcp_f32_e32 v173, v173
	v_lshlrev_b32_e32 v185, 16, v151
	v_max_f32_e32 v148, 0x358637bd, v148
	v_cndmask_b32_e64 v150, v150, 1.0, s[20:21]
	v_mul_f32_e32 v148, v148, v150
	v_max_f32_e32 v150, v185, v185
	v_max_f32_e32 v150, 0x358637bd, v150
	v_cndmask_b32_e64 v169, v169, 1.0, s[20:21]
	v_mul_f32_e32 v150, v150, v169
	v_cndmask_b32_e64 v169, v173, 1.0, s[20:21]
	v_max_f32_e32 v173, v186, v186
	v_max_f32_e32 v173, 0x358637bd, v173
	v_rcp_f32_e32 v173, v173
	v_and_b32_e32 v149, 0xffff0000, v149
	v_and_b32_e32 v151, 0xffff0000, v151
	v_max_f32_e32 v149, v149, v149
	v_max_f32_e32 v149, 0x358637bd, v149
	v_max_f32_e32 v151, v151, v151
	v_mul_f32_e32 v149, v149, v169
	v_max_f32_e32 v151, 0x358637bd, v151
	v_cndmask_b32_e64 v169, v173, 1.0, s[20:21]
	v_mul_f32_e32 v151, v151, v169
	v_pk_mul_f32 v[92:93], v[92:93], v[144:145]
	v_cndmask_b32_e64 v144, 0, 1, s[20:21]
	v_pk_mul_f32 v[94:95], v[94:95], v[148:149]
	v_pk_mul_f32 v[90:91], v[90:91], v[150:151]
	v_cmp_ne_u32_e64 s[4:5], 1, v144
	s_andn2_b64 vcc, exec, s[20:21]
	v_pk_mul_f32 v[88:89], v[88:89], v[146:147]
	s_cbranch_vccnz .LBB0_828
	v_cvt_pk_bf16_f32 v144, v92, v93
	v_cvt_pk_bf16_f32 v145, v94, v95
	v_cvt_pk_bf16_f32 v146, v88, v89
	v_cvt_pk_bf16_f32 v147, v90, v91
	global_store_dwordx4 v[174:175], v[144:147], off offset:256 sc1
.LBB0_828:
	v_ashrrev_i32_e32 v173, 31, v172
	v_lshlrev_b32_e32 v150, 16, v136
	v_lshlrev_b64 v[144:145], 12, v[172:173]
	v_and_b32_e32 v151, 0xffff0000, v136
	v_lshlrev_b32_e32 v169, 16, v137
	v_and_b32_e32 v172, 0xffff0000, v137
	v_lshlrev_b32_e32 v136, 16, v138
	v_and_b32_e32 v137, 0xffff0000, v138
	v_max_f32_e32 v138, v150, v150
	v_max_f32_e32 v138, 0x358637bd, v138
	v_max_f32_e32 v136, v136, v136
	v_lshlrev_b32_e32 v146, 16, v140
	v_rcp_f32_e32 v138, v138
	v_max_f32_e32 v136, 0x358637bd, v136
	v_lshlrev_b32_e32 v173, 16, v139
	v_and_b32_e32 v150, 0xffff0000, v139
	v_max_f32_e32 v139, v146, v146
	v_rcp_f32_e32 v146, v136
	v_max_f32_e32 v139, 0x358637bd, v139
	v_cndmask_b32_e64 v138, v138, 1.0, s[20:21]
	v_mul_f32_e32 v136, v139, v138
	v_cndmask_b32_e64 v139, v146, 1.0, s[20:21]
	v_max_f32_e32 v146, v151, v151
	v_max_f32_e32 v146, 0x358637bd, v146
	v_rcp_f32_e32 v146, v146
	v_lshlrev_b32_e32 v148, 16, v142
	v_max_f32_e32 v138, v148, v148
	v_max_f32_e32 v137, v137, v137
	v_and_b32_e32 v140, 0xffff0000, v140
	v_max_f32_e32 v138, 0x358637bd, v138
	v_max_f32_e32 v137, 0x358637bd, v137
	v_mul_f32_e32 v138, v138, v139
	v_max_f32_e32 v139, v140, v140
	v_cndmask_b32_e64 v140, v146, 1.0, s[20:21]
	v_rcp_f32_e32 v146, v137
	v_and_b32_e32 v142, 0xffff0000, v142
	v_max_f32_e32 v139, 0x358637bd, v139
	v_mul_f32_e32 v137, v139, v140
	v_max_f32_e32 v139, v142, v142
	v_max_f32_e32 v142, v169, v169
	v_max_f32_e32 v142, 0x358637bd, v142
	v_lshlrev_b32_e32 v147, 16, v141
	v_max_f32_e32 v139, 0x358637bd, v139
	v_cndmask_b32_e64 v140, v146, 1.0, s[20:21]
	v_rcp_f32_e32 v142, v142
	v_max_f32_e32 v146, v173, v173
	v_mul_f32_e32 v139, v139, v140
	v_max_f32_e32 v140, v147, v147
	v_max_f32_e32 v146, 0x358637bd, v146
	v_max_f32_e32 v147, v172, v172
	v_rcp_f32_e32 v146, v146
	v_max_f32_e32 v147, 0x358637bd, v147
	v_rcp_f32_e32 v147, v147
	v_lshlrev_b32_e32 v149, 16, v143
	v_max_f32_e32 v140, 0x358637bd, v140
	v_cndmask_b32_e64 v142, v142, 1.0, s[20:21]
	v_mul_f32_e32 v140, v140, v142
	v_max_f32_e32 v142, v149, v149
	v_max_f32_e32 v142, 0x358637bd, v142
	v_cndmask_b32_e64 v146, v146, 1.0, s[20:21]
	v_mul_f32_e32 v142, v142, v146
	v_cndmask_b32_e64 v146, v147, 1.0, s[20:21]
	v_max_f32_e32 v147, v150, v150
	v_max_f32_e32 v147, 0x358637bd, v147
	v_rcp_f32_e32 v147, v147
	v_and_b32_e32 v141, 0xffff0000, v141
	v_and_b32_e32 v143, 0xffff0000, v143
	v_max_f32_e32 v141, v141, v141
	v_max_f32_e32 v141, 0x358637bd, v141
	v_max_f32_e32 v143, v143, v143
	v_mul_f32_e32 v141, v141, v146
	v_max_f32_e32 v143, 0x358637bd, v143
	v_cndmask_b32_e64 v146, v147, 1.0, s[20:21]
	v_mul_f32_e32 v143, v143, v146
	v_pk_mul_f32 v[116:117], v[116:117], v[136:137]
	v_lshl_add_u64 v[136:137], s[58:59], 0, v[144:145]
	v_pk_mul_f32 v[118:119], v[118:119], v[140:141]
	v_pk_mul_f32 v[114:115], v[114:115], v[142:143]
	v_pk_mul_f32 v[112:113], v[112:113], v[138:139]
	s_and_b64 vcc, exec, s[4:5]
	v_lshl_add_u64 v[136:137], v[166:167], 1, v[136:137]
	s_cbranch_vccnz .LBB0_830
	v_cvt_pk_bf16_f32 v138, v116, v117
	v_cvt_pk_bf16_f32 v139, v118, v119
	v_cvt_pk_bf16_f32 v140, v112, v113
	v_cvt_pk_bf16_f32 v141, v114, v115
	global_store_dwordx4 v[136:137], v[138:141], off sc1
; __device__ __forceinline__ unsigned cvt_pk_bf16(float lo, float hi) { unsigned r; asm volatile("v_cvt_pk_bf16_f32 %0, %1, %2" : "=v"(r) : "v"(lo), "v"(hi)); return r; }
; __device__ __forceinline__ float bflo(unsigned w) { return __uint_as_float(w << 16); }
; __device__ __forceinline__ float bfhi(unsigned w) { return __uint_as_float(w & 0xffff0000u); }
;     __device__ __forceinline__ void operator()(f32x4 (&acc)[2][2][4][2], const Unit& u, int wr, int wc, int fr, int fq) const {
;     ...
;                 u32x4 ga[2][2], gb[2][2];
; #pragma unroll
;                 for (int mm = 0; mm < 2; ++mm)
; #pragma unroll
;                     for (int bj = 0; bj < 2; ++bj) {
;                         const bf16_t* zp = Z + (size_t)(row0 + ai * HALF + (2 * m2 + mm) * 16) * NZ + koff + col0 + bj * HALF;
;                         ga[mm][bj] = *(const u32x4*)zp;
;                         gb[mm][bj] = *(const u32x4*)(zp + noff);
;                     }
; #pragma unroll
;                 for (int mm = 0; mm < 2; ++mm)
; #pragma unroll
;                     for (int bj = 0; bj < 2; ++bj) {
;                         const int m = 2 * m2 + mm;
;                         const u32x4 a4 = ga[mm][bj], b4 = gb[mm][bj];
;                         f32x4 g0 = (f32x4){bflo(a4.x), bfhi(a4.x), bflo(a4.y), bfhi(a4.y)}, g1 = (f32x4){bflo(a4.z), bfhi(a4.z), bflo(a4.w), bfhi(a4.w)};
;                         const f32x4 h0 = (f32x4){bflo(b4.x), bfhi(b4.x), bflo(b4.y), bfhi(b4.y)}, h1 = (f32x4){bflo(b4.z), bfhi(b4.z), bflo(b4.w), bfhi(b4.w)};
; #pragma unroll
;                         for (int j = 0; j < 4; ++j) {
;                             g0[j] = fmaxf(g0[j], 1e-6f) * (last ? 1.0f : __builtin_amdgcn_rcpf(fmaxf(h0[j], 1e-6f)));
;                             g1[j] = fmaxf(g1[j], 1e-6f) * (last ? 1.0f : __builtin_amdgcn_rcpf(fmaxf(h1[j], 1e-6f)));
;                         }
;                         acc[ai][bj][m][0] *= g0; acc[ai][bj][m][1] *= g1;
;                         if (last) {
;                             const f32x4 v0 = acc[ai][bj][m][0], v1 = acc[ai][bj][m][1];
;                             u32x4 w; w.x = cvt_pk_bf16(v0[0], v0[1]); w.y = cvt_pk_bf16(v0[2], v0[3]); w.z = cvt_pk_bf16(v1[0], v1[1]); w.w = cvt_pk_bf16(v1[2], v1[3]);
;                             *(u32x4*)(MB + (size_t)(row0 + ai * HALF + m * 16) * D + col0 + bj * HALF) = w;
;                         }
.LBB0_830:
	v_lshlrev_b32_e32 v142, 16, v128
	v_and_b32_e32 v143, 0xffff0000, v128
	v_lshlrev_b32_e32 v144, 16, v129
	v_and_b32_e32 v145, 0xffff0000, v129
	v_lshlrev_b32_e32 v128, 16, v130
	v_and_b32_e32 v129, 0xffff0000, v130
	v_max_f32_e32 v130, v142, v142
	v_max_f32_e32 v130, 0x358637bd, v130
	v_max_f32_e32 v128, v128, v128
	v_lshlrev_b32_e32 v138, 16, v132
	v_rcp_f32_e32 v130, v130
	v_max_f32_e32 v128, 0x358637bd, v128
	v_lshlrev_b32_e32 v146, 16, v131
	v_and_b32_e32 v142, 0xffff0000, v131
	v_max_f32_e32 v131, v138, v138
	v_rcp_f32_e32 v138, v128
	v_max_f32_e32 v131, 0x358637bd, v131
	v_cndmask_b32_e64 v130, v130, 1.0, s[20:21]
	v_mul_f32_e32 v128, v131, v130
	v_cndmask_b32_e64 v131, v138, 1.0, s[20:21]
	v_max_f32_e32 v138, v143, v143
	v_max_f32_e32 v138, 0x358637bd, v138
	v_rcp_f32_e32 v138, v138
	v_lshlrev_b32_e32 v140, 16, v134
	v_max_f32_e32 v130, v140, v140
	v_max_f32_e32 v129, v129, v129
	v_and_b32_e32 v132, 0xffff0000, v132
	v_max_f32_e32 v130, 0x358637bd, v130
	v_max_f32_e32 v129, 0x358637bd, v129
	v_mul_f32_e32 v130, v130, v131
	v_max_f32_e32 v131, v132, v132
	v_cndmask_b32_e64 v132, v138, 1.0, s[20:21]
	v_rcp_f32_e32 v138, v129
	v_and_b32_e32 v134, 0xffff0000, v134
	v_max_f32_e32 v131, 0x358637bd, v131
	v_mul_f32_e32 v129, v131, v132
	v_max_f32_e32 v131, v134, v134
	v_max_f32_e32 v134, v144, v144
	v_max_f32_e32 v134, 0x358637bd, v134
	v_lshlrev_b32_e32 v139, 16, v133
	v_max_f32_e32 v131, 0x358637bd, v131
	v_cndmask_b32_e64 v132, v138, 1.0, s[20:21]
	v_rcp_f32_e32 v134, v134
	v_max_f32_e32 v138, v146, v146
	v_mul_f32_e32 v131, v131, v132
	v_max_f32_e32 v132, v139, v139
	v_max_f32_e32 v138, 0x358637bd, v138
	v_max_f32_e32 v139, v145, v145
	v_rcp_f32_e32 v138, v138
	v_max_f32_e32 v139, 0x358637bd, v139
	v_rcp_f32_e32 v139, v139
	v_lshlrev_b32_e32 v141, 16, v135
	v_max_f32_e32 v132, 0x358637bd, v132
	v_cndmask_b32_e64 v134, v134, 1.0, s[20:21]
	v_mul_f32_e32 v132, v132, v134
	v_max_f32_e32 v134, v141, v141
	v_max_f32_e32 v134, 0x358637bd, v134
	v_cndmask_b32_e64 v138, v138, 1.0, s[20:21]
	v_mul_f32_e32 v134, v134, v138
	v_cndmask_b32_e64 v138, v139, 1.0, s[20:21]
	v_max_f32_e32 v139, v142, v142
	v_max_f32_e32 v139, 0x358637bd, v139
	v_rcp_f32_e32 v139, v139
	v_and_b32_e32 v133, 0xffff0000, v133
	v_and_b32_e32 v135, 0xffff0000, v135
	v_max_f32_e32 v133, v133, v133
	v_max_f32_e32 v133, 0x358637bd, v133
	v_max_f32_e32 v135, v135, v135
	v_mul_f32_e32 v133, v133, v138
	v_max_f32_e32 v135, 0x358637bd, v135
	v_cndmask_b32_e64 v138, v139, 1.0, s[20:21]
	v_mul_f32_e32 v135, v135, v138
	v_pk_mul_f32 v[86:87], v[86:87], v[132:133]
	v_pk_mul_f32 v[84:85], v[84:85], v[128:129]
	v_pk_mul_f32 v[82:83], v[82:83], v[134:135]
	s_and_b64 vcc, exec, s[4:5]
	v_pk_mul_f32 v[80:81], v[80:81], v[130:131]
	s_cbranch_vccnz .LBB0_832
	v_cvt_pk_bf16_f32 v128, v84, v85
	v_cvt_pk_bf16_f32 v129, v86, v87
	v_cvt_pk_bf16_f32 v130, v80, v81
	v_cvt_pk_bf16_f32 v131, v82, v83
	global_store_dwordx4 v[136:137], v[128:131], off offset:256 sc1
.LBB0_832:
	s_nop 1
	v_or_b32_e32 v128, 32, v168
	v_mov_b64_e32 v[130:131], s[22:23]
	v_mad_i64_i32 v[132:133], s[24:25], v128, s46, v[130:131]
	v_lshl_add_u64 v[132:133], v[132:133], 0, v[170:171]
	v_add_co_u32_e32 v134, vcc, 0x2000, v132
	v_or_b32_e32 v172, 48, v168
	s_nop 0
	v_addc_co_u32_e32 v135, vcc, 0, v133, vcc
	v_lshl_add_u64 v[132:133], v[132:133], 0, s[12:13]
	global_load_dwordx4 v[184:187], v[134:135], off offset:2048
	v_lshl_add_u64 v[134:135], v[132:133], 0, s[0:1]
	global_load_dwordx4 v[188:191], v[134:135], off
	v_mad_i64_i32 v[130:131], s[24:25], v172, s46, v[130:131]
	v_lshl_add_u64 v[130:131], v[130:131], 0, v[170:171]
	v_ashrrev_i32_e32 v129, 31, v128
	v_lshl_add_u64 v[192:193], v[130:131], 0, s[12:13]
	v_add_co_u32_e32 v140, vcc, s37, v130
	v_lshlrev_b64 v[174:175], 12, v[128:129]
	v_lshl_add_u64 v[128:129], v[192:193], 0, s[0:1]
	v_addc_co_u32_e32 v141, vcc, 0, v131, vcc
	global_load_dwordx4 v[148:151], v[132:133], off offset:256
	global_load_dwordx4 v[144:147], v[134:135], off offset:256
	global_load_dwordx4 v[136:139], v[128:129], off
	s_nop 0
	global_load_dwordx4 v[128:131], v[128:129], off offset:256
	s_nop 0
	global_load_dwordx4 v[140:143], v[140:141], off offset:2048
	s_nop 0
	global_load_dwordx4 v[132:135], v[192:193], off offset:256
	v_lshl_add_u64 v[174:175], s[58:59], 0, v[174:175]
	s_and_b64 vcc, exec, s[4:5]
	v_lshl_add_u64 v[174:175], v[166:167], 1, v[174:175]
	s_waitcnt vmcnt(7)
	v_lshlrev_b32_e32 v193, 16, v187
	v_and_b32_e32 v194, 0xffff0000, v187
	s_waitcnt vmcnt(6)
; __device__ __forceinline__ unsigned cvt_pk_bf16(float lo, float hi) { unsigned r; asm volatile("v_cvt_pk_bf16_f32 %0, %1, %2" : "=v"(r) : "v"(lo), "v"(hi)); return r; }
; __device__ __forceinline__ float bflo(unsigned w) { return __uint_as_float(w << 16); }
; __device__ __forceinline__ float bfhi(unsigned w) { return __uint_as_float(w & 0xffff0000u); }
;     __device__ __forceinline__ void operator()(f32x4 (&acc)[2][2][4][2], const Unit& u, int wr, int wc, int fr, int fq) const {
;     ...
; #pragma unroll
;                 for (int mm = 0; mm < 2; ++mm)
; #pragma unroll
;                     for (int bj = 0; bj < 2; ++bj) {
;                         const int m = 2 * m2 + mm;
;                         const u32x4 a4 = ga[mm][bj], b4 = gb[mm][bj];
;                         f32x4 g0 = (f32x4){bflo(a4.x), bfhi(a4.x), bflo(a4.y), bfhi(a4.y)}, g1 = (f32x4){bflo(a4.z), bfhi(a4.z), bflo(a4.w), bfhi(a4.w)};
;                         const f32x4 h0 = (f32x4){bflo(b4.x), bfhi(b4.x), bflo(b4.y), bfhi(b4.y)}, h1 = (f32x4){bflo(b4.z), bfhi(b4.z), bflo(b4.w), bfhi(b4.w)};
; #pragma unroll
;                         for (int j = 0; j < 4; ++j) {
;                             g0[j] = fmaxf(g0[j], 1e-6f) * (last ? 1.0f : __builtin_amdgcn_rcpf(fmaxf(h0[j], 1e-6f)));
;                             g1[j] = fmaxf(g1[j], 1e-6f) * (last ? 1.0f : __builtin_amdgcn_rcpf(fmaxf(h1[j], 1e-6f)));
;                         }
;                         acc[ai][bj][m][0] *= g0; acc[ai][bj][m][1] *= g1;
;                         if (last) {
;                             const f32x4 v0 = acc[ai][bj][m][0], v1 = acc[ai][bj][m][1];
;                             u32x4 w; w.x = cvt_pk_bf16(v0[0], v0[1]); w.y = cvt_pk_bf16(v0[2], v0[3]); w.z = cvt_pk_bf16(v1[0], v1[1]); w.w = cvt_pk_bf16(v1[2], v1[3]);
;                             *(u32x4*)(MB + (size_t)(row0 + ai * HALF + m * 16) * D + col0 + bj * HALF) = w;
;                         }
	v_lshlrev_b32_e32 v187, 16, v188
	v_and_b32_e32 v188, 0xffff0000, v188
	v_lshlrev_b32_e32 v196, 16, v190
	v_lshlrev_b32_e32 v169, 16, v184
	v_and_b32_e32 v173, 0xffff0000, v184
	v_lshlrev_b32_e32 v184, 16, v185
	v_and_b32_e32 v192, 0xffff0000, v185
	v_lshlrev_b32_e32 v185, 16, v186
	v_and_b32_e32 v186, 0xffff0000, v186
	v_lshlrev_b32_e32 v195, 16, v189
	v_and_b32_e32 v189, 0xffff0000, v189
	v_and_b32_e32 v190, 0xffff0000, v190
	v_max_f32_e32 v196, v196, v196
	v_max_f32_e32 v188, v188, v188
	v_max_f32_e32 v186, v186, v186
	v_max_f32_e32 v190, v190, v190
	v_max_f32_e32 v189, v189, v189
	v_max_f32_e32 v196, 0x358637bd, v196
	v_max_f32_e32 v188, 0x358637bd, v188
	v_max_f32_e32 v198, 0x358637bd, v186
	v_max_f32_e32 v186, 0x358637bd, v190
	v_max_f32_e32 v189, 0x358637bd, v189
	v_rcp_f32_e32 v196, v196
	v_rcp_f32_e32 v188, v188
	v_max_f32_e32 v187, v187, v187
	v_rcp_f32_e32 v186, v186
	v_rcp_f32_e32 v189, v189
	v_max_f32_e32 v184, v184, v184
	v_max_f32_e32 v195, v195, v195
	v_max_f32_e32 v187, 0x358637bd, v187
	v_lshlrev_b32_e32 v197, 16, v191
	v_max_f32_e32 v185, v185, v185
	v_max_f32_e32 v173, v173, v173
	v_max_f32_e32 v190, 0x358637bd, v184
	v_max_f32_e32 v184, 0x358637bd, v195
	v_rcp_f32_e32 v187, v187
	v_and_b32_e32 v191, 0xffff0000, v191
	v_max_f32_e32 v197, v197, v197
	v_max_f32_e32 v185, 0x358637bd, v185
	v_max_f32_e32 v173, 0x358637bd, v173
	v_rcp_f32_e32 v184, v184
	v_cndmask_b32_e64 v196, v196, 1.0, s[20:21]
	v_cndmask_b32_e64 v188, v188, 1.0, s[20:21]
	v_max_f32_e32 v195, 0x358637bd, v197
	v_cndmask_b32_e64 v197, v186, 1.0, s[20:21]
	v_mul_f32_e32 v186, v185, v196
	v_mul_f32_e32 v185, v173, v188
	v_cndmask_b32_e64 v173, v189, 1.0, s[20:21]
	v_max_f32_e32 v189, v191, v191
	v_max_f32_e32 v169, v169, v169
	v_max_f32_e32 v189, 0x358637bd, v189
	v_max_f32_e32 v169, 0x358637bd, v169
	v_rcp_f32_e32 v195, v195
	v_cndmask_b32_e64 v187, v187, 1.0, s[20:21]
	v_rcp_f32_e32 v191, v189
	v_cndmask_b32_e64 v199, v184, 1.0, s[20:21]
	v_mul_f32_e32 v184, v169, v187
	v_max_f32_e32 v169, v192, v192
	v_max_f32_e32 v169, 0x358637bd, v169
	v_max_f32_e32 v193, v193, v193
	v_mul_f32_e32 v189, v169, v173
	v_max_f32_e32 v169, v194, v194
	v_max_f32_e32 v193, 0x358637bd, v193
	v_cndmask_b32_e64 v195, v195, 1.0, s[20:21]
	v_max_f32_e32 v169, 0x358637bd, v169
	v_cndmask_b32_e64 v173, v191, 1.0, s[20:21]
	v_mul_f32_e32 v187, v198, v197
	v_mul_f32_e32 v188, v190, v199
	v_mul_f32_e32 v190, v193, v195
	v_mul_f32_e32 v191, v169, v173
	v_pk_mul_f32 v[110:111], v[110:111], v[188:189]
	v_pk_mul_f32 v[108:109], v[108:109], v[184:185]
	v_pk_mul_f32 v[106:107], v[106:107], v[190:191]
	v_pk_mul_f32 v[104:105], v[104:105], v[186:187]
	s_cbranch_vccnz .LBB0_834
	v_cvt_pk_bf16_f32 v184, v108, v109
	v_cvt_pk_bf16_f32 v185, v110, v111
	v_cvt_pk_bf16_f32 v186, v104, v105
	v_cvt_pk_bf16_f32 v187, v106, v107
	global_store_dwordx4 v[174:175], v[184:187], off sc1
.LBB0_834:
	s_waitcnt vmcnt(4)
	s_nop 0
	v_lshlrev_b32_e32 v186, 16, v144
	v_and_b32_e32 v187, 0xffff0000, v144
	v_lshlrev_b32_e32 v188, 16, v145
	v_and_b32_e32 v189, 0xffff0000, v145
	v_lshlrev_b32_e32 v144, 16, v146
	v_and_b32_e32 v145, 0xffff0000, v146
	v_max_f32_e32 v146, v186, v186
	v_max_f32_e32 v146, 0x358637bd, v146
	v_max_f32_e32 v144, v144, v144
	v_lshlrev_b32_e32 v169, 16, v148
	v_rcp_f32_e32 v146, v146
	v_max_f32_e32 v144, 0x358637bd, v144
	v_lshlrev_b32_e32 v190, 16, v147
	v_and_b32_e32 v186, 0xffff0000, v147
	v_max_f32_e32 v147, v169, v169
	v_rcp_f32_e32 v169, v144
	v_max_f32_e32 v147, 0x358637bd, v147
	v_cndmask_b32_e64 v146, v146, 1.0, s[20:21]
	v_mul_f32_e32 v144, v147, v146
	v_cndmask_b32_e64 v147, v169, 1.0, s[20:21]
	v_max_f32_e32 v169, v187, v187
	v_max_f32_e32 v169, 0x358637bd, v169
	v_rcp_f32_e32 v169, v169
	v_lshlrev_b32_e32 v184, 16, v150
	v_max_f32_e32 v146, v184, v184
	v_max_f32_e32 v145, v145, v145
	v_and_b32_e32 v148, 0xffff0000, v148
	v_max_f32_e32 v146, 0x358637bd, v146
	v_max_f32_e32 v145, 0x358637bd, v145
	v_mul_f32_e32 v146, v146, v147
	v_max_f32_e32 v147, v148, v148
	v_cndmask_b32_e64 v148, v169, 1.0, s[20:21]
	v_rcp_f32_e32 v169, v145
	v_and_b32_e32 v150, 0xffff0000, v150
	v_max_f32_e32 v147, 0x358637bd, v147
	v_mul_f32_e32 v145, v147, v148
	v_max_f32_e32 v147, v150, v150
	v_max_f32_e32 v150, v188, v188
	v_max_f32_e32 v150, 0x358637bd, v150
	v_lshlrev_b32_e32 v173, 16, v149
	v_max_f32_e32 v147, 0x358637bd, v147
	v_cndmask_b32_e64 v148, v169, 1.0, s[20:21]
	v_rcp_f32_e32 v150, v150
	v_max_f32_e32 v169, v190, v190
	v_mul_f32_e32 v147, v147, v148
	v_max_f32_e32 v148, v173, v173
	v_max_f32_e32 v169, 0x358637bd, v169
	v_max_f32_e32 v173, v189, v189
	v_rcp_f32_e32 v169, v169
	v_max_f32_e32 v173, 0x358637bd, v173
	v_rcp_f32_e32 v173, v173
	v_lshlrev_b32_e32 v185, 16, v151
	v_max_f32_e32 v148, 0x358637bd, v148
	v_cndmask_b32_e64 v150, v150, 1.0, s[20:21]
	v_mul_f32_e32 v148, v148, v150
	v_max_f32_e32 v150, v185, v185
	v_max_f32_e32 v150, 0x358637bd, v150
	v_cndmask_b32_e64 v169, v169, 1.0, s[20:21]
	v_mul_f32_e32 v150, v150, v169
	v_cndmask_b32_e64 v169, v173, 1.0, s[20:21]
	v_max_f32_e32 v173, v186, v186
	v_max_f32_e32 v173, 0x358637bd, v173
	v_rcp_f32_e32 v173, v173
	v_and_b32_e32 v149, 0xffff0000, v149
	v_and_b32_e32 v151, 0xffff0000, v151
	v_max_f32_e32 v149, v149, v149
	v_max_f32_e32 v149, 0x358637bd, v149
	v_max_f32_e32 v151, v151, v151
	v_mul_f32_e32 v149, v149, v169
	v_max_f32_e32 v151, 0x358637bd, v151
	v_cndmask_b32_e64 v169, v173, 1.0, s[20:21]
	v_mul_f32_e32 v151, v151, v169
	v_pk_mul_f32 v[78:79], v[78:79], v[148:149]
	v_pk_mul_f32 v[76:77], v[76:77], v[144:145]
	v_pk_mul_f32 v[74:75], v[74:75], v[150:151]
	s_and_b64 vcc, exec, s[4:5]
	v_pk_mul_f32 v[72:73], v[72:73], v[146:147]
	s_cbranch_vccnz .LBB0_836
	v_cvt_pk_bf16_f32 v144, v76, v77
	v_cvt_pk_bf16_f32 v145, v78, v79
	v_cvt_pk_bf16_f32 v146, v72, v73
	v_cvt_pk_bf16_f32 v147, v74, v75
	global_store_dwordx4 v[174:175], v[144:147], off offset:256 sc1
; __device__ __forceinline__ unsigned cvt_pk_bf16(float lo, float hi) { unsigned r; asm volatile("v_cvt_pk_bf16_f32 %0, %1, %2" : "=v"(r) : "v"(lo), "v"(hi)); return r; }
; __device__ __forceinline__ float bflo(unsigned w) { return __uint_as_float(w << 16); }
; __device__ __forceinline__ float bfhi(unsigned w) { return __uint_as_float(w & 0xffff0000u); }
;     __device__ __forceinline__ void operator()(f32x4 (&acc)[2][2][4][2], const Unit& u, int wr, int wc, int fr, int fq) const {
;     ...
; #pragma unroll
;                 for (int mm = 0; mm < 2; ++mm)
; #pragma unroll
;                     for (int bj = 0; bj < 2; ++bj) {
;                         const int m = 2 * m2 + mm;
;                         const u32x4 a4 = ga[mm][bj], b4 = gb[mm][bj];
;                         f32x4 g0 = (f32x4){bflo(a4.x), bfhi(a4.x), bflo(a4.y), bfhi(a4.y)}, g1 = (f32x4){bflo(a4.z), bfhi(a4.z), bflo(a4.w), bfhi(a4.w)};
;                         const f32x4 h0 = (f32x4){bflo(b4.x), bfhi(b4.x), bflo(b4.y), bfhi(b4.y)}, h1 = (f32x4){bflo(b4.z), bfhi(b4.z), bflo(b4.w), bfhi(b4.w)};
; #pragma unroll
;                         for (int j = 0; j < 4; ++j) {
;                             g0[j] = fmaxf(g0[j], 1e-6f) * (last ? 1.0f : __builtin_amdgcn_rcpf(fmaxf(h0[j], 1e-6f)));
;                             g1[j] = fmaxf(g1[j], 1e-6f) * (last ? 1.0f : __builtin_amdgcn_rcpf(fmaxf(h1[j], 1e-6f)));
;                         }
;                         acc[ai][bj][m][0] *= g0; acc[ai][bj][m][1] *= g1;
;                         if (last) {
;                             const f32x4 v0 = acc[ai][bj][m][0], v1 = acc[ai][bj][m][1];
;                             u32x4 w; w.x = cvt_pk_bf16(v0[0], v0[1]); w.y = cvt_pk_bf16(v0[2], v0[3]); w.z = cvt_pk_bf16(v1[0], v1[1]); w.w = cvt_pk_bf16(v1[2], v1[3]);
;                             *(u32x4*)(MB + (size_t)(row0 + ai * HALF + m * 16) * D + col0 + bj * HALF) = w;
;                         }
.LBB0_836:
	v_ashrrev_i32_e32 v173, 31, v172
	s_waitcnt vmcnt(3)
	v_lshlrev_b32_e32 v150, 16, v136
	v_lshlrev_b64 v[144:145], 12, v[172:173]
	v_and_b32_e32 v151, 0xffff0000, v136
	v_lshlrev_b32_e32 v169, 16, v137
	v_and_b32_e32 v172, 0xffff0000, v137
	v_lshlrev_b32_e32 v136, 16, v138
	v_and_b32_e32 v137, 0xffff0000, v138
	v_max_f32_e32 v138, v150, v150
	v_max_f32_e32 v138, 0x358637bd, v138
	v_max_f32_e32 v136, v136, v136
	s_waitcnt vmcnt(1)
	v_lshlrev_b32_e32 v146, 16, v140
	v_rcp_f32_e32 v138, v138
	v_max_f32_e32 v136, 0x358637bd, v136
	v_lshlrev_b32_e32 v173, 16, v139
	v_and_b32_e32 v150, 0xffff0000, v139
	v_max_f32_e32 v139, v146, v146
	v_rcp_f32_e32 v146, v136
	v_max_f32_e32 v139, 0x358637bd, v139
	v_cndmask_b32_e64 v138, v138, 1.0, s[20:21]
	v_mul_f32_e32 v136, v139, v138
	v_cndmask_b32_e64 v139, v146, 1.0, s[20:21]
	v_max_f32_e32 v146, v151, v151
	v_max_f32_e32 v146, 0x358637bd, v146
	v_rcp_f32_e32 v146, v146
	v_lshlrev_b32_e32 v148, 16, v142
	v_max_f32_e32 v138, v148, v148
	v_max_f32_e32 v137, v137, v137
	v_and_b32_e32 v140, 0xffff0000, v140
	v_max_f32_e32 v138, 0x358637bd, v138
	v_max_f32_e32 v137, 0x358637bd, v137
	v_mul_f32_e32 v138, v138, v139
	v_max_f32_e32 v139, v140, v140
	v_cndmask_b32_e64 v140, v146, 1.0, s[20:21]
	v_rcp_f32_e32 v146, v137
	v_and_b32_e32 v142, 0xffff0000, v142
	v_max_f32_e32 v139, 0x358637bd, v139
	v_mul_f32_e32 v137, v139, v140
	v_max_f32_e32 v139, v142, v142
	v_max_f32_e32 v142, v169, v169
	v_max_f32_e32 v142, 0x358637bd, v142
	v_lshlrev_b32_e32 v147, 16, v141
	v_max_f32_e32 v139, 0x358637bd, v139
	v_cndmask_b32_e64 v140, v146, 1.0, s[20:21]
	v_rcp_f32_e32 v142, v142
	v_max_f32_e32 v146, v173, v173
	v_mul_f32_e32 v139, v139, v140
	v_max_f32_e32 v140, v147, v147
	v_max_f32_e32 v146, 0x358637bd, v146
	v_max_f32_e32 v147, v172, v172
	v_rcp_f32_e32 v146, v146
	v_max_f32_e32 v147, 0x358637bd, v147
	v_rcp_f32_e32 v147, v147
	v_lshlrev_b32_e32 v149, 16, v143
	v_max_f32_e32 v140, 0x358637bd, v140
	v_cndmask_b32_e64 v142, v142, 1.0, s[20:21]
	v_mul_f32_e32 v140, v140, v142
	v_max_f32_e32 v142, v149, v149
	v_max_f32_e32 v142, 0x358637bd, v142
	v_cndmask_b32_e64 v146, v146, 1.0, s[20:21]
	v_mul_f32_e32 v142, v142, v146
	v_cndmask_b32_e64 v146, v147, 1.0, s[20:21]
	v_max_f32_e32 v147, v150, v150
	v_max_f32_e32 v147, 0x358637bd, v147
	v_rcp_f32_e32 v147, v147
	v_and_b32_e32 v141, 0xffff0000, v141
	v_and_b32_e32 v143, 0xffff0000, v143
	v_max_f32_e32 v141, v141, v141
	v_max_f32_e32 v141, 0x358637bd, v141
	v_max_f32_e32 v143, v143, v143
	v_mul_f32_e32 v141, v141, v146
	v_max_f32_e32 v143, 0x358637bd, v143
	v_cndmask_b32_e64 v146, v147, 1.0, s[20:21]
	v_mul_f32_e32 v143, v143, v146
	v_pk_mul_f32 v[100:101], v[100:101], v[136:137]
	v_lshl_add_u64 v[136:137], s[58:59], 0, v[144:145]
	v_pk_mul_f32 v[102:103], v[102:103], v[140:141]
	v_pk_mul_f32 v[98:99], v[98:99], v[142:143]
	v_pk_mul_f32 v[96:97], v[96:97], v[138:139]
	s_and_b64 vcc, exec, s[4:5]
	v_lshl_add_u64 v[136:137], v[166:167], 1, v[136:137]
	s_cbranch_vccnz .LBB0_838
	v_cvt_pk_bf16_f32 v138, v100, v101
	v_cvt_pk_bf16_f32 v139, v102, v103
	v_cvt_pk_bf16_f32 v140, v96, v97
	v_cvt_pk_bf16_f32 v141, v98, v99
	global_store_dwordx4 v[136:137], v[138:141], off sc1
.LBB0_838:
	v_lshlrev_b32_e32 v142, 16, v128
	v_and_b32_e32 v143, 0xffff0000, v128
	v_lshlrev_b32_e32 v144, 16, v129
	v_and_b32_e32 v145, 0xffff0000, v129
	v_lshlrev_b32_e32 v128, 16, v130
	v_and_b32_e32 v129, 0xffff0000, v130
	v_max_f32_e32 v130, v142, v142
	v_max_f32_e32 v130, 0x358637bd, v130
	v_max_f32_e32 v128, v128, v128
	s_waitcnt vmcnt(0)
	v_lshlrev_b32_e32 v138, 16, v132
	v_rcp_f32_e32 v130, v130
	v_max_f32_e32 v128, 0x358637bd, v128
	v_lshlrev_b32_e32 v146, 16, v131
	v_and_b32_e32 v142, 0xffff0000, v131
	v_max_f32_e32 v131, v138, v138
	v_rcp_f32_e32 v138, v128
	v_max_f32_e32 v131, 0x358637bd, v131
	v_cndmask_b32_e64 v130, v130, 1.0, s[20:21]
	v_mul_f32_e32 v128, v131, v130
	v_cndmask_b32_e64 v131, v138, 1.0, s[20:21]
	v_max_f32_e32 v138, v143, v143
	v_max_f32_e32 v138, 0x358637bd, v138
	v_rcp_f32_e32 v138, v138
	v_lshlrev_b32_e32 v140, 16, v134
	v_max_f32_e32 v130, v140, v140
	v_max_f32_e32 v129, v129, v129
	v_and_b32_e32 v132, 0xffff0000, v132
	v_max_f32_e32 v130, 0x358637bd, v130
	v_max_f32_e32 v129, 0x358637bd, v129
	v_mul_f32_e32 v130, v130, v131
	v_max_f32_e32 v131, v132, v132
	v_cndmask_b32_e64 v132, v138, 1.0, s[20:21]
	v_rcp_f32_e32 v138, v129
	v_and_b32_e32 v134, 0xffff0000, v134
	v_max_f32_e32 v131, 0x358637bd, v131
	v_mul_f32_e32 v129, v131, v132
	v_max_f32_e32 v131, v134, v134
	v_max_f32_e32 v134, v144, v144
	v_max_f32_e32 v134, 0x358637bd, v134
	v_lshlrev_b32_e32 v139, 16, v133
	v_max_f32_e32 v131, 0x358637bd, v131
	v_cndmask_b32_e64 v132, v138, 1.0, s[20:21]
	v_rcp_f32_e32 v134, v134
	v_max_f32_e32 v138, v146, v146
	v_mul_f32_e32 v131, v131, v132
	v_max_f32_e32 v132, v139, v139
	v_max_f32_e32 v138, 0x358637bd, v138
	v_max_f32_e32 v139, v145, v145
	v_rcp_f32_e32 v138, v138
	v_max_f32_e32 v139, 0x358637bd, v139
	v_rcp_f32_e32 v139, v139
	v_lshlrev_b32_e32 v141, 16, v135
	v_max_f32_e32 v132, 0x358637bd, v132
	v_cndmask_b32_e64 v134, v134, 1.0, s[20:21]
	v_mul_f32_e32 v132, v132, v134
	v_max_f32_e32 v134, v141, v141
	v_max_f32_e32 v134, 0x358637bd, v134
	v_cndmask_b32_e64 v138, v138, 1.0, s[20:21]
	v_mul_f32_e32 v134, v134, v138
	v_cndmask_b32_e64 v138, v139, 1.0, s[20:21]
	v_max_f32_e32 v139, v142, v142
	v_max_f32_e32 v139, 0x358637bd, v139
	v_rcp_f32_e32 v139, v139
	v_and_b32_e32 v133, 0xffff0000, v133
	v_and_b32_e32 v135, 0xffff0000, v135
	v_max_f32_e32 v133, v133, v133
	v_max_f32_e32 v133, 0x358637bd, v133
	v_max_f32_e32 v135, v135, v135
	v_mul_f32_e32 v133, v133, v138
	v_max_f32_e32 v135, 0x358637bd, v135
	v_cndmask_b32_e64 v138, v139, 1.0, s[20:21]
	v_mul_f32_e32 v135, v135, v138
	v_pk_mul_f32 v[70:71], v[70:71], v[132:133]
	v_pk_mul_f32 v[68:69], v[68:69], v[128:129]
	v_pk_mul_f32 v[66:67], v[66:67], v[134:135]
	s_and_b64 vcc, exec, s[4:5]
	v_pk_mul_f32 v[64:65], v[64:65], v[130:131]
	s_cbranch_vccnz .LBB0_840
	v_cvt_pk_bf16_f32 v128, v68, v69
	v_cvt_pk_bf16_f32 v129, v70, v71
	v_cvt_pk_bf16_f32 v130, v64, v65
	v_cvt_pk_bf16_f32 v131, v66, v67
	global_store_dwordx4 v[136:137], v[128:131], off offset:256 sc1
; __device__ __forceinline__ unsigned cvt_pk_bf16(float lo, float hi) { unsigned r; asm volatile("v_cvt_pk_bf16_f32 %0, %1, %2" : "=v"(r) : "v"(lo), "v"(hi)); return r; }
; __device__ __forceinline__ float bflo(unsigned w) { return __uint_as_float(w << 16); }
; __device__ __forceinline__ float bfhi(unsigned w) { return __uint_as_float(w & 0xffff0000u); }
;     __device__ __forceinline__ void operator()(f32x4 (&acc)[2][2][4][2], const Unit& u, int wr, int wc, int fr, int fq) const {
;     ...
;                 u32x4 ga[2][2], gb[2][2];
; #pragma unroll
;                 for (int mm = 0; mm < 2; ++mm)
; #pragma unroll
;                     for (int bj = 0; bj < 2; ++bj) {
;                         const bf16_t* zp = Z + (size_t)(row0 + ai * HALF + (2 * m2 + mm) * 16) * NZ + koff + col0 + bj * HALF;
;                         ga[mm][bj] = *(const u32x4*)zp;
;                         gb[mm][bj] = *(const u32x4*)(zp + noff);
;                     }
; #pragma unroll
;                 for (int mm = 0; mm < 2; ++mm)
; #pragma unroll
;                     for (int bj = 0; bj < 2; ++bj) {
;                         const int m = 2 * m2 + mm;
;                         const u32x4 a4 = ga[mm][bj], b4 = gb[mm][bj];
;                         f32x4 g0 = (f32x4){bflo(a4.x), bfhi(a4.x), bflo(a4.y), bfhi(a4.y)}, g1 = (f32x4){bflo(a4.z), bfhi(a4.z), bflo(a4.w), bfhi(a4.w)};
;                         const f32x4 h0 = (f32x4){bflo(b4.x), bfhi(b4.x), bflo(b4.y), bfhi(b4.y)}, h1 = (f32x4){bflo(b4.z), bfhi(b4.z), bflo(b4.w), bfhi(b4.w)};
; #pragma unroll
;                         for (int j = 0; j < 4; ++j) {
;                             g0[j] = fmaxf(g0[j], 1e-6f) * (last ? 1.0f : __builtin_amdgcn_rcpf(fmaxf(h0[j], 1e-6f)));
;                             g1[j] = fmaxf(g1[j], 1e-6f) * (last ? 1.0f : __builtin_amdgcn_rcpf(fmaxf(h1[j], 1e-6f)));
;                         }
;                         acc[ai][bj][m][0] *= g0; acc[ai][bj][m][1] *= g1;
;                         if (last) {
;                             const f32x4 v0 = acc[ai][bj][m][0], v1 = acc[ai][bj][m][1];
;                             u32x4 w; w.x = cvt_pk_bf16(v0[0], v0[1]); w.y = cvt_pk_bf16(v0[2], v0[3]); w.z = cvt_pk_bf16(v1[0], v1[1]); w.w = cvt_pk_bf16(v1[2], v1[3]);
;                             *(u32x4*)(MB + (size_t)(row0 + ai * HALF + m * 16) * D + col0 + bj * HALF) = w;
;                         }
.LBB0_840:
	s_nop 1
	v_add_u32_e32 v128, 0x80, v168
	v_mov_b64_e32 v[130:131], s[22:23]
	v_mad_i64_i32 v[132:133], s[24:25], v128, s46, v[130:131]
	v_lshl_add_u64 v[132:133], v[132:133], 0, v[170:171]
	v_add_co_u32_e32 v134, vcc, 0x2000, v132
	v_add_u32_e32 v172, 0x90, v168
	s_nop 0
	v_addc_co_u32_e32 v135, vcc, 0, v133, vcc
	v_lshl_add_u64 v[132:133], v[132:133], 0, s[12:13]
	global_load_dwordx4 v[184:187], v[134:135], off offset:2048
	v_lshl_add_u64 v[134:135], v[132:133], 0, s[0:1]
	global_load_dwordx4 v[188:191], v[134:135], off
	v_mad_i64_i32 v[130:131], s[24:25], v172, s46, v[130:131]
	v_lshl_add_u64 v[130:131], v[130:131], 0, v[170:171]
	v_ashrrev_i32_e32 v129, 31, v128
	v_lshl_add_u64 v[192:193], v[130:131], 0, s[12:13]
	v_add_co_u32_e32 v140, vcc, s37, v130
	v_lshlrev_b64 v[174:175], 12, v[128:129]
	v_lshl_add_u64 v[128:129], v[192:193], 0, s[0:1]
	v_addc_co_u32_e32 v141, vcc, 0, v131, vcc
	global_load_dwordx4 v[148:151], v[132:133], off offset:256
	global_load_dwordx4 v[144:147], v[134:135], off offset:256
	global_load_dwordx4 v[136:139], v[128:129], off
	s_nop 0
	global_load_dwordx4 v[128:131], v[128:129], off offset:256
	s_nop 0
	global_load_dwordx4 v[140:143], v[140:141], off offset:2048
	s_nop 0
	global_load_dwordx4 v[132:135], v[192:193], off offset:256
	v_lshl_add_u64 v[174:175], s[58:59], 0, v[174:175]
	s_and_b64 vcc, exec, s[4:5]
	v_lshl_add_u64 v[174:175], v[166:167], 1, v[174:175]
	s_waitcnt vmcnt(7)
	v_lshlrev_b32_e32 v193, 16, v187
	v_and_b32_e32 v194, 0xffff0000, v187
	s_waitcnt vmcnt(6)
	v_lshlrev_b32_e32 v187, 16, v188
	v_and_b32_e32 v188, 0xffff0000, v188
	v_lshlrev_b32_e32 v196, 16, v190
	v_lshlrev_b32_e32 v169, 16, v184
	v_and_b32_e32 v173, 0xffff0000, v184
	v_lshlrev_b32_e32 v184, 16, v185
	v_and_b32_e32 v192, 0xffff0000, v185
	v_lshlrev_b32_e32 v185, 16, v186
	v_and_b32_e32 v186, 0xffff0000, v186
	v_lshlrev_b32_e32 v195, 16, v189
	v_and_b32_e32 v189, 0xffff0000, v189
	v_and_b32_e32 v190, 0xffff0000, v190
	v_max_f32_e32 v196, v196, v196
	v_max_f32_e32 v188, v188, v188
	v_max_f32_e32 v186, v186, v186
	v_max_f32_e32 v190, v190, v190
	v_max_f32_e32 v189, v189, v189
	v_max_f32_e32 v196, 0x358637bd, v196
	v_max_f32_e32 v188, 0x358637bd, v188
	v_max_f32_e32 v198, 0x358637bd, v186
	v_max_f32_e32 v186, 0x358637bd, v190
	v_max_f32_e32 v189, 0x358637bd, v189
	v_rcp_f32_e32 v196, v196
	v_rcp_f32_e32 v188, v188
	v_max_f32_e32 v187, v187, v187
	v_rcp_f32_e32 v186, v186
	v_rcp_f32_e32 v189, v189
	v_max_f32_e32 v184, v184, v184
	v_max_f32_e32 v195, v195, v195
	v_max_f32_e32 v187, 0x358637bd, v187
	v_lshlrev_b32_e32 v197, 16, v191
	v_max_f32_e32 v185, v185, v185
	v_max_f32_e32 v173, v173, v173
	v_max_f32_e32 v190, 0x358637bd, v184
	v_max_f32_e32 v184, 0x358637bd, v195
	v_rcp_f32_e32 v187, v187
	v_and_b32_e32 v191, 0xffff0000, v191
	v_max_f32_e32 v197, v197, v197
	v_max_f32_e32 v185, 0x358637bd, v185
	v_max_f32_e32 v173, 0x358637bd, v173
	v_rcp_f32_e32 v184, v184
	v_cndmask_b32_e64 v196, v196, 1.0, s[20:21]
	v_cndmask_b32_e64 v188, v188, 1.0, s[20:21]
	v_max_f32_e32 v195, 0x358637bd, v197
	v_cndmask_b32_e64 v197, v186, 1.0, s[20:21]
	v_mul_f32_e32 v186, v185, v196
	v_mul_f32_e32 v185, v173, v188
	v_cndmask_b32_e64 v173, v189, 1.0, s[20:21]
	v_max_f32_e32 v189, v191, v191
	v_max_f32_e32 v169, v169, v169
	v_max_f32_e32 v189, 0x358637bd, v189
	v_max_f32_e32 v169, 0x358637bd, v169
	v_rcp_f32_e32 v195, v195
	v_cndmask_b32_e64 v187, v187, 1.0, s[20:21]
	v_rcp_f32_e32 v191, v189
	v_cndmask_b32_e64 v199, v184, 1.0, s[20:21]
	v_mul_f32_e32 v184, v169, v187
	v_max_f32_e32 v169, v192, v192
	v_max_f32_e32 v169, 0x358637bd, v169
	v_max_f32_e32 v193, v193, v193
	v_mul_f32_e32 v189, v169, v173
	v_max_f32_e32 v169, v194, v194
	v_max_f32_e32 v193, 0x358637bd, v193
	v_cndmask_b32_e64 v195, v195, 1.0, s[20:21]
	v_max_f32_e32 v169, 0x358637bd, v169
	v_cndmask_b32_e64 v173, v191, 1.0, s[20:21]
	v_mul_f32_e32 v187, v198, v197
	v_mul_f32_e32 v188, v190, v199
	v_mul_f32_e32 v190, v193, v195
	v_mul_f32_e32 v191, v169, v173
	v_pk_mul_f32 v[62:63], v[62:63], v[188:189]
	v_pk_mul_f32 v[60:61], v[60:61], v[184:185]
	v_pk_mul_f32 v[58:59], v[58:59], v[190:191]
	v_pk_mul_f32 v[56:57], v[56:57], v[186:187]
	s_cbranch_vccnz .LBB0_842
	v_cvt_pk_bf16_f32 v184, v60, v61
	v_cvt_pk_bf16_f32 v185, v62, v63
	v_cvt_pk_bf16_f32 v186, v56, v57
	v_cvt_pk_bf16_f32 v187, v58, v59
	global_store_dwordx4 v[174:175], v[184:187], off sc1
; __device__ __forceinline__ unsigned cvt_pk_bf16(float lo, float hi) { unsigned r; asm volatile("v_cvt_pk_bf16_f32 %0, %1, %2" : "=v"(r) : "v"(lo), "v"(hi)); return r; }
; __device__ __forceinline__ float bflo(unsigned w) { return __uint_as_float(w << 16); }
; __device__ __forceinline__ float bfhi(unsigned w) { return __uint_as_float(w & 0xffff0000u); }
;     __device__ __forceinline__ void operator()(f32x4 (&acc)[2][2][4][2], const Unit& u, int wr, int wc, int fr, int fq) const {
;     ...
; #pragma unroll
;                 for (int mm = 0; mm < 2; ++mm)
; #pragma unroll
;                     for (int bj = 0; bj < 2; ++bj) {
;                         const int m = 2 * m2 + mm;
;                         const u32x4 a4 = ga[mm][bj], b4 = gb[mm][bj];
;                         f32x4 g0 = (f32x4){bflo(a4.x), bfhi(a4.x), bflo(a4.y), bfhi(a4.y)}, g1 = (f32x4){bflo(a4.z), bfhi(a4.z), bflo(a4.w), bfhi(a4.w)};
;                         const f32x4 h0 = (f32x4){bflo(b4.x), bfhi(b4.x), bflo(b4.y), bfhi(b4.y)}, h1 = (f32x4){bflo(b4.z), bfhi(b4.z), bflo(b4.w), bfhi(b4.w)};
; #pragma unroll
;                         for (int j = 0; j < 4; ++j) {
;                             g0[j] = fmaxf(g0[j], 1e-6f) * (last ? 1.0f : __builtin_amdgcn_rcpf(fmaxf(h0[j], 1e-6f)));
;                             g1[j] = fmaxf(g1[j], 1e-6f) * (last ? 1.0f : __builtin_amdgcn_rcpf(fmaxf(h1[j], 1e-6f)));
;                         }
;                         acc[ai][bj][m][0] *= g0; acc[ai][bj][m][1] *= g1;
;                         if (last) {
;                             const f32x4 v0 = acc[ai][bj][m][0], v1 = acc[ai][bj][m][1];
;                             u32x4 w; w.x = cvt_pk_bf16(v0[0], v0[1]); w.y = cvt_pk_bf16(v0[2], v0[3]); w.z = cvt_pk_bf16(v1[0], v1[1]); w.w = cvt_pk_bf16(v1[2], v1[3]);
;                             *(u32x4*)(MB + (size_t)(row0 + ai * HALF + m * 16) * D + col0 + bj * HALF) = w;
;                         }
.LBB0_842:
	s_waitcnt vmcnt(4)
	s_nop 0
	v_lshlrev_b32_e32 v186, 16, v144
	v_and_b32_e32 v187, 0xffff0000, v144
	v_lshlrev_b32_e32 v188, 16, v145
	v_and_b32_e32 v189, 0xffff0000, v145
	v_lshlrev_b32_e32 v144, 16, v146
	v_and_b32_e32 v145, 0xffff0000, v146
	v_max_f32_e32 v146, v186, v186
	v_max_f32_e32 v146, 0x358637bd, v146
	v_max_f32_e32 v144, v144, v144
	v_lshlrev_b32_e32 v169, 16, v148
	v_rcp_f32_e32 v146, v146
	v_max_f32_e32 v144, 0x358637bd, v144
	v_lshlrev_b32_e32 v190, 16, v147
	v_and_b32_e32 v186, 0xffff0000, v147
	v_max_f32_e32 v147, v169, v169
	v_rcp_f32_e32 v169, v144
	v_max_f32_e32 v147, 0x358637bd, v147
	v_cndmask_b32_e64 v146, v146, 1.0, s[20:21]
	v_mul_f32_e32 v144, v147, v146
	v_cndmask_b32_e64 v147, v169, 1.0, s[20:21]
	v_max_f32_e32 v169, v187, v187
	v_max_f32_e32 v169, 0x358637bd, v169
	v_rcp_f32_e32 v169, v169
	v_lshlrev_b32_e32 v184, 16, v150
	v_max_f32_e32 v146, v184, v184
	v_max_f32_e32 v145, v145, v145
	v_and_b32_e32 v148, 0xffff0000, v148
	v_max_f32_e32 v146, 0x358637bd, v146
	v_max_f32_e32 v145, 0x358637bd, v145
	v_mul_f32_e32 v146, v146, v147
	v_max_f32_e32 v147, v148, v148
	v_cndmask_b32_e64 v148, v169, 1.0, s[20:21]
	v_rcp_f32_e32 v169, v145
	v_and_b32_e32 v150, 0xffff0000, v150
	v_max_f32_e32 v147, 0x358637bd, v147
	v_mul_f32_e32 v145, v147, v148
	v_max_f32_e32 v147, v150, v150
	v_max_f32_e32 v150, v188, v188
	v_max_f32_e32 v150, 0x358637bd, v150
	v_lshlrev_b32_e32 v173, 16, v149
	v_max_f32_e32 v147, 0x358637bd, v147
	v_cndmask_b32_e64 v148, v169, 1.0, s[20:21]
	v_rcp_f32_e32 v150, v150
	v_max_f32_e32 v169, v190, v190
	v_mul_f32_e32 v147, v147, v148
	v_max_f32_e32 v148, v173, v173
	v_max_f32_e32 v169, 0x358637bd, v169
	v_max_f32_e32 v173, v189, v189
	v_rcp_f32_e32 v169, v169
	v_max_f32_e32 v173, 0x358637bd, v173
	v_rcp_f32_e32 v173, v173
	v_lshlrev_b32_e32 v185, 16, v151
	v_max_f32_e32 v148, 0x358637bd, v148
	v_cndmask_b32_e64 v150, v150, 1.0, s[20:21]
	v_mul_f32_e32 v148, v148, v150
	v_max_f32_e32 v150, v185, v185
	v_max_f32_e32 v150, 0x358637bd, v150
	v_cndmask_b32_e64 v169, v169, 1.0, s[20:21]
	v_mul_f32_e32 v150, v150, v169
	v_cndmask_b32_e64 v169, v173, 1.0, s[20:21]
	v_max_f32_e32 v173, v186, v186
	v_max_f32_e32 v173, 0x358637bd, v173
	v_rcp_f32_e32 v173, v173
	v_and_b32_e32 v149, 0xffff0000, v149
	v_and_b32_e32 v151, 0xffff0000, v151
	v_max_f32_e32 v149, v149, v149
	v_max_f32_e32 v149, 0x358637bd, v149
	v_max_f32_e32 v151, v151, v151
	v_mul_f32_e32 v149, v149, v169
	v_max_f32_e32 v151, 0x358637bd, v151
	v_cndmask_b32_e64 v169, v173, 1.0, s[20:21]
	v_mul_f32_e32 v151, v151, v169
	v_pk_mul_f32 v[30:31], v[30:31], v[148:149]
	v_pk_mul_f32 v[28:29], v[28:29], v[144:145]
	v_pk_mul_f32 v[26:27], v[26:27], v[150:151]
	s_and_b64 vcc, exec, s[4:5]
	v_pk_mul_f32 v[24:25], v[24:25], v[146:147]
	s_cbranch_vccnz .LBB0_844
	v_cvt_pk_bf16_f32 v144, v28, v29
	v_cvt_pk_bf16_f32 v145, v30, v31
	v_cvt_pk_bf16_f32 v146, v24, v25
	v_cvt_pk_bf16_f32 v147, v26, v27
	global_store_dwordx4 v[174:175], v[144:147], off offset:256 sc1
.LBB0_844:
	v_ashrrev_i32_e32 v173, 31, v172
	s_waitcnt vmcnt(3)
	v_lshlrev_b32_e32 v150, 16, v136
	v_lshlrev_b64 v[144:145], 12, v[172:173]
	v_and_b32_e32 v151, 0xffff0000, v136
	v_lshlrev_b32_e32 v169, 16, v137
	v_and_b32_e32 v172, 0xffff0000, v137
	v_lshlrev_b32_e32 v136, 16, v138
	v_and_b32_e32 v137, 0xffff0000, v138
	v_max_f32_e32 v138, v150, v150
	v_max_f32_e32 v138, 0x358637bd, v138
	v_max_f32_e32 v136, v136, v136
	s_waitcnt vmcnt(1)
	v_lshlrev_b32_e32 v146, 16, v140
	v_rcp_f32_e32 v138, v138
	v_max_f32_e32 v136, 0x358637bd, v136
	v_lshlrev_b32_e32 v173, 16, v139
	v_and_b32_e32 v150, 0xffff0000, v139
	v_max_f32_e32 v139, v146, v146
	v_rcp_f32_e32 v146, v136
	v_max_f32_e32 v139, 0x358637bd, v139
	v_cndmask_b32_e64 v138, v138, 1.0, s[20:21]
	v_mul_f32_e32 v136, v139, v138
	v_cndmask_b32_e64 v139, v146, 1.0, s[20:21]
	v_max_f32_e32 v146, v151, v151
	v_max_f32_e32 v146, 0x358637bd, v146
	v_rcp_f32_e32 v146, v146
	v_lshlrev_b32_e32 v148, 16, v142
	v_max_f32_e32 v138, v148, v148
	v_max_f32_e32 v137, v137, v137
	v_and_b32_e32 v140, 0xffff0000, v140
	v_max_f32_e32 v138, 0x358637bd, v138
	v_max_f32_e32 v137, 0x358637bd, v137
	v_mul_f32_e32 v138, v138, v139
	v_max_f32_e32 v139, v140, v140
	v_cndmask_b32_e64 v140, v146, 1.0, s[20:21]
	v_rcp_f32_e32 v146, v137
	v_and_b32_e32 v142, 0xffff0000, v142
	v_max_f32_e32 v139, 0x358637bd, v139
	v_mul_f32_e32 v137, v139, v140
	v_max_f32_e32 v139, v142, v142
	v_max_f32_e32 v142, v169, v169
	v_max_f32_e32 v142, 0x358637bd, v142
	v_lshlrev_b32_e32 v147, 16, v141
	v_max_f32_e32 v139, 0x358637bd, v139
	v_cndmask_b32_e64 v140, v146, 1.0, s[20:21]
	v_rcp_f32_e32 v142, v142
	v_max_f32_e32 v146, v173, v173
	v_mul_f32_e32 v139, v139, v140
	v_max_f32_e32 v140, v147, v147
	v_max_f32_e32 v146, 0x358637bd, v146
	v_max_f32_e32 v147, v172, v172
	v_rcp_f32_e32 v146, v146
	v_max_f32_e32 v147, 0x358637bd, v147
	v_rcp_f32_e32 v147, v147
	v_lshlrev_b32_e32 v149, 16, v143
	v_max_f32_e32 v140, 0x358637bd, v140
	v_cndmask_b32_e64 v142, v142, 1.0, s[20:21]
	v_mul_f32_e32 v140, v140, v142
	v_max_f32_e32 v142, v149, v149
	v_max_f32_e32 v142, 0x358637bd, v142
	v_cndmask_b32_e64 v146, v146, 1.0, s[20:21]
	v_mul_f32_e32 v142, v142, v146
	v_cndmask_b32_e64 v146, v147, 1.0, s[20:21]
	v_max_f32_e32 v147, v150, v150
	v_max_f32_e32 v147, 0x358637bd, v147
	v_rcp_f32_e32 v147, v147
	v_and_b32_e32 v141, 0xffff0000, v141
	v_and_b32_e32 v143, 0xffff0000, v143
	v_max_f32_e32 v141, v141, v141
	v_max_f32_e32 v141, 0x358637bd, v141
	v_max_f32_e32 v143, v143, v143
	v_mul_f32_e32 v141, v141, v146
	v_max_f32_e32 v143, 0x358637bd, v143
	v_cndmask_b32_e64 v146, v147, 1.0, s[20:21]
	v_mul_f32_e32 v143, v143, v146
	v_pk_mul_f32 v[52:53], v[52:53], v[136:137]
	v_lshl_add_u64 v[136:137], s[58:59], 0, v[144:145]
	v_pk_mul_f32 v[54:55], v[54:55], v[140:141]
	v_pk_mul_f32 v[50:51], v[50:51], v[142:143]
	v_pk_mul_f32 v[48:49], v[48:49], v[138:139]
	s_and_b64 vcc, exec, s[4:5]
	v_lshl_add_u64 v[136:137], v[166:167], 1, v[136:137]
	s_cbranch_vccnz .LBB0_846
	v_cvt_pk_bf16_f32 v138, v52, v53
	v_cvt_pk_bf16_f32 v139, v54, v55
	v_cvt_pk_bf16_f32 v140, v48, v49
	v_cvt_pk_bf16_f32 v141, v50, v51
	global_store_dwordx4 v[136:137], v[138:141], off sc1
; __device__ __forceinline__ unsigned cvt_pk_bf16(float lo, float hi) { unsigned r; asm volatile("v_cvt_pk_bf16_f32 %0, %1, %2" : "=v"(r) : "v"(lo), "v"(hi)); return r; }
; __device__ __forceinline__ float bflo(unsigned w) { return __uint_as_float(w << 16); }
; __device__ __forceinline__ float bfhi(unsigned w) { return __uint_as_float(w & 0xffff0000u); }
;     __device__ __forceinline__ void operator()(f32x4 (&acc)[2][2][4][2], const Unit& u, int wr, int wc, int fr, int fq) const {
;     ...
; #pragma unroll
;                 for (int mm = 0; mm < 2; ++mm)
; #pragma unroll
;                     for (int bj = 0; bj < 2; ++bj) {
;                         const int m = 2 * m2 + mm;
;                         const u32x4 a4 = ga[mm][bj], b4 = gb[mm][bj];
;                         f32x4 g0 = (f32x4){bflo(a4.x), bfhi(a4.x), bflo(a4.y), bfhi(a4.y)}, g1 = (f32x4){bflo(a4.z), bfhi(a4.z), bflo(a4.w), bfhi(a4.w)};
;                         const f32x4 h0 = (f32x4){bflo(b4.x), bfhi(b4.x), bflo(b4.y), bfhi(b4.y)}, h1 = (f32x4){bflo(b4.z), bfhi(b4.z), bflo(b4.w), bfhi(b4.w)};
; #pragma unroll
;                         for (int j = 0; j < 4; ++j) {
;                             g0[j] = fmaxf(g0[j], 1e-6f) * (last ? 1.0f : __builtin_amdgcn_rcpf(fmaxf(h0[j], 1e-6f)));
;                             g1[j] = fmaxf(g1[j], 1e-6f) * (last ? 1.0f : __builtin_amdgcn_rcpf(fmaxf(h1[j], 1e-6f)));
;                         }
;                         acc[ai][bj][m][0] *= g0; acc[ai][bj][m][1] *= g1;
;                         if (last) {
;                             const f32x4 v0 = acc[ai][bj][m][0], v1 = acc[ai][bj][m][1];
;                             u32x4 w; w.x = cvt_pk_bf16(v0[0], v0[1]); w.y = cvt_pk_bf16(v0[2], v0[3]); w.z = cvt_pk_bf16(v1[0], v1[1]); w.w = cvt_pk_bf16(v1[2], v1[3]);
;                             *(u32x4*)(MB + (size_t)(row0 + ai * HALF + m * 16) * D + col0 + bj * HALF) = w;
;                         }
.LBB0_846:
	v_lshlrev_b32_e32 v142, 16, v128
	v_and_b32_e32 v143, 0xffff0000, v128
	v_lshlrev_b32_e32 v144, 16, v129
	v_and_b32_e32 v145, 0xffff0000, v129
	v_lshlrev_b32_e32 v128, 16, v130
	v_and_b32_e32 v129, 0xffff0000, v130
	v_max_f32_e32 v130, v142, v142
	v_max_f32_e32 v130, 0x358637bd, v130
	v_max_f32_e32 v128, v128, v128
	s_waitcnt vmcnt(0)
	v_lshlrev_b32_e32 v138, 16, v132
	v_rcp_f32_e32 v130, v130
	v_max_f32_e32 v128, 0x358637bd, v128
	v_lshlrev_b32_e32 v146, 16, v131
	v_and_b32_e32 v142, 0xffff0000, v131
	v_max_f32_e32 v131, v138, v138
	v_rcp_f32_e32 v138, v128
	v_max_f32_e32 v131, 0x358637bd, v131
	v_cndmask_b32_e64 v130, v130, 1.0, s[20:21]
	v_mul_f32_e32 v128, v131, v130
	v_cndmask_b32_e64 v131, v138, 1.0, s[20:21]
	v_max_f32_e32 v138, v143, v143
	v_max_f32_e32 v138, 0x358637bd, v138
	v_rcp_f32_e32 v138, v138
	v_lshlrev_b32_e32 v140, 16, v134
	v_max_f32_e32 v130, v140, v140
	v_max_f32_e32 v129, v129, v129
	v_and_b32_e32 v132, 0xffff0000, v132
	v_max_f32_e32 v130, 0x358637bd, v130
	v_max_f32_e32 v129, 0x358637bd, v129
	v_mul_f32_e32 v130, v130, v131
	v_max_f32_e32 v131, v132, v132
	v_cndmask_b32_e64 v132, v138, 1.0, s[20:21]
	v_rcp_f32_e32 v138, v129
	v_and_b32_e32 v134, 0xffff0000, v134
	v_max_f32_e32 v131, 0x358637bd, v131
	v_mul_f32_e32 v129, v131, v132
	v_max_f32_e32 v131, v134, v134
	v_max_f32_e32 v134, v144, v144
	v_max_f32_e32 v134, 0x358637bd, v134
	v_lshlrev_b32_e32 v139, 16, v133
	v_max_f32_e32 v131, 0x358637bd, v131
	v_cndmask_b32_e64 v132, v138, 1.0, s[20:21]
	v_rcp_f32_e32 v134, v134
	v_max_f32_e32 v138, v146, v146
	v_mul_f32_e32 v131, v131, v132
	v_max_f32_e32 v132, v139, v139
	v_max_f32_e32 v138, 0x358637bd, v138
	v_max_f32_e32 v139, v145, v145
	v_rcp_f32_e32 v138, v138
	v_max_f32_e32 v139, 0x358637bd, v139
	v_rcp_f32_e32 v139, v139
	v_lshlrev_b32_e32 v141, 16, v135
	v_max_f32_e32 v132, 0x358637bd, v132
	v_cndmask_b32_e64 v134, v134, 1.0, s[20:21]
	v_mul_f32_e32 v132, v132, v134
	v_max_f32_e32 v134, v141, v141
	v_max_f32_e32 v134, 0x358637bd, v134
	v_cndmask_b32_e64 v138, v138, 1.0, s[20:21]
	v_mul_f32_e32 v134, v134, v138
	v_cndmask_b32_e64 v138, v139, 1.0, s[20:21]
	v_max_f32_e32 v139, v142, v142
	v_max_f32_e32 v139, 0x358637bd, v139
	v_rcp_f32_e32 v139, v139
	v_and_b32_e32 v133, 0xffff0000, v133
	v_and_b32_e32 v135, 0xffff0000, v135
	v_max_f32_e32 v133, v133, v133
	v_max_f32_e32 v133, 0x358637bd, v133
	v_max_f32_e32 v135, v135, v135
	v_mul_f32_e32 v133, v133, v138
	v_max_f32_e32 v135, 0x358637bd, v135
	v_cndmask_b32_e64 v138, v139, 1.0, s[20:21]
	v_mul_f32_e32 v135, v135, v138
	v_pk_mul_f32 v[22:23], v[22:23], v[132:133]
	v_pk_mul_f32 v[20:21], v[20:21], v[128:129]
	v_pk_mul_f32 v[18:19], v[18:19], v[134:135]
	s_and_b64 vcc, exec, s[4:5]
	v_pk_mul_f32 v[16:17], v[16:17], v[130:131]
	s_cbranch_vccnz .LBB0_848
	v_cvt_pk_bf16_f32 v128, v20, v21
	v_cvt_pk_bf16_f32 v129, v22, v23
	v_cvt_pk_bf16_f32 v130, v16, v17
	v_cvt_pk_bf16_f32 v131, v18, v19
	global_store_dwordx4 v[136:137], v[128:131], off offset:256 sc1
.LBB0_848:
	s_nop 1
	v_add_u32_e32 v128, 0xa0, v168
	v_mov_b64_e32 v[130:131], s[22:23]
	v_mad_i64_i32 v[132:133], s[22:23], v128, s46, v[130:131]
	v_lshl_add_u64 v[132:133], v[132:133], 0, v[170:171]
	v_add_co_u32_e32 v134, vcc, 0x2000, v132
	v_add_u32_e32 v168, 0xb0, v168
	s_nop 0
	v_addc_co_u32_e32 v135, vcc, 0, v133, vcc
	v_lshl_add_u64 v[132:133], v[132:133], 0, s[12:13]
	global_load_dwordx4 v[172:175], v[134:135], off offset:2048
	v_lshl_add_u64 v[134:135], v[132:133], 0, s[0:1]
	global_load_dwordx4 v[184:187], v[134:135], off
	v_mad_i64_i32 v[130:131], s[22:23], v168, s46, v[130:131]
	v_lshl_add_u64 v[130:131], v[130:131], 0, v[170:171]
	v_ashrrev_i32_e32 v129, 31, v128
	v_lshl_add_u64 v[188:189], v[130:131], 0, s[12:13]
	v_add_co_u32_e32 v140, vcc, s37, v130
	v_lshlrev_b64 v[170:171], 12, v[128:129]
	v_lshl_add_u64 v[128:129], v[188:189], 0, s[0:1]
	v_addc_co_u32_e32 v141, vcc, 0, v131, vcc
	global_load_dwordx4 v[148:151], v[132:133], off offset:256
	global_load_dwordx4 v[144:147], v[134:135], off offset:256
	global_load_dwordx4 v[136:139], v[128:129], off
	s_nop 0
	global_load_dwordx4 v[128:131], v[128:129], off offset:256
	s_nop 0
	global_load_dwordx4 v[140:143], v[140:141], off offset:2048
	s_nop 0
	global_load_dwordx4 v[132:135], v[188:189], off offset:256
	v_lshl_add_u64 v[170:171], s[58:59], 0, v[170:171]
	s_and_b64 vcc, exec, s[4:5]
	v_lshl_add_u64 v[170:171], v[166:167], 1, v[170:171]
	s_waitcnt vmcnt(7)
	v_lshlrev_b32_e32 v190, 16, v175
	v_and_b32_e32 v191, 0xffff0000, v175
	s_waitcnt vmcnt(6)
; __device__ __forceinline__ unsigned cvt_pk_bf16(float lo, float hi) { unsigned r; asm volatile("v_cvt_pk_bf16_f32 %0, %1, %2" : "=v"(r) : "v"(lo), "v"(hi)); return r; }
; __device__ __forceinline__ float bflo(unsigned w) { return __uint_as_float(w << 16); }
; __device__ __forceinline__ float bfhi(unsigned w) { return __uint_as_float(w & 0xffff0000u); }
;     __device__ __forceinline__ void operator()(f32x4 (&acc)[2][2][4][2], const Unit& u, int wr, int wc, int fr, int fq) const {
;     ...
; #pragma unroll
;                 for (int mm = 0; mm < 2; ++mm)
; #pragma unroll
;                     for (int bj = 0; bj < 2; ++bj) {
;                         const int m = 2 * m2 + mm;
;                         const u32x4 a4 = ga[mm][bj], b4 = gb[mm][bj];
;                         f32x4 g0 = (f32x4){bflo(a4.x), bfhi(a4.x), bflo(a4.y), bfhi(a4.y)}, g1 = (f32x4){bflo(a4.z), bfhi(a4.z), bflo(a4.w), bfhi(a4.w)};
;                         const f32x4 h0 = (f32x4){bflo(b4.x), bfhi(b4.x), bflo(b4.y), bfhi(b4.y)}, h1 = (f32x4){bflo(b4.z), bfhi(b4.z), bflo(b4.w), bfhi(b4.w)};
; #pragma unroll
;                         for (int j = 0; j < 4; ++j) {
;                             g0[j] = fmaxf(g0[j], 1e-6f) * (last ? 1.0f : __builtin_amdgcn_rcpf(fmaxf(h0[j], 1e-6f)));
;                             g1[j] = fmaxf(g1[j], 1e-6f) * (last ? 1.0f : __builtin_amdgcn_rcpf(fmaxf(h1[j], 1e-6f)));
;                         }
;                         acc[ai][bj][m][0] *= g0; acc[ai][bj][m][1] *= g1;
;                         if (last) {
;                             const f32x4 v0 = acc[ai][bj][m][0], v1 = acc[ai][bj][m][1];
;                             u32x4 w; w.x = cvt_pk_bf16(v0[0], v0[1]); w.y = cvt_pk_bf16(v0[2], v0[3]); w.z = cvt_pk_bf16(v1[0], v1[1]); w.w = cvt_pk_bf16(v1[2], v1[3]);
;                             *(u32x4*)(MB + (size_t)(row0 + ai * HALF + m * 16) * D + col0 + bj * HALF) = w;
;                         }
	v_lshlrev_b32_e32 v175, 16, v184
	v_lshlrev_b32_e32 v169, 16, v172
	v_and_b32_e32 v172, 0xffff0000, v172
	v_and_b32_e32 v184, 0xffff0000, v184
	v_max_f32_e32 v175, v175, v175
	v_lshlrev_b32_e32 v192, 16, v185
	v_and_b32_e32 v185, 0xffff0000, v185
	v_max_f32_e32 v172, v172, v172
	v_max_f32_e32 v184, v184, v184
	v_max_f32_e32 v175, 0x358637bd, v175
	v_max_f32_e32 v185, v185, v185
	v_max_f32_e32 v195, 0x358637bd, v172
	v_max_f32_e32 v172, 0x358637bd, v184
	v_rcp_f32_e32 v175, v175
	v_lshlrev_b32_e32 v188, 16, v173
	v_and_b32_e32 v189, 0xffff0000, v173
	v_lshlrev_b32_e32 v173, 16, v174
	v_and_b32_e32 v174, 0xffff0000, v174
	v_lshlrev_b32_e32 v193, 16, v186
	v_and_b32_e32 v186, 0xffff0000, v186
	v_lshlrev_b32_e32 v194, 16, v187
	v_and_b32_e32 v187, 0xffff0000, v187
	v_max_f32_e32 v185, 0x358637bd, v185
	v_rcp_f32_e32 v172, v172
	v_max_f32_e32 v193, v193, v193
	v_max_f32_e32 v174, v174, v174
	v_max_f32_e32 v186, v186, v186
	v_max_f32_e32 v188, v188, v188
	v_max_f32_e32 v192, v192, v192
	v_max_f32_e32 v194, v194, v194
	v_rcp_f32_e32 v185, v185
	v_max_f32_e32 v187, v187, v187
	v_max_f32_e32 v169, v169, v169
	v_max_f32_e32 v193, 0x358637bd, v193
	v_max_f32_e32 v184, 0x358637bd, v174
	v_max_f32_e32 v174, 0x358637bd, v186
	v_max_f32_e32 v186, 0x358637bd, v188
	v_max_f32_e32 v188, 0x358637bd, v192
	v_max_f32_e32 v192, 0x358637bd, v194
	v_max_f32_e32 v187, 0x358637bd, v187
	v_max_f32_e32 v169, 0x358637bd, v169
	v_rcp_f32_e32 v193, v193
	v_rcp_f32_e32 v174, v174
	v_rcp_f32_e32 v188, v188
	v_rcp_f32_e32 v192, v192
	v_cndmask_b32_e64 v175, v175, 1.0, s[20:21]
	v_rcp_f32_e32 v187, v187
	v_cndmask_b32_e64 v194, v172, 1.0, s[20:21]
	v_mul_f32_e32 v172, v169, v175
	v_max_f32_e32 v169, v189, v189
	v_max_f32_e32 v169, 0x358637bd, v169
	v_cndmask_b32_e64 v185, v185, 1.0, s[20:21]
	v_max_f32_e32 v173, v173, v173
	v_max_f32_e32 v190, v190, v190
	v_mul_f32_e32 v185, v169, v185
	v_max_f32_e32 v169, v191, v191
	v_max_f32_e32 v173, 0x358637bd, v173
	v_max_f32_e32 v190, 0x358637bd, v190
	v_cndmask_b32_e64 v193, v193, 1.0, s[20:21]
	v_cndmask_b32_e64 v196, v174, 1.0, s[20:21]
	v_cndmask_b32_e64 v188, v188, 1.0, s[20:21]
	v_cndmask_b32_e64 v192, v192, 1.0, s[20:21]
	v_max_f32_e32 v169, 0x358637bd, v169
	v_cndmask_b32_e64 v187, v187, 1.0, s[20:21]
	v_mul_f32_e32 v174, v173, v193
	v_mul_f32_e32 v173, v195, v194
	v_mul_f32_e32 v175, v184, v196
	v_mul_f32_e32 v184, v186, v188
	v_mul_f32_e32 v186, v190, v192
	v_mul_f32_e32 v187, v169, v187
	v_pk_mul_f32 v[46:47], v[46:47], v[184:185]
	v_pk_mul_f32 v[44:45], v[44:45], v[172:173]
	v_pk_mul_f32 v[42:43], v[42:43], v[186:187]
	v_pk_mul_f32 v[40:41], v[40:41], v[174:175]
	s_cbranch_vccnz .LBB0_850
	v_cvt_pk_bf16_f32 v172, v44, v45
	v_cvt_pk_bf16_f32 v173, v46, v47
	v_cvt_pk_bf16_f32 v174, v40, v41
	v_cvt_pk_bf16_f32 v175, v42, v43
	global_store_dwordx4 v[170:171], v[172:175], off sc1
.LBB0_850:
	s_waitcnt vmcnt(4)
	s_nop 0
	v_lshlrev_b32_e32 v175, 16, v144
	v_and_b32_e32 v184, 0xffff0000, v144
	v_lshlrev_b32_e32 v185, 16, v145
	v_and_b32_e32 v186, 0xffff0000, v145
	v_lshlrev_b32_e32 v144, 16, v146
	v_and_b32_e32 v145, 0xffff0000, v146
	v_max_f32_e32 v146, v175, v175
	v_max_f32_e32 v146, 0x358637bd, v146
	v_max_f32_e32 v144, v144, v144
	v_lshlrev_b32_e32 v169, 16, v148
	v_rcp_f32_e32 v146, v146
	v_max_f32_e32 v144, 0x358637bd, v144
	v_lshlrev_b32_e32 v187, 16, v147
	v_and_b32_e32 v175, 0xffff0000, v147
	v_max_f32_e32 v147, v169, v169
	v_rcp_f32_e32 v169, v144
	v_max_f32_e32 v147, 0x358637bd, v147
	v_cndmask_b32_e64 v146, v146, 1.0, s[20:21]
	v_mul_f32_e32 v144, v147, v146
	v_cndmask_b32_e64 v147, v169, 1.0, s[20:21]
	v_max_f32_e32 v169, v184, v184
	v_max_f32_e32 v169, 0x358637bd, v169
	v_rcp_f32_e32 v169, v169
	v_lshlrev_b32_e32 v173, 16, v150
	v_max_f32_e32 v146, v173, v173
	v_max_f32_e32 v145, v145, v145
	v_and_b32_e32 v148, 0xffff0000, v148
	v_max_f32_e32 v146, 0x358637bd, v146
	v_max_f32_e32 v145, 0x358637bd, v145
	v_mul_f32_e32 v146, v146, v147
	v_max_f32_e32 v147, v148, v148
	v_cndmask_b32_e64 v148, v169, 1.0, s[20:21]
	v_rcp_f32_e32 v169, v145
	v_and_b32_e32 v150, 0xffff0000, v150
	v_max_f32_e32 v147, 0x358637bd, v147
	v_mul_f32_e32 v145, v147, v148
	v_max_f32_e32 v147, v150, v150
	v_max_f32_e32 v150, v185, v185
	v_max_f32_e32 v150, 0x358637bd, v150
	v_lshlrev_b32_e32 v172, 16, v149
	v_max_f32_e32 v147, 0x358637bd, v147
	v_cndmask_b32_e64 v148, v169, 1.0, s[20:21]
	v_rcp_f32_e32 v150, v150
	v_max_f32_e32 v169, v187, v187
	v_mul_f32_e32 v147, v147, v148
	v_max_f32_e32 v148, v172, v172
	v_max_f32_e32 v169, 0x358637bd, v169
	v_max_f32_e32 v172, v186, v186
	v_rcp_f32_e32 v169, v169
	v_max_f32_e32 v172, 0x358637bd, v172
	v_rcp_f32_e32 v172, v172
	v_lshlrev_b32_e32 v174, 16, v151
	v_max_f32_e32 v148, 0x358637bd, v148
	v_cndmask_b32_e64 v150, v150, 1.0, s[20:21]
	v_mul_f32_e32 v148, v148, v150
	v_max_f32_e32 v150, v174, v174
	v_max_f32_e32 v150, 0x358637bd, v150
	v_cndmask_b32_e64 v169, v169, 1.0, s[20:21]
	v_mul_f32_e32 v150, v150, v169
	v_cndmask_b32_e64 v169, v172, 1.0, s[20:21]
	v_max_f32_e32 v172, v175, v175
	v_max_f32_e32 v172, 0x358637bd, v172
	v_rcp_f32_e32 v172, v172
	v_and_b32_e32 v149, 0xffff0000, v149
	v_and_b32_e32 v151, 0xffff0000, v151
	v_max_f32_e32 v149, v149, v149
	v_max_f32_e32 v149, 0x358637bd, v149
	v_max_f32_e32 v151, v151, v151
	v_mul_f32_e32 v149, v149, v169
	v_max_f32_e32 v151, 0x358637bd, v151
	v_cndmask_b32_e64 v169, v172, 1.0, s[20:21]
	v_mul_f32_e32 v151, v151, v169
	v_pk_mul_f32 v[14:15], v[14:15], v[148:149]
	v_pk_mul_f32 v[12:13], v[12:13], v[144:145]
	v_pk_mul_f32 v[10:11], v[10:11], v[150:151]
	s_and_b64 vcc, exec, s[4:5]
	v_pk_mul_f32 v[8:9], v[8:9], v[146:147]
	s_cbranch_vccnz .LBB0_852
	v_cvt_pk_bf16_f32 v144, v12, v13
	v_cvt_pk_bf16_f32 v145, v14, v15
	v_cvt_pk_bf16_f32 v146, v8, v9
	v_cvt_pk_bf16_f32 v147, v10, v11
	global_store_dwordx4 v[170:171], v[144:147], off offset:256 sc1
; __device__ __forceinline__ unsigned cvt_pk_bf16(float lo, float hi) { unsigned r; asm volatile("v_cvt_pk_bf16_f32 %0, %1, %2" : "=v"(r) : "v"(lo), "v"(hi)); return r; }
; __device__ __forceinline__ float bflo(unsigned w) { return __uint_as_float(w << 16); }
; __device__ __forceinline__ float bfhi(unsigned w) { return __uint_as_float(w & 0xffff0000u); }
;     __device__ __forceinline__ void operator()(f32x4 (&acc)[2][2][4][2], const Unit& u, int wr, int wc, int fr, int fq) const {
;     ...
; #pragma unroll
;                 for (int mm = 0; mm < 2; ++mm)
; #pragma unroll
;                     for (int bj = 0; bj < 2; ++bj) {
;                         const int m = 2 * m2 + mm;
;                         const u32x4 a4 = ga[mm][bj], b4 = gb[mm][bj];
;                         f32x4 g0 = (f32x4){bflo(a4.x), bfhi(a4.x), bflo(a4.y), bfhi(a4.y)}, g1 = (f32x4){bflo(a4.z), bfhi(a4.z), bflo(a4.w), bfhi(a4.w)};
;                         const f32x4 h0 = (f32x4){bflo(b4.x), bfhi(b4.x), bflo(b4.y), bfhi(b4.y)}, h1 = (f32x4){bflo(b4.z), bfhi(b4.z), bflo(b4.w), bfhi(b4.w)};
; #pragma unroll
;                         for (int j = 0; j < 4; ++j) {
;                             g0[j] = fmaxf(g0[j], 1e-6f) * (last ? 1.0f : __builtin_amdgcn_rcpf(fmaxf(h0[j], 1e-6f)));
;                             g1[j] = fmaxf(g1[j], 1e-6f) * (last ? 1.0f : __builtin_amdgcn_rcpf(fmaxf(h1[j], 1e-6f)));
;                         }
;                         acc[ai][bj][m][0] *= g0; acc[ai][bj][m][1] *= g1;
;                         if (last) {
;                             const f32x4 v0 = acc[ai][bj][m][0], v1 = acc[ai][bj][m][1];
;                             u32x4 w; w.x = cvt_pk_bf16(v0[0], v0[1]); w.y = cvt_pk_bf16(v0[2], v0[3]); w.z = cvt_pk_bf16(v1[0], v1[1]); w.w = cvt_pk_bf16(v1[2], v1[3]);
;                             *(u32x4*)(MB + (size_t)(row0 + ai * HALF + m * 16) * D + col0 + bj * HALF) = w;
;                         }
.LBB0_852:
	v_ashrrev_i32_e32 v169, 31, v168
	s_waitcnt vmcnt(3)
	v_lshlrev_b32_e32 v150, 16, v136
	v_lshlrev_b64 v[144:145], 12, v[168:169]
	v_and_b32_e32 v151, 0xffff0000, v136
	v_lshlrev_b32_e32 v168, 16, v137
	v_and_b32_e32 v169, 0xffff0000, v137
	v_lshlrev_b32_e32 v136, 16, v138
	v_and_b32_e32 v137, 0xffff0000, v138
	v_max_f32_e32 v138, v150, v150
	v_max_f32_e32 v138, 0x358637bd, v138
	v_max_f32_e32 v136, v136, v136
	s_waitcnt vmcnt(1)
	v_lshlrev_b32_e32 v146, 16, v140
	v_rcp_f32_e32 v138, v138
	v_max_f32_e32 v136, 0x358637bd, v136
	v_lshlrev_b32_e32 v170, 16, v139
	v_and_b32_e32 v150, 0xffff0000, v139
	v_max_f32_e32 v139, v146, v146
	v_rcp_f32_e32 v146, v136
	v_max_f32_e32 v139, 0x358637bd, v139
	v_cndmask_b32_e64 v138, v138, 1.0, s[20:21]
	v_mul_f32_e32 v136, v139, v138
	v_cndmask_b32_e64 v139, v146, 1.0, s[20:21]
	v_max_f32_e32 v146, v151, v151
	v_max_f32_e32 v146, 0x358637bd, v146
	v_rcp_f32_e32 v146, v146
	v_lshlrev_b32_e32 v148, 16, v142
	v_max_f32_e32 v138, v148, v148
	v_max_f32_e32 v137, v137, v137
	v_and_b32_e32 v140, 0xffff0000, v140
	v_max_f32_e32 v138, 0x358637bd, v138
	v_max_f32_e32 v137, 0x358637bd, v137
	v_mul_f32_e32 v138, v138, v139
	v_max_f32_e32 v139, v140, v140
	v_cndmask_b32_e64 v140, v146, 1.0, s[20:21]
	v_rcp_f32_e32 v146, v137
	v_and_b32_e32 v142, 0xffff0000, v142
	v_max_f32_e32 v139, 0x358637bd, v139
	v_mul_f32_e32 v137, v139, v140
	v_max_f32_e32 v139, v142, v142
	v_max_f32_e32 v142, v168, v168
	v_max_f32_e32 v142, 0x358637bd, v142
	v_lshlrev_b32_e32 v147, 16, v141
	v_max_f32_e32 v139, 0x358637bd, v139
	v_cndmask_b32_e64 v140, v146, 1.0, s[20:21]
	v_rcp_f32_e32 v142, v142
	v_max_f32_e32 v146, v170, v170
	v_mul_f32_e32 v139, v139, v140
	v_max_f32_e32 v140, v147, v147
	v_max_f32_e32 v146, 0x358637bd, v146
	v_max_f32_e32 v147, v169, v169
	v_rcp_f32_e32 v146, v146
	v_max_f32_e32 v147, 0x358637bd, v147
	v_rcp_f32_e32 v147, v147
	v_lshlrev_b32_e32 v149, 16, v143
	v_max_f32_e32 v140, 0x358637bd, v140
	v_cndmask_b32_e64 v142, v142, 1.0, s[20:21]
	v_mul_f32_e32 v140, v140, v142
	v_max_f32_e32 v142, v149, v149
	v_max_f32_e32 v142, 0x358637bd, v142
	v_cndmask_b32_e64 v146, v146, 1.0, s[20:21]
	v_mul_f32_e32 v142, v142, v146
	v_cndmask_b32_e64 v146, v147, 1.0, s[20:21]
	v_max_f32_e32 v147, v150, v150
	v_max_f32_e32 v147, 0x358637bd, v147
	v_rcp_f32_e32 v147, v147
	v_and_b32_e32 v141, 0xffff0000, v141
	v_and_b32_e32 v143, 0xffff0000, v143
	v_max_f32_e32 v141, v141, v141
	v_max_f32_e32 v141, 0x358637bd, v141
	v_max_f32_e32 v143, v143, v143
	v_mul_f32_e32 v141, v141, v146
	v_max_f32_e32 v143, 0x358637bd, v143
	v_cndmask_b32_e64 v146, v147, 1.0, s[20:21]
	v_mul_f32_e32 v143, v143, v146
	v_pk_mul_f32 v[36:37], v[36:37], v[136:137]
	v_lshl_add_u64 v[136:137], s[58:59], 0, v[144:145]
	v_pk_mul_f32 v[38:39], v[38:39], v[140:141]
	v_pk_mul_f32 v[34:35], v[34:35], v[142:143]
	v_pk_mul_f32 v[32:33], v[32:33], v[138:139]
	s_and_b64 vcc, exec, s[4:5]
	v_lshl_add_u64 v[136:137], v[166:167], 1, v[136:137]
	s_cbranch_vccnz .LBB0_854
	v_cvt_pk_bf16_f32 v138, v36, v37
	v_cvt_pk_bf16_f32 v139, v38, v39
	v_cvt_pk_bf16_f32 v140, v32, v33
	v_cvt_pk_bf16_f32 v141, v34, v35
	global_store_dwordx4 v[136:137], v[138:141], off sc1
.LBB0_854:
	v_lshlrev_b32_e32 v142, 16, v128
	v_and_b32_e32 v143, 0xffff0000, v128
	v_lshlrev_b32_e32 v144, 16, v129
	v_and_b32_e32 v145, 0xffff0000, v129
	v_lshlrev_b32_e32 v128, 16, v130
	v_and_b32_e32 v129, 0xffff0000, v130
	v_max_f32_e32 v130, v142, v142
	v_max_f32_e32 v130, 0x358637bd, v130
	v_max_f32_e32 v128, v128, v128
	s_waitcnt vmcnt(0)
	v_lshlrev_b32_e32 v138, 16, v132
	v_rcp_f32_e32 v130, v130
	v_max_f32_e32 v128, 0x358637bd, v128
	v_lshlrev_b32_e32 v146, 16, v131
	v_and_b32_e32 v142, 0xffff0000, v131
	v_max_f32_e32 v131, v138, v138
	v_rcp_f32_e32 v138, v128
	v_max_f32_e32 v131, 0x358637bd, v131
	v_cndmask_b32_e64 v130, v130, 1.0, s[20:21]
	v_mul_f32_e32 v128, v131, v130
	v_cndmask_b32_e64 v131, v138, 1.0, s[20:21]
	v_max_f32_e32 v138, v143, v143
	v_max_f32_e32 v138, 0x358637bd, v138
	v_rcp_f32_e32 v138, v138
	v_lshlrev_b32_e32 v140, 16, v134
	v_max_f32_e32 v130, v140, v140
	v_max_f32_e32 v129, v129, v129
	v_and_b32_e32 v132, 0xffff0000, v132
	v_max_f32_e32 v130, 0x358637bd, v130
	v_max_f32_e32 v129, 0x358637bd, v129
	v_mul_f32_e32 v130, v130, v131
	v_max_f32_e32 v131, v132, v132
	v_cndmask_b32_e64 v132, v138, 1.0, s[20:21]
	v_rcp_f32_e32 v138, v129
	v_and_b32_e32 v134, 0xffff0000, v134
	v_max_f32_e32 v131, 0x358637bd, v131
	v_mul_f32_e32 v129, v131, v132
	v_max_f32_e32 v131, v134, v134
	v_max_f32_e32 v134, v144, v144
	v_max_f32_e32 v134, 0x358637bd, v134
	v_lshlrev_b32_e32 v139, 16, v133
	v_max_f32_e32 v131, 0x358637bd, v131
	v_cndmask_b32_e64 v132, v138, 1.0, s[20:21]
	v_rcp_f32_e32 v134, v134
	v_max_f32_e32 v138, v146, v146
	v_mul_f32_e32 v131, v131, v132
	v_max_f32_e32 v132, v139, v139
	v_max_f32_e32 v138, 0x358637bd, v138
	v_max_f32_e32 v139, v145, v145
	v_rcp_f32_e32 v138, v138
	v_max_f32_e32 v139, 0x358637bd, v139
	v_rcp_f32_e32 v139, v139
	v_lshlrev_b32_e32 v141, 16, v135
	v_max_f32_e32 v132, 0x358637bd, v132
	v_cndmask_b32_e64 v134, v134, 1.0, s[20:21]
	v_mul_f32_e32 v132, v132, v134
	v_max_f32_e32 v134, v141, v141
	v_max_f32_e32 v134, 0x358637bd, v134
	v_cndmask_b32_e64 v138, v138, 1.0, s[20:21]
	v_mul_f32_e32 v134, v134, v138
	v_cndmask_b32_e64 v138, v139, 1.0, s[20:21]
	v_max_f32_e32 v139, v142, v142
	v_max_f32_e32 v139, 0x358637bd, v139
	v_rcp_f32_e32 v139, v139
	v_and_b32_e32 v133, 0xffff0000, v133
	v_and_b32_e32 v135, 0xffff0000, v135
	v_max_f32_e32 v133, v133, v133
	v_max_f32_e32 v133, 0x358637bd, v133
	v_max_f32_e32 v135, v135, v135
	v_mul_f32_e32 v133, v133, v138
	v_max_f32_e32 v135, 0x358637bd, v135
	v_cndmask_b32_e64 v138, v139, 1.0, s[20:21]
	v_mul_f32_e32 v135, v135, v138
	v_pk_mul_f32 v[6:7], v[6:7], v[132:133]
	v_pk_mul_f32 v[4:5], v[4:5], v[128:129]
	v_pk_mul_f32 v[2:3], v[2:3], v[134:135]
	s_and_b64 vcc, exec, s[4:5]
	v_pk_mul_f32 v[0:1], v[0:1], v[130:131]
	s_cbranch_vccnz .LBB0_856
	v_cvt_pk_bf16_f32 v128, v4, v5
	v_cvt_pk_bf16_f32 v129, v6, v7
	v_cvt_pk_bf16_f32 v130, v0, v1
	v_cvt_pk_bf16_f32 v131, v2, v3
	global_store_dwordx4 v[136:137], v[128:131], off offset:256 sc1

; __device__ __forceinline__ unsigned cvt_pk_bf16(float lo, float hi) { unsigned r; asm volatile("v_cvt_pk_bf16_f32 %0, %1, %2" : "=v"(r) : "v"(lo), "v"(hi)); return r; }
; __device__ __forceinline__ f32x2 ln_stats(f32x2 sm) { const float mu = sm[0] * (1.f / D); const float var = fmaxf(sm[1] * (1.f / D) - mu * mu, 0.f); return (f32x2){mu, 1.0f / sqrtf(var + LN_EPS)}; }
; template <int MODE> ...
;     ...
;         if (kh == 1) red[tw * 64 + lane] = tot;
;         __syncthreads();
;         if (kh == 0) {
;             tot += red[tw * 64 + lane];
;             const size_t off = (size_t)(rt * 16 + fr) * D + ct * 16 + 4 * fq;
;             if (MODE == 0) {
;                 f32x4 xv = *(const f32x4*)(res + off);
;                 if (rin) { const f32x2 st = ln_stats(*(const f32x2*)(rin + 2 * (rt * 16 + fr))); const int cc = ct * 16 + 4 * fq;
;                     xv = (xv - st[0]) * (*(const f32x4*)(lg + cc) * st[1]) + *(const f32x4*)(lb + cc); }
;                 const f32x4 o = xv * alpha + tot * scale;
;                 *(f32x4*)(Ys + off) = o;
;                 if (ybs) { u32x2 w; w.x = cvt_pk_bf16(o[0], o[1]); w.y = cvt_pk_bf16(o[2], o[3]); *(u32x2*)(ybs + off) = w; }
;                 if (rout) { float ps = (o[0] + o[1]) + (o[2] + o[3]), pq = (o[0] * o[0] + o[1] * o[1]) + (o[2] * o[2] + o[3] * o[3]);
;                     ps += __shfl_xor(ps, 16); pq += __shfl_xor(pq, 16); ps += __shfl_xor(ps, 32); pq += __shfl_xor(pq, 32);
;                     if (fq == 0) { atomicAdd(rout + 2 * (rt * 16 + fr), ps); atomicAdd(rout + 2 * (rt * 16 + fr) + 1, pq); } }
;             }
.LBB0_922:
	s_and_b64 vcc, exec, s[6:7]
	s_waitcnt lgkmcnt(0)
	s_barrier
	s_cbranch_vccnz .LBB0_917
	v_lshlrev_b32_e32 v10, 1, v12
	v_ashrrev_i32_e32 v11, 31, v10
	v_lshl_add_u64 v[14:15], v[10:11], 2, s[30:31]
	global_load_dwordx2 v[34:35], v[14:15], off
	s_and_b32 s0, s2, 0x7c
	s_or_b32 s0, s0, s56
	v_lshlrev_b64 v[36:37], 11, v[12:13]
	s_lshl_b32 s0, s0, 4
	v_or_b32_e32 v12, s0, v36
	v_or_b32_e32 v36, v12, v4
	v_lshl_add_u64 v[38:39], v[36:37], 2, s[50:51]
	global_load_dwordx4 v[12:15], v[38:39], off
	v_or_b32_e32 v22, s0, v4
	v_readlane_b32 s76, v254, 11
	v_lshlrev_b32_e32 v26, 2, v22
	v_readlane_b32 s78, v254, 13
	v_readlane_b32 s79, v254, 14
	v_readlane_b32 s80, v254, 15
	v_readlane_b32 s81, v254, 16
	s_nop 2
	global_load_dwordx4 v[22:25], v26, s[78:79]
	s_nop 0
	global_load_dwordx4 v[26:29], v26, s[80:81]
	ds_read_b128 v[30:33], v16
	v_cmp_lt_i32_e32 vcc, v19, v20
	v_readlane_b32 s77, v254, 12
	v_readlane_b32 s82, v254, 17
	v_cndmask_b32_e32 v40, v18, v19, vcc
	s_waitcnt lgkmcnt(0)
	v_pk_add_f32 v[0:1], v[0:1], v[30:31]
	v_pk_add_f32 v[2:3], v[2:3], v[32:33]
	v_lshlrev_b32_e32 v40, 2, v40
	v_readlane_b32 s83, v254, 18
	v_readlane_b32 s84, v254, 19
	v_readlane_b32 s85, v254, 20
	v_readlane_b32 s86, v254, 21
	v_readlane_b32 s87, v254, 22
	v_readlane_b32 s88, v254, 23
	v_readlane_b32 s89, v254, 24
	v_readlane_b32 s90, v254, 25
	v_readlane_b32 s91, v254, 26
	s_waitcnt vmcnt(3)
	v_pk_mul_f32 v[30:31], v[34:35], s[14:15] op_sel_hi:[1,0]
	s_nop 0
	v_fma_f32 v31, -v30, v30, v31
	v_max_f32_e32 v31, 0, v31
	v_add_f32_e32 v31, 0x3727c5ac, v31
	v_mul_f32_e32 v32, 0x4f800000, v31
	v_cmp_gt_f32_e32 vcc, s15, v31
	s_waitcnt vmcnt(2)
	v_sub_f32_e32 v15, v15, v30
	v_cndmask_b32_e32 v31, v31, v32, vcc
	v_sqrt_f32_e32 v32, v31
	v_sub_f32_e32 v14, v14, v30
	v_sub_f32_e32 v13, v13, v30
	v_sub_f32_e32 v12, v12, v30
	v_add_u32_e32 v33, -1, v32
	v_add_u32_e32 v34, 1, v32
	v_fma_f32 v35, -v33, v32, v31
	v_fma_f32 v41, -v34, v32, v31
	v_cmp_ge_f32_e64 s[0:1], 0, v35
	s_nop 1
	v_cndmask_b32_e64 v32, v32, v33, s[0:1]
	v_cmp_lt_f32_e64 s[0:1], 0, v41
	s_nop 1
	v_cndmask_b32_e64 v32, v32, v34, s[0:1]
	v_mul_f32_e32 v33, 0x37800000, v32
	v_cndmask_b32_e32 v32, v32, v33, vcc
	v_cmp_class_f32_e32 vcc, v31, v17
	s_nop 1
	v_cndmask_b32_e32 v31, v32, v31, vcc
	v_div_scale_f32 v32, s[0:1], v31, v31, 1.0
	v_rcp_f32_e32 v33, v32
	v_div_scale_f32 v30, vcc, 1.0, v31, 1.0
	v_fma_f32 v34, -v32, v33, 1.0
	v_fmac_f32_e32 v33, v34, v33
	v_mul_f32_e32 v34, v30, v33
	v_fma_f32 v35, -v32, v34, v30
	v_fmac_f32_e32 v34, v35, v33
	v_fma_f32 v30, -v32, v34, v30
	v_div_fmas_f32 v30, v30, v33, v34
	v_div_fixup_f32 v30, v30, v31, 1.0
	s_waitcnt vmcnt(1)
	v_pk_mul_f32 v[24:25], v[24:25], v[30:31] op_sel_hi:[1,0]
	v_pk_mul_f32 v[22:23], v[22:23], v[30:31] op_sel_hi:[1,0]
	s_waitcnt vmcnt(0)
	v_pk_fma_f32 v[14:15], v[14:15], v[24:25], v[28:29]
	v_pk_fma_f32 v[12:13], v[12:13], v[22:23], v[26:27]
	v_pk_fma_f32 v[14:15], v[14:15], s[16:17], v[2:3] op_sel_hi:[1,0,1]
	v_pk_fma_f32 v[12:13], v[12:13], s[16:17], v[0:1] op_sel_hi:[1,0,1]
	v_mul_f32_e32 v3, v15, v15
	v_mul_f32_e32 v2, v13, v13
	v_add_f32_e32 v0, v12, v13
	v_add_f32_e32 v1, v14, v15
	v_fmac_f32_e32 v2, v12, v12
	v_fmac_f32_e32 v3, v14, v14
	v_add_f32_e32 v0, v0, v1
	v_add_f32_e32 v1, v2, v3
	ds_bpermute_b32 v2, v40, v0
	ds_bpermute_b32 v3, v40, v1
	v_cmp_lt_i32_e32 vcc, v21, v20
	global_store_dwordx4 v[38:39], v[12:15], off sc1
	s_waitcnt lgkmcnt(1)
	v_add_f32_e32 v0, v0, v2
	v_cndmask_b32_e32 v22, v18, v21, vcc
	v_lshlrev_b32_e32 v22, 2, v22
	s_waitcnt lgkmcnt(0)
	v_add_f32_e32 v1, v1, v3
	ds_bpermute_b32 v2, v22, v0
	ds_bpermute_b32 v3, v22, v1
	v_cvt_pk_bf16_f32 v12, v12, v13
	v_cvt_pk_bf16_f32 v13, v14, v15
	v_lshl_add_u64 v[14:15], v[36:37], 1, s[8:9]
	global_store_dwordx2 v[14:15], v[12:13], off
	s_and_saveexec_b64 s[0:1], s[4:5]
	s_cbranch_execz .LBB0_916
	s_waitcnt lgkmcnt(0)
	v_add_f32_e32 v3, v1, v3
	v_add_f32_e32 v2, v0, v2
	v_lshl_add_u64 v[0:1], v[10:11], 2, s[10:11]
	global_atomic_add_f32 v[0:1], v2, off
	global_atomic_add_f32 v[0:1], v3, off offset:4
	s_branch .LBB0_916

;     __device__ __forceinline__ void operator()(const f32x4 (&acc)[2][2][4][2], const Unit& u, int wr, int wc, int fr, int fq) const {
;         const int row0 = u.pm * BM + wr * 64 + fr, col0 = u.pn * BM + wc * 32 + 4 * fq;
;         f32x4 gg[2][2], bb[2][2];
; #pragma unroll
;         for (int bj = 0; bj < 2; ++bj)
; #pragma unroll
;             for (int n = 0; n < 2; ++n) { gg[bj][n] = (f32x4){1.f, 1.f, 1.f, 1.f}; bb[bj][n] = (f32x4){0.f, 0.f, 0.f, 0.f};
;                 if (rin) { gg[bj][n] = *(const f32x4*)(lg + col0 + bj * HALF + n * 16); bb[bj][n] = *(const f32x4*)(lb + col0 + bj * HALF + n * 16); } }
; #pragma unroll
;         for (int ai = 0; ai < 2; ++ai)
; #pragma unroll
;             for (int m2 = 0; m2 < 2; ++m2) {
;                 f32x4 xv[2][2][2]; f32x2 st[2];
; #pragma unroll
;                 for (int mm = 0; mm < 2; ++mm) {
;                     const int r = row0 + ai * HALF + (2 * m2 + mm) * 16;
;                     st[mm] = (f32x2){0.f, 1.f};
;                     if (rin) st[mm] = ln_stats(*(const f32x2*)(rin + 2 * (size_t)r));
; #pragma unroll
;                     for (int bj = 0; bj < 2; ++bj)
; #pragma unroll
;                         for (int n = 0; n < 2; ++n) { const f32x4* rp = (const f32x4*)(res + (size_t)r * D + col0 + bj * HALF + n * 16); xv[mm][bj][n] = stream ? __builtin_nontemporal_load(rp) : *rp; }
;                 }
; #pragma unroll
;                 for (int mm = 0; mm < 2; ++mm) {
;                     const int r = row0 + ai * HALF + (2 * m2 + mm) * 16;
;                     float ps = 0.f, pq = 0.f;
; #pragma unroll
;                     for (int bj = 0; bj < 2; ++bj)
; #pragma unroll
;                         for (int n = 0; n < 2; ++n) {
;                             const f32x4 x = (xv[mm][bj][n] - st[mm][0]) * (gg[bj][n] * st[mm][1]) + bb[bj][n];
;                             const f32x4 o = x * alpha + acc[ai][bj][2 * m2 + mm][n] * scale;
;                             const size_t off = (size_t)r * D + col0 + bj * HALF + n * 16;
;                             *(f32x4*)(Y + off) = o;
;                             if (yb) { u32x2 w; w.x = cvt_pk_bf16(o[0], o[1]); w.y = cvt_pk_bf16(o[2], o[3]); *(u32x2*)(yb + off) = w; }
;                             ps += (o[0] + o[1]) + (o[2] + o[3]); pq += (o[0] * o[0] + o[1] * o[1]) + (o[2] * o[2] + o[3] * o[3]);
;                         }
.LBB0_948:
	v_lshl_add_u32 v194, s0, 8, v177
	v_ashrrev_i32_e32 v195, 31, v194
	v_lshlrev_b64 v[200:201], 3, v[194:195]
	v_lshl_add_u64 v[54:55], s[54:55], 0, v[200:201]
	global_load_dwordx2 v[230:231], v[54:55], off
	v_lshl_or_b32 v190, s60, 8, v208
	v_ashrrev_i32_e32 v191, 31, v190
	v_readlane_b32 s76, v254, 11
	v_lshlrev_b64 v[52:53], 2, v[190:191]
	v_readlane_b32 s78, v254, 13
	v_readlane_b32 s79, v254, 14
	v_lshl_add_u64 v[192:193], s[38:39], 0, v[52:53]
	v_lshlrev_b64 v[54:55], 13, v[194:195]
	v_readlane_b32 s80, v254, 15
	v_readlane_b32 s81, v254, 16
	s_mov_b64 s[42:43], s[78:79]
	v_lshl_add_u64 v[232:233], v[192:193], 0, v[54:55]
	s_mov_b64 s[44:45], s[80:81]
	v_lshl_add_u64 v[54:55], s[42:43], 0, v[52:53]
	global_load_dwordx4 v[214:217], v[232:233], off
	global_load_dwordx4 v[218:221], v[232:233], off offset:64
	global_load_dwordx4 v[92:95], v[54:55], off
	global_load_dwordx4 v[76:79], v[54:55], off offset:64
	v_lshl_add_u64 v[52:53], s[44:45], 0, v[52:53]
	global_load_dwordx4 v[88:91], v[52:53], off
	global_load_dwordx4 v[72:75], v[52:53], off offset:64
	v_lshlrev_b64 v[56:57], 11, v[194:195]
	v_or_b32_e32 v204, 16, v194
	v_lshl_add_u64 v[206:207], v[56:57], 0, v[190:191]
	global_load_dwordx4 v[68:71], v[54:55], off offset:512
	global_load_dwordx4 v[56:59], v[54:55], off offset:576
	global_load_dwordx4 v[64:67], v[52:53], off offset:512
	s_nop 0
	global_load_dwordx4 v[52:55], v[52:53], off offset:576
	v_ashrrev_i32_e32 v205, 31, v204
	v_lshlrev_b64 v[196:197], 3, v[204:205]
	v_lshlrev_b64 v[160:161], 13, v[204:205]
	v_lshl_add_u64 v[162:163], s[54:55], 0, v[196:197]
	v_lshl_add_u64 v[202:203], v[192:193], 0, v[160:161]
	global_load_dwordx4 v[222:225], v[232:233], off offset:512
	global_load_dwordx4 v[226:229], v[232:233], off offset:576
	global_load_dwordx2 v[198:199], v[162:163], off
	global_load_dwordx4 v[172:175], v[202:203], off
	global_load_dwordx4 v[168:171], v[202:203], off offset:64
	global_load_dwordx4 v[164:167], v[202:203], off offset:512
	s_nop 0
	global_load_dwordx4 v[160:163], v[202:203], off offset:576
	v_or_b32_e32 v240, 16, v206
	v_mov_b32_e32 v241, v207
	v_lshl_add_u64 v[238:239], v[206:207], 1, s[6:7]
	v_lshl_add_u64 v[242:243], v[240:241], 2, s[38:39]
	v_lshl_add_u64 v[240:241], v[240:241], 1, s[6:7]
	v_readlane_b32 s77, v254, 12
	v_readlane_b32 s82, v254, 17
	v_readlane_b32 s83, v254, 18
	v_readlane_b32 s84, v254, 19
	v_readlane_b32 s85, v254, 20
	v_readlane_b32 s86, v254, 21
	v_readlane_b32 s87, v254, 22
	v_readlane_b32 s88, v254, 23
	v_readlane_b32 s89, v254, 24
	v_readlane_b32 s90, v254, 25
	v_readlane_b32 s91, v254, 26
	s_waitcnt vmcnt(0)
	v_pk_mul_f32 v[230:231], v[230:231], s[18:19] op_sel_hi:[1,0]
	s_nop 0
	v_fma_f32 v195, -v230, v230, v231
	v_max_f32_e32 v195, 0, v195
	v_add_f32_e32 v195, 0x3727c5ac, v195
	v_mul_f32_e32 v231, 0x4f800000, v195
	v_cmp_gt_f32_e32 vcc, s52, v195
	v_sub_f32_e32 v217, v217, v230
	s_nop 0
	v_cndmask_b32_e32 v195, v195, v231, vcc
	v_sqrt_f32_e32 v231, v195
	v_sub_f32_e32 v216, v216, v230
	v_sub_f32_e32 v215, v215, v230
	v_sub_f32_e32 v214, v214, v230
	v_add_u32_e32 v237, -1, v231
	v_add_u32_e32 v244, 1, v231
	v_fma_f32 v245, -v237, v231, v195
	v_fma_f32 v246, -v244, v231, v195
	v_cmp_ge_f32_e64 s[0:1], 0, v245
	v_sub_f32_e32 v221, v221, v230
	v_sub_f32_e32 v220, v220, v230
	v_cndmask_b32_e64 v231, v231, v237, s[0:1]
	v_cmp_lt_f32_e64 s[0:1], 0, v246
	v_sub_f32_e32 v219, v219, v230
	v_sub_f32_e32 v218, v218, v230
	v_cndmask_b32_e64 v231, v231, v244, s[0:1]
	v_mul_f32_e32 v237, 0x37800000, v231
	v_cndmask_b32_e32 v231, v231, v237, vcc
	v_cmp_class_f32_e32 vcc, v195, v212
	s_nop 1
	v_cndmask_b32_e32 v195, v231, v195, vcc
	v_div_scale_f32 v231, s[0:1], v195, v195, 1.0
	v_rcp_f32_e32 v237, v231
	v_div_scale_f32 v244, vcc, 1.0, v195, 1.0
	v_fma_f32 v245, -v231, v237, 1.0
	v_fmac_f32_e32 v237, v245, v237
	v_mul_f32_e32 v245, v244, v237
	v_fma_f32 v246, -v231, v245, v244
	v_fmac_f32_e32 v245, v246, v237
	v_fma_f32 v231, -v231, v245, v244
	v_div_fmas_f32 v231, v231, v237, v245
	v_div_fixup_f32 v244, v231, v195, 1.0
	v_pk_mul_f32 v[246:247], v[94:95], v[244:245] op_sel_hi:[1,0]
	v_pk_mul_f32 v[248:249], v[92:93], v[244:245] op_sel_hi:[1,0]
	v_pk_mul_f32 v[250:251], v[78:79], v[244:245] op_sel_hi:[1,0]
	v_pk_mul_f32 v[252:253], v[76:77], v[244:245] op_sel_hi:[1,0]
	v_pk_fma_f32 v[214:215], v[214:215], v[248:249], v[88:89]
	v_pk_fma_f32 v[216:217], v[216:217], v[246:247], v[90:91]
	v_pk_fma_f32 v[218:219], v[218:219], v[252:253], v[72:73]
	v_pk_fma_f32 v[220:221], v[220:221], v[250:251], v[74:75]
	v_pk_fma_f32 v[158:159], v[216:217], s[20:21], v[158:159] op_sel_hi:[1,0,1]
	v_pk_fma_f32 v[156:157], v[214:215], s[20:21], v[156:157] op_sel_hi:[1,0,1]
	v_pk_fma_f32 v[154:155], v[220:221], s[20:21], v[154:155] op_sel_hi:[1,0,1]
	v_pk_fma_f32 v[152:153], v[218:219], s[20:21], v[152:153] op_sel_hi:[1,0,1]
	v_add_f32_e32 v195, v156, v157
	v_add_f32_e32 v216, v159, v158
	global_store_dwordx4 v[232:233], v[156:159], off sc1
	v_cvt_pk_bf16_f32 v214, v156, v157
	v_cvt_pk_bf16_f32 v215, v158, v159
	v_mul_f32_e32 v217, v157, v157
	v_add_f32_e32 v218, v152, v153
	v_mul_f32_e32 v158, v158, v158
	v_add_f32_e32 v219, v155, v154
	v_mul_f32_e32 v220, v153, v153
	v_mul_f32_e32 v221, v154, v154
	v_add_f32_e32 v195, v195, v216
	global_store_dwordx2 v[238:239], v[214:215], off
	v_fmac_f32_e32 v217, v156, v156
	v_fmac_f32_e32 v158, v159, v159
	global_store_dwordx4 v[242:243], v[152:155], off sc1
	v_cvt_pk_bf16_f32 v156, v152, v153
	v_fmac_f32_e32 v220, v152, v152
	v_fmac_f32_e32 v221, v155, v155
	v_add_f32_e32 v153, v218, v219
	v_add_f32_e32 v152, 0, v195
	v_cvt_pk_bf16_f32 v157, v154, v155
; __device__ __forceinline__ unsigned cvt_pk_bf16(float lo, float hi) { unsigned r; asm volatile("v_cvt_pk_bf16_f32 %0, %1, %2" : "=v"(r) : "v"(lo), "v"(hi)); return r; }
; __device__ __forceinline__ f32x2 ln_stats(f32x2 sm) { const float mu = sm[0] * (1.f / D); const float var = fmaxf(sm[1] * (1.f / D) - mu * mu, 0.f); return (f32x2){mu, 1.0f / sqrtf(var + LN_EPS)}; }
;     __device__ __forceinline__ void operator()(const f32x4 (&acc)[2][2][4][2], const Unit& u, int wr, int wc, int fr, int fq) const {
;     ...
;                 for (int mm = 0; mm < 2; ++mm) {
;                     const int r = row0 + ai * HALF + (2 * m2 + mm) * 16;
;                     float ps = 0.f, pq = 0.f;
; #pragma unroll
;                     for (int bj = 0; bj < 2; ++bj)
; #pragma unroll
;                         for (int n = 0; n < 2; ++n) {
;                             const f32x4 x = (xv[mm][bj][n] - st[mm][0]) * (gg[bj][n] * st[mm][1]) + bb[bj][n];
;                             const f32x4 o = x * alpha + acc[ai][bj][2 * m2 + mm][n] * scale;
;                             const size_t off = (size_t)r * D + col0 + bj * HALF + n * 16;
;                             *(f32x4*)(Y + off) = o;
;                             if (yb) { u32x2 w; w.x = cvt_pk_bf16(o[0], o[1]); w.y = cvt_pk_bf16(o[2], o[3]); *(u32x2*)(yb + off) = w; }
;                             ps += (o[0] + o[1]) + (o[2] + o[3]); pq += (o[0] * o[0] + o[1] * o[1]) + (o[2] * o[2] + o[3] * o[3]);
;                         }
;                     if (rout) {
;                         ps += __shfl_xor(ps, 16); pq += __shfl_xor(pq, 16); ps += __shfl_xor(ps, 32); pq += __shfl_xor(pq, 32);
;                         if (fq == 0) { atomicAdd(rout + 2 * (size_t)r, ps); atomicAdd(rout + 2 * (size_t)r + 1, pq); }
;                     }
	v_add_f32_e32 v154, v217, v158
	v_add_f32_e32 v195, v153, v152
	v_add_f32_e32 v152, v220, v221
	global_store_dwordx2 v[240:241], v[156:157], off
	v_add_f32_e32 v216, v154, v152
	v_sub_f32_e32 v155, v225, v230
	v_sub_f32_e32 v154, v224, v230
	v_sub_f32_e32 v157, v223, v230
	v_sub_f32_e32 v156, v222, v230
	v_pk_mul_f32 v[158:159], v[70:71], v[244:245] op_sel_hi:[1,0]
	v_pk_mul_f32 v[214:215], v[68:69], v[244:245] op_sel_hi:[1,0]
	v_or_b32_e32 v152, 0x80, v206
	v_mov_b32_e32 v153, v207
	v_pk_fma_f32 v[156:157], v[156:157], v[214:215], v[64:65]
	v_pk_fma_f32 v[154:155], v[154:155], v[158:159], v[66:67]
	v_pk_fma_f32 v[148:149], v[156:157], s[20:21], v[148:149] op_sel_hi:[1,0,1]
	v_pk_fma_f32 v[150:151], v[154:155], s[20:21], v[150:151] op_sel_hi:[1,0,1]
	v_lshl_add_u64 v[154:155], v[152:153], 2, s[38:39]
	v_lshl_add_u64 v[152:153], v[152:153], 1, s[6:7]
	global_store_dwordx4 v[154:155], v[148:151], off sc1
	v_cvt_pk_bf16_f32 v154, v148, v149
	v_cvt_pk_bf16_f32 v155, v150, v151
	global_store_dwordx2 v[152:153], v[154:155], off
	v_add_f32_e32 v152, v148, v149
	v_mul_f32_e32 v149, v149, v149
	v_fmac_f32_e32 v149, v148, v148
	v_mul_f32_e32 v148, v150, v150
	v_add_f32_e32 v153, v151, v150
	v_fmac_f32_e32 v148, v151, v151
	v_add_f32_e32 v152, v152, v153
	v_add_f32_e32 v148, v149, v148
	v_add_f32_e32 v156, v152, v195
	v_add_f32_e32 v157, v148, v216
	v_sub_f32_e32 v149, v229, v230
	v_sub_f32_e32 v148, v228, v230
	v_sub_f32_e32 v151, v227, v230
	v_sub_f32_e32 v150, v226, v230
	v_pk_mul_f32 v[152:153], v[58:59], v[244:245] op_sel_hi:[1,0]
	v_pk_mul_f32 v[154:155], v[56:57], v[244:245] op_sel_hi:[1,0]
	v_pk_fma_f32 v[148:149], v[148:149], v[152:153], v[54:55]
	v_pk_fma_f32 v[154:155], v[150:151], v[154:155], v[52:53]
	v_pk_fma_f32 v[150:151], v[148:149], s[20:21], v[146:147] op_sel_hi:[1,0,1]
	v_pk_fma_f32 v[148:149], v[154:155], s[20:21], v[144:145] op_sel_hi:[1,0,1]
	v_mul_f32_e32 v145, v150, v150
	v_mul_f32_e32 v144, v149, v149
	v_fmac_f32_e32 v144, v148, v148
	v_fmac_f32_e32 v145, v151, v151
	v_add_f32_e32 v144, v144, v145
	v_add_f32_e32 v146, v144, v157
	v_add_f32_e32 v144, v148, v149
	v_add_f32_e32 v145, v151, v150
	v_add_f32_e32 v144, v144, v145
	v_and_b32_e32 v145, 64, v213
	v_add_f32_e32 v147, v144, v156
	v_xor_b32_e32 v144, 16, v213
	v_add_u32_e32 v152, 64, v145
	v_cmp_lt_i32_e32 vcc, v144, v152
	v_or_b32_e32 v206, 0x90, v206
	s_nop 0
	v_cndmask_b32_e32 v144, v213, v144, vcc
	v_lshlrev_b32_e32 v156, 2, v144
	ds_bpermute_b32 v154, v156, v146
	ds_bpermute_b32 v153, v156, v147
	v_lshl_add_u64 v[144:145], v[206:207], 2, s[38:39]
	global_store_dwordx4 v[144:145], v[148:151], off sc1
	s_waitcnt lgkmcnt(1)
	v_add_f32_e32 v145, v146, v154
	v_xor_b32_e32 v146, 32, v213
	v_cmp_lt_i32_e32 vcc, v146, v152
	s_waitcnt lgkmcnt(0)
	v_add_f32_e32 v144, v147, v153
	v_cvt_pk_bf16_f32 v148, v148, v149
	v_cvt_pk_bf16_f32 v149, v150, v151
	v_lshl_add_u64 v[150:151], v[206:207], 1, s[6:7]
	v_cndmask_b32_e32 v146, v213, v146, vcc
	v_lshlrev_b32_e32 v157, 2, v146
	ds_bpermute_b32 v146, v157, v144
	ds_bpermute_b32 v147, v157, v145
	global_store_dwordx2 v[150:151], v[148:149], off
	s_and_saveexec_b64 s[0:1], s[4:5]
	s_cbranch_execz .LBB0_950
	v_lshl_add_u64 v[148:149], s[8:9], 0, v[200:201]
	s_waitcnt lgkmcnt(1)
	v_add_f32_e32 v144, v144, v146
	s_waitcnt lgkmcnt(0)
	v_add_f32_e32 v145, v145, v147
	global_atomic_add_f32 v[148:149], v144, off
	global_atomic_add_f32 v[148:149], v145, off offset:4
.LBB0_950:
	s_or_b64 exec, exec, s[0:1]
	v_mul_f32_e32 v144, 0x3a000000, v198
	v_mul_f32_e32 v144, v144, v144
	v_fma_f32 v144, v199, s18, -v144
	v_max_f32_e32 v144, 0, v144
	v_add_f32_e32 v144, 0x3727c5ac, v144
	v_mul_f32_e32 v145, 0x4f800000, v144
	v_cmp_gt_f32_e32 vcc, s52, v144
	v_fmamk_f32 v173, v198, 0xba000000, v173
	v_fmac_f32_e32 v172, 0xba000000, v198
	v_cndmask_b32_e32 v144, v144, v145, vcc
	v_sqrt_f32_e32 v145, v144
	v_fmamk_f32 v169, v198, 0xba000000, v169
	v_fmac_f32_e32 v168, 0xba000000, v198
	v_fmamk_f32 v165, v198, 0xba000000, v165
	s_waitcnt lgkmcnt(1)
	v_add_u32_e32 v146, -1, v145
	v_fma_f32 v148, -v146, v145, v144
	s_waitcnt lgkmcnt(0)
	v_add_u32_e32 v147, 1, v145
	v_cmp_ge_f32_e64 s[0:1], 0, v148
	v_fmac_f32_e32 v164, 0xba000000, v198
	v_fmamk_f32 v161, v198, 0xba000000, v161
	v_cndmask_b32_e64 v146, v145, v146, s[0:1]
	v_fma_f32 v145, -v147, v145, v144
	v_cmp_lt_f32_e64 s[0:1], 0, v145
	v_fmac_f32_e32 v160, 0xba000000, v198
	s_nop 0
	v_cndmask_b32_e64 v145, v146, v147, s[0:1]
	v_mul_f32_e32 v146, 0x37800000, v145
	v_cndmask_b32_e32 v145, v145, v146, vcc
	v_cmp_class_f32_e32 vcc, v144, v212
	s_nop 1
	v_cndmask_b32_e32 v144, v145, v144, vcc
	v_div_scale_f32 v145, s[0:1], v144, v144, 1.0
	v_rcp_f32_e32 v146, v145
	s_nop 0
	v_fma_f32 v147, -v145, v146, 1.0
	v_fmac_f32_e32 v146, v147, v146
	v_div_scale_f32 v147, vcc, 1.0, v144, 1.0
	v_mul_f32_e32 v148, v147, v146
	v_fma_f32 v149, -v145, v148, v147
	v_fmac_f32_e32 v148, v149, v146
	v_fma_f32 v145, -v145, v148, v147
	v_div_fmas_f32 v145, v145, v146, v148
	v_div_fixup_f32 v144, v145, v144, 1.0
	v_fmamk_f32 v149, v198, 0xba000000, v175
	v_fmamk_f32 v148, v198, 0xba000000, v174
	v_pk_mul_f32 v[150:151], v[94:95], v[144:145] op_sel_hi:[1,0]
	v_pk_mul_f32 v[152:153], v[92:93], v[144:145] op_sel_hi:[1,0]
	v_lshlrev_b64 v[146:147], 11, v[204:205]
	v_pk_fma_f32 v[152:153], v[172:173], v[152:153], v[88:89]
	v_pk_fma_f32 v[148:149], v[148:149], v[150:151], v[90:91]
	v_lshl_add_u64 v[146:147], v[146:147], 0, v[190:191]
	v_pk_fma_f32 v[142:143], v[148:149], s[20:21], v[142:143] op_sel_hi:[1,0,1]
	v_pk_fma_f32 v[140:141], v[152:153], s[20:21], v[140:141] op_sel_hi:[1,0,1]
	global_store_dwordx4 v[202:203], v[140:143], off sc1
; __device__ __forceinline__ unsigned cvt_pk_bf16(float lo, float hi) { unsigned r; asm volatile("v_cvt_pk_bf16_f32 %0, %1, %2" : "=v"(r) : "v"(lo), "v"(hi)); return r; }
;     __device__ __forceinline__ void operator()(const f32x4 (&acc)[2][2][4][2], const Unit& u, int wr, int wc, int fr, int fq) const {
;     ...
;                 for (int mm = 0; mm < 2; ++mm) {
;                     const int r = row0 + ai * HALF + (2 * m2 + mm) * 16;
;                     float ps = 0.f, pq = 0.f;
; #pragma unroll
;                     for (int bj = 0; bj < 2; ++bj)
; #pragma unroll
;                         for (int n = 0; n < 2; ++n) {
;                             const f32x4 x = (xv[mm][bj][n] - st[mm][0]) * (gg[bj][n] * st[mm][1]) + bb[bj][n];
;                             const f32x4 o = x * alpha + acc[ai][bj][2 * m2 + mm][n] * scale;
;                             const size_t off = (size_t)r * D + col0 + bj * HALF + n * 16;
;                             *(f32x4*)(Y + off) = o;
;                             if (yb) { u32x2 w; w.x = cvt_pk_bf16(o[0], o[1]); w.y = cvt_pk_bf16(o[2], o[3]); *(u32x2*)(yb + off) = w; }
;                             ps += (o[0] + o[1]) + (o[2] + o[3]); pq += (o[0] * o[0] + o[1] * o[1]) + (o[2] * o[2] + o[3] * o[3]);
;                         }
;                     if (rout) {
;                         ps += __shfl_xor(ps, 16); pq += __shfl_xor(pq, 16); ps += __shfl_xor(ps, 32); pq += __shfl_xor(pq, 32);
;                         if (fq == 0) { atomicAdd(rout + 2 * (size_t)r, ps); atomicAdd(rout + 2 * (size_t)r + 1, pq); }
;                     }
	v_cvt_pk_bf16_f32 v148, v140, v141
	v_lshl_add_u64 v[150:151], v[146:147], 1, s[6:7]
	v_cvt_pk_bf16_f32 v149, v142, v143
	global_store_dwordx2 v[150:151], v[148:149], off
	v_add_f32_e32 v145, v140, v141
	v_add_f32_e32 v148, v143, v142
	v_mul_f32_e32 v141, v141, v141
	v_add_f32_e32 v145, v145, v148
	v_fmac_f32_e32 v141, v140, v140
	v_mul_f32_e32 v140, v142, v142
	v_add_f32_e32 v145, 0, v145
	v_fmac_f32_e32 v140, v143, v143
	v_add_f32_e32 v150, v141, v140
	v_fmamk_f32 v141, v198, 0xba000000, v171
	v_fmamk_f32 v140, v198, 0xba000000, v170
	v_pk_mul_f32 v[142:143], v[78:79], v[144:145] op_sel_hi:[1,0]
	v_pk_mul_f32 v[148:149], v[76:77], v[144:145] op_sel_hi:[1,0]
	v_pk_fma_f32 v[140:141], v[140:141], v[142:143], v[74:75]
	v_pk_fma_f32 v[148:149], v[168:169], v[148:149], v[72:73]
	v_pk_fma_f32 v[138:139], v[140:141], s[20:21], v[138:139] op_sel_hi:[1,0,1]
	v_or_b32_e32 v140, 16, v146
	v_mov_b32_e32 v141, v147
	v_pk_fma_f32 v[136:137], v[148:149], s[20:21], v[136:137] op_sel_hi:[1,0,1]
	v_lshl_add_u64 v[142:143], v[140:141], 2, s[38:39]
	v_lshl_add_u64 v[140:141], v[140:141], 1, s[6:7]
	global_store_dwordx4 v[142:143], v[136:139], off sc1
	v_cvt_pk_bf16_f32 v142, v136, v137
	v_cvt_pk_bf16_f32 v143, v138, v139
	global_store_dwordx2 v[140:141], v[142:143], off
	v_add_f32_e32 v140, v136, v137
	v_add_f32_e32 v141, v139, v138
	v_mul_f32_e32 v137, v137, v137
	v_add_f32_e32 v140, v140, v141
	v_fmac_f32_e32 v137, v136, v136
	v_mul_f32_e32 v136, v138, v138
	v_add_f32_e32 v145, v140, v145
	v_fmac_f32_e32 v136, v139, v139
	v_add_f32_e32 v136, v137, v136
	v_fmamk_f32 v139, v198, 0xba000000, v167
	v_fmamk_f32 v138, v198, 0xba000000, v166
	v_pk_mul_f32 v[140:141], v[70:71], v[144:145] op_sel_hi:[1,0]
	v_pk_mul_f32 v[142:143], v[68:69], v[144:145] op_sel_hi:[1,0]
	v_add_f32_e32 v148, v150, v136
	v_or_b32_e32 v136, 0x80, v146
	v_mov_b32_e32 v137, v147
	v_pk_fma_f32 v[142:143], v[164:165], v[142:143], v[64:65]
	v_pk_fma_f32 v[138:139], v[138:139], v[140:141], v[66:67]
	v_pk_fma_f32 v[132:133], v[142:143], s[20:21], v[132:133] op_sel_hi:[1,0,1]
	v_pk_fma_f32 v[134:135], v[138:139], s[20:21], v[134:135] op_sel_hi:[1,0,1]
	v_lshl_add_u64 v[138:139], v[136:137], 2, s[38:39]
	v_lshl_add_u64 v[136:137], v[136:137], 1, s[6:7]
	global_store_dwordx4 v[138:139], v[132:135], off sc1
	v_cvt_pk_bf16_f32 v138, v132, v133
	v_cvt_pk_bf16_f32 v139, v134, v135
	global_store_dwordx2 v[136:137], v[138:139], off
	v_add_f32_e32 v136, v132, v133
	v_mul_f32_e32 v133, v133, v133
	v_fmac_f32_e32 v133, v132, v132
	v_mul_f32_e32 v132, v134, v134
	v_add_f32_e32 v137, v135, v134
	v_fmac_f32_e32 v132, v135, v135
	v_add_f32_e32 v136, v136, v137
	v_add_f32_e32 v132, v133, v132
	v_add_f32_e32 v138, v136, v145
	v_add_f32_e32 v139, v132, v148
	v_fmamk_f32 v133, v198, 0xba000000, v163
	v_fmamk_f32 v132, v198, 0xba000000, v162
	v_pk_mul_f32 v[134:135], v[58:59], v[144:145] op_sel_hi:[1,0]
	v_pk_mul_f32 v[136:137], v[56:57], v[144:145] op_sel_hi:[1,0]
	v_pk_fma_f32 v[132:133], v[132:133], v[134:135], v[54:55]
	v_pk_fma_f32 v[136:137], v[160:161], v[136:137], v[52:53]
	v_pk_fma_f32 v[134:135], v[132:133], s[20:21], v[130:131] op_sel_hi:[1,0,1]
	v_pk_fma_f32 v[132:133], v[136:137], s[20:21], v[128:129] op_sel_hi:[1,0,1]
	v_mul_f32_e32 v129, v134, v134
	v_mul_f32_e32 v128, v133, v133
	v_fmac_f32_e32 v128, v132, v132
	v_fmac_f32_e32 v129, v135, v135
	v_add_f32_e32 v128, v128, v129
	v_add_f32_e32 v130, v128, v139
	v_add_f32_e32 v128, v132, v133
	v_add_f32_e32 v129, v135, v134
	v_add_f32_e32 v128, v128, v129
	v_add_f32_e32 v131, v128, v138
	ds_bpermute_b32 v136, v156, v131
	ds_bpermute_b32 v137, v156, v130
	v_or_b32_e32 v146, 0x90, v146
	v_lshl_add_u64 v[128:129], v[146:147], 2, s[38:39]
	global_store_dwordx4 v[128:129], v[132:135], off sc1
	s_waitcnt lgkmcnt(1)
	v_add_f32_e32 v128, v131, v136
	s_waitcnt lgkmcnt(0)
	v_add_f32_e32 v129, v130, v137
	ds_bpermute_b32 v130, v157, v128
	ds_bpermute_b32 v131, v157, v129
	v_cvt_pk_bf16_f32 v132, v132, v133
	v_cvt_pk_bf16_f32 v133, v134, v135
	v_lshl_add_u64 v[134:135], v[146:147], 1, s[6:7]
	global_store_dwordx2 v[134:135], v[132:133], off
	s_and_saveexec_b64 s[0:1], s[4:5]
	s_cbranch_execz .LBB0_952
	v_lshl_add_u64 v[132:133], s[8:9], 0, v[196:197]
	s_waitcnt lgkmcnt(1)
	v_add_f32_e32 v128, v128, v130
	s_waitcnt lgkmcnt(0)
	v_add_f32_e32 v129, v129, v131
	global_atomic_add_f32 v[132:133], v128, off
	global_atomic_add_f32 v[132:133], v129, off offset:4
; __device__ __forceinline__ unsigned cvt_pk_bf16(float lo, float hi) { unsigned r; asm volatile("v_cvt_pk_bf16_f32 %0, %1, %2" : "=v"(r) : "v"(lo), "v"(hi)); return r; }
; __device__ __forceinline__ f32x2 ln_stats(f32x2 sm) { const float mu = sm[0] * (1.f / D); const float var = fmaxf(sm[1] * (1.f / D) - mu * mu, 0.f); return (f32x2){mu, 1.0f / sqrtf(var + LN_EPS)}; }
;     __device__ __forceinline__ void operator()(const f32x4 (&acc)[2][2][4][2], const Unit& u, int wr, int wc, int fr, int fq) const {
;     ...
;                 f32x4 xv[2][2][2]; f32x2 st[2];
; #pragma unroll
;                 for (int mm = 0; mm < 2; ++mm) {
;                     const int r = row0 + ai * HALF + (2 * m2 + mm) * 16;
;                     st[mm] = (f32x2){0.f, 1.f};
;                     if (rin) st[mm] = ln_stats(*(const f32x2*)(rin + 2 * (size_t)r));
; #pragma unroll
;                     for (int bj = 0; bj < 2; ++bj)
; #pragma unroll
;                         for (int n = 0; n < 2; ++n) { const f32x4* rp = (const f32x4*)(res + (size_t)r * D + col0 + bj * HALF + n * 16); xv[mm][bj][n] = stream ? __builtin_nontemporal_load(rp) : *rp; }
;                 }
; #pragma unroll
;                 for (int mm = 0; mm < 2; ++mm) {
;                     const int r = row0 + ai * HALF + (2 * m2 + mm) * 16;
;                     float ps = 0.f, pq = 0.f;
; #pragma unroll
;                     for (int bj = 0; bj < 2; ++bj)
; #pragma unroll
;                         for (int n = 0; n < 2; ++n) {
;                             const f32x4 x = (xv[mm][bj][n] - st[mm][0]) * (gg[bj][n] * st[mm][1]) + bb[bj][n];
;                             const f32x4 o = x * alpha + acc[ai][bj][2 * m2 + mm][n] * scale;
;                             const size_t off = (size_t)r * D + col0 + bj * HALF + n * 16;
;                             *(f32x4*)(Y + off) = o;
;                             if (yb) { u32x2 w; w.x = cvt_pk_bf16(o[0], o[1]); w.y = cvt_pk_bf16(o[2], o[3]); *(u32x2*)(yb + off) = w; }
;                             ps += (o[0] + o[1]) + (o[2] + o[3]); pq += (o[0] * o[0] + o[1] * o[1]) + (o[2] * o[2] + o[3] * o[3]);
.LBB0_952:
	s_or_b64 exec, exec, s[0:1]
	v_or_b32_e32 v128, 32, v194
	v_ashrrev_i32_e32 v129, 31, v128
	v_lshlrev_b64 v[152:153], 3, v[128:129]
	s_waitcnt lgkmcnt(0)
	v_lshl_add_u64 v[130:131], s[54:55], 0, v[152:153]
	global_load_dwordx2 v[174:175], v[130:131], off
	v_lshlrev_b64 v[130:131], 13, v[128:129]
	v_lshl_add_u64 v[196:197], v[192:193], 0, v[130:131]
	global_load_dwordx4 v[158:161], v[196:197], off
	global_load_dwordx4 v[162:165], v[196:197], off offset:64
	global_load_dwordx4 v[166:169], v[196:197], off offset:512
	v_or_b32_e32 v150, 48, v194
	v_ashrrev_i32_e32 v151, 31, v150
	v_lshlrev_b64 v[144:145], 3, v[150:151]
	v_lshlrev_b64 v[130:131], 13, v[150:151]
	v_lshlrev_b64 v[128:129], 11, v[128:129]
	v_lshl_add_u64 v[132:133], s[54:55], 0, v[144:145]
	v_lshl_add_u64 v[148:149], v[192:193], 0, v[130:131]
	v_lshl_add_u64 v[154:155], v[128:129], 0, v[190:191]
	global_load_dwordx4 v[170:173], v[196:197], off offset:576
	global_load_dwordx2 v[146:147], v[132:133], off
	global_load_dwordx4 v[140:143], v[148:149], off
	global_load_dwordx4 v[136:139], v[148:149], off offset:64
	s_nop 0
	global_load_dwordx4 v[132:135], v[148:149], off offset:512
	global_load_dwordx4 v[128:131], v[148:149], off offset:576
	v_lshl_add_u64 v[198:199], v[154:155], 1, s[6:7]
	v_or_b32_e32 v200, 16, v154
	v_mov_b32_e32 v201, v155
	v_lshl_add_u64 v[204:205], v[200:201], 2, s[38:39]
	v_or_b32_e32 v202, 0x80, v154
	v_mov_b32_e32 v203, v155
	v_lshl_add_u64 v[200:201], v[200:201], 1, s[6:7]
	v_or_b32_e32 v154, 0x90, v154
	s_waitcnt vmcnt(9)
	v_pk_mul_f32 v[174:175], v[174:175], s[18:19] op_sel_hi:[1,0]
	s_nop 0
	v_fma_f32 v175, -v174, v174, v175
	v_max_f32_e32 v175, 0, v175
	v_add_f32_e32 v175, 0x3727c5ac, v175
	v_mul_f32_e32 v195, 0x4f800000, v175
	v_cmp_gt_f32_e32 vcc, s52, v175
	s_waitcnt vmcnt(8)
	v_sub_f32_e32 v161, v161, v174
	v_sub_f32_e32 v160, v160, v174
	v_cndmask_b32_e32 v175, v175, v195, vcc
	v_sqrt_f32_e32 v195, v175
	v_sub_f32_e32 v159, v159, v174
	v_sub_f32_e32 v158, v158, v174
	s_waitcnt vmcnt(7)
	v_sub_f32_e32 v165, v165, v174
	v_add_u32_e32 v206, -1, v195
	v_add_u32_e32 v207, 1, v195
	v_fma_f32 v214, -v206, v195, v175
	v_fma_f32 v215, -v207, v195, v175
	v_cmp_ge_f32_e64 s[0:1], 0, v214
	v_sub_f32_e32 v164, v164, v174
	v_sub_f32_e32 v163, v163, v174
	v_cndmask_b32_e64 v195, v195, v206, s[0:1]
	v_cmp_lt_f32_e64 s[0:1], 0, v215
	v_sub_f32_e32 v162, v162, v174
	s_waitcnt vmcnt(6)
	v_sub_f32_e32 v169, v169, v174
	v_cndmask_b32_e64 v195, v195, v207, s[0:1]
	v_mul_f32_e32 v206, 0x37800000, v195
	v_cndmask_b32_e32 v195, v195, v206, vcc
	v_cmp_class_f32_e32 vcc, v175, v212
	v_sub_f32_e32 v168, v168, v174
	v_sub_f32_e32 v167, v167, v174
	v_cndmask_b32_e32 v175, v195, v175, vcc
	v_div_scale_f32 v195, s[0:1], v175, v175, 1.0
	v_rcp_f32_e32 v206, v195
	v_div_scale_f32 v207, vcc, 1.0, v175, 1.0
	v_sub_f32_e32 v166, v166, v174
	v_fma_f32 v214, -v195, v206, 1.0
	v_fmac_f32_e32 v206, v214, v206
	v_mul_f32_e32 v214, v207, v206
	v_fma_f32 v215, -v195, v214, v207
	v_fmac_f32_e32 v214, v215, v206
	v_fma_f32 v195, -v195, v214, v207
	v_div_fmas_f32 v195, v195, v206, v214
	v_div_fixup_f32 v206, v195, v175, 1.0
	v_pk_mul_f32 v[214:215], v[94:95], v[206:207] op_sel_hi:[1,0]
	v_pk_mul_f32 v[216:217], v[92:93], v[206:207] op_sel_hi:[1,0]
	v_pk_mul_f32 v[218:219], v[78:79], v[206:207] op_sel_hi:[1,0]
	v_pk_mul_f32 v[220:221], v[76:77], v[206:207] op_sel_hi:[1,0]
	v_pk_fma_f32 v[158:159], v[158:159], v[216:217], v[88:89]
	v_pk_fma_f32 v[160:161], v[160:161], v[214:215], v[90:91]
	v_pk_mul_f32 v[222:223], v[70:71], v[206:207] op_sel_hi:[1,0]
	v_pk_fma_f32 v[162:163], v[162:163], v[220:221], v[72:73]
	v_pk_fma_f32 v[164:165], v[164:165], v[218:219], v[74:75]
	v_pk_fma_f32 v[126:127], v[160:161], s[20:21], v[126:127] op_sel_hi:[1,0,1]
	v_pk_fma_f32 v[124:125], v[158:159], s[20:21], v[124:125] op_sel_hi:[1,0,1]
	v_pk_fma_f32 v[168:169], v[168:169], v[222:223], v[66:67]
	v_pk_fma_f32 v[122:123], v[164:165], s[20:21], v[122:123] op_sel_hi:[1,0,1]
	v_pk_fma_f32 v[120:121], v[162:163], s[20:21], v[120:121] op_sel_hi:[1,0,1]
	global_store_dwordx4 v[196:197], v[124:127], off sc1
	v_cvt_pk_bf16_f32 v158, v124, v125
	v_add_f32_e32 v160, v124, v125
	v_add_f32_e32 v161, v127, v126
	v_pk_mul_f32 v[224:225], v[68:69], v[206:207] op_sel_hi:[1,0]
	v_pk_fma_f32 v[118:119], v[168:169], s[20:21], v[118:119] op_sel_hi:[1,0,1]
	v_cvt_pk_bf16_f32 v159, v126, v127
	v_mul_f32_e32 v162, v125, v125
	v_mul_f32_e32 v126, v126, v126
	v_add_f32_e32 v163, v120, v121
	v_add_f32_e32 v164, v123, v122
	v_mul_f32_e32 v165, v121, v121
	v_mul_f32_e32 v168, v122, v122
	global_store_dwordx2 v[198:199], v[158:159], off
	v_add_f32_e32 v158, v160, v161
	v_pk_fma_f32 v[166:167], v[166:167], v[224:225], v[64:65]
	v_fmac_f32_e32 v162, v124, v124
	v_fmac_f32_e32 v126, v127, v127
	global_store_dwordx4 v[204:205], v[120:123], off sc1
	v_cvt_pk_bf16_f32 v124, v120, v121
	v_fmac_f32_e32 v165, v120, v120
	v_fmac_f32_e32 v168, v123, v123
	v_add_f32_e32 v121, v163, v164
	v_add_f32_e32 v120, 0, v158
	v_cvt_pk_bf16_f32 v125, v122, v123
	v_add_f32_e32 v122, v162, v126
	global_store_dwordx2 v[200:201], v[124:125], off
	v_add_f32_e32 v123, v165, v168
	v_add_f32_e32 v124, v121, v120
	v_pk_fma_f32 v[116:117], v[166:167], s[20:21], v[116:117] op_sel_hi:[1,0,1]
	v_lshl_add_u64 v[120:121], v[202:203], 2, s[38:39]
	v_add_f32_e32 v125, v122, v123
	global_store_dwordx4 v[120:121], v[116:119], off sc1
	v_cvt_pk_bf16_f32 v120, v116, v117
	v_lshl_add_u64 v[122:123], v[202:203], 1, s[6:7]
	v_cvt_pk_bf16_f32 v121, v118, v119
	global_store_dwordx2 v[122:123], v[120:121], off
	v_add_f32_e32 v120, v116, v117
	v_mul_f32_e32 v117, v117, v117
	v_fmac_f32_e32 v117, v116, v116
	v_mul_f32_e32 v116, v118, v118
	v_add_f32_e32 v121, v119, v118
	v_fmac_f32_e32 v116, v119, v119
	v_add_f32_e32 v120, v120, v121
	v_add_f32_e32 v116, v117, v116
	v_add_f32_e32 v124, v120, v124
	v_add_f32_e32 v125, v116, v125
	s_waitcnt vmcnt(11)
; __device__ __forceinline__ unsigned cvt_pk_bf16(float lo, float hi) { unsigned r; asm volatile("v_cvt_pk_bf16_f32 %0, %1, %2" : "=v"(r) : "v"(lo), "v"(hi)); return r; }
; __device__ __forceinline__ f32x2 ln_stats(f32x2 sm) { const float mu = sm[0] * (1.f / D); const float var = fmaxf(sm[1] * (1.f / D) - mu * mu, 0.f); return (f32x2){mu, 1.0f / sqrtf(var + LN_EPS)}; }
;     __device__ __forceinline__ void operator()(const f32x4 (&acc)[2][2][4][2], const Unit& u, int wr, int wc, int fr, int fq) const {
;     ...
;                 for (int mm = 0; mm < 2; ++mm) {
;                     const int r = row0 + ai * HALF + (2 * m2 + mm) * 16;
;                     float ps = 0.f, pq = 0.f;
; #pragma unroll
;                     for (int bj = 0; bj < 2; ++bj)
; #pragma unroll
;                         for (int n = 0; n < 2; ++n) {
;                             const f32x4 x = (xv[mm][bj][n] - st[mm][0]) * (gg[bj][n] * st[mm][1]) + bb[bj][n];
;                             const f32x4 o = x * alpha + acc[ai][bj][2 * m2 + mm][n] * scale;
;                             const size_t off = (size_t)r * D + col0 + bj * HALF + n * 16;
;                             *(f32x4*)(Y + off) = o;
;                             if (yb) { u32x2 w; w.x = cvt_pk_bf16(o[0], o[1]); w.y = cvt_pk_bf16(o[2], o[3]); *(u32x2*)(yb + off) = w; }
;                             ps += (o[0] + o[1]) + (o[2] + o[3]); pq += (o[0] * o[0] + o[1] * o[1]) + (o[2] * o[2] + o[3] * o[3]);
;                         }
;                     if (rout) {
;                         ps += __shfl_xor(ps, 16); pq += __shfl_xor(pq, 16); ps += __shfl_xor(ps, 32); pq += __shfl_xor(pq, 32);
;                         if (fq == 0) { atomicAdd(rout + 2 * (size_t)r, ps); atomicAdd(rout + 2 * (size_t)r + 1, pq); }
;                     }
	v_sub_f32_e32 v117, v173, v174
	v_sub_f32_e32 v116, v172, v174
	v_sub_f32_e32 v119, v171, v174
	v_sub_f32_e32 v118, v170, v174
	v_pk_mul_f32 v[120:121], v[58:59], v[206:207] op_sel_hi:[1,0]
	v_pk_mul_f32 v[122:123], v[56:57], v[206:207] op_sel_hi:[1,0]
	v_pk_fma_f32 v[116:117], v[116:117], v[120:121], v[54:55]
	v_pk_fma_f32 v[122:123], v[118:119], v[122:123], v[52:53]
	v_pk_fma_f32 v[118:119], v[116:117], s[20:21], v[114:115] op_sel_hi:[1,0,1]
	v_pk_fma_f32 v[116:117], v[122:123], s[20:21], v[112:113] op_sel_hi:[1,0,1]
	v_mul_f32_e32 v113, v118, v118
	v_mul_f32_e32 v112, v117, v117
	v_fmac_f32_e32 v112, v116, v116
	v_fmac_f32_e32 v113, v119, v119
	v_add_f32_e32 v112, v112, v113
	v_add_f32_e32 v114, v112, v125
	v_add_f32_e32 v112, v116, v117
	v_add_f32_e32 v113, v119, v118
	v_add_f32_e32 v112, v112, v113
	v_add_f32_e32 v115, v112, v124
	ds_bpermute_b32 v120, v156, v115
	ds_bpermute_b32 v121, v156, v114
	v_lshl_add_u64 v[112:113], v[154:155], 2, s[38:39]
	global_store_dwordx4 v[112:113], v[116:119], off sc1
	s_waitcnt lgkmcnt(1)
	v_add_f32_e32 v112, v115, v120
	s_waitcnt lgkmcnt(0)
	v_add_f32_e32 v113, v114, v121
	ds_bpermute_b32 v114, v157, v112
	ds_bpermute_b32 v115, v157, v113
	v_cvt_pk_bf16_f32 v116, v116, v117
	v_cvt_pk_bf16_f32 v117, v118, v119
	v_lshl_add_u64 v[118:119], v[154:155], 1, s[6:7]
	global_store_dwordx2 v[118:119], v[116:117], off
	s_and_saveexec_b64 s[0:1], s[4:5]
	s_cbranch_execz .LBB0_954
	v_lshl_add_u64 v[116:117], s[8:9], 0, v[152:153]
	s_waitcnt lgkmcnt(1)
	v_add_f32_e32 v112, v112, v114
	s_waitcnt lgkmcnt(0)
	v_add_f32_e32 v113, v113, v115
	global_atomic_add_f32 v[116:117], v112, off
	global_atomic_add_f32 v[116:117], v113, off offset:4
.LBB0_954:
	s_or_b64 exec, exec, s[0:1]
	s_waitcnt vmcnt(12)
	v_mul_f32_e32 v112, 0x3a000000, v146
	v_mul_f32_e32 v112, v112, v112
	v_fma_f32 v112, v147, s18, -v112
	v_max_f32_e32 v112, 0, v112
	v_add_f32_e32 v112, 0x3727c5ac, v112
	v_mul_f32_e32 v113, 0x4f800000, v112
	v_cmp_gt_f32_e32 vcc, s52, v112
	s_waitcnt vmcnt(11)
	v_fmamk_f32 v141, v146, 0xba000000, v141
	v_fmac_f32_e32 v140, 0xba000000, v146
	v_cndmask_b32_e32 v112, v112, v113, vcc
	v_sqrt_f32_e32 v113, v112
	s_waitcnt vmcnt(10)
	v_fmamk_f32 v137, v146, 0xba000000, v137
	v_fmac_f32_e32 v136, 0xba000000, v146
	s_waitcnt vmcnt(9)
	v_fmamk_f32 v133, v146, 0xba000000, v133
	s_waitcnt lgkmcnt(1)
	v_add_u32_e32 v114, -1, v113
	v_fma_f32 v116, -v114, v113, v112
	s_waitcnt lgkmcnt(0)
	v_add_u32_e32 v115, 1, v113
	v_cmp_ge_f32_e64 s[0:1], 0, v116
	v_fmac_f32_e32 v132, 0xba000000, v146
	s_waitcnt vmcnt(8)
	v_fmamk_f32 v129, v146, 0xba000000, v129
	v_cndmask_b32_e64 v114, v113, v114, s[0:1]
	v_fma_f32 v113, -v115, v113, v112
	v_cmp_lt_f32_e64 s[0:1], 0, v113
	v_fmac_f32_e32 v128, 0xba000000, v146
	s_nop 0
	v_cndmask_b32_e64 v113, v114, v115, s[0:1]
	v_mul_f32_e32 v114, 0x37800000, v113
	v_cndmask_b32_e32 v113, v113, v114, vcc
	v_cmp_class_f32_e32 vcc, v112, v212
	s_nop 1
	v_cndmask_b32_e32 v112, v113, v112, vcc
	v_div_scale_f32 v113, s[0:1], v112, v112, 1.0
	v_rcp_f32_e32 v114, v113
	s_nop 0
	v_fma_f32 v115, -v113, v114, 1.0
	v_fmac_f32_e32 v114, v115, v114
	v_div_scale_f32 v115, vcc, 1.0, v112, 1.0
	v_mul_f32_e32 v116, v115, v114
	v_fma_f32 v117, -v113, v116, v115
	v_fmac_f32_e32 v116, v117, v114
	v_fma_f32 v113, -v113, v116, v115
	v_div_fmas_f32 v113, v113, v114, v116
	v_div_fixup_f32 v112, v113, v112, 1.0
	v_fmamk_f32 v117, v146, 0xba000000, v143
	v_fmamk_f32 v116, v146, 0xba000000, v142
	v_pk_mul_f32 v[118:119], v[94:95], v[112:113] op_sel_hi:[1,0]
	v_pk_mul_f32 v[120:121], v[92:93], v[112:113] op_sel_hi:[1,0]
	v_lshlrev_b64 v[114:115], 11, v[150:151]
	v_pk_fma_f32 v[120:121], v[140:141], v[120:121], v[88:89]
	v_pk_fma_f32 v[116:117], v[116:117], v[118:119], v[90:91]
	v_lshl_add_u64 v[114:115], v[114:115], 0, v[190:191]
	v_pk_fma_f32 v[110:111], v[116:117], s[20:21], v[110:111] op_sel_hi:[1,0,1]
	v_pk_fma_f32 v[108:109], v[120:121], s[20:21], v[108:109] op_sel_hi:[1,0,1]
	global_store_dwordx4 v[148:149], v[108:111], off sc1
	v_cvt_pk_bf16_f32 v116, v108, v109
	v_lshl_add_u64 v[118:119], v[114:115], 1, s[6:7]
	v_cvt_pk_bf16_f32 v117, v110, v111
	global_store_dwordx2 v[118:119], v[116:117], off
	v_add_f32_e32 v113, v108, v109
	v_add_f32_e32 v116, v111, v110
	v_mul_f32_e32 v109, v109, v109
	v_add_f32_e32 v113, v113, v116
	v_fmac_f32_e32 v109, v108, v108
	v_mul_f32_e32 v108, v110, v110
	v_add_f32_e32 v113, 0, v113
	v_fmac_f32_e32 v108, v111, v111
	v_add_f32_e32 v118, v109, v108
	v_fmamk_f32 v109, v146, 0xba000000, v139
	v_fmamk_f32 v108, v146, 0xba000000, v138
	v_pk_mul_f32 v[110:111], v[78:79], v[112:113] op_sel_hi:[1,0]
	v_pk_mul_f32 v[116:117], v[76:77], v[112:113] op_sel_hi:[1,0]
	v_pk_fma_f32 v[108:109], v[108:109], v[110:111], v[74:75]
	v_pk_fma_f32 v[116:117], v[136:137], v[116:117], v[72:73]
	v_pk_fma_f32 v[106:107], v[108:109], s[20:21], v[106:107] op_sel_hi:[1,0,1]
	v_or_b32_e32 v108, 16, v114
	v_mov_b32_e32 v109, v115
	v_pk_fma_f32 v[104:105], v[116:117], s[20:21], v[104:105] op_sel_hi:[1,0,1]
	v_lshl_add_u64 v[110:111], v[108:109], 2, s[38:39]
	v_lshl_add_u64 v[108:109], v[108:109], 1, s[6:7]
	global_store_dwordx4 v[110:111], v[104:107], off sc1
	v_cvt_pk_bf16_f32 v110, v104, v105
	v_cvt_pk_bf16_f32 v111, v106, v107
	global_store_dwordx2 v[108:109], v[110:111], off
	v_add_f32_e32 v108, v104, v105
	v_add_f32_e32 v109, v107, v106
	v_mul_f32_e32 v105, v105, v105
	v_add_f32_e32 v108, v108, v109
	v_fmac_f32_e32 v105, v104, v104
	v_mul_f32_e32 v104, v106, v106
	v_add_f32_e32 v113, v108, v113
	v_fmac_f32_e32 v104, v107, v107
	v_add_f32_e32 v104, v105, v104
	v_fmamk_f32 v107, v146, 0xba000000, v135
	v_fmamk_f32 v106, v146, 0xba000000, v134
; __device__ __forceinline__ f32x2 ln_stats(f32x2 sm) { const float mu = sm[0] * (1.f / D); const float var = fmaxf(sm[1] * (1.f / D) - mu * mu, 0.f); return (f32x2){mu, 1.0f / sqrtf(var + LN_EPS)}; }
;     __device__ __forceinline__ void operator()(const f32x4 (&acc)[2][2][4][2], const Unit& u, int wr, int wc, int fr, int fq) const {
;     ...
;                 f32x4 xv[2][2][2]; f32x2 st[2];
; #pragma unroll
;                 for (int mm = 0; mm < 2; ++mm) {
;                     const int r = row0 + ai * HALF + (2 * m2 + mm) * 16;
;                     st[mm] = (f32x2){0.f, 1.f};
;                     if (rin) st[mm] = ln_stats(*(const f32x2*)(rin + 2 * (size_t)r));
; #pragma unroll
;                     for (int bj = 0; bj < 2; ++bj)
; #pragma unroll
;                         for (int n = 0; n < 2; ++n) { const f32x4* rp = (const f32x4*)(res + (size_t)r * D + col0 + bj * HALF + n * 16); xv[mm][bj][n] = stream ? __builtin_nontemporal_load(rp) : *rp; }
;                 }
; #pragma unroll
;                 for (int mm = 0; mm < 2; ++mm) {
;                     const int r = row0 + ai * HALF + (2 * m2 + mm) * 16;
;                     float ps = 0.f, pq = 0.f;
; #pragma unroll
;                     for (int bj = 0; bj < 2; ++bj)
; #pragma unroll
;                         for (int n = 0; n < 2; ++n) {
;                             const f32x4 x = (xv[mm][bj][n] - st[mm][0]) * (gg[bj][n] * st[mm][1]) + bb[bj][n];
;                             const f32x4 o = x * alpha + acc[ai][bj][2 * m2 + mm][n] * scale;
;                             const size_t off = (size_t)r * D + col0 + bj * HALF + n * 16;
;                             *(f32x4*)(Y + off) = o;
;                             if (yb) { u32x2 w; w.x = cvt_pk_bf16(o[0], o[1]); w.y = cvt_pk_bf16(o[2], o[3]); *(u32x2*)(yb + off) = w; }
;                             ps += (o[0] + o[1]) + (o[2] + o[3]); pq += (o[0] * o[0] + o[1] * o[1]) + (o[2] * o[2] + o[3] * o[3]);
;                         }
;                     if (rout) {
;                         ps += __shfl_xor(ps, 16); pq += __shfl_xor(pq, 16); ps += __shfl_xor(ps, 32); pq += __shfl_xor(pq, 32);
;                         if (fq == 0) { atomicAdd(rout + 2 * (size_t)r, ps); atomicAdd(rout + 2 * (size_t)r + 1, pq); }
;                     }
	v_pk_mul_f32 v[108:109], v[70:71], v[112:113] op_sel_hi:[1,0]
	v_pk_mul_f32 v[110:111], v[68:69], v[112:113] op_sel_hi:[1,0]
	v_add_f32_e32 v116, v118, v104
	v_or_b32_e32 v104, 0x80, v114
	v_mov_b32_e32 v105, v115
	v_pk_fma_f32 v[110:111], v[132:133], v[110:111], v[64:65]
	v_pk_fma_f32 v[106:107], v[106:107], v[108:109], v[66:67]
	v_pk_fma_f32 v[100:101], v[110:111], s[20:21], v[100:101] op_sel_hi:[1,0,1]
	v_pk_fma_f32 v[102:103], v[106:107], s[20:21], v[102:103] op_sel_hi:[1,0,1]
	v_lshl_add_u64 v[106:107], v[104:105], 2, s[38:39]
	v_lshl_add_u64 v[104:105], v[104:105], 1, s[6:7]
	global_store_dwordx4 v[106:107], v[100:103], off sc1
	v_cvt_pk_bf16_f32 v106, v100, v101
	v_cvt_pk_bf16_f32 v107, v102, v103
	global_store_dwordx2 v[104:105], v[106:107], off
	v_add_f32_e32 v104, v100, v101
	v_mul_f32_e32 v101, v101, v101
	v_fmac_f32_e32 v101, v100, v100
	v_mul_f32_e32 v100, v102, v102
	v_add_f32_e32 v105, v103, v102
	v_fmac_f32_e32 v100, v103, v103
	v_add_f32_e32 v104, v104, v105
	v_add_f32_e32 v100, v101, v100
	v_add_f32_e32 v106, v104, v113
	v_add_f32_e32 v107, v100, v116
	v_fmamk_f32 v101, v146, 0xba000000, v131
	v_fmamk_f32 v100, v146, 0xba000000, v130
	v_pk_mul_f32 v[102:103], v[58:59], v[112:113] op_sel_hi:[1,0]
	v_pk_mul_f32 v[104:105], v[56:57], v[112:113] op_sel_hi:[1,0]
	v_pk_fma_f32 v[100:101], v[100:101], v[102:103], v[54:55]
	v_pk_fma_f32 v[104:105], v[128:129], v[104:105], v[52:53]
	v_pk_fma_f32 v[102:103], v[100:101], s[20:21], v[98:99] op_sel_hi:[1,0,1]
	v_pk_fma_f32 v[100:101], v[104:105], s[20:21], v[96:97] op_sel_hi:[1,0,1]
	v_mul_f32_e32 v97, v102, v102
	v_mul_f32_e32 v96, v101, v101
	v_fmac_f32_e32 v96, v100, v100
	v_fmac_f32_e32 v97, v103, v103
	v_add_f32_e32 v96, v96, v97
	v_add_f32_e32 v98, v96, v107
	v_add_f32_e32 v96, v100, v101
	v_add_f32_e32 v97, v103, v102
	v_add_f32_e32 v96, v96, v97
	v_add_f32_e32 v99, v96, v106
	ds_bpermute_b32 v104, v156, v99
	ds_bpermute_b32 v105, v156, v98
	v_or_b32_e32 v114, 0x90, v114
	v_lshl_add_u64 v[96:97], v[114:115], 2, s[38:39]
	global_store_dwordx4 v[96:97], v[100:103], off sc1
	s_waitcnt lgkmcnt(1)
	v_add_f32_e32 v96, v99, v104
	s_waitcnt lgkmcnt(0)
	v_add_f32_e32 v97, v98, v105
	ds_bpermute_b32 v98, v157, v96
	ds_bpermute_b32 v99, v157, v97
	v_cvt_pk_bf16_f32 v100, v100, v101
	v_cvt_pk_bf16_f32 v101, v102, v103
	v_lshl_add_u64 v[102:103], v[114:115], 1, s[6:7]
	global_store_dwordx2 v[102:103], v[100:101], off
	s_and_saveexec_b64 s[0:1], s[4:5]
	s_cbranch_execz .LBB0_956
	v_lshl_add_u64 v[100:101], s[8:9], 0, v[144:145]
	s_waitcnt lgkmcnt(1)
	v_add_f32_e32 v96, v96, v98
	s_waitcnt lgkmcnt(0)
	v_add_f32_e32 v97, v97, v99
	global_atomic_add_f32 v[100:101], v96, off
	global_atomic_add_f32 v[100:101], v97, off offset:4
.LBB0_956:
	s_or_b64 exec, exec, s[0:1]
	v_add_u32_e32 v96, 0x80, v194
	v_ashrrev_i32_e32 v97, 31, v96
	v_lshlrev_b64 v[120:121], 3, v[96:97]
	s_waitcnt lgkmcnt(0)
	v_lshl_add_u64 v[98:99], s[54:55], 0, v[120:121]
	global_load_dwordx2 v[140:141], v[98:99], off
	v_lshlrev_b64 v[98:99], 13, v[96:97]
	v_lshl_add_u64 v[142:143], v[192:193], 0, v[98:99]
	global_load_dwordx4 v[124:127], v[142:143], off
	global_load_dwordx4 v[128:131], v[142:143], off offset:64
	global_load_dwordx4 v[132:135], v[142:143], off offset:512
	v_add_u32_e32 v118, 0x90, v194
	v_ashrrev_i32_e32 v119, 31, v118
	v_lshlrev_b64 v[112:113], 3, v[118:119]
	v_lshlrev_b64 v[98:99], 13, v[118:119]
	v_lshlrev_b64 v[96:97], 11, v[96:97]
	v_lshl_add_u64 v[100:101], s[54:55], 0, v[112:113]
	v_lshl_add_u64 v[116:117], v[192:193], 0, v[98:99]
	v_lshl_add_u64 v[122:123], v[96:97], 0, v[190:191]
	global_load_dwordx4 v[136:139], v[142:143], off offset:576
	global_load_dwordx2 v[114:115], v[100:101], off
	global_load_dwordx4 v[108:111], v[116:117], off
	global_load_dwordx4 v[104:107], v[116:117], off offset:64
	s_nop 0
	global_load_dwordx4 v[100:103], v[116:117], off offset:512
	global_load_dwordx4 v[96:99], v[116:117], off offset:576
	v_lshl_add_u64 v[144:145], v[122:123], 1, s[6:7]
	v_or_b32_e32 v146, 16, v122
	v_mov_b32_e32 v147, v123
	v_lshl_add_u64 v[150:151], v[146:147], 2, s[38:39]
	v_or_b32_e32 v148, 0x80, v122
	v_mov_b32_e32 v149, v123
	v_lshl_add_u64 v[146:147], v[146:147], 1, s[6:7]
	v_or_b32_e32 v122, 0x90, v122
	s_waitcnt vmcnt(9)
	v_pk_mul_f32 v[140:141], v[140:141], s[18:19] op_sel_hi:[1,0]
	s_nop 0
	v_fma_f32 v141, -v140, v140, v141
	v_max_f32_e32 v141, 0, v141
	v_add_f32_e32 v141, 0x3727c5ac, v141
	v_mul_f32_e32 v152, 0x4f800000, v141
	v_cmp_gt_f32_e32 vcc, s52, v141
	s_waitcnt vmcnt(8)
	v_sub_f32_e32 v127, v127, v140
	v_sub_f32_e32 v126, v126, v140
	v_cndmask_b32_e32 v141, v141, v152, vcc
	v_sqrt_f32_e32 v152, v141
	v_sub_f32_e32 v125, v125, v140
	v_sub_f32_e32 v124, v124, v140
	s_waitcnt vmcnt(7)
	v_sub_f32_e32 v131, v131, v140
	v_add_u32_e32 v153, -1, v152
	v_add_u32_e32 v154, 1, v152
	v_fma_f32 v155, -v153, v152, v141
	v_fma_f32 v158, -v154, v152, v141
	v_cmp_ge_f32_e64 s[0:1], 0, v155
	v_sub_f32_e32 v130, v130, v140
	v_sub_f32_e32 v129, v129, v140
	v_cndmask_b32_e64 v152, v152, v153, s[0:1]
	v_cmp_lt_f32_e64 s[0:1], 0, v158
	v_sub_f32_e32 v128, v128, v140
	s_waitcnt vmcnt(6)
; __device__ __forceinline__ unsigned cvt_pk_bf16(float lo, float hi) { unsigned r; asm volatile("v_cvt_pk_bf16_f32 %0, %1, %2" : "=v"(r) : "v"(lo), "v"(hi)); return r; }
; __device__ __forceinline__ f32x2 ln_stats(f32x2 sm) { const float mu = sm[0] * (1.f / D); const float var = fmaxf(sm[1] * (1.f / D) - mu * mu, 0.f); return (f32x2){mu, 1.0f / sqrtf(var + LN_EPS)}; }
;     __device__ __forceinline__ void operator()(const f32x4 (&acc)[2][2][4][2], const Unit& u, int wr, int wc, int fr, int fq) const {
;     ...
;                 for (int mm = 0; mm < 2; ++mm) {
;                     const int r = row0 + ai * HALF + (2 * m2 + mm) * 16;
;                     float ps = 0.f, pq = 0.f;
; #pragma unroll
;                     for (int bj = 0; bj < 2; ++bj)
; #pragma unroll
;                         for (int n = 0; n < 2; ++n) {
;                             const f32x4 x = (xv[mm][bj][n] - st[mm][0]) * (gg[bj][n] * st[mm][1]) + bb[bj][n];
;                             const f32x4 o = x * alpha + acc[ai][bj][2 * m2 + mm][n] * scale;
;                             const size_t off = (size_t)r * D + col0 + bj * HALF + n * 16;
;                             *(f32x4*)(Y + off) = o;
;                             if (yb) { u32x2 w; w.x = cvt_pk_bf16(o[0], o[1]); w.y = cvt_pk_bf16(o[2], o[3]); *(u32x2*)(yb + off) = w; }
;                             ps += (o[0] + o[1]) + (o[2] + o[3]); pq += (o[0] * o[0] + o[1] * o[1]) + (o[2] * o[2] + o[3] * o[3]);
;                         }
;                     if (rout) {
;                         ps += __shfl_xor(ps, 16); pq += __shfl_xor(pq, 16); ps += __shfl_xor(ps, 32); pq += __shfl_xor(pq, 32);
;                         if (fq == 0) { atomicAdd(rout + 2 * (size_t)r, ps); atomicAdd(rout + 2 * (size_t)r + 1, pq); }
;                     }
	v_sub_f32_e32 v135, v135, v140
	v_cndmask_b32_e64 v152, v152, v154, s[0:1]
	v_mul_f32_e32 v153, 0x37800000, v152
	v_cndmask_b32_e32 v152, v152, v153, vcc
	v_cmp_class_f32_e32 vcc, v141, v212
	v_sub_f32_e32 v134, v134, v140
	v_sub_f32_e32 v133, v133, v140
	v_cndmask_b32_e32 v141, v152, v141, vcc
	v_div_scale_f32 v152, s[0:1], v141, v141, 1.0
	v_rcp_f32_e32 v153, v152
	v_div_scale_f32 v154, vcc, 1.0, v141, 1.0
	v_sub_f32_e32 v132, v132, v140
	v_fma_f32 v155, -v152, v153, 1.0
	v_fmac_f32_e32 v153, v155, v153
	v_mul_f32_e32 v155, v154, v153
	v_fma_f32 v158, -v152, v155, v154
	v_fmac_f32_e32 v155, v158, v153
	v_fma_f32 v152, -v152, v155, v154
	v_div_fmas_f32 v152, v152, v153, v155
	v_div_fixup_f32 v152, v152, v141, 1.0
	v_pk_mul_f32 v[154:155], v[94:95], v[152:153] op_sel_hi:[1,0]
	v_pk_mul_f32 v[158:159], v[92:93], v[152:153] op_sel_hi:[1,0]
	v_pk_mul_f32 v[160:161], v[78:79], v[152:153] op_sel_hi:[1,0]
	v_pk_mul_f32 v[162:163], v[76:77], v[152:153] op_sel_hi:[1,0]
	v_pk_fma_f32 v[124:125], v[124:125], v[158:159], v[88:89]
	v_pk_fma_f32 v[126:127], v[126:127], v[154:155], v[90:91]
	v_pk_mul_f32 v[164:165], v[70:71], v[152:153] op_sel_hi:[1,0]
	v_pk_fma_f32 v[128:129], v[128:129], v[162:163], v[72:73]
	v_pk_fma_f32 v[130:131], v[130:131], v[160:161], v[74:75]
	v_pk_fma_f32 v[86:87], v[126:127], s[20:21], v[86:87] op_sel_hi:[1,0,1]
	v_pk_fma_f32 v[84:85], v[124:125], s[20:21], v[84:85] op_sel_hi:[1,0,1]
	v_pk_fma_f32 v[134:135], v[134:135], v[164:165], v[66:67]
	v_pk_fma_f32 v[82:83], v[130:131], s[20:21], v[82:83] op_sel_hi:[1,0,1]
	v_pk_fma_f32 v[80:81], v[128:129], s[20:21], v[80:81] op_sel_hi:[1,0,1]
	global_store_dwordx4 v[142:143], v[84:87], off sc1
	v_cvt_pk_bf16_f32 v124, v84, v85
	v_add_f32_e32 v126, v84, v85
	v_add_f32_e32 v127, v87, v86
	v_pk_mul_f32 v[166:167], v[68:69], v[152:153] op_sel_hi:[1,0]
	v_pk_fma_f32 v[62:63], v[134:135], s[20:21], v[62:63] op_sel_hi:[1,0,1]
	v_cvt_pk_bf16_f32 v125, v86, v87
	v_mul_f32_e32 v128, v85, v85
	v_mul_f32_e32 v86, v86, v86
	v_add_f32_e32 v129, v80, v81
	v_add_f32_e32 v130, v83, v82
	v_mul_f32_e32 v131, v81, v81
	v_mul_f32_e32 v134, v82, v82
	global_store_dwordx2 v[144:145], v[124:125], off
	v_add_f32_e32 v124, v126, v127
	v_pk_fma_f32 v[132:133], v[132:133], v[166:167], v[64:65]
	v_fmac_f32_e32 v128, v84, v84
	v_fmac_f32_e32 v86, v87, v87
	global_store_dwordx4 v[150:151], v[80:83], off sc1
	v_cvt_pk_bf16_f32 v84, v80, v81
	v_fmac_f32_e32 v131, v80, v80
	v_fmac_f32_e32 v134, v83, v83
	v_add_f32_e32 v81, v129, v130
	v_add_f32_e32 v80, 0, v124
	v_cvt_pk_bf16_f32 v85, v82, v83
	v_add_f32_e32 v82, v128, v86
	global_store_dwordx2 v[146:147], v[84:85], off
	v_add_f32_e32 v83, v131, v134
	v_add_f32_e32 v84, v81, v80
	v_pk_fma_f32 v[60:61], v[132:133], s[20:21], v[60:61] op_sel_hi:[1,0,1]
	v_lshl_add_u64 v[80:81], v[148:149], 2, s[38:39]
	v_add_f32_e32 v85, v82, v83
	global_store_dwordx4 v[80:81], v[60:63], off sc1
	v_cvt_pk_bf16_f32 v80, v60, v61
	v_lshl_add_u64 v[82:83], v[148:149], 1, s[6:7]
	v_cvt_pk_bf16_f32 v81, v62, v63
	global_store_dwordx2 v[82:83], v[80:81], off
	v_add_f32_e32 v80, v60, v61
	v_mul_f32_e32 v61, v61, v61
	v_fmac_f32_e32 v61, v60, v60
	v_mul_f32_e32 v60, v62, v62
	v_add_f32_e32 v81, v63, v62
	v_fmac_f32_e32 v60, v63, v63
	v_add_f32_e32 v80, v80, v81
	v_add_f32_e32 v60, v61, v60
	v_add_f32_e32 v84, v80, v84
	v_add_f32_e32 v85, v60, v85
	s_waitcnt vmcnt(11)
	v_sub_f32_e32 v61, v139, v140
	v_sub_f32_e32 v60, v138, v140
	v_sub_f32_e32 v63, v137, v140
	v_sub_f32_e32 v62, v136, v140
	v_pk_mul_f32 v[80:81], v[58:59], v[152:153] op_sel_hi:[1,0]
	v_pk_mul_f32 v[82:83], v[56:57], v[152:153] op_sel_hi:[1,0]
	v_pk_fma_f32 v[60:61], v[60:61], v[80:81], v[54:55]
	v_pk_fma_f32 v[82:83], v[62:63], v[82:83], v[52:53]
	v_pk_fma_f32 v[62:63], v[60:61], s[20:21], v[50:51] op_sel_hi:[1,0,1]
	v_pk_fma_f32 v[60:61], v[82:83], s[20:21], v[48:49] op_sel_hi:[1,0,1]
	v_mul_f32_e32 v49, v62, v62
	v_mul_f32_e32 v48, v61, v61
	v_fmac_f32_e32 v48, v60, v60
	v_fmac_f32_e32 v49, v63, v63
	v_add_f32_e32 v48, v48, v49
	v_add_f32_e32 v50, v48, v85
	v_add_f32_e32 v48, v60, v61
	v_add_f32_e32 v49, v63, v62
	v_add_f32_e32 v48, v48, v49
	v_add_f32_e32 v51, v48, v84
	ds_bpermute_b32 v80, v156, v51
	ds_bpermute_b32 v81, v156, v50
	v_lshl_add_u64 v[48:49], v[122:123], 2, s[38:39]
	global_store_dwordx4 v[48:49], v[60:63], off sc1
	s_waitcnt lgkmcnt(1)
	v_add_f32_e32 v48, v51, v80
	s_waitcnt lgkmcnt(0)
	v_add_f32_e32 v49, v50, v81
	ds_bpermute_b32 v50, v157, v48
	ds_bpermute_b32 v51, v157, v49
	v_cvt_pk_bf16_f32 v60, v60, v61
	v_cvt_pk_bf16_f32 v61, v62, v63
	v_lshl_add_u64 v[62:63], v[122:123], 1, s[6:7]
	global_store_dwordx2 v[62:63], v[60:61], off
	s_and_saveexec_b64 s[0:1], s[4:5]
	s_cbranch_execz .LBB0_958
	v_lshl_add_u64 v[60:61], s[8:9], 0, v[120:121]
	s_waitcnt lgkmcnt(1)
	v_add_f32_e32 v48, v48, v50
	s_waitcnt lgkmcnt(0)
	v_add_f32_e32 v49, v49, v51
	global_atomic_add_f32 v[60:61], v48, off
	global_atomic_add_f32 v[60:61], v49, off offset:4
; __device__ __forceinline__ unsigned cvt_pk_bf16(float lo, float hi) { unsigned r; asm volatile("v_cvt_pk_bf16_f32 %0, %1, %2" : "=v"(r) : "v"(lo), "v"(hi)); return r; }
; __device__ __forceinline__ f32x2 ln_stats(f32x2 sm) { const float mu = sm[0] * (1.f / D); const float var = fmaxf(sm[1] * (1.f / D) - mu * mu, 0.f); return (f32x2){mu, 1.0f / sqrtf(var + LN_EPS)}; }
;     __device__ __forceinline__ void operator()(const f32x4 (&acc)[2][2][4][2], const Unit& u, int wr, int wc, int fr, int fq) const {
;     ...
;                 for (int mm = 0; mm < 2; ++mm) {
;                     const int r = row0 + ai * HALF + (2 * m2 + mm) * 16;
;                     float ps = 0.f, pq = 0.f;
; #pragma unroll
;                     for (int bj = 0; bj < 2; ++bj)
; #pragma unroll
;                         for (int n = 0; n < 2; ++n) {
;                             const f32x4 x = (xv[mm][bj][n] - st[mm][0]) * (gg[bj][n] * st[mm][1]) + bb[bj][n];
;                             const f32x4 o = x * alpha + acc[ai][bj][2 * m2 + mm][n] * scale;
;                             const size_t off = (size_t)r * D + col0 + bj * HALF + n * 16;
;                             *(f32x4*)(Y + off) = o;
;                             if (yb) { u32x2 w; w.x = cvt_pk_bf16(o[0], o[1]); w.y = cvt_pk_bf16(o[2], o[3]); *(u32x2*)(yb + off) = w; }
;                             ps += (o[0] + o[1]) + (o[2] + o[3]); pq += (o[0] * o[0] + o[1] * o[1]) + (o[2] * o[2] + o[3] * o[3]);
;                         }
;                     if (rout) {
;                         ps += __shfl_xor(ps, 16); pq += __shfl_xor(pq, 16); ps += __shfl_xor(ps, 32); pq += __shfl_xor(pq, 32);
;                         if (fq == 0) { atomicAdd(rout + 2 * (size_t)r, ps); atomicAdd(rout + 2 * (size_t)r + 1, pq); }
;                     }
.LBB0_958:
	s_or_b64 exec, exec, s[0:1]
	s_waitcnt vmcnt(12)
	v_mul_f32_e32 v48, 0x3a000000, v114
	v_mul_f32_e32 v48, v48, v48
	v_fma_f32 v48, v115, s18, -v48
	v_max_f32_e32 v48, 0, v48
	v_add_f32_e32 v48, 0x3727c5ac, v48
	v_mul_f32_e32 v49, 0x4f800000, v48
	v_cmp_gt_f32_e32 vcc, s52, v48
	s_waitcnt vmcnt(11)
	v_fmamk_f32 v109, v114, 0xba000000, v109
	v_fmac_f32_e32 v108, 0xba000000, v114
	v_cndmask_b32_e32 v48, v48, v49, vcc
	v_sqrt_f32_e32 v49, v48
	s_waitcnt vmcnt(10)
	v_fmamk_f32 v105, v114, 0xba000000, v105
	v_fmac_f32_e32 v104, 0xba000000, v114
	s_waitcnt vmcnt(9)
	v_fmamk_f32 v101, v114, 0xba000000, v101
	s_waitcnt lgkmcnt(1)
	v_add_u32_e32 v50, -1, v49
	v_fma_f32 v60, -v50, v49, v48
	s_waitcnt lgkmcnt(0)
	v_add_u32_e32 v51, 1, v49
	v_cmp_ge_f32_e64 s[0:1], 0, v60
	v_fmac_f32_e32 v100, 0xba000000, v114
	s_waitcnt vmcnt(8)
	v_fmamk_f32 v97, v114, 0xba000000, v97
	v_cndmask_b32_e64 v50, v49, v50, s[0:1]
	v_fma_f32 v49, -v51, v49, v48
	v_cmp_lt_f32_e64 s[0:1], 0, v49
	v_fmac_f32_e32 v96, 0xba000000, v114
	s_nop 0
	v_cndmask_b32_e64 v49, v50, v51, s[0:1]
	v_mul_f32_e32 v50, 0x37800000, v49
	v_cndmask_b32_e32 v49, v49, v50, vcc
	v_cmp_class_f32_e32 vcc, v48, v212
	s_nop 1
	v_cndmask_b32_e32 v48, v49, v48, vcc
	v_div_scale_f32 v49, s[0:1], v48, v48, 1.0
	v_rcp_f32_e32 v50, v49
	s_nop 0
	v_fma_f32 v51, -v49, v50, 1.0
	v_fmac_f32_e32 v50, v51, v50
	v_div_scale_f32 v51, vcc, 1.0, v48, 1.0
	v_mul_f32_e32 v60, v51, v50
	v_fma_f32 v61, -v49, v60, v51
	v_fmac_f32_e32 v60, v61, v50
	v_fma_f32 v49, -v49, v60, v51
	v_div_fmas_f32 v49, v49, v50, v60
	v_div_fixup_f32 v48, v49, v48, 1.0
	v_fmamk_f32 v61, v114, 0xba000000, v111
	v_fmamk_f32 v60, v114, 0xba000000, v110
	v_pk_mul_f32 v[62:63], v[94:95], v[48:49] op_sel_hi:[1,0]
	v_pk_mul_f32 v[80:81], v[92:93], v[48:49] op_sel_hi:[1,0]
	v_lshlrev_b64 v[50:51], 11, v[118:119]
	v_pk_fma_f32 v[80:81], v[108:109], v[80:81], v[88:89]
	v_pk_fma_f32 v[60:61], v[60:61], v[62:63], v[90:91]
	v_lshl_add_u64 v[50:51], v[50:51], 0, v[190:191]
	v_pk_fma_f32 v[46:47], v[60:61], s[20:21], v[46:47] op_sel_hi:[1,0,1]
	v_pk_fma_f32 v[44:45], v[80:81], s[20:21], v[44:45] op_sel_hi:[1,0,1]
	global_store_dwordx4 v[116:117], v[44:47], off sc1
	v_cvt_pk_bf16_f32 v60, v44, v45
	v_lshl_add_u64 v[62:63], v[50:51], 1, s[6:7]
	v_cvt_pk_bf16_f32 v61, v46, v47
	global_store_dwordx2 v[62:63], v[60:61], off
	v_add_f32_e32 v49, v44, v45
	v_add_f32_e32 v60, v47, v46
	v_mul_f32_e32 v45, v45, v45
	v_add_f32_e32 v49, v49, v60
	v_fmac_f32_e32 v45, v44, v44
	v_mul_f32_e32 v44, v46, v46
	v_add_f32_e32 v49, 0, v49
	v_fmac_f32_e32 v44, v47, v47
	v_add_f32_e32 v62, v45, v44
	v_fmamk_f32 v45, v114, 0xba000000, v107
	v_fmamk_f32 v44, v114, 0xba000000, v106
	v_pk_mul_f32 v[46:47], v[78:79], v[48:49] op_sel_hi:[1,0]
	v_pk_mul_f32 v[60:61], v[76:77], v[48:49] op_sel_hi:[1,0]
	v_pk_fma_f32 v[44:45], v[44:45], v[46:47], v[74:75]
	v_pk_fma_f32 v[60:61], v[104:105], v[60:61], v[72:73]
	v_pk_fma_f32 v[42:43], v[44:45], s[20:21], v[42:43] op_sel_hi:[1,0,1]
	v_or_b32_e32 v44, 16, v50
	v_mov_b32_e32 v45, v51
	v_pk_fma_f32 v[40:41], v[60:61], s[20:21], v[40:41] op_sel_hi:[1,0,1]
	v_lshl_add_u64 v[46:47], v[44:45], 2, s[38:39]
	v_lshl_add_u64 v[44:45], v[44:45], 1, s[6:7]
	global_store_dwordx4 v[46:47], v[40:43], off sc1
	v_cvt_pk_bf16_f32 v46, v40, v41
	v_cvt_pk_bf16_f32 v47, v42, v43
	global_store_dwordx2 v[44:45], v[46:47], off
	v_add_f32_e32 v44, v40, v41
	v_add_f32_e32 v45, v43, v42
	v_mul_f32_e32 v41, v41, v41
	v_add_f32_e32 v44, v44, v45
	v_fmac_f32_e32 v41, v40, v40
	v_mul_f32_e32 v40, v42, v42
	v_add_f32_e32 v49, v44, v49
	v_fmac_f32_e32 v40, v43, v43
	v_add_f32_e32 v40, v41, v40
	v_fmamk_f32 v43, v114, 0xba000000, v103
	v_fmamk_f32 v42, v114, 0xba000000, v102
	v_pk_mul_f32 v[44:45], v[70:71], v[48:49] op_sel_hi:[1,0]
	v_pk_mul_f32 v[46:47], v[68:69], v[48:49] op_sel_hi:[1,0]
	v_add_f32_e32 v60, v62, v40
	v_or_b32_e32 v40, 0x80, v50
	v_mov_b32_e32 v41, v51
	v_pk_fma_f32 v[46:47], v[100:101], v[46:47], v[64:65]
	v_pk_fma_f32 v[42:43], v[42:43], v[44:45], v[66:67]
	v_pk_fma_f32 v[36:37], v[46:47], s[20:21], v[36:37] op_sel_hi:[1,0,1]
	v_pk_fma_f32 v[38:39], v[42:43], s[20:21], v[38:39] op_sel_hi:[1,0,1]
	v_lshl_add_u64 v[42:43], v[40:41], 2, s[38:39]
	v_lshl_add_u64 v[40:41], v[40:41], 1, s[6:7]
	global_store_dwordx4 v[42:43], v[36:39], off sc1
	v_cvt_pk_bf16_f32 v42, v36, v37
	v_cvt_pk_bf16_f32 v43, v38, v39
	global_store_dwordx2 v[40:41], v[42:43], off
	v_add_f32_e32 v40, v36, v37
	v_mul_f32_e32 v37, v37, v37
	v_fmac_f32_e32 v37, v36, v36
	v_mul_f32_e32 v36, v38, v38
	v_add_f32_e32 v41, v39, v38
	v_fmac_f32_e32 v36, v39, v39
	v_add_f32_e32 v40, v40, v41
	v_add_f32_e32 v36, v37, v36
	v_add_f32_e32 v42, v40, v49
	v_add_f32_e32 v43, v36, v60
	v_fmamk_f32 v37, v114, 0xba000000, v99
	v_fmamk_f32 v36, v114, 0xba000000, v98
	v_pk_mul_f32 v[38:39], v[58:59], v[48:49] op_sel_hi:[1,0]
	v_pk_mul_f32 v[40:41], v[56:57], v[48:49] op_sel_hi:[1,0]
	v_pk_fma_f32 v[36:37], v[36:37], v[38:39], v[54:55]
	v_pk_fma_f32 v[40:41], v[96:97], v[40:41], v[52:53]
	v_pk_fma_f32 v[38:39], v[36:37], s[20:21], v[34:35] op_sel_hi:[1,0,1]
	v_pk_fma_f32 v[36:37], v[40:41], s[20:21], v[32:33] op_sel_hi:[1,0,1]
	v_mul_f32_e32 v33, v38, v38
	v_mul_f32_e32 v32, v37, v37
	v_fmac_f32_e32 v32, v36, v36
	v_fmac_f32_e32 v33, v39, v39
	v_add_f32_e32 v32, v32, v33
	v_add_f32_e32 v34, v32, v43
	v_add_f32_e32 v32, v36, v37
	v_add_f32_e32 v33, v39, v38
	v_add_f32_e32 v32, v32, v33
	v_add_f32_e32 v35, v32, v42
	ds_bpermute_b32 v40, v156, v35
	ds_bpermute_b32 v41, v156, v34
	v_or_b32_e32 v50, 0x90, v50
	v_lshl_add_u64 v[32:33], v[50:51], 2, s[38:39]
	global_store_dwordx4 v[32:33], v[36:39], off sc1
	s_waitcnt lgkmcnt(1)
	v_add_f32_e32 v32, v35, v40
	s_waitcnt lgkmcnt(0)
	v_add_f32_e32 v33, v34, v41
	ds_bpermute_b32 v34, v157, v32
	ds_bpermute_b32 v35, v157, v33
	v_cvt_pk_bf16_f32 v36, v36, v37
	v_cvt_pk_bf16_f32 v37, v38, v39
	v_lshl_add_u64 v[38:39], v[50:51], 1, s[6:7]
	global_store_dwordx2 v[38:39], v[36:37], off
	s_and_saveexec_b64 s[0:1], s[4:5]
	s_cbranch_execz .LBB0_960
	v_lshl_add_u64 v[36:37], s[8:9], 0, v[112:113]
	s_waitcnt lgkmcnt(1)
	v_add_f32_e32 v32, v32, v34
	s_waitcnt lgkmcnt(0)
	v_add_f32_e32 v33, v33, v35
	global_atomic_add_f32 v[36:37], v32, off
	global_atomic_add_f32 v[36:37], v33, off offset:4
; __device__ __forceinline__ f32x2 ln_stats(f32x2 sm) { const float mu = sm[0] * (1.f / D); const float var = fmaxf(sm[1] * (1.f / D) - mu * mu, 0.f); return (f32x2){mu, 1.0f / sqrtf(var + LN_EPS)}; }
;     __device__ __forceinline__ void operator()(const f32x4 (&acc)[2][2][4][2], const Unit& u, int wr, int wc, int fr, int fq) const {
;     ...
;                 f32x4 xv[2][2][2]; f32x2 st[2];
; #pragma unroll
;                 for (int mm = 0; mm < 2; ++mm) {
;                     const int r = row0 + ai * HALF + (2 * m2 + mm) * 16;
;                     st[mm] = (f32x2){0.f, 1.f};
;                     if (rin) st[mm] = ln_stats(*(const f32x2*)(rin + 2 * (size_t)r));
; #pragma unroll
;                     for (int bj = 0; bj < 2; ++bj)
; #pragma unroll
;                         for (int n = 0; n < 2; ++n) { const f32x4* rp = (const f32x4*)(res + (size_t)r * D + col0 + bj * HALF + n * 16); xv[mm][bj][n] = stream ? __builtin_nontemporal_load(rp) : *rp; }
;                 }
; #pragma unroll
;                 for (int mm = 0; mm < 2; ++mm) {
;                     const int r = row0 + ai * HALF + (2 * m2 + mm) * 16;
;                     float ps = 0.f, pq = 0.f;
; #pragma unroll
;                     for (int bj = 0; bj < 2; ++bj)
; #pragma unroll
;                         for (int n = 0; n < 2; ++n) {
;                             const f32x4 x = (xv[mm][bj][n] - st[mm][0]) * (gg[bj][n] * st[mm][1]) + bb[bj][n];
;                             const f32x4 o = x * alpha + acc[ai][bj][2 * m2 + mm][n] * scale;
;                             const size_t off = (size_t)r * D + col0 + bj * HALF + n * 16;
;                             *(f32x4*)(Y + off) = o;
;                             if (yb) { u32x2 w; w.x = cvt_pk_bf16(o[0], o[1]); w.y = cvt_pk_bf16(o[2], o[3]); *(u32x2*)(yb + off) = w; }
;                             ps += (o[0] + o[1]) + (o[2] + o[3]); pq += (o[0] * o[0] + o[1] * o[1]) + (o[2] * o[2] + o[3] * o[3]);
;                         }
;                     if (rout) {
;                         ps += __shfl_xor(ps, 16); pq += __shfl_xor(pq, 16); ps += __shfl_xor(ps, 32); pq += __shfl_xor(pq, 32);
;                         if (fq == 0) { atomicAdd(rout + 2 * (size_t)r, ps); atomicAdd(rout + 2 * (size_t)r + 1, pq); }
;                     }
.LBB0_960:
	s_or_b64 exec, exec, s[0:1]
	v_add_u32_e32 v32, 0xa0, v194
	v_ashrrev_i32_e32 v33, 31, v32
	v_lshlrev_b64 v[80:81], 3, v[32:33]
	s_waitcnt lgkmcnt(0)
	v_lshl_add_u64 v[34:35], s[54:55], 0, v[80:81]
	global_load_dwordx2 v[108:109], v[34:35], off
	v_lshlrev_b64 v[34:35], 13, v[32:33]
	v_lshl_add_u64 v[110:111], v[192:193], 0, v[34:35]
	global_load_dwordx4 v[84:87], v[110:111], off
	global_load_dwordx4 v[96:99], v[110:111], off offset:64
	global_load_dwordx4 v[100:103], v[110:111], off offset:512
	v_add_u32_e32 v62, 0xb0, v194
	v_ashrrev_i32_e32 v63, 31, v62
	v_lshlrev_b64 v[48:49], 3, v[62:63]
	v_lshlrev_b64 v[34:35], 13, v[62:63]
	v_lshlrev_b64 v[32:33], 11, v[32:33]
	v_lshl_add_u64 v[36:37], s[54:55], 0, v[48:49]
	v_lshl_add_u64 v[60:61], v[192:193], 0, v[34:35]
	v_lshl_add_u64 v[82:83], v[32:33], 0, v[190:191]
	global_load_dwordx4 v[104:107], v[110:111], off offset:576
	global_load_dwordx2 v[50:51], v[36:37], off
	global_load_dwordx4 v[44:47], v[60:61], off
	global_load_dwordx4 v[40:43], v[60:61], off offset:64
	s_nop 0
	global_load_dwordx4 v[36:39], v[60:61], off offset:512
	global_load_dwordx4 v[32:35], v[60:61], off offset:576
	v_lshl_add_u64 v[112:113], v[82:83], 1, s[6:7]
	v_or_b32_e32 v114, 16, v82
	v_mov_b32_e32 v115, v83
	v_lshl_add_u64 v[118:119], v[114:115], 2, s[38:39]
	v_or_b32_e32 v116, 0x80, v82
	v_mov_b32_e32 v117, v83
	v_lshl_add_u64 v[114:115], v[114:115], 1, s[6:7]
	v_or_b32_e32 v82, 0x90, v82
	s_waitcnt vmcnt(9)
	v_pk_mul_f32 v[108:109], v[108:109], s[18:19] op_sel_hi:[1,0]
	s_nop 0
	v_fma_f32 v109, -v108, v108, v109
	v_max_f32_e32 v109, 0, v109
	v_add_f32_e32 v109, 0x3727c5ac, v109
	v_mul_f32_e32 v120, 0x4f800000, v109
	v_cmp_gt_f32_e32 vcc, s52, v109
	s_waitcnt vmcnt(8)
	v_sub_f32_e32 v87, v87, v108
	v_sub_f32_e32 v86, v86, v108
	v_cndmask_b32_e32 v109, v109, v120, vcc
	v_sqrt_f32_e32 v120, v109
	v_sub_f32_e32 v85, v85, v108
	v_sub_f32_e32 v84, v84, v108
	s_waitcnt vmcnt(7)
	v_sub_f32_e32 v99, v99, v108
	v_add_u32_e32 v121, -1, v120
	v_add_u32_e32 v122, 1, v120
	v_fma_f32 v123, -v121, v120, v109
	v_fma_f32 v124, -v122, v120, v109
	v_cmp_ge_f32_e64 s[0:1], 0, v123
	v_sub_f32_e32 v98, v98, v108
	v_sub_f32_e32 v97, v97, v108
	v_cndmask_b32_e64 v120, v120, v121, s[0:1]
	v_cmp_lt_f32_e64 s[0:1], 0, v124
	v_sub_f32_e32 v96, v96, v108
	s_waitcnt vmcnt(6)
	v_sub_f32_e32 v103, v103, v108
	v_cndmask_b32_e64 v120, v120, v122, s[0:1]
	v_mul_f32_e32 v121, 0x37800000, v120
	v_cndmask_b32_e32 v120, v120, v121, vcc
	v_cmp_class_f32_e32 vcc, v109, v212
	v_sub_f32_e32 v102, v102, v108
	v_sub_f32_e32 v101, v101, v108
	v_cndmask_b32_e32 v109, v120, v109, vcc
	v_div_scale_f32 v120, s[0:1], v109, v109, 1.0
	v_rcp_f32_e32 v121, v120
	v_div_scale_f32 v122, vcc, 1.0, v109, 1.0
	v_sub_f32_e32 v100, v100, v108
	v_fma_f32 v123, -v120, v121, 1.0
	v_fmac_f32_e32 v121, v123, v121
	v_mul_f32_e32 v123, v122, v121
	v_fma_f32 v124, -v120, v123, v122
	v_fmac_f32_e32 v123, v124, v121
	v_fma_f32 v120, -v120, v123, v122
	v_div_fmas_f32 v120, v120, v121, v123
	v_div_fixup_f32 v120, v120, v109, 1.0
	v_pk_mul_f32 v[122:123], v[94:95], v[120:121] op_sel_hi:[1,0]
	v_pk_mul_f32 v[124:125], v[92:93], v[120:121] op_sel_hi:[1,0]
	v_pk_mul_f32 v[126:127], v[78:79], v[120:121] op_sel_hi:[1,0]
	v_pk_mul_f32 v[128:129], v[76:77], v[120:121] op_sel_hi:[1,0]
	v_pk_fma_f32 v[84:85], v[84:85], v[124:125], v[88:89]
	v_pk_fma_f32 v[86:87], v[86:87], v[122:123], v[90:91]
	v_pk_mul_f32 v[130:131], v[70:71], v[120:121] op_sel_hi:[1,0]
	v_pk_fma_f32 v[96:97], v[96:97], v[128:129], v[72:73]
	v_pk_fma_f32 v[98:99], v[98:99], v[126:127], v[74:75]
	v_pk_fma_f32 v[30:31], v[86:87], s[20:21], v[30:31] op_sel_hi:[1,0,1]
	v_pk_fma_f32 v[28:29], v[84:85], s[20:21], v[28:29] op_sel_hi:[1,0,1]
	v_pk_fma_f32 v[102:103], v[102:103], v[130:131], v[66:67]
	v_pk_fma_f32 v[26:27], v[98:99], s[20:21], v[26:27] op_sel_hi:[1,0,1]
	v_pk_fma_f32 v[24:25], v[96:97], s[20:21], v[24:25] op_sel_hi:[1,0,1]
	global_store_dwordx4 v[110:111], v[28:31], off sc1
	v_cvt_pk_bf16_f32 v84, v28, v29
	v_add_f32_e32 v86, v28, v29
	v_add_f32_e32 v87, v31, v30
	v_pk_mul_f32 v[132:133], v[68:69], v[120:121] op_sel_hi:[1,0]
	v_pk_fma_f32 v[22:23], v[102:103], s[20:21], v[22:23] op_sel_hi:[1,0,1]
	v_cvt_pk_bf16_f32 v85, v30, v31
	v_mul_f32_e32 v96, v29, v29
	v_mul_f32_e32 v30, v30, v30
	v_add_f32_e32 v97, v24, v25
	v_add_f32_e32 v98, v27, v26
	v_mul_f32_e32 v99, v25, v25
	v_mul_f32_e32 v102, v26, v26
	global_store_dwordx2 v[112:113], v[84:85], off
	v_add_f32_e32 v84, v86, v87
	v_pk_fma_f32 v[100:101], v[100:101], v[132:133], v[64:65]
	v_fmac_f32_e32 v96, v28, v28
	v_fmac_f32_e32 v30, v31, v31
	global_store_dwordx4 v[118:119], v[24:27], off sc1
	v_cvt_pk_bf16_f32 v28, v24, v25
	v_fmac_f32_e32 v99, v24, v24
	v_fmac_f32_e32 v102, v27, v27
	v_add_f32_e32 v25, v97, v98
	v_add_f32_e32 v24, 0, v84
	v_cvt_pk_bf16_f32 v29, v26, v27
	v_add_f32_e32 v26, v96, v30
	global_store_dwordx2 v[114:115], v[28:29], off
	v_add_f32_e32 v27, v99, v102
	v_add_f32_e32 v28, v25, v24
	v_pk_fma_f32 v[20:21], v[100:101], s[20:21], v[20:21] op_sel_hi:[1,0,1]
	v_lshl_add_u64 v[24:25], v[116:117], 2, s[38:39]
	v_add_f32_e32 v29, v26, v27
	global_store_dwordx4 v[24:25], v[20:23], off sc1
	v_cvt_pk_bf16_f32 v24, v20, v21
	v_lshl_add_u64 v[26:27], v[116:117], 1, s[6:7]
	v_cvt_pk_bf16_f32 v25, v22, v23
	global_store_dwordx2 v[26:27], v[24:25], off
	v_add_f32_e32 v24, v20, v21
	v_mul_f32_e32 v21, v21, v21
	v_fmac_f32_e32 v21, v20, v20
	v_mul_f32_e32 v20, v22, v22
	v_add_f32_e32 v25, v23, v22
	v_fmac_f32_e32 v20, v23, v23
	v_add_f32_e32 v24, v24, v25
	v_add_f32_e32 v20, v21, v20
	v_add_f32_e32 v28, v24, v28
	v_add_f32_e32 v29, v20, v29
	s_waitcnt vmcnt(11)
	v_sub_f32_e32 v21, v107, v108
	v_sub_f32_e32 v20, v106, v108
	v_sub_f32_e32 v23, v105, v108
	v_sub_f32_e32 v22, v104, v108
	v_pk_mul_f32 v[24:25], v[58:59], v[120:121] op_sel_hi:[1,0]
	v_pk_mul_f32 v[26:27], v[56:57], v[120:121] op_sel_hi:[1,0]
	v_pk_fma_f32 v[20:21], v[20:21], v[24:25], v[54:55]
	v_pk_fma_f32 v[26:27], v[22:23], v[26:27], v[52:53]
	v_pk_fma_f32 v[22:23], v[20:21], s[20:21], v[18:19] op_sel_hi:[1,0,1]
	v_pk_fma_f32 v[20:21], v[26:27], s[20:21], v[16:17] op_sel_hi:[1,0,1]
	v_mul_f32_e32 v17, v22, v22
	v_mul_f32_e32 v16, v21, v21
	v_fmac_f32_e32 v16, v20, v20
	v_fmac_f32_e32 v17, v23, v23
	v_add_f32_e32 v16, v16, v17
	v_add_f32_e32 v18, v16, v29
	v_add_f32_e32 v16, v20, v21
	v_add_f32_e32 v17, v23, v22
	v_add_f32_e32 v16, v16, v17
	v_add_f32_e32 v19, v16, v28
	ds_bpermute_b32 v24, v156, v19
	ds_bpermute_b32 v25, v156, v18
	v_lshl_add_u64 v[16:17], v[82:83], 2, s[38:39]
	global_store_dwordx4 v[16:17], v[20:23], off sc1
	s_waitcnt lgkmcnt(1)
	v_add_f32_e32 v16, v19, v24
	s_waitcnt lgkmcnt(0)
	v_add_f32_e32 v17, v18, v25
	ds_bpermute_b32 v18, v157, v16
	ds_bpermute_b32 v19, v157, v17
	v_cvt_pk_bf16_f32 v20, v20, v21
	v_cvt_pk_bf16_f32 v21, v22, v23
	v_lshl_add_u64 v[22:23], v[82:83], 1, s[6:7]
	global_store_dwordx2 v[22:23], v[20:21], off
	s_and_saveexec_b64 s[0:1], s[4:5]
	s_cbranch_execz .LBB0_962
; __device__ __forceinline__ unsigned cvt_pk_bf16(float lo, float hi) { unsigned r; asm volatile("v_cvt_pk_bf16_f32 %0, %1, %2" : "=v"(r) : "v"(lo), "v"(hi)); return r; }
; __device__ __forceinline__ f32x2 ln_stats(f32x2 sm) { const float mu = sm[0] * (1.f / D); const float var = fmaxf(sm[1] * (1.f / D) - mu * mu, 0.f); return (f32x2){mu, 1.0f / sqrtf(var + LN_EPS)}; }
;     __device__ __forceinline__ void operator()(const f32x4 (&acc)[2][2][4][2], const Unit& u, int wr, int wc, int fr, int fq) const {
;     ...
;                 for (int mm = 0; mm < 2; ++mm) {
;                     const int r = row0 + ai * HALF + (2 * m2 + mm) * 16;
;                     float ps = 0.f, pq = 0.f;
; #pragma unroll
;                     for (int bj = 0; bj < 2; ++bj)
; #pragma unroll
;                         for (int n = 0; n < 2; ++n) {
;                             const f32x4 x = (xv[mm][bj][n] - st[mm][0]) * (gg[bj][n] * st[mm][1]) + bb[bj][n];
;                             const f32x4 o = x * alpha + acc[ai][bj][2 * m2 + mm][n] * scale;
;                             const size_t off = (size_t)r * D + col0 + bj * HALF + n * 16;
;                             *(f32x4*)(Y + off) = o;
;                             if (yb) { u32x2 w; w.x = cvt_pk_bf16(o[0], o[1]); w.y = cvt_pk_bf16(o[2], o[3]); *(u32x2*)(yb + off) = w; }
;                             ps += (o[0] + o[1]) + (o[2] + o[3]); pq += (o[0] * o[0] + o[1] * o[1]) + (o[2] * o[2] + o[3] * o[3]);
;                         }
;                     if (rout) {
;                         ps += __shfl_xor(ps, 16); pq += __shfl_xor(pq, 16); ps += __shfl_xor(ps, 32); pq += __shfl_xor(pq, 32);
;                         if (fq == 0) { atomicAdd(rout + 2 * (size_t)r, ps); atomicAdd(rout + 2 * (size_t)r + 1, pq); }
;                     }
	v_lshl_add_u64 v[20:21], s[8:9], 0, v[80:81]
	s_waitcnt lgkmcnt(1)
	v_add_f32_e32 v16, v16, v18
	s_waitcnt lgkmcnt(0)
	v_add_f32_e32 v17, v17, v19
	global_atomic_add_f32 v[20:21], v16, off
	global_atomic_add_f32 v[20:21], v17, off offset:4
.LBB0_962:
	s_or_b64 exec, exec, s[0:1]
	s_waitcnt vmcnt(12)
	v_mul_f32_e32 v16, 0x3a000000, v50
	v_mul_f32_e32 v16, v16, v16
	v_fma_f32 v16, v51, s18, -v16
	v_max_f32_e32 v16, 0, v16
	v_add_f32_e32 v16, 0x3727c5ac, v16
	v_mul_f32_e32 v17, 0x4f800000, v16
	v_cmp_gt_f32_e32 vcc, s52, v16
	s_waitcnt vmcnt(11)
	v_fmamk_f32 v45, v50, 0xba000000, v45
	v_fmac_f32_e32 v44, 0xba000000, v50
	v_cndmask_b32_e32 v16, v16, v17, vcc
	v_sqrt_f32_e32 v17, v16
	s_waitcnt vmcnt(10)
	v_fmamk_f32 v41, v50, 0xba000000, v41
	v_fmac_f32_e32 v40, 0xba000000, v50
	s_waitcnt vmcnt(9)
	v_fmamk_f32 v37, v50, 0xba000000, v37
	s_waitcnt lgkmcnt(1)
	v_add_u32_e32 v18, -1, v17
	v_fma_f32 v20, -v18, v17, v16
	s_waitcnt lgkmcnt(0)
	v_add_u32_e32 v19, 1, v17
	v_cmp_ge_f32_e64 s[0:1], 0, v20
	v_fmac_f32_e32 v36, 0xba000000, v50
	s_waitcnt vmcnt(8)
	v_fmamk_f32 v33, v50, 0xba000000, v33
	v_cndmask_b32_e64 v18, v17, v18, s[0:1]
	v_fma_f32 v17, -v19, v17, v16
	v_cmp_lt_f32_e64 s[0:1], 0, v17
	v_fmac_f32_e32 v32, 0xba000000, v50
	s_nop 0
	v_cndmask_b32_e64 v17, v18, v19, s[0:1]
	v_mul_f32_e32 v18, 0x37800000, v17
	v_cndmask_b32_e32 v17, v17, v18, vcc
	v_cmp_class_f32_e32 vcc, v16, v212
	s_nop 1
	v_cndmask_b32_e32 v16, v17, v16, vcc
	v_div_scale_f32 v17, s[0:1], v16, v16, 1.0
	v_rcp_f32_e32 v18, v17
	s_nop 0
	v_fma_f32 v19, -v17, v18, 1.0
	v_fmac_f32_e32 v18, v19, v18
	v_div_scale_f32 v19, vcc, 1.0, v16, 1.0
	v_mul_f32_e32 v20, v19, v18
	v_fma_f32 v21, -v17, v20, v19
	v_fmac_f32_e32 v20, v21, v18
	v_fma_f32 v17, -v17, v20, v19
	v_div_fmas_f32 v17, v17, v18, v20
	v_div_fixup_f32 v16, v17, v16, 1.0
	v_fmamk_f32 v21, v50, 0xba000000, v47
	v_fmamk_f32 v20, v50, 0xba000000, v46
	v_pk_mul_f32 v[22:23], v[94:95], v[16:17] op_sel_hi:[1,0]
	v_pk_mul_f32 v[24:25], v[92:93], v[16:17] op_sel_hi:[1,0]
	v_lshlrev_b64 v[18:19], 11, v[62:63]
	v_pk_fma_f32 v[24:25], v[44:45], v[24:25], v[88:89]
	v_pk_fma_f32 v[20:21], v[20:21], v[22:23], v[90:91]
	v_lshl_add_u64 v[18:19], v[18:19], 0, v[190:191]
	v_pk_fma_f32 v[14:15], v[20:21], s[20:21], v[14:15] op_sel_hi:[1,0,1]
	v_pk_fma_f32 v[12:13], v[24:25], s[20:21], v[12:13] op_sel_hi:[1,0,1]
	global_store_dwordx4 v[60:61], v[12:15], off sc1
	v_cvt_pk_bf16_f32 v20, v12, v13
	v_lshl_add_u64 v[22:23], v[18:19], 1, s[6:7]
	v_cvt_pk_bf16_f32 v21, v14, v15
	global_store_dwordx2 v[22:23], v[20:21], off
	v_add_f32_e32 v17, v12, v13
	v_add_f32_e32 v20, v15, v14
	v_mul_f32_e32 v13, v13, v13
	v_add_f32_e32 v17, v17, v20
	v_fmac_f32_e32 v13, v12, v12
	v_mul_f32_e32 v12, v14, v14
	v_add_f32_e32 v17, 0, v17
	v_fmac_f32_e32 v12, v15, v15
	v_add_f32_e32 v22, v13, v12
	v_fmamk_f32 v13, v50, 0xba000000, v43
	v_fmamk_f32 v12, v50, 0xba000000, v42
	v_pk_mul_f32 v[14:15], v[78:79], v[16:17] op_sel_hi:[1,0]
	v_pk_mul_f32 v[20:21], v[76:77], v[16:17] op_sel_hi:[1,0]
	v_pk_fma_f32 v[12:13], v[12:13], v[14:15], v[74:75]
	v_pk_fma_f32 v[20:21], v[40:41], v[20:21], v[72:73]
	v_pk_fma_f32 v[10:11], v[12:13], s[20:21], v[10:11] op_sel_hi:[1,0,1]
	v_or_b32_e32 v12, 16, v18
	v_mov_b32_e32 v13, v19
	v_pk_fma_f32 v[8:9], v[20:21], s[20:21], v[8:9] op_sel_hi:[1,0,1]
	v_lshl_add_u64 v[14:15], v[12:13], 2, s[38:39]
	v_lshl_add_u64 v[12:13], v[12:13], 1, s[6:7]
	global_store_dwordx4 v[14:15], v[8:11], off sc1
	v_cvt_pk_bf16_f32 v14, v8, v9
	v_cvt_pk_bf16_f32 v15, v10, v11
	global_store_dwordx2 v[12:13], v[14:15], off
	v_add_f32_e32 v12, v8, v9
	v_add_f32_e32 v13, v11, v10
	v_mul_f32_e32 v9, v9, v9
	v_add_f32_e32 v12, v12, v13
	v_fmac_f32_e32 v9, v8, v8
	v_mul_f32_e32 v8, v10, v10
	v_add_f32_e32 v17, v12, v17
	v_fmac_f32_e32 v8, v11, v11
	v_add_f32_e32 v8, v9, v8
	v_fmamk_f32 v11, v50, 0xba000000, v39
	v_fmamk_f32 v10, v50, 0xba000000, v38
	v_pk_mul_f32 v[12:13], v[70:71], v[16:17] op_sel_hi:[1,0]
	v_pk_mul_f32 v[14:15], v[68:69], v[16:17] op_sel_hi:[1,0]
	v_add_f32_e32 v20, v22, v8
	v_or_b32_e32 v8, 0x80, v18
	v_mov_b32_e32 v9, v19
	v_pk_fma_f32 v[14:15], v[36:37], v[14:15], v[64:65]
	v_pk_fma_f32 v[10:11], v[10:11], v[12:13], v[66:67]
	v_pk_fma_f32 v[4:5], v[14:15], s[20:21], v[4:5] op_sel_hi:[1,0,1]
	v_pk_fma_f32 v[6:7], v[10:11], s[20:21], v[6:7] op_sel_hi:[1,0,1]
	v_lshl_add_u64 v[10:11], v[8:9], 2, s[38:39]
	v_lshl_add_u64 v[8:9], v[8:9], 1, s[6:7]
	global_store_dwordx4 v[10:11], v[4:7], off sc1
	v_cvt_pk_bf16_f32 v10, v4, v5
	v_cvt_pk_bf16_f32 v11, v6, v7
	global_store_dwordx2 v[8:9], v[10:11], off
	v_add_f32_e32 v8, v4, v5
	v_mul_f32_e32 v5, v5, v5
	v_fmac_f32_e32 v5, v4, v4
	v_mul_f32_e32 v4, v6, v6
	v_add_f32_e32 v9, v7, v6
	v_fmac_f32_e32 v4, v7, v7
	v_add_f32_e32 v8, v8, v9
	v_add_f32_e32 v4, v5, v4
	v_add_f32_e32 v10, v8, v17
	v_add_f32_e32 v11, v4, v20
	v_fmamk_f32 v5, v50, 0xba000000, v35
	v_fmamk_f32 v4, v50, 0xba000000, v34
	v_pk_mul_f32 v[6:7], v[58:59], v[16:17] op_sel_hi:[1,0]
	v_pk_mul_f32 v[8:9], v[56:57], v[16:17] op_sel_hi:[1,0]
	v_pk_fma_f32 v[4:5], v[4:5], v[6:7], v[54:55]
	v_pk_fma_f32 v[8:9], v[32:33], v[8:9], v[52:53]
	v_pk_fma_f32 v[6:7], v[4:5], s[20:21], v[2:3] op_sel_hi:[1,0,1]
	v_pk_fma_f32 v[4:5], v[8:9], s[20:21], v[0:1] op_sel_hi:[1,0,1]
	v_mul_f32_e32 v1, v6, v6
	v_mul_f32_e32 v0, v5, v5
	v_fmac_f32_e32 v0, v4, v4
	v_fmac_f32_e32 v1, v7, v7
	v_add_f32_e32 v0, v0, v1
	v_add_f32_e32 v2, v0, v11
	v_add_f32_e32 v0, v4, v5
	v_add_f32_e32 v1, v7, v6
	v_add_f32_e32 v0, v0, v1
	v_add_f32_e32 v3, v0, v10
	ds_bpermute_b32 v8, v156, v3
	ds_bpermute_b32 v9, v156, v2
	v_or_b32_e32 v18, 0x90, v18
	v_lshl_add_u64 v[0:1], v[18:19], 2, s[38:39]
	global_store_dwordx4 v[0:1], v[4:7], off sc1
	s_waitcnt lgkmcnt(1)
	v_add_f32_e32 v0, v3, v8
	s_waitcnt lgkmcnt(0)
	v_add_f32_e32 v1, v2, v9
	ds_bpermute_b32 v2, v157, v0
	ds_bpermute_b32 v3, v157, v1
	v_cvt_pk_bf16_f32 v4, v4, v5
	v_cvt_pk_bf16_f32 v5, v6, v7
	v_lshl_add_u64 v[6:7], v[18:19], 1, s[6:7]
	global_store_dwordx2 v[6:7], v[4:5], off
	s_and_saveexec_b64 s[0:1], s[4:5]
	s_cbranch_execz .LBB0_964
	v_lshl_add_u64 v[4:5], s[8:9], 0, v[48:49]
	s_waitcnt lgkmcnt(1)
	v_add_f32_e32 v0, v0, v2
	s_waitcnt lgkmcnt(0)
	v_add_f32_e32 v1, v1, v3
	global_atomic_add_f32 v[4:5], v0, off
	global_atomic_add_f32 v[4:5], v1, off offset:4

; __device__ __forceinline__ float sigmoidf_(float x) { return __builtin_amdgcn_rcpf(1.0f + __expf(-x)); }
; __device__ __forceinline__ float siluf_(float x) { return x * sigmoidf_(x); }
; __device__ __forceinline__ float gelu_tanh(float x) { return x * sigmoidf_(1.5957691216057308f * (x + 0.044715f * x * x * x)); }
; __device__ __forceinline__ f32x2 ln_stats(f32x2 sm) { const float mu = sm[0] * (1.f / D); const float var = fmaxf(sm[1] * (1.f / D) - mu * mu, 0.f); return (f32x2){mu, 1.0f / sqrtf(var + LN_EPS)}; }
;     __device__ __forceinline__ void operator()(const f32x4 (&acc)[2][2][4][2], const Unit& u, int wr, int wc, int fr, int fq) const {
;         const int row0 = u.pm * BM + wr * 64 + fr, col0 = u.pn * HALF + wc * 32 + 8 * fq;
;         f32x4 s1[2][2], s2[2][2];
; #pragma unroll
;         for (int bj = 0; bj < 2; ++bj)
; #pragma unroll
;             for (int n = 0; n < 2; ++n) { s1[bj][n] = (f32x4){0.f, 0.f, 0.f, 0.f}; s2[bj][n] = s1[bj][n];
;                 if (rsum) { const int ci = u.pn * BM + bj * HALF + wc * 32 + 8 * fq + 4 * n; s1[bj][n] = *(const f32x4*)(cs + ci); s2[bj][n] = *(const f32x4*)(cs + NZ + ci); } }
; #pragma unroll
;         for (int ai = 0; ai < 2; ++ai)
; #pragma unroll
;             for (int m = 0; m < 4; ++m) {
;                 const int r = row0 + ai * HALF + m * 16;
;                 bf16_t* rowp = H + (size_t)r * ldh + col0;
;                 f32x2 st = (f32x2){0.f, 1.f};
;                 if (rsum) st = ln_stats(*(const f32x2*)(rsum + 2 * (size_t)r));
;                 f32x4 v0, v1;
; #pragma unroll
;                 for (int j = 0; j < 4; ++j) {
;                     const float g0 = st[1] * (acc[ai][0][m][0][j] - st[0] * s1[0][0][j]) + s2[0][0][j], u0 = st[1] * (acc[ai][1][m][0][j] - st[0] * s1[1][0][j]) + s2[1][0][j];
;                     const float g1 = st[1] * (acc[ai][0][m][1][j] - st[0] * s1[0][1][j]) + s2[0][1][j], u1 = st[1] * (acc[ai][1][m][1][j] - st[0] * s1[1][1][j]) + s2[1][1][j];
;                     v0[j] = siluf_(g0) * u0; v1[j] = siluf_(g1) * u1;
.LBB0_1040:
	v_lshl_or_b32 v144, s1, 8, v182
	v_lshl_add_u32 v162, s0, 8, v177
	v_ashrrev_i32_e32 v145, 31, v144
	v_lshlrev_b64 v[64:65], 2, v[144:145]
	v_ashrrev_i32_e32 v163, 31, v162
	v_lshl_add_u64 v[68:69], s[18:19], 0, v[64:65]
	v_lshl_add_u64 v[70:71], s[12:13], 0, v[64:65]
	v_lshl_add_u64 v[64:65], v[162:163], 3, s[8:9]
	global_load_dwordx2 v[164:165], v[64:65], off
	global_load_dwordx2 v[238:239], v[64:65], off offset:128
	global_load_dwordx2 v[240:241], v[64:65], off offset:256
	global_load_dwordx2 v[242:243], v[64:65], off offset:384
	global_load_dwordx2 v[244:245], v[64:65], off offset:1024
	global_load_dwordx2 v[246:247], v[64:65], off offset:1152
	global_load_dwordx2 v[248:249], v[64:65], off offset:1280
	global_load_dwordx2 v[250:251], v[64:65], off offset:1408
	s_nop 0
	global_load_dwordx4 v[64:67], v[70:71], off offset:16
	global_load_dwordx4 v[76:79], v[70:71], off
	global_load_dwordx4 v[72:75], v[68:69], off
	s_nop 0
	global_load_dwordx4 v[68:71], v[68:69], off offset:16
	v_or_b32_e32 v144, 0x80, v144
	v_ashrrev_i32_e32 v145, 31, v144
	v_lshlrev_b64 v[144:145], 2, v[144:145]
	v_lshl_add_u64 v[146:147], s[18:19], 0, v[144:145]
	v_lshl_add_u64 v[144:145], s[12:13], 0, v[144:145]
	global_load_dwordx4 v[188:191], v[144:145], off
	global_load_dwordx4 v[192:195], v[146:147], off
	global_load_dwordx4 v[196:199], v[144:145], off offset:16
	s_nop 0
	global_load_dwordx4 v[144:147], v[146:147], off offset:16
	v_lshl_or_b32 v166, s1, 7, v182
	v_mov_b64_e32 v[160:161], s[40:41]
	v_ashrrev_i32_e32 v167, 31, v166
	v_mov_b32_e32 v202, v128
	v_mov_b32_e32 v203, v136
	v_mov_b32_e32 v136, v129
	v_mad_i64_i32 v[128:129], s[0:1], v162, s53, v[160:161]
	v_lshlrev_b64 v[170:171], 1, v[166:167]
	v_lshl_add_u64 v[208:209], v[128:129], 0, v[170:171]
	v_mov_b32_e32 v204, v134
	v_mov_b32_e32 v206, v130
	v_mov_b32_e32 v207, v138
	v_mov_b32_e32 v200, v132
	v_mov_b32_e32 v201, v140
	v_mov_b32_e32 v140, v133
	v_mov_b32_e32 v205, v142
	v_mov_b32_e32 v142, v135
	s_waitcnt vmcnt(0)
	v_pk_mul_f32 v[210:211], v[164:165], s[20:21] op_sel_hi:[1,0]
	s_nop 0
	v_fma_f32 v128, -v210, v210, v211
	v_mov_b32_e32 v169, v66
	v_max_f32_e32 v66, 0, v128
	v_add_f32_e32 v66, 0x3727c5ac, v66
	v_mov_b32_e32 v129, v74
	v_mul_f32_e32 v74, 0x4f800000, v66
	v_cmp_gt_f32_e32 vcc, s54, v66
	v_mov_b32_e32 v167, v78
	v_mov_b32_e32 v173, v76
	v_cndmask_b32_e32 v66, v66, v74, vcc
	v_sqrt_f32_e32 v74, v66
	v_mov_b32_e32 v172, v188
	v_mov_b32_e32 v133, v72
	v_mov_b32_e32 v165, v68
	v_add_u32_e32 v78, -1, v74
	v_add_u32_e32 v130, 1, v74
	v_fma_f32 v134, -v78, v74, v66
	v_fma_f32 v138, -v130, v74, v66
	v_cmp_ge_f32_e64 s[0:1], 0, v134
	v_mov_b32_e32 v132, v192
	v_mov_b32_e32 v164, v144
	v_cndmask_b32_e64 v74, v74, v78, s[0:1]
	v_cmp_lt_f32_e64 s[0:1], 0, v138
	v_mov_b32_e32 v68, v145
	v_pk_fma_f32 v[144:145], v[172:173], v[210:211], v[200:201] op_sel_hi:[1,0,1] neg_lo:[1,0,0] neg_hi:[1,0,0]
	v_cndmask_b32_e64 v74, v74, v130, s[0:1]
	v_mul_f32_e32 v78, 0x37800000, v74
	v_cndmask_b32_e32 v74, v74, v78, vcc
	v_cmp_class_f32_e32 vcc, v66, v186
	v_mov_b32_e32 v76, v189
	v_mov_b32_e32 v72, v193
	v_cndmask_b32_e32 v66, v74, v66, vcc
	v_div_scale_f32 v74, s[0:1], v66, v66, 1.0
	v_rcp_f32_e32 v78, v74
	v_div_scale_f32 v130, vcc, 1.0, v66, 1.0
	v_pk_fma_f32 v[140:141], v[76:77], v[210:211], v[140:141] op_sel_hi:[1,0,1] neg_lo:[1,0,0] neg_hi:[1,0,0]
	v_fma_f32 v134, -v74, v78, 1.0
	v_fmac_f32_e32 v78, v134, v78
	v_mul_f32_e32 v134, v130, v78
	v_fma_f32 v138, -v74, v134, v130
	v_fmac_f32_e32 v134, v138, v78
	v_fma_f32 v74, -v74, v134, v130
	v_div_fmas_f32 v74, v74, v78, v134
	v_div_fixup_f32 v130, v74, v66, 1.0
	v_pk_fma_f32 v[144:145], v[144:145], v[130:131], v[132:133] op_sel_hi:[1,0,1]
	v_pk_fma_f32 v[140:141], v[140:141], v[130:131], v[72:73] op_sel_hi:[1,0,1]
	v_mul_f32_e32 v66, 0xbfb8aa3b, v145
	v_exp_f32_e32 v66, v66
	v_mul_f32_e32 v78, 0xbfb8aa3b, v141
	v_exp_f32_e32 v78, v78
	v_mov_b32_e32 v166, v190
	v_add_f32_e32 v66, 1.0, v66
	v_rcp_f32_e32 v66, v66
	v_mov_b32_e32 v175, v64
	v_mov_b32_e32 v174, v196
	v_mov_b32_e32 v64, v197
	v_mov_b32_e32 v128, v194
	v_pk_fma_f32 v[192:193], v[166:167], v[210:211], v[204:205] op_sel_hi:[1,0,1] neg_lo:[1,0,0] neg_hi:[1,0,0]
	v_pk_fma_f32 v[188:189], v[174:175], v[210:211], v[202:203] op_sel_hi:[1,0,1] neg_lo:[1,0,0] neg_hi:[1,0,0]
	v_pk_fma_f32 v[136:137], v[64:65], v[210:211], v[136:137] op_sel_hi:[1,0,1] neg_lo:[1,0,0] neg_hi:[1,0,0]
	v_pk_fma_f32 v[192:193], v[192:193], v[130:131], v[128:129] op_sel_hi:[1,0,1]
	v_add_f32_e32 v78, 1.0, v78
	v_pk_fma_f32 v[188:189], v[188:189], v[130:131], v[164:165] op_sel_hi:[1,0,1]
	v_pk_fma_f32 v[200:201], v[136:137], v[130:131], v[68:69] op_sel_hi:[1,0,1]
	v_mul_f32_e32 v136, 0xbfb8aa3b, v193
	v_rcp_f32_e32 v78, v78
	v_mul_f32_e32 v66, v145, v66
	v_mul_f32_e32 v74, 0xbfb8aa3b, v189
	v_mul_f32_e32 v144, v144, v66
	v_exp_f32_e32 v66, v136
	v_mul_f32_e32 v134, 0xbfb8aa3b, v201
	v_exp_f32_e32 v74, v74
	v_mov_b32_e32 v168, v198
	v_exp_f32_e32 v134, v134
	v_pk_fma_f32 v[196:197], v[168:169], v[210:211], v[206:207] op_sel_hi:[1,0,1] neg_lo:[1,0,0] neg_hi:[1,0,0]
	v_mul_f32_e32 v78, v141, v78
	v_mov_b32_e32 v136, v146
	v_mov_b32_e32 v137, v70
	v_mul_f32_e32 v163, v140, v78
	v_pk_fma_f32 v[140:141], v[196:197], v[130:131], v[136:137] op_sel_hi:[1,0,1]
	v_add_f32_e32 v66, 1.0, v66
	v_add_f32_e32 v74, 1.0, v74
	v_rcp_f32_e32 v66, v66
	v_mul_f32_e32 v70, 0xbfb8aa3b, v141
	v_add_f32_e32 v134, 1.0, v134
	v_rcp_f32_e32 v74, v74
	v_exp_f32_e32 v70, v70
	v_rcp_f32_e32 v134, v134
	v_mul_f32_e32 v66, v193, v66
	v_mul_f32_e32 v74, v189, v74
	v_mul_f32_e32 v187, v192, v66
	v_add_f32_e32 v66, 1.0, v70
	v_mul_f32_e32 v134, v201, v134
; __device__ __forceinline__ unsigned cvt_pk_bf16(float lo, float hi) { unsigned r; asm volatile("v_cvt_pk_bf16_f32 %0, %1, %2" : "=v"(r) : "v"(lo), "v"(hi)); return r; }
; __device__ __forceinline__ float sigmoidf_(float x) { return __builtin_amdgcn_rcpf(1.0f + __expf(-x)); }
; __device__ __forceinline__ float siluf_(float x) { return x * sigmoidf_(x); }
; __device__ __forceinline__ float gelu_tanh(float x) { return x * sigmoidf_(1.5957691216057308f * (x + 0.044715f * x * x * x)); }
; __device__ __forceinline__ f32x2 ln_stats(f32x2 sm) { const float mu = sm[0] * (1.f / D); const float var = fmaxf(sm[1] * (1.f / D) - mu * mu, 0.f); return (f32x2){mu, 1.0f / sqrtf(var + LN_EPS)}; }
;     __device__ __forceinline__ void operator()(const f32x4 (&acc)[2][2][4][2], const Unit& u, int wr, int wc, int fr, int fq) const {
;     ...
;             for (int m = 0; m < 4; ++m) {
;                 const int r = row0 + ai * HALF + m * 16;
;                 bf16_t* rowp = H + (size_t)r * ldh + col0;
;                 f32x2 st = (f32x2){0.f, 1.f};
;                 if (rsum) st = ln_stats(*(const f32x2*)(rsum + 2 * (size_t)r));
;                 f32x4 v0, v1;
; #pragma unroll
;                 for (int j = 0; j < 4; ++j) {
;                     const float g0 = st[1] * (acc[ai][0][m][0][j] - st[0] * s1[0][0][j]) + s2[0][0][j], u0 = st[1] * (acc[ai][1][m][0][j] - st[0] * s1[1][0][j]) + s2[1][0][j];
;                     const float g1 = st[1] * (acc[ai][0][m][1][j] - st[0] * s1[0][1][j]) + s2[0][1][j], u1 = st[1] * (acc[ai][1][m][1][j] - st[0] * s1[1][1][j]) + s2[1][1][j];
;                     v0[j] = siluf_(g0) * u0; v1[j] = siluf_(g1) * u1;
;                 }
;                 u32x4 w; w.x = cvt_pk_bf16(v0[0], v0[1]); w.y = cvt_pk_bf16(v0[2], v0[3]); w.z = cvt_pk_bf16(v1[0], v1[1]); w.w = cvt_pk_bf16(v1[2], v1[3]);
;                 *(u32x4*)rowp = w;
;             }
	v_mul_f32_e32 v145, v188, v74
	v_rcp_f32_e32 v188, v66
	v_mov_b32_e32 v78, v191
	v_mov_b32_e32 v66, v199
	v_mov_b32_e32 v138, v131
	v_mul_f32_e32 v146, v200, v134
	v_pk_fma_f32 v[134:135], v[78:79], v[210:211], v[142:143] op_sel_hi:[1,0,1] neg_lo:[1,0,0] neg_hi:[1,0,0]
	v_mov_b32_e32 v74, v195
	v_pk_fma_f32 v[138:139], v[66:67], v[210:211], v[138:139] op_sel_hi:[1,0,1] neg_lo:[1,0,0] neg_hi:[1,0,0]
	v_mov_b32_e32 v70, v147
	v_pk_fma_f32 v[134:135], v[134:135], v[130:131], v[74:75] op_sel_hi:[1,0,1]
	v_pk_fma_f32 v[130:131], v[138:139], v[130:131], v[70:71] op_sel_hi:[1,0,1]
	v_mul_f32_e32 v138, 0xbfb8aa3b, v135
	v_mul_f32_e32 v139, 0xbfb8aa3b, v131
	v_exp_f32_e32 v139, v139
	v_exp_f32_e32 v138, v138
	v_mul_f32_e32 v141, v141, v188
	v_mul_f32_e32 v141, v140, v141
	v_add_f32_e32 v139, 1.0, v139
	v_add_f32_e32 v138, 1.0, v138
	v_rcp_f32_e32 v139, v139
	v_rcp_f32_e32 v138, v138
	v_mul_f32_e32 v131, v131, v139
	v_mul_f32_e32 v135, v135, v138
	v_mul_f32_e32 v130, v130, v131
	v_mul_f32_e32 v134, v134, v135
	v_cvt_pk_bf16_f32 v138, v144, v163
	v_cvt_pk_bf16_f32 v139, v187, v134
	v_cvt_pk_bf16_f32 v140, v145, v146
	v_cvt_pk_bf16_f32 v141, v141, v130
	v_or_b32_e32 v130, 16, v162
	v_ashrrev_i32_e32 v131, 31, v130
	global_store_dwordx4 v[208:209], v[138:141], off sc1
	v_lshl_add_u64 v[134:135], v[130:131], 3, s[8:9]
	v_mov_b32_e32 v134, v238
	v_mov_b32_e32 v135, v239
	v_mov_b32_e32 v138, v116
	v_mov_b32_e32 v116, v114
	v_mov_b32_e32 v139, v124
	v_mov_b32_e32 v124, v117
	v_mov_b32_e32 v140, v112
	v_mov_b32_e32 v112, v118
	v_mov_b32_e32 v141, v120
	v_mov_b32_e32 v120, v113
	v_mov_b32_e32 v113, v126
	v_mad_i64_i32 v[130:131], s[0:1], v130, s53, v[160:161]
	v_lshl_add_u64 v[130:131], v[130:131], 0, v[170:171]
	s_nop 0
	v_pk_mul_f32 v[134:135], v[134:135], s[20:21] op_sel_hi:[1,0]
	s_nop 0
	v_fma_f32 v114, -v134, v134, v135
	v_max_f32_e32 v114, 0, v114
	v_add_f32_e32 v114, 0x3727c5ac, v114
	v_mul_f32_e32 v117, 0x4f800000, v114
	v_cmp_gt_f32_e32 vcc, s54, v114
	v_pk_fma_f32 v[138:139], v[172:173], v[134:135], v[138:139] op_sel_hi:[1,0,1] neg_lo:[1,0,0] neg_hi:[1,0,0]
	v_pk_fma_f32 v[140:141], v[174:175], v[134:135], v[140:141] op_sel_hi:[1,0,1] neg_lo:[1,0,0] neg_hi:[1,0,0]
	v_cndmask_b32_e32 v114, v114, v117, vcc
	v_sqrt_f32_e32 v117, v114
	v_pk_fma_f32 v[120:121], v[64:65], v[134:135], v[120:121] op_sel_hi:[1,0,1] neg_lo:[1,0,0] neg_hi:[1,0,0]
	v_pk_fma_f32 v[112:113], v[166:167], v[134:135], v[112:113] op_sel_hi:[1,0,1] neg_lo:[1,0,0] neg_hi:[1,0,0]
	v_pk_fma_f32 v[124:125], v[76:77], v[134:135], v[124:125] op_sel_hi:[1,0,1] neg_lo:[1,0,0] neg_hi:[1,0,0]
	v_add_u32_e32 v118, -1, v117
	v_add_u32_e32 v126, 1, v117
	v_fma_f32 v142, -v118, v117, v114
	v_fma_f32 v143, -v126, v117, v114
	v_cmp_ge_f32_e64 s[0:1], 0, v142
	s_nop 1
	v_cndmask_b32_e64 v117, v117, v118, s[0:1]
	v_cmp_lt_f32_e64 s[0:1], 0, v143
	s_nop 1
	v_cndmask_b32_e64 v117, v117, v126, s[0:1]
	v_mul_f32_e32 v118, 0x37800000, v117
	v_cndmask_b32_e32 v117, v117, v118, vcc
	v_cmp_class_f32_e32 vcc, v114, v186
	s_nop 1
	v_cndmask_b32_e32 v114, v117, v114, vcc
	v_div_scale_f32 v117, s[0:1], v114, v114, 1.0
	v_rcp_f32_e32 v118, v117
	v_div_scale_f32 v126, vcc, 1.0, v114, 1.0
	v_fma_f32 v142, -v117, v118, 1.0
	v_fmac_f32_e32 v118, v142, v118
	v_mul_f32_e32 v142, v126, v118
	v_fma_f32 v143, -v117, v142, v126
	v_fmac_f32_e32 v142, v143, v118
	v_fma_f32 v117, -v117, v142, v126
	v_div_fmas_f32 v117, v117, v118, v142
	v_div_fixup_f32 v114, v117, v114, 1.0
	v_pk_fma_f32 v[138:139], v[138:139], v[114:115], v[132:133] op_sel_hi:[1,0,1]
	v_pk_fma_f32 v[140:141], v[140:141], v[114:115], v[164:165] op_sel_hi:[1,0,1]
	v_mul_f32_e32 v117, 0xbfb8aa3b, v139
	v_mul_f32_e32 v118, 0xbfb8aa3b, v141
	v_exp_f32_e32 v117, v117
	v_exp_f32_e32 v118, v118
	v_pk_fma_f32 v[120:121], v[120:121], v[114:115], v[68:69] op_sel_hi:[1,0,1]
	v_pk_fma_f32 v[112:113], v[112:113], v[114:115], v[128:129] op_sel_hi:[1,0,1]
	v_add_f32_e32 v117, 1.0, v117
	v_add_f32_e32 v118, 1.0, v118
	v_rcp_f32_e32 v117, v117
	v_rcp_f32_e32 v118, v118
	v_pk_fma_f32 v[124:125], v[124:125], v[114:115], v[72:73] op_sel_hi:[1,0,1]
	v_mul_f32_e32 v142, 0xbfb8aa3b, v121
	v_mul_f32_e32 v117, v139, v117
	v_mul_f32_e32 v118, v141, v118
	v_mul_f32_e32 v138, v138, v117
	v_mul_f32_e32 v117, 0xbfb8aa3b, v113
	v_mul_f32_e32 v126, 0xbfb8aa3b, v125
	v_exp_f32_e32 v142, v142
	v_mul_f32_e32 v139, v140, v118
	v_exp_f32_e32 v118, v117
	v_exp_f32_e32 v126, v126
	v_mov_b32_e32 v117, v122
	v_pk_fma_f32 v[116:117], v[168:169], v[134:135], v[116:117] op_sel_hi:[1,0,1] neg_lo:[1,0,0] neg_hi:[1,0,0]
	v_add_f32_e32 v142, 1.0, v142
	v_pk_fma_f32 v[116:117], v[116:117], v[114:115], v[136:137] op_sel_hi:[1,0,1]
	v_add_f32_e32 v118, 1.0, v118
	v_add_f32_e32 v126, 1.0, v126
	v_rcp_f32_e32 v142, v142
	v_rcp_f32_e32 v118, v118
	v_mul_f32_e32 v122, 0xbfb8aa3b, v117
	v_rcp_f32_e32 v126, v126
	v_exp_f32_e32 v122, v122
	v_mul_f32_e32 v121, v121, v142
	v_mul_f32_e32 v113, v113, v118
	v_mul_f32_e32 v125, v125, v126
	v_mul_f32_e32 v120, v120, v121
	v_mul_f32_e32 v121, v112, v113
	v_add_f32_e32 v112, 1.0, v122
	v_mov_b32_e32 v126, v119
	v_mul_f32_e32 v124, v124, v125
	v_rcp_f32_e32 v125, v112
	v_pk_fma_f32 v[112:113], v[78:79], v[134:135], v[126:127] op_sel_hi:[1,0,1] neg_lo:[1,0,0] neg_hi:[1,0,0]
	v_mov_b32_e32 v122, v115
	v_pk_fma_f32 v[112:113], v[112:113], v[114:115], v[74:75] op_sel_hi:[1,0,1]
	v_pk_fma_f32 v[118:119], v[66:67], v[134:135], v[122:123] op_sel_hi:[1,0,1] neg_lo:[1,0,0] neg_hi:[1,0,0]
	v_mul_f32_e32 v117, v117, v125
	v_pk_fma_f32 v[114:115], v[118:119], v[114:115], v[70:71] op_sel_hi:[1,0,1]
	v_mul_f32_e32 v118, 0xbfb8aa3b, v113
	v_exp_f32_e32 v118, v118
	v_mul_f32_e32 v119, 0xbfb8aa3b, v115
; __device__ __forceinline__ unsigned cvt_pk_bf16(float lo, float hi) { unsigned r; asm volatile("v_cvt_pk_bf16_f32 %0, %1, %2" : "=v"(r) : "v"(lo), "v"(hi)); return r; }
; __device__ __forceinline__ float sigmoidf_(float x) { return __builtin_amdgcn_rcpf(1.0f + __expf(-x)); }
; __device__ __forceinline__ float siluf_(float x) { return x * sigmoidf_(x); }
; __device__ __forceinline__ float gelu_tanh(float x) { return x * sigmoidf_(1.5957691216057308f * (x + 0.044715f * x * x * x)); }
; __device__ __forceinline__ f32x2 ln_stats(f32x2 sm) { const float mu = sm[0] * (1.f / D); const float var = fmaxf(sm[1] * (1.f / D) - mu * mu, 0.f); return (f32x2){mu, 1.0f / sqrtf(var + LN_EPS)}; }
;     __device__ __forceinline__ void operator()(const f32x4 (&acc)[2][2][4][2], const Unit& u, int wr, int wc, int fr, int fq) const {
;     ...
;             for (int m = 0; m < 4; ++m) {
;                 const int r = row0 + ai * HALF + m * 16;
;                 bf16_t* rowp = H + (size_t)r * ldh + col0;
;                 f32x2 st = (f32x2){0.f, 1.f};
;                 if (rsum) st = ln_stats(*(const f32x2*)(rsum + 2 * (size_t)r));
;                 f32x4 v0, v1;
; #pragma unroll
;                 for (int j = 0; j < 4; ++j) {
;                     const float g0 = st[1] * (acc[ai][0][m][0][j] - st[0] * s1[0][0][j]) + s2[0][0][j], u0 = st[1] * (acc[ai][1][m][0][j] - st[0] * s1[1][0][j]) + s2[1][0][j];
;                     const float g1 = st[1] * (acc[ai][0][m][1][j] - st[0] * s1[0][1][j]) + s2[0][1][j], u1 = st[1] * (acc[ai][1][m][1][j] - st[0] * s1[1][1][j]) + s2[1][1][j];
;                     v0[j] = siluf_(g0) * u0; v1[j] = siluf_(g1) * u1;
;                 }
;                 u32x4 w; w.x = cvt_pk_bf16(v0[0], v0[1]); w.y = cvt_pk_bf16(v0[2], v0[3]); w.z = cvt_pk_bf16(v1[0], v1[1]); w.w = cvt_pk_bf16(v1[2], v1[3]);
;                 *(u32x4*)rowp = w;
;             }
	v_exp_f32_e32 v119, v119
	v_mul_f32_e32 v116, v116, v117
	v_add_f32_e32 v118, 1.0, v118
	v_rcp_f32_e32 v118, v118
	v_add_f32_e32 v119, 1.0, v119
	v_rcp_f32_e32 v119, v119
	v_mov_b32_e32 v117, v108
	v_mul_f32_e32 v113, v113, v118
	v_mul_f32_e32 v113, v112, v113
	v_mul_f32_e32 v112, v115, v119
	v_mul_f32_e32 v115, v114, v112
	v_cvt_pk_bf16_f32 v112, v138, v124
	v_cvt_pk_bf16_f32 v113, v121, v113
	v_cvt_pk_bf16_f32 v114, v139, v120
	v_cvt_pk_bf16_f32 v115, v116, v115
	global_store_dwordx4 v[130:131], v[112:115], off sc1
	v_mov_b32_e32 v116, v100
	v_mov_b32_e32 v100, v98
	v_or_b32_e32 v112, 32, v162
	v_ashrrev_i32_e32 v113, 31, v112
	v_lshl_add_u64 v[114:115], v[112:113], 3, s[8:9]
	v_mov_b32_e32 v114, v240
	v_mov_b32_e32 v115, v241
	v_mov_b32_e32 v118, v96
	v_mov_b32_e32 v96, v102
	v_mov_b32_e32 v108, v101
	v_mov_b32_e32 v101, v106
	v_mov_b32_e32 v119, v104
	v_mov_b32_e32 v104, v97
	v_mov_b32_e32 v97, v110
	v_mad_i64_i32 v[112:113], s[0:1], v112, s53, v[160:161]
	v_lshl_add_u64 v[112:113], v[112:113], 0, v[170:171]
	s_nop 0
	v_pk_mul_f32 v[114:115], v[114:115], s[20:21] op_sel_hi:[1,0]
	s_nop 0
	v_fma_f32 v98, -v114, v114, v115
	v_max_f32_e32 v98, 0, v98
	v_add_f32_e32 v98, 0x3727c5ac, v98
	v_mul_f32_e32 v102, 0x4f800000, v98
	v_cmp_gt_f32_e32 vcc, s54, v98
	v_pk_fma_f32 v[116:117], v[172:173], v[114:115], v[116:117] op_sel_hi:[1,0,1] neg_lo:[1,0,0] neg_hi:[1,0,0]
	v_pk_fma_f32 v[118:119], v[174:175], v[114:115], v[118:119] op_sel_hi:[1,0,1] neg_lo:[1,0,0] neg_hi:[1,0,0]
	v_cndmask_b32_e32 v98, v98, v102, vcc
	v_sqrt_f32_e32 v102, v98
	v_pk_fma_f32 v[104:105], v[64:65], v[114:115], v[104:105] op_sel_hi:[1,0,1] neg_lo:[1,0,0] neg_hi:[1,0,0]
	v_pk_fma_f32 v[96:97], v[166:167], v[114:115], v[96:97] op_sel_hi:[1,0,1] neg_lo:[1,0,0] neg_hi:[1,0,0]
	v_pk_fma_f32 v[108:109], v[76:77], v[114:115], v[108:109] op_sel_hi:[1,0,1] neg_lo:[1,0,0] neg_hi:[1,0,0]
	v_add_u32_e32 v106, -1, v102
	v_add_u32_e32 v110, 1, v102
	v_fma_f32 v120, -v106, v102, v98
	v_fma_f32 v121, -v110, v102, v98
	v_cmp_ge_f32_e64 s[0:1], 0, v120
	v_pk_fma_f32 v[100:101], v[168:169], v[114:115], v[100:101] op_sel_hi:[1,0,1] neg_lo:[1,0,0] neg_hi:[1,0,0]
	s_nop 0
	v_cndmask_b32_e64 v102, v102, v106, s[0:1]
	v_cmp_lt_f32_e64 s[0:1], 0, v121
	s_nop 1
	v_cndmask_b32_e64 v102, v102, v110, s[0:1]
	v_mul_f32_e32 v106, 0x37800000, v102
	v_cndmask_b32_e32 v102, v102, v106, vcc
	v_cmp_class_f32_e32 vcc, v98, v186
	s_nop 1
	v_cndmask_b32_e32 v98, v102, v98, vcc
	v_div_scale_f32 v102, s[0:1], v98, v98, 1.0
	v_rcp_f32_e32 v106, v102
	v_div_scale_f32 v110, vcc, 1.0, v98, 1.0
	v_fma_f32 v120, -v102, v106, 1.0
	v_fmac_f32_e32 v106, v120, v106
	v_mul_f32_e32 v120, v110, v106
	v_fma_f32 v121, -v102, v120, v110
	v_fmac_f32_e32 v120, v121, v106
	v_fma_f32 v102, -v102, v120, v110
	v_div_fmas_f32 v102, v102, v106, v120
	v_div_fixup_f32 v98, v102, v98, 1.0
	v_pk_fma_f32 v[116:117], v[116:117], v[98:99], v[132:133] op_sel_hi:[1,0,1]
	v_pk_fma_f32 v[118:119], v[118:119], v[98:99], v[164:165] op_sel_hi:[1,0,1]
	v_mul_f32_e32 v102, 0xbfb8aa3b, v117
	v_mul_f32_e32 v106, 0xbfb8aa3b, v119
	v_exp_f32_e32 v102, v102
	v_exp_f32_e32 v106, v106
	v_pk_fma_f32 v[104:105], v[104:105], v[98:99], v[68:69] op_sel_hi:[1,0,1]
	v_pk_fma_f32 v[96:97], v[96:97], v[98:99], v[128:129] op_sel_hi:[1,0,1]
	v_add_f32_e32 v102, 1.0, v102
	v_pk_fma_f32 v[108:109], v[108:109], v[98:99], v[72:73] op_sel_hi:[1,0,1]
	v_mul_f32_e32 v120, 0xbfb8aa3b, v105
	v_mul_f32_e32 v121, 0xbfb8aa3b, v97
	v_add_f32_e32 v106, 1.0, v106
	v_rcp_f32_e32 v102, v102
	v_mul_f32_e32 v110, 0xbfb8aa3b, v109
	v_exp_f32_e32 v120, v120
	v_exp_f32_e32 v121, v121
	v_rcp_f32_e32 v106, v106
	v_exp_f32_e32 v110, v110
	v_mul_f32_e32 v102, v117, v102
	v_add_f32_e32 v120, 1.0, v120
	v_mul_f32_e32 v106, v119, v106
	v_mul_f32_e32 v116, v116, v102
	v_pk_fma_f32 v[100:101], v[100:101], v[98:99], v[136:137] op_sel_hi:[1,0,1]
	v_add_f32_e32 v102, 1.0, v121
	v_add_f32_e32 v110, 1.0, v110
	v_rcp_f32_e32 v120, v120
	v_mul_f32_e32 v117, v118, v106
	v_rcp_f32_e32 v102, v102
	v_mul_f32_e32 v106, 0xbfb8aa3b, v101
	v_rcp_f32_e32 v110, v110
	v_exp_f32_e32 v106, v106
	v_mul_f32_e32 v105, v105, v120
	v_mul_f32_e32 v97, v97, v102
	v_mul_f32_e32 v109, v109, v110
	v_mul_f32_e32 v104, v104, v105
	v_mul_f32_e32 v105, v96, v97
	v_add_f32_e32 v96, 1.0, v106
	v_mov_b32_e32 v110, v103
	v_mul_f32_e32 v108, v108, v109
	v_rcp_f32_e32 v109, v96
	v_pk_fma_f32 v[96:97], v[78:79], v[114:115], v[110:111] op_sel_hi:[1,0,1] neg_lo:[1,0,0] neg_hi:[1,0,0]
	v_mov_b32_e32 v106, v99
	v_pk_fma_f32 v[96:97], v[96:97], v[98:99], v[74:75] op_sel_hi:[1,0,1]
	v_pk_fma_f32 v[102:103], v[66:67], v[114:115], v[106:107] op_sel_hi:[1,0,1] neg_lo:[1,0,0] neg_hi:[1,0,0]
	v_mul_f32_e32 v101, v101, v109
	v_pk_fma_f32 v[98:99], v[102:103], v[98:99], v[70:71] op_sel_hi:[1,0,1]
	v_mul_f32_e32 v102, 0xbfb8aa3b, v97
	v_exp_f32_e32 v102, v102
	v_mul_f32_e32 v103, 0xbfb8aa3b, v99
	v_exp_f32_e32 v103, v103
	v_mul_f32_e32 v100, v100, v101
	v_add_f32_e32 v102, 1.0, v102
	v_rcp_f32_e32 v102, v102
	v_add_f32_e32 v103, 1.0, v103
	v_rcp_f32_e32 v103, v103
	v_mov_b32_e32 v101, v92
	v_mul_f32_e32 v97, v97, v102
	v_mul_f32_e32 v97, v96, v97
	v_mul_f32_e32 v96, v99, v103
	v_mul_f32_e32 v99, v98, v96
	v_cvt_pk_bf16_f32 v96, v116, v108
	v_cvt_pk_bf16_f32 v97, v105, v97
	v_cvt_pk_bf16_f32 v98, v117, v104
	v_cvt_pk_bf16_f32 v99, v100, v99
	global_store_dwordx4 v[112:113], v[96:99], off sc1
	v_mov_b32_e32 v100, v84
	v_mov_b32_e32 v84, v82
	v_or_b32_e32 v96, 48, v162
	v_ashrrev_i32_e32 v97, 31, v96
	v_lshl_add_u64 v[98:99], v[96:97], 3, s[8:9]
	v_mov_b32_e32 v98, v242
	v_mov_b32_e32 v99, v243
	v_mov_b32_e32 v102, v80
	v_mov_b32_e32 v80, v86
; __device__ __forceinline__ unsigned cvt_pk_bf16(float lo, float hi) { unsigned r; asm volatile("v_cvt_pk_bf16_f32 %0, %1, %2" : "=v"(r) : "v"(lo), "v"(hi)); return r; }
; __device__ __forceinline__ float sigmoidf_(float x) { return __builtin_amdgcn_rcpf(1.0f + __expf(-x)); }
; __device__ __forceinline__ float siluf_(float x) { return x * sigmoidf_(x); }
; __device__ __forceinline__ float gelu_tanh(float x) { return x * sigmoidf_(1.5957691216057308f * (x + 0.044715f * x * x * x)); }
; __device__ __forceinline__ f32x2 ln_stats(f32x2 sm) { const float mu = sm[0] * (1.f / D); const float var = fmaxf(sm[1] * (1.f / D) - mu * mu, 0.f); return (f32x2){mu, 1.0f / sqrtf(var + LN_EPS)}; }
;     __device__ __forceinline__ void operator()(const f32x4 (&acc)[2][2][4][2], const Unit& u, int wr, int wc, int fr, int fq) const {
;     ...
;             for (int m = 0; m < 4; ++m) {
;                 const int r = row0 + ai * HALF + m * 16;
;                 bf16_t* rowp = H + (size_t)r * ldh + col0;
;                 f32x2 st = (f32x2){0.f, 1.f};
;                 if (rsum) st = ln_stats(*(const f32x2*)(rsum + 2 * (size_t)r));
;                 f32x4 v0, v1;
; #pragma unroll
;                 for (int j = 0; j < 4; ++j) {
;                     const float g0 = st[1] * (acc[ai][0][m][0][j] - st[0] * s1[0][0][j]) + s2[0][0][j], u0 = st[1] * (acc[ai][1][m][0][j] - st[0] * s1[1][0][j]) + s2[1][0][j];
;                     const float g1 = st[1] * (acc[ai][0][m][1][j] - st[0] * s1[0][1][j]) + s2[0][1][j], u1 = st[1] * (acc[ai][1][m][1][j] - st[0] * s1[1][1][j]) + s2[1][1][j];
;                     v0[j] = siluf_(g0) * u0; v1[j] = siluf_(g1) * u1;
;                 }
;                 u32x4 w; w.x = cvt_pk_bf16(v0[0], v0[1]); w.y = cvt_pk_bf16(v0[2], v0[3]); w.z = cvt_pk_bf16(v1[0], v1[1]); w.w = cvt_pk_bf16(v1[2], v1[3]);
;                 *(u32x4*)rowp = w;
;             }
	v_mov_b32_e32 v92, v85
	v_mov_b32_e32 v85, v90
	v_mov_b32_e32 v103, v88
	v_mov_b32_e32 v88, v81
	v_mov_b32_e32 v81, v94
	v_mad_i64_i32 v[96:97], s[0:1], v96, s53, v[160:161]
	v_lshl_add_u64 v[96:97], v[96:97], 0, v[170:171]
	s_nop 0
	v_pk_mul_f32 v[98:99], v[98:99], s[20:21] op_sel_hi:[1,0]
	s_nop 0
	v_fma_f32 v82, -v98, v98, v99
	v_max_f32_e32 v82, 0, v82
	v_add_f32_e32 v82, 0x3727c5ac, v82
	v_mul_f32_e32 v86, 0x4f800000, v82
	v_cmp_gt_f32_e32 vcc, s54, v82
	v_pk_fma_f32 v[100:101], v[172:173], v[98:99], v[100:101] op_sel_hi:[1,0,1] neg_lo:[1,0,0] neg_hi:[1,0,0]
	v_pk_fma_f32 v[102:103], v[174:175], v[98:99], v[102:103] op_sel_hi:[1,0,1] neg_lo:[1,0,0] neg_hi:[1,0,0]
	v_cndmask_b32_e32 v82, v82, v86, vcc
	v_sqrt_f32_e32 v86, v82
	v_pk_fma_f32 v[88:89], v[64:65], v[98:99], v[88:89] op_sel_hi:[1,0,1] neg_lo:[1,0,0] neg_hi:[1,0,0]
	v_pk_fma_f32 v[80:81], v[166:167], v[98:99], v[80:81] op_sel_hi:[1,0,1] neg_lo:[1,0,0] neg_hi:[1,0,0]
	v_pk_fma_f32 v[92:93], v[76:77], v[98:99], v[92:93] op_sel_hi:[1,0,1] neg_lo:[1,0,0] neg_hi:[1,0,0]
	v_add_u32_e32 v90, -1, v86
	v_add_u32_e32 v94, 1, v86
	v_fma_f32 v104, -v90, v86, v82
	v_fma_f32 v105, -v94, v86, v82
	v_cmp_ge_f32_e64 s[0:1], 0, v104
	v_pk_fma_f32 v[84:85], v[168:169], v[98:99], v[84:85] op_sel_hi:[1,0,1] neg_lo:[1,0,0] neg_hi:[1,0,0]
	s_nop 0
	v_cndmask_b32_e64 v86, v86, v90, s[0:1]
	v_cmp_lt_f32_e64 s[0:1], 0, v105
	s_nop 1
	v_cndmask_b32_e64 v86, v86, v94, s[0:1]
	v_mul_f32_e32 v90, 0x37800000, v86
	v_cndmask_b32_e32 v86, v86, v90, vcc
	v_cmp_class_f32_e32 vcc, v82, v186
	s_nop 1
	v_cndmask_b32_e32 v82, v86, v82, vcc
	v_div_scale_f32 v86, s[0:1], v82, v82, 1.0
	v_rcp_f32_e32 v90, v86
	v_div_scale_f32 v94, vcc, 1.0, v82, 1.0
	v_fma_f32 v104, -v86, v90, 1.0
	v_fmac_f32_e32 v90, v104, v90
	v_mul_f32_e32 v104, v94, v90
	v_fma_f32 v105, -v86, v104, v94
	v_fmac_f32_e32 v104, v105, v90
	v_fma_f32 v86, -v86, v104, v94
	v_div_fmas_f32 v86, v86, v90, v104
	v_div_fixup_f32 v82, v86, v82, 1.0
	v_pk_fma_f32 v[100:101], v[100:101], v[82:83], v[132:133] op_sel_hi:[1,0,1]
	v_pk_fma_f32 v[102:103], v[102:103], v[82:83], v[164:165] op_sel_hi:[1,0,1]
	v_mul_f32_e32 v86, 0xbfb8aa3b, v101
	v_mul_f32_e32 v90, 0xbfb8aa3b, v103
	v_exp_f32_e32 v86, v86
	v_exp_f32_e32 v90, v90
	v_pk_fma_f32 v[88:89], v[88:89], v[82:83], v[68:69] op_sel_hi:[1,0,1]
	v_pk_fma_f32 v[80:81], v[80:81], v[82:83], v[128:129] op_sel_hi:[1,0,1]
	v_pk_fma_f32 v[92:93], v[92:93], v[82:83], v[72:73] op_sel_hi:[1,0,1]
	v_mul_f32_e32 v104, 0xbfb8aa3b, v89
	v_mul_f32_e32 v105, 0xbfb8aa3b, v81
	v_add_f32_e32 v86, 1.0, v86
	v_add_f32_e32 v90, 1.0, v90
	v_mul_f32_e32 v94, 0xbfb8aa3b, v93
	v_exp_f32_e32 v104, v104
	v_exp_f32_e32 v105, v105
	v_rcp_f32_e32 v86, v86
	v_rcp_f32_e32 v90, v90
	v_exp_f32_e32 v94, v94
	v_pk_fma_f32 v[84:85], v[84:85], v[82:83], v[136:137] op_sel_hi:[1,0,1]
	v_add_f32_e32 v104, 1.0, v104
	v_add_f32_e32 v105, 1.0, v105
	v_mul_f32_e32 v86, v101, v86
	v_mul_f32_e32 v90, v103, v90
	v_add_f32_e32 v94, 1.0, v94
	v_rcp_f32_e32 v104, v104
	v_mul_f32_e32 v100, v100, v86
	v_mul_f32_e32 v101, v102, v90
	v_rcp_f32_e32 v86, v105
	v_mul_f32_e32 v90, 0xbfb8aa3b, v85
	v_rcp_f32_e32 v94, v94
	v_exp_f32_e32 v90, v90
	v_mul_f32_e32 v89, v89, v104
	v_mul_f32_e32 v81, v81, v86
	v_mul_f32_e32 v93, v93, v94
	v_mul_f32_e32 v88, v88, v89
	v_mul_f32_e32 v89, v80, v81
	v_add_f32_e32 v80, 1.0, v90
	v_mov_b32_e32 v94, v87
	v_mul_f32_e32 v92, v92, v93
	v_rcp_f32_e32 v93, v80
	v_pk_fma_f32 v[80:81], v[78:79], v[98:99], v[94:95] op_sel_hi:[1,0,1] neg_lo:[1,0,0] neg_hi:[1,0,0]
	v_mov_b32_e32 v90, v83
	v_pk_fma_f32 v[80:81], v[80:81], v[82:83], v[74:75] op_sel_hi:[1,0,1]
	v_pk_fma_f32 v[86:87], v[66:67], v[98:99], v[90:91] op_sel_hi:[1,0,1] neg_lo:[1,0,0] neg_hi:[1,0,0]
	v_mul_f32_e32 v85, v85, v93
	v_pk_fma_f32 v[82:83], v[86:87], v[82:83], v[70:71] op_sel_hi:[1,0,1]
	v_mul_f32_e32 v86, 0xbfb8aa3b, v81
	v_exp_f32_e32 v86, v86
	v_mul_f32_e32 v87, 0xbfb8aa3b, v83
	v_exp_f32_e32 v87, v87
	v_mul_f32_e32 v84, v84, v85
	v_add_f32_e32 v86, 1.0, v86
	v_rcp_f32_e32 v86, v86
	v_add_f32_e32 v87, 1.0, v87
	v_rcp_f32_e32 v87, v87
	v_mov_b32_e32 v85, v60
	v_mul_f32_e32 v81, v81, v86
	v_mul_f32_e32 v81, v80, v81
	v_mul_f32_e32 v80, v83, v87
	v_mul_f32_e32 v83, v82, v80
	v_cvt_pk_bf16_f32 v80, v100, v92
	v_cvt_pk_bf16_f32 v81, v89, v81
	v_cvt_pk_bf16_f32 v82, v101, v88
	v_cvt_pk_bf16_f32 v83, v84, v83
	global_store_dwordx4 v[96:97], v[80:83], off sc1
	v_mov_b32_e32 v84, v52
	v_mov_b32_e32 v52, v50
	v_add_u32_e32 v80, 0x80, v162
	v_ashrrev_i32_e32 v81, 31, v80
	v_lshl_add_u64 v[82:83], v[80:81], 3, s[8:9]
	v_mov_b32_e32 v82, v244
	v_mov_b32_e32 v83, v245
	v_mov_b32_e32 v86, v48
	v_mov_b32_e32 v48, v54
	v_mov_b32_e32 v60, v53
	v_mov_b32_e32 v53, v58
	v_mov_b32_e32 v87, v56
	v_mov_b32_e32 v56, v49
	v_mov_b32_e32 v49, v62
	v_mad_i64_i32 v[80:81], s[0:1], v80, s53, v[160:161]
	v_lshl_add_u64 v[80:81], v[80:81], 0, v[170:171]
	s_nop 0
	v_pk_mul_f32 v[82:83], v[82:83], s[20:21] op_sel_hi:[1,0]
	s_nop 0
	v_fma_f32 v50, -v82, v82, v83
	v_max_f32_e32 v50, 0, v50
	v_add_f32_e32 v50, 0x3727c5ac, v50
	v_mul_f32_e32 v54, 0x4f800000, v50
	v_cmp_gt_f32_e32 vcc, s54, v50
	v_pk_fma_f32 v[56:57], v[64:65], v[82:83], v[56:57] op_sel_hi:[1,0,1] neg_lo:[1,0,0] neg_hi:[1,0,0]
	v_pk_fma_f32 v[48:49], v[166:167], v[82:83], v[48:49] op_sel_hi:[1,0,1] neg_lo:[1,0,0] neg_hi:[1,0,0]
	v_cndmask_b32_e32 v50, v50, v54, vcc
	v_sqrt_f32_e32 v54, v50
	v_pk_fma_f32 v[86:87], v[174:175], v[82:83], v[86:87] op_sel_hi:[1,0,1] neg_lo:[1,0,0] neg_hi:[1,0,0]
	v_pk_fma_f32 v[60:61], v[76:77], v[82:83], v[60:61] op_sel_hi:[1,0,1] neg_lo:[1,0,0] neg_hi:[1,0,0]
	v_pk_fma_f32 v[84:85], v[172:173], v[82:83], v[84:85] op_sel_hi:[1,0,1] neg_lo:[1,0,0] neg_hi:[1,0,0]
; __device__ __forceinline__ unsigned cvt_pk_bf16(float lo, float hi) { unsigned r; asm volatile("v_cvt_pk_bf16_f32 %0, %1, %2" : "=v"(r) : "v"(lo), "v"(hi)); return r; }
; __device__ __forceinline__ float sigmoidf_(float x) { return __builtin_amdgcn_rcpf(1.0f + __expf(-x)); }
; __device__ __forceinline__ float siluf_(float x) { return x * sigmoidf_(x); }
; __device__ __forceinline__ float gelu_tanh(float x) { return x * sigmoidf_(1.5957691216057308f * (x + 0.044715f * x * x * x)); }
; __device__ __forceinline__ f32x2 ln_stats(f32x2 sm) { const float mu = sm[0] * (1.f / D); const float var = fmaxf(sm[1] * (1.f / D) - mu * mu, 0.f); return (f32x2){mu, 1.0f / sqrtf(var + LN_EPS)}; }
;     __device__ __forceinline__ void operator()(const f32x4 (&acc)[2][2][4][2], const Unit& u, int wr, int wc, int fr, int fq) const {
;     ...
;             for (int m = 0; m < 4; ++m) {
;                 const int r = row0 + ai * HALF + m * 16;
;                 bf16_t* rowp = H + (size_t)r * ldh + col0;
;                 f32x2 st = (f32x2){0.f, 1.f};
;                 if (rsum) st = ln_stats(*(const f32x2*)(rsum + 2 * (size_t)r));
;                 f32x4 v0, v1;
; #pragma unroll
;                 for (int j = 0; j < 4; ++j) {
;                     const float g0 = st[1] * (acc[ai][0][m][0][j] - st[0] * s1[0][0][j]) + s2[0][0][j], u0 = st[1] * (acc[ai][1][m][0][j] - st[0] * s1[1][0][j]) + s2[1][0][j];
;                     const float g1 = st[1] * (acc[ai][0][m][1][j] - st[0] * s1[0][1][j]) + s2[0][1][j], u1 = st[1] * (acc[ai][1][m][1][j] - st[0] * s1[1][1][j]) + s2[1][1][j];
;                     v0[j] = siluf_(g0) * u0; v1[j] = siluf_(g1) * u1;
;                 }
;                 u32x4 w; w.x = cvt_pk_bf16(v0[0], v0[1]); w.y = cvt_pk_bf16(v0[2], v0[3]); w.z = cvt_pk_bf16(v1[0], v1[1]); w.w = cvt_pk_bf16(v1[2], v1[3]);
;                 *(u32x4*)rowp = w;
;             }
	v_add_u32_e32 v58, -1, v54
	v_add_u32_e32 v62, 1, v54
	v_fma_f32 v88, -v58, v54, v50
	v_fma_f32 v89, -v62, v54, v50
	v_cmp_ge_f32_e64 s[0:1], 0, v88
	v_pk_fma_f32 v[52:53], v[168:169], v[82:83], v[52:53] op_sel_hi:[1,0,1] neg_lo:[1,0,0] neg_hi:[1,0,0]
	s_nop 0
	v_cndmask_b32_e64 v54, v54, v58, s[0:1]
	v_cmp_lt_f32_e64 s[0:1], 0, v89
	s_nop 1
	v_cndmask_b32_e64 v54, v54, v62, s[0:1]
	v_mul_f32_e32 v58, 0x37800000, v54
	v_cndmask_b32_e32 v54, v54, v58, vcc
	v_cmp_class_f32_e32 vcc, v50, v186
	s_nop 1
	v_cndmask_b32_e32 v50, v54, v50, vcc
	v_div_scale_f32 v54, s[0:1], v50, v50, 1.0
	v_rcp_f32_e32 v58, v54
	v_div_scale_f32 v62, vcc, 1.0, v50, 1.0
	v_fma_f32 v88, -v54, v58, 1.0
	v_fmac_f32_e32 v58, v88, v58
	v_mul_f32_e32 v88, v62, v58
	v_fma_f32 v89, -v54, v88, v62
	v_fmac_f32_e32 v88, v89, v58
	v_fma_f32 v54, -v54, v88, v62
	v_div_fmas_f32 v54, v54, v58, v88
	v_div_fixup_f32 v50, v54, v50, 1.0
	v_pk_fma_f32 v[56:57], v[56:57], v[50:51], v[68:69] op_sel_hi:[1,0,1]
	v_pk_fma_f32 v[48:49], v[48:49], v[50:51], v[128:129] op_sel_hi:[1,0,1]
	v_pk_fma_f32 v[86:87], v[86:87], v[50:51], v[164:165] op_sel_hi:[1,0,1]
	v_pk_fma_f32 v[60:61], v[60:61], v[50:51], v[72:73] op_sel_hi:[1,0,1]
	v_mul_f32_e32 v88, 0xbfb8aa3b, v57
	v_mul_f32_e32 v89, 0xbfb8aa3b, v49
	v_pk_fma_f32 v[84:85], v[84:85], v[50:51], v[132:133] op_sel_hi:[1,0,1]
	v_mul_f32_e32 v58, 0xbfb8aa3b, v87
	v_mul_f32_e32 v62, 0xbfb8aa3b, v61
	v_exp_f32_e32 v88, v88
	v_exp_f32_e32 v89, v89
	v_mul_f32_e32 v54, 0xbfb8aa3b, v85
	v_exp_f32_e32 v58, v58
	v_exp_f32_e32 v62, v62
	v_exp_f32_e32 v54, v54
	v_pk_fma_f32 v[52:53], v[52:53], v[50:51], v[136:137] op_sel_hi:[1,0,1]
	v_add_f32_e32 v88, 1.0, v88
	v_add_f32_e32 v89, 1.0, v89
	v_mul_f32_e32 v90, 0xbfb8aa3b, v53
	v_add_f32_e32 v58, 1.0, v58
	v_add_f32_e32 v62, 1.0, v62
	v_rcp_f32_e32 v88, v88
	v_rcp_f32_e32 v89, v89
	v_exp_f32_e32 v90, v90
	v_add_f32_e32 v54, 1.0, v54
	v_rcp_f32_e32 v58, v58
	v_rcp_f32_e32 v62, v62
	v_rcp_f32_e32 v54, v54
	v_mul_f32_e32 v57, v57, v88
	v_mul_f32_e32 v49, v49, v89
	v_mul_f32_e32 v58, v87, v58
	v_mul_f32_e32 v61, v61, v62
	v_mul_f32_e32 v56, v56, v57
	v_mul_f32_e32 v57, v48, v49
	v_add_f32_e32 v48, 1.0, v90
	v_mov_b32_e32 v62, v55
	v_mul_f32_e32 v54, v85, v54
	v_mul_f32_e32 v85, v86, v58
	v_mul_f32_e32 v60, v60, v61
	v_rcp_f32_e32 v61, v48
	v_pk_fma_f32 v[48:49], v[78:79], v[82:83], v[62:63] op_sel_hi:[1,0,1] neg_lo:[1,0,0] neg_hi:[1,0,0]
	v_mov_b32_e32 v58, v51
	v_mul_f32_e32 v84, v84, v54
	v_pk_fma_f32 v[48:49], v[48:49], v[50:51], v[74:75] op_sel_hi:[1,0,1]
	v_pk_fma_f32 v[54:55], v[66:67], v[82:83], v[58:59] op_sel_hi:[1,0,1] neg_lo:[1,0,0] neg_hi:[1,0,0]
	v_mul_f32_e32 v53, v53, v61
	v_pk_fma_f32 v[50:51], v[54:55], v[50:51], v[70:71] op_sel_hi:[1,0,1]
	v_mul_f32_e32 v54, 0xbfb8aa3b, v49
	v_exp_f32_e32 v54, v54
	v_mul_f32_e32 v55, 0xbfb8aa3b, v51
	v_exp_f32_e32 v55, v55
	v_mul_f32_e32 v52, v52, v53
	v_add_f32_e32 v54, 1.0, v54
	v_rcp_f32_e32 v54, v54
	v_add_f32_e32 v55, 1.0, v55
	v_rcp_f32_e32 v55, v55
	v_mov_b32_e32 v53, v44
	v_mul_f32_e32 v49, v49, v54
	v_mul_f32_e32 v49, v48, v49
	v_mul_f32_e32 v48, v51, v55
	v_mul_f32_e32 v51, v50, v48
	v_cvt_pk_bf16_f32 v48, v84, v60
	v_cvt_pk_bf16_f32 v49, v57, v49
	v_cvt_pk_bf16_f32 v50, v85, v56
	v_cvt_pk_bf16_f32 v51, v52, v51
	global_store_dwordx4 v[80:81], v[48:51], off sc1
	v_mov_b32_e32 v52, v36
	v_mov_b32_e32 v36, v34
	v_add_u32_e32 v48, 0x90, v162
	v_ashrrev_i32_e32 v49, 31, v48
	v_lshl_add_u64 v[50:51], v[48:49], 3, s[8:9]
	v_mov_b32_e32 v50, v246
	v_mov_b32_e32 v51, v247
	v_mov_b32_e32 v54, v32
	v_mov_b32_e32 v32, v38
	v_mov_b32_e32 v44, v37
	v_mov_b32_e32 v37, v42
	v_mov_b32_e32 v55, v40
	v_mov_b32_e32 v40, v33
	v_mov_b32_e32 v33, v46
	v_mad_i64_i32 v[48:49], s[0:1], v48, s53, v[160:161]
	v_lshl_add_u64 v[48:49], v[48:49], 0, v[170:171]
	s_nop 0
	v_pk_mul_f32 v[50:51], v[50:51], s[20:21] op_sel_hi:[1,0]
	s_nop 0
	v_fma_f32 v34, -v50, v50, v51
	v_max_f32_e32 v34, 0, v34
	v_add_f32_e32 v34, 0x3727c5ac, v34
	v_mul_f32_e32 v38, 0x4f800000, v34
	v_cmp_gt_f32_e32 vcc, s54, v34
	v_pk_fma_f32 v[40:41], v[64:65], v[50:51], v[40:41] op_sel_hi:[1,0,1] neg_lo:[1,0,0] neg_hi:[1,0,0]
	v_pk_fma_f32 v[32:33], v[166:167], v[50:51], v[32:33] op_sel_hi:[1,0,1] neg_lo:[1,0,0] neg_hi:[1,0,0]
	v_cndmask_b32_e32 v34, v34, v38, vcc
	v_sqrt_f32_e32 v38, v34
	v_pk_fma_f32 v[54:55], v[174:175], v[50:51], v[54:55] op_sel_hi:[1,0,1] neg_lo:[1,0,0] neg_hi:[1,0,0]
	v_pk_fma_f32 v[44:45], v[76:77], v[50:51], v[44:45] op_sel_hi:[1,0,1] neg_lo:[1,0,0] neg_hi:[1,0,0]
	v_pk_fma_f32 v[52:53], v[172:173], v[50:51], v[52:53] op_sel_hi:[1,0,1] neg_lo:[1,0,0] neg_hi:[1,0,0]
	v_add_u32_e32 v42, -1, v38
	v_add_u32_e32 v46, 1, v38
	v_fma_f32 v56, -v42, v38, v34
	v_fma_f32 v57, -v46, v38, v34
	v_cmp_ge_f32_e64 s[0:1], 0, v56
	v_pk_fma_f32 v[36:37], v[168:169], v[50:51], v[36:37] op_sel_hi:[1,0,1] neg_lo:[1,0,0] neg_hi:[1,0,0]
	s_nop 0
	v_cndmask_b32_e64 v38, v38, v42, s[0:1]
	v_cmp_lt_f32_e64 s[0:1], 0, v57
	s_nop 1
	v_cndmask_b32_e64 v38, v38, v46, s[0:1]
	v_mul_f32_e32 v42, 0x37800000, v38
	v_cndmask_b32_e32 v38, v38, v42, vcc
	v_cmp_class_f32_e32 vcc, v34, v186
	s_nop 1
	v_cndmask_b32_e32 v34, v38, v34, vcc
	v_div_scale_f32 v38, s[0:1], v34, v34, 1.0
	v_rcp_f32_e32 v42, v38
	v_div_scale_f32 v46, vcc, 1.0, v34, 1.0
	v_fma_f32 v56, -v38, v42, 1.0
	v_fmac_f32_e32 v42, v56, v42
	v_mul_f32_e32 v56, v46, v42
	v_fma_f32 v57, -v38, v56, v46
	v_fmac_f32_e32 v56, v57, v42
	v_fma_f32 v38, -v38, v56, v46
	v_div_fmas_f32 v38, v38, v42, v56
	v_div_fixup_f32 v34, v38, v34, 1.0
	v_pk_fma_f32 v[40:41], v[40:41], v[34:35], v[68:69] op_sel_hi:[1,0,1]
	v_pk_fma_f32 v[32:33], v[32:33], v[34:35], v[128:129] op_sel_hi:[1,0,1]
; __device__ __forceinline__ unsigned cvt_pk_bf16(float lo, float hi) { unsigned r; asm volatile("v_cvt_pk_bf16_f32 %0, %1, %2" : "=v"(r) : "v"(lo), "v"(hi)); return r; }
; __device__ __forceinline__ float sigmoidf_(float x) { return __builtin_amdgcn_rcpf(1.0f + __expf(-x)); }
; __device__ __forceinline__ float siluf_(float x) { return x * sigmoidf_(x); }
; __device__ __forceinline__ float gelu_tanh(float x) { return x * sigmoidf_(1.5957691216057308f * (x + 0.044715f * x * x * x)); }
; __device__ __forceinline__ f32x2 ln_stats(f32x2 sm) { const float mu = sm[0] * (1.f / D); const float var = fmaxf(sm[1] * (1.f / D) - mu * mu, 0.f); return (f32x2){mu, 1.0f / sqrtf(var + LN_EPS)}; }
;     __device__ __forceinline__ void operator()(const f32x4 (&acc)[2][2][4][2], const Unit& u, int wr, int wc, int fr, int fq) const {
;     ...
;             for (int m = 0; m < 4; ++m) {
;                 const int r = row0 + ai * HALF + m * 16;
;                 bf16_t* rowp = H + (size_t)r * ldh + col0;
;                 f32x2 st = (f32x2){0.f, 1.f};
;                 if (rsum) st = ln_stats(*(const f32x2*)(rsum + 2 * (size_t)r));
;                 f32x4 v0, v1;
; #pragma unroll
;                 for (int j = 0; j < 4; ++j) {
;                     const float g0 = st[1] * (acc[ai][0][m][0][j] - st[0] * s1[0][0][j]) + s2[0][0][j], u0 = st[1] * (acc[ai][1][m][0][j] - st[0] * s1[1][0][j]) + s2[1][0][j];
;                     const float g1 = st[1] * (acc[ai][0][m][1][j] - st[0] * s1[0][1][j]) + s2[0][1][j], u1 = st[1] * (acc[ai][1][m][1][j] - st[0] * s1[1][1][j]) + s2[1][1][j];
;                     v0[j] = siluf_(g0) * u0; v1[j] = siluf_(g1) * u1;
;                 }
;                 u32x4 w; w.x = cvt_pk_bf16(v0[0], v0[1]); w.y = cvt_pk_bf16(v0[2], v0[3]); w.z = cvt_pk_bf16(v1[0], v1[1]); w.w = cvt_pk_bf16(v1[2], v1[3]);
;                 *(u32x4*)rowp = w;
;             }
	v_pk_fma_f32 v[54:55], v[54:55], v[34:35], v[164:165] op_sel_hi:[1,0,1]
	v_pk_fma_f32 v[44:45], v[44:45], v[34:35], v[72:73] op_sel_hi:[1,0,1]
	v_mul_f32_e32 v56, 0xbfb8aa3b, v41
	v_mul_f32_e32 v57, 0xbfb8aa3b, v33
	v_pk_fma_f32 v[52:53], v[52:53], v[34:35], v[132:133] op_sel_hi:[1,0,1]
	v_mul_f32_e32 v42, 0xbfb8aa3b, v55
	v_mul_f32_e32 v46, 0xbfb8aa3b, v45
	v_exp_f32_e32 v56, v56
	v_exp_f32_e32 v57, v57
	v_mul_f32_e32 v38, 0xbfb8aa3b, v53
	v_exp_f32_e32 v42, v42
	v_exp_f32_e32 v46, v46
	v_exp_f32_e32 v38, v38
	v_pk_fma_f32 v[36:37], v[36:37], v[34:35], v[136:137] op_sel_hi:[1,0,1]
	v_add_f32_e32 v56, 1.0, v56
	v_add_f32_e32 v57, 1.0, v57
	v_mul_f32_e32 v58, 0xbfb8aa3b, v37
	v_add_f32_e32 v42, 1.0, v42
	v_add_f32_e32 v46, 1.0, v46
	v_rcp_f32_e32 v56, v56
	v_rcp_f32_e32 v57, v57
	v_exp_f32_e32 v58, v58
	v_add_f32_e32 v38, 1.0, v38
	v_rcp_f32_e32 v42, v42
	v_rcp_f32_e32 v46, v46
	v_rcp_f32_e32 v38, v38
	v_mul_f32_e32 v41, v41, v56
	v_mul_f32_e32 v33, v33, v57
	v_mul_f32_e32 v42, v55, v42
	v_mul_f32_e32 v45, v45, v46
	v_mul_f32_e32 v40, v40, v41
	v_mul_f32_e32 v41, v32, v33
	v_add_f32_e32 v32, 1.0, v58
	v_mov_b32_e32 v46, v39
	v_mul_f32_e32 v38, v53, v38
	v_mul_f32_e32 v53, v54, v42
	v_mul_f32_e32 v44, v44, v45
	v_rcp_f32_e32 v45, v32
	v_pk_fma_f32 v[32:33], v[78:79], v[50:51], v[46:47] op_sel_hi:[1,0,1] neg_lo:[1,0,0] neg_hi:[1,0,0]
	v_mov_b32_e32 v42, v35
	v_mul_f32_e32 v52, v52, v38
	v_pk_fma_f32 v[32:33], v[32:33], v[34:35], v[74:75] op_sel_hi:[1,0,1]
	v_pk_fma_f32 v[38:39], v[66:67], v[50:51], v[42:43] op_sel_hi:[1,0,1] neg_lo:[1,0,0] neg_hi:[1,0,0]
	v_mul_f32_e32 v37, v37, v45
	v_pk_fma_f32 v[34:35], v[38:39], v[34:35], v[70:71] op_sel_hi:[1,0,1]
	v_mul_f32_e32 v38, 0xbfb8aa3b, v33
	v_exp_f32_e32 v38, v38
	v_mul_f32_e32 v39, 0xbfb8aa3b, v35
	v_exp_f32_e32 v39, v39
	v_mul_f32_e32 v36, v36, v37
	v_add_f32_e32 v38, 1.0, v38
	v_rcp_f32_e32 v38, v38
	v_add_f32_e32 v39, 1.0, v39
	v_rcp_f32_e32 v39, v39
	v_mov_b32_e32 v37, v24
	v_mul_f32_e32 v33, v33, v38
	v_mul_f32_e32 v33, v32, v33
	v_mul_f32_e32 v32, v35, v39
	v_mul_f32_e32 v35, v34, v32
	v_cvt_pk_bf16_f32 v32, v52, v44
	v_cvt_pk_bf16_f32 v33, v41, v33
	v_cvt_pk_bf16_f32 v34, v53, v40
	v_cvt_pk_bf16_f32 v35, v36, v35
	global_store_dwordx4 v[48:49], v[32:35], off sc1
	v_mov_b32_e32 v38, v16
	v_mov_b32_e32 v39, v20
	v_add_u32_e32 v32, 0xa0, v162
	v_ashrrev_i32_e32 v33, 31, v32
	v_lshl_add_u64 v[34:35], v[32:33], 3, s[8:9]
	v_mov_b32_e32 v34, v248
	v_mov_b32_e32 v35, v249
	v_mov_b32_e32 v20, v17
	v_mov_b32_e32 v16, v30
	v_mov_b32_e32 v17, v26
	v_mov_b32_e32 v26, v31
	v_mad_i64_i32 v[30:31], s[0:1], v32, s53, v[160:161]
	v_mov_b32_e32 v36, v28
	v_mov_b32_e32 v28, v18
	v_mov_b32_e32 v24, v29
	v_mov_b32_e32 v29, v22
	v_lshl_add_u64 v[30:31], v[30:31], 0, v[170:171]
	s_nop 0
	v_pk_mul_f32 v[32:33], v[34:35], s[20:21] op_sel_hi:[1,0]
	s_nop 0
	v_fma_f32 v18, -v32, v32, v33
	v_max_f32_e32 v18, 0, v18
	v_add_f32_e32 v18, 0x3727c5ac, v18
	v_mul_f32_e32 v22, 0x4f800000, v18
	v_cmp_gt_f32_e32 vcc, s54, v18
	v_pk_fma_f32 v[34:35], v[172:173], v[32:33], v[36:37] op_sel_hi:[1,0,1] neg_lo:[1,0,0] neg_hi:[1,0,0]
	v_pk_fma_f32 v[36:37], v[174:175], v[32:33], v[38:39] op_sel_hi:[1,0,1] neg_lo:[1,0,0] neg_hi:[1,0,0]
	v_cndmask_b32_e32 v18, v18, v22, vcc
	v_sqrt_f32_e32 v22, v18
	v_pk_fma_f32 v[16:17], v[166:167], v[32:33], v[16:17] op_sel_hi:[1,0,1] neg_lo:[1,0,0] neg_hi:[1,0,0]
	v_pk_fma_f32 v[24:25], v[76:77], v[32:33], v[24:25] op_sel_hi:[1,0,1] neg_lo:[1,0,0] neg_hi:[1,0,0]
	v_pk_fma_f32 v[20:21], v[64:65], v[32:33], v[20:21] op_sel_hi:[1,0,1] neg_lo:[1,0,0] neg_hi:[1,0,0]
	v_add_u32_e32 v38, -1, v22
	v_add_u32_e32 v39, 1, v22
	v_fma_f32 v40, -v38, v22, v18
	v_fma_f32 v41, -v39, v22, v18
	v_cmp_ge_f32_e64 s[0:1], 0, v40
	v_pk_fma_f32 v[28:29], v[168:169], v[32:33], v[28:29] op_sel_hi:[1,0,1] neg_lo:[1,0,0] neg_hi:[1,0,0]
	s_nop 0
	v_cndmask_b32_e64 v22, v22, v38, s[0:1]
	v_cmp_lt_f32_e64 s[0:1], 0, v41
	s_nop 1
	v_cndmask_b32_e64 v22, v22, v39, s[0:1]
	v_mul_f32_e32 v38, 0x37800000, v22
	v_cndmask_b32_e32 v22, v22, v38, vcc
	v_cmp_class_f32_e32 vcc, v18, v186
	s_nop 1
	v_cndmask_b32_e32 v18, v22, v18, vcc
	v_div_scale_f32 v22, s[0:1], v18, v18, 1.0
	v_rcp_f32_e32 v38, v22
	v_div_scale_f32 v39, vcc, 1.0, v18, 1.0
	v_fma_f32 v40, -v22, v38, 1.0
	v_fmac_f32_e32 v38, v40, v38
	v_mul_f32_e32 v40, v39, v38
	v_fma_f32 v41, -v22, v40, v39
	v_fmac_f32_e32 v40, v41, v38
	v_fma_f32 v22, -v22, v40, v39
	v_div_fmas_f32 v22, v22, v38, v40
	v_div_fixup_f32 v18, v22, v18, 1.0
	v_pk_fma_f32 v[34:35], v[34:35], v[18:19], v[132:133] op_sel_hi:[1,0,1]
	v_pk_fma_f32 v[36:37], v[36:37], v[18:19], v[164:165] op_sel_hi:[1,0,1]
	v_pk_fma_f32 v[16:17], v[16:17], v[18:19], v[128:129] op_sel_hi:[1,0,1]
	v_pk_fma_f32 v[24:25], v[24:25], v[18:19], v[72:73] op_sel_hi:[1,0,1]
	v_pk_fma_f32 v[20:21], v[20:21], v[18:19], v[68:69] op_sel_hi:[1,0,1]
	v_mul_f32_e32 v22, 0xbfb8aa3b, v35
	v_mul_f32_e32 v38, 0xbfb8aa3b, v37
	v_mul_f32_e32 v41, 0xbfb8aa3b, v17
	v_mul_f32_e32 v39, 0xbfb8aa3b, v25
	v_mul_f32_e32 v40, 0xbfb8aa3b, v21
	v_exp_f32_e32 v22, v22
	v_exp_f32_e32 v38, v38
	v_exp_f32_e32 v41, v41
	v_exp_f32_e32 v39, v39
	v_exp_f32_e32 v40, v40
	v_add_f32_e32 v22, 1.0, v22
	v_add_f32_e32 v38, 1.0, v38
	v_add_f32_e32 v41, 1.0, v41
	v_add_f32_e32 v39, 1.0, v39
	v_add_f32_e32 v40, 1.0, v40
	v_rcp_f32_e32 v22, v22
	v_rcp_f32_e32 v38, v38
	v_rcp_f32_e32 v41, v41
	v_rcp_f32_e32 v39, v39
	v_rcp_f32_e32 v40, v40
	v_mul_f32_e32 v22, v35, v22
	v_mul_f32_e32 v35, v37, v38
	v_mul_f32_e32 v17, v17, v41
	v_mul_f32_e32 v25, v25, v39
	v_mul_f32_e32 v21, v21, v40
	v_mul_f32_e32 v34, v34, v22
	v_mul_f32_e32 v35, v36, v35
	v_mul_f32_e32 v36, v16, v17
; __device__ __forceinline__ unsigned cvt_pk_bf16(float lo, float hi) { unsigned r; asm volatile("v_cvt_pk_bf16_f32 %0, %1, %2" : "=v"(r) : "v"(lo), "v"(hi)); return r; }
; __device__ __forceinline__ float siluf_(float x) { return x * sigmoidf_(x); }
; #define PG8_BAR __builtin_amdgcn_s_barrier()
; template <class Sched, class Epi, bool ALIGN_EPI, bool SP2>
; __device__ __forceinline__ void gemm_phase(LAS unsigned char* lds, const int K, const int lda, const int ldb, const Sched& S, const Epi& E) {
;     ...
;         if constexpr (ALIGN_EPI) { if (wr == 0) PG8_BAR; }
;         E(acc, cur, wr, wc, fr, fq);
;         if (!has_next) break;
;         bool keep = false;
;         if constexpr (Epi::CAN_KEEP) keep = (cur.kind < 2);
;         if (!keep) {
; #pragma unroll
;         for (int a = 0; a < 2; ++a)
; #pragma unroll
;             for (int b = 0; b < 2; ++b)
; #pragma unroll
;                 for (int m = 0; m < 4; ++m)
; #pragma unroll
;                     for (int n = 0; n < 2; ++n) acc[a][b][m][n] = (f32x4){0.f, 0.f, 0.f, 0.f};
;         }
;         cur = nxt; cA = nA; cB = nB; ++ui;
;         if constexpr (ALIGN_EPI) { if (wr == 1) PG8_BAR; }
;     __device__ __forceinline__ void operator()(const f32x4 (&acc)[2][2][4][2], const Unit& u, int wr, int wc, int fr, int fq) const {
;     ...
;             for (int m = 0; m < 4; ++m) {
;                 const int r = row0 + ai * HALF + m * 16;
;                 bf16_t* rowp = H + (size_t)r * ldh + col0;
;                 f32x2 st = (f32x2){0.f, 1.f};
;                 if (rsum) st = ln_stats(*(const f32x2*)(rsum + 2 * (size_t)r));
;                 f32x4 v0, v1;
; #pragma unroll
;                 for (int j = 0; j < 4; ++j) {
;                     const float g0 = st[1] * (acc[ai][0][m][0][j] - st[0] * s1[0][0][j]) + s2[0][0][j], u0 = st[1] * (acc[ai][1][m][0][j] - st[0] * s1[1][0][j]) + s2[1][0][j];
;                     const float g1 = st[1] * (acc[ai][0][m][1][j] - st[0] * s1[0][1][j]) + s2[0][1][j], u1 = st[1] * (acc[ai][1][m][1][j] - st[0] * s1[1][1][j]) + s2[1][1][j];
;                     v0[j] = siluf_(g0) * u0; v1[j] = siluf_(g1) * u1;
;                 }
;                 u32x4 w; w.x = cvt_pk_bf16(v0[0], v0[1]); w.y = cvt_pk_bf16(v0[2], v0[3]); w.z = cvt_pk_bf16(v1[0], v1[1]); w.w = cvt_pk_bf16(v1[2], v1[3]);
;                 *(u32x4*)rowp = w;
;             }
	v_pk_fma_f32 v[16:17], v[78:79], v[32:33], v[26:27] op_sel_hi:[1,0,1] neg_lo:[1,0,0] neg_hi:[1,0,0]
	v_mov_b32_e32 v22, v19
	v_mul_f32_e32 v24, v24, v25
	v_mul_f32_e32 v25, v20, v21
	v_pk_fma_f32 v[16:17], v[16:17], v[18:19], v[74:75] op_sel_hi:[1,0,1]
	v_pk_fma_f32 v[20:21], v[66:67], v[32:33], v[22:23] op_sel_hi:[1,0,1] neg_lo:[1,0,0] neg_hi:[1,0,0]
	v_pk_fma_f32 v[28:29], v[28:29], v[18:19], v[136:137] op_sel_hi:[1,0,1]
	v_pk_fma_f32 v[18:19], v[20:21], v[18:19], v[70:71] op_sel_hi:[1,0,1]
	v_mul_f32_e32 v20, 0xbfb8aa3b, v17
	v_exp_f32_e32 v20, v20
	v_mul_f32_e32 v21, 0xbfb8aa3b, v19
	v_mul_f32_e32 v42, 0xbfb8aa3b, v29
	v_exp_f32_e32 v21, v21
	v_exp_f32_e32 v42, v42
	v_add_f32_e32 v20, 1.0, v20
	v_rcp_f32_e32 v20, v20
	v_add_f32_e32 v21, 1.0, v21
	v_add_f32_e32 v42, 1.0, v42
	v_rcp_f32_e32 v21, v21
	v_rcp_f32_e32 v42, v42
	v_mul_f32_e32 v17, v17, v20
	v_mul_f32_e32 v17, v16, v17
	v_mul_f32_e32 v16, v19, v21
	v_mul_f32_e32 v22, v29, v42
	v_mul_f32_e32 v19, v18, v16
	v_cvt_pk_bf16_f32 v16, v34, v24
	v_mul_f32_e32 v22, v28, v22
	v_cvt_pk_bf16_f32 v17, v36, v17
	v_cvt_pk_bf16_f32 v18, v35, v25
	v_cvt_pk_bf16_f32 v19, v22, v19
	global_store_dwordx4 v[30:31], v[16:19], off sc1
	v_mov_b32_e32 v22, v4
	v_mov_b32_e32 v23, v0
	v_add_u32_e32 v16, 0xb0, v162
	v_ashrrev_i32_e32 v17, 31, v16
	v_lshl_add_u64 v[18:19], v[16:17], 3, s[8:9]
	v_mov_b32_e32 v18, v250
	v_mov_b32_e32 v19, v251
	v_mov_b32_e32 v0, v5
	v_mov_b32_e32 v4, v14
	v_mov_b32_e32 v5, v10
	v_mov_b32_e32 v10, v15
	v_mov_b32_e32 v20, v12
	v_mov_b32_e32 v21, v8
	v_mov_b32_e32 v8, v13
	v_mov_b32_e32 v12, v6
	v_mov_b32_e32 v13, v2
	v_mov_b32_e32 v2, v7
	v_mad_i64_i32 v[6:7], s[0:1], v16, s53, v[160:161]
	v_lshl_add_u64 v[6:7], v[6:7], 0, v[170:171]
	s_nop 0
	v_pk_mul_f32 v[14:15], v[18:19], s[20:21] op_sel_hi:[1,0]
	s_nop 0
	v_fma_f32 v24, -v14, v14, v15
	v_pk_fma_f32 v[16:17], v[172:173], v[14:15], v[20:21] op_sel_hi:[1,0,1] neg_lo:[1,0,0] neg_hi:[1,0,0]
	v_max_f32_e32 v20, 0, v24
	v_add_f32_e32 v20, 0x3727c5ac, v20
	v_mul_f32_e32 v21, 0x4f800000, v20
	v_cmp_gt_f32_e32 vcc, s54, v20
	v_pk_fma_f32 v[18:19], v[174:175], v[14:15], v[22:23] op_sel_hi:[1,0,1] neg_lo:[1,0,0] neg_hi:[1,0,0]
	v_pk_fma_f32 v[8:9], v[76:77], v[14:15], v[8:9] op_sel_hi:[1,0,1] neg_lo:[1,0,0] neg_hi:[1,0,0]
	v_cndmask_b32_e32 v20, v20, v21, vcc
	v_sqrt_f32_e32 v21, v20
	v_pk_fma_f32 v[0:1], v[64:65], v[14:15], v[0:1] op_sel_hi:[1,0,1] neg_lo:[1,0,0] neg_hi:[1,0,0]
	v_pk_fma_f32 v[4:5], v[166:167], v[14:15], v[4:5] op_sel_hi:[1,0,1] neg_lo:[1,0,0] neg_hi:[1,0,0]
	v_pk_fma_f32 v[12:13], v[168:169], v[14:15], v[12:13] op_sel_hi:[1,0,1] neg_lo:[1,0,0] neg_hi:[1,0,0]
	v_add_u32_e32 v22, -1, v21
	v_add_u32_e32 v23, 1, v21
	v_fma_f32 v24, -v22, v21, v20
	v_fma_f32 v25, -v23, v21, v20
	v_cmp_ge_f32_e64 s[0:1], 0, v24
	v_pk_fma_f32 v[10:11], v[78:79], v[14:15], v[10:11] op_sel_hi:[1,0,1] neg_lo:[1,0,0] neg_hi:[1,0,0]
	s_nop 0
	v_cndmask_b32_e64 v21, v21, v22, s[0:1]
	v_cmp_lt_f32_e64 s[0:1], 0, v25
	s_nop 1
	v_cndmask_b32_e64 v21, v21, v23, s[0:1]
	v_mul_f32_e32 v22, 0x37800000, v21
	v_cndmask_b32_e32 v21, v21, v22, vcc
	v_cmp_class_f32_e32 vcc, v20, v186
	s_nop 1
	v_cndmask_b32_e32 v20, v21, v20, vcc
	v_div_scale_f32 v21, s[0:1], v20, v20, 1.0
	v_rcp_f32_e32 v22, v21
	v_div_scale_f32 v23, vcc, 1.0, v20, 1.0
	s_mov_b64 s[0:1], -1
	v_fma_f32 v24, -v21, v22, 1.0
	v_fmac_f32_e32 v22, v24, v22
	v_mul_f32_e32 v24, v23, v22
	v_fma_f32 v25, -v21, v24, v23
	v_fmac_f32_e32 v24, v25, v22
	v_fma_f32 v21, -v21, v24, v23
	v_div_fmas_f32 v21, v21, v22, v24
	v_div_fixup_f32 v20, v21, v20, 1.0
	v_pk_fma_f32 v[8:9], v[8:9], v[20:21], v[72:73] op_sel_hi:[1,0,1]
	v_pk_fma_f32 v[0:1], v[0:1], v[20:21], v[68:69] op_sel_hi:[1,0,1]
	v_mul_f32_e32 v23, 0xbfb8aa3b, v9
	v_mul_f32_e32 v24, 0xbfb8aa3b, v1
	v_pk_fma_f32 v[16:17], v[16:17], v[20:21], v[132:133] op_sel_hi:[1,0,1]
	v_exp_f32_e32 v23, v23
	v_exp_f32_e32 v24, v24
	v_pk_fma_f32 v[18:19], v[18:19], v[20:21], v[164:165] op_sel_hi:[1,0,1]
	v_pk_fma_f32 v[4:5], v[4:5], v[20:21], v[128:129] op_sel_hi:[1,0,1]
	v_pk_fma_f32 v[12:13], v[12:13], v[20:21], v[136:137] op_sel_hi:[1,0,1]
	v_pk_fma_f32 v[10:11], v[10:11], v[20:21], v[74:75] op_sel_hi:[1,0,1]
	v_mul_f32_e32 v21, 0xbfb8aa3b, v17
	v_exp_f32_e32 v21, v21
	v_add_f32_e32 v23, 1.0, v23
	v_add_f32_e32 v24, 1.0, v24
	v_rcp_f32_e32 v23, v23
	v_rcp_f32_e32 v24, v24
	v_add_f32_e32 v21, 1.0, v21
	v_rcp_f32_e32 v21, v21
	v_mul_f32_e32 v9, v9, v23
	v_mul_f32_e32 v1, v1, v24
	v_mul_f32_e32 v8, v8, v9
	v_mul_f32_e32 v9, v0, v1
	v_pk_fma_f32 v[0:1], v[66:67], v[14:15], v[2:3] op_sel_hi:[1,0,1] neg_lo:[1,0,0] neg_hi:[1,0,0]
	v_mul_f32_e32 v25, 0xbfb8aa3b, v5
	v_pk_fma_f32 v[0:1], v[0:1], v[20:21], v[70:71] op_sel_hi:[1,0,1]
	v_mul_f32_e32 v2, 0xbfb8aa3b, v11
	v_mul_f32_e32 v3, 0xbfb8aa3b, v1
	v_mul_f32_e32 v22, 0xbfb8aa3b, v19
	v_mul_f32_e32 v26, 0xbfb8aa3b, v13
	v_exp_f32_e32 v25, v25
	v_exp_f32_e32 v2, v2
	v_exp_f32_e32 v3, v3
	v_exp_f32_e32 v22, v22
	v_exp_f32_e32 v26, v26
	v_add_f32_e32 v25, 1.0, v25
	v_add_f32_e32 v2, 1.0, v2
	v_add_f32_e32 v3, 1.0, v3
	v_add_f32_e32 v22, 1.0, v22
	v_add_f32_e32 v26, 1.0, v26
	v_rcp_f32_e32 v25, v25
	v_rcp_f32_e32 v2, v2
	v_rcp_f32_e32 v3, v3
	v_rcp_f32_e32 v22, v22
	v_rcp_f32_e32 v26, v26
	v_mul_f32_e32 v5, v5, v25
	v_mul_f32_e32 v2, v11, v2
	v_mul_f32_e32 v1, v1, v3
	v_mul_f32_e32 v17, v17, v21
	v_mul_f32_e32 v19, v19, v22
	v_mul_f32_e32 v4, v4, v5
	v_mul_f32_e32 v5, v13, v26
	v_mul_f32_e32 v2, v10, v2
	v_mul_f32_e32 v3, v0, v1
	s_andn2_b64 vcc, exec, s[22:23]
	v_mul_f32_e32 v16, v16, v17
	v_mul_f32_e32 v17, v18, v19
	v_mul_f32_e32 v5, v12, v5
	v_cvt_pk_bf16_f32 v0, v16, v8
	v_cvt_pk_bf16_f32 v1, v4, v2
	v_cvt_pk_bf16_f32 v2, v17, v9
	v_cvt_pk_bf16_f32 v3, v5, v3
	global_store_dwordx4 v[6:7], v[0:3], off sc1
	s_cbranch_vccnz .LBB0_1029
	s_andn2_b64 vcc, exec, s[4:5]
	s_cbranch_vccnz .LBB0_1028
	s_barrier
	s_branch .LBB0_1028

; __device__ __forceinline__ unsigned cvt_pk_bf16(float lo, float hi) { unsigned r; asm volatile("v_cvt_pk_bf16_f32 %0, %1, %2" : "=v"(r) : "v"(lo), "v"(hi)); return r; }
; __device__ __forceinline__ f32x2 ln_stats(f32x2 sm) { const float mu = sm[0] * (1.f / D); const float var = fmaxf(sm[1] * (1.f / D) - mu * mu, 0.f); return (f32x2){mu, 1.0f / sqrtf(var + LN_EPS)}; }
; template <int MODE> ...
;     ...
;         if (kh == 1) red[tw * 64 + lane] = tot;
;         __syncthreads();
;         if (kh == 0) {
;             tot += red[tw * 64 + lane];
;             const size_t off = (size_t)(rt * 16 + fr) * D + ct * 16 + 4 * fq;
;             if (MODE == 0) {
;                 f32x4 xv = *(const f32x4*)(res + off);
;                 if (rin) { const f32x2 st = ln_stats(*(const f32x2*)(rin + 2 * (rt * 16 + fr))); const int cc = ct * 16 + 4 * fq;
;                     xv = (xv - st[0]) * (*(const f32x4*)(lg + cc) * st[1]) + *(const f32x4*)(lb + cc); }
;                 const f32x4 o = xv * alpha + tot * scale;
;                 *(f32x4*)(Ys + off) = o;
;                 if (ybs) { u32x2 w; w.x = cvt_pk_bf16(o[0], o[1]); w.y = cvt_pk_bf16(o[2], o[3]); *(u32x2*)(ybs + off) = w; }
;                 if (rout) { float ps = (o[0] + o[1]) + (o[2] + o[3]), pq = (o[0] * o[0] + o[1] * o[1]) + (o[2] * o[2] + o[3] * o[3]);
;                     ps += __shfl_xor(ps, 16); pq += __shfl_xor(pq, 16); ps += __shfl_xor(ps, 32); pq += __shfl_xor(pq, 32);
;                     if (fq == 0) { atomicAdd(rout + 2 * (rt * 16 + fr), ps); atomicAdd(rout + 2 * (rt * 16 + fr) + 1, pq); } }
;             }
;             else { u32x2 w; w.x = cvt_pk_bf16(tot[0], tot[1]); w.y = cvt_pk_bf16(tot[2], tot[3]); *(u32x2*)(MBs + off) = w; }
;         }
.LBB0_1101:
	s_and_b64 vcc, exec, s[6:7]
	s_waitcnt lgkmcnt(0)
	s_barrier
	s_cbranch_vccnz .LBB0_1098
	v_lshlrev_b32_e32 v16, 1, v12
	v_ashrrev_i32_e32 v17, 31, v16
	v_lshl_add_u64 v[16:17], v[16:17], 2, s[10:11]
	global_load_dwordx2 v[32:33], v[16:17], off
	v_ashrrev_i32_e32 v13, 31, v12
	v_lshlrev_b64 v[12:13], 13, v[12:13]
	s_lshl_b32 s12, s0, 2
	v_lshl_add_u64 v[12:13], s[50:51], 0, v[12:13]
	v_mov_b32_e32 v11, v181
	v_lshl_add_u64 v[12:13], v[12:13], 0, s[12:13]
	v_lshl_add_u64 v[12:13], v[12:13], 0, v[10:11]
	global_load_dwordx4 v[16:19], v[12:13], off
	v_or_b32_e32 v11, s0, v8
	v_readlane_b32 s72, v254, 27
	v_lshlrev_b32_e32 v11, 2, v11
	v_readlane_b32 s82, v254, 37
	v_readlane_b32 s83, v254, 38
	v_readlane_b32 s84, v254, 39
	v_readlane_b32 s85, v254, 40
	s_nop 2
	global_load_dwordx4 v[20:23], v11, s[82:83]
	s_nop 0
	global_load_dwordx4 v[24:27], v11, s[84:85]
	ds_read_b128 v[28:31], v14
	v_readlane_b32 s73, v254, 28
	v_readlane_b32 s74, v254, 29
	v_readlane_b32 s75, v254, 30
	v_readlane_b32 s76, v254, 31
	s_waitcnt lgkmcnt(0)
	v_pk_add_f32 v[0:1], v[0:1], v[28:29]
	v_pk_add_f32 v[2:3], v[2:3], v[30:31]
	v_readlane_b32 s77, v254, 32
	v_readlane_b32 s78, v254, 33
	v_readlane_b32 s79, v254, 34
	v_readlane_b32 s80, v254, 35
	v_readlane_b32 s81, v254, 36
	v_readlane_b32 s86, v254, 41
	v_readlane_b32 s87, v254, 42
	s_waitcnt vmcnt(3)
	v_pk_mul_f32 v[28:29], v[32:33], s[14:15] op_sel_hi:[1,0]
	s_nop 0
	v_fma_f32 v11, -v28, v28, v29
	v_max_f32_e32 v11, 0, v11
	v_add_f32_e32 v11, 0x3727c5ac, v11
	v_mul_f32_e32 v29, 0x4f800000, v11
	v_cmp_gt_f32_e32 vcc, s20, v11
	s_waitcnt vmcnt(2)
	v_sub_f32_e32 v17, v17, v28
	v_cndmask_b32_e32 v11, v11, v29, vcc
	v_sqrt_f32_e32 v29, v11
	v_sub_f32_e32 v16, v16, v28
	v_sub_f32_e32 v19, v19, v28
	v_sub_f32_e32 v18, v18, v28
	v_add_u32_e32 v30, -1, v29
	v_add_u32_e32 v31, 1, v29
	v_fma_f32 v32, -v30, v29, v11
	v_fma_f32 v33, -v31, v29, v11
	v_cmp_ge_f32_e64 s[0:1], 0, v32
	s_nop 1
	v_cndmask_b32_e64 v29, v29, v30, s[0:1]
	v_cmp_lt_f32_e64 s[0:1], 0, v33
	s_nop 1
	v_cndmask_b32_e64 v29, v29, v31, s[0:1]
	v_mul_f32_e32 v30, 0x37800000, v29
	v_cndmask_b32_e32 v29, v29, v30, vcc
	v_cmp_class_f32_e32 vcc, v11, v15
	s_nop 1
	v_cndmask_b32_e32 v11, v29, v11, vcc
	v_div_scale_f32 v29, s[0:1], v11, v11, 1.0
	v_rcp_f32_e32 v30, v29
	v_div_scale_f32 v28, vcc, 1.0, v11, 1.0
	v_fma_f32 v31, -v29, v30, 1.0
	v_fmac_f32_e32 v30, v31, v30
	v_mul_f32_e32 v31, v28, v30
	v_fma_f32 v32, -v29, v31, v28
	v_fmac_f32_e32 v31, v32, v30
	v_fma_f32 v28, -v29, v31, v28
	v_div_fmas_f32 v28, v28, v30, v31
	v_div_fixup_f32 v28, v28, v11, 1.0
	s_waitcnt vmcnt(1)
	v_pk_mul_f32 v[20:21], v[20:21], v[28:29] op_sel_hi:[1,0]
	v_pk_mul_f32 v[22:23], v[22:23], v[28:29] op_sel_hi:[1,0]
	s_waitcnt vmcnt(0)
	v_pk_fma_f32 v[16:17], v[16:17], v[20:21], v[24:25]
	v_pk_fma_f32 v[18:19], v[18:19], v[22:23], v[26:27]
	v_pk_mul_f32 v[16:17], v[16:17], s[16:17] op_sel_hi:[1,0]
	v_pk_mul_f32 v[18:19], v[18:19], s[16:17] op_sel_hi:[1,0]
	v_pk_fma_f32 v[0:1], v[0:1], 0.5, v[16:17] op_sel_hi:[1,0,1]
	v_pk_fma_f32 v[2:3], v[2:3], 0.5, v[18:19] op_sel_hi:[1,0,1]
	global_store_dwordx4 v[12:13], v[0:3], off sc1
	s_branch .LBB0_1098

; __device__ __forceinline__ f32x2 ln_stats(f32x2 sm) { const float mu = sm[0] * (1.f / D); const float var = fmaxf(sm[1] * (1.f / D) - mu * mu, 0.f); return (f32x2){mu, 1.0f / sqrtf(var + LN_EPS)}; }
;     __device__ __forceinline__ void operator()(const f32x4 (&acc)[2][2][4][2], const Unit& u, int wr, int wc, int fr, int fq) const {
;     ...
;         for (int ai = 0; ai < 2; ++ai)
; #pragma unroll
;             for (int m2 = 0; m2 < 2; ++m2) {
;                 f32x4 xv[2][2][2]; f32x2 st[2];
; #pragma unroll
;                 for (int mm = 0; mm < 2; ++mm) {
;                     const int r = row0 + ai * HALF + (2 * m2 + mm) * 16;
;                     st[mm] = (f32x2){0.f, 1.f};
;                     if (rin) st[mm] = ln_stats(*(const f32x2*)(rin + 2 * (size_t)r));
; #pragma unroll
;                     for (int bj = 0; bj < 2; ++bj)
; #pragma unroll
;                         for (int n = 0; n < 2; ++n) { const f32x4* rp = (const f32x4*)(res + (size_t)r * D + col0 + bj * HALF + n * 16); xv[mm][bj][n] = stream ? __builtin_nontemporal_load(rp) : *rp; }
;                 }
; #pragma unroll
;                 for (int mm = 0; mm < 2; ++mm) {
;                     const int r = row0 + ai * HALF + (2 * m2 + mm) * 16;
;                     float ps = 0.f, pq = 0.f;
; #pragma unroll
;                     for (int bj = 0; bj < 2; ++bj)
; #pragma unroll
;                         for (int n = 0; n < 2; ++n) {
;                             const f32x4 x = (xv[mm][bj][n] - st[mm][0]) * (gg[bj][n] * st[mm][1]) + bb[bj][n];
;                             const f32x4 o = x * alpha + acc[ai][bj][2 * m2 + mm][n] * scale;
;                             const size_t off = (size_t)r * D + col0 + bj * HALF + n * 16;
;                             *(f32x4*)(Y + off) = o;
.LBB0_1123:
	v_mbcnt_lo_u32_b32 v246, -1, 0
	v_mbcnt_hi_u32_b32 v246, -1, v246
	v_lshrrev_b32_e32 v247, 2, v246
	v_and_b32_e32 v248, 3, v246
	v_lshl_add_u32 v238, v248, 4, v247
	v_lshlrev_b32_e32 v238, 2, v238
	v_and_b32_e32 v249, 15, v246
	v_sub_u32_e32 v247, v247, v249
	v_lshrrev_b32_e32 v249, 4, v246
	v_sub_u32_e32 v248, v248, v249
	v_mul_i32_i24_e32 v240, 0x2000, v247
	v_lshl_add_u32 v240, v248, 4, v240
	v_ashrrev_i32_e32 v241, 31, v240
	v_mul_i32_i24_e32 v242, 0x1000, v247
	v_lshl_add_u32 v242, v248, 3, v242
	v_ashrrev_i32_e32 v243, 31, v242
	v_lshl_or_b32 v96, s48, 8, v177
	v_lshl_add_u32 v172, s47, 8, v174
	v_ashrrev_i32_e32 v97, 31, v96
	v_ashrrev_i32_e32 v173, 31, v172
	v_lshlrev_b64 v[168:169], 2, v[96:97]
	v_lshl_add_u64 v[96:97], v[172:173], 3, s[8:9]
	global_load_dwordx2 v[216:217], v[96:97], off
	v_or_b32_e32 v98, 16, v172
	v_ashrrev_i32_e32 v99, 31, v98
	v_lshl_add_u64 v[170:171], s[38:39], 0, v[168:169]
	v_lshlrev_b64 v[96:97], 13, v[172:173]
	v_lshl_add_u64 v[100:101], v[98:99], 3, s[8:9]
	v_lshl_add_u64 v[196:197], v[170:171], 0, v[96:97]
	global_load_dwordx2 v[218:219], v[100:101], off
	global_load_dwordx4 v[184:187], v[196:197], off
	global_load_dwordx4 v[188:191], v[196:197], off offset:64
	global_load_dwordx4 v[192:195], v[196:197], off offset:576
	v_readlane_b32 s48, v254, 27
	v_readlane_b32 s50, v254, 29
	v_readlane_b32 s51, v254, 30
	v_readlane_b32 s58, v254, 37
	v_readlane_b32 s59, v254, 38
	v_readlane_b32 s52, v254, 31
	v_readlane_b32 s53, v254, 32
	v_readlane_b32 s60, v254, 39
	v_readlane_b32 s61, v254, 40
	s_mov_b64 s[50:51], s[58:59]
	s_mov_b64 s[52:53], s[60:61]
	v_lshl_add_u64 v[100:101], s[50:51], 0, v[168:169]
	v_lshl_add_u64 v[198:199], s[52:53], 0, v[168:169]
	v_lshlrev_b64 v[220:221], 13, v[98:99]
	v_lshl_add_u64 v[200:201], s[38:39], 0, v[96:97]
	global_load_dwordx4 v[124:127], v[100:101], off
	global_load_dwordx4 v[116:119], v[100:101], off offset:64
	global_load_dwordx4 v[120:123], v[198:199], off
	global_load_dwordx4 v[112:115], v[198:199], off offset:64
	global_load_dwordx4 v[108:111], v[100:101], off offset:512
	s_nop 0
	global_load_dwordx4 v[100:103], v[100:101], off offset:576
	s_nop 0
	global_load_dwordx4 v[104:107], v[198:199], off offset:512
	global_load_dwordx4 v[96:99], v[198:199], off offset:576
	v_lshl_add_u64 v[212:213], v[170:171], 0, v[220:221]
	v_lshl_add_u64 v[222:223], v[200:201], 0, v[168:169]
	global_load_dwordx4 v[196:199], v[196:197], off offset:512
	s_nop 0
	global_load_dwordx4 v[200:203], v[212:213], off
	global_load_dwordx4 v[204:207], v[212:213], off offset:64
	global_load_dwordx4 v[208:211], v[212:213], off offset:512
	s_nop 0
	global_load_dwordx4 v[212:215], v[212:213], off offset:576
	v_readlane_b32 s49, v254, 28
	v_readlane_b32 s54, v254, 33
	v_readlane_b32 s55, v254, 34
	v_readlane_b32 s56, v254, 35
	v_readlane_b32 s57, v254, 36
	v_readlane_b32 s62, v254, 41
	v_readlane_b32 s63, v254, 42
	s_waitcnt vmcnt(0)
	v_pk_mul_f32 v[216:217], v[216:217], s[14:15] op_sel_hi:[1,0]
	s_nop 0
	v_fma_f32 v173, -v216, v216, v217
	v_max_f32_e32 v173, 0, v173
	v_add_f32_e32 v173, 0x3727c5ac, v173
	v_pk_mul_f32 v[218:219], v[218:219], s[14:15] op_sel_hi:[1,0]
	v_mul_f32_e32 v217, 0x4f800000, v173
	v_fma_f32 v183, -v218, v218, v219
	v_cmp_gt_f32_e32 vcc, s44, v173
	v_max_f32_e32 v183, 0, v183
	v_add_f32_e32 v183, 0x3727c5ac, v183
	v_cndmask_b32_e32 v173, v173, v217, vcc
	v_sqrt_f32_e32 v217, v173
	v_mul_f32_e32 v219, 0x4f800000, v183
	v_cmp_gt_f32_e64 s[0:1], s44, v183
	v_sub_f32_e32 v185, v185, v216
	v_add_u32_e32 v224, -1, v217
	v_cndmask_b32_e64 v183, v183, v219, s[0:1]
	v_sqrt_f32_e32 v219, v183
	v_add_u32_e32 v225, 1, v217
	v_fma_f32 v226, -v224, v217, v173
	v_fma_f32 v227, -v225, v217, v173
	v_cmp_ge_f32_e64 s[4:5], 0, v226
	v_add_u32_e32 v226, 1, v219
	v_sub_f32_e32 v184, v184, v216
	v_cndmask_b32_e64 v217, v217, v224, s[4:5]
	v_add_u32_e32 v224, -1, v219
	v_cmp_lt_f32_e64 s[4:5], 0, v227
	v_fma_f32 v227, -v226, v219, v183
	v_sub_f32_e32 v187, v187, v216
	v_cndmask_b32_e64 v217, v217, v225, s[4:5]
	v_fma_f32 v225, -v224, v219, v183
	v_mul_f32_e32 v228, 0x37800000, v217
	v_cmp_ge_f32_e64 s[4:5], 0, v225
	v_cndmask_b32_e32 v217, v217, v228, vcc
	v_cmp_lt_f32_e32 vcc, 0, v227
	v_cndmask_b32_e64 v219, v219, v224, s[4:5]
	v_sub_f32_e32 v186, v186, v216
	v_cndmask_b32_e32 v219, v219, v226, vcc
	v_cmp_class_f32_e32 vcc, v173, v182
	v_sub_f32_e32 v189, v189, v216
	v_sub_f32_e32 v188, v188, v216
	v_cndmask_b32_e32 v173, v217, v173, vcc
	v_mul_f32_e32 v217, 0x37800000, v219
	v_div_scale_f32 v224, s[4:5], v173, v173, 1.0
	v_cndmask_b32_e64 v217, v219, v217, s[0:1]
	v_cmp_class_f32_e64 s[0:1], v183, v182
	v_rcp_f32_e32 v219, v224
	v_div_scale_f32 v225, vcc, 1.0, v173, 1.0
	v_cndmask_b32_e64 v183, v217, v183, s[0:1]
	v_div_scale_f32 v217, s[0:1], v183, v183, 1.0
	v_rcp_f32_e32 v227, v217
	v_fma_f32 v228, -v224, v219, 1.0
	v_fmac_f32_e32 v219, v228, v219
	v_mul_f32_e32 v228, v225, v219
	v_fma_f32 v229, -v217, v227, 1.0
	v_div_scale_f32 v226, s[0:1], 1.0, v183, 1.0
	v_fma_f32 v230, -v224, v228, v225
	v_fmac_f32_e32 v227, v229, v227
	v_fmac_f32_e32 v228, v230, v219
	v_mul_f32_e32 v229, v226, v227
	v_fma_f32 v224, -v224, v228, v225
	v_fma_f32 v225, -v217, v229, v226
	v_div_fmas_f32 v219, v224, v219, v228
	v_fmac_f32_e32 v229, v225, v227
	v_div_fixup_f32 v224, v219, v173, 1.0
	v_fma_f32 v173, -v217, v229, v226
	s_mov_b64 vcc, s[0:1]
	v_div_fmas_f32 v173, v173, v227, v229
	v_pk_mul_f32 v[226:227], v[124:125], v[224:225] op_sel_hi:[1,0]
	v_pk_mul_f32 v[228:229], v[126:127], v[224:225] op_sel_hi:[1,0]
	v_pk_fma_f32 v[184:185], v[184:185], v[226:227], v[120:121]
	v_pk_fma_f32 v[186:187], v[186:187], v[228:229], v[122:123]
	v_pk_mul_f32 v[184:185], v[184:185], s[16:17] op_sel_hi:[1,0]
	v_pk_mul_f32 v[186:187], v[186:187], s[16:17] op_sel_hi:[1,0]
	v_pk_fma_f32 v[156:157], v[156:157], 0.5, v[184:185] op_sel_hi:[1,0,1]
	v_pk_fma_f32 v[158:159], v[158:159], 0.5, v[186:187] op_sel_hi:[1,0,1]
	ds_bpermute_b32 v246, v238, v156
	ds_bpermute_b32 v247, v238, v157
	ds_bpermute_b32 v248, v238, v158
	ds_bpermute_b32 v249, v238, v159
	v_lshl_add_u64 v[244:245], v[222:223], 0, v[240:241]
	s_waitcnt lgkmcnt(0)
; __device__ __forceinline__ f32x2 ln_stats(f32x2 sm) { const float mu = sm[0] * (1.f / D); const float var = fmaxf(sm[1] * (1.f / D) - mu * mu, 0.f); return (f32x2){mu, 1.0f / sqrtf(var + LN_EPS)}; }
;     __device__ __forceinline__ void operator()(const f32x4 (&acc)[2][2][4][2], const Unit& u, int wr, int wc, int fr, int fq) const {
;     ...
;                 for (int mm = 0; mm < 2; ++mm) {
;                     const int r = row0 + ai * HALF + (2 * m2 + mm) * 16;
;                     float ps = 0.f, pq = 0.f;
; #pragma unroll
;                     for (int bj = 0; bj < 2; ++bj)
; #pragma unroll
;                         for (int n = 0; n < 2; ++n) {
;                             const f32x4 x = (xv[mm][bj][n] - st[mm][0]) * (gg[bj][n] * st[mm][1]) + bb[bj][n];
;                             const f32x4 o = x * alpha + acc[ai][bj][2 * m2 + mm][n] * scale;
;                             const size_t off = (size_t)r * D + col0 + bj * HALF + n * 16;
;                             *(f32x4*)(Y + off) = o;
	global_store_dwordx4 v[244:245], v[246:249], off sc1
	v_pk_mul_f32 v[184:185], v[118:119], v[224:225] op_sel_hi:[1,0]
	v_div_fixup_f32 v230, v173, v183, 1.0
	v_sub_f32_e32 v157, v191, v216
	v_sub_f32_e32 v156, v190, v216
	v_pk_mul_f32 v[158:159], v[116:117], v[224:225] op_sel_hi:[1,0]
	v_pk_fma_f32 v[156:157], v[156:157], v[184:185], v[114:115]
	v_pk_fma_f32 v[158:159], v[188:189], v[158:159], v[112:113]
	v_pk_mul_f32 v[156:157], v[156:157], s[16:17] op_sel_hi:[1,0]
	v_pk_mul_f32 v[158:159], v[158:159], s[16:17] op_sel_hi:[1,0]
	v_pk_fma_f32 v[154:155], v[154:155], 0.5, v[156:157] op_sel_hi:[1,0,1]
	v_pk_fma_f32 v[152:153], v[152:153], 0.5, v[158:159] op_sel_hi:[1,0,1]
	ds_bpermute_b32 v250, v238, v152
	ds_bpermute_b32 v251, v238, v153
	ds_bpermute_b32 v252, v238, v154
	ds_bpermute_b32 v253, v238, v155
	v_lshl_add_u64 v[244:245], v[222:223], 0, v[240:241]
	s_waitcnt lgkmcnt(0)
	global_store_dwordx4 v[244:245], v[250:253], off offset:64 sc1
	v_pk_mul_f32 v[156:157], v[108:109], v[224:225] op_sel_hi:[1,0]
	v_pk_mul_f32 v[158:159], v[110:111], v[224:225] op_sel_hi:[1,0]
	v_sub_f32_e32 v153, v197, v216
	v_sub_f32_e32 v152, v196, v216
	v_sub_f32_e32 v155, v199, v216
	v_sub_f32_e32 v154, v198, v216
	v_pk_fma_f32 v[154:155], v[154:155], v[158:159], v[106:107]
	v_pk_fma_f32 v[152:153], v[152:153], v[156:157], v[104:105]
	v_pk_mul_f32 v[154:155], v[154:155], s[16:17] op_sel_hi:[1,0]
	v_pk_mul_f32 v[152:153], v[152:153], s[16:17] op_sel_hi:[1,0]
	v_pk_fma_f32 v[150:151], v[150:151], 0.5, v[154:155] op_sel_hi:[1,0,1]
	v_pk_fma_f32 v[148:149], v[148:149], 0.5, v[152:153] op_sel_hi:[1,0,1]
	ds_bpermute_b32 v246, v238, v148
	ds_bpermute_b32 v247, v238, v149
	ds_bpermute_b32 v248, v238, v150
	ds_bpermute_b32 v249, v238, v151
	v_lshl_add_u64 v[244:245], v[222:223], 0, v[240:241]
	s_waitcnt lgkmcnt(0)
	global_store_dwordx4 v[244:245], v[246:249], off offset:512 sc1
	v_pk_mul_f32 v[152:153], v[100:101], v[224:225] op_sel_hi:[1,0]
	v_pk_mul_f32 v[154:155], v[102:103], v[224:225] op_sel_hi:[1,0]
	v_sub_f32_e32 v149, v193, v216
	v_sub_f32_e32 v148, v192, v216
	v_sub_f32_e32 v151, v195, v216
	v_sub_f32_e32 v150, v194, v216
	v_pk_fma_f32 v[150:151], v[150:151], v[154:155], v[98:99]
	v_pk_fma_f32 v[148:149], v[148:149], v[152:153], v[96:97]
	v_pk_mul_f32 v[150:151], v[150:151], s[16:17] op_sel_hi:[1,0]
	v_pk_mul_f32 v[148:149], v[148:149], s[16:17] op_sel_hi:[1,0]
	v_pk_fma_f32 v[142:143], v[142:143], 0.5, v[150:151] op_sel_hi:[1,0,1]
	v_pk_fma_f32 v[140:141], v[140:141], 0.5, v[148:149] op_sel_hi:[1,0,1]
	ds_bpermute_b32 v250, v238, v140
	ds_bpermute_b32 v251, v238, v141
	ds_bpermute_b32 v252, v238, v142
	ds_bpermute_b32 v253, v238, v143
	v_lshl_add_u64 v[244:245], v[222:223], 0, v[240:241]
	s_waitcnt lgkmcnt(0)
	global_store_dwordx4 v[244:245], v[250:253], off offset:576 sc1
	v_pk_mul_f32 v[148:149], v[124:125], v[230:231] op_sel_hi:[1,0]
	v_pk_mul_f32 v[150:151], v[126:127], v[230:231] op_sel_hi:[1,0]
	v_sub_f32_e32 v141, v201, v218
	v_sub_f32_e32 v140, v200, v218
	v_sub_f32_e32 v143, v203, v218
	v_sub_f32_e32 v142, v202, v218
	v_pk_fma_f32 v[140:141], v[140:141], v[148:149], v[120:121]
	v_pk_fma_f32 v[142:143], v[142:143], v[150:151], v[122:123]
	v_pk_mul_f32 v[140:141], v[140:141], s[16:17] op_sel_hi:[1,0]
	v_pk_mul_f32 v[142:143], v[142:143], s[16:17] op_sel_hi:[1,0]
	v_pk_fma_f32 v[140:141], v[144:145], 0.5, v[140:141] op_sel_hi:[1,0,1]
	v_lshl_add_u64 v[144:145], s[38:39], 0, v[220:221]
	v_pk_fma_f32 v[142:143], v[146:147], 0.5, v[142:143] op_sel_hi:[1,0,1]
	v_lshl_add_u64 v[144:145], v[144:145], 0, v[168:169]
	ds_bpermute_b32 v246, v238, v140
	ds_bpermute_b32 v247, v238, v141
	ds_bpermute_b32 v248, v238, v142
	ds_bpermute_b32 v249, v238, v143
	v_lshl_add_u64 v[244:245], v[144:145], 0, v[240:241]
	s_waitcnt lgkmcnt(0)
	global_store_dwordx4 v[244:245], v[246:249], off sc1
	v_pk_mul_f32 v[146:147], v[116:117], v[230:231] op_sel_hi:[1,0]
	v_pk_mul_f32 v[148:149], v[118:119], v[230:231] op_sel_hi:[1,0]
	v_sub_f32_e32 v141, v205, v218
	v_sub_f32_e32 v140, v204, v218
	v_sub_f32_e32 v143, v207, v218
	v_sub_f32_e32 v142, v206, v218
	v_pk_fma_f32 v[142:143], v[142:143], v[148:149], v[114:115]
	v_pk_fma_f32 v[140:141], v[140:141], v[146:147], v[112:113]
	v_pk_mul_f32 v[142:143], v[142:143], s[16:17] op_sel_hi:[1,0]
	v_pk_mul_f32 v[140:141], v[140:141], s[16:17] op_sel_hi:[1,0]
	v_pk_fma_f32 v[138:139], v[138:139], 0.5, v[142:143] op_sel_hi:[1,0,1]
	v_pk_fma_f32 v[136:137], v[136:137], 0.5, v[140:141] op_sel_hi:[1,0,1]
	ds_bpermute_b32 v250, v238, v136
	ds_bpermute_b32 v251, v238, v137
	ds_bpermute_b32 v252, v238, v138
	ds_bpermute_b32 v253, v238, v139
	v_lshl_add_u64 v[244:245], v[144:145], 0, v[240:241]
	s_waitcnt lgkmcnt(0)
	global_store_dwordx4 v[244:245], v[250:253], off offset:64 sc1
	v_pk_mul_f32 v[140:141], v[108:109], v[230:231] op_sel_hi:[1,0]
	v_pk_mul_f32 v[142:143], v[110:111], v[230:231] op_sel_hi:[1,0]
	v_sub_f32_e32 v137, v209, v218
	v_sub_f32_e32 v136, v208, v218
	v_sub_f32_e32 v139, v211, v218
	v_sub_f32_e32 v138, v210, v218
	v_pk_fma_f32 v[138:139], v[138:139], v[142:143], v[106:107]
	v_pk_fma_f32 v[136:137], v[136:137], v[140:141], v[104:105]
	v_pk_mul_f32 v[138:139], v[138:139], s[16:17] op_sel_hi:[1,0]
	v_pk_mul_f32 v[136:137], v[136:137], s[16:17] op_sel_hi:[1,0]
	v_pk_fma_f32 v[134:135], v[134:135], 0.5, v[138:139] op_sel_hi:[1,0,1]
	v_pk_fma_f32 v[132:133], v[132:133], 0.5, v[136:137] op_sel_hi:[1,0,1]
	ds_bpermute_b32 v246, v238, v132
	ds_bpermute_b32 v247, v238, v133
	ds_bpermute_b32 v248, v238, v134
	ds_bpermute_b32 v249, v238, v135
	v_lshl_add_u64 v[244:245], v[144:145], 0, v[240:241]
	s_waitcnt lgkmcnt(0)
; __device__ __forceinline__ f32x2 ln_stats(f32x2 sm) { const float mu = sm[0] * (1.f / D); const float var = fmaxf(sm[1] * (1.f / D) - mu * mu, 0.f); return (f32x2){mu, 1.0f / sqrtf(var + LN_EPS)}; }
;     __device__ __forceinline__ void operator()(const f32x4 (&acc)[2][2][4][2], const Unit& u, int wr, int wc, int fr, int fq) const {
;     ...
;         for (int ai = 0; ai < 2; ++ai)
; #pragma unroll
;             for (int m2 = 0; m2 < 2; ++m2) {
;                 f32x4 xv[2][2][2]; f32x2 st[2];
; #pragma unroll
;                 for (int mm = 0; mm < 2; ++mm) {
;                     const int r = row0 + ai * HALF + (2 * m2 + mm) * 16;
;                     st[mm] = (f32x2){0.f, 1.f};
;                     if (rin) st[mm] = ln_stats(*(const f32x2*)(rin + 2 * (size_t)r));
; #pragma unroll
;                     for (int bj = 0; bj < 2; ++bj)
; #pragma unroll
;                         for (int n = 0; n < 2; ++n) { const f32x4* rp = (const f32x4*)(res + (size_t)r * D + col0 + bj * HALF + n * 16); xv[mm][bj][n] = stream ? __builtin_nontemporal_load(rp) : *rp; }
;                 }
; #pragma unroll
;                 for (int mm = 0; mm < 2; ++mm) {
;                     const int r = row0 + ai * HALF + (2 * m2 + mm) * 16;
;                     float ps = 0.f, pq = 0.f;
; #pragma unroll
;                     for (int bj = 0; bj < 2; ++bj)
; #pragma unroll
;                         for (int n = 0; n < 2; ++n) {
;                             const f32x4 x = (xv[mm][bj][n] - st[mm][0]) * (gg[bj][n] * st[mm][1]) + bb[bj][n];
;                             const f32x4 o = x * alpha + acc[ai][bj][2 * m2 + mm][n] * scale;
;                             const size_t off = (size_t)r * D + col0 + bj * HALF + n * 16;
;                             *(f32x4*)(Y + off) = o;
	global_store_dwordx4 v[244:245], v[246:249], off offset:512 sc1
	v_pk_mul_f32 v[136:137], v[100:101], v[230:231] op_sel_hi:[1,0]
	v_pk_mul_f32 v[138:139], v[102:103], v[230:231] op_sel_hi:[1,0]
	v_sub_f32_e32 v133, v213, v218
	v_sub_f32_e32 v132, v212, v218
	v_sub_f32_e32 v135, v215, v218
	v_sub_f32_e32 v134, v214, v218
	v_pk_fma_f32 v[134:135], v[134:135], v[138:139], v[98:99]
	v_pk_fma_f32 v[132:133], v[132:133], v[136:137], v[96:97]
	v_pk_mul_f32 v[134:135], v[134:135], s[16:17] op_sel_hi:[1,0]
	v_pk_mul_f32 v[132:133], v[132:133], s[16:17] op_sel_hi:[1,0]
	v_pk_fma_f32 v[130:131], v[130:131], 0.5, v[134:135] op_sel_hi:[1,0,1]
	v_pk_fma_f32 v[128:129], v[128:129], 0.5, v[132:133] op_sel_hi:[1,0,1]
	ds_bpermute_b32 v250, v238, v128
	ds_bpermute_b32 v251, v238, v129
	ds_bpermute_b32 v252, v238, v130
	ds_bpermute_b32 v253, v238, v131
	v_lshl_add_u64 v[244:245], v[144:145], 0, v[240:241]
	s_waitcnt lgkmcnt(0)
	global_store_dwordx4 v[244:245], v[250:253], off offset:576 sc1
	v_or_b32_e32 v144, 48, v172
	v_ashrrev_i32_e32 v145, 31, v144
	v_or_b32_e32 v128, 32, v172
	v_ashrrev_i32_e32 v129, 31, v128
	v_lshl_add_u64 v[130:131], v[128:129], 3, s[8:9]
	global_load_dwordx2 v[132:133], v[130:131], off
	v_lshl_add_u64 v[130:131], v[144:145], 3, s[8:9]
	global_load_dwordx2 v[146:147], v[130:131], off
	v_lshlrev_b64 v[184:185], 13, v[128:129]
	v_lshl_add_u64 v[140:141], v[170:171], 0, v[184:185]
	v_lshlrev_b64 v[190:191], 13, v[144:145]
	v_lshl_add_u64 v[156:157], v[170:171], 0, v[190:191]
	s_waitcnt vmcnt(1)
	v_pk_mul_f32 v[186:187], v[132:133], s[14:15] op_sel_hi:[1,0]
	s_nop 0
	v_fma_f32 v132, -v186, v186, v187
	v_max_f32_e32 v132, 0, v132
	v_add_f32_e32 v132, 0x3727c5ac, v132
	v_mul_f32_e32 v133, 0x4f800000, v132
	v_cmp_gt_f32_e32 vcc, s44, v132
	s_nop 1
	v_cndmask_b32_e32 v136, v132, v133, vcc
	v_sqrt_f32_e32 v137, v136
	s_nop 0
	v_add_u32_e32 v132, -1, v137
	v_fma_f32 v133, -v132, v137, v136
	v_cmp_ge_f32_e64 s[0:1], 0, v133
	v_add_u32_e32 v139, 1, v137
	s_nop 0
	v_cndmask_b32_e64 v138, v137, v132, s[0:1]
	v_fma_f32 v137, -v139, v137, v136
	v_cmp_lt_f32_e64 s[0:1], 0, v137
	global_load_dwordx4 v[132:135], v[140:141], off offset:64
	s_waitcnt vmcnt(1)
	v_pk_mul_f32 v[188:189], v[146:147], s[14:15] op_sel_hi:[1,0]
	v_cndmask_b32_e64 v137, v138, v139, s[0:1]
	v_mul_f32_e32 v138, 0x37800000, v137
	v_cndmask_b32_e32 v137, v137, v138, vcc
	v_cmp_class_f32_e32 vcc, v136, v182
	v_fma_f32 v146, -v188, v188, v189
	v_max_f32_e32 v146, 0, v146
	v_cndmask_b32_e32 v148, v137, v136, vcc
	v_div_scale_f32 v149, s[0:1], v148, v148, 1.0
	v_rcp_f32_e32 v150, v149
	global_load_dwordx4 v[128:131], v[140:141], off
	v_add_f32_e32 v146, 0x3727c5ac, v146
	v_mul_f32_e32 v147, 0x4f800000, v146
	v_cmp_gt_f32_e64 s[0:1], s44, v146
	v_fma_f32 v151, -v149, v150, 1.0
	v_fmac_f32_e32 v150, v151, v150
	v_cndmask_b32_e64 v153, v146, v147, s[0:1]
	v_sqrt_f32_e32 v146, v153
	v_div_scale_f32 v151, vcc, 1.0, v148, 1.0
	v_mul_f32_e32 v152, v151, v150
	v_fma_f32 v147, -v149, v152, v151
	v_fmac_f32_e32 v152, v147, v150
	v_add_u32_e32 v147, -1, v146
	v_fma_f32 v149, -v149, v152, v151
	v_fma_f32 v151, -v147, v146, v153
	v_add_u32_e32 v154, 1, v146
	global_load_dwordx4 v[136:139], v[140:141], off offset:576
	s_nop 0
	global_load_dwordx4 v[140:143], v[140:141], off offset:512
	v_cmp_ge_f32_e64 s[4:5], 0, v151
	v_fma_f32 v155, -v154, v146, v153
	v_div_fmas_f32 v149, v149, v150, v152
	v_cndmask_b32_e64 v151, v146, v147, s[4:5]
	v_cmp_lt_f32_e64 s[4:5], 0, v155
	global_load_dwordx4 v[144:147], v[156:157], off
	v_div_fixup_f32 v192, v149, v148, 1.0
	v_cndmask_b32_e64 v151, v151, v154, s[4:5]
	v_mul_f32_e32 v154, 0x37800000, v151
	v_cndmask_b32_e64 v151, v151, v154, s[0:1]
	v_cmp_class_f32_e64 s[0:1], v153, v182
	v_pk_mul_f32 v[196:197], v[124:125], v[192:193] op_sel_hi:[1,0]
	v_pk_mul_f32 v[198:199], v[126:127], v[192:193] op_sel_hi:[1,0]
	v_cndmask_b32_e64 v153, v151, v153, s[0:1]
	v_div_scale_f32 v154, s[0:1], v153, v153, 1.0
	v_rcp_f32_e32 v155, v154
	v_div_scale_f32 v152, vcc, 1.0, v153, 1.0
	v_fma_f32 v148, -v154, v155, 1.0
	v_fmac_f32_e32 v155, v148, v155
	global_load_dwordx4 v[148:151], v[156:157], off offset:64
	v_mul_f32_e32 v158, v152, v155
	v_fma_f32 v159, -v154, v158, v152
	v_fmac_f32_e32 v158, v159, v155
	v_fma_f32 v152, -v154, v158, v152
	v_div_fmas_f32 v152, v152, v155, v158
	v_div_fixup_f32 v194, v152, v153, 1.0
	global_load_dwordx4 v[152:155], v[156:157], off offset:512
	s_nop 0
	global_load_dwordx4 v[156:159], v[156:157], off offset:576
	s_waitcnt vmcnt(6)
	v_sub_f32_e32 v129, v129, v186
	v_sub_f32_e32 v128, v128, v186
	v_sub_f32_e32 v131, v131, v186
	v_sub_f32_e32 v130, v130, v186
	v_pk_fma_f32 v[128:129], v[128:129], v[196:197], v[120:121]
	v_pk_fma_f32 v[130:131], v[130:131], v[198:199], v[122:123]
	v_pk_mul_f32 v[128:129], v[128:129], s[16:17] op_sel_hi:[1,0]
	v_pk_mul_f32 v[130:131], v[130:131], s[16:17] op_sel_hi:[1,0]
	v_pk_fma_f32 v[92:93], v[92:93], 0.5, v[128:129] op_sel_hi:[1,0,1]
	v_lshl_add_u64 v[128:129], s[38:39], 0, v[184:185]
	v_pk_fma_f32 v[94:95], v[94:95], 0.5, v[130:131] op_sel_hi:[1,0,1]
	v_lshl_add_u64 v[128:129], v[128:129], 0, v[168:169]
	ds_bpermute_b32 v246, v238, v92
	ds_bpermute_b32 v247, v238, v93
	ds_bpermute_b32 v248, v238, v94
	ds_bpermute_b32 v249, v238, v95
	v_lshl_add_u64 v[244:245], v[128:129], 0, v[240:241]
	s_waitcnt lgkmcnt(0)
;     __device__ __forceinline__ void operator()(const f32x4 (&acc)[2][2][4][2], const Unit& u, int wr, int wc, int fr, int fq) const {
;     ...
;                 for (int mm = 0; mm < 2; ++mm) {
;                     const int r = row0 + ai * HALF + (2 * m2 + mm) * 16;
;                     float ps = 0.f, pq = 0.f;
; #pragma unroll
;                     for (int bj = 0; bj < 2; ++bj)
; #pragma unroll
;                         for (int n = 0; n < 2; ++n) {
;                             const f32x4 x = (xv[mm][bj][n] - st[mm][0]) * (gg[bj][n] * st[mm][1]) + bb[bj][n];
;                             const f32x4 o = x * alpha + acc[ai][bj][2 * m2 + mm][n] * scale;
;                             const size_t off = (size_t)r * D + col0 + bj * HALF + n * 16;
;                             *(f32x4*)(Y + off) = o;
	global_store_dwordx4 v[244:245], v[246:249], off sc1
	v_pk_mul_f32 v[130:131], v[116:117], v[192:193] op_sel_hi:[1,0]
	s_nop 0
	v_sub_f32_e32 v93, v133, v186
	v_sub_f32_e32 v92, v132, v186
	v_sub_f32_e32 v95, v135, v186
	v_sub_f32_e32 v94, v134, v186
	v_pk_mul_f32 v[132:133], v[118:119], v[192:193] op_sel_hi:[1,0]
	v_pk_fma_f32 v[92:93], v[92:93], v[130:131], v[112:113]
	v_pk_fma_f32 v[94:95], v[94:95], v[132:133], v[114:115]
	v_pk_mul_f32 v[92:93], v[92:93], s[16:17] op_sel_hi:[1,0]
	v_pk_mul_f32 v[94:95], v[94:95], s[16:17] op_sel_hi:[1,0]
	v_pk_fma_f32 v[88:89], v[88:89], 0.5, v[92:93] op_sel_hi:[1,0,1]
	v_pk_fma_f32 v[90:91], v[90:91], 0.5, v[94:95] op_sel_hi:[1,0,1]
	ds_bpermute_b32 v250, v238, v88
	ds_bpermute_b32 v251, v238, v89
	ds_bpermute_b32 v252, v238, v90
	ds_bpermute_b32 v253, v238, v91
	v_lshl_add_u64 v[244:245], v[128:129], 0, v[240:241]
	s_waitcnt lgkmcnt(0)
	global_store_dwordx4 v[244:245], v[250:253], off offset:64 sc1
	v_pk_mul_f32 v[92:93], v[108:109], v[192:193] op_sel_hi:[1,0]
	v_pk_mul_f32 v[94:95], v[110:111], v[192:193] op_sel_hi:[1,0]
	s_waitcnt vmcnt(6)
	v_sub_f32_e32 v89, v141, v186
	v_sub_f32_e32 v88, v140, v186
	v_sub_f32_e32 v91, v143, v186
	v_sub_f32_e32 v90, v142, v186
	v_pk_fma_f32 v[90:91], v[90:91], v[94:95], v[106:107]
	v_pk_fma_f32 v[88:89], v[88:89], v[92:93], v[104:105]
	v_pk_mul_f32 v[90:91], v[90:91], s[16:17] op_sel_hi:[1,0]
	v_pk_mul_f32 v[88:89], v[88:89], s[16:17] op_sel_hi:[1,0]
	v_pk_fma_f32 v[86:87], v[86:87], 0.5, v[90:91] op_sel_hi:[1,0,1]
	v_pk_fma_f32 v[84:85], v[84:85], 0.5, v[88:89] op_sel_hi:[1,0,1]
	ds_bpermute_b32 v246, v238, v84
	ds_bpermute_b32 v247, v238, v85
	ds_bpermute_b32 v248, v238, v86
	ds_bpermute_b32 v249, v238, v87
	v_lshl_add_u64 v[244:245], v[128:129], 0, v[240:241]
	s_waitcnt lgkmcnt(0)
	global_store_dwordx4 v[244:245], v[246:249], off offset:512 sc1
	v_pk_mul_f32 v[88:89], v[100:101], v[192:193] op_sel_hi:[1,0]
	v_pk_mul_f32 v[90:91], v[102:103], v[192:193] op_sel_hi:[1,0]
	v_sub_f32_e32 v85, v137, v186
	v_sub_f32_e32 v84, v136, v186
	v_sub_f32_e32 v87, v139, v186
	v_sub_f32_e32 v86, v138, v186
	v_pk_fma_f32 v[86:87], v[86:87], v[90:91], v[98:99]
	v_pk_fma_f32 v[84:85], v[84:85], v[88:89], v[96:97]
	v_pk_mul_f32 v[86:87], v[86:87], s[16:17] op_sel_hi:[1,0]
	v_pk_mul_f32 v[84:85], v[84:85], s[16:17] op_sel_hi:[1,0]
	v_pk_fma_f32 v[78:79], v[78:79], 0.5, v[86:87] op_sel_hi:[1,0,1]
	v_pk_fma_f32 v[76:77], v[76:77], 0.5, v[84:85] op_sel_hi:[1,0,1]
	ds_bpermute_b32 v250, v238, v76
	ds_bpermute_b32 v251, v238, v77
	ds_bpermute_b32 v252, v238, v78
	ds_bpermute_b32 v253, v238, v79
	v_lshl_add_u64 v[244:245], v[128:129], 0, v[240:241]
	s_waitcnt lgkmcnt(0)
	global_store_dwordx4 v[244:245], v[250:253], off offset:576 sc1
	v_pk_mul_f32 v[84:85], v[124:125], v[194:195] op_sel_hi:[1,0]
	v_pk_mul_f32 v[86:87], v[126:127], v[194:195] op_sel_hi:[1,0]
	s_waitcnt vmcnt(7)
	v_sub_f32_e32 v77, v145, v188
	v_sub_f32_e32 v76, v144, v188
	v_sub_f32_e32 v79, v147, v188
	v_sub_f32_e32 v78, v146, v188
	v_pk_fma_f32 v[76:77], v[76:77], v[84:85], v[120:121]
	v_pk_fma_f32 v[78:79], v[78:79], v[86:87], v[122:123]
	v_pk_mul_f32 v[76:77], v[76:77], s[16:17] op_sel_hi:[1,0]
	v_pk_mul_f32 v[78:79], v[78:79], s[16:17] op_sel_hi:[1,0]
	v_pk_fma_f32 v[76:77], v[80:81], 0.5, v[76:77] op_sel_hi:[1,0,1]
	v_lshl_add_u64 v[80:81], s[38:39], 0, v[190:191]
	v_pk_fma_f32 v[78:79], v[82:83], 0.5, v[78:79] op_sel_hi:[1,0,1]
	v_lshl_add_u64 v[80:81], v[80:81], 0, v[168:169]
	ds_bpermute_b32 v246, v238, v76
	ds_bpermute_b32 v247, v238, v77
	ds_bpermute_b32 v248, v238, v78
	ds_bpermute_b32 v249, v238, v79
	v_lshl_add_u64 v[244:245], v[80:81], 0, v[240:241]
	s_waitcnt lgkmcnt(0)
	global_store_dwordx4 v[244:245], v[246:249], off sc1
	v_pk_mul_f32 v[82:83], v[116:117], v[194:195] op_sel_hi:[1,0]
	v_pk_mul_f32 v[84:85], v[118:119], v[194:195] op_sel_hi:[1,0]
	s_waitcnt vmcnt(7)
	v_sub_f32_e32 v77, v149, v188
	v_sub_f32_e32 v76, v148, v188
	v_sub_f32_e32 v79, v151, v188
	v_sub_f32_e32 v78, v150, v188
	v_pk_fma_f32 v[78:79], v[78:79], v[84:85], v[114:115]
	v_pk_fma_f32 v[76:77], v[76:77], v[82:83], v[112:113]
	v_pk_mul_f32 v[78:79], v[78:79], s[16:17] op_sel_hi:[1,0]
	v_pk_mul_f32 v[76:77], v[76:77], s[16:17] op_sel_hi:[1,0]
	v_pk_fma_f32 v[74:75], v[74:75], 0.5, v[78:79] op_sel_hi:[1,0,1]
	v_pk_fma_f32 v[72:73], v[72:73], 0.5, v[76:77] op_sel_hi:[1,0,1]
	ds_bpermute_b32 v250, v238, v72
	ds_bpermute_b32 v251, v238, v73
	ds_bpermute_b32 v252, v238, v74
	ds_bpermute_b32 v253, v238, v75
	v_lshl_add_u64 v[244:245], v[80:81], 0, v[240:241]
	s_waitcnt lgkmcnt(0)
	global_store_dwordx4 v[244:245], v[250:253], off offset:64 sc1
	v_pk_mul_f32 v[76:77], v[108:109], v[194:195] op_sel_hi:[1,0]
	v_pk_mul_f32 v[78:79], v[110:111], v[194:195] op_sel_hi:[1,0]
	s_waitcnt vmcnt(7)
	v_sub_f32_e32 v73, v153, v188
	v_sub_f32_e32 v72, v152, v188
	v_sub_f32_e32 v75, v155, v188
	v_sub_f32_e32 v74, v154, v188
	v_pk_fma_f32 v[74:75], v[74:75], v[78:79], v[106:107]
	v_pk_fma_f32 v[72:73], v[72:73], v[76:77], v[104:105]
	v_pk_mul_f32 v[74:75], v[74:75], s[16:17] op_sel_hi:[1,0]
	v_pk_mul_f32 v[72:73], v[72:73], s[16:17] op_sel_hi:[1,0]
	v_pk_fma_f32 v[70:71], v[70:71], 0.5, v[74:75] op_sel_hi:[1,0,1]
	v_pk_fma_f32 v[68:69], v[68:69], 0.5, v[72:73] op_sel_hi:[1,0,1]
	ds_bpermute_b32 v246, v238, v68
	ds_bpermute_b32 v247, v238, v69
	ds_bpermute_b32 v248, v238, v70
	ds_bpermute_b32 v249, v238, v71
	v_lshl_add_u64 v[244:245], v[80:81], 0, v[240:241]
	s_waitcnt lgkmcnt(0)
	global_store_dwordx4 v[244:245], v[246:249], off offset:512 sc1
	v_pk_mul_f32 v[72:73], v[100:101], v[194:195] op_sel_hi:[1,0]
	v_pk_mul_f32 v[74:75], v[102:103], v[194:195] op_sel_hi:[1,0]
	s_waitcnt vmcnt(7)
; __device__ __forceinline__ f32x2 ln_stats(f32x2 sm) { const float mu = sm[0] * (1.f / D); const float var = fmaxf(sm[1] * (1.f / D) - mu * mu, 0.f); return (f32x2){mu, 1.0f / sqrtf(var + LN_EPS)}; }
;     __device__ __forceinline__ void operator()(const f32x4 (&acc)[2][2][4][2], const Unit& u, int wr, int wc, int fr, int fq) const {
;     ...
;                 f32x4 xv[2][2][2]; f32x2 st[2];
; #pragma unroll
;                 for (int mm = 0; mm < 2; ++mm) {
;                     const int r = row0 + ai * HALF + (2 * m2 + mm) * 16;
;                     st[mm] = (f32x2){0.f, 1.f};
;                     if (rin) st[mm] = ln_stats(*(const f32x2*)(rin + 2 * (size_t)r));
; #pragma unroll
;                     for (int bj = 0; bj < 2; ++bj)
; #pragma unroll
;                         for (int n = 0; n < 2; ++n) { const f32x4* rp = (const f32x4*)(res + (size_t)r * D + col0 + bj * HALF + n * 16); xv[mm][bj][n] = stream ? __builtin_nontemporal_load(rp) : *rp; }
;                 }
; #pragma unroll
;                 for (int mm = 0; mm < 2; ++mm) {
;                     const int r = row0 + ai * HALF + (2 * m2 + mm) * 16;
;                     float ps = 0.f, pq = 0.f;
; #pragma unroll
;                     for (int bj = 0; bj < 2; ++bj)
; #pragma unroll
;                         for (int n = 0; n < 2; ++n) {
;                             const f32x4 x = (xv[mm][bj][n] - st[mm][0]) * (gg[bj][n] * st[mm][1]) + bb[bj][n];
;                             const f32x4 o = x * alpha + acc[ai][bj][2 * m2 + mm][n] * scale;
;                             const size_t off = (size_t)r * D + col0 + bj * HALF + n * 16;
;                             *(f32x4*)(Y + off) = o;
	v_sub_f32_e32 v69, v157, v188
	v_sub_f32_e32 v68, v156, v188
	v_sub_f32_e32 v71, v159, v188
	v_sub_f32_e32 v70, v158, v188
	v_pk_fma_f32 v[70:71], v[70:71], v[74:75], v[98:99]
	v_pk_fma_f32 v[68:69], v[68:69], v[72:73], v[96:97]
	v_pk_mul_f32 v[70:71], v[70:71], s[16:17] op_sel_hi:[1,0]
	v_pk_mul_f32 v[68:69], v[68:69], s[16:17] op_sel_hi:[1,0]
	v_pk_fma_f32 v[66:67], v[66:67], 0.5, v[70:71] op_sel_hi:[1,0,1]
	v_pk_fma_f32 v[64:65], v[64:65], 0.5, v[68:69] op_sel_hi:[1,0,1]
	ds_bpermute_b32 v250, v238, v64
	ds_bpermute_b32 v251, v238, v65
	ds_bpermute_b32 v252, v238, v66
	ds_bpermute_b32 v253, v238, v67
	v_lshl_add_u64 v[244:245], v[80:81], 0, v[240:241]
	s_waitcnt lgkmcnt(0)
	global_store_dwordx4 v[244:245], v[250:253], off offset:576 sc1
	v_add_u32_e32 v80, 0x90, v172
	v_ashrrev_i32_e32 v81, 31, v80
	v_add_u32_e32 v64, 0x80, v172
	v_ashrrev_i32_e32 v65, 31, v64
	v_lshl_add_u64 v[66:67], v[64:65], 3, s[8:9]
	global_load_dwordx2 v[68:69], v[66:67], off
	v_lshl_add_u64 v[66:67], v[80:81], 3, s[8:9]
	global_load_dwordx2 v[82:83], v[66:67], off
	v_lshlrev_b64 v[128:129], 13, v[64:65]
	v_lshl_add_u64 v[76:77], v[170:171], 0, v[128:129]
	v_lshlrev_b64 v[134:135], 13, v[80:81]
	v_lshl_add_u64 v[92:93], v[170:171], 0, v[134:135]
	s_waitcnt vmcnt(1)
	v_pk_mul_f32 v[130:131], v[68:69], s[14:15] op_sel_hi:[1,0]
	s_nop 0
	v_fma_f32 v68, -v130, v130, v131
	v_max_f32_e32 v68, 0, v68
	v_add_f32_e32 v68, 0x3727c5ac, v68
	v_mul_f32_e32 v69, 0x4f800000, v68
	v_cmp_gt_f32_e32 vcc, s44, v68
	s_nop 1
	v_cndmask_b32_e32 v72, v68, v69, vcc
	v_sqrt_f32_e32 v73, v72
	s_nop 0
	v_add_u32_e32 v68, -1, v73
	v_fma_f32 v69, -v68, v73, v72
	v_cmp_ge_f32_e64 s[0:1], 0, v69
	v_add_u32_e32 v75, 1, v73
	s_nop 0
	v_cndmask_b32_e64 v74, v73, v68, s[0:1]
	v_fma_f32 v73, -v75, v73, v72
	v_cmp_lt_f32_e64 s[0:1], 0, v73
	global_load_dwordx4 v[68:71], v[76:77], off offset:64
	s_waitcnt vmcnt(1)
	v_pk_mul_f32 v[132:133], v[82:83], s[14:15] op_sel_hi:[1,0]
	v_cndmask_b32_e64 v73, v74, v75, s[0:1]
	v_mul_f32_e32 v74, 0x37800000, v73
	v_cndmask_b32_e32 v73, v73, v74, vcc
	v_cmp_class_f32_e32 vcc, v72, v182
	v_fma_f32 v82, -v132, v132, v133
	v_max_f32_e32 v82, 0, v82
	v_cndmask_b32_e32 v84, v73, v72, vcc
	v_div_scale_f32 v85, s[0:1], v84, v84, 1.0
	v_rcp_f32_e32 v86, v85
	global_load_dwordx4 v[64:67], v[76:77], off
	v_add_f32_e32 v82, 0x3727c5ac, v82
	v_mul_f32_e32 v83, 0x4f800000, v82
	v_cmp_gt_f32_e64 s[0:1], s44, v82
	v_fma_f32 v87, -v85, v86, 1.0
	v_fmac_f32_e32 v86, v87, v86
	v_cndmask_b32_e64 v89, v82, v83, s[0:1]
	v_sqrt_f32_e32 v82, v89
	v_div_scale_f32 v87, vcc, 1.0, v84, 1.0
	v_mul_f32_e32 v88, v87, v86
	v_fma_f32 v83, -v85, v88, v87
	v_fmac_f32_e32 v88, v83, v86
	v_add_u32_e32 v83, -1, v82
	v_fma_f32 v85, -v85, v88, v87
	v_fma_f32 v87, -v83, v82, v89
	v_add_u32_e32 v90, 1, v82
	global_load_dwordx4 v[72:75], v[76:77], off offset:576
	s_nop 0
	global_load_dwordx4 v[76:79], v[76:77], off offset:512
	v_cmp_ge_f32_e64 s[4:5], 0, v87
	v_fma_f32 v91, -v90, v82, v89
	v_div_fmas_f32 v85, v85, v86, v88
	v_cndmask_b32_e64 v87, v82, v83, s[4:5]
	v_cmp_lt_f32_e64 s[4:5], 0, v91
	global_load_dwordx4 v[80:83], v[92:93], off
	v_div_fixup_f32 v136, v85, v84, 1.0
	v_cndmask_b32_e64 v87, v87, v90, s[4:5]
	v_mul_f32_e32 v90, 0x37800000, v87
	v_cndmask_b32_e64 v87, v87, v90, s[0:1]
	v_cmp_class_f32_e64 s[0:1], v89, v182
	v_pk_mul_f32 v[140:141], v[124:125], v[136:137] op_sel_hi:[1,0]
	v_pk_mul_f32 v[142:143], v[126:127], v[136:137] op_sel_hi:[1,0]
	v_cndmask_b32_e64 v89, v87, v89, s[0:1]
	v_div_scale_f32 v90, s[0:1], v89, v89, 1.0
	v_rcp_f32_e32 v91, v90
	v_div_scale_f32 v88, vcc, 1.0, v89, 1.0
	v_fma_f32 v84, -v90, v91, 1.0
	v_fmac_f32_e32 v91, v84, v91
	global_load_dwordx4 v[84:87], v[92:93], off offset:64
	v_mul_f32_e32 v94, v88, v91
	v_fma_f32 v95, -v90, v94, v88
	v_fmac_f32_e32 v94, v95, v91
	v_fma_f32 v88, -v90, v94, v88
	v_div_fmas_f32 v88, v88, v91, v94
	v_div_fixup_f32 v138, v88, v89, 1.0
	global_load_dwordx4 v[88:91], v[92:93], off offset:512
	s_nop 0
	global_load_dwordx4 v[92:95], v[92:93], off offset:576
	s_waitcnt vmcnt(6)
	v_sub_f32_e32 v65, v65, v130
	v_sub_f32_e32 v64, v64, v130
	v_sub_f32_e32 v67, v67, v130
	v_sub_f32_e32 v66, v66, v130
	v_pk_fma_f32 v[64:65], v[64:65], v[140:141], v[120:121]
	v_pk_fma_f32 v[66:67], v[66:67], v[142:143], v[122:123]
	v_pk_mul_f32 v[64:65], v[64:65], s[16:17] op_sel_hi:[1,0]
	v_pk_mul_f32 v[66:67], v[66:67], s[16:17] op_sel_hi:[1,0]
	v_pk_fma_f32 v[60:61], v[60:61], 0.5, v[64:65] op_sel_hi:[1,0,1]
	v_lshl_add_u64 v[64:65], s[38:39], 0, v[128:129]
	v_pk_fma_f32 v[62:63], v[62:63], 0.5, v[66:67] op_sel_hi:[1,0,1]
	v_lshl_add_u64 v[64:65], v[64:65], 0, v[168:169]
	ds_bpermute_b32 v246, v238, v60
	ds_bpermute_b32 v247, v238, v61
	ds_bpermute_b32 v248, v238, v62
	ds_bpermute_b32 v249, v238, v63
	v_lshl_add_u64 v[244:245], v[64:65], 0, v[240:241]
	s_waitcnt lgkmcnt(0)
	global_store_dwordx4 v[244:245], v[246:249], off sc1
	v_pk_mul_f32 v[66:67], v[116:117], v[136:137] op_sel_hi:[1,0]
	s_nop 0
	v_sub_f32_e32 v61, v69, v130
	v_sub_f32_e32 v60, v68, v130
	v_sub_f32_e32 v63, v71, v130
	v_sub_f32_e32 v62, v70, v130
	v_pk_mul_f32 v[68:69], v[118:119], v[136:137] op_sel_hi:[1,0]
	v_pk_fma_f32 v[60:61], v[60:61], v[66:67], v[112:113]
	v_pk_fma_f32 v[62:63], v[62:63], v[68:69], v[114:115]
	v_pk_mul_f32 v[60:61], v[60:61], s[16:17] op_sel_hi:[1,0]
	v_pk_mul_f32 v[62:63], v[62:63], s[16:17] op_sel_hi:[1,0]
	v_pk_fma_f32 v[56:57], v[56:57], 0.5, v[60:61] op_sel_hi:[1,0,1]
	v_pk_fma_f32 v[58:59], v[58:59], 0.5, v[62:63] op_sel_hi:[1,0,1]
	ds_bpermute_b32 v250, v238, v56
	ds_bpermute_b32 v251, v238, v57
	ds_bpermute_b32 v252, v238, v58
	ds_bpermute_b32 v253, v238, v59
	v_lshl_add_u64 v[244:245], v[64:65], 0, v[240:241]
	s_waitcnt lgkmcnt(0)
;     __device__ __forceinline__ void operator()(const f32x4 (&acc)[2][2][4][2], const Unit& u, int wr, int wc, int fr, int fq) const {
;     ...
;                 for (int mm = 0; mm < 2; ++mm) {
;                     const int r = row0 + ai * HALF + (2 * m2 + mm) * 16;
;                     float ps = 0.f, pq = 0.f;
; #pragma unroll
;                     for (int bj = 0; bj < 2; ++bj)
; #pragma unroll
;                         for (int n = 0; n < 2; ++n) {
;                             const f32x4 x = (xv[mm][bj][n] - st[mm][0]) * (gg[bj][n] * st[mm][1]) + bb[bj][n];
;                             const f32x4 o = x * alpha + acc[ai][bj][2 * m2 + mm][n] * scale;
;                             const size_t off = (size_t)r * D + col0 + bj * HALF + n * 16;
;                             *(f32x4*)(Y + off) = o;
	global_store_dwordx4 v[244:245], v[250:253], off offset:64 sc1
	v_pk_mul_f32 v[60:61], v[108:109], v[136:137] op_sel_hi:[1,0]
	v_pk_mul_f32 v[62:63], v[110:111], v[136:137] op_sel_hi:[1,0]
	s_waitcnt vmcnt(6)
	v_sub_f32_e32 v57, v77, v130
	v_sub_f32_e32 v56, v76, v130
	v_sub_f32_e32 v59, v79, v130
	v_sub_f32_e32 v58, v78, v130
	v_pk_fma_f32 v[58:59], v[58:59], v[62:63], v[106:107]
	v_pk_fma_f32 v[56:57], v[56:57], v[60:61], v[104:105]
	v_pk_mul_f32 v[58:59], v[58:59], s[16:17] op_sel_hi:[1,0]
	v_pk_mul_f32 v[56:57], v[56:57], s[16:17] op_sel_hi:[1,0]
	v_pk_fma_f32 v[54:55], v[54:55], 0.5, v[58:59] op_sel_hi:[1,0,1]
	v_pk_fma_f32 v[52:53], v[52:53], 0.5, v[56:57] op_sel_hi:[1,0,1]
	ds_bpermute_b32 v246, v238, v52
	ds_bpermute_b32 v247, v238, v53
	ds_bpermute_b32 v248, v238, v54
	ds_bpermute_b32 v249, v238, v55
	v_lshl_add_u64 v[244:245], v[64:65], 0, v[240:241]
	s_waitcnt lgkmcnt(0)
	global_store_dwordx4 v[244:245], v[246:249], off offset:512 sc1
	v_pk_mul_f32 v[56:57], v[100:101], v[136:137] op_sel_hi:[1,0]
	v_pk_mul_f32 v[58:59], v[102:103], v[136:137] op_sel_hi:[1,0]
	v_sub_f32_e32 v53, v73, v130
	v_sub_f32_e32 v52, v72, v130
	v_sub_f32_e32 v55, v75, v130
	v_sub_f32_e32 v54, v74, v130
	v_pk_fma_f32 v[54:55], v[54:55], v[58:59], v[98:99]
	v_pk_fma_f32 v[52:53], v[52:53], v[56:57], v[96:97]
	v_pk_mul_f32 v[54:55], v[54:55], s[16:17] op_sel_hi:[1,0]
	v_pk_mul_f32 v[52:53], v[52:53], s[16:17] op_sel_hi:[1,0]
	v_pk_fma_f32 v[46:47], v[46:47], 0.5, v[54:55] op_sel_hi:[1,0,1]
	v_pk_fma_f32 v[44:45], v[44:45], 0.5, v[52:53] op_sel_hi:[1,0,1]
	ds_bpermute_b32 v250, v238, v44
	ds_bpermute_b32 v251, v238, v45
	ds_bpermute_b32 v252, v238, v46
	ds_bpermute_b32 v253, v238, v47
	v_lshl_add_u64 v[244:245], v[64:65], 0, v[240:241]
	s_waitcnt lgkmcnt(0)
	global_store_dwordx4 v[244:245], v[250:253], off offset:576 sc1
	v_pk_mul_f32 v[52:53], v[124:125], v[138:139] op_sel_hi:[1,0]
	v_pk_mul_f32 v[54:55], v[126:127], v[138:139] op_sel_hi:[1,0]
	s_waitcnt vmcnt(7)
	v_sub_f32_e32 v45, v81, v132
	v_sub_f32_e32 v44, v80, v132
	v_sub_f32_e32 v47, v83, v132
	v_sub_f32_e32 v46, v82, v132
	v_pk_fma_f32 v[44:45], v[44:45], v[52:53], v[120:121]
	v_pk_fma_f32 v[46:47], v[46:47], v[54:55], v[122:123]
	v_pk_mul_f32 v[44:45], v[44:45], s[16:17] op_sel_hi:[1,0]
	v_pk_mul_f32 v[46:47], v[46:47], s[16:17] op_sel_hi:[1,0]
	v_pk_fma_f32 v[44:45], v[48:49], 0.5, v[44:45] op_sel_hi:[1,0,1]
	v_lshl_add_u64 v[48:49], s[38:39], 0, v[134:135]
	v_pk_fma_f32 v[46:47], v[50:51], 0.5, v[46:47] op_sel_hi:[1,0,1]
	v_lshl_add_u64 v[48:49], v[48:49], 0, v[168:169]
	ds_bpermute_b32 v246, v238, v44
	ds_bpermute_b32 v247, v238, v45
	ds_bpermute_b32 v248, v238, v46
	ds_bpermute_b32 v249, v238, v47
	v_lshl_add_u64 v[244:245], v[48:49], 0, v[240:241]
	s_waitcnt lgkmcnt(0)
	global_store_dwordx4 v[244:245], v[246:249], off sc1
	v_pk_mul_f32 v[50:51], v[116:117], v[138:139] op_sel_hi:[1,0]
	v_pk_mul_f32 v[52:53], v[118:119], v[138:139] op_sel_hi:[1,0]
	s_waitcnt vmcnt(7)
	v_sub_f32_e32 v45, v85, v132
	v_sub_f32_e32 v44, v84, v132
	v_sub_f32_e32 v47, v87, v132
	v_sub_f32_e32 v46, v86, v132
	v_pk_fma_f32 v[46:47], v[46:47], v[52:53], v[114:115]
	v_pk_fma_f32 v[44:45], v[44:45], v[50:51], v[112:113]
	v_pk_mul_f32 v[46:47], v[46:47], s[16:17] op_sel_hi:[1,0]
	v_pk_mul_f32 v[44:45], v[44:45], s[16:17] op_sel_hi:[1,0]
	v_pk_fma_f32 v[42:43], v[42:43], 0.5, v[46:47] op_sel_hi:[1,0,1]
	v_pk_fma_f32 v[40:41], v[40:41], 0.5, v[44:45] op_sel_hi:[1,0,1]
	ds_bpermute_b32 v250, v238, v40
	ds_bpermute_b32 v251, v238, v41
	ds_bpermute_b32 v252, v238, v42
	ds_bpermute_b32 v253, v238, v43
	v_lshl_add_u64 v[244:245], v[48:49], 0, v[240:241]
	s_waitcnt lgkmcnt(0)
	global_store_dwordx4 v[244:245], v[250:253], off offset:64 sc1
	v_pk_mul_f32 v[44:45], v[108:109], v[138:139] op_sel_hi:[1,0]
	v_pk_mul_f32 v[46:47], v[110:111], v[138:139] op_sel_hi:[1,0]
	s_waitcnt vmcnt(7)
	v_sub_f32_e32 v41, v89, v132
	v_sub_f32_e32 v40, v88, v132
	v_sub_f32_e32 v43, v91, v132
	v_sub_f32_e32 v42, v90, v132
	v_pk_fma_f32 v[42:43], v[42:43], v[46:47], v[106:107]
	v_pk_fma_f32 v[40:41], v[40:41], v[44:45], v[104:105]
	v_pk_mul_f32 v[42:43], v[42:43], s[16:17] op_sel_hi:[1,0]
	v_pk_mul_f32 v[40:41], v[40:41], s[16:17] op_sel_hi:[1,0]
	v_pk_fma_f32 v[38:39], v[38:39], 0.5, v[42:43] op_sel_hi:[1,0,1]
	v_pk_fma_f32 v[36:37], v[36:37], 0.5, v[40:41] op_sel_hi:[1,0,1]
	ds_bpermute_b32 v246, v238, v36
	ds_bpermute_b32 v247, v238, v37
	ds_bpermute_b32 v248, v238, v38
	ds_bpermute_b32 v249, v238, v39
	v_lshl_add_u64 v[244:245], v[48:49], 0, v[240:241]
	s_waitcnt lgkmcnt(0)
	global_store_dwordx4 v[244:245], v[246:249], off offset:512 sc1
	v_pk_mul_f32 v[40:41], v[100:101], v[138:139] op_sel_hi:[1,0]
	v_pk_mul_f32 v[42:43], v[102:103], v[138:139] op_sel_hi:[1,0]
	s_waitcnt vmcnt(7)
	v_sub_f32_e32 v37, v93, v132
	v_sub_f32_e32 v36, v92, v132
	v_sub_f32_e32 v39, v95, v132
	v_sub_f32_e32 v38, v94, v132
	v_pk_fma_f32 v[38:39], v[38:39], v[42:43], v[98:99]
	v_pk_fma_f32 v[36:37], v[36:37], v[40:41], v[96:97]
	v_pk_mul_f32 v[38:39], v[38:39], s[16:17] op_sel_hi:[1,0]
	v_pk_mul_f32 v[36:37], v[36:37], s[16:17] op_sel_hi:[1,0]
	v_pk_fma_f32 v[34:35], v[34:35], 0.5, v[38:39] op_sel_hi:[1,0,1]
	v_pk_fma_f32 v[32:33], v[32:33], 0.5, v[36:37] op_sel_hi:[1,0,1]
	ds_bpermute_b32 v250, v238, v32
	ds_bpermute_b32 v251, v238, v33
	ds_bpermute_b32 v252, v238, v34
	ds_bpermute_b32 v253, v238, v35
	v_lshl_add_u64 v[244:245], v[48:49], 0, v[240:241]
	s_waitcnt lgkmcnt(0)
; __device__ __forceinline__ f32x2 ln_stats(f32x2 sm) { const float mu = sm[0] * (1.f / D); const float var = fmaxf(sm[1] * (1.f / D) - mu * mu, 0.f); return (f32x2){mu, 1.0f / sqrtf(var + LN_EPS)}; }
;     __device__ __forceinline__ void operator()(const f32x4 (&acc)[2][2][4][2], const Unit& u, int wr, int wc, int fr, int fq) const {
;     ...
;                 f32x4 xv[2][2][2]; f32x2 st[2];
; #pragma unroll
;                 for (int mm = 0; mm < 2; ++mm) {
;                     const int r = row0 + ai * HALF + (2 * m2 + mm) * 16;
;                     st[mm] = (f32x2){0.f, 1.f};
;                     if (rin) st[mm] = ln_stats(*(const f32x2*)(rin + 2 * (size_t)r));
; #pragma unroll
;                     for (int bj = 0; bj < 2; ++bj)
; #pragma unroll
;                         for (int n = 0; n < 2; ++n) { const f32x4* rp = (const f32x4*)(res + (size_t)r * D + col0 + bj * HALF + n * 16); xv[mm][bj][n] = stream ? __builtin_nontemporal_load(rp) : *rp; }
;                 }
; #pragma unroll
;                 for (int mm = 0; mm < 2; ++mm) {
;                     const int r = row0 + ai * HALF + (2 * m2 + mm) * 16;
;                     float ps = 0.f, pq = 0.f;
; #pragma unroll
;                     for (int bj = 0; bj < 2; ++bj)
; #pragma unroll
;                         for (int n = 0; n < 2; ++n) {
;                             const f32x4 x = (xv[mm][bj][n] - st[mm][0]) * (gg[bj][n] * st[mm][1]) + bb[bj][n];
;                             const f32x4 o = x * alpha + acc[ai][bj][2 * m2 + mm][n] * scale;
;                             const size_t off = (size_t)r * D + col0 + bj * HALF + n * 16;
;                             *(f32x4*)(Y + off) = o;
	global_store_dwordx4 v[244:245], v[250:253], off offset:576 sc1
	v_add_u32_e32 v48, 0xb0, v172
	v_ashrrev_i32_e32 v49, 31, v48
	v_add_u32_e32 v32, 0xa0, v172
	v_ashrrev_i32_e32 v33, 31, v32
	v_lshl_add_u64 v[34:35], v[32:33], 3, s[8:9]
	global_load_dwordx2 v[36:37], v[34:35], off
	v_lshl_add_u64 v[34:35], v[48:49], 3, s[8:9]
	global_load_dwordx2 v[50:51], v[34:35], off
	v_lshlrev_b64 v[64:65], 13, v[32:33]
	v_lshl_add_u64 v[44:45], v[170:171], 0, v[64:65]
	v_lshlrev_b64 v[70:71], 13, v[48:49]
	v_lshl_add_u64 v[60:61], v[170:171], 0, v[70:71]
	s_waitcnt vmcnt(1)
	v_pk_mul_f32 v[66:67], v[36:37], s[14:15] op_sel_hi:[1,0]
	s_nop 0
	v_fma_f32 v36, -v66, v66, v67
	v_max_f32_e32 v36, 0, v36
	v_add_f32_e32 v36, 0x3727c5ac, v36
	v_mul_f32_e32 v37, 0x4f800000, v36
	v_cmp_gt_f32_e32 vcc, s44, v36
	s_nop 1
	v_cndmask_b32_e32 v40, v36, v37, vcc
	v_sqrt_f32_e32 v41, v40
	s_nop 0
	v_add_u32_e32 v36, -1, v41
	v_fma_f32 v37, -v36, v41, v40
	v_cmp_ge_f32_e64 s[0:1], 0, v37
	v_add_u32_e32 v43, 1, v41
	s_nop 0
	v_cndmask_b32_e64 v42, v41, v36, s[0:1]
	v_fma_f32 v41, -v43, v41, v40
	v_cmp_lt_f32_e64 s[0:1], 0, v41
	global_load_dwordx4 v[36:39], v[44:45], off offset:64
	s_waitcnt vmcnt(1)
	v_pk_mul_f32 v[68:69], v[50:51], s[14:15] op_sel_hi:[1,0]
	v_cndmask_b32_e64 v41, v42, v43, s[0:1]
	v_mul_f32_e32 v42, 0x37800000, v41
	v_cndmask_b32_e32 v41, v41, v42, vcc
	v_cmp_class_f32_e32 vcc, v40, v182
	v_fma_f32 v50, -v68, v68, v69
	v_max_f32_e32 v50, 0, v50
	v_cndmask_b32_e32 v52, v41, v40, vcc
	v_div_scale_f32 v53, s[0:1], v52, v52, 1.0
	v_rcp_f32_e32 v54, v53
	global_load_dwordx4 v[32:35], v[44:45], off
	v_add_f32_e32 v50, 0x3727c5ac, v50
	v_mul_f32_e32 v51, 0x4f800000, v50
	v_cmp_gt_f32_e64 s[0:1], s44, v50
	v_fma_f32 v55, -v53, v54, 1.0
	v_fmac_f32_e32 v54, v55, v54
	v_cndmask_b32_e64 v57, v50, v51, s[0:1]
	v_sqrt_f32_e32 v50, v57
	v_div_scale_f32 v55, vcc, 1.0, v52, 1.0
	v_mul_f32_e32 v56, v55, v54
	v_fma_f32 v51, -v53, v56, v55
	v_fmac_f32_e32 v56, v51, v54
	v_add_u32_e32 v51, -1, v50
	v_fma_f32 v53, -v53, v56, v55
	v_fma_f32 v55, -v51, v50, v57
	v_add_u32_e32 v58, 1, v50
	global_load_dwordx4 v[40:43], v[44:45], off offset:576
	s_nop 0
	global_load_dwordx4 v[44:47], v[44:45], off offset:512
	v_cmp_ge_f32_e64 s[4:5], 0, v55
	v_fma_f32 v59, -v58, v50, v57
	v_div_fmas_f32 v53, v53, v54, v56
	v_cndmask_b32_e64 v55, v50, v51, s[4:5]
	v_cmp_lt_f32_e64 s[4:5], 0, v59
	global_load_dwordx4 v[48:51], v[60:61], off
	v_div_fixup_f32 v72, v53, v52, 1.0
	v_cndmask_b32_e64 v55, v55, v58, s[4:5]
	v_mul_f32_e32 v58, 0x37800000, v55
	v_cndmask_b32_e64 v55, v55, v58, s[0:1]
	v_cmp_class_f32_e64 s[0:1], v57, v182
	v_pk_mul_f32 v[76:77], v[124:125], v[72:73] op_sel_hi:[1,0]
	v_pk_mul_f32 v[78:79], v[126:127], v[72:73] op_sel_hi:[1,0]
	v_cndmask_b32_e64 v57, v55, v57, s[0:1]
	v_div_scale_f32 v58, s[0:1], v57, v57, 1.0
	v_rcp_f32_e32 v59, v58
	v_div_scale_f32 v56, vcc, 1.0, v57, 1.0
	s_mov_b64 s[0:1], -1
	v_fma_f32 v52, -v58, v59, 1.0
	v_fmac_f32_e32 v59, v52, v59
	global_load_dwordx4 v[52:55], v[60:61], off offset:64
	v_mul_f32_e32 v62, v56, v59
	v_fma_f32 v63, -v58, v62, v56
	v_fmac_f32_e32 v62, v63, v59
	v_fma_f32 v56, -v58, v62, v56
	v_div_fmas_f32 v56, v56, v59, v62
	v_div_fixup_f32 v74, v56, v57, 1.0
	global_load_dwordx4 v[56:59], v[60:61], off offset:512
	s_nop 0
	global_load_dwordx4 v[60:63], v[60:61], off offset:576
	s_andn2_b64 vcc, exec, s[18:19]
	s_waitcnt vmcnt(6)
	v_sub_f32_e32 v33, v33, v66
	v_sub_f32_e32 v32, v32, v66
	v_sub_f32_e32 v35, v35, v66
	v_sub_f32_e32 v34, v34, v66
	v_pk_fma_f32 v[32:33], v[32:33], v[76:77], v[120:121]
	v_pk_fma_f32 v[34:35], v[34:35], v[78:79], v[122:123]
	v_pk_mul_f32 v[32:33], v[32:33], s[16:17] op_sel_hi:[1,0]
	v_pk_mul_f32 v[34:35], v[34:35], s[16:17] op_sel_hi:[1,0]
	v_pk_fma_f32 v[28:29], v[28:29], 0.5, v[32:33] op_sel_hi:[1,0,1]
	v_lshl_add_u64 v[32:33], s[38:39], 0, v[64:65]
	v_pk_fma_f32 v[30:31], v[30:31], 0.5, v[34:35] op_sel_hi:[1,0,1]
	v_lshl_add_u64 v[32:33], v[32:33], 0, v[168:169]
	ds_bpermute_b32 v246, v238, v28
	ds_bpermute_b32 v247, v238, v29
	ds_bpermute_b32 v248, v238, v30
	ds_bpermute_b32 v249, v238, v31
	v_lshl_add_u64 v[244:245], v[32:33], 0, v[240:241]
	s_waitcnt lgkmcnt(0)
	global_store_dwordx4 v[244:245], v[246:249], off sc1
	v_pk_mul_f32 v[34:35], v[116:117], v[72:73] op_sel_hi:[1,0]
	s_nop 0
	v_sub_f32_e32 v29, v37, v66
	v_sub_f32_e32 v28, v36, v66
	v_sub_f32_e32 v31, v39, v66
	v_sub_f32_e32 v30, v38, v66
	v_pk_mul_f32 v[36:37], v[118:119], v[72:73] op_sel_hi:[1,0]
	v_pk_fma_f32 v[28:29], v[28:29], v[34:35], v[112:113]
	v_pk_fma_f32 v[30:31], v[30:31], v[36:37], v[114:115]
	v_pk_mul_f32 v[28:29], v[28:29], s[16:17] op_sel_hi:[1,0]
	v_pk_mul_f32 v[30:31], v[30:31], s[16:17] op_sel_hi:[1,0]
	v_pk_fma_f32 v[24:25], v[24:25], 0.5, v[28:29] op_sel_hi:[1,0,1]
	v_pk_fma_f32 v[26:27], v[26:27], 0.5, v[30:31] op_sel_hi:[1,0,1]
	ds_bpermute_b32 v250, v238, v24
	ds_bpermute_b32 v251, v238, v25
	ds_bpermute_b32 v252, v238, v26
	ds_bpermute_b32 v253, v238, v27
	v_lshl_add_u64 v[244:245], v[32:33], 0, v[240:241]
	s_waitcnt lgkmcnt(0)
	global_store_dwordx4 v[244:245], v[250:253], off offset:64 sc1
	v_pk_mul_f32 v[28:29], v[108:109], v[72:73] op_sel_hi:[1,0]
	v_pk_mul_f32 v[30:31], v[110:111], v[72:73] op_sel_hi:[1,0]
	s_waitcnt vmcnt(6)
; #define PG8_BAR __builtin_amdgcn_s_barrier()
; template <class Sched, class Epi, bool ALIGN_EPI, bool SP2>
; __device__ __forceinline__ void gemm_phase(LAS unsigned char* lds, const int K, const int lda, const int ldb, const Sched& S, const Epi& E) {
;     ...
;         cur = nxt; cA = nA; cB = nB; ++ui;
;         if constexpr (ALIGN_EPI) { if (wr == 1) PG8_BAR; }
;     __device__ __forceinline__ void operator()(const f32x4 (&acc)[2][2][4][2], const Unit& u, int wr, int wc, int fr, int fq) const {
;     ...
;                 for (int mm = 0; mm < 2; ++mm) {
;                     const int r = row0 + ai * HALF + (2 * m2 + mm) * 16;
;                     float ps = 0.f, pq = 0.f;
; #pragma unroll
;                     for (int bj = 0; bj < 2; ++bj)
; #pragma unroll
;                         for (int n = 0; n < 2; ++n) {
;                             const f32x4 x = (xv[mm][bj][n] - st[mm][0]) * (gg[bj][n] * st[mm][1]) + bb[bj][n];
;                             const f32x4 o = x * alpha + acc[ai][bj][2 * m2 + mm][n] * scale;
;                             const size_t off = (size_t)r * D + col0 + bj * HALF + n * 16;
;                             *(f32x4*)(Y + off) = o;
	v_sub_f32_e32 v25, v45, v66
	v_sub_f32_e32 v24, v44, v66
	v_sub_f32_e32 v27, v47, v66
	v_sub_f32_e32 v26, v46, v66
	v_pk_fma_f32 v[26:27], v[26:27], v[30:31], v[106:107]
	v_pk_fma_f32 v[24:25], v[24:25], v[28:29], v[104:105]
	v_pk_mul_f32 v[26:27], v[26:27], s[16:17] op_sel_hi:[1,0]
	v_pk_mul_f32 v[24:25], v[24:25], s[16:17] op_sel_hi:[1,0]
	v_pk_fma_f32 v[22:23], v[22:23], 0.5, v[26:27] op_sel_hi:[1,0,1]
	v_pk_fma_f32 v[20:21], v[20:21], 0.5, v[24:25] op_sel_hi:[1,0,1]
	ds_bpermute_b32 v246, v238, v20
	ds_bpermute_b32 v247, v238, v21
	ds_bpermute_b32 v248, v238, v22
	ds_bpermute_b32 v249, v238, v23
	v_lshl_add_u64 v[244:245], v[32:33], 0, v[240:241]
	s_waitcnt lgkmcnt(0)
	global_store_dwordx4 v[244:245], v[246:249], off offset:512 sc1
	v_pk_mul_f32 v[24:25], v[100:101], v[72:73] op_sel_hi:[1,0]
	v_pk_mul_f32 v[26:27], v[102:103], v[72:73] op_sel_hi:[1,0]
	v_sub_f32_e32 v21, v41, v66
	v_sub_f32_e32 v20, v40, v66
	v_sub_f32_e32 v23, v43, v66
	v_sub_f32_e32 v22, v42, v66
	v_pk_fma_f32 v[22:23], v[22:23], v[26:27], v[98:99]
	v_pk_fma_f32 v[20:21], v[20:21], v[24:25], v[96:97]
	v_pk_mul_f32 v[22:23], v[22:23], s[16:17] op_sel_hi:[1,0]
	v_pk_mul_f32 v[20:21], v[20:21], s[16:17] op_sel_hi:[1,0]
	v_pk_fma_f32 v[14:15], v[14:15], 0.5, v[22:23] op_sel_hi:[1,0,1]
	v_pk_fma_f32 v[12:13], v[12:13], 0.5, v[20:21] op_sel_hi:[1,0,1]
	ds_bpermute_b32 v250, v238, v12
	ds_bpermute_b32 v251, v238, v13
	ds_bpermute_b32 v252, v238, v14
	ds_bpermute_b32 v253, v238, v15
	v_lshl_add_u64 v[244:245], v[32:33], 0, v[240:241]
	s_waitcnt lgkmcnt(0)
	global_store_dwordx4 v[244:245], v[250:253], off offset:576 sc1
	v_pk_mul_f32 v[20:21], v[124:125], v[74:75] op_sel_hi:[1,0]
	v_pk_mul_f32 v[22:23], v[126:127], v[74:75] op_sel_hi:[1,0]
	s_waitcnt vmcnt(7)
	v_sub_f32_e32 v13, v49, v68
	v_sub_f32_e32 v12, v48, v68
	v_sub_f32_e32 v15, v51, v68
	v_sub_f32_e32 v14, v50, v68
	v_pk_fma_f32 v[12:13], v[12:13], v[20:21], v[120:121]
	v_pk_fma_f32 v[14:15], v[14:15], v[22:23], v[122:123]
	v_pk_mul_f32 v[12:13], v[12:13], s[16:17] op_sel_hi:[1,0]
	v_pk_mul_f32 v[14:15], v[14:15], s[16:17] op_sel_hi:[1,0]
	v_pk_fma_f32 v[12:13], v[16:17], 0.5, v[12:13] op_sel_hi:[1,0,1]
	v_lshl_add_u64 v[16:17], s[38:39], 0, v[70:71]
	v_pk_fma_f32 v[14:15], v[18:19], 0.5, v[14:15] op_sel_hi:[1,0,1]
	v_lshl_add_u64 v[16:17], v[16:17], 0, v[168:169]
	ds_bpermute_b32 v246, v238, v12
	ds_bpermute_b32 v247, v238, v13
	ds_bpermute_b32 v248, v238, v14
	ds_bpermute_b32 v249, v238, v15
	v_lshl_add_u64 v[244:245], v[16:17], 0, v[240:241]
	s_waitcnt lgkmcnt(0)
	global_store_dwordx4 v[244:245], v[246:249], off sc1
	v_pk_mul_f32 v[18:19], v[116:117], v[74:75] op_sel_hi:[1,0]
	v_pk_mul_f32 v[20:21], v[118:119], v[74:75] op_sel_hi:[1,0]
	s_waitcnt vmcnt(7)
	v_sub_f32_e32 v13, v53, v68
	v_sub_f32_e32 v12, v52, v68
	v_sub_f32_e32 v15, v55, v68
	v_sub_f32_e32 v14, v54, v68
	v_pk_fma_f32 v[14:15], v[14:15], v[20:21], v[114:115]
	v_pk_fma_f32 v[12:13], v[12:13], v[18:19], v[112:113]
	v_pk_mul_f32 v[14:15], v[14:15], s[16:17] op_sel_hi:[1,0]
	v_pk_mul_f32 v[12:13], v[12:13], s[16:17] op_sel_hi:[1,0]
	v_pk_fma_f32 v[10:11], v[10:11], 0.5, v[14:15] op_sel_hi:[1,0,1]
	v_pk_fma_f32 v[8:9], v[8:9], 0.5, v[12:13] op_sel_hi:[1,0,1]
	ds_bpermute_b32 v250, v238, v8
	ds_bpermute_b32 v251, v238, v9
	ds_bpermute_b32 v252, v238, v10
	ds_bpermute_b32 v253, v238, v11
	v_lshl_add_u64 v[244:245], v[16:17], 0, v[240:241]
	s_waitcnt lgkmcnt(0)
	global_store_dwordx4 v[244:245], v[250:253], off offset:64 sc1
	v_pk_mul_f32 v[12:13], v[108:109], v[74:75] op_sel_hi:[1,0]
	v_pk_mul_f32 v[14:15], v[110:111], v[74:75] op_sel_hi:[1,0]
	s_waitcnt vmcnt(7)
	v_sub_f32_e32 v9, v57, v68
	v_sub_f32_e32 v8, v56, v68
	v_sub_f32_e32 v11, v59, v68
	v_sub_f32_e32 v10, v58, v68
	v_pk_fma_f32 v[10:11], v[10:11], v[14:15], v[106:107]
	v_pk_fma_f32 v[8:9], v[8:9], v[12:13], v[104:105]
	v_pk_mul_f32 v[10:11], v[10:11], s[16:17] op_sel_hi:[1,0]
	v_pk_mul_f32 v[8:9], v[8:9], s[16:17] op_sel_hi:[1,0]
	v_pk_fma_f32 v[6:7], v[6:7], 0.5, v[10:11] op_sel_hi:[1,0,1]
	v_pk_fma_f32 v[4:5], v[4:5], 0.5, v[8:9] op_sel_hi:[1,0,1]
	ds_bpermute_b32 v246, v238, v4
	ds_bpermute_b32 v247, v238, v5
	ds_bpermute_b32 v248, v238, v6
	ds_bpermute_b32 v249, v238, v7
	v_lshl_add_u64 v[244:245], v[16:17], 0, v[240:241]
	s_waitcnt lgkmcnt(0)
	global_store_dwordx4 v[244:245], v[246:249], off offset:512 sc1
	v_pk_mul_f32 v[8:9], v[100:101], v[74:75] op_sel_hi:[1,0]
	v_pk_mul_f32 v[10:11], v[102:103], v[74:75] op_sel_hi:[1,0]
	s_waitcnt vmcnt(7)
	v_sub_f32_e32 v5, v61, v68
	v_sub_f32_e32 v4, v60, v68
	v_sub_f32_e32 v7, v63, v68
	v_sub_f32_e32 v6, v62, v68
	v_pk_fma_f32 v[6:7], v[6:7], v[10:11], v[98:99]
	v_pk_fma_f32 v[4:5], v[4:5], v[8:9], v[96:97]
	v_pk_mul_f32 v[6:7], v[6:7], s[16:17] op_sel_hi:[1,0]
	v_pk_mul_f32 v[4:5], v[4:5], s[16:17] op_sel_hi:[1,0]
	v_pk_fma_f32 v[2:3], v[2:3], 0.5, v[6:7] op_sel_hi:[1,0,1]
	v_pk_fma_f32 v[0:1], v[0:1], 0.5, v[4:5] op_sel_hi:[1,0,1]
	ds_bpermute_b32 v250, v238, v0
	ds_bpermute_b32 v251, v238, v1
	ds_bpermute_b32 v252, v238, v2
	ds_bpermute_b32 v253, v238, v3
	v_lshl_add_u64 v[244:245], v[16:17], 0, v[240:241]
	s_waitcnt lgkmcnt(0)
	global_store_dwordx4 v[244:245], v[250:253], off offset:576 sc1
	s_cbranch_vccnz .LBB0_1112
	s_andn2_b64 vcc, exec, s[6:7]
	s_cbranch_vccnz .LBB0_1111
	s_barrier
	s_branch .LBB0_1111
